# GEMM loops: phase-5 LDS-DMA pair (A second half) issued in phase 4 instead (phase 5 carries 12 ds_reads), counted wait adjusted; on top of v8
# speedup vs baseline: 1.0071x; 1.0001x over previous
; #define PG8_STAGE(bufoff, gbase, voff) do { _Pragma("unroll") for (int _i = 0; _i < 2; ++_i) \
;         __builtin_amdgcn_global_load_lds((const unsigned*)((const char*)(gbase) + (voff)[_i]), (LAS unsigned*)(lds + (bufoff) + ldsw + _i * 8192), 16, 0, 0); } while (0)
; #define PG8_LDA(dst, b, h) do { _Pragma("unroll") for (int m = 0; m < 4; ++m) _Pragma("unroll") for (int k = 0; k < 2; ++k) dst[m][k] = *(const LAS bf16x8*)(lds + PG8_SA(b, h) + aoff + m * 2048 + k * 1024); } while (0)
; #define PG8_LDB(dst, b, h) do { _Pragma("unroll") for (int n = 0; n < 2; ++n) _Pragma("unroll") for (int k = 0; k < 2; ++k) dst[n][k] = *(const LAS bf16x8*)(lds + PG8_SB(b, h) + boff + n * 2048 + k * 1024); } while (0)
; #define PG8_WAIT_V(n) asm volatile("s_waitcnt vmcnt(" #n ")" ::: "memory")
; #define PG8_WAIT_L(n) asm volatile("s_waitcnt lgkmcnt(" #n ")" ::: "memory")
; #define PG8_BAR __builtin_amdgcn_s_barrier()
; #define PG8_SCHED __builtin_amdgcn_sched_barrier(0)
; template <class Epi, class Sched>
; __device__ __forceinline__ void gemm_phase(LAS unsigned char* lds, const Gemm g, const Sched& S, const Epi& E) {
;     ...
;         const bool has_next = S.next(ui + 1, nxt);
;         const char* nA = has_next ? (const char*)g.A + (size_t)nxt.pm * tstep : cA; const char* nB = has_next ? (const char*)g.Bt + (size_t)nxt.pn * tstep : cB;
;         for (int t = 0; t < nt; t += 2) {
;             const bool last = (t == nt - 2);
;             const char* a1 = cA + (size_t)(t + 1) * kstep;
;             const char* a2 = last ? nA : cA + (size_t)(t + 2) * kstep; const char* b2 = last ? nB : cB + (size_t)(t + 2) * kstep;
;             const char* a3 = a2 + kstep; const char* b3 = b2 + kstep;
;             PG8_LDB(B0, 0, 0); PG8_SCHED; PG8_LDA(At, 0, 0); PG8_STAGE(PG8_SA(1, 1), a1 + hstep, voffA);
;             PG8_WAIT_L(8); PG8_BAR; PG8_WAIT_L(0); PG8_MMA(0, 0, At, B0); PG8_BAR; PG8_SCHED;
;             PG8_LDB(B1, 0, 1); PG8_STAGE(PG8_SB(0, 0), b2, voffB);
;             PG8_BAR; PG8_WAIT_L(0); PG8_MMA(0, 1, At, B1); PG8_BAR;
;             PG8_LDA(At, 0, 1); PG8_STAGE(PG8_SA(0, 0), a2, voffA);
;             PG8_BAR; PG8_WAIT_L(0); PG8_MMA(1, 0, At, B0); PG8_BAR; PG8_SCHED;
;             PG8_STAGE(PG8_SB(0, 1), b2 + hstep, voffB);
;             PG8_WAIT_V(6); PG8_BAR; PG8_MMA(1, 1, At, B1); PG8_BAR;
.LBB0_234:
	s_ashr_i32 s7, s6, 31
	v_cmp_lt_i64_e32 vcc, s[8:9], v[140:141]
	s_lshl_b64 s[8:9], s[6:7], 19
	s_add_u32 s8, s96, s8
	s_addc_u32 s9, s97, s9
	s_and_b64 s[10:11], vcc, exec
	s_cselect_b32 s7, s9, s15
	s_cselect_b32 s44, s8, s14
	s_ashr_i32 s5, s4, 31
	s_lshl_b64 s[10:11], s[4:5], 19
	s_add_u32 s10, s72, s10
	s_addc_u32 s11, s73, s11
	s_and_b64 s[16:17], vcc, exec
	s_cselect_b32 s5, s11, s19
	s_cselect_b32 s45, s10, s18
	s_add_u32 s14, s14, 0x40080
	s_addc_u32 s15, s15, 0
	s_add_u32 s46, s18, 0x100
	s_addc_u32 s47, s19, 0
	s_mov_b32 s48, -2
	ds_read_b128 v[150:153], v147
	ds_read_b128 v[154:157], v147 offset:1024
	ds_read_b128 v[158:161], v147 offset:2048
	ds_read_b128 v[162:165], v147 offset:3072
	s_add_u32 s16, s14, 0xfffc0080
	s_addc_u32 s17, s15, -1
	s_cmp_eq_u32 s48, 12
	s_cselect_b32 s23, s7, s17
	s_cselect_b32 s22, s44, s16
	s_cselect_b32 s19, s5, s47
	s_cselect_b32 s18, s45, s46
	s_add_i32 m0, s13, 0xc000
	ds_read_b128 v[166:169], v148
	ds_read_b128 v[170:173], v148 offset:1024
	ds_read_b128 v[174:177], v148 offset:2048
	ds_read_b128 v[178:181], v148 offset:3072
	ds_read_b128 v[182:185], v148 offset:4096
	ds_read_b128 v[186:189], v148 offset:5120
	ds_read_b128 v[190:193], v148 offset:6144
	ds_read_b128 v[194:197], v148 offset:7168
	global_load_lds_dwordx4 v136, s[14:15]
	s_add_i32 m0, s13, 0xe000
	s_nop 0
	global_load_lds_dwordx4 v138, s[14:15]
	s_waitcnt lgkmcnt(8)
	s_waitcnt vmcnt(10)
	s_barrier
	s_waitcnt lgkmcnt(0)
	s_setprio 1
	s_waitcnt lgkmcnt(0)
	v_mfma_f32_16x16x32_bf16 v[124:127], v[150:153], v[166:169], 0
	v_mfma_f32_16x16x32_bf16 v[116:119], v[158:161], v[166:169], 0
	v_mfma_f32_16x16x32_bf16 v[108:111], v[150:153], v[174:177], 0
	v_mfma_f32_16x16x32_bf16 v[100:103], v[158:161], v[174:177], 0
	v_mfma_f32_16x16x32_bf16 v[92:95], v[150:153], v[182:185], 0
	v_mfma_f32_16x16x32_bf16 v[84:87], v[158:161], v[182:185], 0
	v_mfma_f32_16x16x32_bf16 v[76:79], v[150:153], v[190:193], 0
	v_mfma_f32_16x16x32_bf16 v[68:71], v[158:161], v[190:193], 0
	v_mfma_f32_16x16x32_bf16 v[124:127], v[154:157], v[170:173], v[124:127]
	v_mfma_f32_16x16x32_bf16 v[116:119], v[162:165], v[170:173], v[116:119]
	v_mfma_f32_16x16x32_bf16 v[108:111], v[154:157], v[178:181], v[108:111]
	v_mfma_f32_16x16x32_bf16 v[100:103], v[162:165], v[178:181], v[100:103]
	v_mfma_f32_16x16x32_bf16 v[92:95], v[154:157], v[186:189], v[92:95]
	v_mfma_f32_16x16x32_bf16 v[84:87], v[162:165], v[186:189], v[84:87]
	v_mfma_f32_16x16x32_bf16 v[76:79], v[154:157], v[194:197], v[76:79]
	v_mfma_f32_16x16x32_bf16 v[68:71], v[162:165], v[194:197], v[68:71]
	s_setprio 0
	s_barrier
	s_add_i32 s16, s40, s25
	s_mov_b32 m0, s16
	ds_read_b128 v[202:205], v149
	ds_read_b128 v[206:209], v149 offset:1024
	ds_read_b128 v[210:213], v149 offset:2048
	ds_read_b128 v[214:217], v149 offset:3072
	global_load_lds_dwordx4 v132, s[18:19]
	s_add_i32 m0, s16, 0x2000
	s_nop 0
	global_load_lds_dwordx4 v128, s[18:19]
	s_waitcnt vmcnt(10)
	s_barrier
	s_waitcnt lgkmcnt(0)
	s_setprio 1
	s_waitcnt lgkmcnt(0)
	v_mfma_f32_16x16x32_bf16 v[120:123], v[202:205], v[166:169], 0
	v_mfma_f32_16x16x32_bf16 v[112:115], v[210:213], v[166:169], 0
	v_mfma_f32_16x16x32_bf16 v[104:107], v[202:205], v[174:177], 0
	v_mfma_f32_16x16x32_bf16 v[96:99], v[210:213], v[174:177], 0
	v_mfma_f32_16x16x32_bf16 v[88:91], v[202:205], v[182:185], 0
	v_mfma_f32_16x16x32_bf16 v[80:83], v[210:213], v[182:185], 0
	v_mfma_f32_16x16x32_bf16 v[72:75], v[202:205], v[190:193], 0
	v_mfma_f32_16x16x32_bf16 v[64:67], v[210:213], v[190:193], 0
	v_mfma_f32_16x16x32_bf16 v[120:123], v[206:209], v[170:173], v[120:123]
	v_mfma_f32_16x16x32_bf16 v[112:115], v[214:217], v[170:173], v[112:115]
	v_mfma_f32_16x16x32_bf16 v[104:107], v[206:209], v[178:181], v[104:107]
	v_mfma_f32_16x16x32_bf16 v[96:99], v[214:217], v[178:181], v[96:99]
	v_mfma_f32_16x16x32_bf16 v[88:91], v[206:209], v[186:189], v[88:91]
	v_mfma_f32_16x16x32_bf16 v[80:83], v[214:217], v[186:189], v[80:83]
	v_mfma_f32_16x16x32_bf16 v[72:75], v[206:209], v[194:197], v[72:75]
	v_mfma_f32_16x16x32_bf16 v[64:67], v[214:217], v[194:197], v[64:67]
	s_setprio 0
	s_mov_b32 m0, s13
	s_barrier
	ds_read_b128 v[166:169], v148 offset:16384
	ds_read_b128 v[170:173], v148 offset:17408
	ds_read_b128 v[174:177], v148 offset:18432
	ds_read_b128 v[178:181], v148 offset:19456
	ds_read_b128 v[182:185], v148 offset:20480
	ds_read_b128 v[186:189], v148 offset:21504
	ds_read_b128 v[190:193], v148 offset:22528
	ds_read_b128 v[194:197], v148 offset:23552
	global_load_lds_dwordx4 v134, s[22:23]
	s_mov_b32 m0, s28
	s_nop 0
	global_load_lds_dwordx4 v130, s[22:23]
	s_barrier
	s_waitcnt lgkmcnt(0)
	s_setprio 1
	s_waitcnt lgkmcnt(0)
	v_mfma_f32_16x16x32_bf16 v[60:63], v[150:153], v[166:169], 0
	v_mfma_f32_16x16x32_bf16 v[56:59], v[158:161], v[166:169], 0
	v_mfma_f32_16x16x32_bf16 v[44:47], v[150:153], v[174:177], 0
	v_mfma_f32_16x16x32_bf16 v[40:43], v[158:161], v[174:177], 0
	v_mfma_f32_16x16x32_bf16 v[28:31], v[150:153], v[182:185], 0
	v_mfma_f32_16x16x32_bf16 v[24:27], v[158:161], v[182:185], 0
	v_mfma_f32_16x16x32_bf16 v[12:15], v[150:153], v[190:193], 0
	v_mfma_f32_16x16x32_bf16 v[8:11], v[158:161], v[190:193], 0
	v_mfma_f32_16x16x32_bf16 v[60:63], v[154:157], v[170:173], v[60:63]
	v_mfma_f32_16x16x32_bf16 v[56:59], v[162:165], v[170:173], v[56:59]
	v_mfma_f32_16x16x32_bf16 v[44:47], v[154:157], v[178:181], v[44:47]
	v_mfma_f32_16x16x32_bf16 v[40:43], v[162:165], v[178:181], v[40:43]
	v_mfma_f32_16x16x32_bf16 v[28:31], v[154:157], v[186:189], v[28:31]
	v_mfma_f32_16x16x32_bf16 v[24:27], v[162:165], v[186:189], v[24:27]
	v_mfma_f32_16x16x32_bf16 v[12:15], v[154:157], v[194:197], v[12:15]
	v_mfma_f32_16x16x32_bf16 v[8:11], v[162:165], v[194:197], v[8:11]
	s_setprio 0
	s_barrier
; #define PG8_STAGE(bufoff, gbase, voff) do { _Pragma("unroll") for (int _i = 0; _i < 2; ++_i) \
;         __builtin_amdgcn_global_load_lds((const unsigned*)((const char*)(gbase) + (voff)[_i]), (LAS unsigned*)(lds + (bufoff) + ldsw + _i * 8192), 16, 0, 0); } while (0)
; #define PG8_LDA(dst, b, h) do { _Pragma("unroll") for (int m = 0; m < 4; ++m) _Pragma("unroll") for (int k = 0; k < 2; ++k) dst[m][k] = *(const LAS bf16x8*)(lds + PG8_SA(b, h) + aoff + m * 2048 + k * 1024); } while (0)
; #define PG8_LDB(dst, b, h) do { _Pragma("unroll") for (int n = 0; n < 2; ++n) _Pragma("unroll") for (int k = 0; k < 2; ++k) dst[n][k] = *(const LAS bf16x8*)(lds + PG8_SB(b, h) + boff + n * 2048 + k * 1024); } while (0)
; #define PG8_MMA(ai, bj, At, Bt) do { __builtin_amdgcn_s_setprio(1); _Pragma("unroll") for (int m = 0; m < 4; ++m) _Pragma("unroll") for (int n = 0; n < 2; ++n) _Pragma("unroll") for (int k = 0; k < 2; ++k) \
;         acc[ai][bj][m][n] = __builtin_amdgcn_mfma_f32_16x16x32_bf16(Bt[n][k], At[m][k], acc[ai][bj][m][n], 0, 0, 0); __builtin_amdgcn_s_setprio(0); } while (0)
; #define PG8_WAIT_V(n) asm volatile("s_waitcnt vmcnt(" #n ")" ::: "memory")
; #define PG8_WAIT_L(n) asm volatile("s_waitcnt lgkmcnt(" #n ")" ::: "memory")
; #define PG8_BAR __builtin_amdgcn_s_barrier()
; #define PG8_SCHED __builtin_amdgcn_sched_barrier(0)
; template <class Epi, class Sched>
; __device__ __forceinline__ void gemm_phase(LAS unsigned char* lds, const Gemm g, const Sched& S, const Epi& E) {
;     ...
;             PG8_STAGE(PG8_SB(0, 1), b2 + hstep, voffB);
;             PG8_WAIT_V(6); PG8_BAR; PG8_MMA(1, 1, At, B1); PG8_BAR;
;             PG8_LDB(B0, 1, 0); PG8_SCHED; PG8_LDA(At, 1, 0); PG8_STAGE(PG8_SA(0, 1), a2 + hstep, voffA);
;             PG8_WAIT_L(8); PG8_BAR; PG8_WAIT_L(0); PG8_MMA(0, 0, At, B0); PG8_BAR; PG8_SCHED;
;             PG8_LDB(B1, 1, 1); PG8_STAGE(PG8_SB(1, 0), b3, voffB);
;             PG8_BAR; PG8_WAIT_L(0); PG8_MMA(0, 1, At, B1); PG8_BAR;
;             PG8_LDA(At, 1, 1); PG8_STAGE(PG8_SA(1, 0), a3, voffA);
;             PG8_BAR; PG8_WAIT_L(0); PG8_MMA(1, 0, At, B0); PG8_BAR; PG8_SCHED;
	s_add_u32 s16, s18, 0x40000
	s_addc_u32 s17, s19, 0
	s_add_i32 s20, s41, s25
	s_mov_b32 m0, s20
	s_nop 0
	global_load_lds_dwordx4 v132, s[16:17]
	s_add_i32 m0, s20, 0x2000
	s_nop 0
	global_load_lds_dwordx4 v128, s[16:17]
	s_add_u32 s16, s22, 0x40000
	s_addc_u32 s17, s23, 0
	s_mov_b32 m0, s29
	s_nop 0
	global_load_lds_dwordx4 v134, s[16:17]
	s_mov_b32 m0, s33
	s_nop 0
	global_load_lds_dwordx4 v130, s[16:17]
	s_waitcnt vmcnt(12)
	s_barrier
	s_setprio 1
	v_mfma_f32_16x16x32_bf16 v[52:55], v[202:205], v[166:169], 0
	v_mfma_f32_16x16x32_bf16 v[48:51], v[210:213], v[166:169], 0
	v_mfma_f32_16x16x32_bf16 v[36:39], v[202:205], v[174:177], 0
	v_mfma_f32_16x16x32_bf16 v[32:35], v[210:213], v[174:177], 0
	v_mfma_f32_16x16x32_bf16 v[20:23], v[202:205], v[182:185], 0
	v_mfma_f32_16x16x32_bf16 v[16:19], v[210:213], v[182:185], 0
	v_mfma_f32_16x16x32_bf16 v[4:7], v[202:205], v[190:193], 0
	v_mfma_f32_16x16x32_bf16 v[0:3], v[210:213], v[190:193], 0
	v_mfma_f32_16x16x32_bf16 v[52:55], v[206:209], v[170:173], v[52:55]
	v_mfma_f32_16x16x32_bf16 v[48:51], v[214:217], v[170:173], v[48:51]
	v_mfma_f32_16x16x32_bf16 v[36:39], v[206:209], v[178:181], v[36:39]
	v_mfma_f32_16x16x32_bf16 v[32:35], v[214:217], v[178:181], v[32:35]
	v_mfma_f32_16x16x32_bf16 v[20:23], v[206:209], v[186:189], v[20:23]
	v_mfma_f32_16x16x32_bf16 v[16:19], v[214:217], v[186:189], v[16:19]
	v_mfma_f32_16x16x32_bf16 v[4:7], v[206:209], v[194:197], v[4:7]
	v_mfma_f32_16x16x32_bf16 v[0:3], v[214:217], v[194:197], v[0:3]
	s_setprio 0
	s_add_i32 s20, 0, 0x18000
	v_add_u32_e32 v162, s20, v146
	s_barrier
	ds_read_b128 v[150:153], v162
	ds_read_b128 v[154:157], v162 offset:1024
	ds_read_b128 v[158:161], v162 offset:2048
	ds_read_b128 v[162:165], v162 offset:3072
	ds_read_b128 v[166:169], v148 offset:32768
	ds_read_b128 v[170:173], v148 offset:33792
	ds_read_b128 v[174:177], v148 offset:34816
	ds_read_b128 v[178:181], v148 offset:35840
	ds_read_b128 v[182:185], v148 offset:36864
	ds_read_b128 v[186:189], v148 offset:37888
	ds_read_b128 v[190:193], v148 offset:38912
	ds_read_b128 v[194:197], v148 offset:39936
	s_waitcnt lgkmcnt(8)
	s_waitcnt vmcnt(10)
	s_barrier
	s_waitcnt lgkmcnt(0)
	s_setprio 1
	s_waitcnt lgkmcnt(0)
	v_mfma_f32_16x16x32_bf16 v[124:127], v[150:153], v[166:169], v[124:127]
	v_mfma_f32_16x16x32_bf16 v[116:119], v[158:161], v[166:169], v[116:119]
	v_mfma_f32_16x16x32_bf16 v[108:111], v[150:153], v[174:177], v[108:111]
	v_mfma_f32_16x16x32_bf16 v[100:103], v[158:161], v[174:177], v[100:103]
	v_mfma_f32_16x16x32_bf16 v[92:95], v[150:153], v[182:185], v[92:95]
	v_mfma_f32_16x16x32_bf16 v[84:87], v[158:161], v[182:185], v[84:87]
	v_mfma_f32_16x16x32_bf16 v[76:79], v[150:153], v[190:193], v[76:79]
	v_mfma_f32_16x16x32_bf16 v[68:71], v[158:161], v[190:193], v[68:71]
	v_mfma_f32_16x16x32_bf16 v[124:127], v[154:157], v[170:173], v[124:127]
	v_mfma_f32_16x16x32_bf16 v[116:119], v[162:165], v[170:173], v[116:119]
	v_mfma_f32_16x16x32_bf16 v[108:111], v[154:157], v[178:181], v[108:111]
	v_mfma_f32_16x16x32_bf16 v[100:103], v[162:165], v[178:181], v[100:103]
	v_mfma_f32_16x16x32_bf16 v[92:95], v[154:157], v[186:189], v[92:95]
	v_mfma_f32_16x16x32_bf16 v[84:87], v[162:165], v[186:189], v[84:87]
	v_mfma_f32_16x16x32_bf16 v[76:79], v[154:157], v[194:197], v[76:79]
	v_mfma_f32_16x16x32_bf16 v[68:71], v[162:165], v[194:197], v[68:71]
	s_setprio 0
	s_barrier
	s_add_i32 s21, 0, 0x1c000
	s_add_i32 s16, s20, s25
	v_add_u32_e32 v214, s21, v146
	s_add_u32 s0, s18, 0x80
	s_addc_u32 s1, s19, 0
	s_mov_b32 m0, s16
	ds_read_b128 v[202:205], v214
	ds_read_b128 v[206:209], v214 offset:1024
	ds_read_b128 v[210:213], v214 offset:2048
	ds_read_b128 v[214:217], v214 offset:3072
	global_load_lds_dwordx4 v132, s[0:1]
	s_add_i32 m0, s16, 0x2000
	s_nop 0
	global_load_lds_dwordx4 v128, s[0:1]
	s_waitcnt vmcnt(10)
	s_barrier
	s_waitcnt lgkmcnt(0)
	s_setprio 1
	s_waitcnt lgkmcnt(0)
	v_mfma_f32_16x16x32_bf16 v[120:123], v[202:205], v[166:169], v[120:123]
	v_mfma_f32_16x16x32_bf16 v[112:115], v[210:213], v[166:169], v[112:115]
	v_mfma_f32_16x16x32_bf16 v[104:107], v[202:205], v[174:177], v[104:107]
	v_mfma_f32_16x16x32_bf16 v[96:99], v[210:213], v[174:177], v[96:99]
	v_mfma_f32_16x16x32_bf16 v[88:91], v[202:205], v[182:185], v[88:91]
	v_mfma_f32_16x16x32_bf16 v[80:83], v[210:213], v[182:185], v[80:83]
	v_mfma_f32_16x16x32_bf16 v[72:75], v[202:205], v[190:193], v[72:75]
	v_mfma_f32_16x16x32_bf16 v[64:67], v[210:213], v[190:193], v[64:67]
	v_mfma_f32_16x16x32_bf16 v[120:123], v[206:209], v[170:173], v[120:123]
	v_mfma_f32_16x16x32_bf16 v[112:115], v[214:217], v[170:173], v[112:115]
	v_mfma_f32_16x16x32_bf16 v[104:107], v[206:209], v[178:181], v[104:107]
	v_mfma_f32_16x16x32_bf16 v[96:99], v[214:217], v[178:181], v[96:99]
	v_mfma_f32_16x16x32_bf16 v[88:91], v[206:209], v[186:189], v[88:91]
	v_mfma_f32_16x16x32_bf16 v[80:83], v[214:217], v[186:189], v[80:83]
	v_mfma_f32_16x16x32_bf16 v[72:75], v[206:209], v[194:197], v[72:75]
	v_mfma_f32_16x16x32_bf16 v[64:67], v[214:217], v[194:197], v[64:67]
	s_setprio 0
	s_mov_b32 m0, s36
	s_add_u32 s0, s22, 0x80
	s_addc_u32 s1, s23, 0
	s_barrier
	ds_read_b128 v[166:169], v148 offset:49152
	ds_read_b128 v[170:173], v148 offset:50176
	ds_read_b128 v[174:177], v148 offset:51200
	ds_read_b128 v[178:181], v148 offset:52224
	ds_read_b128 v[182:185], v148 offset:53248
	ds_read_b128 v[186:189], v148 offset:54272
	ds_read_b128 v[190:193], v148 offset:55296
	ds_read_b128 v[194:197], v148 offset:56320
	global_load_lds_dwordx4 v134, s[0:1]
	s_mov_b32 m0, s37
	s_nop 0
	global_load_lds_dwordx4 v130, s[0:1]
	s_barrier
; #define PG8_STAGE(bufoff, gbase, voff) do { _Pragma("unroll") for (int _i = 0; _i < 2; ++_i) \
;         __builtin_amdgcn_global_load_lds((const unsigned*)((const char*)(gbase) + (voff)[_i]), (LAS unsigned*)(lds + (bufoff) + ldsw + _i * 8192), 16, 0, 0); } while (0)
; #define PG8_LDA(dst, b, h) do { _Pragma("unroll") for (int m = 0; m < 4; ++m) _Pragma("unroll") for (int k = 0; k < 2; ++k) dst[m][k] = *(const LAS bf16x8*)(lds + PG8_SA(b, h) + aoff + m * 2048 + k * 1024); } while (0)
; #define PG8_LDB(dst, b, h) do { _Pragma("unroll") for (int n = 0; n < 2; ++n) _Pragma("unroll") for (int k = 0; k < 2; ++k) dst[n][k] = *(const LAS bf16x8*)(lds + PG8_SB(b, h) + boff + n * 2048 + k * 1024); } while (0)
; #define PG8_MMA(ai, bj, At, Bt) do { __builtin_amdgcn_s_setprio(1); _Pragma("unroll") for (int m = 0; m < 4; ++m) _Pragma("unroll") for (int n = 0; n < 2; ++n) _Pragma("unroll") for (int k = 0; k < 2; ++k) \
;         acc[ai][bj][m][n] = __builtin_amdgcn_mfma_f32_16x16x32_bf16(Bt[n][k], At[m][k], acc[ai][bj][m][n], 0, 0, 0); __builtin_amdgcn_s_setprio(0); } while (0)
; #define PG8_WAIT_V(n) asm volatile("s_waitcnt vmcnt(" #n ")" ::: "memory")
; #define PG8_WAIT_L(n) asm volatile("s_waitcnt lgkmcnt(" #n ")" ::: "memory")
; #define PG8_BAR __builtin_amdgcn_s_barrier()
; #define PG8_SCHED __builtin_amdgcn_sched_barrier(0)
; template <class Epi, class Sched>
; __device__ __forceinline__ void gemm_phase(LAS unsigned char* lds, const Gemm g, const Sched& S, const Epi& E) {
;     ...
;             PG8_LDB(B0, 0, 0); PG8_SCHED; PG8_LDA(At, 0, 0); PG8_STAGE(PG8_SA(1, 1), a1 + hstep, voffA);
;             PG8_WAIT_L(8); PG8_BAR; PG8_WAIT_L(0); PG8_MMA(0, 0, At, B0); PG8_BAR; PG8_SCHED;
;             PG8_LDB(B1, 0, 1); PG8_STAGE(PG8_SB(0, 0), b2, voffB);
;     ...
;             PG8_BAR; PG8_WAIT_L(0); PG8_MMA(1, 0, At, B0); PG8_BAR; PG8_SCHED;
;             PG8_STAGE(PG8_SB(1, 1), b3 + hstep, voffB);
;             PG8_WAIT_V(6); PG8_BAR; PG8_MMA(1, 1, At, B1); PG8_BAR;
	s_waitcnt lgkmcnt(0)
	s_setprio 1
	s_waitcnt lgkmcnt(0)
	v_mfma_f32_16x16x32_bf16 v[60:63], v[150:153], v[166:169], v[60:63]
	v_mfma_f32_16x16x32_bf16 v[56:59], v[158:161], v[166:169], v[56:59]
	v_mfma_f32_16x16x32_bf16 v[44:47], v[150:153], v[174:177], v[44:47]
	v_mfma_f32_16x16x32_bf16 v[40:43], v[158:161], v[174:177], v[40:43]
	v_mfma_f32_16x16x32_bf16 v[28:31], v[150:153], v[182:185], v[28:31]
	v_mfma_f32_16x16x32_bf16 v[24:27], v[158:161], v[182:185], v[24:27]
	v_mfma_f32_16x16x32_bf16 v[12:15], v[150:153], v[190:193], v[12:15]
	v_mfma_f32_16x16x32_bf16 v[8:11], v[158:161], v[190:193], v[8:11]
	v_mfma_f32_16x16x32_bf16 v[60:63], v[154:157], v[170:173], v[60:63]
	v_mfma_f32_16x16x32_bf16 v[56:59], v[162:165], v[170:173], v[56:59]
	v_mfma_f32_16x16x32_bf16 v[44:47], v[154:157], v[178:181], v[44:47]
	v_mfma_f32_16x16x32_bf16 v[40:43], v[162:165], v[178:181], v[40:43]
	v_mfma_f32_16x16x32_bf16 v[28:31], v[154:157], v[186:189], v[28:31]
	v_mfma_f32_16x16x32_bf16 v[24:27], v[162:165], v[186:189], v[24:27]
	v_mfma_f32_16x16x32_bf16 v[12:15], v[154:157], v[194:197], v[12:15]
	v_mfma_f32_16x16x32_bf16 v[8:11], v[162:165], v[194:197], v[8:11]
	s_setprio 0
	s_barrier
	s_add_u32 s16, s18, 0x40080
	s_addc_u32 s17, s19, 0
	s_add_i32 s18, s21, s25
	s_mov_b32 m0, s18
	s_nop 0
	global_load_lds_dwordx4 v132, s[16:17]
	s_add_i32 m0, s18, 0x2000
	s_nop 0
	global_load_lds_dwordx4 v128, s[16:17]
	s_waitcnt vmcnt(10)
	s_barrier
	s_setprio 1
	v_mfma_f32_16x16x32_bf16 v[52:55], v[202:205], v[166:169], v[52:55]
	v_mfma_f32_16x16x32_bf16 v[48:51], v[210:213], v[166:169], v[48:51]
	v_mfma_f32_16x16x32_bf16 v[36:39], v[202:205], v[174:177], v[36:39]
	v_mfma_f32_16x16x32_bf16 v[32:35], v[210:213], v[174:177], v[32:35]
	v_mfma_f32_16x16x32_bf16 v[20:23], v[202:205], v[182:185], v[20:23]
	v_mfma_f32_16x16x32_bf16 v[16:19], v[210:213], v[182:185], v[16:19]
	v_mfma_f32_16x16x32_bf16 v[4:7], v[202:205], v[190:193], v[4:7]
	v_mfma_f32_16x16x32_bf16 v[0:3], v[210:213], v[190:193], v[0:3]
	v_mfma_f32_16x16x32_bf16 v[52:55], v[206:209], v[170:173], v[52:55]
	v_mfma_f32_16x16x32_bf16 v[48:51], v[214:217], v[170:173], v[48:51]
	v_mfma_f32_16x16x32_bf16 v[36:39], v[206:209], v[178:181], v[36:39]
	v_mfma_f32_16x16x32_bf16 v[32:35], v[214:217], v[178:181], v[32:35]
	v_mfma_f32_16x16x32_bf16 v[20:23], v[206:209], v[186:189], v[20:23]
	v_mfma_f32_16x16x32_bf16 v[16:19], v[214:217], v[186:189], v[16:19]
	v_mfma_f32_16x16x32_bf16 v[4:7], v[206:209], v[194:197], v[4:7]
	v_mfma_f32_16x16x32_bf16 v[0:3], v[214:217], v[194:197], v[0:3]
	s_setprio 0
	s_add_i32 s48, s48, 2
	s_add_u32 s14, s14, 0x100
	s_addc_u32 s15, s15, 0
	s_add_u32 s46, s46, 0x100
	s_addc_u32 s47, s47, 0
	s_cmp_gt_u32 s48, 13
	s_barrier
.LBB0_235:
	ds_read_b128 v[150:153], v147
	ds_read_b128 v[154:157], v147 offset:1024
	ds_read_b128 v[158:161], v147 offset:2048
	ds_read_b128 v[162:165], v147 offset:3072
	s_add_u32 s16, s14, 0xfffc0080
	s_addc_u32 s17, s15, -1
	s_cmp_eq_u32 s48, 12
	s_cselect_b32 s23, s7, s17
	s_cselect_b32 s22, s44, s16
	s_cselect_b32 s19, s5, s47
	s_cselect_b32 s18, s45, s46
	s_add_i32 m0, s13, 0xc000
	ds_read_b128 v[166:169], v148
	ds_read_b128 v[170:173], v148 offset:1024
	ds_read_b128 v[174:177], v148 offset:2048
	ds_read_b128 v[178:181], v148 offset:3072
	ds_read_b128 v[182:185], v148 offset:4096
	ds_read_b128 v[186:189], v148 offset:5120
	ds_read_b128 v[190:193], v148 offset:6144
	ds_read_b128 v[194:197], v148 offset:7168
	global_load_lds_dwordx4 v136, s[14:15]
	s_add_i32 m0, s13, 0xe000
	s_nop 0
	global_load_lds_dwordx4 v138, s[14:15]
	s_waitcnt lgkmcnt(8)
	s_waitcnt vmcnt(10)
	s_barrier
	s_waitcnt lgkmcnt(0)
	s_setprio 1
	s_waitcnt lgkmcnt(0)
	v_mfma_f32_16x16x32_bf16 v[124:127], v[150:153], v[166:169], v[124:127]
	v_mfma_f32_16x16x32_bf16 v[116:119], v[158:161], v[166:169], v[116:119]
	v_mfma_f32_16x16x32_bf16 v[108:111], v[150:153], v[174:177], v[108:111]
	v_mfma_f32_16x16x32_bf16 v[100:103], v[158:161], v[174:177], v[100:103]
	v_mfma_f32_16x16x32_bf16 v[92:95], v[150:153], v[182:185], v[92:95]
	v_mfma_f32_16x16x32_bf16 v[84:87], v[158:161], v[182:185], v[84:87]
	v_mfma_f32_16x16x32_bf16 v[76:79], v[150:153], v[190:193], v[76:79]
	v_mfma_f32_16x16x32_bf16 v[68:71], v[158:161], v[190:193], v[68:71]
	v_mfma_f32_16x16x32_bf16 v[124:127], v[154:157], v[170:173], v[124:127]
	v_mfma_f32_16x16x32_bf16 v[116:119], v[162:165], v[170:173], v[116:119]
	v_mfma_f32_16x16x32_bf16 v[108:111], v[154:157], v[178:181], v[108:111]
	v_mfma_f32_16x16x32_bf16 v[100:103], v[162:165], v[178:181], v[100:103]
	v_mfma_f32_16x16x32_bf16 v[92:95], v[154:157], v[186:189], v[92:95]
	v_mfma_f32_16x16x32_bf16 v[84:87], v[162:165], v[186:189], v[84:87]
	v_mfma_f32_16x16x32_bf16 v[76:79], v[154:157], v[194:197], v[76:79]
	v_mfma_f32_16x16x32_bf16 v[68:71], v[162:165], v[194:197], v[68:71]
	s_setprio 0
	s_barrier
	s_add_i32 s16, s40, s25
	s_mov_b32 m0, s16
	ds_read_b128 v[202:205], v149
	ds_read_b128 v[206:209], v149 offset:1024
	ds_read_b128 v[210:213], v149 offset:2048
	ds_read_b128 v[214:217], v149 offset:3072
	global_load_lds_dwordx4 v132, s[18:19]
	s_add_i32 m0, s16, 0x2000
	s_nop 0
	global_load_lds_dwordx4 v128, s[18:19]
	s_waitcnt vmcnt(10)
	s_barrier
; #define PG8_STAGE(bufoff, gbase, voff) do { _Pragma("unroll") for (int _i = 0; _i < 2; ++_i) \
;         __builtin_amdgcn_global_load_lds((const unsigned*)((const char*)(gbase) + (voff)[_i]), (LAS unsigned*)(lds + (bufoff) + ldsw + _i * 8192), 16, 0, 0); } while (0)
; #define PG8_LDA(dst, b, h) do { _Pragma("unroll") for (int m = 0; m < 4; ++m) _Pragma("unroll") for (int k = 0; k < 2; ++k) dst[m][k] = *(const LAS bf16x8*)(lds + PG8_SA(b, h) + aoff + m * 2048 + k * 1024); } while (0)
; #define PG8_LDB(dst, b, h) do { _Pragma("unroll") for (int n = 0; n < 2; ++n) _Pragma("unroll") for (int k = 0; k < 2; ++k) dst[n][k] = *(const LAS bf16x8*)(lds + PG8_SB(b, h) + boff + n * 2048 + k * 1024); } while (0)
; #define PG8_MMA(ai, bj, At, Bt) do { __builtin_amdgcn_s_setprio(1); _Pragma("unroll") for (int m = 0; m < 4; ++m) _Pragma("unroll") for (int n = 0; n < 2; ++n) _Pragma("unroll") for (int k = 0; k < 2; ++k) \
;         acc[ai][bj][m][n] = __builtin_amdgcn_mfma_f32_16x16x32_bf16(Bt[n][k], At[m][k], acc[ai][bj][m][n], 0, 0, 0); __builtin_amdgcn_s_setprio(0); } while (0)
; #define PG8_WAIT_V(n) asm volatile("s_waitcnt vmcnt(" #n ")" ::: "memory")
; #define PG8_WAIT_L(n) asm volatile("s_waitcnt lgkmcnt(" #n ")" ::: "memory")
; #define PG8_BAR __builtin_amdgcn_s_barrier()
; #define PG8_SCHED __builtin_amdgcn_sched_barrier(0)
; template <class Epi, class Sched>
; __device__ __forceinline__ void gemm_phase(LAS unsigned char* lds, const Gemm g, const Sched& S, const Epi& E) {
;     ...
;             PG8_BAR; PG8_WAIT_L(0); PG8_MMA(0, 1, At, B1); PG8_BAR;
;             PG8_LDA(At, 0, 1); PG8_STAGE(PG8_SA(0, 0), a2, voffA);
;             PG8_BAR; PG8_WAIT_L(0); PG8_MMA(1, 0, At, B0); PG8_BAR; PG8_SCHED;
;             PG8_STAGE(PG8_SB(0, 1), b2 + hstep, voffB);
;             PG8_WAIT_V(6); PG8_BAR; PG8_MMA(1, 1, At, B1); PG8_BAR;
;             PG8_LDB(B0, 1, 0); PG8_SCHED; PG8_LDA(At, 1, 0); PG8_STAGE(PG8_SA(0, 1), a2 + hstep, voffA);
;             PG8_WAIT_L(8); PG8_BAR; PG8_WAIT_L(0); PG8_MMA(0, 0, At, B0); PG8_BAR; PG8_SCHED;
	s_waitcnt lgkmcnt(0)
	s_setprio 1
	s_waitcnt lgkmcnt(0)
	v_mfma_f32_16x16x32_bf16 v[120:123], v[202:205], v[166:169], v[120:123]
	v_mfma_f32_16x16x32_bf16 v[112:115], v[210:213], v[166:169], v[112:115]
	v_mfma_f32_16x16x32_bf16 v[104:107], v[202:205], v[174:177], v[104:107]
	v_mfma_f32_16x16x32_bf16 v[96:99], v[210:213], v[174:177], v[96:99]
	v_mfma_f32_16x16x32_bf16 v[88:91], v[202:205], v[182:185], v[88:91]
	v_mfma_f32_16x16x32_bf16 v[80:83], v[210:213], v[182:185], v[80:83]
	v_mfma_f32_16x16x32_bf16 v[72:75], v[202:205], v[190:193], v[72:75]
	v_mfma_f32_16x16x32_bf16 v[64:67], v[210:213], v[190:193], v[64:67]
	v_mfma_f32_16x16x32_bf16 v[120:123], v[206:209], v[170:173], v[120:123]
	v_mfma_f32_16x16x32_bf16 v[112:115], v[214:217], v[170:173], v[112:115]
	v_mfma_f32_16x16x32_bf16 v[104:107], v[206:209], v[178:181], v[104:107]
	v_mfma_f32_16x16x32_bf16 v[96:99], v[214:217], v[178:181], v[96:99]
	v_mfma_f32_16x16x32_bf16 v[88:91], v[206:209], v[186:189], v[88:91]
	v_mfma_f32_16x16x32_bf16 v[80:83], v[214:217], v[186:189], v[80:83]
	v_mfma_f32_16x16x32_bf16 v[72:75], v[206:209], v[194:197], v[72:75]
	v_mfma_f32_16x16x32_bf16 v[64:67], v[214:217], v[194:197], v[64:67]
	s_setprio 0
	s_mov_b32 m0, s13
	s_barrier
	ds_read_b128 v[166:169], v148 offset:16384
	ds_read_b128 v[170:173], v148 offset:17408
	ds_read_b128 v[174:177], v148 offset:18432
	ds_read_b128 v[178:181], v148 offset:19456
	ds_read_b128 v[182:185], v148 offset:20480
	ds_read_b128 v[186:189], v148 offset:21504
	ds_read_b128 v[190:193], v148 offset:22528
	ds_read_b128 v[194:197], v148 offset:23552
	global_load_lds_dwordx4 v134, s[22:23]
	s_mov_b32 m0, s28
	s_nop 0
	global_load_lds_dwordx4 v130, s[22:23]
	s_barrier
	s_waitcnt lgkmcnt(0)
	s_setprio 1
	s_waitcnt lgkmcnt(0)
	v_mfma_f32_16x16x32_bf16 v[60:63], v[150:153], v[166:169], v[60:63]
	v_mfma_f32_16x16x32_bf16 v[56:59], v[158:161], v[166:169], v[56:59]
	v_mfma_f32_16x16x32_bf16 v[44:47], v[150:153], v[174:177], v[44:47]
	v_mfma_f32_16x16x32_bf16 v[40:43], v[158:161], v[174:177], v[40:43]
	v_mfma_f32_16x16x32_bf16 v[28:31], v[150:153], v[182:185], v[28:31]
	v_mfma_f32_16x16x32_bf16 v[24:27], v[158:161], v[182:185], v[24:27]
	v_mfma_f32_16x16x32_bf16 v[12:15], v[150:153], v[190:193], v[12:15]
	v_mfma_f32_16x16x32_bf16 v[8:11], v[158:161], v[190:193], v[8:11]
	v_mfma_f32_16x16x32_bf16 v[60:63], v[154:157], v[170:173], v[60:63]
	v_mfma_f32_16x16x32_bf16 v[56:59], v[162:165], v[170:173], v[56:59]
	v_mfma_f32_16x16x32_bf16 v[44:47], v[154:157], v[178:181], v[44:47]
	v_mfma_f32_16x16x32_bf16 v[40:43], v[162:165], v[178:181], v[40:43]
	v_mfma_f32_16x16x32_bf16 v[28:31], v[154:157], v[186:189], v[28:31]
	v_mfma_f32_16x16x32_bf16 v[24:27], v[162:165], v[186:189], v[24:27]
	v_mfma_f32_16x16x32_bf16 v[12:15], v[154:157], v[194:197], v[12:15]
	v_mfma_f32_16x16x32_bf16 v[8:11], v[162:165], v[194:197], v[8:11]
	s_setprio 0
	s_barrier
	s_add_u32 s16, s18, 0x40000
	s_addc_u32 s17, s19, 0
	s_add_i32 s20, s41, s25
	s_mov_b32 m0, s20
	s_nop 0
	global_load_lds_dwordx4 v132, s[16:17]
	s_add_i32 m0, s20, 0x2000
	s_nop 0
	global_load_lds_dwordx4 v128, s[16:17]
	s_add_u32 s16, s22, 0x40000
	s_addc_u32 s17, s23, 0
	s_mov_b32 m0, s29
	s_nop 0
	global_load_lds_dwordx4 v134, s[16:17]
	s_mov_b32 m0, s33
	s_nop 0
	global_load_lds_dwordx4 v130, s[16:17]
	s_waitcnt vmcnt(12)
	s_barrier
	s_setprio 1
	v_mfma_f32_16x16x32_bf16 v[52:55], v[202:205], v[166:169], v[52:55]
	v_mfma_f32_16x16x32_bf16 v[48:51], v[210:213], v[166:169], v[48:51]
	v_mfma_f32_16x16x32_bf16 v[36:39], v[202:205], v[174:177], v[36:39]
	v_mfma_f32_16x16x32_bf16 v[32:35], v[210:213], v[174:177], v[32:35]
	v_mfma_f32_16x16x32_bf16 v[20:23], v[202:205], v[182:185], v[20:23]
	v_mfma_f32_16x16x32_bf16 v[16:19], v[210:213], v[182:185], v[16:19]
	v_mfma_f32_16x16x32_bf16 v[4:7], v[202:205], v[190:193], v[4:7]
	v_mfma_f32_16x16x32_bf16 v[0:3], v[210:213], v[190:193], v[0:3]
	v_mfma_f32_16x16x32_bf16 v[52:55], v[206:209], v[170:173], v[52:55]
	v_mfma_f32_16x16x32_bf16 v[48:51], v[214:217], v[170:173], v[48:51]
	v_mfma_f32_16x16x32_bf16 v[36:39], v[206:209], v[178:181], v[36:39]
	v_mfma_f32_16x16x32_bf16 v[32:35], v[214:217], v[178:181], v[32:35]
	v_mfma_f32_16x16x32_bf16 v[20:23], v[206:209], v[186:189], v[20:23]
	v_mfma_f32_16x16x32_bf16 v[16:19], v[214:217], v[186:189], v[16:19]
	v_mfma_f32_16x16x32_bf16 v[4:7], v[206:209], v[194:197], v[4:7]
	v_mfma_f32_16x16x32_bf16 v[0:3], v[214:217], v[194:197], v[0:3]
	s_setprio 0
	s_add_i32 s20, 0, 0x18000
	v_add_u32_e32 v162, s20, v146
	s_barrier
	ds_read_b128 v[150:153], v162
	ds_read_b128 v[154:157], v162 offset:1024
	ds_read_b128 v[158:161], v162 offset:2048
	ds_read_b128 v[162:165], v162 offset:3072
	ds_read_b128 v[166:169], v148 offset:32768
	ds_read_b128 v[170:173], v148 offset:33792
	ds_read_b128 v[174:177], v148 offset:34816
	ds_read_b128 v[178:181], v148 offset:35840
	ds_read_b128 v[182:185], v148 offset:36864
	ds_read_b128 v[186:189], v148 offset:37888
	ds_read_b128 v[190:193], v148 offset:38912
	ds_read_b128 v[194:197], v148 offset:39936
	s_waitcnt lgkmcnt(8)
	s_waitcnt vmcnt(10)
	s_barrier
; #define PG8_STAGE(bufoff, gbase, voff) do { _Pragma("unroll") for (int _i = 0; _i < 2; ++_i) \
;         __builtin_amdgcn_global_load_lds((const unsigned*)((const char*)(gbase) + (voff)[_i]), (LAS unsigned*)(lds + (bufoff) + ldsw + _i * 8192), 16, 0, 0); } while (0)
; #define PG8_LDA(dst, b, h) do { _Pragma("unroll") for (int m = 0; m < 4; ++m) _Pragma("unroll") for (int k = 0; k < 2; ++k) dst[m][k] = *(const LAS bf16x8*)(lds + PG8_SA(b, h) + aoff + m * 2048 + k * 1024); } while (0)
; #define PG8_LDB(dst, b, h) do { _Pragma("unroll") for (int n = 0; n < 2; ++n) _Pragma("unroll") for (int k = 0; k < 2; ++k) dst[n][k] = *(const LAS bf16x8*)(lds + PG8_SB(b, h) + boff + n * 2048 + k * 1024); } while (0)
; #define PG8_MMA(ai, bj, At, Bt) do { __builtin_amdgcn_s_setprio(1); _Pragma("unroll") for (int m = 0; m < 4; ++m) _Pragma("unroll") for (int n = 0; n < 2; ++n) _Pragma("unroll") for (int k = 0; k < 2; ++k) \
;         acc[ai][bj][m][n] = __builtin_amdgcn_mfma_f32_16x16x32_bf16(Bt[n][k], At[m][k], acc[ai][bj][m][n], 0, 0, 0); __builtin_amdgcn_s_setprio(0); } while (0)
; #define PG8_WAIT_V(n) asm volatile("s_waitcnt vmcnt(" #n ")" ::: "memory")
; #define PG8_WAIT_L(n) asm volatile("s_waitcnt lgkmcnt(" #n ")" ::: "memory")
; #define PG8_BAR __builtin_amdgcn_s_barrier()
; #define PG8_SCHED __builtin_amdgcn_sched_barrier(0)
; template <class Epi, class Sched>
; __device__ __forceinline__ void gemm_phase(LAS unsigned char* lds, const Gemm g, const Sched& S, const Epi& E) {
;     ...
;             PG8_WAIT_L(8); PG8_BAR; PG8_WAIT_L(0); PG8_MMA(0, 0, At, B0); PG8_BAR; PG8_SCHED;
;             PG8_LDB(B1, 1, 1); PG8_STAGE(PG8_SB(1, 0), b3, voffB);
;             PG8_BAR; PG8_WAIT_L(0); PG8_MMA(0, 1, At, B1); PG8_BAR;
;             PG8_LDA(At, 1, 1); PG8_STAGE(PG8_SA(1, 0), a3, voffA);
;             PG8_BAR; PG8_WAIT_L(0); PG8_MMA(1, 0, At, B0); PG8_BAR; PG8_SCHED;
;             PG8_STAGE(PG8_SB(1, 1), b3 + hstep, voffB);
;             PG8_WAIT_V(6); PG8_BAR; PG8_MMA(1, 1, At, B1); PG8_BAR;
	s_waitcnt lgkmcnt(0)
	s_setprio 1
	s_waitcnt lgkmcnt(0)
	v_mfma_f32_16x16x32_bf16 v[124:127], v[150:153], v[166:169], v[124:127]
	v_mfma_f32_16x16x32_bf16 v[116:119], v[158:161], v[166:169], v[116:119]
	v_mfma_f32_16x16x32_bf16 v[108:111], v[150:153], v[174:177], v[108:111]
	v_mfma_f32_16x16x32_bf16 v[100:103], v[158:161], v[174:177], v[100:103]
	v_mfma_f32_16x16x32_bf16 v[92:95], v[150:153], v[182:185], v[92:95]
	v_mfma_f32_16x16x32_bf16 v[84:87], v[158:161], v[182:185], v[84:87]
	v_mfma_f32_16x16x32_bf16 v[76:79], v[150:153], v[190:193], v[76:79]
	v_mfma_f32_16x16x32_bf16 v[68:71], v[158:161], v[190:193], v[68:71]
	v_mfma_f32_16x16x32_bf16 v[124:127], v[154:157], v[170:173], v[124:127]
	v_mfma_f32_16x16x32_bf16 v[116:119], v[162:165], v[170:173], v[116:119]
	v_mfma_f32_16x16x32_bf16 v[108:111], v[154:157], v[178:181], v[108:111]
	v_mfma_f32_16x16x32_bf16 v[100:103], v[162:165], v[178:181], v[100:103]
	v_mfma_f32_16x16x32_bf16 v[92:95], v[154:157], v[186:189], v[92:95]
	v_mfma_f32_16x16x32_bf16 v[84:87], v[162:165], v[186:189], v[84:87]
	v_mfma_f32_16x16x32_bf16 v[76:79], v[154:157], v[194:197], v[76:79]
	v_mfma_f32_16x16x32_bf16 v[68:71], v[162:165], v[194:197], v[68:71]
	s_setprio 0
	s_barrier
	s_add_i32 s21, 0, 0x1c000
	s_add_i32 s16, s20, s25
	v_add_u32_e32 v214, s21, v146
	s_add_u32 s0, s18, 0x80
	s_addc_u32 s1, s19, 0
	s_mov_b32 m0, s16
	ds_read_b128 v[202:205], v214
	ds_read_b128 v[206:209], v214 offset:1024
	ds_read_b128 v[210:213], v214 offset:2048
	ds_read_b128 v[214:217], v214 offset:3072
	global_load_lds_dwordx4 v132, s[0:1]
	s_add_i32 m0, s16, 0x2000
	s_nop 0
	global_load_lds_dwordx4 v128, s[0:1]
	s_waitcnt vmcnt(10)
	s_barrier
	s_waitcnt lgkmcnt(0)
	s_setprio 1
	s_waitcnt lgkmcnt(0)
	v_mfma_f32_16x16x32_bf16 v[120:123], v[202:205], v[166:169], v[120:123]
	v_mfma_f32_16x16x32_bf16 v[112:115], v[210:213], v[166:169], v[112:115]
	v_mfma_f32_16x16x32_bf16 v[104:107], v[202:205], v[174:177], v[104:107]
	v_mfma_f32_16x16x32_bf16 v[96:99], v[210:213], v[174:177], v[96:99]
	v_mfma_f32_16x16x32_bf16 v[88:91], v[202:205], v[182:185], v[88:91]
	v_mfma_f32_16x16x32_bf16 v[80:83], v[210:213], v[182:185], v[80:83]
	v_mfma_f32_16x16x32_bf16 v[72:75], v[202:205], v[190:193], v[72:75]
	v_mfma_f32_16x16x32_bf16 v[64:67], v[210:213], v[190:193], v[64:67]
	v_mfma_f32_16x16x32_bf16 v[120:123], v[206:209], v[170:173], v[120:123]
	v_mfma_f32_16x16x32_bf16 v[112:115], v[214:217], v[170:173], v[112:115]
	v_mfma_f32_16x16x32_bf16 v[104:107], v[206:209], v[178:181], v[104:107]
	v_mfma_f32_16x16x32_bf16 v[96:99], v[214:217], v[178:181], v[96:99]
	v_mfma_f32_16x16x32_bf16 v[88:91], v[206:209], v[186:189], v[88:91]
	v_mfma_f32_16x16x32_bf16 v[80:83], v[214:217], v[186:189], v[80:83]
	v_mfma_f32_16x16x32_bf16 v[72:75], v[206:209], v[194:197], v[72:75]
	v_mfma_f32_16x16x32_bf16 v[64:67], v[214:217], v[194:197], v[64:67]
	s_setprio 0
	s_mov_b32 m0, s36
	s_add_u32 s0, s22, 0x80
	s_addc_u32 s1, s23, 0
	s_barrier
	ds_read_b128 v[166:169], v148 offset:49152
	ds_read_b128 v[170:173], v148 offset:50176
	ds_read_b128 v[174:177], v148 offset:51200
	ds_read_b128 v[178:181], v148 offset:52224
	ds_read_b128 v[182:185], v148 offset:53248
	ds_read_b128 v[186:189], v148 offset:54272
	ds_read_b128 v[190:193], v148 offset:55296
	ds_read_b128 v[194:197], v148 offset:56320
	global_load_lds_dwordx4 v134, s[0:1]
	s_mov_b32 m0, s37
	s_nop 0
	global_load_lds_dwordx4 v130, s[0:1]
	s_barrier
	s_waitcnt lgkmcnt(0)
	s_setprio 1
	s_waitcnt lgkmcnt(0)
	v_mfma_f32_16x16x32_bf16 v[60:63], v[150:153], v[166:169], v[60:63]
	v_mfma_f32_16x16x32_bf16 v[56:59], v[158:161], v[166:169], v[56:59]
	v_mfma_f32_16x16x32_bf16 v[44:47], v[150:153], v[174:177], v[44:47]
	v_mfma_f32_16x16x32_bf16 v[40:43], v[158:161], v[174:177], v[40:43]
	v_mfma_f32_16x16x32_bf16 v[28:31], v[150:153], v[182:185], v[28:31]
	v_mfma_f32_16x16x32_bf16 v[24:27], v[158:161], v[182:185], v[24:27]
	v_mfma_f32_16x16x32_bf16 v[12:15], v[150:153], v[190:193], v[12:15]
	v_mfma_f32_16x16x32_bf16 v[8:11], v[158:161], v[190:193], v[8:11]
	v_mfma_f32_16x16x32_bf16 v[60:63], v[154:157], v[170:173], v[60:63]
	v_mfma_f32_16x16x32_bf16 v[56:59], v[162:165], v[170:173], v[56:59]
	v_mfma_f32_16x16x32_bf16 v[44:47], v[154:157], v[178:181], v[44:47]
	v_mfma_f32_16x16x32_bf16 v[40:43], v[162:165], v[178:181], v[40:43]
	v_mfma_f32_16x16x32_bf16 v[28:31], v[154:157], v[186:189], v[28:31]
	v_mfma_f32_16x16x32_bf16 v[24:27], v[162:165], v[186:189], v[24:27]
	v_mfma_f32_16x16x32_bf16 v[12:15], v[154:157], v[194:197], v[12:15]
	v_mfma_f32_16x16x32_bf16 v[8:11], v[162:165], v[194:197], v[8:11]
	s_setprio 0
	s_barrier
	s_add_u32 s16, s18, 0x40080
	s_addc_u32 s17, s19, 0
	s_add_i32 s18, s21, s25
	s_mov_b32 m0, s18
	s_nop 0
	global_load_lds_dwordx4 v132, s[16:17]
	s_add_i32 m0, s18, 0x2000
	s_nop 0
	global_load_lds_dwordx4 v128, s[16:17]
	s_waitcnt vmcnt(10)
	s_barrier
	s_setprio 1
	v_mfma_f32_16x16x32_bf16 v[52:55], v[202:205], v[166:169], v[52:55]
	v_mfma_f32_16x16x32_bf16 v[48:51], v[210:213], v[166:169], v[48:51]
	v_mfma_f32_16x16x32_bf16 v[36:39], v[202:205], v[174:177], v[36:39]
	v_mfma_f32_16x16x32_bf16 v[32:35], v[210:213], v[174:177], v[32:35]
	v_mfma_f32_16x16x32_bf16 v[20:23], v[202:205], v[182:185], v[20:23]
	v_mfma_f32_16x16x32_bf16 v[16:19], v[210:213], v[182:185], v[16:19]
	v_mfma_f32_16x16x32_bf16 v[4:7], v[202:205], v[190:193], v[4:7]
	v_mfma_f32_16x16x32_bf16 v[0:3], v[210:213], v[190:193], v[0:3]
	v_mfma_f32_16x16x32_bf16 v[52:55], v[206:209], v[170:173], v[52:55]
	v_mfma_f32_16x16x32_bf16 v[48:51], v[214:217], v[170:173], v[48:51]
	v_mfma_f32_16x16x32_bf16 v[36:39], v[206:209], v[178:181], v[36:39]
	v_mfma_f32_16x16x32_bf16 v[32:35], v[214:217], v[178:181], v[32:35]
	v_mfma_f32_16x16x32_bf16 v[20:23], v[206:209], v[186:189], v[20:23]
	v_mfma_f32_16x16x32_bf16 v[16:19], v[214:217], v[186:189], v[16:19]
	v_mfma_f32_16x16x32_bf16 v[4:7], v[206:209], v[194:197], v[4:7]
	v_mfma_f32_16x16x32_bf16 v[0:3], v[214:217], v[194:197], v[0:3]
	s_setprio 0
	s_add_i32 s48, s48, 2
	s_add_u32 s14, s14, 0x100
	s_addc_u32 s15, s15, 0
	s_add_u32 s46, s46, 0x100
	s_addc_u32 s47, s47, 0
	s_cmp_gt_u32 s48, 13
	s_barrier
; __device__ __forceinline__ unsigned cvt_pk_bf16(float lo, float hi) { unsigned r; asm volatile("v_cvt_pk_bf16_f32 %0, %1, %2" : "=v"(r) : "v"(lo), "v"(hi)); return r; }
; __device__ __forceinline__ float silu_f(float a) { return a * __builtin_amdgcn_rcpf(1.0f + __expf(-a)); }
;     __device__ __forceinline__ void operator()(const AccT& acc, const Unit& u, int wr, int wc, int fr, int fq) const {
;     ...
;         const int row0 = u.pm * 256 + wr * 64 + fr, hc0 = u.pn * 128 + wc * 32 + 8 * fq;
; #pragma unroll
;         for (int ai = 0; ai < 2; ++ai)
; #pragma unroll
;             for (int m = 0; m < 4; ++m) {
;                 const f32x4 a0 = acc[ai][0][m][0], a1 = acc[ai][0][m][1], b0 = acc[ai][1][m][0], b1 = acc[ai][1][m][1];
;                 u32x4 w;
;                 w.x = cvt_pk_bf16(silu_f(a0[0]) * b0[0], silu_f(a0[1]) * b0[1]); w.y = cvt_pk_bf16(silu_f(a0[2]) * b0[2], silu_f(a0[3]) * b0[3]);
;                 w.z = cvt_pk_bf16(silu_f(a1[0]) * b1[0], silu_f(a1[1]) * b1[1]); w.w = cvt_pk_bf16(silu_f(a1[2]) * b1[2], silu_f(a1[3]) * b1[3]);
;                 *(u32x4*)(H + (size_t)(row0 + ai * 128 + m * 16) * DFF + hc0) = w;
;             }
	s_cbranch_scc0 .LBB0_235
	v_mul_f32_e32 v152, 0xbfb8aa3b, v124
	v_mov_b32_e32 v151, v145
	v_mov_b32_e32 v150, v144
	s_lshl_b32 s5, s12, 8
	v_exp_f32_e32 v153, v152
	v_mul_f32_e32 v152, 0xbfb8aa3b, v125
	s_add_i32 s5, s5, s34
	v_exp_f32_e32 v154, v152
	v_add_u32_e32 v150, s5, v150
	s_lshl_b32 s5, s43, 7
	s_or_b32 s5, s5, s35
	v_lshl_add_u32 v152, v151, 3, s5
	v_add_f32_e32 v151, 1.0, v153
	v_rcp_f32_e32 v151, v151
	v_add_f32_e32 v153, 1.0, v154
	v_rcp_f32_e32 v154, v153
	v_ashrrev_i32_e32 v153, 31, v152
	v_mul_f32_e32 v124, v124, v151
	v_mul_f32_e32 v120, v124, v120
	v_mul_f32_e32 v124, v125, v154
	v_mul_f32_e32 v125, 0xbfb8aa3b, v126
	v_exp_f32_e32 v125, v125
	v_mul_f32_e32 v151, 0xbfb8aa3b, v127
	v_exp_f32_e32 v151, v151
	v_mul_f32_e32 v121, v124, v121
	v_add_f32_e32 v124, 1.0, v125
	v_rcp_f32_e32 v124, v124
	v_add_f32_e32 v125, 1.0, v151
	v_rcp_f32_e32 v125, v125
	v_cvt_pk_bf16_f32 v120, v120, v121
	v_mul_f32_e32 v121, v126, v124
	v_mul_f32_e32 v124, 0xbfb8aa3b, v116
	v_mul_f32_e32 v121, v121, v122
	v_mul_f32_e32 v122, v127, v125
	v_exp_f32_e32 v124, v124
	v_mul_f32_e32 v125, 0xbfb8aa3b, v117
	v_exp_f32_e32 v125, v125
	v_mul_f32_e32 v122, v122, v123
	v_add_f32_e32 v123, 1.0, v124
	v_rcp_f32_e32 v123, v123
	v_add_f32_e32 v124, 1.0, v125
	v_rcp_f32_e32 v124, v124
	v_cvt_pk_bf16_f32 v121, v121, v122
	v_mul_f32_e32 v116, v116, v123
	v_mul_f32_e32 v112, v116, v112
	v_mul_f32_e32 v116, v117, v124
	v_mul_f32_e32 v117, 0xbfb8aa3b, v118
	v_exp_f32_e32 v117, v117
	v_mul_f32_e32 v122, 0xbfb8aa3b, v119
	v_exp_f32_e32 v122, v122
	v_mul_f32_e32 v113, v116, v113
	v_add_f32_e32 v116, 1.0, v117
	v_rcp_f32_e32 v116, v116
	v_add_f32_e32 v117, 1.0, v122
	v_rcp_f32_e32 v117, v117
	v_cvt_pk_bf16_f32 v122, v112, v113
	v_mul_f32_e32 v112, v118, v116
	v_mul_f32_e32 v118, 0xbfb8aa3b, v108
	v_mul_f32_e32 v113, v119, v117
	v_exp_f32_e32 v118, v118
	v_mul_f32_e32 v119, 0xbfb8aa3b, v109
	v_exp_f32_e32 v119, v119
	v_mul_f32_e32 v112, v112, v114
	v_add_f32_e32 v118, 1.0, v118
	v_rcp_f32_e32 v118, v118
	v_add_f32_e32 v119, 1.0, v119
	v_rcp_f32_e32 v119, v119
	v_mul_f32_e32 v113, v113, v115
	v_cvt_pk_bf16_f32 v123, v112, v113
	v_mov_b64_e32 v[112:113], s[82:83]
	v_mad_i64_i32 v[116:117], s[14:15], v150, s42, v[112:113]
	v_lshlrev_b64 v[114:115], 1, v[152:153]
	v_mul_f32_e32 v108, v108, v118
	v_lshl_add_u64 v[116:117], v[116:117], 0, v[114:115]
	v_mul_f32_e32 v104, v108, v104
	v_mul_f32_e32 v108, v109, v119
	v_mul_f32_e32 v109, 0xbfb8aa3b, v110
	global_store_dwordx4 v[116:117], v[120:123], off
	v_exp_f32_e32 v109, v109
	v_mul_f32_e32 v116, 0xbfb8aa3b, v111
	v_exp_f32_e32 v116, v116
	v_mul_f32_e32 v105, v108, v105
	v_add_f32_e32 v108, 1.0, v109
	v_rcp_f32_e32 v108, v108
	v_add_f32_e32 v109, 1.0, v116
	v_rcp_f32_e32 v109, v109
	v_cvt_pk_bf16_f32 v104, v104, v105
	v_mul_f32_e32 v105, v110, v108
	v_mul_f32_e32 v108, 0xbfb8aa3b, v100
	v_mul_f32_e32 v105, v105, v106
	v_mul_f32_e32 v106, v111, v109
	v_exp_f32_e32 v108, v108
	v_mul_f32_e32 v109, 0xbfb8aa3b, v101
	v_exp_f32_e32 v109, v109
	v_mul_f32_e32 v106, v106, v107
	v_add_f32_e32 v107, 1.0, v108
	v_rcp_f32_e32 v107, v107
	v_add_f32_e32 v108, 1.0, v109
	v_rcp_f32_e32 v108, v108
	v_cvt_pk_bf16_f32 v105, v105, v106
	v_mul_f32_e32 v100, v100, v107
	v_mul_f32_e32 v96, v100, v96
	v_mul_f32_e32 v100, v101, v108
	v_mul_f32_e32 v101, 0xbfb8aa3b, v102
	v_exp_f32_e32 v101, v101
	v_mul_f32_e32 v106, 0xbfb8aa3b, v103
	v_exp_f32_e32 v106, v106
	v_mul_f32_e32 v97, v100, v97
	v_add_f32_e32 v100, 1.0, v101
	v_rcp_f32_e32 v100, v100
	v_add_f32_e32 v101, 1.0, v106
	v_rcp_f32_e32 v101, v101
	v_cvt_pk_bf16_f32 v106, v96, v97
	v_mul_f32_e32 v96, v102, v100
	v_mul_f32_e32 v96, v96, v98
	v_mul_f32_e32 v97, v103, v101
	v_mul_f32_e32 v98, 0xbfb8aa3b, v92
	v_mul_f32_e32 v97, v97, v99
	v_exp_f32_e32 v98, v98
	v_mul_f32_e32 v99, 0xbfb8aa3b, v93
	v_exp_f32_e32 v99, v99
	v_cvt_pk_bf16_f32 v107, v96, v97
	v_add_f32_e32 v98, 1.0, v98
	v_rcp_f32_e32 v98, v98
	v_add_f32_e32 v99, 1.0, v99
	v_rcp_f32_e32 v99, v99
	v_add_u32_e32 v96, 16, v150
	v_mad_i64_i32 v[96:97], s[14:15], v96, s42, v[112:113]
	v_mul_f32_e32 v92, v92, v98
	v_lshl_add_u64 v[96:97], v[96:97], 0, v[114:115]
	v_mul_f32_e32 v88, v92, v88
	v_mul_f32_e32 v92, v93, v99
	v_mul_f32_e32 v93, 0xbfb8aa3b, v94
	global_store_dwordx4 v[96:97], v[104:107], off
	v_exp_f32_e32 v93, v93
	v_mul_f32_e32 v96, 0xbfb8aa3b, v95
	v_exp_f32_e32 v96, v96
	v_mul_f32_e32 v89, v92, v89
	v_add_f32_e32 v92, 1.0, v93
	v_rcp_f32_e32 v92, v92
	v_add_f32_e32 v93, 1.0, v96
	v_rcp_f32_e32 v93, v93
	v_cvt_pk_bf16_f32 v88, v88, v89
	v_mul_f32_e32 v89, v94, v92
	v_mul_f32_e32 v92, 0xbfb8aa3b, v84
	v_mul_f32_e32 v89, v89, v90
	v_mul_f32_e32 v90, v95, v93
	v_exp_f32_e32 v92, v92
	v_mul_f32_e32 v93, 0xbfb8aa3b, v85
	v_exp_f32_e32 v93, v93
	v_mul_f32_e32 v90, v90, v91
	v_add_f32_e32 v91, 1.0, v92
	v_rcp_f32_e32 v91, v91
	v_add_f32_e32 v92, 1.0, v93
	v_rcp_f32_e32 v92, v92
	v_cvt_pk_bf16_f32 v89, v89, v90
	v_mul_f32_e32 v84, v84, v91
	v_mul_f32_e32 v80, v84, v80
	v_mul_f32_e32 v84, v85, v92
	v_mul_f32_e32 v85, 0xbfb8aa3b, v86
	v_exp_f32_e32 v85, v85
	v_mul_f32_e32 v90, 0xbfb8aa3b, v87
	v_exp_f32_e32 v90, v90
	v_mul_f32_e32 v81, v84, v81
	v_add_f32_e32 v84, 1.0, v85
	v_rcp_f32_e32 v84, v84
	v_add_f32_e32 v85, 1.0, v90
	v_rcp_f32_e32 v85, v85
	v_cvt_pk_bf16_f32 v90, v80, v81
	v_mul_f32_e32 v80, v86, v84
	v_mul_f32_e32 v80, v80, v82
	v_mul_f32_e32 v81, v87, v85
	v_mul_f32_e32 v82, 0xbfb8aa3b, v76
	v_mul_f32_e32 v81, v81, v83
	v_exp_f32_e32 v82, v82
	v_mul_f32_e32 v83, 0xbfb8aa3b, v77
	v_exp_f32_e32 v83, v83
	v_cvt_pk_bf16_f32 v91, v80, v81
	v_add_f32_e32 v82, 1.0, v82
	v_rcp_f32_e32 v82, v82
	v_add_f32_e32 v83, 1.0, v83
	v_rcp_f32_e32 v83, v83
; __device__ __forceinline__ unsigned cvt_pk_bf16(float lo, float hi) { unsigned r; asm volatile("v_cvt_pk_bf16_f32 %0, %1, %2" : "=v"(r) : "v"(lo), "v"(hi)); return r; }
; __device__ __forceinline__ float silu_f(float a) { return a * __builtin_amdgcn_rcpf(1.0f + __expf(-a)); }
;     __device__ __forceinline__ void operator()(const AccT& acc, const Unit& u, int wr, int wc, int fr, int fq) const {
;     ...
;         const int row0 = u.pm * 256 + wr * 64 + fr, hc0 = u.pn * 128 + wc * 32 + 8 * fq;
; #pragma unroll
;         for (int ai = 0; ai < 2; ++ai)
; #pragma unroll
;             for (int m = 0; m < 4; ++m) {
;                 const f32x4 a0 = acc[ai][0][m][0], a1 = acc[ai][0][m][1], b0 = acc[ai][1][m][0], b1 = acc[ai][1][m][1];
;                 u32x4 w;
;                 w.x = cvt_pk_bf16(silu_f(a0[0]) * b0[0], silu_f(a0[1]) * b0[1]); w.y = cvt_pk_bf16(silu_f(a0[2]) * b0[2], silu_f(a0[3]) * b0[3]);
;                 w.z = cvt_pk_bf16(silu_f(a1[0]) * b1[0], silu_f(a1[1]) * b1[1]); w.w = cvt_pk_bf16(silu_f(a1[2]) * b1[2], silu_f(a1[3]) * b1[3]);
;                 *(u32x4*)(H + (size_t)(row0 + ai * 128 + m * 16) * DFF + hc0) = w;
;             }
	v_add_u32_e32 v80, 32, v150
	v_mad_i64_i32 v[80:81], s[14:15], v80, s42, v[112:113]
	v_mul_f32_e32 v76, v76, v82
	v_lshl_add_u64 v[80:81], v[80:81], 0, v[114:115]
	v_mul_f32_e32 v72, v76, v72
	v_mul_f32_e32 v76, v77, v83
	v_mul_f32_e32 v77, 0xbfb8aa3b, v78
	global_store_dwordx4 v[80:81], v[88:91], off
	v_exp_f32_e32 v77, v77
	v_mul_f32_e32 v80, 0xbfb8aa3b, v79
	v_exp_f32_e32 v80, v80
	v_mul_f32_e32 v73, v76, v73
	v_add_f32_e32 v76, 1.0, v77
	v_rcp_f32_e32 v76, v76
	v_add_f32_e32 v77, 1.0, v80
	v_rcp_f32_e32 v77, v77
	v_cvt_pk_bf16_f32 v72, v72, v73
	v_mul_f32_e32 v73, v78, v76
	v_mul_f32_e32 v76, 0xbfb8aa3b, v68
	v_mul_f32_e32 v73, v73, v74
	v_mul_f32_e32 v74, v79, v77
	v_exp_f32_e32 v76, v76
	v_mul_f32_e32 v77, 0xbfb8aa3b, v69
	v_exp_f32_e32 v77, v77
	v_mul_f32_e32 v74, v74, v75
	v_add_f32_e32 v75, 1.0, v76
	v_rcp_f32_e32 v75, v75
	v_add_f32_e32 v76, 1.0, v77
	v_rcp_f32_e32 v76, v76
	v_cvt_pk_bf16_f32 v73, v73, v74
	v_mul_f32_e32 v68, v68, v75
	v_mul_f32_e32 v64, v68, v64
	v_mul_f32_e32 v68, v69, v76
	v_mul_f32_e32 v69, 0xbfb8aa3b, v70
	v_exp_f32_e32 v69, v69
	v_mul_f32_e32 v74, 0xbfb8aa3b, v71
	v_exp_f32_e32 v74, v74
	v_mul_f32_e32 v65, v68, v65
	v_add_f32_e32 v68, 1.0, v69
	v_rcp_f32_e32 v68, v68
	v_add_f32_e32 v69, 1.0, v74
	v_rcp_f32_e32 v69, v69
	v_cvt_pk_bf16_f32 v74, v64, v65
	v_mul_f32_e32 v64, v70, v68
	v_mul_f32_e32 v64, v64, v66
	v_mul_f32_e32 v65, v71, v69
	v_mul_f32_e32 v66, 0xbfb8aa3b, v60
	v_mul_f32_e32 v65, v65, v67
	v_exp_f32_e32 v66, v66
	v_mul_f32_e32 v67, 0xbfb8aa3b, v61
	v_cvt_pk_bf16_f32 v75, v64, v65
	v_add_u32_e32 v64, 48, v150
	v_exp_f32_e32 v67, v67
	v_mad_i64_i32 v[64:65], s[14:15], v64, s42, v[112:113]
	v_lshl_add_u64 v[64:65], v[64:65], 0, v[114:115]
	global_store_dwordx4 v[64:65], v[72:75], off
	v_add_f32_e32 v64, 1.0, v66
	v_rcp_f32_e32 v64, v64
	v_add_f32_e32 v65, 1.0, v67
	v_rcp_f32_e32 v65, v65
	v_add_u32_e32 v66, 0x80, v150
	v_mul_f32_e32 v60, v60, v64
	v_mul_f32_e32 v52, v60, v52
	v_mul_f32_e32 v60, v61, v65
	v_mul_f32_e32 v61, 0xbfb8aa3b, v62
	v_exp_f32_e32 v61, v61
	v_mul_f32_e32 v64, 0xbfb8aa3b, v63
	v_exp_f32_e32 v64, v64
	v_mul_f32_e32 v53, v60, v53
	v_add_f32_e32 v60, 1.0, v61
	v_rcp_f32_e32 v60, v60
	v_add_f32_e32 v61, 1.0, v64
	v_rcp_f32_e32 v61, v61
	v_cvt_pk_bf16_f32 v52, v52, v53
	v_mul_f32_e32 v53, v62, v60
	v_mul_f32_e32 v60, 0xbfb8aa3b, v56
	v_exp_f32_e32 v60, v60
	v_mul_f32_e32 v53, v53, v54
	v_mul_f32_e32 v54, v63, v61
	v_mul_f32_e32 v61, 0xbfb8aa3b, v57
	v_exp_f32_e32 v61, v61
	v_mul_f32_e32 v54, v54, v55
	v_add_f32_e32 v55, 1.0, v60
	v_rcp_f32_e32 v55, v55
	v_add_f32_e32 v60, 1.0, v61
	v_rcp_f32_e32 v60, v60
	v_cvt_pk_bf16_f32 v53, v53, v54
	v_mul_f32_e32 v54, v56, v55
	v_mul_f32_e32 v55, 0xbfb8aa3b, v58
	v_exp_f32_e32 v55, v55
	v_mul_f32_e32 v56, 0xbfb8aa3b, v59
	v_exp_f32_e32 v56, v56
	v_mul_f32_e32 v48, v54, v48
	v_mul_f32_e32 v54, v57, v60
	v_mul_f32_e32 v49, v54, v49
	v_add_f32_e32 v54, 1.0, v55
	v_rcp_f32_e32 v55, v54
	v_add_f32_e32 v54, 1.0, v56
	v_rcp_f32_e32 v56, v54
	v_cvt_pk_bf16_f32 v54, v48, v49
	v_mul_f32_e32 v48, v58, v55
	v_mul_f32_e32 v48, v48, v50
	v_mul_f32_e32 v49, v59, v56
	v_mul_f32_e32 v50, 0xbfb8aa3b, v44
	v_mul_f32_e32 v49, v49, v51
	v_exp_f32_e32 v50, v50
	v_mul_f32_e32 v51, 0xbfb8aa3b, v45
	v_exp_f32_e32 v51, v51
	v_cvt_pk_bf16_f32 v55, v48, v49
	v_add_f32_e32 v50, 1.0, v50
	v_rcp_f32_e32 v50, v50
	v_add_f32_e32 v51, 1.0, v51
	v_rcp_f32_e32 v51, v51
	v_mad_i64_i32 v[48:49], s[14:15], v66, s42, v[112:113]
	v_mul_f32_e32 v44, v44, v50
	v_mul_f32_e32 v36, v44, v36
	v_mul_f32_e32 v44, v45, v51
	v_mul_f32_e32 v45, 0xbfb8aa3b, v46
	v_exp_f32_e32 v45, v45
	v_lshl_add_u64 v[48:49], v[48:49], 0, v[114:115]
	global_store_dwordx4 v[48:49], v[52:55], off
	v_mul_f32_e32 v48, 0xbfb8aa3b, v47
	v_exp_f32_e32 v48, v48
	v_mul_f32_e32 v37, v44, v37
	v_add_f32_e32 v44, 1.0, v45
	v_rcp_f32_e32 v44, v44
	v_add_f32_e32 v45, 1.0, v48
	v_rcp_f32_e32 v45, v45
	v_cvt_pk_bf16_f32 v36, v36, v37
	v_mul_f32_e32 v37, v46, v44
	v_mul_f32_e32 v44, 0xbfb8aa3b, v40
	v_exp_f32_e32 v44, v44
	v_mul_f32_e32 v37, v37, v38
	v_mul_f32_e32 v38, v47, v45
	v_mul_f32_e32 v45, 0xbfb8aa3b, v41
	v_exp_f32_e32 v45, v45
	v_mul_f32_e32 v38, v38, v39
	v_add_f32_e32 v39, 1.0, v44
	v_rcp_f32_e32 v39, v39
	v_add_f32_e32 v44, 1.0, v45
	v_rcp_f32_e32 v44, v44
; __device__ __forceinline__ unsigned cvt_pk_bf16(float lo, float hi) { unsigned r; asm volatile("v_cvt_pk_bf16_f32 %0, %1, %2" : "=v"(r) : "v"(lo), "v"(hi)); return r; }
; __device__ __forceinline__ float silu_f(float a) { return a * __builtin_amdgcn_rcpf(1.0f + __expf(-a)); }
; #define PG8_WAIT_V(n) asm volatile("s_waitcnt vmcnt(" #n ")" ::: "memory")
; #define PG8_BAR __builtin_amdgcn_s_barrier()
; template <class Epi, class Sched>
; __device__ __forceinline__ void gemm_phase(LAS unsigned char* lds, const Gemm g, const Sched& S, const Epi& E) {
;     ...
;         cur = nxt; cA = nA; cB = nB; ++ui;
;     }
;     PG8_WAIT_V(0);
;     if (wr == 0) PG8_BAR;
;     PG8_BAR;
;     __device__ __forceinline__ void operator()(const AccT& acc, const Unit& u, int wr, int wc, int fr, int fq) const {
;     ...
;         const int row0 = u.pm * 256 + wr * 64 + fr, hc0 = u.pn * 128 + wc * 32 + 8 * fq;
; #pragma unroll
;         for (int ai = 0; ai < 2; ++ai)
; #pragma unroll
;             for (int m = 0; m < 4; ++m) {
;                 const f32x4 a0 = acc[ai][0][m][0], a1 = acc[ai][0][m][1], b0 = acc[ai][1][m][0], b1 = acc[ai][1][m][1];
;                 u32x4 w;
;                 w.x = cvt_pk_bf16(silu_f(a0[0]) * b0[0], silu_f(a0[1]) * b0[1]); w.y = cvt_pk_bf16(silu_f(a0[2]) * b0[2], silu_f(a0[3]) * b0[3]);
;                 w.z = cvt_pk_bf16(silu_f(a1[0]) * b1[0], silu_f(a1[1]) * b1[1]); w.w = cvt_pk_bf16(silu_f(a1[2]) * b1[2], silu_f(a1[3]) * b1[3]);
;                 *(u32x4*)(H + (size_t)(row0 + ai * 128 + m * 16) * DFF + hc0) = w;
;             }
	v_cvt_pk_bf16_f32 v37, v37, v38
	v_mul_f32_e32 v38, v40, v39
	v_mul_f32_e32 v39, 0xbfb8aa3b, v42
	v_exp_f32_e32 v39, v39
	v_mul_f32_e32 v40, 0xbfb8aa3b, v43
	v_exp_f32_e32 v40, v40
	v_mul_f32_e32 v32, v38, v32
	v_mul_f32_e32 v38, v41, v44
	v_mul_f32_e32 v33, v38, v33
	v_add_f32_e32 v38, 1.0, v39
	v_rcp_f32_e32 v39, v38
	v_add_f32_e32 v38, 1.0, v40
	v_rcp_f32_e32 v40, v38
	v_cvt_pk_bf16_f32 v38, v32, v33
	v_mul_f32_e32 v32, v42, v39
	v_mul_f32_e32 v32, v32, v34
	v_mul_f32_e32 v33, v43, v40
	v_mul_f32_e32 v34, 0xbfb8aa3b, v28
	v_mul_f32_e32 v33, v33, v35
	v_exp_f32_e32 v34, v34
	v_mul_f32_e32 v35, 0xbfb8aa3b, v29
	v_exp_f32_e32 v35, v35
	v_cvt_pk_bf16_f32 v39, v32, v33
	v_add_f32_e32 v34, 1.0, v34
	v_rcp_f32_e32 v34, v34
	v_add_f32_e32 v35, 1.0, v35
	v_rcp_f32_e32 v35, v35
	v_add_u32_e32 v32, 0x90, v150
	v_mul_f32_e32 v28, v28, v34
	v_mul_f32_e32 v20, v28, v20
	v_mul_f32_e32 v28, v29, v35
	v_mul_f32_e32 v29, 0xbfb8aa3b, v30
	v_exp_f32_e32 v29, v29
	v_mad_i64_i32 v[32:33], s[14:15], v32, s42, v[112:113]
	v_lshl_add_u64 v[32:33], v[32:33], 0, v[114:115]
	global_store_dwordx4 v[32:33], v[36:39], off
	v_mul_f32_e32 v32, 0xbfb8aa3b, v31
	v_exp_f32_e32 v32, v32
	v_mul_f32_e32 v21, v28, v21
	v_add_f32_e32 v28, 1.0, v29
	v_rcp_f32_e32 v28, v28
	v_add_f32_e32 v29, 1.0, v32
	v_rcp_f32_e32 v29, v29
	v_cvt_pk_bf16_f32 v20, v20, v21
	v_mul_f32_e32 v21, v30, v28
	v_mul_f32_e32 v28, 0xbfb8aa3b, v24
	v_exp_f32_e32 v28, v28
	v_mul_f32_e32 v21, v21, v22
	v_mul_f32_e32 v22, v31, v29
	v_mul_f32_e32 v29, 0xbfb8aa3b, v25
	v_exp_f32_e32 v29, v29
	v_mul_f32_e32 v22, v22, v23
	v_add_f32_e32 v23, 1.0, v28
	v_rcp_f32_e32 v23, v23
	v_add_f32_e32 v28, 1.0, v29
	v_rcp_f32_e32 v28, v28
	v_cvt_pk_bf16_f32 v21, v21, v22
	v_mul_f32_e32 v22, v24, v23
	v_mul_f32_e32 v23, 0xbfb8aa3b, v26
	v_exp_f32_e32 v23, v23
	v_mul_f32_e32 v24, 0xbfb8aa3b, v27
	v_exp_f32_e32 v24, v24
	v_mul_f32_e32 v16, v22, v16
	v_mul_f32_e32 v22, v25, v28
	v_mul_f32_e32 v17, v22, v17
	v_add_f32_e32 v22, 1.0, v23
	v_rcp_f32_e32 v23, v22
	v_add_f32_e32 v22, 1.0, v24
	v_rcp_f32_e32 v24, v22
	v_cvt_pk_bf16_f32 v22, v16, v17
	v_mul_f32_e32 v16, v26, v23
	v_mul_f32_e32 v16, v16, v18
	v_mul_f32_e32 v17, v27, v24
	v_mul_f32_e32 v18, 0xbfb8aa3b, v12
	v_mul_f32_e32 v17, v17, v19
	v_exp_f32_e32 v18, v18
	v_mul_f32_e32 v19, 0xbfb8aa3b, v13
	v_exp_f32_e32 v19, v19
	v_cvt_pk_bf16_f32 v23, v16, v17
	v_add_f32_e32 v18, 1.0, v18
	v_rcp_f32_e32 v18, v18
	v_add_f32_e32 v19, 1.0, v19
	v_rcp_f32_e32 v19, v19
	v_add_u32_e32 v16, 0xa0, v150
	v_mul_f32_e32 v12, v12, v18
	v_mul_f32_e32 v4, v12, v4
	v_mul_f32_e32 v12, v13, v19
	v_mul_f32_e32 v13, 0xbfb8aa3b, v14
	v_exp_f32_e32 v13, v13
	v_mad_i64_i32 v[16:17], s[14:15], v16, s42, v[112:113]
	v_lshl_add_u64 v[16:17], v[16:17], 0, v[114:115]
	global_store_dwordx4 v[16:17], v[20:23], off
	v_mul_f32_e32 v16, 0xbfb8aa3b, v15
	v_exp_f32_e32 v16, v16
	v_mul_f32_e32 v5, v12, v5
	v_add_f32_e32 v12, 1.0, v13
	v_rcp_f32_e32 v12, v12
	v_add_f32_e32 v13, 1.0, v16
	v_rcp_f32_e32 v13, v13
	v_cvt_pk_bf16_f32 v4, v4, v5
	v_mul_f32_e32 v5, v14, v12
	v_mul_f32_e32 v12, 0xbfb8aa3b, v8
	v_exp_f32_e32 v12, v12
	v_mul_f32_e32 v5, v5, v6
	v_mul_f32_e32 v6, v15, v13
	v_mul_f32_e32 v13, 0xbfb8aa3b, v9
	v_exp_f32_e32 v13, v13
	v_mul_f32_e32 v6, v6, v7
	v_add_f32_e32 v7, 1.0, v12
	v_rcp_f32_e32 v7, v7
	v_add_f32_e32 v12, 1.0, v13
	v_rcp_f32_e32 v12, v12
	v_cvt_pk_bf16_f32 v5, v5, v6
	v_mul_f32_e32 v6, v8, v7
	v_mul_f32_e32 v7, 0xbfb8aa3b, v10
	v_exp_f32_e32 v7, v7
	v_mul_f32_e32 v8, 0xbfb8aa3b, v11
	v_exp_f32_e32 v8, v8
	v_mul_f32_e32 v0, v6, v0
	v_mul_f32_e32 v6, v9, v12
	v_mul_f32_e32 v1, v6, v1
	v_add_f32_e32 v6, 1.0, v7
	v_rcp_f32_e32 v7, v6
	v_add_f32_e32 v6, 1.0, v8
	v_rcp_f32_e32 v8, v6
	v_cvt_pk_bf16_f32 v6, v0, v1
	v_mul_f32_e32 v0, v10, v7
	v_mul_f32_e32 v0, v0, v2
	v_mul_f32_e32 v1, v11, v8
	v_mul_f32_e32 v1, v1, v3
	v_cvt_pk_bf16_f32 v7, v0, v1
	v_add_u32_e32 v0, 0xb0, v150
	v_mad_i64_i32 v[0:1], s[14:15], v0, s42, v[112:113]
	v_lshl_add_u64 v[0:1], v[0:1], 0, v[114:115]
	s_and_b64 vcc, exec, s[2:3]
	s_mov_b32 s43, s4
	s_mov_b32 s12, s6
	s_mov_b64 s[18:19], s[10:11]
	s_mov_b64 s[14:15], s[8:9]
	global_store_dwordx4 v[0:1], v[4:7], off
	s_cbranch_vccz .LBB0_232
	s_waitcnt vmcnt(0)
	s_cmpk_gt_u32 s24, 0xff
	s_cbranch_scc1 .LBB0_239
	s_barrier

; #define PG8_STAGE(bufoff, gbase, voff) do { _Pragma("unroll") for (int _i = 0; _i < 2; ++_i) \
;         __builtin_amdgcn_global_load_lds((const unsigned*)((const char*)(gbase) + (voff)[_i]), (LAS unsigned*)(lds + (bufoff) + ldsw + _i * 8192), 16, 0, 0); } while (0)
; #define PG8_LDA(dst, b, h) do { _Pragma("unroll") for (int m = 0; m < 4; ++m) _Pragma("unroll") for (int k = 0; k < 2; ++k) dst[m][k] = *(const LAS bf16x8*)(lds + PG8_SA(b, h) + aoff + m * 2048 + k * 1024); } while (0)
; #define PG8_LDB(dst, b, h) do { _Pragma("unroll") for (int n = 0; n < 2; ++n) _Pragma("unroll") for (int k = 0; k < 2; ++k) dst[n][k] = *(const LAS bf16x8*)(lds + PG8_SB(b, h) + boff + n * 2048 + k * 1024); } while (0)
; #define PG8_WAIT_V(n) asm volatile("s_waitcnt vmcnt(" #n ")" ::: "memory")
; #define PG8_WAIT_L(n) asm volatile("s_waitcnt lgkmcnt(" #n ")" ::: "memory")
; #define PG8_BAR __builtin_amdgcn_s_barrier()
; #define PG8_SCHED __builtin_amdgcn_sched_barrier(0)
; template <class Epi, class Sched>
; __device__ __forceinline__ void gemm_phase(LAS unsigned char* lds, const Gemm g, const Sched& S, const Epi& E) {
;     ...
;         const bool has_next = S.next(ui + 1, nxt);
;         const char* nA = has_next ? (const char*)g.A + (size_t)nxt.pm * tstep : cA; const char* nB = has_next ? (const char*)g.Bt + (size_t)nxt.pn * tstep : cB;
;         for (int t = 0; t < nt; t += 2) {
;             const bool last = (t == nt - 2);
;             const char* a1 = cA + (size_t)(t + 1) * kstep;
;             const char* a2 = last ? nA : cA + (size_t)(t + 2) * kstep; const char* b2 = last ? nB : cB + (size_t)(t + 2) * kstep;
;             const char* a3 = a2 + kstep; const char* b3 = b2 + kstep;
;             PG8_LDB(B0, 0, 0); PG8_SCHED; PG8_LDA(At, 0, 0); PG8_STAGE(PG8_SA(1, 1), a1 + hstep, voffA);
;             PG8_WAIT_L(8); PG8_BAR; PG8_WAIT_L(0); PG8_MMA(0, 0, At, B0); PG8_BAR; PG8_SCHED;
;             PG8_LDB(B1, 0, 1); PG8_STAGE(PG8_SB(0, 0), b2, voffB);
;             PG8_BAR; PG8_WAIT_L(0); PG8_MMA(0, 1, At, B1); PG8_BAR;
;             PG8_LDA(At, 0, 1); PG8_STAGE(PG8_SA(0, 0), a2, voffA);
;             PG8_BAR; PG8_WAIT_L(0); PG8_MMA(1, 0, At, B0); PG8_BAR; PG8_SCHED;
;             PG8_STAGE(PG8_SB(0, 1), b2 + hstep, voffB);
;             PG8_WAIT_V(6); PG8_BAR; PG8_MMA(1, 1, At, B1); PG8_BAR;
.LBB0_304:
	s_add_u32 s0, s28, 0x100
	s_addc_u32 s67, s29, 0
	s_mov_b32 s68, -2
	ds_read_b128 v[144:147], v165
	ds_read_b128 v[148:151], v165 offset:1024
	ds_read_b128 v[152:155], v165 offset:2048
	ds_read_b128 v[156:159], v165 offset:3072
	s_add_u32 s28, s26, 0x100
	s_addc_u32 s29, s27, 0
	s_cmp_eq_u32 s68, 40
	s_cselect_b32 s37, s5, s29
	s_cselect_b32 s36, s4, s28
	s_cselect_b32 s35, s7, s67
	s_cselect_b32 s34, s6, s0
	v_lshl_add_u64 v[160:161], s[26:27], 0, v[136:137]
	s_add_i32 m0, s42, 0xc000
	ds_read_b128 v[168:171], v166
	ds_read_b128 v[172:175], v166 offset:1024
	ds_read_b128 v[176:179], v166 offset:2048
	ds_read_b128 v[180:183], v166 offset:3072
	ds_read_b128 v[184:187], v166 offset:4096
	ds_read_b128 v[188:191], v166 offset:5120
	ds_read_b128 v[192:195], v166 offset:6144
	ds_read_b128 v[196:199], v166 offset:7168
	global_load_lds_dwordx4 v[160:161], off
	v_lshl_add_u64 v[160:161], s[26:27], 0, v[138:139]
	s_add_i32 m0, s42, 0xe000
	s_nop 0
	global_load_lds_dwordx4 v[160:161], off
	s_waitcnt lgkmcnt(8)
	s_waitcnt vmcnt(10)
	s_barrier
	s_waitcnt lgkmcnt(0)
	s_setprio 1
	s_waitcnt lgkmcnt(0)
	v_mfma_f32_16x16x32_bf16 v[124:127], v[144:147], v[168:171], 0
	v_mfma_f32_16x16x32_bf16 v[120:123], v[152:155], v[168:171], 0
	v_mfma_f32_16x16x32_bf16 v[116:119], v[144:147], v[176:179], 0
	v_mfma_f32_16x16x32_bf16 v[104:107], v[152:155], v[176:179], 0
	v_mfma_f32_16x16x32_bf16 v[96:99], v[144:147], v[184:187], 0
	v_mfma_f32_16x16x32_bf16 v[88:91], v[152:155], v[184:187], 0
	v_mfma_f32_16x16x32_bf16 v[80:83], v[144:147], v[192:195], 0
	v_mfma_f32_16x16x32_bf16 v[72:75], v[152:155], v[192:195], 0
	v_mfma_f32_16x16x32_bf16 v[124:127], v[148:151], v[172:175], v[124:127]
	v_mfma_f32_16x16x32_bf16 v[120:123], v[156:159], v[172:175], v[120:123]
	v_mfma_f32_16x16x32_bf16 v[116:119], v[148:151], v[180:183], v[116:119]
	v_mfma_f32_16x16x32_bf16 v[104:107], v[156:159], v[180:183], v[104:107]
	v_mfma_f32_16x16x32_bf16 v[96:99], v[148:151], v[188:191], v[96:99]
	v_mfma_f32_16x16x32_bf16 v[88:91], v[156:159], v[188:191], v[88:91]
	v_mfma_f32_16x16x32_bf16 v[80:83], v[148:151], v[196:199], v[80:83]
	v_mfma_f32_16x16x32_bf16 v[72:75], v[156:159], v[196:199], v[72:75]
	s_setprio 0
	s_barrier
	s_add_i32 s16, s58, s40
	s_mov_b32 m0, s16
	ds_read_b128 v[202:205], v167
	ds_read_b128 v[206:209], v167 offset:1024
	ds_read_b128 v[210:213], v167 offset:2048
	ds_read_b128 v[214:217], v167 offset:3072
	global_load_lds_dwordx4 v132, s[34:35]
	s_add_i32 m0, s16, 0x2000
	s_nop 0
	global_load_lds_dwordx4 v128, s[34:35]
	s_waitcnt vmcnt(10)
	s_barrier
	s_waitcnt lgkmcnt(0)
	s_setprio 1
	s_waitcnt lgkmcnt(0)
	v_mfma_f32_16x16x32_bf16 v[112:115], v[202:205], v[168:171], 0
	v_mfma_f32_16x16x32_bf16 v[108:111], v[210:213], v[168:171], 0
	v_mfma_f32_16x16x32_bf16 v[100:103], v[202:205], v[176:179], 0
	v_mfma_f32_16x16x32_bf16 v[92:95], v[210:213], v[176:179], 0
	v_mfma_f32_16x16x32_bf16 v[84:87], v[202:205], v[184:187], 0
	v_mfma_f32_16x16x32_bf16 v[76:79], v[210:213], v[184:187], 0
	v_mfma_f32_16x16x32_bf16 v[68:71], v[202:205], v[192:195], 0
	v_mfma_f32_16x16x32_bf16 v[64:67], v[210:213], v[192:195], 0
	v_mfma_f32_16x16x32_bf16 v[112:115], v[206:209], v[172:175], v[112:115]
	v_mfma_f32_16x16x32_bf16 v[108:111], v[214:217], v[172:175], v[108:111]
	v_mfma_f32_16x16x32_bf16 v[100:103], v[206:209], v[180:183], v[100:103]
	v_mfma_f32_16x16x32_bf16 v[92:95], v[214:217], v[180:183], v[92:95]
	v_mfma_f32_16x16x32_bf16 v[84:87], v[206:209], v[188:191], v[84:87]
	v_mfma_f32_16x16x32_bf16 v[76:79], v[214:217], v[188:191], v[76:79]
	v_mfma_f32_16x16x32_bf16 v[68:71], v[206:209], v[196:199], v[68:71]
	v_mfma_f32_16x16x32_bf16 v[64:67], v[214:217], v[196:199], v[64:67]
	s_setprio 0
	s_mov_b32 m0, s42
	s_barrier
	ds_read_b128 v[168:171], v166 offset:16384
	ds_read_b128 v[172:175], v166 offset:17408
	ds_read_b128 v[176:179], v166 offset:18432
	ds_read_b128 v[180:183], v166 offset:19456
	ds_read_b128 v[184:187], v166 offset:20480
	ds_read_b128 v[188:191], v166 offset:21504
	ds_read_b128 v[192:195], v166 offset:22528
	ds_read_b128 v[196:199], v166 offset:23552
	global_load_lds_dwordx4 v134, s[36:37]
	s_mov_b32 m0, s43
	s_nop 0
	global_load_lds_dwordx4 v130, s[36:37]
	s_barrier
	s_waitcnt lgkmcnt(0)
	s_setprio 1
	s_waitcnt lgkmcnt(0)
	v_mfma_f32_16x16x32_bf16 v[60:63], v[144:147], v[168:171], 0
	v_mfma_f32_16x16x32_bf16 v[56:59], v[152:155], v[168:171], 0
	v_mfma_f32_16x16x32_bf16 v[48:51], v[144:147], v[176:179], 0
	v_mfma_f32_16x16x32_bf16 v[40:43], v[152:155], v[176:179], 0
	v_mfma_f32_16x16x32_bf16 v[32:35], v[144:147], v[184:187], 0
	v_mfma_f32_16x16x32_bf16 v[24:27], v[152:155], v[184:187], 0
	v_mfma_f32_16x16x32_bf16 v[16:19], v[144:147], v[192:195], 0
	v_mfma_f32_16x16x32_bf16 v[8:11], v[152:155], v[192:195], 0
	v_mfma_f32_16x16x32_bf16 v[60:63], v[148:151], v[172:175], v[60:63]
	v_mfma_f32_16x16x32_bf16 v[56:59], v[156:159], v[172:175], v[56:59]
	v_mfma_f32_16x16x32_bf16 v[48:51], v[148:151], v[180:183], v[48:51]
	v_mfma_f32_16x16x32_bf16 v[40:43], v[156:159], v[180:183], v[40:43]
	v_mfma_f32_16x16x32_bf16 v[32:35], v[148:151], v[188:191], v[32:35]
	v_mfma_f32_16x16x32_bf16 v[24:27], v[156:159], v[188:191], v[24:27]
	v_mfma_f32_16x16x32_bf16 v[16:19], v[148:151], v[196:199], v[16:19]
	v_mfma_f32_16x16x32_bf16 v[8:11], v[156:159], v[196:199], v[8:11]
	s_setprio 0
	s_barrier
	s_add_u32 s16, s34, 0xb0000
	s_addc_u32 s17, s35, 0
	s_add_i32 s20, s59, s40
	s_mov_b32 m0, s20
	s_nop 0
	global_load_lds_dwordx4 v132, s[16:17]
	s_add_i32 m0, s20, 0x2000
	s_nop 0
	global_load_lds_dwordx4 v128, s[16:17]
	s_add_u32 s16, s36, 0xb0000
	s_addc_u32 s17, s37, 0
	s_mov_b32 m0, s44
	s_nop 0
	global_load_lds_dwordx4 v134, s[16:17]
	s_mov_b32 m0, s45
	s_nop 0
	global_load_lds_dwordx4 v130, s[16:17]
	s_waitcnt vmcnt(12)
	s_barrier
; #define PG8_STAGE(bufoff, gbase, voff) do { _Pragma("unroll") for (int _i = 0; _i < 2; ++_i) \
;         __builtin_amdgcn_global_load_lds((const unsigned*)((const char*)(gbase) + (voff)[_i]), (LAS unsigned*)(lds + (bufoff) + ldsw + _i * 8192), 16, 0, 0); } while (0)
; #define PG8_LDA(dst, b, h) do { _Pragma("unroll") for (int m = 0; m < 4; ++m) _Pragma("unroll") for (int k = 0; k < 2; ++k) dst[m][k] = *(const LAS bf16x8*)(lds + PG8_SA(b, h) + aoff + m * 2048 + k * 1024); } while (0)
; #define PG8_LDB(dst, b, h) do { _Pragma("unroll") for (int n = 0; n < 2; ++n) _Pragma("unroll") for (int k = 0; k < 2; ++k) dst[n][k] = *(const LAS bf16x8*)(lds + PG8_SB(b, h) + boff + n * 2048 + k * 1024); } while (0)
; #define PG8_MMA(ai, bj, At, Bt) do { __builtin_amdgcn_s_setprio(1); _Pragma("unroll") for (int m = 0; m < 4; ++m) _Pragma("unroll") for (int n = 0; n < 2; ++n) _Pragma("unroll") for (int k = 0; k < 2; ++k) \
;         acc[ai][bj][m][n] = __builtin_amdgcn_mfma_f32_16x16x32_bf16(Bt[n][k], At[m][k], acc[ai][bj][m][n], 0, 0, 0); __builtin_amdgcn_s_setprio(0); } while (0)
; #define PG8_WAIT_V(n) asm volatile("s_waitcnt vmcnt(" #n ")" ::: "memory")
; #define PG8_WAIT_L(n) asm volatile("s_waitcnt lgkmcnt(" #n ")" ::: "memory")
; #define PG8_BAR __builtin_amdgcn_s_barrier()
; #define PG8_SCHED __builtin_amdgcn_sched_barrier(0)
; template <class Epi, class Sched>
; __device__ __forceinline__ void gemm_phase(LAS unsigned char* lds, const Gemm g, const Sched& S, const Epi& E) {
;     ...
;             PG8_WAIT_V(6); PG8_BAR; PG8_MMA(1, 1, At, B1); PG8_BAR;
;             PG8_LDB(B0, 1, 0); PG8_SCHED; PG8_LDA(At, 1, 0); PG8_STAGE(PG8_SA(0, 1), a2 + hstep, voffA);
;             PG8_WAIT_L(8); PG8_BAR; PG8_WAIT_L(0); PG8_MMA(0, 0, At, B0); PG8_BAR; PG8_SCHED;
;             PG8_LDB(B1, 1, 1); PG8_STAGE(PG8_SB(1, 0), b3, voffB);
;             PG8_BAR; PG8_WAIT_L(0); PG8_MMA(0, 1, At, B1); PG8_BAR;
;             PG8_LDA(At, 1, 1); PG8_STAGE(PG8_SA(1, 0), a3, voffA);
	s_setprio 1
	v_mfma_f32_16x16x32_bf16 v[52:55], v[202:205], v[168:171], 0
	v_mfma_f32_16x16x32_bf16 v[44:47], v[210:213], v[168:171], 0
	v_mfma_f32_16x16x32_bf16 v[36:39], v[202:205], v[176:179], 0
	v_mfma_f32_16x16x32_bf16 v[28:31], v[210:213], v[176:179], 0
	v_mfma_f32_16x16x32_bf16 v[20:23], v[202:205], v[184:187], 0
	v_mfma_f32_16x16x32_bf16 v[12:15], v[210:213], v[184:187], 0
	v_mfma_f32_16x16x32_bf16 v[4:7], v[202:205], v[192:195], 0
	v_mfma_f32_16x16x32_bf16 v[0:3], v[210:213], v[192:195], 0
	v_mfma_f32_16x16x32_bf16 v[52:55], v[206:209], v[172:175], v[52:55]
	v_mfma_f32_16x16x32_bf16 v[44:47], v[214:217], v[172:175], v[44:47]
	v_mfma_f32_16x16x32_bf16 v[36:39], v[206:209], v[180:183], v[36:39]
	v_mfma_f32_16x16x32_bf16 v[28:31], v[214:217], v[180:183], v[28:31]
	v_mfma_f32_16x16x32_bf16 v[20:23], v[206:209], v[188:191], v[20:23]
	v_mfma_f32_16x16x32_bf16 v[12:15], v[214:217], v[188:191], v[12:15]
	v_mfma_f32_16x16x32_bf16 v[4:7], v[206:209], v[196:199], v[4:7]
	v_mfma_f32_16x16x32_bf16 v[0:3], v[214:217], v[196:199], v[0:3]
	s_setprio 0
	s_add_i32 s20, 0, 0x18000
	v_add_u32_e32 v156, s20, v164
	s_barrier
	ds_read_b128 v[144:147], v156
	ds_read_b128 v[148:151], v156 offset:1024
	ds_read_b128 v[152:155], v156 offset:2048
	ds_read_b128 v[156:159], v156 offset:3072
	ds_read_b128 v[168:171], v166 offset:32768
	ds_read_b128 v[172:175], v166 offset:33792
	ds_read_b128 v[176:179], v166 offset:34816
	ds_read_b128 v[180:183], v166 offset:35840
	ds_read_b128 v[184:187], v166 offset:36864
	ds_read_b128 v[188:191], v166 offset:37888
	ds_read_b128 v[192:195], v166 offset:38912
	ds_read_b128 v[196:199], v166 offset:39936
	s_waitcnt lgkmcnt(8)
	s_waitcnt vmcnt(10)
	s_barrier
	s_waitcnt lgkmcnt(0)
	s_setprio 1
	s_waitcnt lgkmcnt(0)
	v_mfma_f32_16x16x32_bf16 v[124:127], v[144:147], v[168:171], v[124:127]
	v_mfma_f32_16x16x32_bf16 v[120:123], v[152:155], v[168:171], v[120:123]
	v_mfma_f32_16x16x32_bf16 v[116:119], v[144:147], v[176:179], v[116:119]
	v_mfma_f32_16x16x32_bf16 v[104:107], v[152:155], v[176:179], v[104:107]
	v_mfma_f32_16x16x32_bf16 v[96:99], v[144:147], v[184:187], v[96:99]
	v_mfma_f32_16x16x32_bf16 v[88:91], v[152:155], v[184:187], v[88:91]
	v_mfma_f32_16x16x32_bf16 v[80:83], v[144:147], v[192:195], v[80:83]
	v_mfma_f32_16x16x32_bf16 v[72:75], v[152:155], v[192:195], v[72:75]
	v_mfma_f32_16x16x32_bf16 v[124:127], v[148:151], v[172:175], v[124:127]
	v_mfma_f32_16x16x32_bf16 v[120:123], v[156:159], v[172:175], v[120:123]
	v_mfma_f32_16x16x32_bf16 v[116:119], v[148:151], v[180:183], v[116:119]
	v_mfma_f32_16x16x32_bf16 v[104:107], v[156:159], v[180:183], v[104:107]
	v_mfma_f32_16x16x32_bf16 v[96:99], v[148:151], v[188:191], v[96:99]
	v_mfma_f32_16x16x32_bf16 v[88:91], v[156:159], v[188:191], v[88:91]
	v_mfma_f32_16x16x32_bf16 v[80:83], v[148:151], v[196:199], v[80:83]
	v_mfma_f32_16x16x32_bf16 v[72:75], v[156:159], v[196:199], v[72:75]
	s_setprio 0
	s_barrier
	s_add_i32 s21, 0, 0x1c000
	s_add_i32 s16, s20, s40
	v_add_u32_e32 v214, s21, v164
	s_add_u32 s8, s34, 0x80
	s_addc_u32 s9, s35, 0
	s_mov_b32 m0, s16
	ds_read_b128 v[202:205], v214
	ds_read_b128 v[206:209], v214 offset:1024
	ds_read_b128 v[210:213], v214 offset:2048
	ds_read_b128 v[214:217], v214 offset:3072
	global_load_lds_dwordx4 v132, s[8:9]
	s_add_i32 m0, s16, 0x2000
	s_nop 0
	global_load_lds_dwordx4 v128, s[8:9]
	s_waitcnt vmcnt(10)
	s_barrier
	s_waitcnt lgkmcnt(0)
	s_setprio 1
	s_waitcnt lgkmcnt(0)
	v_mfma_f32_16x16x32_bf16 v[112:115], v[202:205], v[168:171], v[112:115]
	v_mfma_f32_16x16x32_bf16 v[108:111], v[210:213], v[168:171], v[108:111]
	v_mfma_f32_16x16x32_bf16 v[100:103], v[202:205], v[176:179], v[100:103]
	v_mfma_f32_16x16x32_bf16 v[92:95], v[210:213], v[176:179], v[92:95]
	v_mfma_f32_16x16x32_bf16 v[84:87], v[202:205], v[184:187], v[84:87]
	v_mfma_f32_16x16x32_bf16 v[76:79], v[210:213], v[184:187], v[76:79]
	v_mfma_f32_16x16x32_bf16 v[68:71], v[202:205], v[192:195], v[68:71]
	v_mfma_f32_16x16x32_bf16 v[64:67], v[210:213], v[192:195], v[64:67]
	v_mfma_f32_16x16x32_bf16 v[112:115], v[206:209], v[172:175], v[112:115]
	v_mfma_f32_16x16x32_bf16 v[108:111], v[214:217], v[172:175], v[108:111]
	v_mfma_f32_16x16x32_bf16 v[100:103], v[206:209], v[180:183], v[100:103]
	v_mfma_f32_16x16x32_bf16 v[92:95], v[214:217], v[180:183], v[92:95]
	v_mfma_f32_16x16x32_bf16 v[84:87], v[206:209], v[188:191], v[84:87]
	v_mfma_f32_16x16x32_bf16 v[76:79], v[214:217], v[188:191], v[76:79]
	v_mfma_f32_16x16x32_bf16 v[68:71], v[206:209], v[196:199], v[68:71]
	v_mfma_f32_16x16x32_bf16 v[64:67], v[214:217], v[196:199], v[64:67]
	s_setprio 0
	s_mov_b32 m0, s52
	s_add_u32 s8, s36, 0x80
	s_addc_u32 s9, s37, 0
	s_barrier
	ds_read_b128 v[168:171], v166 offset:49152
	ds_read_b128 v[172:175], v166 offset:50176
	ds_read_b128 v[176:179], v166 offset:51200
	ds_read_b128 v[180:183], v166 offset:52224
	ds_read_b128 v[184:187], v166 offset:53248
	ds_read_b128 v[188:191], v166 offset:54272
	ds_read_b128 v[192:195], v166 offset:55296
	ds_read_b128 v[196:199], v166 offset:56320
	global_load_lds_dwordx4 v134, s[8:9]
	s_mov_b32 m0, s53
	s_nop 0
	global_load_lds_dwordx4 v130, s[8:9]
	s_barrier
; #define PG8_STAGE(bufoff, gbase, voff) do { _Pragma("unroll") for (int _i = 0; _i < 2; ++_i) \
;         __builtin_amdgcn_global_load_lds((const unsigned*)((const char*)(gbase) + (voff)[_i]), (LAS unsigned*)(lds + (bufoff) + ldsw + _i * 8192), 16, 0, 0); } while (0)
; #define PG8_LDA(dst, b, h) do { _Pragma("unroll") for (int m = 0; m < 4; ++m) _Pragma("unroll") for (int k = 0; k < 2; ++k) dst[m][k] = *(const LAS bf16x8*)(lds + PG8_SA(b, h) + aoff + m * 2048 + k * 1024); } while (0)
; #define PG8_LDB(dst, b, h) do { _Pragma("unroll") for (int n = 0; n < 2; ++n) _Pragma("unroll") for (int k = 0; k < 2; ++k) dst[n][k] = *(const LAS bf16x8*)(lds + PG8_SB(b, h) + boff + n * 2048 + k * 1024); } while (0)
; #define PG8_MMA(ai, bj, At, Bt) do { __builtin_amdgcn_s_setprio(1); _Pragma("unroll") for (int m = 0; m < 4; ++m) _Pragma("unroll") for (int n = 0; n < 2; ++n) _Pragma("unroll") for (int k = 0; k < 2; ++k) \
;         acc[ai][bj][m][n] = __builtin_amdgcn_mfma_f32_16x16x32_bf16(Bt[n][k], At[m][k], acc[ai][bj][m][n], 0, 0, 0); __builtin_amdgcn_s_setprio(0); } while (0)
; #define PG8_WAIT_V(n) asm volatile("s_waitcnt vmcnt(" #n ")" ::: "memory")
; #define PG8_WAIT_L(n) asm volatile("s_waitcnt lgkmcnt(" #n ")" ::: "memory")
; #define PG8_BAR __builtin_amdgcn_s_barrier()
; #define PG8_SCHED __builtin_amdgcn_sched_barrier(0)
; template <class Epi, class Sched>
; __device__ __forceinline__ void gemm_phase(LAS unsigned char* lds, const Gemm g, const Sched& S, const Epi& E) {
;     ...
;             PG8_LDB(B0, 0, 0); PG8_SCHED; PG8_LDA(At, 0, 0); PG8_STAGE(PG8_SA(1, 1), a1 + hstep, voffA);
;             PG8_WAIT_L(8); PG8_BAR; PG8_WAIT_L(0); PG8_MMA(0, 0, At, B0); PG8_BAR; PG8_SCHED;
;             PG8_LDB(B1, 0, 1); PG8_STAGE(PG8_SB(0, 0), b2, voffB);
;     ...
;             PG8_BAR; PG8_WAIT_L(0); PG8_MMA(1, 0, At, B0); PG8_BAR; PG8_SCHED;
;             PG8_STAGE(PG8_SB(1, 1), b3 + hstep, voffB);
;             PG8_WAIT_V(6); PG8_BAR; PG8_MMA(1, 1, At, B1); PG8_BAR;
	s_waitcnt lgkmcnt(0)
	s_setprio 1
	s_waitcnt lgkmcnt(0)
	v_mfma_f32_16x16x32_bf16 v[60:63], v[144:147], v[168:171], v[60:63]
	v_mfma_f32_16x16x32_bf16 v[56:59], v[152:155], v[168:171], v[56:59]
	v_mfma_f32_16x16x32_bf16 v[48:51], v[144:147], v[176:179], v[48:51]
	v_mfma_f32_16x16x32_bf16 v[40:43], v[152:155], v[176:179], v[40:43]
	v_mfma_f32_16x16x32_bf16 v[32:35], v[144:147], v[184:187], v[32:35]
	v_mfma_f32_16x16x32_bf16 v[24:27], v[152:155], v[184:187], v[24:27]
	v_mfma_f32_16x16x32_bf16 v[16:19], v[144:147], v[192:195], v[16:19]
	v_mfma_f32_16x16x32_bf16 v[8:11], v[152:155], v[192:195], v[8:11]
	v_mfma_f32_16x16x32_bf16 v[60:63], v[148:151], v[172:175], v[60:63]
	v_mfma_f32_16x16x32_bf16 v[56:59], v[156:159], v[172:175], v[56:59]
	v_mfma_f32_16x16x32_bf16 v[48:51], v[148:151], v[180:183], v[48:51]
	v_mfma_f32_16x16x32_bf16 v[40:43], v[156:159], v[180:183], v[40:43]
	v_mfma_f32_16x16x32_bf16 v[32:35], v[148:151], v[188:191], v[32:35]
	v_mfma_f32_16x16x32_bf16 v[24:27], v[156:159], v[188:191], v[24:27]
	v_mfma_f32_16x16x32_bf16 v[16:19], v[148:151], v[196:199], v[16:19]
	v_mfma_f32_16x16x32_bf16 v[8:11], v[156:159], v[196:199], v[8:11]
	s_setprio 0
	s_barrier
	s_add_u32 s16, s34, 0xb0080
	s_addc_u32 s17, s35, 0
	s_add_i32 s20, s21, s40
	s_mov_b32 m0, s20
	s_nop 0
	global_load_lds_dwordx4 v132, s[16:17]
	s_add_i32 m0, s20, 0x2000
	s_nop 0
	global_load_lds_dwordx4 v128, s[16:17]
	s_waitcnt vmcnt(10)
	s_barrier
	s_setprio 1
	v_mfma_f32_16x16x32_bf16 v[52:55], v[202:205], v[168:171], v[52:55]
	v_mfma_f32_16x16x32_bf16 v[44:47], v[210:213], v[168:171], v[44:47]
	v_mfma_f32_16x16x32_bf16 v[36:39], v[202:205], v[176:179], v[36:39]
	v_mfma_f32_16x16x32_bf16 v[28:31], v[210:213], v[176:179], v[28:31]
	v_mfma_f32_16x16x32_bf16 v[20:23], v[202:205], v[184:187], v[20:23]
	v_mfma_f32_16x16x32_bf16 v[12:15], v[210:213], v[184:187], v[12:15]
	v_mfma_f32_16x16x32_bf16 v[4:7], v[202:205], v[192:195], v[4:7]
	v_mfma_f32_16x16x32_bf16 v[0:3], v[210:213], v[192:195], v[0:3]
	v_mfma_f32_16x16x32_bf16 v[52:55], v[206:209], v[172:175], v[52:55]
	v_mfma_f32_16x16x32_bf16 v[44:47], v[214:217], v[172:175], v[44:47]
	v_mfma_f32_16x16x32_bf16 v[36:39], v[206:209], v[180:183], v[36:39]
	v_mfma_f32_16x16x32_bf16 v[28:31], v[214:217], v[180:183], v[28:31]
	v_mfma_f32_16x16x32_bf16 v[20:23], v[206:209], v[188:191], v[20:23]
	v_mfma_f32_16x16x32_bf16 v[12:15], v[214:217], v[188:191], v[12:15]
	v_mfma_f32_16x16x32_bf16 v[4:7], v[206:209], v[196:199], v[4:7]
	v_mfma_f32_16x16x32_bf16 v[0:3], v[214:217], v[196:199], v[0:3]
	s_setprio 0
	s_add_i32 s68, s68, 2
	s_add_u32 s0, s0, 0x100
	s_addc_u32 s67, s67, 0
	s_cmp_gt_u32 s68, 41
	s_mov_b64 s[26:27], s[28:29]
	s_barrier
.LBB0_305:
	ds_read_b128 v[144:147], v165
	ds_read_b128 v[148:151], v165 offset:1024
	ds_read_b128 v[152:155], v165 offset:2048
	ds_read_b128 v[156:159], v165 offset:3072
	s_add_u32 s28, s26, 0x100
	s_addc_u32 s29, s27, 0
	s_cmp_eq_u32 s68, 40
	s_cselect_b32 s37, s5, s29
	s_cselect_b32 s36, s4, s28
	s_cselect_b32 s35, s7, s67
	s_cselect_b32 s34, s6, s0
	v_lshl_add_u64 v[160:161], s[26:27], 0, v[136:137]
	s_add_i32 m0, s42, 0xc000
	ds_read_b128 v[168:171], v166
	ds_read_b128 v[172:175], v166 offset:1024
	ds_read_b128 v[176:179], v166 offset:2048
	ds_read_b128 v[180:183], v166 offset:3072
	ds_read_b128 v[184:187], v166 offset:4096
	ds_read_b128 v[188:191], v166 offset:5120
	ds_read_b128 v[192:195], v166 offset:6144
	ds_read_b128 v[196:199], v166 offset:7168
	global_load_lds_dwordx4 v[160:161], off
	v_lshl_add_u64 v[160:161], s[26:27], 0, v[138:139]
	s_add_i32 m0, s42, 0xe000
	s_nop 0
	global_load_lds_dwordx4 v[160:161], off
	s_waitcnt lgkmcnt(8)
	s_waitcnt vmcnt(10)
	s_barrier
	s_waitcnt lgkmcnt(0)
	s_setprio 1
	s_waitcnt lgkmcnt(0)
	v_mfma_f32_16x16x32_bf16 v[124:127], v[144:147], v[168:171], v[124:127]
	v_mfma_f32_16x16x32_bf16 v[120:123], v[152:155], v[168:171], v[120:123]
	v_mfma_f32_16x16x32_bf16 v[116:119], v[144:147], v[176:179], v[116:119]
	v_mfma_f32_16x16x32_bf16 v[104:107], v[152:155], v[176:179], v[104:107]
	v_mfma_f32_16x16x32_bf16 v[96:99], v[144:147], v[184:187], v[96:99]
	v_mfma_f32_16x16x32_bf16 v[88:91], v[152:155], v[184:187], v[88:91]
	v_mfma_f32_16x16x32_bf16 v[80:83], v[144:147], v[192:195], v[80:83]
	v_mfma_f32_16x16x32_bf16 v[72:75], v[152:155], v[192:195], v[72:75]
	v_mfma_f32_16x16x32_bf16 v[124:127], v[148:151], v[172:175], v[124:127]
	v_mfma_f32_16x16x32_bf16 v[120:123], v[156:159], v[172:175], v[120:123]
	v_mfma_f32_16x16x32_bf16 v[116:119], v[148:151], v[180:183], v[116:119]
	v_mfma_f32_16x16x32_bf16 v[104:107], v[156:159], v[180:183], v[104:107]
	v_mfma_f32_16x16x32_bf16 v[96:99], v[148:151], v[188:191], v[96:99]
	v_mfma_f32_16x16x32_bf16 v[88:91], v[156:159], v[188:191], v[88:91]
	v_mfma_f32_16x16x32_bf16 v[80:83], v[148:151], v[196:199], v[80:83]
	v_mfma_f32_16x16x32_bf16 v[72:75], v[156:159], v[196:199], v[72:75]
	s_setprio 0
	s_barrier
	s_add_i32 s16, s58, s40
	s_mov_b32 m0, s16
	ds_read_b128 v[202:205], v167
	ds_read_b128 v[206:209], v167 offset:1024
	ds_read_b128 v[210:213], v167 offset:2048
	ds_read_b128 v[214:217], v167 offset:3072
	global_load_lds_dwordx4 v132, s[34:35]
	s_add_i32 m0, s16, 0x2000
	s_nop 0
	global_load_lds_dwordx4 v128, s[34:35]
	s_waitcnt vmcnt(10)
	s_barrier
; #define PG8_STAGE(bufoff, gbase, voff) do { _Pragma("unroll") for (int _i = 0; _i < 2; ++_i) \
;         __builtin_amdgcn_global_load_lds((const unsigned*)((const char*)(gbase) + (voff)[_i]), (LAS unsigned*)(lds + (bufoff) + ldsw + _i * 8192), 16, 0, 0); } while (0)
; #define PG8_LDA(dst, b, h) do { _Pragma("unroll") for (int m = 0; m < 4; ++m) _Pragma("unroll") for (int k = 0; k < 2; ++k) dst[m][k] = *(const LAS bf16x8*)(lds + PG8_SA(b, h) + aoff + m * 2048 + k * 1024); } while (0)
; #define PG8_LDB(dst, b, h) do { _Pragma("unroll") for (int n = 0; n < 2; ++n) _Pragma("unroll") for (int k = 0; k < 2; ++k) dst[n][k] = *(const LAS bf16x8*)(lds + PG8_SB(b, h) + boff + n * 2048 + k * 1024); } while (0)
; #define PG8_MMA(ai, bj, At, Bt) do { __builtin_amdgcn_s_setprio(1); _Pragma("unroll") for (int m = 0; m < 4; ++m) _Pragma("unroll") for (int n = 0; n < 2; ++n) _Pragma("unroll") for (int k = 0; k < 2; ++k) \
;         acc[ai][bj][m][n] = __builtin_amdgcn_mfma_f32_16x16x32_bf16(Bt[n][k], At[m][k], acc[ai][bj][m][n], 0, 0, 0); __builtin_amdgcn_s_setprio(0); } while (0)
; #define PG8_WAIT_V(n) asm volatile("s_waitcnt vmcnt(" #n ")" ::: "memory")
; #define PG8_WAIT_L(n) asm volatile("s_waitcnt lgkmcnt(" #n ")" ::: "memory")
; #define PG8_BAR __builtin_amdgcn_s_barrier()
; #define PG8_SCHED __builtin_amdgcn_sched_barrier(0)
; template <class Epi, class Sched>
; __device__ __forceinline__ void gemm_phase(LAS unsigned char* lds, const Gemm g, const Sched& S, const Epi& E) {
;     ...
;             PG8_BAR; PG8_WAIT_L(0); PG8_MMA(0, 1, At, B1); PG8_BAR;
;             PG8_LDA(At, 0, 1); PG8_STAGE(PG8_SA(0, 0), a2, voffA);
;             PG8_BAR; PG8_WAIT_L(0); PG8_MMA(1, 0, At, B0); PG8_BAR; PG8_SCHED;
;             PG8_STAGE(PG8_SB(0, 1), b2 + hstep, voffB);
;             PG8_WAIT_V(6); PG8_BAR; PG8_MMA(1, 1, At, B1); PG8_BAR;
;             PG8_LDB(B0, 1, 0); PG8_SCHED; PG8_LDA(At, 1, 0); PG8_STAGE(PG8_SA(0, 1), a2 + hstep, voffA);
;             PG8_WAIT_L(8); PG8_BAR; PG8_WAIT_L(0); PG8_MMA(0, 0, At, B0); PG8_BAR; PG8_SCHED;
	s_waitcnt lgkmcnt(0)
	s_setprio 1
	s_waitcnt lgkmcnt(0)
	v_mfma_f32_16x16x32_bf16 v[112:115], v[202:205], v[168:171], v[112:115]
	v_mfma_f32_16x16x32_bf16 v[108:111], v[210:213], v[168:171], v[108:111]
	v_mfma_f32_16x16x32_bf16 v[100:103], v[202:205], v[176:179], v[100:103]
	v_mfma_f32_16x16x32_bf16 v[92:95], v[210:213], v[176:179], v[92:95]
	v_mfma_f32_16x16x32_bf16 v[84:87], v[202:205], v[184:187], v[84:87]
	v_mfma_f32_16x16x32_bf16 v[76:79], v[210:213], v[184:187], v[76:79]
	v_mfma_f32_16x16x32_bf16 v[68:71], v[202:205], v[192:195], v[68:71]
	v_mfma_f32_16x16x32_bf16 v[64:67], v[210:213], v[192:195], v[64:67]
	v_mfma_f32_16x16x32_bf16 v[112:115], v[206:209], v[172:175], v[112:115]
	v_mfma_f32_16x16x32_bf16 v[108:111], v[214:217], v[172:175], v[108:111]
	v_mfma_f32_16x16x32_bf16 v[100:103], v[206:209], v[180:183], v[100:103]
	v_mfma_f32_16x16x32_bf16 v[92:95], v[214:217], v[180:183], v[92:95]
	v_mfma_f32_16x16x32_bf16 v[84:87], v[206:209], v[188:191], v[84:87]
	v_mfma_f32_16x16x32_bf16 v[76:79], v[214:217], v[188:191], v[76:79]
	v_mfma_f32_16x16x32_bf16 v[68:71], v[206:209], v[196:199], v[68:71]
	v_mfma_f32_16x16x32_bf16 v[64:67], v[214:217], v[196:199], v[64:67]
	s_setprio 0
	s_mov_b32 m0, s42
	s_barrier
	ds_read_b128 v[168:171], v166 offset:16384
	ds_read_b128 v[172:175], v166 offset:17408
	ds_read_b128 v[176:179], v166 offset:18432
	ds_read_b128 v[180:183], v166 offset:19456
	ds_read_b128 v[184:187], v166 offset:20480
	ds_read_b128 v[188:191], v166 offset:21504
	ds_read_b128 v[192:195], v166 offset:22528
	ds_read_b128 v[196:199], v166 offset:23552
	global_load_lds_dwordx4 v134, s[36:37]
	s_mov_b32 m0, s43
	s_nop 0
	global_load_lds_dwordx4 v130, s[36:37]
	s_barrier
	s_waitcnt lgkmcnt(0)
	s_setprio 1
	s_waitcnt lgkmcnt(0)
	v_mfma_f32_16x16x32_bf16 v[60:63], v[144:147], v[168:171], v[60:63]
	v_mfma_f32_16x16x32_bf16 v[56:59], v[152:155], v[168:171], v[56:59]
	v_mfma_f32_16x16x32_bf16 v[48:51], v[144:147], v[176:179], v[48:51]
	v_mfma_f32_16x16x32_bf16 v[40:43], v[152:155], v[176:179], v[40:43]
	v_mfma_f32_16x16x32_bf16 v[32:35], v[144:147], v[184:187], v[32:35]
	v_mfma_f32_16x16x32_bf16 v[24:27], v[152:155], v[184:187], v[24:27]
	v_mfma_f32_16x16x32_bf16 v[16:19], v[144:147], v[192:195], v[16:19]
	v_mfma_f32_16x16x32_bf16 v[8:11], v[152:155], v[192:195], v[8:11]
	v_mfma_f32_16x16x32_bf16 v[60:63], v[148:151], v[172:175], v[60:63]
	v_mfma_f32_16x16x32_bf16 v[56:59], v[156:159], v[172:175], v[56:59]
	v_mfma_f32_16x16x32_bf16 v[48:51], v[148:151], v[180:183], v[48:51]
	v_mfma_f32_16x16x32_bf16 v[40:43], v[156:159], v[180:183], v[40:43]
	v_mfma_f32_16x16x32_bf16 v[32:35], v[148:151], v[188:191], v[32:35]
	v_mfma_f32_16x16x32_bf16 v[24:27], v[156:159], v[188:191], v[24:27]
	v_mfma_f32_16x16x32_bf16 v[16:19], v[148:151], v[196:199], v[16:19]
	v_mfma_f32_16x16x32_bf16 v[8:11], v[156:159], v[196:199], v[8:11]
	s_setprio 0
	s_barrier
	s_add_u32 s16, s34, 0xb0000
	s_addc_u32 s17, s35, 0
	s_add_i32 s20, s59, s40
	s_mov_b32 m0, s20
	s_nop 0
	global_load_lds_dwordx4 v132, s[16:17]
	s_add_i32 m0, s20, 0x2000
	s_nop 0
	global_load_lds_dwordx4 v128, s[16:17]
	s_add_u32 s16, s36, 0xb0000
	s_addc_u32 s17, s37, 0
	s_mov_b32 m0, s44
	s_nop 0
	global_load_lds_dwordx4 v134, s[16:17]
	s_mov_b32 m0, s45
	s_nop 0
	global_load_lds_dwordx4 v130, s[16:17]
	s_waitcnt vmcnt(12)
	s_barrier
	s_setprio 1
	v_mfma_f32_16x16x32_bf16 v[52:55], v[202:205], v[168:171], v[52:55]
	v_mfma_f32_16x16x32_bf16 v[44:47], v[210:213], v[168:171], v[44:47]
	v_mfma_f32_16x16x32_bf16 v[36:39], v[202:205], v[176:179], v[36:39]
	v_mfma_f32_16x16x32_bf16 v[28:31], v[210:213], v[176:179], v[28:31]
	v_mfma_f32_16x16x32_bf16 v[20:23], v[202:205], v[184:187], v[20:23]
	v_mfma_f32_16x16x32_bf16 v[12:15], v[210:213], v[184:187], v[12:15]
	v_mfma_f32_16x16x32_bf16 v[4:7], v[202:205], v[192:195], v[4:7]
	v_mfma_f32_16x16x32_bf16 v[0:3], v[210:213], v[192:195], v[0:3]
	v_mfma_f32_16x16x32_bf16 v[52:55], v[206:209], v[172:175], v[52:55]
	v_mfma_f32_16x16x32_bf16 v[44:47], v[214:217], v[172:175], v[44:47]
	v_mfma_f32_16x16x32_bf16 v[36:39], v[206:209], v[180:183], v[36:39]
	v_mfma_f32_16x16x32_bf16 v[28:31], v[214:217], v[180:183], v[28:31]
	v_mfma_f32_16x16x32_bf16 v[20:23], v[206:209], v[188:191], v[20:23]
	v_mfma_f32_16x16x32_bf16 v[12:15], v[214:217], v[188:191], v[12:15]
	v_mfma_f32_16x16x32_bf16 v[4:7], v[206:209], v[196:199], v[4:7]
	v_mfma_f32_16x16x32_bf16 v[0:3], v[214:217], v[196:199], v[0:3]
	s_setprio 0
	s_add_i32 s20, 0, 0x18000
	v_add_u32_e32 v156, s20, v164
	s_barrier
	ds_read_b128 v[144:147], v156
	ds_read_b128 v[148:151], v156 offset:1024
	ds_read_b128 v[152:155], v156 offset:2048
	ds_read_b128 v[156:159], v156 offset:3072
	ds_read_b128 v[168:171], v166 offset:32768
	ds_read_b128 v[172:175], v166 offset:33792
	ds_read_b128 v[176:179], v166 offset:34816
	ds_read_b128 v[180:183], v166 offset:35840
	ds_read_b128 v[184:187], v166 offset:36864
	ds_read_b128 v[188:191], v166 offset:37888
	ds_read_b128 v[192:195], v166 offset:38912
	ds_read_b128 v[196:199], v166 offset:39936
	s_waitcnt lgkmcnt(8)
	s_waitcnt vmcnt(10)
	s_barrier
; #define PG8_STAGE(bufoff, gbase, voff) do { _Pragma("unroll") for (int _i = 0; _i < 2; ++_i) \
;         __builtin_amdgcn_global_load_lds((const unsigned*)((const char*)(gbase) + (voff)[_i]), (LAS unsigned*)(lds + (bufoff) + ldsw + _i * 8192), 16, 0, 0); } while (0)
; #define PG8_LDA(dst, b, h) do { _Pragma("unroll") for (int m = 0; m < 4; ++m) _Pragma("unroll") for (int k = 0; k < 2; ++k) dst[m][k] = *(const LAS bf16x8*)(lds + PG8_SA(b, h) + aoff + m * 2048 + k * 1024); } while (0)
; #define PG8_LDB(dst, b, h) do { _Pragma("unroll") for (int n = 0; n < 2; ++n) _Pragma("unroll") for (int k = 0; k < 2; ++k) dst[n][k] = *(const LAS bf16x8*)(lds + PG8_SB(b, h) + boff + n * 2048 + k * 1024); } while (0)
; #define PG8_MMA(ai, bj, At, Bt) do { __builtin_amdgcn_s_setprio(1); _Pragma("unroll") for (int m = 0; m < 4; ++m) _Pragma("unroll") for (int n = 0; n < 2; ++n) _Pragma("unroll") for (int k = 0; k < 2; ++k) \
;         acc[ai][bj][m][n] = __builtin_amdgcn_mfma_f32_16x16x32_bf16(Bt[n][k], At[m][k], acc[ai][bj][m][n], 0, 0, 0); __builtin_amdgcn_s_setprio(0); } while (0)
; #define PG8_WAIT_V(n) asm volatile("s_waitcnt vmcnt(" #n ")" ::: "memory")
; #define PG8_WAIT_L(n) asm volatile("s_waitcnt lgkmcnt(" #n ")" ::: "memory")
; #define PG8_BAR __builtin_amdgcn_s_barrier()
; #define PG8_SCHED __builtin_amdgcn_sched_barrier(0)
; template <class Epi, class Sched>
; __device__ __forceinline__ void gemm_phase(LAS unsigned char* lds, const Gemm g, const Sched& S, const Epi& E) {
;     ...
;             PG8_WAIT_L(8); PG8_BAR; PG8_WAIT_L(0); PG8_MMA(0, 0, At, B0); PG8_BAR; PG8_SCHED;
;             PG8_LDB(B1, 1, 1); PG8_STAGE(PG8_SB(1, 0), b3, voffB);
;             PG8_BAR; PG8_WAIT_L(0); PG8_MMA(0, 1, At, B1); PG8_BAR;
;             PG8_LDA(At, 1, 1); PG8_STAGE(PG8_SA(1, 0), a3, voffA);
;             PG8_BAR; PG8_WAIT_L(0); PG8_MMA(1, 0, At, B0); PG8_BAR; PG8_SCHED;
;             PG8_STAGE(PG8_SB(1, 1), b3 + hstep, voffB);
;             PG8_WAIT_V(6); PG8_BAR; PG8_MMA(1, 1, At, B1); PG8_BAR;
;     __device__ __forceinline__ void operator()(const AccT& acc, const Unit& u, int wr, int wc, int fr, int fq) const {
;     ...
;         const int rowt = u.pm * 256; const bool isc = rowt >= MX; const int b = isc ? 32 : (rowt >> 11);
;         const float* res = isc ? res_c + (size_t)(rowt - MX) * DM : res_x + (size_t)rowt * DM; bf16_t* out = hb + (size_t)rowt * DM;
	s_waitcnt lgkmcnt(0)
	s_setprio 1
	s_waitcnt lgkmcnt(0)
	v_mfma_f32_16x16x32_bf16 v[124:127], v[144:147], v[168:171], v[124:127]
	v_mfma_f32_16x16x32_bf16 v[120:123], v[152:155], v[168:171], v[120:123]
	v_mfma_f32_16x16x32_bf16 v[116:119], v[144:147], v[176:179], v[116:119]
	v_mfma_f32_16x16x32_bf16 v[104:107], v[152:155], v[176:179], v[104:107]
	v_mfma_f32_16x16x32_bf16 v[96:99], v[144:147], v[184:187], v[96:99]
	v_mfma_f32_16x16x32_bf16 v[88:91], v[152:155], v[184:187], v[88:91]
	v_mfma_f32_16x16x32_bf16 v[80:83], v[144:147], v[192:195], v[80:83]
	v_mfma_f32_16x16x32_bf16 v[72:75], v[152:155], v[192:195], v[72:75]
	v_mfma_f32_16x16x32_bf16 v[124:127], v[148:151], v[172:175], v[124:127]
	v_mfma_f32_16x16x32_bf16 v[120:123], v[156:159], v[172:175], v[120:123]
	v_mfma_f32_16x16x32_bf16 v[116:119], v[148:151], v[180:183], v[116:119]
	v_mfma_f32_16x16x32_bf16 v[104:107], v[156:159], v[180:183], v[104:107]
	v_mfma_f32_16x16x32_bf16 v[96:99], v[148:151], v[188:191], v[96:99]
	v_mfma_f32_16x16x32_bf16 v[88:91], v[156:159], v[188:191], v[88:91]
	v_mfma_f32_16x16x32_bf16 v[80:83], v[148:151], v[196:199], v[80:83]
	v_mfma_f32_16x16x32_bf16 v[72:75], v[156:159], v[196:199], v[72:75]
	s_setprio 0
	s_barrier
	s_add_i32 s21, 0, 0x1c000
	s_add_i32 s16, s20, s40
	v_add_u32_e32 v214, s21, v164
	s_add_u32 s8, s34, 0x80
	s_addc_u32 s9, s35, 0
	s_mov_b32 m0, s16
	ds_read_b128 v[202:205], v214
	ds_read_b128 v[206:209], v214 offset:1024
	ds_read_b128 v[210:213], v214 offset:2048
	ds_read_b128 v[214:217], v214 offset:3072
	global_load_lds_dwordx4 v132, s[8:9]
	s_add_i32 m0, s16, 0x2000
	s_nop 0
	global_load_lds_dwordx4 v128, s[8:9]
	s_waitcnt vmcnt(10)
	s_barrier
	s_waitcnt lgkmcnt(0)
	s_setprio 1
	s_waitcnt lgkmcnt(0)
	v_mfma_f32_16x16x32_bf16 v[112:115], v[202:205], v[168:171], v[112:115]
	v_mfma_f32_16x16x32_bf16 v[108:111], v[210:213], v[168:171], v[108:111]
	v_mfma_f32_16x16x32_bf16 v[100:103], v[202:205], v[176:179], v[100:103]
	v_mfma_f32_16x16x32_bf16 v[92:95], v[210:213], v[176:179], v[92:95]
	v_mfma_f32_16x16x32_bf16 v[84:87], v[202:205], v[184:187], v[84:87]
	v_mfma_f32_16x16x32_bf16 v[76:79], v[210:213], v[184:187], v[76:79]
	v_mfma_f32_16x16x32_bf16 v[68:71], v[202:205], v[192:195], v[68:71]
	v_mfma_f32_16x16x32_bf16 v[64:67], v[210:213], v[192:195], v[64:67]
	v_mfma_f32_16x16x32_bf16 v[112:115], v[206:209], v[172:175], v[112:115]
	v_mfma_f32_16x16x32_bf16 v[108:111], v[214:217], v[172:175], v[108:111]
	v_mfma_f32_16x16x32_bf16 v[100:103], v[206:209], v[180:183], v[100:103]
	v_mfma_f32_16x16x32_bf16 v[92:95], v[214:217], v[180:183], v[92:95]
	v_mfma_f32_16x16x32_bf16 v[84:87], v[206:209], v[188:191], v[84:87]
	v_mfma_f32_16x16x32_bf16 v[76:79], v[214:217], v[188:191], v[76:79]
	v_mfma_f32_16x16x32_bf16 v[68:71], v[206:209], v[196:199], v[68:71]
	v_mfma_f32_16x16x32_bf16 v[64:67], v[214:217], v[196:199], v[64:67]
	s_setprio 0
	s_mov_b32 m0, s52
	s_add_u32 s8, s36, 0x80
	s_addc_u32 s9, s37, 0
	s_barrier
	ds_read_b128 v[168:171], v166 offset:49152
	ds_read_b128 v[172:175], v166 offset:50176
	ds_read_b128 v[176:179], v166 offset:51200
	ds_read_b128 v[180:183], v166 offset:52224
	ds_read_b128 v[184:187], v166 offset:53248
	ds_read_b128 v[188:191], v166 offset:54272
	ds_read_b128 v[192:195], v166 offset:55296
	ds_read_b128 v[196:199], v166 offset:56320
	global_load_lds_dwordx4 v134, s[8:9]
	s_mov_b32 m0, s53
	s_nop 0
	global_load_lds_dwordx4 v130, s[8:9]
	s_barrier
	s_waitcnt lgkmcnt(0)
	s_setprio 1
	s_waitcnt lgkmcnt(0)
	v_mfma_f32_16x16x32_bf16 v[60:63], v[144:147], v[168:171], v[60:63]
	v_mfma_f32_16x16x32_bf16 v[56:59], v[152:155], v[168:171], v[56:59]
	v_mfma_f32_16x16x32_bf16 v[48:51], v[144:147], v[176:179], v[48:51]
	v_mfma_f32_16x16x32_bf16 v[40:43], v[152:155], v[176:179], v[40:43]
	v_mfma_f32_16x16x32_bf16 v[32:35], v[144:147], v[184:187], v[32:35]
	v_mfma_f32_16x16x32_bf16 v[24:27], v[152:155], v[184:187], v[24:27]
	v_mfma_f32_16x16x32_bf16 v[16:19], v[144:147], v[192:195], v[16:19]
	v_mfma_f32_16x16x32_bf16 v[8:11], v[152:155], v[192:195], v[8:11]
	v_mfma_f32_16x16x32_bf16 v[60:63], v[148:151], v[172:175], v[60:63]
	v_mfma_f32_16x16x32_bf16 v[56:59], v[156:159], v[172:175], v[56:59]
	v_mfma_f32_16x16x32_bf16 v[48:51], v[148:151], v[180:183], v[48:51]
	v_mfma_f32_16x16x32_bf16 v[40:43], v[156:159], v[180:183], v[40:43]
	v_mfma_f32_16x16x32_bf16 v[32:35], v[148:151], v[188:191], v[32:35]
	v_mfma_f32_16x16x32_bf16 v[24:27], v[156:159], v[188:191], v[24:27]
	v_mfma_f32_16x16x32_bf16 v[16:19], v[148:151], v[196:199], v[16:19]
	v_mfma_f32_16x16x32_bf16 v[8:11], v[156:159], v[196:199], v[8:11]
	s_setprio 0
	s_barrier
	s_add_u32 s16, s34, 0xb0080
	s_addc_u32 s17, s35, 0
	s_add_i32 s20, s21, s40
	s_mov_b32 m0, s20
	s_nop 0
	global_load_lds_dwordx4 v132, s[16:17]
	s_add_i32 m0, s20, 0x2000
	s_nop 0
	global_load_lds_dwordx4 v128, s[16:17]
	s_waitcnt vmcnt(10)
	s_barrier
	s_setprio 1
	v_mfma_f32_16x16x32_bf16 v[52:55], v[202:205], v[168:171], v[52:55]
	v_mfma_f32_16x16x32_bf16 v[44:47], v[210:213], v[168:171], v[44:47]
	v_mfma_f32_16x16x32_bf16 v[36:39], v[202:205], v[176:179], v[36:39]
	v_mfma_f32_16x16x32_bf16 v[28:31], v[210:213], v[176:179], v[28:31]
	v_mfma_f32_16x16x32_bf16 v[20:23], v[202:205], v[184:187], v[20:23]
	v_mfma_f32_16x16x32_bf16 v[12:15], v[210:213], v[184:187], v[12:15]
	v_mfma_f32_16x16x32_bf16 v[4:7], v[202:205], v[192:195], v[4:7]
	v_mfma_f32_16x16x32_bf16 v[0:3], v[210:213], v[192:195], v[0:3]
	v_mfma_f32_16x16x32_bf16 v[52:55], v[206:209], v[172:175], v[52:55]
	v_mfma_f32_16x16x32_bf16 v[44:47], v[214:217], v[172:175], v[44:47]
	v_mfma_f32_16x16x32_bf16 v[36:39], v[206:209], v[180:183], v[36:39]
	v_mfma_f32_16x16x32_bf16 v[28:31], v[214:217], v[180:183], v[28:31]
	v_mfma_f32_16x16x32_bf16 v[20:23], v[206:209], v[188:191], v[20:23]
	v_mfma_f32_16x16x32_bf16 v[12:15], v[214:217], v[188:191], v[12:15]
	v_mfma_f32_16x16x32_bf16 v[4:7], v[206:209], v[196:199], v[4:7]
	v_mfma_f32_16x16x32_bf16 v[0:3], v[214:217], v[196:199], v[0:3]
	s_setprio 0
	s_add_i32 s68, s68, 2
	s_add_u32 s0, s0, 0x100
	s_addc_u32 s67, s67, 0
	s_cmp_gt_u32 s68, 41
	s_mov_b64 s[26:27], s[28:29]
	s_barrier
	s_cbranch_scc0 .LBB0_305
	s_lshl_b32 s0, s66, 8
	v_mov_b32_e32 v145, v163
	v_mov_b32_e32 v144, v162
	s_cmpk_lt_i32 s66, 0x100
	s_cbranch_scc0 .LBB0_308
	s_ashr_i32 s29, s0, 31
	s_mov_b32 s28, s0
	s_lshl_b64 s[16:17], s[28:29], 12
	v_readlane_b32 s80, v254, 23
	v_readlane_b32 s81, v254, 24
	s_add_u32 s26, s80, s16
	v_readlane_b32 s82, v254, 25
	v_readlane_b32 s83, v254, 26
	v_readlane_b32 s84, v254, 27
	v_readlane_b32 s85, v254, 28
	v_readlane_b32 s86, v254, 29
	v_readlane_b32 s87, v254, 30
	v_readlane_b32 s88, v254, 31
	v_readlane_b32 s89, v254, 32
	v_readlane_b32 s90, v254, 33
	v_readlane_b32 s91, v254, 34
	v_readlane_b32 s92, v254, 35
	v_readlane_b32 s93, v254, 36
	v_readlane_b32 s94, v254, 37
	v_readlane_b32 s95, v254, 38
	s_addc_u32 s27, s81, s17
	s_cbranch_execnz .LBB0_297
	s_branch .LBB0_296

; #define PG8_STAGE(bufoff, gbase, voff) do { _Pragma("unroll") for (int _i = 0; _i < 2; ++_i) \
;         __builtin_amdgcn_global_load_lds((const unsigned*)((const char*)(gbase) + (voff)[_i]), (LAS unsigned*)(lds + (bufoff) + ldsw + _i * 8192), 16, 0, 0); } while (0)
; #define PG8_LDA(dst, b, h) do { _Pragma("unroll") for (int m = 0; m < 4; ++m) _Pragma("unroll") for (int k = 0; k < 2; ++k) dst[m][k] = *(const LAS bf16x8*)(lds + PG8_SA(b, h) + aoff + m * 2048 + k * 1024); } while (0)
; #define PG8_LDB(dst, b, h) do { _Pragma("unroll") for (int n = 0; n < 2; ++n) _Pragma("unroll") for (int k = 0; k < 2; ++k) dst[n][k] = *(const LAS bf16x8*)(lds + PG8_SB(b, h) + boff + n * 2048 + k * 1024); } while (0)
; #define PG8_WAIT_V(n) asm volatile("s_waitcnt vmcnt(" #n ")" ::: "memory")
; #define PG8_WAIT_L(n) asm volatile("s_waitcnt lgkmcnt(" #n ")" ::: "memory")
; #define PG8_BAR __builtin_amdgcn_s_barrier()
; #define PG8_SCHED __builtin_amdgcn_sched_barrier(0)
; template <class Epi, class Sched>
; __device__ __forceinline__ void gemm_phase(LAS unsigned char* lds, const Gemm g, const Sched& S, const Epi& E) {
;     ...
;         const bool has_next = S.next(ui + 1, nxt);
;         const char* nA = has_next ? (const char*)g.A + (size_t)nxt.pm * tstep : cA; const char* nB = has_next ? (const char*)g.Bt + (size_t)nxt.pn * tstep : cB;
;         for (int t = 0; t < nt; t += 2) {
;             const bool last = (t == nt - 2);
;             const char* a1 = cA + (size_t)(t + 1) * kstep;
;             const char* a2 = last ? nA : cA + (size_t)(t + 2) * kstep; const char* b2 = last ? nB : cB + (size_t)(t + 2) * kstep;
;             const char* a3 = a2 + kstep; const char* b3 = b2 + kstep;
;             PG8_LDB(B0, 0, 0); PG8_SCHED; PG8_LDA(At, 0, 0); PG8_STAGE(PG8_SA(1, 1), a1 + hstep, voffA);
;             PG8_WAIT_L(8); PG8_BAR; PG8_WAIT_L(0); PG8_MMA(0, 0, At, B0); PG8_BAR; PG8_SCHED;
;             PG8_LDB(B1, 0, 1); PG8_STAGE(PG8_SB(0, 0), b2, voffB);
;             PG8_BAR; PG8_WAIT_L(0); PG8_MMA(0, 1, At, B1); PG8_BAR;
;             PG8_LDA(At, 0, 1); PG8_STAGE(PG8_SA(0, 0), a2, voffA);
;             PG8_BAR; PG8_WAIT_L(0); PG8_MMA(1, 0, At, B0); PG8_BAR; PG8_SCHED;
;             PG8_STAGE(PG8_SB(0, 1), b2 + hstep, voffB);
;             PG8_WAIT_V(6); PG8_BAR; PG8_MMA(1, 1, At, B1); PG8_BAR;
.LBB0_577:
	s_ashr_i32 s21, s20, 31
	v_cmp_lt_i64_e32 vcc, s[22:23], v[156:157]
	s_lshl_b64 s[22:23], s[20:21], 19
	s_add_u32 s22, s96, s22
	s_addc_u32 s23, s97, s23
	s_and_b64 s[24:25], vcc, exec
	s_cselect_b32 s5, s23, s7
	s_cselect_b32 s21, s22, s6
	s_ashr_i32 s19, s18, 31
	s_lshl_b64 s[24:25], s[18:19], 19
	s_add_u32 s24, s31, s24
	s_addc_u32 s25, s33, s25
	s_and_b64 s[28:29], vcc, exec
	s_cselect_b32 s19, s25, s27
	s_cselect_b32 s53, s24, s26
	s_add_u32 s6, s6, 0x40080
	s_addc_u32 s7, s7, 0
	s_add_u32 s54, s26, 0x100
	s_addc_u32 s55, s27, 0
	s_mov_b32 s56, -2
	s_waitcnt lgkmcnt(0)
	ds_read_b128 v[128:131], v167
	ds_read_b128 v[132:135], v167 offset:1024
	ds_read_b128 v[136:139], v167 offset:2048
	ds_read_b128 v[160:163], v167 offset:3072
	s_add_u32 s26, s6, 0xfffc0080
	s_addc_u32 s27, s7, -1
	s_cmp_eq_u32 s56, 12
	s_cselect_b32 s29, s5, s27
	s_cselect_b32 s28, s21, s26
	s_cselect_b32 s27, s19, s55
	s_cselect_b32 s26, s53, s54
	s_add_i32 m0, s37, 0xc000
	ds_read_b128 v[170:173], v168
	ds_read_b128 v[174:177], v168 offset:1024
	ds_read_b128 v[178:181], v168 offset:2048
	ds_read_b128 v[182:185], v168 offset:3072
	ds_read_b128 v[186:189], v168 offset:4096
	ds_read_b128 v[190:193], v168 offset:5120
	ds_read_b128 v[194:197], v168 offset:6144
	ds_read_b128 v[202:205], v168 offset:7168
	global_load_lds_dwordx4 v152, s[6:7]
	s_add_i32 m0, s37, 0xe000
	s_nop 0
	global_load_lds_dwordx4 v154, s[6:7]
	s_waitcnt lgkmcnt(8)
	s_waitcnt vmcnt(10)
	s_barrier
	s_waitcnt lgkmcnt(0)
	s_setprio 1
	s_waitcnt lgkmcnt(0)
	v_mfma_f32_16x16x32_bf16 v[124:127], v[128:131], v[170:173], 0
	v_mfma_f32_16x16x32_bf16 v[120:123], v[136:139], v[170:173], 0
	v_mfma_f32_16x16x32_bf16 v[108:111], v[128:131], v[178:181], 0
	v_mfma_f32_16x16x32_bf16 v[104:107], v[136:139], v[178:181], 0
	v_mfma_f32_16x16x32_bf16 v[92:95], v[128:131], v[186:189], 0
	v_mfma_f32_16x16x32_bf16 v[88:91], v[136:139], v[186:189], 0
	v_mfma_f32_16x16x32_bf16 v[76:79], v[128:131], v[194:197], 0
	v_mfma_f32_16x16x32_bf16 v[72:75], v[136:139], v[194:197], 0
	v_mfma_f32_16x16x32_bf16 v[124:127], v[132:135], v[174:177], v[124:127]
	v_mfma_f32_16x16x32_bf16 v[120:123], v[160:163], v[174:177], v[120:123]
	v_mfma_f32_16x16x32_bf16 v[108:111], v[132:135], v[182:185], v[108:111]
	v_mfma_f32_16x16x32_bf16 v[104:107], v[160:163], v[182:185], v[104:107]
	v_mfma_f32_16x16x32_bf16 v[92:95], v[132:135], v[190:193], v[92:95]
	v_mfma_f32_16x16x32_bf16 v[88:91], v[160:163], v[190:193], v[88:91]
	v_mfma_f32_16x16x32_bf16 v[76:79], v[132:135], v[202:205], v[76:79]
	v_mfma_f32_16x16x32_bf16 v[72:75], v[160:163], v[202:205], v[72:75]
	s_setprio 0
	s_barrier
	s_add_i32 s57, s48, s34
	s_mov_b32 m0, s57
	ds_read_b128 v[206:209], v169
	ds_read_b128 v[210:213], v169 offset:1024
	ds_read_b128 v[214:217], v169 offset:2048
	ds_read_b128 v[218:221], v169 offset:3072
	global_load_lds_dwordx4 v146, s[26:27]
	s_add_i32 m0, s57, 0x2000
	s_nop 0
	global_load_lds_dwordx4 v142, s[26:27]
	s_waitcnt vmcnt(10)
	s_barrier
	s_waitcnt lgkmcnt(0)
	s_setprio 1
	s_waitcnt lgkmcnt(0)
	v_mfma_f32_16x16x32_bf16 v[116:119], v[206:209], v[170:173], 0
	v_mfma_f32_16x16x32_bf16 v[112:115], v[214:217], v[170:173], 0
	v_mfma_f32_16x16x32_bf16 v[100:103], v[206:209], v[178:181], 0
	v_mfma_f32_16x16x32_bf16 v[96:99], v[214:217], v[178:181], 0
	v_mfma_f32_16x16x32_bf16 v[84:87], v[206:209], v[186:189], 0
	v_mfma_f32_16x16x32_bf16 v[80:83], v[214:217], v[186:189], 0
	v_mfma_f32_16x16x32_bf16 v[68:71], v[206:209], v[194:197], 0
	v_mfma_f32_16x16x32_bf16 v[64:67], v[214:217], v[194:197], 0
	v_mfma_f32_16x16x32_bf16 v[116:119], v[210:213], v[174:177], v[116:119]
	v_mfma_f32_16x16x32_bf16 v[112:115], v[218:221], v[174:177], v[112:115]
	v_mfma_f32_16x16x32_bf16 v[100:103], v[210:213], v[182:185], v[100:103]
	v_mfma_f32_16x16x32_bf16 v[96:99], v[218:221], v[182:185], v[96:99]
	v_mfma_f32_16x16x32_bf16 v[84:87], v[210:213], v[190:193], v[84:87]
	v_mfma_f32_16x16x32_bf16 v[80:83], v[218:221], v[190:193], v[80:83]
	v_mfma_f32_16x16x32_bf16 v[68:71], v[210:213], v[202:205], v[68:71]
	v_mfma_f32_16x16x32_bf16 v[64:67], v[218:221], v[202:205], v[64:67]
	s_setprio 0
	s_mov_b32 m0, s37
	v_lshl_add_u64 v[222:223], s[28:29], 0, v[148:149]
	s_barrier
	ds_read_b128 v[170:173], v168 offset:16384
	ds_read_b128 v[174:177], v168 offset:17408
	ds_read_b128 v[178:181], v168 offset:18432
	ds_read_b128 v[182:185], v168 offset:19456
	ds_read_b128 v[186:189], v168 offset:20480
	ds_read_b128 v[190:193], v168 offset:21504
	ds_read_b128 v[194:197], v168 offset:22528
	ds_read_b128 v[202:205], v168 offset:23552
	global_load_lds_dwordx4 v148, s[28:29]
	v_lshl_add_u64 v[224:225], s[28:29], 0, v[144:145]
	s_mov_b32 m0, s38
	s_nop 0
	global_load_lds_dwordx4 v144, s[28:29]
	s_barrier
	s_waitcnt lgkmcnt(0)
	s_setprio 1
	s_waitcnt lgkmcnt(0)
	v_mfma_f32_16x16x32_bf16 v[60:63], v[128:131], v[170:173], 0
	v_mfma_f32_16x16x32_bf16 v[56:59], v[136:139], v[170:173], 0
	v_mfma_f32_16x16x32_bf16 v[44:47], v[128:131], v[178:181], 0
	v_mfma_f32_16x16x32_bf16 v[40:43], v[136:139], v[178:181], 0
	v_mfma_f32_16x16x32_bf16 v[28:31], v[128:131], v[186:189], 0
	v_mfma_f32_16x16x32_bf16 v[24:27], v[136:139], v[186:189], 0
	v_mfma_f32_16x16x32_bf16 v[12:15], v[128:131], v[194:197], 0
	v_mfma_f32_16x16x32_bf16 v[8:11], v[136:139], v[194:197], 0
	v_mfma_f32_16x16x32_bf16 v[60:63], v[132:135], v[174:177], v[60:63]
	v_mfma_f32_16x16x32_bf16 v[56:59], v[160:163], v[174:177], v[56:59]
	v_mfma_f32_16x16x32_bf16 v[44:47], v[132:135], v[182:185], v[44:47]
	v_mfma_f32_16x16x32_bf16 v[40:43], v[160:163], v[182:185], v[40:43]
	v_mfma_f32_16x16x32_bf16 v[28:31], v[132:135], v[190:193], v[28:31]
	v_mfma_f32_16x16x32_bf16 v[24:27], v[160:163], v[190:193], v[24:27]
	v_mfma_f32_16x16x32_bf16 v[12:15], v[132:135], v[202:205], v[12:15]
	v_mfma_f32_16x16x32_bf16 v[8:11], v[160:163], v[202:205], v[8:11]
	s_setprio 0
	s_barrier
; #define PG8_STAGE(bufoff, gbase, voff) do { _Pragma("unroll") for (int _i = 0; _i < 2; ++_i) \
;         __builtin_amdgcn_global_load_lds((const unsigned*)((const char*)(gbase) + (voff)[_i]), (LAS unsigned*)(lds + (bufoff) + ldsw + _i * 8192), 16, 0, 0); } while (0)
; #define PG8_LDA(dst, b, h) do { _Pragma("unroll") for (int m = 0; m < 4; ++m) _Pragma("unroll") for (int k = 0; k < 2; ++k) dst[m][k] = *(const LAS bf16x8*)(lds + PG8_SA(b, h) + aoff + m * 2048 + k * 1024); } while (0)
; #define PG8_LDB(dst, b, h) do { _Pragma("unroll") for (int n = 0; n < 2; ++n) _Pragma("unroll") for (int k = 0; k < 2; ++k) dst[n][k] = *(const LAS bf16x8*)(lds + PG8_SB(b, h) + boff + n * 2048 + k * 1024); } while (0)
; #define PG8_MMA(ai, bj, At, Bt) do { __builtin_amdgcn_s_setprio(1); _Pragma("unroll") for (int m = 0; m < 4; ++m) _Pragma("unroll") for (int n = 0; n < 2; ++n) _Pragma("unroll") for (int k = 0; k < 2; ++k) \
;         acc[ai][bj][m][n] = __builtin_amdgcn_mfma_f32_16x16x32_bf16(Bt[n][k], At[m][k], acc[ai][bj][m][n], 0, 0, 0); __builtin_amdgcn_s_setprio(0); } while (0)
; #define PG8_WAIT_V(n) asm volatile("s_waitcnt vmcnt(" #n ")" ::: "memory")
; #define PG8_WAIT_L(n) asm volatile("s_waitcnt lgkmcnt(" #n ")" ::: "memory")
; #define PG8_BAR __builtin_amdgcn_s_barrier()
; #define PG8_SCHED __builtin_amdgcn_sched_barrier(0)
; template <class Epi, class Sched>
; __device__ __forceinline__ void gemm_phase(LAS unsigned char* lds, const Gemm g, const Sched& S, const Epi& E) {
;     ...
;             PG8_STAGE(PG8_SB(0, 1), b2 + hstep, voffB);
;             PG8_WAIT_V(6); PG8_BAR; PG8_MMA(1, 1, At, B1); PG8_BAR;
;             PG8_LDB(B0, 1, 0); PG8_SCHED; PG8_LDA(At, 1, 0); PG8_STAGE(PG8_SA(0, 1), a2 + hstep, voffA);
;             PG8_WAIT_L(8); PG8_BAR; PG8_WAIT_L(0); PG8_MMA(0, 0, At, B0); PG8_BAR; PG8_SCHED;
;             PG8_LDB(B1, 1, 1); PG8_STAGE(PG8_SB(1, 0), b3, voffB);
;             PG8_BAR; PG8_WAIT_L(0); PG8_MMA(0, 1, At, B1); PG8_BAR;
;             PG8_LDA(At, 1, 1); PG8_STAGE(PG8_SA(1, 0), a3, voffA);
;             PG8_BAR; PG8_WAIT_L(0); PG8_MMA(1, 0, At, B0); PG8_BAR; PG8_SCHED;
	s_add_u32 s58, s26, 0x40000
	s_addc_u32 s59, s27, 0
	s_add_i32 s57, s49, s34
	s_mov_b32 m0, s57
	s_nop 0
	global_load_lds_dwordx4 v146, s[58:59]
	s_add_i32 m0, s57, 0x2000
	s_nop 0
	global_load_lds_dwordx4 v142, s[58:59]
	s_add_u32 s28, s28, 0x40000
	s_addc_u32 s29, s29, 0
	s_mov_b32 m0, s39
	s_nop 0
	global_load_lds_dwordx4 v148, s[28:29]
	s_mov_b32 m0, s40
	s_nop 0
	global_load_lds_dwordx4 v144, s[28:29]
	s_waitcnt vmcnt(12)
	s_barrier
	s_setprio 1
	v_mfma_f32_16x16x32_bf16 v[52:55], v[206:209], v[170:173], 0
	v_mfma_f32_16x16x32_bf16 v[48:51], v[214:217], v[170:173], 0
	v_mfma_f32_16x16x32_bf16 v[36:39], v[206:209], v[178:181], 0
	v_mfma_f32_16x16x32_bf16 v[32:35], v[214:217], v[178:181], 0
	v_mfma_f32_16x16x32_bf16 v[20:23], v[206:209], v[186:189], 0
	v_mfma_f32_16x16x32_bf16 v[16:19], v[214:217], v[186:189], 0
	v_mfma_f32_16x16x32_bf16 v[4:7], v[206:209], v[194:197], 0
	v_mfma_f32_16x16x32_bf16 v[0:3], v[214:217], v[194:197], 0
	v_mfma_f32_16x16x32_bf16 v[52:55], v[210:213], v[174:177], v[52:55]
	v_mfma_f32_16x16x32_bf16 v[48:51], v[218:221], v[174:177], v[48:51]
	v_mfma_f32_16x16x32_bf16 v[36:39], v[210:213], v[182:185], v[36:39]
	v_mfma_f32_16x16x32_bf16 v[32:35], v[218:221], v[182:185], v[32:35]
	v_mfma_f32_16x16x32_bf16 v[20:23], v[210:213], v[190:193], v[20:23]
	v_mfma_f32_16x16x32_bf16 v[16:19], v[218:221], v[190:193], v[16:19]
	v_mfma_f32_16x16x32_bf16 v[4:7], v[210:213], v[202:205], v[4:7]
	v_mfma_f32_16x16x32_bf16 v[0:3], v[218:221], v[202:205], v[0:3]
	s_setprio 0
	s_add_i32 s57, 0, 0x18000
	v_add_u32_e32 v150, s57, v166
	s_barrier
	ds_read_b128 v[128:131], v150
	ds_read_b128 v[132:135], v150 offset:1024
	ds_read_b128 v[136:139], v150 offset:2048
	ds_read_b128 v[160:163], v150 offset:3072
	ds_read_b128 v[170:173], v168 offset:32768
	ds_read_b128 v[174:177], v168 offset:33792
	ds_read_b128 v[178:181], v168 offset:34816
	ds_read_b128 v[182:185], v168 offset:35840
	ds_read_b128 v[186:189], v168 offset:36864
	ds_read_b128 v[190:193], v168 offset:37888
	ds_read_b128 v[194:197], v168 offset:38912
	ds_read_b128 v[202:205], v168 offset:39936
	s_waitcnt lgkmcnt(8)
	s_waitcnt vmcnt(10)
	s_barrier
	s_waitcnt lgkmcnt(0)
	s_setprio 1
	s_waitcnt lgkmcnt(0)
	v_mfma_f32_16x16x32_bf16 v[124:127], v[128:131], v[170:173], v[124:127]
	v_mfma_f32_16x16x32_bf16 v[120:123], v[136:139], v[170:173], v[120:123]
	v_mfma_f32_16x16x32_bf16 v[108:111], v[128:131], v[178:181], v[108:111]
	v_mfma_f32_16x16x32_bf16 v[104:107], v[136:139], v[178:181], v[104:107]
	v_mfma_f32_16x16x32_bf16 v[92:95], v[128:131], v[186:189], v[92:95]
	v_mfma_f32_16x16x32_bf16 v[88:91], v[136:139], v[186:189], v[88:91]
	v_mfma_f32_16x16x32_bf16 v[76:79], v[128:131], v[194:197], v[76:79]
	v_mfma_f32_16x16x32_bf16 v[72:75], v[136:139], v[194:197], v[72:75]
	v_mfma_f32_16x16x32_bf16 v[124:127], v[132:135], v[174:177], v[124:127]
	v_mfma_f32_16x16x32_bf16 v[120:123], v[160:163], v[174:177], v[120:123]
	v_mfma_f32_16x16x32_bf16 v[108:111], v[132:135], v[182:185], v[108:111]
	v_mfma_f32_16x16x32_bf16 v[104:107], v[160:163], v[182:185], v[104:107]
	v_mfma_f32_16x16x32_bf16 v[92:95], v[132:135], v[190:193], v[92:95]
	v_mfma_f32_16x16x32_bf16 v[88:91], v[160:163], v[190:193], v[88:91]
	v_mfma_f32_16x16x32_bf16 v[76:79], v[132:135], v[202:205], v[76:79]
	v_mfma_f32_16x16x32_bf16 v[72:75], v[160:163], v[202:205], v[72:75]
	s_setprio 0
	s_barrier
	s_add_i32 s28, 0, 0x1c000
	s_add_i32 s29, s57, s34
	v_add_u32_e32 v150, s28, v166
	s_add_u32 s0, s26, 0x80
	s_addc_u32 s1, s27, 0
	s_mov_b32 m0, s29
	ds_read_b128 v[206:209], v150
	ds_read_b128 v[210:213], v150 offset:1024
	ds_read_b128 v[214:217], v150 offset:2048
	ds_read_b128 v[218:221], v150 offset:3072
	global_load_lds_dwordx4 v146, s[0:1]
	s_add_i32 m0, s29, 0x2000
	s_nop 0
	global_load_lds_dwordx4 v142, s[0:1]
	s_waitcnt vmcnt(10)
	s_barrier
	s_waitcnt lgkmcnt(0)
	s_setprio 1
	s_waitcnt lgkmcnt(0)
	v_mfma_f32_16x16x32_bf16 v[116:119], v[206:209], v[170:173], v[116:119]
	v_mfma_f32_16x16x32_bf16 v[112:115], v[214:217], v[170:173], v[112:115]
	v_mfma_f32_16x16x32_bf16 v[100:103], v[206:209], v[178:181], v[100:103]
	v_mfma_f32_16x16x32_bf16 v[96:99], v[214:217], v[178:181], v[96:99]
	v_mfma_f32_16x16x32_bf16 v[84:87], v[206:209], v[186:189], v[84:87]
	v_mfma_f32_16x16x32_bf16 v[80:83], v[214:217], v[186:189], v[80:83]
	v_mfma_f32_16x16x32_bf16 v[68:71], v[206:209], v[194:197], v[68:71]
	v_mfma_f32_16x16x32_bf16 v[64:67], v[214:217], v[194:197], v[64:67]
	v_mfma_f32_16x16x32_bf16 v[116:119], v[210:213], v[174:177], v[116:119]
	v_mfma_f32_16x16x32_bf16 v[112:115], v[218:221], v[174:177], v[112:115]
	v_mfma_f32_16x16x32_bf16 v[100:103], v[210:213], v[182:185], v[100:103]
	v_mfma_f32_16x16x32_bf16 v[96:99], v[218:221], v[182:185], v[96:99]
	v_mfma_f32_16x16x32_bf16 v[84:87], v[210:213], v[190:193], v[84:87]
	v_mfma_f32_16x16x32_bf16 v[80:83], v[218:221], v[190:193], v[80:83]
	v_mfma_f32_16x16x32_bf16 v[68:71], v[210:213], v[202:205], v[68:71]
	v_mfma_f32_16x16x32_bf16 v[64:67], v[218:221], v[202:205], v[64:67]
	s_setprio 0
	s_mov_b32 m0, s44
	s_mov_b64 s[0:1], 0x80
	v_lshl_add_u64 v[140:141], v[222:223], 0, s[0:1]
	s_barrier
	ds_read_b128 v[170:173], v168 offset:49152
	ds_read_b128 v[174:177], v168 offset:50176
	ds_read_b128 v[178:181], v168 offset:51200
	ds_read_b128 v[182:185], v168 offset:52224
	ds_read_b128 v[186:189], v168 offset:53248
	ds_read_b128 v[190:193], v168 offset:54272
	ds_read_b128 v[194:197], v168 offset:55296
	ds_read_b128 v[202:205], v168 offset:56320
	global_load_lds_dwordx4 v[140:141], off
	v_lshl_add_u64 v[140:141], v[224:225], 0, s[0:1]
	s_mov_b32 m0, s45
	s_nop 0
	global_load_lds_dwordx4 v[140:141], off
	s_barrier
; #define PG8_STAGE(bufoff, gbase, voff) do { _Pragma("unroll") for (int _i = 0; _i < 2; ++_i) \
;         __builtin_amdgcn_global_load_lds((const unsigned*)((const char*)(gbase) + (voff)[_i]), (LAS unsigned*)(lds + (bufoff) + ldsw + _i * 8192), 16, 0, 0); } while (0)
; #define PG8_LDA(dst, b, h) do { _Pragma("unroll") for (int m = 0; m < 4; ++m) _Pragma("unroll") for (int k = 0; k < 2; ++k) dst[m][k] = *(const LAS bf16x8*)(lds + PG8_SA(b, h) + aoff + m * 2048 + k * 1024); } while (0)
; #define PG8_LDB(dst, b, h) do { _Pragma("unroll") for (int n = 0; n < 2; ++n) _Pragma("unroll") for (int k = 0; k < 2; ++k) dst[n][k] = *(const LAS bf16x8*)(lds + PG8_SB(b, h) + boff + n * 2048 + k * 1024); } while (0)
; #define PG8_MMA(ai, bj, At, Bt) do { __builtin_amdgcn_s_setprio(1); _Pragma("unroll") for (int m = 0; m < 4; ++m) _Pragma("unroll") for (int n = 0; n < 2; ++n) _Pragma("unroll") for (int k = 0; k < 2; ++k) \
;         acc[ai][bj][m][n] = __builtin_amdgcn_mfma_f32_16x16x32_bf16(Bt[n][k], At[m][k], acc[ai][bj][m][n], 0, 0, 0); __builtin_amdgcn_s_setprio(0); } while (0)
; #define PG8_WAIT_V(n) asm volatile("s_waitcnt vmcnt(" #n ")" ::: "memory")
; #define PG8_WAIT_L(n) asm volatile("s_waitcnt lgkmcnt(" #n ")" ::: "memory")
; #define PG8_BAR __builtin_amdgcn_s_barrier()
; #define PG8_SCHED __builtin_amdgcn_sched_barrier(0)
; template <class Epi, class Sched>
; __device__ __forceinline__ void gemm_phase(LAS unsigned char* lds, const Gemm g, const Sched& S, const Epi& E) {
;     ...
;             PG8_LDB(B0, 0, 0); PG8_SCHED; PG8_LDA(At, 0, 0); PG8_STAGE(PG8_SA(1, 1), a1 + hstep, voffA);
;             PG8_WAIT_L(8); PG8_BAR; PG8_WAIT_L(0); PG8_MMA(0, 0, At, B0); PG8_BAR; PG8_SCHED;
;             PG8_LDB(B1, 0, 1); PG8_STAGE(PG8_SB(0, 0), b2, voffB);
;     ...
;             PG8_BAR; PG8_WAIT_L(0); PG8_MMA(1, 0, At, B0); PG8_BAR; PG8_SCHED;
;             PG8_STAGE(PG8_SB(1, 1), b3 + hstep, voffB);
;             PG8_WAIT_V(6); PG8_BAR; PG8_MMA(1, 1, At, B1); PG8_BAR;
	s_waitcnt lgkmcnt(0)
	s_setprio 1
	s_waitcnt lgkmcnt(0)
	v_mfma_f32_16x16x32_bf16 v[60:63], v[128:131], v[170:173], v[60:63]
	v_mfma_f32_16x16x32_bf16 v[56:59], v[136:139], v[170:173], v[56:59]
	v_mfma_f32_16x16x32_bf16 v[44:47], v[128:131], v[178:181], v[44:47]
	v_mfma_f32_16x16x32_bf16 v[40:43], v[136:139], v[178:181], v[40:43]
	v_mfma_f32_16x16x32_bf16 v[28:31], v[128:131], v[186:189], v[28:31]
	v_mfma_f32_16x16x32_bf16 v[24:27], v[136:139], v[186:189], v[24:27]
	v_mfma_f32_16x16x32_bf16 v[12:15], v[128:131], v[194:197], v[12:15]
	v_mfma_f32_16x16x32_bf16 v[8:11], v[136:139], v[194:197], v[8:11]
	v_mfma_f32_16x16x32_bf16 v[60:63], v[132:135], v[174:177], v[60:63]
	v_mfma_f32_16x16x32_bf16 v[56:59], v[160:163], v[174:177], v[56:59]
	v_mfma_f32_16x16x32_bf16 v[44:47], v[132:135], v[182:185], v[44:47]
	v_mfma_f32_16x16x32_bf16 v[40:43], v[160:163], v[182:185], v[40:43]
	v_mfma_f32_16x16x32_bf16 v[28:31], v[132:135], v[190:193], v[28:31]
	v_mfma_f32_16x16x32_bf16 v[24:27], v[160:163], v[190:193], v[24:27]
	v_mfma_f32_16x16x32_bf16 v[12:15], v[132:135], v[202:205], v[12:15]
	v_mfma_f32_16x16x32_bf16 v[8:11], v[160:163], v[202:205], v[8:11]
	s_setprio 0
	s_barrier
	s_add_u32 s26, s26, 0x40080
	s_addc_u32 s27, s27, 0
	s_add_i32 s28, s28, s34
	s_mov_b32 m0, s28
	s_nop 0
	global_load_lds_dwordx4 v146, s[26:27]
	s_add_i32 m0, s28, 0x2000
	s_nop 0
	global_load_lds_dwordx4 v142, s[26:27]
	s_waitcnt vmcnt(10)
	s_barrier
	s_setprio 1
	v_mfma_f32_16x16x32_bf16 v[52:55], v[206:209], v[170:173], v[52:55]
	v_mfma_f32_16x16x32_bf16 v[48:51], v[214:217], v[170:173], v[48:51]
	v_mfma_f32_16x16x32_bf16 v[36:39], v[206:209], v[178:181], v[36:39]
	v_mfma_f32_16x16x32_bf16 v[32:35], v[214:217], v[178:181], v[32:35]
	v_mfma_f32_16x16x32_bf16 v[20:23], v[206:209], v[186:189], v[20:23]
	v_mfma_f32_16x16x32_bf16 v[16:19], v[214:217], v[186:189], v[16:19]
	v_mfma_f32_16x16x32_bf16 v[4:7], v[206:209], v[194:197], v[4:7]
	v_mfma_f32_16x16x32_bf16 v[0:3], v[214:217], v[194:197], v[0:3]
	v_mfma_f32_16x16x32_bf16 v[52:55], v[210:213], v[174:177], v[52:55]
	v_mfma_f32_16x16x32_bf16 v[48:51], v[218:221], v[174:177], v[48:51]
	v_mfma_f32_16x16x32_bf16 v[36:39], v[210:213], v[182:185], v[36:39]
	v_mfma_f32_16x16x32_bf16 v[32:35], v[218:221], v[182:185], v[32:35]
	v_mfma_f32_16x16x32_bf16 v[20:23], v[210:213], v[190:193], v[20:23]
	v_mfma_f32_16x16x32_bf16 v[16:19], v[218:221], v[190:193], v[16:19]
	v_mfma_f32_16x16x32_bf16 v[4:7], v[210:213], v[202:205], v[4:7]
	v_mfma_f32_16x16x32_bf16 v[0:3], v[218:221], v[202:205], v[0:3]
	s_setprio 0
	s_add_i32 s56, s56, 2
	s_add_u32 s6, s6, 0x100
	s_addc_u32 s7, s7, 0
	s_add_u32 s54, s54, 0x100
	s_addc_u32 s55, s55, 0
	s_cmp_gt_u32 s56, 13
	s_barrier
.LBB0_578:
	ds_read_b128 v[128:131], v167
	ds_read_b128 v[132:135], v167 offset:1024
	ds_read_b128 v[136:139], v167 offset:2048
	ds_read_b128 v[160:163], v167 offset:3072
	s_add_u32 s26, s6, 0xfffc0080
	s_addc_u32 s27, s7, -1
	s_cmp_eq_u32 s56, 12
	s_cselect_b32 s29, s5, s27
	s_cselect_b32 s28, s21, s26
	s_cselect_b32 s27, s19, s55
	s_cselect_b32 s26, s53, s54
	s_add_i32 m0, s37, 0xc000
	ds_read_b128 v[170:173], v168
	ds_read_b128 v[174:177], v168 offset:1024
	ds_read_b128 v[178:181], v168 offset:2048
	ds_read_b128 v[182:185], v168 offset:3072
	ds_read_b128 v[186:189], v168 offset:4096
	ds_read_b128 v[190:193], v168 offset:5120
	ds_read_b128 v[194:197], v168 offset:6144
	ds_read_b128 v[202:205], v168 offset:7168
	global_load_lds_dwordx4 v152, s[6:7]
	s_add_i32 m0, s37, 0xe000
	s_nop 0
	global_load_lds_dwordx4 v154, s[6:7]
	s_waitcnt lgkmcnt(8)
	s_waitcnt vmcnt(10)
	s_barrier
	s_waitcnt lgkmcnt(0)
	s_setprio 1
	s_waitcnt lgkmcnt(0)
	v_mfma_f32_16x16x32_bf16 v[124:127], v[128:131], v[170:173], v[124:127]
	v_mfma_f32_16x16x32_bf16 v[120:123], v[136:139], v[170:173], v[120:123]
	v_mfma_f32_16x16x32_bf16 v[108:111], v[128:131], v[178:181], v[108:111]
	v_mfma_f32_16x16x32_bf16 v[104:107], v[136:139], v[178:181], v[104:107]
	v_mfma_f32_16x16x32_bf16 v[92:95], v[128:131], v[186:189], v[92:95]
	v_mfma_f32_16x16x32_bf16 v[88:91], v[136:139], v[186:189], v[88:91]
	v_mfma_f32_16x16x32_bf16 v[76:79], v[128:131], v[194:197], v[76:79]
	v_mfma_f32_16x16x32_bf16 v[72:75], v[136:139], v[194:197], v[72:75]
	v_mfma_f32_16x16x32_bf16 v[124:127], v[132:135], v[174:177], v[124:127]
	v_mfma_f32_16x16x32_bf16 v[120:123], v[160:163], v[174:177], v[120:123]
	v_mfma_f32_16x16x32_bf16 v[108:111], v[132:135], v[182:185], v[108:111]
	v_mfma_f32_16x16x32_bf16 v[104:107], v[160:163], v[182:185], v[104:107]
	v_mfma_f32_16x16x32_bf16 v[92:95], v[132:135], v[190:193], v[92:95]
	v_mfma_f32_16x16x32_bf16 v[88:91], v[160:163], v[190:193], v[88:91]
	v_mfma_f32_16x16x32_bf16 v[76:79], v[132:135], v[202:205], v[76:79]
	v_mfma_f32_16x16x32_bf16 v[72:75], v[160:163], v[202:205], v[72:75]
	s_setprio 0
	s_barrier
	s_add_i32 s57, s48, s34
	s_mov_b32 m0, s57
	ds_read_b128 v[206:209], v169
	ds_read_b128 v[210:213], v169 offset:1024
	ds_read_b128 v[214:217], v169 offset:2048
	ds_read_b128 v[218:221], v169 offset:3072
	global_load_lds_dwordx4 v146, s[26:27]
	s_add_i32 m0, s57, 0x2000
	s_nop 0
	global_load_lds_dwordx4 v142, s[26:27]
	s_waitcnt vmcnt(10)
	s_barrier
; #define PG8_STAGE(bufoff, gbase, voff) do { _Pragma("unroll") for (int _i = 0; _i < 2; ++_i) \
;         __builtin_amdgcn_global_load_lds((const unsigned*)((const char*)(gbase) + (voff)[_i]), (LAS unsigned*)(lds + (bufoff) + ldsw + _i * 8192), 16, 0, 0); } while (0)
; #define PG8_LDA(dst, b, h) do { _Pragma("unroll") for (int m = 0; m < 4; ++m) _Pragma("unroll") for (int k = 0; k < 2; ++k) dst[m][k] = *(const LAS bf16x8*)(lds + PG8_SA(b, h) + aoff + m * 2048 + k * 1024); } while (0)
; #define PG8_LDB(dst, b, h) do { _Pragma("unroll") for (int n = 0; n < 2; ++n) _Pragma("unroll") for (int k = 0; k < 2; ++k) dst[n][k] = *(const LAS bf16x8*)(lds + PG8_SB(b, h) + boff + n * 2048 + k * 1024); } while (0)
; #define PG8_MMA(ai, bj, At, Bt) do { __builtin_amdgcn_s_setprio(1); _Pragma("unroll") for (int m = 0; m < 4; ++m) _Pragma("unroll") for (int n = 0; n < 2; ++n) _Pragma("unroll") for (int k = 0; k < 2; ++k) \
;         acc[ai][bj][m][n] = __builtin_amdgcn_mfma_f32_16x16x32_bf16(Bt[n][k], At[m][k], acc[ai][bj][m][n], 0, 0, 0); __builtin_amdgcn_s_setprio(0); } while (0)
; #define PG8_WAIT_V(n) asm volatile("s_waitcnt vmcnt(" #n ")" ::: "memory")
; #define PG8_WAIT_L(n) asm volatile("s_waitcnt lgkmcnt(" #n ")" ::: "memory")
; #define PG8_BAR __builtin_amdgcn_s_barrier()
; #define PG8_SCHED __builtin_amdgcn_sched_barrier(0)
; template <class Epi, class Sched>
; __device__ __forceinline__ void gemm_phase(LAS unsigned char* lds, const Gemm g, const Sched& S, const Epi& E) {
;     ...
;             PG8_BAR; PG8_WAIT_L(0); PG8_MMA(0, 1, At, B1); PG8_BAR;
;             PG8_LDA(At, 0, 1); PG8_STAGE(PG8_SA(0, 0), a2, voffA);
;             PG8_BAR; PG8_WAIT_L(0); PG8_MMA(1, 0, At, B0); PG8_BAR; PG8_SCHED;
;             PG8_STAGE(PG8_SB(0, 1), b2 + hstep, voffB);
;             PG8_WAIT_V(6); PG8_BAR; PG8_MMA(1, 1, At, B1); PG8_BAR;
;             PG8_LDB(B0, 1, 0); PG8_SCHED; PG8_LDA(At, 1, 0); PG8_STAGE(PG8_SA(0, 1), a2 + hstep, voffA);
;             PG8_WAIT_L(8); PG8_BAR; PG8_WAIT_L(0); PG8_MMA(0, 0, At, B0); PG8_BAR; PG8_SCHED;
	s_waitcnt lgkmcnt(0)
	s_setprio 1
	s_waitcnt lgkmcnt(0)
	v_mfma_f32_16x16x32_bf16 v[116:119], v[206:209], v[170:173], v[116:119]
	v_mfma_f32_16x16x32_bf16 v[112:115], v[214:217], v[170:173], v[112:115]
	v_mfma_f32_16x16x32_bf16 v[100:103], v[206:209], v[178:181], v[100:103]
	v_mfma_f32_16x16x32_bf16 v[96:99], v[214:217], v[178:181], v[96:99]
	v_mfma_f32_16x16x32_bf16 v[84:87], v[206:209], v[186:189], v[84:87]
	v_mfma_f32_16x16x32_bf16 v[80:83], v[214:217], v[186:189], v[80:83]
	v_mfma_f32_16x16x32_bf16 v[68:71], v[206:209], v[194:197], v[68:71]
	v_mfma_f32_16x16x32_bf16 v[64:67], v[214:217], v[194:197], v[64:67]
	v_mfma_f32_16x16x32_bf16 v[116:119], v[210:213], v[174:177], v[116:119]
	v_mfma_f32_16x16x32_bf16 v[112:115], v[218:221], v[174:177], v[112:115]
	v_mfma_f32_16x16x32_bf16 v[100:103], v[210:213], v[182:185], v[100:103]
	v_mfma_f32_16x16x32_bf16 v[96:99], v[218:221], v[182:185], v[96:99]
	v_mfma_f32_16x16x32_bf16 v[84:87], v[210:213], v[190:193], v[84:87]
	v_mfma_f32_16x16x32_bf16 v[80:83], v[218:221], v[190:193], v[80:83]
	v_mfma_f32_16x16x32_bf16 v[68:71], v[210:213], v[202:205], v[68:71]
	v_mfma_f32_16x16x32_bf16 v[64:67], v[218:221], v[202:205], v[64:67]
	s_setprio 0
	s_mov_b32 m0, s37
	v_lshl_add_u64 v[222:223], s[28:29], 0, v[148:149]
	s_barrier
	ds_read_b128 v[170:173], v168 offset:16384
	ds_read_b128 v[174:177], v168 offset:17408
	ds_read_b128 v[178:181], v168 offset:18432
	ds_read_b128 v[182:185], v168 offset:19456
	ds_read_b128 v[186:189], v168 offset:20480
	ds_read_b128 v[190:193], v168 offset:21504
	ds_read_b128 v[194:197], v168 offset:22528
	ds_read_b128 v[202:205], v168 offset:23552
	global_load_lds_dwordx4 v148, s[28:29]
	v_lshl_add_u64 v[224:225], s[28:29], 0, v[144:145]
	s_mov_b32 m0, s38
	s_nop 0
	global_load_lds_dwordx4 v144, s[28:29]
	s_barrier
	s_waitcnt lgkmcnt(0)
	s_setprio 1
	s_waitcnt lgkmcnt(0)
	v_mfma_f32_16x16x32_bf16 v[60:63], v[128:131], v[170:173], v[60:63]
	v_mfma_f32_16x16x32_bf16 v[56:59], v[136:139], v[170:173], v[56:59]
	v_mfma_f32_16x16x32_bf16 v[44:47], v[128:131], v[178:181], v[44:47]
	v_mfma_f32_16x16x32_bf16 v[40:43], v[136:139], v[178:181], v[40:43]
	v_mfma_f32_16x16x32_bf16 v[28:31], v[128:131], v[186:189], v[28:31]
	v_mfma_f32_16x16x32_bf16 v[24:27], v[136:139], v[186:189], v[24:27]
	v_mfma_f32_16x16x32_bf16 v[12:15], v[128:131], v[194:197], v[12:15]
	v_mfma_f32_16x16x32_bf16 v[8:11], v[136:139], v[194:197], v[8:11]
	v_mfma_f32_16x16x32_bf16 v[60:63], v[132:135], v[174:177], v[60:63]
	v_mfma_f32_16x16x32_bf16 v[56:59], v[160:163], v[174:177], v[56:59]
	v_mfma_f32_16x16x32_bf16 v[44:47], v[132:135], v[182:185], v[44:47]
	v_mfma_f32_16x16x32_bf16 v[40:43], v[160:163], v[182:185], v[40:43]
	v_mfma_f32_16x16x32_bf16 v[28:31], v[132:135], v[190:193], v[28:31]
	v_mfma_f32_16x16x32_bf16 v[24:27], v[160:163], v[190:193], v[24:27]
	v_mfma_f32_16x16x32_bf16 v[12:15], v[132:135], v[202:205], v[12:15]
	v_mfma_f32_16x16x32_bf16 v[8:11], v[160:163], v[202:205], v[8:11]
	s_setprio 0
	s_barrier
	s_add_u32 s58, s26, 0x40000
	s_addc_u32 s59, s27, 0
	s_add_i32 s57, s49, s34
	s_mov_b32 m0, s57
	s_nop 0
	global_load_lds_dwordx4 v146, s[58:59]
	s_add_i32 m0, s57, 0x2000
	s_nop 0
	global_load_lds_dwordx4 v142, s[58:59]
	s_add_u32 s28, s28, 0x40000
	s_addc_u32 s29, s29, 0
	s_mov_b32 m0, s39
	s_nop 0
	global_load_lds_dwordx4 v148, s[28:29]
	s_mov_b32 m0, s40
	s_nop 0
	global_load_lds_dwordx4 v144, s[28:29]
	s_waitcnt vmcnt(12)
	s_barrier
	s_setprio 1
	v_mfma_f32_16x16x32_bf16 v[52:55], v[206:209], v[170:173], v[52:55]
	v_mfma_f32_16x16x32_bf16 v[48:51], v[214:217], v[170:173], v[48:51]
	v_mfma_f32_16x16x32_bf16 v[36:39], v[206:209], v[178:181], v[36:39]
	v_mfma_f32_16x16x32_bf16 v[32:35], v[214:217], v[178:181], v[32:35]
	v_mfma_f32_16x16x32_bf16 v[20:23], v[206:209], v[186:189], v[20:23]
	v_mfma_f32_16x16x32_bf16 v[16:19], v[214:217], v[186:189], v[16:19]
	v_mfma_f32_16x16x32_bf16 v[4:7], v[206:209], v[194:197], v[4:7]
	v_mfma_f32_16x16x32_bf16 v[0:3], v[214:217], v[194:197], v[0:3]
	v_mfma_f32_16x16x32_bf16 v[52:55], v[210:213], v[174:177], v[52:55]
	v_mfma_f32_16x16x32_bf16 v[48:51], v[218:221], v[174:177], v[48:51]
	v_mfma_f32_16x16x32_bf16 v[36:39], v[210:213], v[182:185], v[36:39]
	v_mfma_f32_16x16x32_bf16 v[32:35], v[218:221], v[182:185], v[32:35]
	v_mfma_f32_16x16x32_bf16 v[20:23], v[210:213], v[190:193], v[20:23]
	v_mfma_f32_16x16x32_bf16 v[16:19], v[218:221], v[190:193], v[16:19]
	v_mfma_f32_16x16x32_bf16 v[4:7], v[210:213], v[202:205], v[4:7]
	v_mfma_f32_16x16x32_bf16 v[0:3], v[218:221], v[202:205], v[0:3]
	s_setprio 0
	s_add_i32 s57, 0, 0x18000
	v_add_u32_e32 v150, s57, v166
	s_barrier
	ds_read_b128 v[128:131], v150
	ds_read_b128 v[132:135], v150 offset:1024
	ds_read_b128 v[136:139], v150 offset:2048
	ds_read_b128 v[160:163], v150 offset:3072
	ds_read_b128 v[170:173], v168 offset:32768
	ds_read_b128 v[174:177], v168 offset:33792
	ds_read_b128 v[178:181], v168 offset:34816
	ds_read_b128 v[182:185], v168 offset:35840
	ds_read_b128 v[186:189], v168 offset:36864
	ds_read_b128 v[190:193], v168 offset:37888
	ds_read_b128 v[194:197], v168 offset:38912
	ds_read_b128 v[202:205], v168 offset:39936
	s_waitcnt lgkmcnt(8)
	s_waitcnt vmcnt(10)
	s_barrier
; #define PG8_STAGE(bufoff, gbase, voff) do { _Pragma("unroll") for (int _i = 0; _i < 2; ++_i) \
;         __builtin_amdgcn_global_load_lds((const unsigned*)((const char*)(gbase) + (voff)[_i]), (LAS unsigned*)(lds + (bufoff) + ldsw + _i * 8192), 16, 0, 0); } while (0)
; #define PG8_LDA(dst, b, h) do { _Pragma("unroll") for (int m = 0; m < 4; ++m) _Pragma("unroll") for (int k = 0; k < 2; ++k) dst[m][k] = *(const LAS bf16x8*)(lds + PG8_SA(b, h) + aoff + m * 2048 + k * 1024); } while (0)
; #define PG8_LDB(dst, b, h) do { _Pragma("unroll") for (int n = 0; n < 2; ++n) _Pragma("unroll") for (int k = 0; k < 2; ++k) dst[n][k] = *(const LAS bf16x8*)(lds + PG8_SB(b, h) + boff + n * 2048 + k * 1024); } while (0)
; #define PG8_MMA(ai, bj, At, Bt) do { __builtin_amdgcn_s_setprio(1); _Pragma("unroll") for (int m = 0; m < 4; ++m) _Pragma("unroll") for (int n = 0; n < 2; ++n) _Pragma("unroll") for (int k = 0; k < 2; ++k) \
;         acc[ai][bj][m][n] = __builtin_amdgcn_mfma_f32_16x16x32_bf16(Bt[n][k], At[m][k], acc[ai][bj][m][n], 0, 0, 0); __builtin_amdgcn_s_setprio(0); } while (0)
; #define PG8_WAIT_L(n) asm volatile("s_waitcnt lgkmcnt(" #n ")" ::: "memory")
; #define PG8_BAR __builtin_amdgcn_s_barrier()
; #define PG8_SCHED __builtin_amdgcn_sched_barrier(0)
; template <class Epi, class Sched>
; __device__ __forceinline__ void gemm_phase(LAS unsigned char* lds, const Gemm g, const Sched& S, const Epi& E) {
;     ...
;             PG8_WAIT_L(8); PG8_BAR; PG8_WAIT_L(0); PG8_MMA(0, 0, At, B0); PG8_BAR; PG8_SCHED;
;             PG8_LDB(B1, 1, 1); PG8_STAGE(PG8_SB(1, 0), b3, voffB);
;             PG8_BAR; PG8_WAIT_L(0); PG8_MMA(0, 1, At, B1); PG8_BAR;
;             PG8_LDA(At, 1, 1); PG8_STAGE(PG8_SA(1, 0), a3, voffA);
;             PG8_BAR; PG8_WAIT_L(0); PG8_MMA(1, 0, At, B0); PG8_BAR; PG8_SCHED;
	s_waitcnt lgkmcnt(0)
	s_setprio 1
	s_waitcnt lgkmcnt(0)
	v_mfma_f32_16x16x32_bf16 v[124:127], v[128:131], v[170:173], v[124:127]
	v_mfma_f32_16x16x32_bf16 v[120:123], v[136:139], v[170:173], v[120:123]
	v_mfma_f32_16x16x32_bf16 v[108:111], v[128:131], v[178:181], v[108:111]
	v_mfma_f32_16x16x32_bf16 v[104:107], v[136:139], v[178:181], v[104:107]
	v_mfma_f32_16x16x32_bf16 v[92:95], v[128:131], v[186:189], v[92:95]
	v_mfma_f32_16x16x32_bf16 v[88:91], v[136:139], v[186:189], v[88:91]
	v_mfma_f32_16x16x32_bf16 v[76:79], v[128:131], v[194:197], v[76:79]
	v_mfma_f32_16x16x32_bf16 v[72:75], v[136:139], v[194:197], v[72:75]
	v_mfma_f32_16x16x32_bf16 v[124:127], v[132:135], v[174:177], v[124:127]
	v_mfma_f32_16x16x32_bf16 v[120:123], v[160:163], v[174:177], v[120:123]
	v_mfma_f32_16x16x32_bf16 v[108:111], v[132:135], v[182:185], v[108:111]
	v_mfma_f32_16x16x32_bf16 v[104:107], v[160:163], v[182:185], v[104:107]
	v_mfma_f32_16x16x32_bf16 v[92:95], v[132:135], v[190:193], v[92:95]
	v_mfma_f32_16x16x32_bf16 v[88:91], v[160:163], v[190:193], v[88:91]
	v_mfma_f32_16x16x32_bf16 v[76:79], v[132:135], v[202:205], v[76:79]
	v_mfma_f32_16x16x32_bf16 v[72:75], v[160:163], v[202:205], v[72:75]
	s_setprio 0
	s_barrier
	s_add_i32 s28, 0, 0x1c000
	s_add_i32 s29, s57, s34
	v_add_u32_e32 v150, s28, v166
	s_add_u32 s0, s26, 0x80
	s_addc_u32 s1, s27, 0
	s_mov_b32 m0, s29
	ds_read_b128 v[206:209], v150
	ds_read_b128 v[210:213], v150 offset:1024
	ds_read_b128 v[214:217], v150 offset:2048
	ds_read_b128 v[218:221], v150 offset:3072
	global_load_lds_dwordx4 v146, s[0:1]
	s_add_i32 m0, s29, 0x2000
	s_nop 0
	global_load_lds_dwordx4 v142, s[0:1]
	s_waitcnt vmcnt(10)
	s_barrier
	s_waitcnt lgkmcnt(0)
	s_setprio 1
	s_waitcnt lgkmcnt(0)
	v_mfma_f32_16x16x32_bf16 v[116:119], v[206:209], v[170:173], v[116:119]
	v_mfma_f32_16x16x32_bf16 v[112:115], v[214:217], v[170:173], v[112:115]
	v_mfma_f32_16x16x32_bf16 v[100:103], v[206:209], v[178:181], v[100:103]
	v_mfma_f32_16x16x32_bf16 v[96:99], v[214:217], v[178:181], v[96:99]
	v_mfma_f32_16x16x32_bf16 v[84:87], v[206:209], v[186:189], v[84:87]
	v_mfma_f32_16x16x32_bf16 v[80:83], v[214:217], v[186:189], v[80:83]
	v_mfma_f32_16x16x32_bf16 v[68:71], v[206:209], v[194:197], v[68:71]
	v_mfma_f32_16x16x32_bf16 v[64:67], v[214:217], v[194:197], v[64:67]
	v_mfma_f32_16x16x32_bf16 v[116:119], v[210:213], v[174:177], v[116:119]
	v_mfma_f32_16x16x32_bf16 v[112:115], v[218:221], v[174:177], v[112:115]
	v_mfma_f32_16x16x32_bf16 v[100:103], v[210:213], v[182:185], v[100:103]
	v_mfma_f32_16x16x32_bf16 v[96:99], v[218:221], v[182:185], v[96:99]
	v_mfma_f32_16x16x32_bf16 v[84:87], v[210:213], v[190:193], v[84:87]
	v_mfma_f32_16x16x32_bf16 v[80:83], v[218:221], v[190:193], v[80:83]
	v_mfma_f32_16x16x32_bf16 v[68:71], v[210:213], v[202:205], v[68:71]
	v_mfma_f32_16x16x32_bf16 v[64:67], v[218:221], v[202:205], v[64:67]
	s_setprio 0
	s_mov_b32 m0, s44
	s_mov_b64 s[0:1], 0x80
	v_lshl_add_u64 v[140:141], v[222:223], 0, s[0:1]
	s_barrier
	ds_read_b128 v[170:173], v168 offset:49152
	ds_read_b128 v[174:177], v168 offset:50176
	ds_read_b128 v[178:181], v168 offset:51200
	ds_read_b128 v[182:185], v168 offset:52224
	ds_read_b128 v[186:189], v168 offset:53248
	ds_read_b128 v[190:193], v168 offset:54272
	ds_read_b128 v[194:197], v168 offset:55296
	ds_read_b128 v[202:205], v168 offset:56320
	global_load_lds_dwordx4 v[140:141], off
	v_lshl_add_u64 v[140:141], v[224:225], 0, s[0:1]
	s_mov_b32 m0, s45
	s_nop 0
	global_load_lds_dwordx4 v[140:141], off
	s_barrier
; #define PG8_STAGE(bufoff, gbase, voff) do { _Pragma("unroll") for (int _i = 0; _i < 2; ++_i) \
;         __builtin_amdgcn_global_load_lds((const unsigned*)((const char*)(gbase) + (voff)[_i]), (LAS unsigned*)(lds + (bufoff) + ldsw + _i * 8192), 16, 0, 0); } while (0)
; #define PG8_MMA(ai, bj, At, Bt) do { __builtin_amdgcn_s_setprio(1); _Pragma("unroll") for (int m = 0; m < 4; ++m) _Pragma("unroll") for (int n = 0; n < 2; ++n) _Pragma("unroll") for (int k = 0; k < 2; ++k) \
;         acc[ai][bj][m][n] = __builtin_amdgcn_mfma_f32_16x16x32_bf16(Bt[n][k], At[m][k], acc[ai][bj][m][n], 0, 0, 0); __builtin_amdgcn_s_setprio(0); } while (0)
; #define PG8_WAIT_V(n) asm volatile("s_waitcnt vmcnt(" #n ")" ::: "memory")
; #define PG8_WAIT_L(n) asm volatile("s_waitcnt lgkmcnt(" #n ")" ::: "memory")
; #define PG8_BAR __builtin_amdgcn_s_barrier()
; #define PG8_SCHED __builtin_amdgcn_sched_barrier(0)
; template <class Epi, class Sched>
; __device__ __forceinline__ void gemm_phase(LAS unsigned char* lds, const Gemm g, const Sched& S, const Epi& E) {
;     ...
;             PG8_BAR; PG8_WAIT_L(0); PG8_MMA(1, 0, At, B0); PG8_BAR; PG8_SCHED;
;             PG8_STAGE(PG8_SB(1, 1), b3 + hstep, voffB);
;             PG8_WAIT_V(6); PG8_BAR; PG8_MMA(1, 1, At, B1); PG8_BAR;
;     __device__ __forceinline__ void operator()(const AccT& acc, const Unit& u, int wr, int wc, int fr, int fq) const {
;     ...
;         const int row0 = u.pm * 256 + wr * 64 + fr, col0 = u.pn * 256 + wc * 32 + 8 * fq;
;         const bool rope = u.pn < 2;
;         const int i = 4 * (wc & 1) + fq;
; #pragma unroll
;         for (int ai = 0; ai < 2; ++ai)
; #pragma unroll
;             for (int m = 0; m < 4; ++m) {
;                 const int row = row0 + ai * 128 + m * 16;
;                 f32x4 cs = {1.f, 1.f, 1.f, 1.f}, sn = {0.f, 0.f, 0.f, 0.f};
;                 if (rope) { const int t = row & 2047; const int pos = (i < 4) ? (t >> 6) : (t & 63);
;                     cs = *(const f32x4*)(ropeA + pos * 16 + ((4 * i) & 15)); sn = *(const f32x4*)(ropeA + 1024 + pos * 16 + ((4 * i) & 15)); }
	s_waitcnt lgkmcnt(0)
	s_setprio 1
	s_waitcnt lgkmcnt(0)
	v_mfma_f32_16x16x32_bf16 v[60:63], v[128:131], v[170:173], v[60:63]
	v_mfma_f32_16x16x32_bf16 v[56:59], v[136:139], v[170:173], v[56:59]
	v_mfma_f32_16x16x32_bf16 v[44:47], v[128:131], v[178:181], v[44:47]
	v_mfma_f32_16x16x32_bf16 v[40:43], v[136:139], v[178:181], v[40:43]
	v_mfma_f32_16x16x32_bf16 v[28:31], v[128:131], v[186:189], v[28:31]
	v_mfma_f32_16x16x32_bf16 v[24:27], v[136:139], v[186:189], v[24:27]
	v_mfma_f32_16x16x32_bf16 v[12:15], v[128:131], v[194:197], v[12:15]
	v_mfma_f32_16x16x32_bf16 v[8:11], v[136:139], v[194:197], v[8:11]
	v_mfma_f32_16x16x32_bf16 v[60:63], v[132:135], v[174:177], v[60:63]
	v_mfma_f32_16x16x32_bf16 v[56:59], v[160:163], v[174:177], v[56:59]
	v_mfma_f32_16x16x32_bf16 v[44:47], v[132:135], v[182:185], v[44:47]
	v_mfma_f32_16x16x32_bf16 v[40:43], v[160:163], v[182:185], v[40:43]
	v_mfma_f32_16x16x32_bf16 v[28:31], v[132:135], v[190:193], v[28:31]
	v_mfma_f32_16x16x32_bf16 v[24:27], v[160:163], v[190:193], v[24:27]
	v_mfma_f32_16x16x32_bf16 v[12:15], v[132:135], v[202:205], v[12:15]
	v_mfma_f32_16x16x32_bf16 v[8:11], v[160:163], v[202:205], v[8:11]
	s_setprio 0
	s_barrier
	s_add_u32 s26, s26, 0x40080
	s_addc_u32 s27, s27, 0
	s_add_i32 s28, s28, s34
	s_mov_b32 m0, s28
	s_nop 0
	global_load_lds_dwordx4 v146, s[26:27]
	s_add_i32 m0, s28, 0x2000
	s_nop 0
	global_load_lds_dwordx4 v142, s[26:27]
	s_waitcnt vmcnt(10)
	s_barrier
	s_setprio 1
	v_mfma_f32_16x16x32_bf16 v[52:55], v[206:209], v[170:173], v[52:55]
	v_mfma_f32_16x16x32_bf16 v[48:51], v[214:217], v[170:173], v[48:51]
	v_mfma_f32_16x16x32_bf16 v[36:39], v[206:209], v[178:181], v[36:39]
	v_mfma_f32_16x16x32_bf16 v[32:35], v[214:217], v[178:181], v[32:35]
	v_mfma_f32_16x16x32_bf16 v[20:23], v[206:209], v[186:189], v[20:23]
	v_mfma_f32_16x16x32_bf16 v[16:19], v[214:217], v[186:189], v[16:19]
	v_mfma_f32_16x16x32_bf16 v[4:7], v[206:209], v[194:197], v[4:7]
	v_mfma_f32_16x16x32_bf16 v[0:3], v[214:217], v[194:197], v[0:3]
	v_mfma_f32_16x16x32_bf16 v[52:55], v[210:213], v[174:177], v[52:55]
	v_mfma_f32_16x16x32_bf16 v[48:51], v[218:221], v[174:177], v[48:51]
	v_mfma_f32_16x16x32_bf16 v[36:39], v[210:213], v[182:185], v[36:39]
	v_mfma_f32_16x16x32_bf16 v[32:35], v[218:221], v[182:185], v[32:35]
	v_mfma_f32_16x16x32_bf16 v[20:23], v[210:213], v[190:193], v[20:23]
	v_mfma_f32_16x16x32_bf16 v[16:19], v[218:221], v[190:193], v[16:19]
	v_mfma_f32_16x16x32_bf16 v[4:7], v[210:213], v[202:205], v[4:7]
	v_mfma_f32_16x16x32_bf16 v[0:3], v[218:221], v[202:205], v[0:3]
	s_setprio 0
	s_add_i32 s56, s56, 2
	s_add_u32 s6, s6, 0x100
	s_addc_u32 s7, s7, 0
	s_add_u32 s54, s54, 0x100
	s_addc_u32 s55, s55, 0
	s_cmp_gt_u32 s56, 13
	s_barrier
	s_cbranch_scc0 .LBB0_578
	v_mov_b32_e32 v129, v165
	v_mov_b32_e32 v173, v164
	s_lshl_b32 s4, s4, 8
	s_add_i32 s4, s4, s42
	v_add_u32_e32 v128, s46, v129
	v_add_u32_e32 v170, s4, v173
	v_cmp_gt_i32_e64 s[4:5], 4, v128
	v_lshlrev_b32_e32 v128, 2, v128
	s_cmp_lt_i32 s52, 2
	v_and_b32_e32 v130, 12, v128
	s_cselect_b64 s[26:27], -1, 0
	s_cmp_gt_i32 s52, 1
	v_and_b32_e32 v172, 63, v173
	v_mov_b32_e32 v128, 1.0
	v_mov_b32_e32 v132, 0
	v_lshlrev_b32_e32 v162, 2, v130
	v_mov_b32_e32 v134, 0
	v_mov_b32_e32 v135, 0
	v_mov_b32_e32 v136, 0
	v_mov_b32_e32 v137, 0
	v_mov_b32_e32 v138, 1.0
	v_mov_b32_e32 v139, 1.0
	v_mov_b32_e32 v140, 1.0
	v_mov_b32_e32 v141, 1.0
	s_cbranch_scc1 .LBB0_581
	v_bfe_u32 v130, v170, 6, 5
	v_cndmask_b32_e64 v130, v172, v130, s[4:5]
	v_lshlrev_b32_e32 v150, 6, v130
	v_lshl_add_u64 v[130:131], s[16:17], 0, v[150:151]
	v_mov_b32_e32 v163, v151
	v_lshl_add_u64 v[134:135], s[8:9], 0, v[150:151]
	v_lshl_add_u64 v[130:131], v[130:131], 0, v[162:163]
	v_lshl_add_u64 v[134:135], v[134:135], 0, v[162:163]
	global_load_dwordx4 v[138:141], v[130:131], off
	s_nop 0
	global_load_dwordx4 v[134:137], v[134:135], off
	s_waitcnt vmcnt(0)

; #define PG8_STAGE(bufoff, gbase, voff) do { _Pragma("unroll") for (int _i = 0; _i < 2; ++_i) \
;         __builtin_amdgcn_global_load_lds((const unsigned*)((const char*)(gbase) + (voff)[_i]), (LAS unsigned*)(lds + (bufoff) + ldsw + _i * 8192), 16, 0, 0); } while (0)
; #define PG8_LDA(dst, b, h) do { _Pragma("unroll") for (int m = 0; m < 4; ++m) _Pragma("unroll") for (int k = 0; k < 2; ++k) dst[m][k] = *(const LAS bf16x8*)(lds + PG8_SA(b, h) + aoff + m * 2048 + k * 1024); } while (0)
; #define PG8_LDB(dst, b, h) do { _Pragma("unroll") for (int n = 0; n < 2; ++n) _Pragma("unroll") for (int k = 0; k < 2; ++k) dst[n][k] = *(const LAS bf16x8*)(lds + PG8_SB(b, h) + boff + n * 2048 + k * 1024); } while (0)
; #define PG8_WAIT_V(n) asm volatile("s_waitcnt vmcnt(" #n ")" ::: "memory")
; #define PG8_WAIT_L(n) asm volatile("s_waitcnt lgkmcnt(" #n ")" ::: "memory")
; #define PG8_BAR __builtin_amdgcn_s_barrier()
; #define PG8_SCHED __builtin_amdgcn_sched_barrier(0)
; template <class Epi, class Sched>
; __device__ __forceinline__ void gemm_phase(LAS unsigned char* lds, const Gemm g, const Sched& S, const Epi& E) {
;     ...
;         const bool has_next = S.next(ui + 1, nxt);
;         const char* nA = has_next ? (const char*)g.A + (size_t)nxt.pm * tstep : cA; const char* nB = has_next ? (const char*)g.Bt + (size_t)nxt.pn * tstep : cB;
;         for (int t = 0; t < nt; t += 2) {
;             const bool last = (t == nt - 2);
;             const char* a1 = cA + (size_t)(t + 1) * kstep;
;             const char* a2 = last ? nA : cA + (size_t)(t + 2) * kstep; const char* b2 = last ? nB : cB + (size_t)(t + 2) * kstep;
;             const char* a3 = a2 + kstep; const char* b3 = b2 + kstep;
;             PG8_LDB(B0, 0, 0); PG8_SCHED; PG8_LDA(At, 0, 0); PG8_STAGE(PG8_SA(1, 1), a1 + hstep, voffA);
;             PG8_WAIT_L(8); PG8_BAR; PG8_WAIT_L(0); PG8_MMA(0, 0, At, B0); PG8_BAR; PG8_SCHED;
;             PG8_LDB(B1, 0, 1); PG8_STAGE(PG8_SB(0, 0), b2, voffB);
;             PG8_BAR; PG8_WAIT_L(0); PG8_MMA(0, 1, At, B1); PG8_BAR;
;             PG8_LDA(At, 0, 1); PG8_STAGE(PG8_SA(0, 0), a2, voffA);
;             PG8_BAR; PG8_WAIT_L(0); PG8_MMA(1, 0, At, B0); PG8_BAR; PG8_SCHED;
;             PG8_STAGE(PG8_SB(0, 1), b2 + hstep, voffB);
;             PG8_WAIT_V(6); PG8_BAR; PG8_MMA(1, 1, At, B1); PG8_BAR;
.LBB0_612:
	s_ashr_i32 s35, s34, 31
	v_cmp_lt_i64_e32 vcc, s[6:7], v[142:143]
	s_lshl_b64 s[6:7], s[34:35], 19
	s_add_u32 s36, s40, s6
	s_addc_u32 s37, s41, s7
	s_and_b64 s[6:7], vcc, exec
	s_cselect_b32 s8, s37, s1
	s_cselect_b32 s9, s36, s0
	s_ashr_i32 s31, s30, 31
	s_lshl_b64 s[6:7], s[30:31], 19
	s_add_u32 s38, s96, s6
	s_addc_u32 s39, s97, s7
	s_and_b64 s[6:7], vcc, exec
	s_cselect_b32 s31, s39, s5
	s_cselect_b32 s35, s38, s4
	s_add_u32 s0, s0, 0x40080
	s_addc_u32 s1, s1, 0
	s_add_u32 s65, s4, 0x100
	s_addc_u32 s66, s5, 0
	s_mov_b32 s67, -2
	s_waitcnt lgkmcnt(0)
	ds_read_b128 v[146:149], v171
	ds_read_b128 v[150:153], v171 offset:1024
	ds_read_b128 v[154:157], v171 offset:2048
	ds_read_b128 v[158:161], v171 offset:3072
	s_add_u32 s4, s0, 0xfffc0080
	s_addc_u32 s5, s1, -1
	s_cmp_eq_u32 s67, 12
	s_cselect_b32 s7, s8, s5
	s_cselect_b32 s6, s9, s4
	s_cselect_b32 s5, s31, s66
	s_cselect_b32 s4, s35, s65
	s_add_i32 m0, s45, 0xc000
	ds_read_b128 v[162:165], v172
	ds_read_b128 v[178:181], v172 offset:1024
	ds_read_b128 v[182:185], v172 offset:2048
	ds_read_b128 v[186:189], v172 offset:3072
	ds_read_b128 v[190:193], v172 offset:4096
	ds_read_b128 v[194:197], v172 offset:5120
	ds_read_b128 v[202:205], v172 offset:6144
	ds_read_b128 v[206:209], v172 offset:7168
	global_load_lds_dwordx4 v138, s[0:1]
	s_add_i32 m0, s45, 0xe000
	s_nop 0
	global_load_lds_dwordx4 v140, s[0:1]
	s_waitcnt lgkmcnt(8)
	s_waitcnt vmcnt(10)
	s_barrier
	s_waitcnt lgkmcnt(0)
	s_setprio 1
	s_waitcnt lgkmcnt(0)
	v_mfma_f32_16x16x32_bf16 v[124:127], v[146:149], v[162:165], 0
	v_mfma_f32_16x16x32_bf16 v[120:123], v[154:157], v[162:165], 0
	v_mfma_f32_16x16x32_bf16 v[108:111], v[146:149], v[182:185], 0
	v_mfma_f32_16x16x32_bf16 v[104:107], v[154:157], v[182:185], 0
	v_mfma_f32_16x16x32_bf16 v[92:95], v[146:149], v[190:193], 0
	v_mfma_f32_16x16x32_bf16 v[88:91], v[154:157], v[190:193], 0
	v_mfma_f32_16x16x32_bf16 v[76:79], v[146:149], v[202:205], 0
	v_mfma_f32_16x16x32_bf16 v[72:75], v[154:157], v[202:205], 0
	v_mfma_f32_16x16x32_bf16 v[124:127], v[150:153], v[178:181], v[124:127]
	v_mfma_f32_16x16x32_bf16 v[120:123], v[158:161], v[178:181], v[120:123]
	v_mfma_f32_16x16x32_bf16 v[108:111], v[150:153], v[186:189], v[108:111]
	v_mfma_f32_16x16x32_bf16 v[104:107], v[158:161], v[186:189], v[104:107]
	v_mfma_f32_16x16x32_bf16 v[92:95], v[150:153], v[194:197], v[92:95]
	v_mfma_f32_16x16x32_bf16 v[88:91], v[158:161], v[194:197], v[88:91]
	v_mfma_f32_16x16x32_bf16 v[76:79], v[150:153], v[206:209], v[76:79]
	v_mfma_f32_16x16x32_bf16 v[72:75], v[158:161], v[206:209], v[72:75]
	s_setprio 0
	s_barrier
	s_add_i32 s68, s57, s44
	s_mov_b32 m0, s68
	ds_read_b128 v[210:213], v173
	ds_read_b128 v[214:217], v173 offset:1024
	ds_read_b128 v[218:221], v173 offset:2048
	ds_read_b128 v[222:225], v173 offset:3072
	global_load_lds_dwordx4 v130, s[4:5]
	s_add_i32 m0, s68, 0x2000
	s_nop 0
	global_load_lds_dwordx4 v134, s[4:5]
	s_waitcnt vmcnt(10)
	s_barrier
	s_waitcnt lgkmcnt(0)
	s_setprio 1
	s_waitcnt lgkmcnt(0)
	v_mfma_f32_16x16x32_bf16 v[116:119], v[210:213], v[162:165], 0
	v_mfma_f32_16x16x32_bf16 v[112:115], v[218:221], v[162:165], 0
	v_mfma_f32_16x16x32_bf16 v[100:103], v[210:213], v[182:185], 0
	v_mfma_f32_16x16x32_bf16 v[96:99], v[218:221], v[182:185], 0
	v_mfma_f32_16x16x32_bf16 v[84:87], v[210:213], v[190:193], 0
	v_mfma_f32_16x16x32_bf16 v[80:83], v[218:221], v[190:193], 0
	v_mfma_f32_16x16x32_bf16 v[68:71], v[210:213], v[202:205], 0
	v_mfma_f32_16x16x32_bf16 v[64:67], v[218:221], v[202:205], 0
	v_mfma_f32_16x16x32_bf16 v[116:119], v[214:217], v[178:181], v[116:119]
	v_mfma_f32_16x16x32_bf16 v[112:115], v[222:225], v[178:181], v[112:115]
	v_mfma_f32_16x16x32_bf16 v[100:103], v[214:217], v[186:189], v[100:103]
	v_mfma_f32_16x16x32_bf16 v[96:99], v[222:225], v[186:189], v[96:99]
	v_mfma_f32_16x16x32_bf16 v[84:87], v[214:217], v[194:197], v[84:87]
	v_mfma_f32_16x16x32_bf16 v[80:83], v[222:225], v[194:197], v[80:83]
	v_mfma_f32_16x16x32_bf16 v[68:71], v[214:217], v[206:209], v[68:71]
	v_mfma_f32_16x16x32_bf16 v[64:67], v[222:225], v[206:209], v[64:67]
	s_setprio 0
	s_mov_b32 m0, s45
	v_lshl_add_u64 v[226:227], s[6:7], 0, v[128:129]
	s_barrier
	ds_read_b128 v[162:165], v172 offset:16384
	ds_read_b128 v[178:181], v172 offset:17408
	ds_read_b128 v[182:185], v172 offset:18432
	ds_read_b128 v[186:189], v172 offset:19456
	ds_read_b128 v[190:193], v172 offset:20480
	ds_read_b128 v[194:197], v172 offset:21504
	ds_read_b128 v[202:205], v172 offset:22528
	ds_read_b128 v[206:209], v172 offset:23552
	global_load_lds_dwordx4 v128, s[6:7]
	v_lshl_add_u64 v[228:229], s[6:7], 0, v[132:133]
	s_mov_b32 m0, s46
	s_nop 0
	global_load_lds_dwordx4 v132, s[6:7]
	s_barrier
	s_waitcnt lgkmcnt(0)
	s_setprio 1
	s_waitcnt lgkmcnt(0)
	v_mfma_f32_16x16x32_bf16 v[60:63], v[146:149], v[162:165], 0
	v_mfma_f32_16x16x32_bf16 v[56:59], v[154:157], v[162:165], 0
	v_mfma_f32_16x16x32_bf16 v[44:47], v[146:149], v[182:185], 0
	v_mfma_f32_16x16x32_bf16 v[40:43], v[154:157], v[182:185], 0
	v_mfma_f32_16x16x32_bf16 v[28:31], v[146:149], v[190:193], 0
	v_mfma_f32_16x16x32_bf16 v[24:27], v[154:157], v[190:193], 0
	v_mfma_f32_16x16x32_bf16 v[12:15], v[146:149], v[202:205], 0
	v_mfma_f32_16x16x32_bf16 v[8:11], v[154:157], v[202:205], 0
	v_mfma_f32_16x16x32_bf16 v[60:63], v[150:153], v[178:181], v[60:63]
	v_mfma_f32_16x16x32_bf16 v[56:59], v[158:161], v[178:181], v[56:59]
	v_mfma_f32_16x16x32_bf16 v[44:47], v[150:153], v[186:189], v[44:47]
	v_mfma_f32_16x16x32_bf16 v[40:43], v[158:161], v[186:189], v[40:43]
	v_mfma_f32_16x16x32_bf16 v[28:31], v[150:153], v[194:197], v[28:31]
	v_mfma_f32_16x16x32_bf16 v[24:27], v[158:161], v[194:197], v[24:27]
	v_mfma_f32_16x16x32_bf16 v[12:15], v[150:153], v[206:209], v[12:15]
	v_mfma_f32_16x16x32_bf16 v[8:11], v[158:161], v[206:209], v[8:11]
	s_setprio 0
	s_barrier
; #define PG8_STAGE(bufoff, gbase, voff) do { _Pragma("unroll") for (int _i = 0; _i < 2; ++_i) \
;         __builtin_amdgcn_global_load_lds((const unsigned*)((const char*)(gbase) + (voff)[_i]), (LAS unsigned*)(lds + (bufoff) + ldsw + _i * 8192), 16, 0, 0); } while (0)
; #define PG8_LDA(dst, b, h) do { _Pragma("unroll") for (int m = 0; m < 4; ++m) _Pragma("unroll") for (int k = 0; k < 2; ++k) dst[m][k] = *(const LAS bf16x8*)(lds + PG8_SA(b, h) + aoff + m * 2048 + k * 1024); } while (0)
; #define PG8_LDB(dst, b, h) do { _Pragma("unroll") for (int n = 0; n < 2; ++n) _Pragma("unroll") for (int k = 0; k < 2; ++k) dst[n][k] = *(const LAS bf16x8*)(lds + PG8_SB(b, h) + boff + n * 2048 + k * 1024); } while (0)
; #define PG8_MMA(ai, bj, At, Bt) do { __builtin_amdgcn_s_setprio(1); _Pragma("unroll") for (int m = 0; m < 4; ++m) _Pragma("unroll") for (int n = 0; n < 2; ++n) _Pragma("unroll") for (int k = 0; k < 2; ++k) \
;         acc[ai][bj][m][n] = __builtin_amdgcn_mfma_f32_16x16x32_bf16(Bt[n][k], At[m][k], acc[ai][bj][m][n], 0, 0, 0); __builtin_amdgcn_s_setprio(0); } while (0)
; #define PG8_WAIT_V(n) asm volatile("s_waitcnt vmcnt(" #n ")" ::: "memory")
; #define PG8_WAIT_L(n) asm volatile("s_waitcnt lgkmcnt(" #n ")" ::: "memory")
; #define PG8_BAR __builtin_amdgcn_s_barrier()
; #define PG8_SCHED __builtin_amdgcn_sched_barrier(0)
; template <class Epi, class Sched>
; __device__ __forceinline__ void gemm_phase(LAS unsigned char* lds, const Gemm g, const Sched& S, const Epi& E) {
;     ...
;             PG8_STAGE(PG8_SB(0, 1), b2 + hstep, voffB);
;             PG8_WAIT_V(6); PG8_BAR; PG8_MMA(1, 1, At, B1); PG8_BAR;
;             PG8_LDB(B0, 1, 0); PG8_SCHED; PG8_LDA(At, 1, 0); PG8_STAGE(PG8_SA(0, 1), a2 + hstep, voffA);
;             PG8_WAIT_L(8); PG8_BAR; PG8_WAIT_L(0); PG8_MMA(0, 0, At, B0); PG8_BAR; PG8_SCHED;
;             PG8_LDB(B1, 1, 1); PG8_STAGE(PG8_SB(1, 0), b3, voffB);
;             PG8_BAR; PG8_WAIT_L(0); PG8_MMA(0, 1, At, B1); PG8_BAR;
;             PG8_LDA(At, 1, 1); PG8_STAGE(PG8_SA(1, 0), a3, voffA);
;             PG8_BAR; PG8_WAIT_L(0); PG8_MMA(1, 0, At, B0); PG8_BAR; PG8_SCHED;
	s_add_u32 s68, s4, 0x40000
	s_addc_u32 s69, s5, 0
	s_add_i32 s70, s58, s44
	s_mov_b32 m0, s70
	s_nop 0
	global_load_lds_dwordx4 v130, s[68:69]
	s_add_i32 m0, s70, 0x2000
	s_nop 0
	global_load_lds_dwordx4 v134, s[68:69]
	s_add_u32 s6, s6, 0x40000
	s_addc_u32 s7, s7, 0
	s_mov_b32 m0, s47
	s_nop 0
	global_load_lds_dwordx4 v128, s[6:7]
	s_mov_b32 m0, s48
	s_nop 0
	global_load_lds_dwordx4 v132, s[6:7]
	s_waitcnt vmcnt(12)
	s_barrier
	s_setprio 1
	v_mfma_f32_16x16x32_bf16 v[52:55], v[210:213], v[162:165], 0
	v_mfma_f32_16x16x32_bf16 v[48:51], v[218:221], v[162:165], 0
	v_mfma_f32_16x16x32_bf16 v[36:39], v[210:213], v[182:185], 0
	v_mfma_f32_16x16x32_bf16 v[32:35], v[218:221], v[182:185], 0
	v_mfma_f32_16x16x32_bf16 v[20:23], v[210:213], v[190:193], 0
	v_mfma_f32_16x16x32_bf16 v[16:19], v[218:221], v[190:193], 0
	v_mfma_f32_16x16x32_bf16 v[4:7], v[210:213], v[202:205], 0
	v_mfma_f32_16x16x32_bf16 v[0:3], v[218:221], v[202:205], 0
	v_mfma_f32_16x16x32_bf16 v[52:55], v[214:217], v[178:181], v[52:55]
	v_mfma_f32_16x16x32_bf16 v[48:51], v[222:225], v[178:181], v[48:51]
	v_mfma_f32_16x16x32_bf16 v[36:39], v[214:217], v[186:189], v[36:39]
	v_mfma_f32_16x16x32_bf16 v[32:35], v[222:225], v[186:189], v[32:35]
	v_mfma_f32_16x16x32_bf16 v[20:23], v[214:217], v[194:197], v[20:23]
	v_mfma_f32_16x16x32_bf16 v[16:19], v[222:225], v[194:197], v[16:19]
	v_mfma_f32_16x16x32_bf16 v[4:7], v[214:217], v[206:209], v[4:7]
	v_mfma_f32_16x16x32_bf16 v[0:3], v[222:225], v[206:209], v[0:3]
	s_setprio 0
	s_add_i32 s68, 0, 0x18000
	v_add_u32_e32 v136, s68, v170
	s_barrier
	ds_read_b128 v[146:149], v136
	ds_read_b128 v[150:153], v136 offset:1024
	ds_read_b128 v[154:157], v136 offset:2048
	ds_read_b128 v[158:161], v136 offset:3072
	ds_read_b128 v[162:165], v172 offset:32768
	ds_read_b128 v[178:181], v172 offset:33792
	ds_read_b128 v[182:185], v172 offset:34816
	ds_read_b128 v[186:189], v172 offset:35840
	ds_read_b128 v[190:193], v172 offset:36864
	ds_read_b128 v[194:197], v172 offset:37888
	ds_read_b128 v[202:205], v172 offset:38912
	ds_read_b128 v[206:209], v172 offset:39936
	s_waitcnt lgkmcnt(8)
	s_waitcnt vmcnt(10)
	s_barrier
	s_waitcnt lgkmcnt(0)
	s_setprio 1
	s_waitcnt lgkmcnt(0)
	v_mfma_f32_16x16x32_bf16 v[124:127], v[146:149], v[162:165], v[124:127]
	v_mfma_f32_16x16x32_bf16 v[120:123], v[154:157], v[162:165], v[120:123]
	v_mfma_f32_16x16x32_bf16 v[108:111], v[146:149], v[182:185], v[108:111]
	v_mfma_f32_16x16x32_bf16 v[104:107], v[154:157], v[182:185], v[104:107]
	v_mfma_f32_16x16x32_bf16 v[92:95], v[146:149], v[190:193], v[92:95]
	v_mfma_f32_16x16x32_bf16 v[88:91], v[154:157], v[190:193], v[88:91]
	v_mfma_f32_16x16x32_bf16 v[76:79], v[146:149], v[202:205], v[76:79]
	v_mfma_f32_16x16x32_bf16 v[72:75], v[154:157], v[202:205], v[72:75]
	v_mfma_f32_16x16x32_bf16 v[124:127], v[150:153], v[178:181], v[124:127]
	v_mfma_f32_16x16x32_bf16 v[120:123], v[158:161], v[178:181], v[120:123]
	v_mfma_f32_16x16x32_bf16 v[108:111], v[150:153], v[186:189], v[108:111]
	v_mfma_f32_16x16x32_bf16 v[104:107], v[158:161], v[186:189], v[104:107]
	v_mfma_f32_16x16x32_bf16 v[92:95], v[150:153], v[194:197], v[92:95]
	v_mfma_f32_16x16x32_bf16 v[88:91], v[158:161], v[194:197], v[88:91]
	v_mfma_f32_16x16x32_bf16 v[76:79], v[150:153], v[206:209], v[76:79]
	v_mfma_f32_16x16x32_bf16 v[72:75], v[158:161], v[206:209], v[72:75]
	s_setprio 0
	s_barrier
	s_add_i32 s6, 0, 0x1c000
	s_add_i32 s7, s68, s44
	v_add_u32_e32 v136, s6, v170
	s_add_u32 s20, s4, 0x80
	s_addc_u32 s21, s5, 0
	s_mov_b32 m0, s7
	ds_read_b128 v[210:213], v136
	ds_read_b128 v[214:217], v136 offset:1024
	ds_read_b128 v[218:221], v136 offset:2048
	ds_read_b128 v[222:225], v136 offset:3072
	global_load_lds_dwordx4 v130, s[20:21]
	s_add_i32 m0, s7, 0x2000
	s_nop 0
	global_load_lds_dwordx4 v134, s[20:21]
	s_waitcnt vmcnt(10)
	s_barrier
	s_waitcnt lgkmcnt(0)
	s_setprio 1
	s_waitcnt lgkmcnt(0)
	v_mfma_f32_16x16x32_bf16 v[116:119], v[210:213], v[162:165], v[116:119]
	v_mfma_f32_16x16x32_bf16 v[112:115], v[218:221], v[162:165], v[112:115]
	v_mfma_f32_16x16x32_bf16 v[100:103], v[210:213], v[182:185], v[100:103]
	v_mfma_f32_16x16x32_bf16 v[96:99], v[218:221], v[182:185], v[96:99]
	v_mfma_f32_16x16x32_bf16 v[84:87], v[210:213], v[190:193], v[84:87]
	v_mfma_f32_16x16x32_bf16 v[80:83], v[218:221], v[190:193], v[80:83]
	v_mfma_f32_16x16x32_bf16 v[68:71], v[210:213], v[202:205], v[68:71]
	v_mfma_f32_16x16x32_bf16 v[64:67], v[218:221], v[202:205], v[64:67]
	v_mfma_f32_16x16x32_bf16 v[116:119], v[214:217], v[178:181], v[116:119]
	v_mfma_f32_16x16x32_bf16 v[112:115], v[222:225], v[178:181], v[112:115]
	v_mfma_f32_16x16x32_bf16 v[100:103], v[214:217], v[186:189], v[100:103]
	v_mfma_f32_16x16x32_bf16 v[96:99], v[222:225], v[186:189], v[96:99]
	v_mfma_f32_16x16x32_bf16 v[84:87], v[214:217], v[194:197], v[84:87]
	v_mfma_f32_16x16x32_bf16 v[80:83], v[222:225], v[194:197], v[80:83]
	v_mfma_f32_16x16x32_bf16 v[68:71], v[214:217], v[206:209], v[68:71]
	v_mfma_f32_16x16x32_bf16 v[64:67], v[222:225], v[206:209], v[64:67]
	s_setprio 0
	s_mov_b32 m0, s54
	s_mov_b64 s[20:21], 0x80
	v_lshl_add_u64 v[166:167], v[226:227], 0, s[20:21]
	s_barrier
	ds_read_b128 v[162:165], v172 offset:49152
	ds_read_b128 v[178:181], v172 offset:50176
	ds_read_b128 v[182:185], v172 offset:51200
	ds_read_b128 v[186:189], v172 offset:52224
	ds_read_b128 v[190:193], v172 offset:53248
	ds_read_b128 v[194:197], v172 offset:54272
	ds_read_b128 v[202:205], v172 offset:55296
	ds_read_b128 v[206:209], v172 offset:56320
	global_load_lds_dwordx4 v[166:167], off
	v_lshl_add_u64 v[166:167], v[228:229], 0, s[20:21]
	s_mov_b32 m0, s55
	s_nop 0
	global_load_lds_dwordx4 v[166:167], off
	s_barrier
; #define PG8_STAGE(bufoff, gbase, voff) do { _Pragma("unroll") for (int _i = 0; _i < 2; ++_i) \
;         __builtin_amdgcn_global_load_lds((const unsigned*)((const char*)(gbase) + (voff)[_i]), (LAS unsigned*)(lds + (bufoff) + ldsw + _i * 8192), 16, 0, 0); } while (0)
; #define PG8_LDA(dst, b, h) do { _Pragma("unroll") for (int m = 0; m < 4; ++m) _Pragma("unroll") for (int k = 0; k < 2; ++k) dst[m][k] = *(const LAS bf16x8*)(lds + PG8_SA(b, h) + aoff + m * 2048 + k * 1024); } while (0)
; #define PG8_LDB(dst, b, h) do { _Pragma("unroll") for (int n = 0; n < 2; ++n) _Pragma("unroll") for (int k = 0; k < 2; ++k) dst[n][k] = *(const LAS bf16x8*)(lds + PG8_SB(b, h) + boff + n * 2048 + k * 1024); } while (0)
; #define PG8_MMA(ai, bj, At, Bt) do { __builtin_amdgcn_s_setprio(1); _Pragma("unroll") for (int m = 0; m < 4; ++m) _Pragma("unroll") for (int n = 0; n < 2; ++n) _Pragma("unroll") for (int k = 0; k < 2; ++k) \
;         acc[ai][bj][m][n] = __builtin_amdgcn_mfma_f32_16x16x32_bf16(Bt[n][k], At[m][k], acc[ai][bj][m][n], 0, 0, 0); __builtin_amdgcn_s_setprio(0); } while (0)
; #define PG8_WAIT_V(n) asm volatile("s_waitcnt vmcnt(" #n ")" ::: "memory")
; #define PG8_WAIT_L(n) asm volatile("s_waitcnt lgkmcnt(" #n ")" ::: "memory")
; #define PG8_BAR __builtin_amdgcn_s_barrier()
; #define PG8_SCHED __builtin_amdgcn_sched_barrier(0)
; template <class Epi, class Sched>
; __device__ __forceinline__ void gemm_phase(LAS unsigned char* lds, const Gemm g, const Sched& S, const Epi& E) {
;     ...
;             PG8_LDB(B0, 0, 0); PG8_SCHED; PG8_LDA(At, 0, 0); PG8_STAGE(PG8_SA(1, 1), a1 + hstep, voffA);
;             PG8_WAIT_L(8); PG8_BAR; PG8_WAIT_L(0); PG8_MMA(0, 0, At, B0); PG8_BAR; PG8_SCHED;
;             PG8_LDB(B1, 0, 1); PG8_STAGE(PG8_SB(0, 0), b2, voffB);
;     ...
;             PG8_BAR; PG8_WAIT_L(0); PG8_MMA(1, 0, At, B0); PG8_BAR; PG8_SCHED;
;             PG8_STAGE(PG8_SB(1, 1), b3 + hstep, voffB);
;             PG8_WAIT_V(6); PG8_BAR; PG8_MMA(1, 1, At, B1); PG8_BAR;
	s_waitcnt lgkmcnt(0)
	s_setprio 1
	s_waitcnt lgkmcnt(0)
	v_mfma_f32_16x16x32_bf16 v[60:63], v[146:149], v[162:165], v[60:63]
	v_mfma_f32_16x16x32_bf16 v[56:59], v[154:157], v[162:165], v[56:59]
	v_mfma_f32_16x16x32_bf16 v[44:47], v[146:149], v[182:185], v[44:47]
	v_mfma_f32_16x16x32_bf16 v[40:43], v[154:157], v[182:185], v[40:43]
	v_mfma_f32_16x16x32_bf16 v[28:31], v[146:149], v[190:193], v[28:31]
	v_mfma_f32_16x16x32_bf16 v[24:27], v[154:157], v[190:193], v[24:27]
	v_mfma_f32_16x16x32_bf16 v[12:15], v[146:149], v[202:205], v[12:15]
	v_mfma_f32_16x16x32_bf16 v[8:11], v[154:157], v[202:205], v[8:11]
	v_mfma_f32_16x16x32_bf16 v[60:63], v[150:153], v[178:181], v[60:63]
	v_mfma_f32_16x16x32_bf16 v[56:59], v[158:161], v[178:181], v[56:59]
	v_mfma_f32_16x16x32_bf16 v[44:47], v[150:153], v[186:189], v[44:47]
	v_mfma_f32_16x16x32_bf16 v[40:43], v[158:161], v[186:189], v[40:43]
	v_mfma_f32_16x16x32_bf16 v[28:31], v[150:153], v[194:197], v[28:31]
	v_mfma_f32_16x16x32_bf16 v[24:27], v[158:161], v[194:197], v[24:27]
	v_mfma_f32_16x16x32_bf16 v[12:15], v[150:153], v[206:209], v[12:15]
	v_mfma_f32_16x16x32_bf16 v[8:11], v[158:161], v[206:209], v[8:11]
	s_setprio 0
	s_barrier
	s_add_u32 s4, s4, 0x40080
	s_addc_u32 s5, s5, 0
	s_add_i32 s6, s6, s44
	s_mov_b32 m0, s6
	s_nop 0
	global_load_lds_dwordx4 v130, s[4:5]
	s_add_i32 m0, s6, 0x2000
	s_nop 0
	global_load_lds_dwordx4 v134, s[4:5]
	s_waitcnt vmcnt(10)
	s_barrier
	s_setprio 1
	v_mfma_f32_16x16x32_bf16 v[52:55], v[210:213], v[162:165], v[52:55]
	v_mfma_f32_16x16x32_bf16 v[48:51], v[218:221], v[162:165], v[48:51]
	v_mfma_f32_16x16x32_bf16 v[36:39], v[210:213], v[182:185], v[36:39]
	v_mfma_f32_16x16x32_bf16 v[32:35], v[218:221], v[182:185], v[32:35]
	v_mfma_f32_16x16x32_bf16 v[20:23], v[210:213], v[190:193], v[20:23]
	v_mfma_f32_16x16x32_bf16 v[16:19], v[218:221], v[190:193], v[16:19]
	v_mfma_f32_16x16x32_bf16 v[4:7], v[210:213], v[202:205], v[4:7]
	v_mfma_f32_16x16x32_bf16 v[0:3], v[218:221], v[202:205], v[0:3]
	v_mfma_f32_16x16x32_bf16 v[52:55], v[214:217], v[178:181], v[52:55]
	v_mfma_f32_16x16x32_bf16 v[48:51], v[222:225], v[178:181], v[48:51]
	v_mfma_f32_16x16x32_bf16 v[36:39], v[214:217], v[186:189], v[36:39]
	v_mfma_f32_16x16x32_bf16 v[32:35], v[222:225], v[186:189], v[32:35]
	v_mfma_f32_16x16x32_bf16 v[20:23], v[214:217], v[194:197], v[20:23]
	v_mfma_f32_16x16x32_bf16 v[16:19], v[222:225], v[194:197], v[16:19]
	v_mfma_f32_16x16x32_bf16 v[4:7], v[214:217], v[206:209], v[4:7]
	v_mfma_f32_16x16x32_bf16 v[0:3], v[222:225], v[206:209], v[0:3]
	s_setprio 0
	s_add_i32 s67, s67, 2
	s_add_u32 s0, s0, 0x100
	s_addc_u32 s1, s1, 0
	s_add_u32 s65, s65, 0x100
	s_addc_u32 s66, s66, 0
	s_cmp_gt_u32 s67, 13
	s_barrier
.LBB0_613:
	ds_read_b128 v[146:149], v171
	ds_read_b128 v[150:153], v171 offset:1024
	ds_read_b128 v[154:157], v171 offset:2048
	ds_read_b128 v[158:161], v171 offset:3072
	s_add_u32 s4, s0, 0xfffc0080
	s_addc_u32 s5, s1, -1
	s_cmp_eq_u32 s67, 12
	s_cselect_b32 s7, s8, s5
	s_cselect_b32 s6, s9, s4
	s_cselect_b32 s5, s31, s66
	s_cselect_b32 s4, s35, s65
	s_add_i32 m0, s45, 0xc000
	ds_read_b128 v[162:165], v172
	ds_read_b128 v[178:181], v172 offset:1024
	ds_read_b128 v[182:185], v172 offset:2048
	ds_read_b128 v[186:189], v172 offset:3072
	ds_read_b128 v[190:193], v172 offset:4096
	ds_read_b128 v[194:197], v172 offset:5120
	ds_read_b128 v[202:205], v172 offset:6144
	ds_read_b128 v[206:209], v172 offset:7168
	global_load_lds_dwordx4 v138, s[0:1]
	s_add_i32 m0, s45, 0xe000
	s_nop 0
	global_load_lds_dwordx4 v140, s[0:1]
	s_waitcnt lgkmcnt(8)
	s_waitcnt vmcnt(10)
	s_barrier
	s_waitcnt lgkmcnt(0)
	s_setprio 1
	s_waitcnt lgkmcnt(0)
	v_mfma_f32_16x16x32_bf16 v[124:127], v[146:149], v[162:165], v[124:127]
	v_mfma_f32_16x16x32_bf16 v[120:123], v[154:157], v[162:165], v[120:123]
	v_mfma_f32_16x16x32_bf16 v[108:111], v[146:149], v[182:185], v[108:111]
	v_mfma_f32_16x16x32_bf16 v[104:107], v[154:157], v[182:185], v[104:107]
	v_mfma_f32_16x16x32_bf16 v[92:95], v[146:149], v[190:193], v[92:95]
	v_mfma_f32_16x16x32_bf16 v[88:91], v[154:157], v[190:193], v[88:91]
	v_mfma_f32_16x16x32_bf16 v[76:79], v[146:149], v[202:205], v[76:79]
	v_mfma_f32_16x16x32_bf16 v[72:75], v[154:157], v[202:205], v[72:75]
	v_mfma_f32_16x16x32_bf16 v[124:127], v[150:153], v[178:181], v[124:127]
	v_mfma_f32_16x16x32_bf16 v[120:123], v[158:161], v[178:181], v[120:123]
	v_mfma_f32_16x16x32_bf16 v[108:111], v[150:153], v[186:189], v[108:111]
	v_mfma_f32_16x16x32_bf16 v[104:107], v[158:161], v[186:189], v[104:107]
	v_mfma_f32_16x16x32_bf16 v[92:95], v[150:153], v[194:197], v[92:95]
	v_mfma_f32_16x16x32_bf16 v[88:91], v[158:161], v[194:197], v[88:91]
	v_mfma_f32_16x16x32_bf16 v[76:79], v[150:153], v[206:209], v[76:79]
	v_mfma_f32_16x16x32_bf16 v[72:75], v[158:161], v[206:209], v[72:75]
	s_setprio 0
	s_barrier
	s_add_i32 s68, s57, s44
	s_mov_b32 m0, s68
	ds_read_b128 v[210:213], v173
	ds_read_b128 v[214:217], v173 offset:1024
	ds_read_b128 v[218:221], v173 offset:2048
	ds_read_b128 v[222:225], v173 offset:3072
	global_load_lds_dwordx4 v130, s[4:5]
	s_add_i32 m0, s68, 0x2000
	s_nop 0
	global_load_lds_dwordx4 v134, s[4:5]
	s_waitcnt vmcnt(10)
	s_barrier
; #define PG8_STAGE(bufoff, gbase, voff) do { _Pragma("unroll") for (int _i = 0; _i < 2; ++_i) \
;         __builtin_amdgcn_global_load_lds((const unsigned*)((const char*)(gbase) + (voff)[_i]), (LAS unsigned*)(lds + (bufoff) + ldsw + _i * 8192), 16, 0, 0); } while (0)
; #define PG8_LDA(dst, b, h) do { _Pragma("unroll") for (int m = 0; m < 4; ++m) _Pragma("unroll") for (int k = 0; k < 2; ++k) dst[m][k] = *(const LAS bf16x8*)(lds + PG8_SA(b, h) + aoff + m * 2048 + k * 1024); } while (0)
; #define PG8_LDB(dst, b, h) do { _Pragma("unroll") for (int n = 0; n < 2; ++n) _Pragma("unroll") for (int k = 0; k < 2; ++k) dst[n][k] = *(const LAS bf16x8*)(lds + PG8_SB(b, h) + boff + n * 2048 + k * 1024); } while (0)
; #define PG8_MMA(ai, bj, At, Bt) do { __builtin_amdgcn_s_setprio(1); _Pragma("unroll") for (int m = 0; m < 4; ++m) _Pragma("unroll") for (int n = 0; n < 2; ++n) _Pragma("unroll") for (int k = 0; k < 2; ++k) \
;         acc[ai][bj][m][n] = __builtin_amdgcn_mfma_f32_16x16x32_bf16(Bt[n][k], At[m][k], acc[ai][bj][m][n], 0, 0, 0); __builtin_amdgcn_s_setprio(0); } while (0)
; #define PG8_WAIT_V(n) asm volatile("s_waitcnt vmcnt(" #n ")" ::: "memory")
; #define PG8_WAIT_L(n) asm volatile("s_waitcnt lgkmcnt(" #n ")" ::: "memory")
; #define PG8_BAR __builtin_amdgcn_s_barrier()
; #define PG8_SCHED __builtin_amdgcn_sched_barrier(0)
; template <class Epi, class Sched>
; __device__ __forceinline__ void gemm_phase(LAS unsigned char* lds, const Gemm g, const Sched& S, const Epi& E) {
;     ...
;             PG8_BAR; PG8_WAIT_L(0); PG8_MMA(0, 1, At, B1); PG8_BAR;
;             PG8_LDA(At, 0, 1); PG8_STAGE(PG8_SA(0, 0), a2, voffA);
;             PG8_BAR; PG8_WAIT_L(0); PG8_MMA(1, 0, At, B0); PG8_BAR; PG8_SCHED;
;             PG8_STAGE(PG8_SB(0, 1), b2 + hstep, voffB);
;             PG8_WAIT_V(6); PG8_BAR; PG8_MMA(1, 1, At, B1); PG8_BAR;
;             PG8_LDB(B0, 1, 0); PG8_SCHED; PG8_LDA(At, 1, 0); PG8_STAGE(PG8_SA(0, 1), a2 + hstep, voffA);
;             PG8_WAIT_L(8); PG8_BAR; PG8_WAIT_L(0); PG8_MMA(0, 0, At, B0); PG8_BAR; PG8_SCHED;
	s_waitcnt lgkmcnt(0)
	s_setprio 1
	s_waitcnt lgkmcnt(0)
	v_mfma_f32_16x16x32_bf16 v[116:119], v[210:213], v[162:165], v[116:119]
	v_mfma_f32_16x16x32_bf16 v[112:115], v[218:221], v[162:165], v[112:115]
	v_mfma_f32_16x16x32_bf16 v[100:103], v[210:213], v[182:185], v[100:103]
	v_mfma_f32_16x16x32_bf16 v[96:99], v[218:221], v[182:185], v[96:99]
	v_mfma_f32_16x16x32_bf16 v[84:87], v[210:213], v[190:193], v[84:87]
	v_mfma_f32_16x16x32_bf16 v[80:83], v[218:221], v[190:193], v[80:83]
	v_mfma_f32_16x16x32_bf16 v[68:71], v[210:213], v[202:205], v[68:71]
	v_mfma_f32_16x16x32_bf16 v[64:67], v[218:221], v[202:205], v[64:67]
	v_mfma_f32_16x16x32_bf16 v[116:119], v[214:217], v[178:181], v[116:119]
	v_mfma_f32_16x16x32_bf16 v[112:115], v[222:225], v[178:181], v[112:115]
	v_mfma_f32_16x16x32_bf16 v[100:103], v[214:217], v[186:189], v[100:103]
	v_mfma_f32_16x16x32_bf16 v[96:99], v[222:225], v[186:189], v[96:99]
	v_mfma_f32_16x16x32_bf16 v[84:87], v[214:217], v[194:197], v[84:87]
	v_mfma_f32_16x16x32_bf16 v[80:83], v[222:225], v[194:197], v[80:83]
	v_mfma_f32_16x16x32_bf16 v[68:71], v[214:217], v[206:209], v[68:71]
	v_mfma_f32_16x16x32_bf16 v[64:67], v[222:225], v[206:209], v[64:67]
	s_setprio 0
	s_mov_b32 m0, s45
	v_lshl_add_u64 v[226:227], s[6:7], 0, v[128:129]
	s_barrier
	ds_read_b128 v[162:165], v172 offset:16384
	ds_read_b128 v[178:181], v172 offset:17408
	ds_read_b128 v[182:185], v172 offset:18432
	ds_read_b128 v[186:189], v172 offset:19456
	ds_read_b128 v[190:193], v172 offset:20480
	ds_read_b128 v[194:197], v172 offset:21504
	ds_read_b128 v[202:205], v172 offset:22528
	ds_read_b128 v[206:209], v172 offset:23552
	global_load_lds_dwordx4 v128, s[6:7]
	v_lshl_add_u64 v[228:229], s[6:7], 0, v[132:133]
	s_mov_b32 m0, s46
	s_nop 0
	global_load_lds_dwordx4 v132, s[6:7]
	s_barrier
	s_waitcnt lgkmcnt(0)
	s_setprio 1
	s_waitcnt lgkmcnt(0)
	v_mfma_f32_16x16x32_bf16 v[60:63], v[146:149], v[162:165], v[60:63]
	v_mfma_f32_16x16x32_bf16 v[56:59], v[154:157], v[162:165], v[56:59]
	v_mfma_f32_16x16x32_bf16 v[44:47], v[146:149], v[182:185], v[44:47]
	v_mfma_f32_16x16x32_bf16 v[40:43], v[154:157], v[182:185], v[40:43]
	v_mfma_f32_16x16x32_bf16 v[28:31], v[146:149], v[190:193], v[28:31]
	v_mfma_f32_16x16x32_bf16 v[24:27], v[154:157], v[190:193], v[24:27]
	v_mfma_f32_16x16x32_bf16 v[12:15], v[146:149], v[202:205], v[12:15]
	v_mfma_f32_16x16x32_bf16 v[8:11], v[154:157], v[202:205], v[8:11]
	v_mfma_f32_16x16x32_bf16 v[60:63], v[150:153], v[178:181], v[60:63]
	v_mfma_f32_16x16x32_bf16 v[56:59], v[158:161], v[178:181], v[56:59]
	v_mfma_f32_16x16x32_bf16 v[44:47], v[150:153], v[186:189], v[44:47]
	v_mfma_f32_16x16x32_bf16 v[40:43], v[158:161], v[186:189], v[40:43]
	v_mfma_f32_16x16x32_bf16 v[28:31], v[150:153], v[194:197], v[28:31]
	v_mfma_f32_16x16x32_bf16 v[24:27], v[158:161], v[194:197], v[24:27]
	v_mfma_f32_16x16x32_bf16 v[12:15], v[150:153], v[206:209], v[12:15]
	v_mfma_f32_16x16x32_bf16 v[8:11], v[158:161], v[206:209], v[8:11]
	s_setprio 0
	s_barrier
	s_add_u32 s68, s4, 0x40000
	s_addc_u32 s69, s5, 0
	s_add_i32 s70, s58, s44
	s_mov_b32 m0, s70
	s_nop 0
	global_load_lds_dwordx4 v130, s[68:69]
	s_add_i32 m0, s70, 0x2000
	s_nop 0
	global_load_lds_dwordx4 v134, s[68:69]
	s_add_u32 s6, s6, 0x40000
	s_addc_u32 s7, s7, 0
	s_mov_b32 m0, s47
	s_nop 0
	global_load_lds_dwordx4 v128, s[6:7]
	s_mov_b32 m0, s48
	s_nop 0
	global_load_lds_dwordx4 v132, s[6:7]
	s_waitcnt vmcnt(12)
	s_barrier
	s_setprio 1
	v_mfma_f32_16x16x32_bf16 v[52:55], v[210:213], v[162:165], v[52:55]
	v_mfma_f32_16x16x32_bf16 v[48:51], v[218:221], v[162:165], v[48:51]
	v_mfma_f32_16x16x32_bf16 v[36:39], v[210:213], v[182:185], v[36:39]
	v_mfma_f32_16x16x32_bf16 v[32:35], v[218:221], v[182:185], v[32:35]
	v_mfma_f32_16x16x32_bf16 v[20:23], v[210:213], v[190:193], v[20:23]
	v_mfma_f32_16x16x32_bf16 v[16:19], v[218:221], v[190:193], v[16:19]
	v_mfma_f32_16x16x32_bf16 v[4:7], v[210:213], v[202:205], v[4:7]
	v_mfma_f32_16x16x32_bf16 v[0:3], v[218:221], v[202:205], v[0:3]
	v_mfma_f32_16x16x32_bf16 v[52:55], v[214:217], v[178:181], v[52:55]
	v_mfma_f32_16x16x32_bf16 v[48:51], v[222:225], v[178:181], v[48:51]
	v_mfma_f32_16x16x32_bf16 v[36:39], v[214:217], v[186:189], v[36:39]
	v_mfma_f32_16x16x32_bf16 v[32:35], v[222:225], v[186:189], v[32:35]
	v_mfma_f32_16x16x32_bf16 v[20:23], v[214:217], v[194:197], v[20:23]
	v_mfma_f32_16x16x32_bf16 v[16:19], v[222:225], v[194:197], v[16:19]
	v_mfma_f32_16x16x32_bf16 v[4:7], v[214:217], v[206:209], v[4:7]
	v_mfma_f32_16x16x32_bf16 v[0:3], v[222:225], v[206:209], v[0:3]
	s_setprio 0
	s_add_i32 s68, 0, 0x18000
	v_add_u32_e32 v136, s68, v170
	s_barrier
	ds_read_b128 v[146:149], v136
	ds_read_b128 v[150:153], v136 offset:1024
	ds_read_b128 v[154:157], v136 offset:2048
	ds_read_b128 v[158:161], v136 offset:3072
	ds_read_b128 v[162:165], v172 offset:32768
	ds_read_b128 v[178:181], v172 offset:33792
	ds_read_b128 v[182:185], v172 offset:34816
	ds_read_b128 v[186:189], v172 offset:35840
	ds_read_b128 v[190:193], v172 offset:36864
	ds_read_b128 v[194:197], v172 offset:37888
	ds_read_b128 v[202:205], v172 offset:38912
	ds_read_b128 v[206:209], v172 offset:39936
	s_waitcnt lgkmcnt(8)
	s_waitcnt vmcnt(10)
	s_barrier
; #define PG8_STAGE(bufoff, gbase, voff) do { _Pragma("unroll") for (int _i = 0; _i < 2; ++_i) \
;         __builtin_amdgcn_global_load_lds((const unsigned*)((const char*)(gbase) + (voff)[_i]), (LAS unsigned*)(lds + (bufoff) + ldsw + _i * 8192), 16, 0, 0); } while (0)
; #define PG8_LDA(dst, b, h) do { _Pragma("unroll") for (int m = 0; m < 4; ++m) _Pragma("unroll") for (int k = 0; k < 2; ++k) dst[m][k] = *(const LAS bf16x8*)(lds + PG8_SA(b, h) + aoff + m * 2048 + k * 1024); } while (0)
; #define PG8_LDB(dst, b, h) do { _Pragma("unroll") for (int n = 0; n < 2; ++n) _Pragma("unroll") for (int k = 0; k < 2; ++k) dst[n][k] = *(const LAS bf16x8*)(lds + PG8_SB(b, h) + boff + n * 2048 + k * 1024); } while (0)
; #define PG8_MMA(ai, bj, At, Bt) do { __builtin_amdgcn_s_setprio(1); _Pragma("unroll") for (int m = 0; m < 4; ++m) _Pragma("unroll") for (int n = 0; n < 2; ++n) _Pragma("unroll") for (int k = 0; k < 2; ++k) \
;         acc[ai][bj][m][n] = __builtin_amdgcn_mfma_f32_16x16x32_bf16(Bt[n][k], At[m][k], acc[ai][bj][m][n], 0, 0, 0); __builtin_amdgcn_s_setprio(0); } while (0)
; #define PG8_WAIT_V(n) asm volatile("s_waitcnt vmcnt(" #n ")" ::: "memory")
; #define PG8_WAIT_L(n) asm volatile("s_waitcnt lgkmcnt(" #n ")" ::: "memory")
; #define PG8_BAR __builtin_amdgcn_s_barrier()
; #define PG8_SCHED __builtin_amdgcn_sched_barrier(0)
; template <class Epi, class Sched>
; __device__ __forceinline__ void gemm_phase(LAS unsigned char* lds, const Gemm g, const Sched& S, const Epi& E) {
;     ...
;             PG8_LDB(B0, 1, 0); PG8_SCHED; PG8_LDA(At, 1, 0); PG8_STAGE(PG8_SA(0, 1), a2 + hstep, voffA);
;             PG8_WAIT_L(8); PG8_BAR; PG8_WAIT_L(0); PG8_MMA(0, 0, At, B0); PG8_BAR; PG8_SCHED;
;             PG8_LDB(B1, 1, 1); PG8_STAGE(PG8_SB(1, 0), b3, voffB);
;             PG8_BAR; PG8_WAIT_L(0); PG8_MMA(0, 1, At, B1); PG8_BAR;
;             PG8_LDA(At, 1, 1); PG8_STAGE(PG8_SA(1, 0), a3, voffA);
;             PG8_BAR; PG8_WAIT_L(0); PG8_MMA(1, 0, At, B0); PG8_BAR; PG8_SCHED;
;             PG8_STAGE(PG8_SB(1, 1), b3 + hstep, voffB);
;             PG8_WAIT_V(6); PG8_BAR; PG8_MMA(1, 1, At, B1); PG8_BAR;
	s_waitcnt lgkmcnt(0)
	s_setprio 1
	s_waitcnt lgkmcnt(0)
	v_mfma_f32_16x16x32_bf16 v[124:127], v[146:149], v[162:165], v[124:127]
	v_mfma_f32_16x16x32_bf16 v[120:123], v[154:157], v[162:165], v[120:123]
	v_mfma_f32_16x16x32_bf16 v[108:111], v[146:149], v[182:185], v[108:111]
	v_mfma_f32_16x16x32_bf16 v[104:107], v[154:157], v[182:185], v[104:107]
	v_mfma_f32_16x16x32_bf16 v[92:95], v[146:149], v[190:193], v[92:95]
	v_mfma_f32_16x16x32_bf16 v[88:91], v[154:157], v[190:193], v[88:91]
	v_mfma_f32_16x16x32_bf16 v[76:79], v[146:149], v[202:205], v[76:79]
	v_mfma_f32_16x16x32_bf16 v[72:75], v[154:157], v[202:205], v[72:75]
	v_mfma_f32_16x16x32_bf16 v[124:127], v[150:153], v[178:181], v[124:127]
	v_mfma_f32_16x16x32_bf16 v[120:123], v[158:161], v[178:181], v[120:123]
	v_mfma_f32_16x16x32_bf16 v[108:111], v[150:153], v[186:189], v[108:111]
	v_mfma_f32_16x16x32_bf16 v[104:107], v[158:161], v[186:189], v[104:107]
	v_mfma_f32_16x16x32_bf16 v[92:95], v[150:153], v[194:197], v[92:95]
	v_mfma_f32_16x16x32_bf16 v[88:91], v[158:161], v[194:197], v[88:91]
	v_mfma_f32_16x16x32_bf16 v[76:79], v[150:153], v[206:209], v[76:79]
	v_mfma_f32_16x16x32_bf16 v[72:75], v[158:161], v[206:209], v[72:75]
	s_setprio 0
	s_barrier
	s_add_i32 s6, 0, 0x1c000
	s_add_i32 s7, s68, s44
	v_add_u32_e32 v136, s6, v170
	s_add_u32 s20, s4, 0x80
	s_addc_u32 s21, s5, 0
	s_mov_b32 m0, s7
	ds_read_b128 v[210:213], v136
	ds_read_b128 v[214:217], v136 offset:1024
	ds_read_b128 v[218:221], v136 offset:2048
	ds_read_b128 v[222:225], v136 offset:3072
	global_load_lds_dwordx4 v130, s[20:21]
	s_add_i32 m0, s7, 0x2000
	s_nop 0
	global_load_lds_dwordx4 v134, s[20:21]
	s_waitcnt vmcnt(10)
	s_barrier
	s_waitcnt lgkmcnt(0)
	s_setprio 1
	s_waitcnt lgkmcnt(0)
	v_mfma_f32_16x16x32_bf16 v[116:119], v[210:213], v[162:165], v[116:119]
	v_mfma_f32_16x16x32_bf16 v[112:115], v[218:221], v[162:165], v[112:115]
	v_mfma_f32_16x16x32_bf16 v[100:103], v[210:213], v[182:185], v[100:103]
	v_mfma_f32_16x16x32_bf16 v[96:99], v[218:221], v[182:185], v[96:99]
	v_mfma_f32_16x16x32_bf16 v[84:87], v[210:213], v[190:193], v[84:87]
	v_mfma_f32_16x16x32_bf16 v[80:83], v[218:221], v[190:193], v[80:83]
	v_mfma_f32_16x16x32_bf16 v[68:71], v[210:213], v[202:205], v[68:71]
	v_mfma_f32_16x16x32_bf16 v[64:67], v[218:221], v[202:205], v[64:67]
	v_mfma_f32_16x16x32_bf16 v[116:119], v[214:217], v[178:181], v[116:119]
	v_mfma_f32_16x16x32_bf16 v[112:115], v[222:225], v[178:181], v[112:115]
	v_mfma_f32_16x16x32_bf16 v[100:103], v[214:217], v[186:189], v[100:103]
	v_mfma_f32_16x16x32_bf16 v[96:99], v[222:225], v[186:189], v[96:99]
	v_mfma_f32_16x16x32_bf16 v[84:87], v[214:217], v[194:197], v[84:87]
	v_mfma_f32_16x16x32_bf16 v[80:83], v[222:225], v[194:197], v[80:83]
	v_mfma_f32_16x16x32_bf16 v[68:71], v[214:217], v[206:209], v[68:71]
	v_mfma_f32_16x16x32_bf16 v[64:67], v[222:225], v[206:209], v[64:67]
	s_setprio 0
	s_mov_b32 m0, s54
	s_mov_b64 s[20:21], 0x80
	v_lshl_add_u64 v[166:167], v[226:227], 0, s[20:21]
	s_barrier
	ds_read_b128 v[162:165], v172 offset:49152
	ds_read_b128 v[178:181], v172 offset:50176
	ds_read_b128 v[182:185], v172 offset:51200
	ds_read_b128 v[186:189], v172 offset:52224
	ds_read_b128 v[190:193], v172 offset:53248
	ds_read_b128 v[194:197], v172 offset:54272
	ds_read_b128 v[202:205], v172 offset:55296
	ds_read_b128 v[206:209], v172 offset:56320
	global_load_lds_dwordx4 v[166:167], off
	v_lshl_add_u64 v[166:167], v[228:229], 0, s[20:21]
	s_mov_b32 m0, s55
	s_nop 0
	global_load_lds_dwordx4 v[166:167], off
	s_barrier
	s_waitcnt lgkmcnt(0)
	s_setprio 1
	s_waitcnt lgkmcnt(0)
	v_mfma_f32_16x16x32_bf16 v[60:63], v[146:149], v[162:165], v[60:63]
	v_mfma_f32_16x16x32_bf16 v[56:59], v[154:157], v[162:165], v[56:59]
	v_mfma_f32_16x16x32_bf16 v[44:47], v[146:149], v[182:185], v[44:47]
	v_mfma_f32_16x16x32_bf16 v[40:43], v[154:157], v[182:185], v[40:43]
	v_mfma_f32_16x16x32_bf16 v[28:31], v[146:149], v[190:193], v[28:31]
	v_mfma_f32_16x16x32_bf16 v[24:27], v[154:157], v[190:193], v[24:27]
	v_mfma_f32_16x16x32_bf16 v[12:15], v[146:149], v[202:205], v[12:15]
	v_mfma_f32_16x16x32_bf16 v[8:11], v[154:157], v[202:205], v[8:11]
	v_mfma_f32_16x16x32_bf16 v[60:63], v[150:153], v[178:181], v[60:63]
	v_mfma_f32_16x16x32_bf16 v[56:59], v[158:161], v[178:181], v[56:59]
	v_mfma_f32_16x16x32_bf16 v[44:47], v[150:153], v[186:189], v[44:47]
	v_mfma_f32_16x16x32_bf16 v[40:43], v[158:161], v[186:189], v[40:43]
	v_mfma_f32_16x16x32_bf16 v[28:31], v[150:153], v[194:197], v[28:31]
	v_mfma_f32_16x16x32_bf16 v[24:27], v[158:161], v[194:197], v[24:27]
	v_mfma_f32_16x16x32_bf16 v[12:15], v[150:153], v[206:209], v[12:15]
	v_mfma_f32_16x16x32_bf16 v[8:11], v[158:161], v[206:209], v[8:11]
	s_setprio 0
	s_barrier
	s_add_u32 s4, s4, 0x40080
	s_addc_u32 s5, s5, 0
	s_add_i32 s6, s6, s44
	s_mov_b32 m0, s6
	s_nop 0
	global_load_lds_dwordx4 v130, s[4:5]
	s_add_i32 m0, s6, 0x2000
	s_nop 0
	global_load_lds_dwordx4 v134, s[4:5]
	s_waitcnt vmcnt(10)
	s_barrier
	s_setprio 1
	v_mfma_f32_16x16x32_bf16 v[52:55], v[210:213], v[162:165], v[52:55]
	v_mfma_f32_16x16x32_bf16 v[48:51], v[218:221], v[162:165], v[48:51]
	v_mfma_f32_16x16x32_bf16 v[36:39], v[210:213], v[182:185], v[36:39]
	v_mfma_f32_16x16x32_bf16 v[32:35], v[218:221], v[182:185], v[32:35]
	v_mfma_f32_16x16x32_bf16 v[20:23], v[210:213], v[190:193], v[20:23]
	v_mfma_f32_16x16x32_bf16 v[16:19], v[218:221], v[190:193], v[16:19]
	v_mfma_f32_16x16x32_bf16 v[4:7], v[210:213], v[202:205], v[4:7]
	v_mfma_f32_16x16x32_bf16 v[0:3], v[218:221], v[202:205], v[0:3]
	v_mfma_f32_16x16x32_bf16 v[52:55], v[214:217], v[178:181], v[52:55]
	v_mfma_f32_16x16x32_bf16 v[48:51], v[222:225], v[178:181], v[48:51]
	v_mfma_f32_16x16x32_bf16 v[36:39], v[214:217], v[186:189], v[36:39]
	v_mfma_f32_16x16x32_bf16 v[32:35], v[222:225], v[186:189], v[32:35]
	v_mfma_f32_16x16x32_bf16 v[20:23], v[214:217], v[194:197], v[20:23]
	v_mfma_f32_16x16x32_bf16 v[16:19], v[222:225], v[194:197], v[16:19]
	v_mfma_f32_16x16x32_bf16 v[4:7], v[214:217], v[206:209], v[4:7]
	v_mfma_f32_16x16x32_bf16 v[0:3], v[222:225], v[206:209], v[0:3]
	s_setprio 0
	s_add_i32 s67, s67, 2
	s_add_u32 s0, s0, 0x100
	s_addc_u32 s1, s1, 0
	s_add_u32 s65, s65, 0x100
	s_addc_u32 s66, s66, 0
	s_cmp_gt_u32 s67, 13
	s_barrier
;     __device__ __forceinline__ void operator()(const AccT& acc, const Unit& u, int wr, int wc, int fr, int fq) const {
;     ...
;         const int rbase = wr * 64 + fr;
;         const int tb = u.pn * 256 + wc * 32 + 8 * fq;
;         const int o0 = wc * 32 + 8 * fq;
;         const int j = fr & 3; const float sgn = ((fr >> 2) & 1) ? 1.0f : -1.0f;
; #pragma unroll
;         for (int ai = 0; ai < 2; ++ai) {
;             const int hh = 2 * ai + wr;
;             const float l2f = lgd[hh] * 1.4426950408889634f, l2b = lgd[4 + hh] * 1.4426950408889634f;
;             const float zf0 = exp2f((float)(127 - o0) * l2f), zfs = exp2f(-l2f), zb0 = exp2f((float)o0 * l2b), zbs = exp2f(l2b);
; #pragma unroll
;             for (int m = 0; m < 4; ++m) {
;                 const int r = rbase + ai * 128 + m * 16;
;                 const int d = 4 * (2 * m + (fr >> 3)) + j;
; #pragma unroll
;                 for (int bj = 0; bj < 2; ++bj) {
;                     const int t0 = tb + bj * 128;
;                     float v[8];
; #pragma unroll
;                     for (int jj = 0; jj < 4; ++jj) { v[jj] = acc[ai][bj][m][0][jj]; v[4 + jj] = acc[ai][bj][m][1][jj]; }
;                     if constexpr (ROPE) {
;                         const int t = t0 & 2047;
; #pragma unroll
;                         for (int hf = 0; hf < 2; ++hf) {
;                             f32x4 cs, sn;
;                             if (m < 2) { const float c1 = ropeA[(t >> 6) * 16 + d], s1 = ropeA[1024 + (t >> 6) * 16 + d]; cs = (f32x4){c1, c1, c1, c1}; sn = (f32x4){s1, s1, s1, s1}; }
;                             else { const float* cb = ropeA + 2048 + (d - 16) * 64 + (t & 63) + 4 * hf; cs = *(const f32x4*)(cb); sn = *(const f32x4*)(cb + 1024); }
; #pragma unroll
;                             for (int jj = 0; jj < 4; ++jj) { const float pr = __shfl_xor(v[4 * hf + jj], 4); v[4 * hf + jj] = v[4 * hf + jj] * cs[jj] + sgn * pr * sn[jj]; }
;                             __builtin_amdgcn_sched_barrier(0);
;                         }
;                     }
;                     float zf[8], zb[8]; zf[0] = zf0; zb[0] = zb0;
; #pragma unroll
;                     for (int jj = 1; jj < 8; ++jj) { zf[jj] = zf[jj - 1] * zfs; zb[jj] = zb[jj - 1] * zbs; }
;                     u32x4 wf, wb;
	s_cbranch_scc0 .LBB0_613
	v_mov_b32_e32 v136, v169
	v_mov_b32_e32 v150, v168
	s_lshl_b32 s0, s33, 8
	global_load_dword v154, v137, s[22:23]
	global_load_dword v155, v137, s[22:23] offset:16
	s_or_b32 s0, s0, s53
	v_lshlrev_b32_e32 v151, 3, v136
	v_ashrrev_i32_e32 v136, 1, v150
	v_add_u32_e32 v162, s0, v151
	v_bfi_b32 v136, -4, v136, v150
	v_lshrrev_b32_e32 v146, 2, v162
	v_add_u32_e32 v192, 0x400, v136
	v_and_b32_e32 v187, 0x1f0, v146
	v_add_u32_e32 v146, v192, v187
	v_add_u32_e32 v148, v187, v136
	v_ashrrev_i32_e32 v147, 31, v146
	v_ashrrev_i32_e32 v149, 31, v148
	v_lshl_add_u64 v[146:147], v[146:147], 2, s[16:17]
	v_lshl_add_u64 v[148:149], v[148:149], 2, s[16:17]
	global_load_dword v153, v[146:147], off
	global_load_dword v166, v[148:149], off
	v_and_b32_e32 v157, 64, v174
	v_xor_b32_e32 v156, 4, v174
	v_add_u32_e32 v157, 64, v157
	v_cmp_lt_i32_e32 vcc, v156, v157
	v_mov_b32_e32 v152, v124
	v_add_u32_e32 v151, s53, v151
	v_cndmask_b32_e32 v156, v174, v156, vcc
	v_lshlrev_b32_e32 v177, 2, v156
	ds_bpermute_b32 v124, v177, v124
	v_sub_u32_e32 v156, 0x7f, v151
	v_add_u32_e32 v164, s52, v150
	v_and_b32_e32 v150, 4, v150
	v_cvt_f32_i32_e32 v179, v156
	v_cvt_f32_i32_e32 v178, v151
	v_cmp_eq_u32_e32 vcc, 0, v150
	ds_bpermute_b32 v157, v177, v125
	ds_bpermute_b32 v158, v177, v127
	s_waitcnt lgkmcnt(0)
	v_cndmask_b32_e64 v167, v124, -v124, vcc
	ds_bpermute_b32 v151, v177, v126
	v_ashrrev_i32_e32 v165, 31, v164
	v_and_b32_e32 v186, 56, v162
	s_waitcnt lgkmcnt(0)
	v_cndmask_b32_e64 v151, v151, -v151, vcc
	s_waitcnt vmcnt(0)
	v_mul_f32_e32 v124, 0x3fb8aa3b, v154
	v_mul_f32_e32 v150, 0x3fb8aa3b, v155
	v_cmp_lt_f32_e64 s[4:5], s60, v124
	v_mul_f32_e32 v156, v124, v179
	v_cmp_gt_f32_e64 s[6:7], s59, v150
	v_cndmask_b32_e64 v159, 0, v176, s[4:5]
	v_mul_f32_e32 v160, v150, v178
	v_cndmask_b32_e64 v161, 0, v176, s[6:7]
	v_cmp_gt_f32_e64 s[8:9], s59, v156
	v_fmac_f32_e32 v159, 0xbfb8aa3b, v154
	s_and_b64 s[0:1], s[4:5], exec
	v_cmp_gt_f32_e64 s[4:5], s59, v160
	v_fmac_f32_e32 v161, 0x3fb8aa3b, v155
	v_cndmask_b32_e64 v154, 0, v176, s[8:9]
	v_exp_f32_e32 v155, v159
	v_cndmask_b32_e64 v159, 0, v176, s[4:5]
	v_fmac_f32_e32 v154, v124, v179
	v_fmac_f32_e32 v159, v150, v178
	v_exp_f32_e32 v150, v154
	v_cndmask_b32_e64 v156, 0, v175, s[8:9]
	s_cselect_b32 s8, 0xffffffc0, 0
	v_exp_f32_e32 v161, v161
	v_exp_f32_e32 v159, v159
	v_ldexp_f32 v163, v155, s8
	v_pk_mul_f32 v[154:155], v[152:153], v[166:167]
	v_cndmask_b32_e64 v167, v157, -v157, vcc
	v_mov_b32_e32 v152, v125
	s_and_b64 s[0:1], s[6:7], exec
	v_add_f32_e32 v190, v154, v155
	v_pk_mul_f32 v[154:155], v[152:153], v[166:167]
	v_cndmask_b32_e64 v167, v158, -v158, vcc
	v_mov_b32_e32 v152, v127
	v_cndmask_b32_e64 v160, 0, v175, s[4:5]
	s_cselect_b32 s0, 0xffffffc0, 0
	v_ldexp_f32 v180, v150, v156
	v_add_f32_e32 v191, v154, v155
	v_pk_mul_f32 v[154:155], v[152:153], v[166:167]
	v_ldexp_f32 v124, v161, s0
	v_mul_f32_e32 v161, v126, v166
	v_ldexp_f32 v150, v159, v160
	v_mul_f32_e32 v181, v163, v180
	v_add_f32_e32 v193, v154, v155
	global_load_dword v188, v[148:149], off
	global_load_dword v157, v[146:147], off
	ds_bpermute_b32 v127, v177, v121
	v_mov_b32_e32 v156, v121
	ds_bpermute_b32 v121, v177, v123
	ds_bpermute_b32 v125, v177, v120
	ds_bpermute_b32 v152, v177, v122
	s_waitcnt lgkmcnt(3)
	v_cndmask_b32_e64 v189, v127, -v127, vcc
	s_waitcnt lgkmcnt(1)
	v_cndmask_b32_e64 v158, v125, -v125, vcc
	s_waitcnt lgkmcnt(0)
	v_cndmask_b32_e64 v127, v152, -v152, vcc
	s_waitcnt vmcnt(1)
	v_mul_f32_e32 v159, v120, v188
	s_waitcnt vmcnt(0)
	v_pk_mul_f32 v[154:155], v[156:157], v[188:189]
	v_cndmask_b32_e64 v189, v121, -v121, vcc
	v_mov_b32_e32 v156, v123
	v_add_f32_e32 v121, v154, v155
	v_pk_mul_f32 v[154:155], v[156:157], v[188:189]
	s_nop 0
	v_add_f32_e32 v123, v154, v155
	v_mov_b32_e32 v125, v153
	v_pk_mul_f32 v[152:153], v[124:125], v[150:151]
	v_mov_b32_e32 v125, v161
	v_pk_mul_f32 v[154:155], v[124:125], v[152:153]
	v_mov_b32_e32 v125, v157
	v_mov_b32_e32 v155, v158
	v_pk_mul_f32 v[156:157], v[124:125], v[154:155]
	v_mov_b32_e32 v158, v124
	v_pk_mul_f32 v[158:159], v[158:159], v[156:157]
	v_mul_f32_e32 v167, v163, v181
	v_mov_b32_e32 v159, v127
	v_mul_f32_e32 v183, v163, v167
	v_pk_mul_f32 v[160:161], v[124:125], v[158:159]
	v_mul_f32_e32 v182, v163, v183
	v_mul_f32_e32 v151, v124, v160
	v_mul_f32_e32 v185, v163, v182
	v_mul_f32_e32 v155, v124, v151
	v_mul_f32_e32 v124, v180, v190
	v_mul_f32_e32 v125, v181, v191
	v_fma_f32 v153, v126, v166, v153
	v_mul_f32_e32 v184, v163, v185
	v_cvt_pk_bf16_f32 v124, v124, v125
	v_mul_f32_e32 v125, v167, v153
	v_mul_f32_e32 v126, v183, v193
	v_fma_f32 v120, v120, v188, v157
	v_mul_f32_e32 v159, v163, v184
	v_cvt_pk_bf16_f32 v125, v125, v126
	v_mul_f32_e32 v126, v182, v120
	v_mul_f32_e32 v127, v185, v121
	v_fma_f32 v122, v122, v188, v161
	v_cvt_pk_bf16_f32 v126, v126, v127
	v_mul_f32_e32 v127, v184, v122
	v_mul_f32_e32 v157, v159, v123
	v_cvt_pk_bf16_f32 v127, v127, v157
	v_mul_f32_e32 v157, v150, v190
	v_mul_f32_e32 v120, v158, v120
	v_mul_f32_e32 v121, v160, v121
	v_mul_f32_e32 v161, v152, v191
	v_cvt_pk_bf16_f32 v188, v157, v161
	v_mul_f32_e32 v153, v154, v153
	v_mul_f32_e32 v157, v156, v193
	v_cvt_pk_bf16_f32 v189, v153, v157
	v_cvt_pk_bf16_f32 v190, v120, v121
	v_mul_f32_e32 v120, v151, v122
	v_mul_f32_e32 v121, v155, v123
	v_cvt_pk_bf16_f32 v191, v120, v121
	v_lshlrev_b64 v[120:121], 17, v[164:165]
	v_lshl_add_u64 v[120:121], s[80:81], 0, v[120:121]
	v_ashrrev_i32_e32 v163, 31, v162
	v_lshl_add_u64 v[120:121], v[162:163], 1, v[120:121]
	s_mov_b64 s[0:1], 0x2000000
	global_store_dwordx4 v[120:121], v[124:127], off
	s_nop 1
	v_lshl_add_u64 v[126:127], v[120:121], 0, s[0:1]
	s_brev_b32 s0, 64
	v_add_co_u32_e64 v122, s[4:5], s0, v120
	s_nop 1
	v_addc_co_u32_e64 v123, s[4:5], 0, v121, s[4:5]
	global_store_dwordx4 v[122:123], v[188:191], off
	v_add_u32_e32 v122, 0x80, v162
	v_lshrrev_b32_e32 v122, 2, v122
	v_and_b32_e32 v153, 0x1f0, v122
	v_add_u32_e32 v122, v153, v192
	v_add_u32_e32 v124, v153, v136
	v_ashrrev_i32_e32 v123, 31, v122
	v_ashrrev_i32_e32 v125, 31, v124
	v_lshl_add_u64 v[122:123], v[122:123], 2, s[16:17]
	v_lshl_add_u64 v[124:125], v[124:125], 2, s[16:17]
	global_load_dword v163, v[122:123], off
	global_load_dword v164, v[124:125], off
	ds_bpermute_b32 v157, v177, v116
	v_mov_b32_e32 v162, v116
	ds_bpermute_b32 v116, v177, v117
	ds_bpermute_b32 v161, v177, v118
	ds_bpermute_b32 v166, v177, v119
	s_waitcnt lgkmcnt(3)
; __device__ __forceinline__ unsigned cvt_pk_bf16(float lo, float hi) { unsigned r; asm volatile("v_cvt_pk_bf16_f32 %0, %1, %2" : "=v"(r) : "v"(lo), "v"(hi)); return r; }
;     __device__ __forceinline__ void operator()(const AccT& acc, const Unit& u, int wr, int wc, int fr, int fq) const {
;     ...
;                 const int r = rbase + ai * 128 + m * 16;
;                 const int d = 4 * (2 * m + (fr >> 3)) + j;
; #pragma unroll
;                 for (int bj = 0; bj < 2; ++bj) {
;                     const int t0 = tb + bj * 128;
;                     float v[8];
; #pragma unroll
;                     for (int jj = 0; jj < 4; ++jj) { v[jj] = acc[ai][bj][m][0][jj]; v[4 + jj] = acc[ai][bj][m][1][jj]; }
;                     if constexpr (ROPE) {
;                         const int t = t0 & 2047;
; #pragma unroll
;                         for (int hf = 0; hf < 2; ++hf) {
;                             f32x4 cs, sn;
;                             if (m < 2) { const float c1 = ropeA[(t >> 6) * 16 + d], s1 = ropeA[1024 + (t >> 6) * 16 + d]; cs = (f32x4){c1, c1, c1, c1}; sn = (f32x4){s1, s1, s1, s1}; }
;                             else { const float* cb = ropeA + 2048 + (d - 16) * 64 + (t & 63) + 4 * hf; cs = *(const f32x4*)(cb); sn = *(const f32x4*)(cb + 1024); }
; #pragma unroll
;                             for (int jj = 0; jj < 4; ++jj) { const float pr = __shfl_xor(v[4 * hf + jj], 4); v[4 * hf + jj] = v[4 * hf + jj] * cs[jj] + sgn * pr * sn[jj]; }
;                             __builtin_amdgcn_sched_barrier(0);
;                         }
;                     }
;                     float zf[8], zb[8]; zf[0] = zf0; zb[0] = zb0;
; #pragma unroll
;                     for (int jj = 1; jj < 8; ++jj) { zf[jj] = zf[jj - 1] * zfs; zb[jj] = zb[jj - 1] * zbs; }
;                     u32x4 wf, wb;
;                     wf.x = cvt_pk_bf16(v[0] * zf[0], v[1] * zf[1]); wf.y = cvt_pk_bf16(v[2] * zf[2], v[3] * zf[3]); wf.z = cvt_pk_bf16(v[4] * zf[4], v[5] * zf[5]); wf.w = cvt_pk_bf16(v[6] * zf[6], v[7] * zf[7]);
;                     wb.x = cvt_pk_bf16(v[0] * zb[0], v[1] * zb[1]); wb.y = cvt_pk_bf16(v[2] * zb[2], v[3] * zb[3]); wb.z = cvt_pk_bf16(v[4] * zb[4], v[5] * zb[5]); wb.w = cvt_pk_bf16(v[6] * zb[6], v[7] * zb[7]);
;                     *(u32x4*)(KTZ + (size_t)r * NT + t0) = wf;
;                     *(u32x4*)(KTZ + (size_t)(256 + r) * NT + t0) = wb;
	v_cndmask_b32_e64 v165, v157, -v157, vcc
	s_waitcnt vmcnt(0)
	v_pk_mul_f32 v[188:189], v[162:163], v[164:165]
	s_waitcnt lgkmcnt(2)
	v_cndmask_b32_e64 v165, v116, -v116, vcc
	v_mov_b32_e32 v162, v117
	v_pk_mul_f32 v[116:117], v[162:163], v[164:165]
	s_waitcnt lgkmcnt(1)
	v_cndmask_b32_e64 v165, v161, -v161, vcc
	v_mov_b32_e32 v162, v118
	v_add_f32_e32 v161, v116, v117
	v_pk_mul_f32 v[116:117], v[162:163], v[164:165]
	s_waitcnt lgkmcnt(0)
	v_cndmask_b32_e64 v165, v166, -v166, vcc
	v_mov_b32_e32 v162, v119
	v_add_f32_e32 v166, v116, v117
	v_pk_mul_f32 v[116:117], v[162:163], v[164:165]
	v_add_f32_e32 v157, v188, v189
	v_add_f32_e32 v164, v116, v117
	global_load_dword v117, v[122:123], off
	global_load_dword v118, v[124:125], off
	ds_bpermute_b32 v119, v177, v112
	v_mov_b32_e32 v116, v112
	ds_bpermute_b32 v112, v177, v113
	ds_bpermute_b32 v165, v177, v114
	ds_bpermute_b32 v188, v177, v115
	s_waitcnt lgkmcnt(3)
	v_cndmask_b32_e64 v119, v119, -v119, vcc
	s_waitcnt vmcnt(0)
	v_pk_mul_f32 v[162:163], v[116:117], v[118:119]
	s_waitcnt lgkmcnt(2)
	v_cndmask_b32_e64 v119, v112, -v112, vcc
	v_mov_b32_e32 v116, v113
	v_pk_mul_f32 v[112:113], v[116:117], v[118:119]
	s_waitcnt lgkmcnt(1)
	v_cndmask_b32_e64 v119, v165, -v165, vcc
	v_mov_b32_e32 v116, v114
	v_add_f32_e32 v162, v162, v163
	v_add_f32_e32 v163, v112, v113
	v_pk_mul_f32 v[112:113], v[116:117], v[118:119]
	s_waitcnt lgkmcnt(0)
	v_cndmask_b32_e64 v119, v188, -v188, vcc
	v_mov_b32_e32 v116, v115
	v_add_f32_e32 v165, v112, v113
	v_pk_mul_f32 v[112:113], v[116:117], v[118:119]
	s_nop 0
	v_add_f32_e32 v119, v112, v113
	v_mul_f32_e32 v112, v180, v157
	v_mul_f32_e32 v113, v181, v161
	v_cvt_pk_bf16_f32 v112, v112, v113
	v_mul_f32_e32 v113, v167, v166
	v_mul_f32_e32 v114, v183, v164
	v_cvt_pk_bf16_f32 v113, v113, v114
	v_mul_f32_e32 v114, v182, v162
	v_mul_f32_e32 v115, v185, v163
	v_cvt_pk_bf16_f32 v114, v114, v115
	v_mul_f32_e32 v115, v184, v165
	v_mul_f32_e32 v116, v159, v119
	v_cvt_pk_bf16_f32 v115, v115, v116
	v_mul_f32_e32 v116, v150, v157
	v_mul_f32_e32 v117, v152, v161
	v_cvt_pk_bf16_f32 v116, v116, v117
	v_mul_f32_e32 v117, v154, v166
	v_mul_f32_e32 v118, v156, v164
	v_cvt_pk_bf16_f32 v117, v117, v118
	v_mul_f32_e32 v118, v158, v162
	v_mul_f32_e32 v157, v160, v163
	v_mul_f32_e32 v119, v155, v119
	v_cvt_pk_bf16_f32 v118, v118, v157
	v_mul_f32_e32 v157, v151, v165
	v_cvt_pk_bf16_f32 v119, v157, v119
	global_store_dwordx4 v[120:121], v[112:115], off offset:256
	global_store_dwordx4 v[126:127], v[116:119], off offset:256
	v_add_u32_e32 v161, 0x408, v136
	v_add_u32_e32 v157, 8, v136
	v_add_u32_e32 v112, v161, v187
	v_add_u32_e32 v114, v187, v157
	v_ashrrev_i32_e32 v113, 31, v112
	v_ashrrev_i32_e32 v115, 31, v114
	v_lshl_add_u64 v[112:113], v[112:113], 2, s[16:17]
	v_lshl_add_u64 v[114:115], v[114:115], 2, s[16:17]
	global_load_dword v117, v[112:113], off
	global_load_dword v118, v[114:115], off
	ds_bpermute_b32 v119, v177, v108
	v_mov_b32_e32 v116, v108
	ds_bpermute_b32 v108, v177, v109
	ds_bpermute_b32 v162, v177, v110
	ds_bpermute_b32 v163, v177, v111
	s_waitcnt lgkmcnt(3)
	v_cndmask_b32_e64 v119, v119, -v119, vcc
	s_waitcnt vmcnt(0)
	v_pk_mul_f32 v[126:127], v[116:117], v[118:119]
	s_waitcnt lgkmcnt(2)
	v_cndmask_b32_e64 v119, v108, -v108, vcc
	v_mov_b32_e32 v116, v109
	v_pk_mul_f32 v[108:109], v[116:117], v[118:119]
	s_waitcnt lgkmcnt(1)
	v_cndmask_b32_e64 v119, v162, -v162, vcc
	v_mov_b32_e32 v116, v110
	v_add_f32_e32 v126, v126, v127
	v_add_f32_e32 v127, v108, v109
	v_pk_mul_f32 v[108:109], v[116:117], v[118:119]
	s_waitcnt lgkmcnt(0)
	v_cndmask_b32_e64 v119, v163, -v163, vcc
	v_mov_b32_e32 v116, v111
	v_add_f32_e32 v162, v108, v109
	v_pk_mul_f32 v[108:109], v[116:117], v[118:119]
	s_nop 0
	v_add_f32_e32 v118, v108, v109
	global_load_dword v109, v[112:113], off
	global_load_dword v110, v[114:115], off
	ds_bpermute_b32 v111, v177, v104
	v_mov_b32_e32 v108, v104
	ds_bpermute_b32 v104, v177, v105
	ds_bpermute_b32 v119, v177, v106
	ds_bpermute_b32 v163, v177, v107
	s_waitcnt lgkmcnt(3)
	v_cndmask_b32_e64 v111, v111, -v111, vcc
	s_waitcnt vmcnt(0)
	v_pk_mul_f32 v[116:117], v[108:109], v[110:111]
	s_waitcnt lgkmcnt(2)
	v_cndmask_b32_e64 v111, v104, -v104, vcc
	v_mov_b32_e32 v108, v105
	v_pk_mul_f32 v[104:105], v[108:109], v[110:111]
	s_waitcnt lgkmcnt(1)
	v_cndmask_b32_e64 v111, v119, -v119, vcc
	v_mov_b32_e32 v108, v106
	v_add_f32_e32 v119, v104, v105
	v_pk_mul_f32 v[104:105], v[108:109], v[110:111]
	s_waitcnt lgkmcnt(0)
	v_cndmask_b32_e64 v111, v163, -v163, vcc
	v_mov_b32_e32 v108, v107
	v_add_f32_e32 v163, v104, v105
	v_pk_mul_f32 v[104:105], v[108:109], v[110:111]
	v_add_f32_e32 v164, v116, v117
	v_add_f32_e32 v108, v104, v105
	v_mul_f32_e32 v104, v180, v126
	v_mul_f32_e32 v105, v181, v127
	v_cvt_pk_bf16_f32 v104, v104, v105
	v_mul_f32_e32 v105, v167, v162
	v_mul_f32_e32 v106, v183, v118
	v_cvt_pk_bf16_f32 v105, v105, v106
	v_mul_f32_e32 v106, v182, v164
	v_mul_f32_e32 v107, v185, v119
	v_cvt_pk_bf16_f32 v106, v106, v107
	v_mul_f32_e32 v107, v184, v163
	v_mul_f32_e32 v109, v159, v108
	v_cvt_pk_bf16_f32 v107, v107, v109
	v_mul_f32_e32 v109, v150, v126
	v_mul_f32_e32 v110, v152, v127
	v_cvt_pk_bf16_f32 v116, v109, v110
	v_mul_f32_e32 v109, v154, v162
	v_mul_f32_e32 v110, v156, v118
	v_cvt_pk_bf16_f32 v117, v109, v110
	v_mul_f32_e32 v109, v158, v164
	v_mul_f32_e32 v110, v160, v119
	v_cvt_pk_bf16_f32 v118, v109, v110
	v_mul_f32_e32 v109, v151, v163
	v_mul_f32_e32 v108, v155, v108
	s_mov_b64 s[0:1], 0x200000
	v_cvt_pk_bf16_f32 v119, v109, v108
	v_lshl_add_u64 v[108:109], v[120:121], 0, s[0:1]
	s_mov_b32 s0, 0x200000
	v_add_co_u32_e64 v110, s[4:5], s0, v120
	s_mov_b64 s[0:1], 0x2200000
	s_nop 0
	v_addc_co_u32_e64 v111, s[4:5], 0, v121, s[4:5]
	global_store_dwordx4 v[110:111], v[104:107], off
	v_lshl_add_u64 v[110:111], v[120:121], 0, s[0:1]
	s_mov_b32 s0, 0x2200000
	v_add_co_u32_e64 v104, s[4:5], s0, v120
	s_nop 1
	v_addc_co_u32_e64 v105, s[4:5], 0, v121, s[4:5]
	global_store_dwordx4 v[104:105], v[116:119], off
	v_add_u32_e32 v104, v153, v161
	v_add_u32_e32 v106, v153, v157
	v_ashrrev_i32_e32 v105, 31, v104
	v_ashrrev_i32_e32 v107, 31, v106
	v_lshl_add_u64 v[104:105], v[104:105], 2, s[16:17]
	v_lshl_add_u64 v[106:107], v[106:107], 2, s[16:17]
	global_load_dword v117, v[104:105], off
	global_load_dword v118, v[106:107], off
	ds_bpermute_b32 v119, v177, v100
	v_mov_b32_e32 v116, v100
	ds_bpermute_b32 v100, v177, v101
	ds_bpermute_b32 v153, v177, v102
	ds_bpermute_b32 v157, v177, v103
	s_waitcnt lgkmcnt(3)
; __device__ __forceinline__ unsigned cvt_pk_bf16(float lo, float hi) { unsigned r; asm volatile("v_cvt_pk_bf16_f32 %0, %1, %2" : "=v"(r) : "v"(lo), "v"(hi)); return r; }
;     __device__ __forceinline__ void operator()(const AccT& acc, const Unit& u, int wr, int wc, int fr, int fq) const {
;     ...
;                         const int t = t0 & 2047;
; #pragma unroll
;                         for (int hf = 0; hf < 2; ++hf) {
;                             f32x4 cs, sn;
;                             if (m < 2) { const float c1 = ropeA[(t >> 6) * 16 + d], s1 = ropeA[1024 + (t >> 6) * 16 + d]; cs = (f32x4){c1, c1, c1, c1}; sn = (f32x4){s1, s1, s1, s1}; }
;                             else { const float* cb = ropeA + 2048 + (d - 16) * 64 + (t & 63) + 4 * hf; cs = *(const f32x4*)(cb); sn = *(const f32x4*)(cb + 1024); }
; #pragma unroll
;                             for (int jj = 0; jj < 4; ++jj) { const float pr = __shfl_xor(v[4 * hf + jj], 4); v[4 * hf + jj] = v[4 * hf + jj] * cs[jj] + sgn * pr * sn[jj]; }
;                             __builtin_amdgcn_sched_barrier(0);
;                         }
;                     }
;                     float zf[8], zb[8]; zf[0] = zf0; zb[0] = zb0;
; #pragma unroll
;                     for (int jj = 1; jj < 8; ++jj) { zf[jj] = zf[jj - 1] * zfs; zb[jj] = zb[jj - 1] * zbs; }
;                     u32x4 wf, wb;
;                     wf.x = cvt_pk_bf16(v[0] * zf[0], v[1] * zf[1]); wf.y = cvt_pk_bf16(v[2] * zf[2], v[3] * zf[3]); wf.z = cvt_pk_bf16(v[4] * zf[4], v[5] * zf[5]); wf.w = cvt_pk_bf16(v[6] * zf[6], v[7] * zf[7]);
;                     wb.x = cvt_pk_bf16(v[0] * zb[0], v[1] * zb[1]); wb.y = cvt_pk_bf16(v[2] * zb[2], v[3] * zb[3]); wb.z = cvt_pk_bf16(v[4] * zb[4], v[5] * zb[5]); wb.w = cvt_pk_bf16(v[6] * zb[6], v[7] * zb[7]);
;                     *(u32x4*)(KTZ + (size_t)r * NT + t0) = wf;
;                     *(u32x4*)(KTZ + (size_t)(256 + r) * NT + t0) = wb;
	v_cndmask_b32_e64 v119, v119, -v119, vcc
	s_waitcnt vmcnt(0)
	v_pk_mul_f32 v[126:127], v[116:117], v[118:119]
	s_waitcnt lgkmcnt(2)
	v_cndmask_b32_e64 v119, v100, -v100, vcc
	v_mov_b32_e32 v116, v101
	v_pk_mul_f32 v[100:101], v[116:117], v[118:119]
	s_waitcnt lgkmcnt(1)
	v_cndmask_b32_e64 v119, v153, -v153, vcc
	v_mov_b32_e32 v116, v102
	v_add_f32_e32 v126, v126, v127
	v_add_f32_e32 v127, v100, v101
	v_pk_mul_f32 v[100:101], v[116:117], v[118:119]
	s_waitcnt lgkmcnt(0)
	v_cndmask_b32_e64 v119, v157, -v157, vcc
	v_mov_b32_e32 v116, v103
	v_add_f32_e32 v153, v100, v101
	v_pk_mul_f32 v[100:101], v[116:117], v[118:119]
	s_nop 0
	v_add_f32_e32 v118, v100, v101
	global_load_dword v101, v[104:105], off
	global_load_dword v102, v[106:107], off
	ds_bpermute_b32 v103, v177, v96
	v_mov_b32_e32 v100, v96
	ds_bpermute_b32 v96, v177, v97
	ds_bpermute_b32 v119, v177, v98
	ds_bpermute_b32 v157, v177, v99
	s_waitcnt lgkmcnt(3)
	v_cndmask_b32_e64 v103, v103, -v103, vcc
	s_waitcnt vmcnt(0)
	v_pk_mul_f32 v[116:117], v[100:101], v[102:103]
	s_waitcnt lgkmcnt(2)
	v_cndmask_b32_e64 v103, v96, -v96, vcc
	v_mov_b32_e32 v100, v97
	v_pk_mul_f32 v[96:97], v[100:101], v[102:103]
	s_waitcnt lgkmcnt(1)
	v_cndmask_b32_e64 v103, v119, -v119, vcc
	v_mov_b32_e32 v100, v98
	v_add_f32_e32 v116, v116, v117
	v_add_f32_e32 v117, v96, v97
	v_pk_mul_f32 v[96:97], v[100:101], v[102:103]
	s_waitcnt lgkmcnt(0)
	v_cndmask_b32_e64 v103, v157, -v157, vcc
	v_mov_b32_e32 v100, v99
	v_add_f32_e32 v119, v96, v97
	v_pk_mul_f32 v[96:97], v[100:101], v[102:103]
	s_nop 0
	v_add_f32_e32 v103, v96, v97
	v_mul_f32_e32 v96, v180, v126
	v_mul_f32_e32 v97, v181, v127
	v_cvt_pk_bf16_f32 v96, v96, v97
	v_mul_f32_e32 v97, v167, v153
	v_mul_f32_e32 v98, v183, v118
	v_cvt_pk_bf16_f32 v97, v97, v98
	v_mul_f32_e32 v98, v182, v116
	v_mul_f32_e32 v99, v185, v117
	v_cvt_pk_bf16_f32 v98, v98, v99
	v_mul_f32_e32 v99, v184, v119
	v_mul_f32_e32 v100, v159, v103
	v_cvt_pk_bf16_f32 v99, v99, v100
	v_mul_f32_e32 v100, v150, v126
	v_mul_f32_e32 v101, v152, v127
	v_cvt_pk_bf16_f32 v100, v100, v101
	v_mul_f32_e32 v101, v154, v153
	v_mul_f32_e32 v102, v156, v118
	v_cvt_pk_bf16_f32 v101, v101, v102
	v_mul_f32_e32 v102, v158, v116
	v_mul_f32_e32 v116, v160, v117
	v_mul_f32_e32 v103, v155, v103
	v_cvt_pk_bf16_f32 v102, v102, v116
	v_mul_f32_e32 v116, v151, v119
	v_cvt_pk_bf16_f32 v103, v116, v103
	global_store_dwordx4 v[108:109], v[96:99], off offset:256
	global_store_dwordx4 v[110:111], v[100:103], off offset:256
	s_nop 1
	v_lshlrev_b32_e32 v100, 6, v136
	v_ashrrev_i32_e32 v101, 31, v100
	v_lshlrev_b64 v[102:103], 2, v[100:101]
	v_lshl_add_u64 v[96:97], s[24:25], 0, v[102:103]
	v_lshlrev_b32_e32 v136, 2, v186
	v_lshl_add_u64 v[96:97], v[96:97], 0, v[136:137]
	v_add_co_u32_e64 v98, s[4:5], s61, v96
	ds_bpermute_b32 v101, v177, v92
	s_nop 0
	v_addc_co_u32_e64 v99, s[4:5], 0, v97, s[4:5]
	global_load_dwordx4 v[108:111], v[98:99], off
	global_load_dwordx4 v[116:119], v[96:97], off
	ds_bpermute_b32 v127, v177, v93
	ds_bpermute_b32 v153, v177, v94
	ds_bpermute_b32 v157, v177, v95
	v_mov_b32_e32 v126, v92
	v_mov_b32_e32 v92, v94
	s_waitcnt lgkmcnt(3)
	v_cndmask_b32_e64 v163, v101, -v101, vcc
	s_waitcnt lgkmcnt(2)
	v_cndmask_b32_e64 v165, v127, -v127, vcc
	s_waitcnt lgkmcnt(1)
	v_cndmask_b32_e64 v187, v153, -v153, vcc
	s_waitcnt lgkmcnt(0)
	v_cndmask_b32_e64 v189, v157, -v157, vcc
	s_waitcnt vmcnt(1)
	v_mov_b32_e32 v127, v108
	s_waitcnt vmcnt(0)
	v_mov_b32_e32 v162, v116
	v_mov_b32_e32 v108, v93
	v_mov_b32_e32 v164, v117
	v_mov_b32_e32 v93, v110
	v_mov_b32_e32 v186, v118
	v_mov_b32_e32 v110, v95
	v_mov_b32_e32 v188, v119
	v_pk_mul_f32 v[94:95], v[126:127], v[162:163]
	v_pk_mul_f32 v[108:109], v[108:109], v[164:165]
	v_pk_mul_f32 v[92:93], v[92:93], v[186:187]
	v_pk_mul_f32 v[110:111], v[110:111], v[188:189]
	v_add_f32_e32 v101, v94, v95
	v_add_f32_e32 v153, v108, v109
	v_add_f32_e32 v157, v92, v93
	v_add_f32_e32 v161, v110, v111
	v_lshl_add_u64 v[92:93], s[16:17], 0, v[102:103]
	v_lshl_add_u64 v[94:95], v[92:93], 0, v[136:137]
	v_add_co_u32_e64 v92, s[4:5], s62, v94
	ds_bpermute_b32 v103, v177, v88
	s_nop 0
	v_addc_co_u32_e64 v93, s[4:5], 0, v95, s[4:5]
	v_add_co_u32_e64 v94, s[4:5], s49, v94
	ds_bpermute_b32 v126, v177, v89
	s_nop 0
	v_addc_co_u32_e64 v95, s[4:5], 0, v95, s[4:5]
	global_load_dwordx4 v[108:111], v[92:93], off offset:16
	global_load_dwordx4 v[116:119], v[94:95], off offset:16
	ds_bpermute_b32 v162, v177, v90
	ds_bpermute_b32 v164, v177, v91
	v_mov_b32_e32 v102, v88
	v_mov_b32_e32 v88, v90
	s_waitcnt lgkmcnt(3)
	v_cndmask_b32_e64 v127, v103, -v103, vcc
	s_waitcnt lgkmcnt(2)
	v_cndmask_b32_e64 v163, v126, -v126, vcc
	s_waitcnt lgkmcnt(1)
	v_cndmask_b32_e64 v165, v162, -v162, vcc
	s_waitcnt lgkmcnt(0)
	v_cndmask_b32_e64 v187, v164, -v164, vcc
	s_waitcnt vmcnt(1)
	v_mov_b32_e32 v103, v108
	s_waitcnt vmcnt(0)
; __device__ __forceinline__ unsigned cvt_pk_bf16(float lo, float hi) { unsigned r; asm volatile("v_cvt_pk_bf16_f32 %0, %1, %2" : "=v"(r) : "v"(lo), "v"(hi)); return r; }
;     __device__ __forceinline__ void operator()(const AccT& acc, const Unit& u, int wr, int wc, int fr, int fq) const {
;     ...
;                         const int t = t0 & 2047;
; #pragma unroll
;                         for (int hf = 0; hf < 2; ++hf) {
;                             f32x4 cs, sn;
;                             if (m < 2) { const float c1 = ropeA[(t >> 6) * 16 + d], s1 = ropeA[1024 + (t >> 6) * 16 + d]; cs = (f32x4){c1, c1, c1, c1}; sn = (f32x4){s1, s1, s1, s1}; }
;                             else { const float* cb = ropeA + 2048 + (d - 16) * 64 + (t & 63) + 4 * hf; cs = *(const f32x4*)(cb); sn = *(const f32x4*)(cb + 1024); }
; #pragma unroll
;                             for (int jj = 0; jj < 4; ++jj) { const float pr = __shfl_xor(v[4 * hf + jj], 4); v[4 * hf + jj] = v[4 * hf + jj] * cs[jj] + sgn * pr * sn[jj]; }
;                             __builtin_amdgcn_sched_barrier(0);
;                         }
;                     }
;                     float zf[8], zb[8]; zf[0] = zf0; zb[0] = zb0;
; #pragma unroll
;                     for (int jj = 1; jj < 8; ++jj) { zf[jj] = zf[jj - 1] * zfs; zb[jj] = zb[jj - 1] * zbs; }
;                     u32x4 wf, wb;
;                     wf.x = cvt_pk_bf16(v[0] * zf[0], v[1] * zf[1]); wf.y = cvt_pk_bf16(v[2] * zf[2], v[3] * zf[3]); wf.z = cvt_pk_bf16(v[4] * zf[4], v[5] * zf[5]); wf.w = cvt_pk_bf16(v[6] * zf[6], v[7] * zf[7]);
;                     wb.x = cvt_pk_bf16(v[0] * zb[0], v[1] * zb[1]); wb.y = cvt_pk_bf16(v[2] * zb[2], v[3] * zb[3]); wb.z = cvt_pk_bf16(v[4] * zb[4], v[5] * zb[5]); wb.w = cvt_pk_bf16(v[6] * zb[6], v[7] * zb[7]);
;                     *(u32x4*)(KTZ + (size_t)r * NT + t0) = wf;
;                     *(u32x4*)(KTZ + (size_t)(256 + r) * NT + t0) = wb;
	v_mov_b32_e32 v126, v116
	v_mov_b32_e32 v108, v89
	v_mov_b32_e32 v162, v117
	v_mov_b32_e32 v89, v110
	v_mov_b32_e32 v164, v118
	v_mov_b32_e32 v110, v91
	v_mov_b32_e32 v186, v119
	v_pk_mul_f32 v[90:91], v[102:103], v[126:127]
	v_pk_mul_f32 v[102:103], v[108:109], v[162:163]
	v_pk_mul_f32 v[88:89], v[88:89], v[164:165]
	v_pk_mul_f32 v[108:109], v[110:111], v[186:187]
	v_add_f32_e32 v90, v90, v91
	v_add_f32_e32 v91, v102, v103
	v_add_f32_e32 v88, v88, v89
	v_add_f32_e32 v89, v108, v109
	v_mul_f32_e32 v102, v180, v101
	v_mul_f32_e32 v103, v181, v153
	v_cvt_pk_bf16_f32 v108, v102, v103
	v_mul_f32_e32 v102, v167, v157
	v_mul_f32_e32 v103, v183, v161
	v_cvt_pk_bf16_f32 v109, v102, v103
	v_mul_f32_e32 v102, v182, v90
	v_mul_f32_e32 v103, v185, v91
	v_cvt_pk_bf16_f32 v110, v102, v103
	v_mul_f32_e32 v102, v184, v88
	v_mul_f32_e32 v103, v159, v89
	v_cvt_pk_bf16_f32 v111, v102, v103
	v_mul_f32_e32 v101, v150, v101
	v_mul_f32_e32 v102, v152, v153
	v_mul_f32_e32 v88, v151, v88
	v_mul_f32_e32 v89, v155, v89
	s_mov_b64 s[0:1], 0x400000
	v_cvt_pk_bf16_f32 v116, v101, v102
	v_mul_f32_e32 v101, v154, v157
	v_mul_f32_e32 v102, v156, v161
	v_cvt_pk_bf16_f32 v117, v101, v102
	v_mul_f32_e32 v90, v158, v90
	v_mul_f32_e32 v91, v160, v91
	v_cvt_pk_bf16_f32 v118, v90, v91
	v_cvt_pk_bf16_f32 v119, v88, v89
	v_lshl_add_u64 v[88:89], v[120:121], 0, s[0:1]
	s_mov_b32 s0, 0x400000
	v_add_co_u32_e64 v90, s[4:5], s0, v120
	s_mov_b64 s[0:1], 0x2400000
	s_nop 0
	v_addc_co_u32_e64 v91, s[4:5], 0, v121, s[4:5]
	global_store_dwordx4 v[90:91], v[108:111], off
	v_lshl_add_u64 v[90:91], v[120:121], 0, s[0:1]
	s_mov_b32 s0, 0x2400000
	v_add_co_u32_e64 v102, s[4:5], s0, v120
	s_nop 1
	v_addc_co_u32_e64 v103, s[4:5], 0, v121, s[4:5]
	global_store_dwordx4 v[102:103], v[116:119], off
	global_load_dwordx4 v[108:111], v[98:99], off
	s_nop 0
	global_load_dwordx4 v[116:119], v[96:97], off
	ds_bpermute_b32 v101, v177, v84
	ds_bpermute_b32 v103, v177, v85
	ds_bpermute_b32 v126, v177, v86
	ds_bpermute_b32 v153, v177, v87
	v_mov_b32_e32 v102, v84
	v_mov_b32_e32 v84, v86
	s_waitcnt lgkmcnt(3)
	v_cndmask_b32_e64 v127, v101, -v101, vcc
	s_waitcnt lgkmcnt(2)
	v_cndmask_b32_e64 v163, v103, -v103, vcc
	s_waitcnt lgkmcnt(1)
	v_cndmask_b32_e64 v165, v126, -v126, vcc
	s_waitcnt lgkmcnt(0)
	v_cndmask_b32_e64 v187, v153, -v153, vcc
	s_waitcnt vmcnt(1)
	v_mov_b32_e32 v103, v108
	s_waitcnt vmcnt(0)
	v_mov_b32_e32 v126, v116
	v_mov_b32_e32 v108, v85
	v_mov_b32_e32 v162, v117
	v_mov_b32_e32 v85, v110
	v_mov_b32_e32 v164, v118
	v_mov_b32_e32 v110, v87
	v_mov_b32_e32 v186, v119
	v_pk_mul_f32 v[86:87], v[102:103], v[126:127]
	v_pk_mul_f32 v[102:103], v[108:109], v[162:163]
	v_pk_mul_f32 v[84:85], v[84:85], v[164:165]
	v_pk_mul_f32 v[108:109], v[110:111], v[186:187]
	v_add_f32_e32 v101, v86, v87
	v_add_f32_e32 v153, v102, v103
	v_add_f32_e32 v157, v84, v85
	v_add_f32_e32 v161, v108, v109
	global_load_dwordx4 v[84:87], v[92:93], off offset:16
	global_load_dwordx4 v[108:111], v[94:95], off offset:16
	ds_bpermute_b32 v103, v177, v80
	ds_bpermute_b32 v116, v177, v81
	ds_bpermute_b32 v118, v177, v82
	ds_bpermute_b32 v126, v177, v83
	v_mov_b32_e32 v102, v80
	v_mov_b32_e32 v80, v82
	s_waitcnt lgkmcnt(3)
	v_cndmask_b32_e64 v117, v103, -v103, vcc
	s_waitcnt lgkmcnt(2)
	v_cndmask_b32_e64 v119, v116, -v116, vcc
	s_waitcnt lgkmcnt(1)
	v_cndmask_b32_e64 v127, v118, -v118, vcc
	s_waitcnt lgkmcnt(0)
	v_cndmask_b32_e64 v163, v126, -v126, vcc
	s_waitcnt vmcnt(1)
	v_mov_b32_e32 v103, v84
	s_waitcnt vmcnt(0)
	v_mov_b32_e32 v116, v108
	v_mov_b32_e32 v84, v81
	v_mov_b32_e32 v118, v109
	v_mov_b32_e32 v81, v86
	v_mov_b32_e32 v126, v110
	v_mov_b32_e32 v86, v83
	v_mov_b32_e32 v162, v111
	v_pk_mul_f32 v[82:83], v[102:103], v[116:117]
	v_pk_mul_f32 v[84:85], v[84:85], v[118:119]
	v_pk_mul_f32 v[80:81], v[80:81], v[126:127]
	v_pk_mul_f32 v[86:87], v[86:87], v[162:163]
	v_add_f32_e32 v102, v82, v83
	v_add_f32_e32 v103, v84, v85
	v_add_f32_e32 v108, v80, v81
	v_add_f32_e32 v87, v86, v87
	v_mul_f32_e32 v80, v180, v101
	v_mul_f32_e32 v81, v181, v153
	v_cvt_pk_bf16_f32 v80, v80, v81
	v_mul_f32_e32 v81, v167, v157
	v_mul_f32_e32 v82, v183, v161
	v_cvt_pk_bf16_f32 v81, v81, v82
	v_mul_f32_e32 v82, v182, v102
	v_mul_f32_e32 v83, v185, v103
	v_cvt_pk_bf16_f32 v82, v82, v83
	v_mul_f32_e32 v83, v184, v108
	v_mul_f32_e32 v84, v159, v87
	v_cvt_pk_bf16_f32 v83, v83, v84
	v_mul_f32_e32 v84, v150, v101
	v_mul_f32_e32 v85, v152, v153
	v_cvt_pk_bf16_f32 v84, v84, v85
	v_mul_f32_e32 v85, v154, v157
	v_mul_f32_e32 v86, v156, v161
	v_cvt_pk_bf16_f32 v85, v85, v86
	v_mul_f32_e32 v86, v158, v102
	v_mul_f32_e32 v101, v160, v103
	v_mul_f32_e32 v87, v155, v87
	v_cvt_pk_bf16_f32 v86, v86, v101
	v_mul_f32_e32 v101, v151, v108
	v_cvt_pk_bf16_f32 v87, v101, v87
	global_store_dwordx4 v[88:89], v[80:83], off offset:256
	global_store_dwordx4 v[90:91], v[84:87], off offset:256
	s_nop 0
	v_add_u32_e32 v80, 0x200, v100
	v_ashrrev_i32_e32 v81, 31, v80
	v_lshl_add_u64 v[82:83], s[24:25], 0, v[136:137]
	v_lshlrev_b64 v[100:101], 2, v[80:81]
	v_lshl_add_u64 v[80:81], v[82:83], 0, v[100:101]
	v_add_co_u32_e64 v82, s[4:5], s61, v80
	ds_bpermute_b32 v103, v177, v76
	s_nop 0
	v_addc_co_u32_e64 v83, s[4:5], 0, v81, s[4:5]
	global_load_dwordx4 v[84:87], v[82:83], off
	global_load_dwordx4 v[88:91], v[80:81], off
	ds_bpermute_b32 v108, v177, v77
	ds_bpermute_b32 v110, v177, v78
	ds_bpermute_b32 v116, v177, v79
	v_mov_b32_e32 v102, v76
	v_mov_b32_e32 v76, v78
	s_waitcnt lgkmcnt(3)
	v_cndmask_b32_e64 v109, v103, -v103, vcc
	s_waitcnt lgkmcnt(2)
	v_cndmask_b32_e64 v111, v108, -v108, vcc
	s_waitcnt lgkmcnt(1)
	v_cndmask_b32_e64 v117, v110, -v110, vcc
	s_waitcnt lgkmcnt(0)
; __device__ __forceinline__ unsigned cvt_pk_bf16(float lo, float hi) { unsigned r; asm volatile("v_cvt_pk_bf16_f32 %0, %1, %2" : "=v"(r) : "v"(lo), "v"(hi)); return r; }
;     __device__ __forceinline__ void operator()(const AccT& acc, const Unit& u, int wr, int wc, int fr, int fq) const {
;     ...
;                         const int t = t0 & 2047;
; #pragma unroll
;                         for (int hf = 0; hf < 2; ++hf) {
;                             f32x4 cs, sn;
;                             if (m < 2) { const float c1 = ropeA[(t >> 6) * 16 + d], s1 = ropeA[1024 + (t >> 6) * 16 + d]; cs = (f32x4){c1, c1, c1, c1}; sn = (f32x4){s1, s1, s1, s1}; }
;                             else { const float* cb = ropeA + 2048 + (d - 16) * 64 + (t & 63) + 4 * hf; cs = *(const f32x4*)(cb); sn = *(const f32x4*)(cb + 1024); }
; #pragma unroll
;                             for (int jj = 0; jj < 4; ++jj) { const float pr = __shfl_xor(v[4 * hf + jj], 4); v[4 * hf + jj] = v[4 * hf + jj] * cs[jj] + sgn * pr * sn[jj]; }
;                             __builtin_amdgcn_sched_barrier(0);
;                         }
;                     }
;                     float zf[8], zb[8]; zf[0] = zf0; zb[0] = zb0;
; #pragma unroll
;                     for (int jj = 1; jj < 8; ++jj) { zf[jj] = zf[jj - 1] * zfs; zb[jj] = zb[jj - 1] * zbs; }
;                     u32x4 wf, wb;
;                     wf.x = cvt_pk_bf16(v[0] * zf[0], v[1] * zf[1]); wf.y = cvt_pk_bf16(v[2] * zf[2], v[3] * zf[3]); wf.z = cvt_pk_bf16(v[4] * zf[4], v[5] * zf[5]); wf.w = cvt_pk_bf16(v[6] * zf[6], v[7] * zf[7]);
;                     wb.x = cvt_pk_bf16(v[0] * zb[0], v[1] * zb[1]); wb.y = cvt_pk_bf16(v[2] * zb[2], v[3] * zb[3]); wb.z = cvt_pk_bf16(v[4] * zb[4], v[5] * zb[5]); wb.w = cvt_pk_bf16(v[6] * zb[6], v[7] * zb[7]);
;                     *(u32x4*)(KTZ + (size_t)r * NT + t0) = wf;
;                     *(u32x4*)(KTZ + (size_t)(256 + r) * NT + t0) = wb;
	v_cndmask_b32_e64 v119, v116, -v116, vcc
	s_waitcnt vmcnt(1)
	v_mov_b32_e32 v103, v84
	s_waitcnt vmcnt(0)
	v_mov_b32_e32 v108, v88
	v_mov_b32_e32 v84, v77
	v_mov_b32_e32 v110, v89
	v_mov_b32_e32 v77, v86
	v_mov_b32_e32 v116, v90
	v_mov_b32_e32 v86, v79
	v_mov_b32_e32 v118, v91
	v_pk_mul_f32 v[78:79], v[102:103], v[108:109]
	v_pk_mul_f32 v[84:85], v[84:85], v[110:111]
	v_pk_mul_f32 v[76:77], v[76:77], v[116:117]
	v_pk_mul_f32 v[86:87], v[86:87], v[118:119]
	v_add_f32_e32 v118, v78, v79
	v_add_f32_e32 v119, v84, v85
	v_add_f32_e32 v126, v76, v77
	v_add_f32_e32 v127, v86, v87
	v_lshl_add_u64 v[76:77], s[16:17], 0, v[100:101]
	v_lshl_add_u64 v[78:79], v[76:77], 0, v[136:137]
	v_add_co_u32_e64 v76, s[4:5], s62, v78
	ds_bpermute_b32 v101, v177, v72
	s_nop 0
	v_addc_co_u32_e64 v77, s[4:5], 0, v79, s[4:5]
	v_add_co_u32_e64 v78, s[4:5], s49, v78
	ds_bpermute_b32 v102, v177, v73
	s_nop 0
	v_addc_co_u32_e64 v79, s[4:5], 0, v79, s[4:5]
	global_load_dwordx4 v[84:87], v[76:77], off offset:16
	global_load_dwordx4 v[88:91], v[78:79], off offset:16
	ds_bpermute_b32 v108, v177, v74
	ds_bpermute_b32 v110, v177, v75
	v_mov_b32_e32 v100, v72
	v_mov_b32_e32 v72, v74
	s_waitcnt lgkmcnt(3)
	v_cndmask_b32_e64 v103, v101, -v101, vcc
	s_waitcnt lgkmcnt(2)
	v_cndmask_b32_e64 v109, v102, -v102, vcc
	s_waitcnt lgkmcnt(1)
	v_cndmask_b32_e64 v111, v108, -v108, vcc
	s_waitcnt lgkmcnt(0)
	v_cndmask_b32_e64 v117, v110, -v110, vcc
	s_waitcnt vmcnt(1)
	v_mov_b32_e32 v101, v84
	s_waitcnt vmcnt(0)
	v_mov_b32_e32 v102, v88
	v_mov_b32_e32 v84, v73
	v_mov_b32_e32 v108, v89
	v_mov_b32_e32 v73, v86
	v_mov_b32_e32 v110, v90
	v_mov_b32_e32 v86, v75
	v_mov_b32_e32 v116, v91
	v_pk_mul_f32 v[74:75], v[100:101], v[102:103]
	v_pk_mul_f32 v[84:85], v[84:85], v[108:109]
	v_pk_mul_f32 v[72:73], v[72:73], v[110:111]
	v_pk_mul_f32 v[86:87], v[86:87], v[116:117]
	v_add_f32_e32 v74, v74, v75
	v_add_f32_e32 v75, v84, v85
	v_add_f32_e32 v72, v72, v73
	v_add_f32_e32 v73, v86, v87
	v_mul_f32_e32 v84, v180, v118
	v_mul_f32_e32 v85, v181, v119
	v_cvt_pk_bf16_f32 v84, v84, v85
	v_mul_f32_e32 v85, v167, v126
	v_mul_f32_e32 v86, v183, v127
	v_cvt_pk_bf16_f32 v85, v85, v86
	v_mul_f32_e32 v86, v182, v74
	v_mul_f32_e32 v87, v185, v75
	v_cvt_pk_bf16_f32 v86, v86, v87
	v_mul_f32_e32 v87, v184, v72
	v_mul_f32_e32 v88, v159, v73
	v_cvt_pk_bf16_f32 v87, v87, v88
	v_mul_f32_e32 v88, v150, v118
	v_mul_f32_e32 v89, v152, v119
	v_cvt_pk_bf16_f32 v88, v88, v89
	v_mul_f32_e32 v89, v154, v126
	v_mul_f32_e32 v90, v156, v127
	v_mul_f32_e32 v72, v151, v72
	v_mul_f32_e32 v73, v155, v73
	s_mov_b64 s[0:1], 0x600000
	v_cvt_pk_bf16_f32 v89, v89, v90
	v_mul_f32_e32 v74, v158, v74
	v_mul_f32_e32 v75, v160, v75
	v_cvt_pk_bf16_f32 v90, v74, v75
	v_cvt_pk_bf16_f32 v91, v72, v73
	v_lshl_add_u64 v[72:73], v[120:121], 0, s[0:1]
	s_mov_b32 s0, 0x600000
	v_add_co_u32_e64 v74, s[4:5], s0, v120
	s_mov_b64 s[0:1], 0x2600000
	s_nop 0
	v_addc_co_u32_e64 v75, s[4:5], 0, v121, s[4:5]
	global_store_dwordx4 v[74:75], v[84:87], off
	v_lshl_add_u64 v[74:75], v[120:121], 0, s[0:1]
	s_mov_b32 s0, 0x2600000
	v_add_co_u32_e64 v84, s[4:5], s0, v120
	s_nop 1
	v_addc_co_u32_e64 v85, s[4:5], 0, v121, s[4:5]
	global_store_dwordx4 v[84:85], v[88:91], off
	global_load_dwordx4 v[84:87], v[82:83], off
	s_nop 0
	global_load_dwordx4 v[88:91], v[80:81], off
	ds_bpermute_b32 v101, v177, v68
	ds_bpermute_b32 v102, v177, v69
	ds_bpermute_b32 v108, v177, v70
	ds_bpermute_b32 v110, v177, v71
	v_mov_b32_e32 v100, v68
	v_mov_b32_e32 v68, v70
	s_waitcnt lgkmcnt(3)
	v_cndmask_b32_e64 v103, v101, -v101, vcc
	s_waitcnt lgkmcnt(2)
	v_cndmask_b32_e64 v109, v102, -v102, vcc
	s_waitcnt lgkmcnt(1)
	v_cndmask_b32_e64 v111, v108, -v108, vcc
	s_waitcnt lgkmcnt(0)
	v_cndmask_b32_e64 v117, v110, -v110, vcc
	s_waitcnt vmcnt(1)
	v_mov_b32_e32 v101, v84
	s_waitcnt vmcnt(0)
	v_mov_b32_e32 v102, v88
	v_mov_b32_e32 v84, v69
	v_mov_b32_e32 v108, v89
	v_mov_b32_e32 v69, v86
	v_mov_b32_e32 v110, v90
	v_mov_b32_e32 v86, v71
	v_mov_b32_e32 v116, v91
	v_pk_mul_f32 v[70:71], v[100:101], v[102:103]
	v_pk_mul_f32 v[84:85], v[84:85], v[108:109]
	v_pk_mul_f32 v[68:69], v[68:69], v[110:111]
	v_pk_mul_f32 v[86:87], v[86:87], v[116:117]
	v_add_f32_e32 v110, v70, v71
	v_add_f32_e32 v111, v84, v85
	v_add_f32_e32 v116, v68, v69
	v_add_f32_e32 v117, v86, v87
	global_load_dwordx4 v[68:71], v[76:77], off offset:16
	global_load_dwordx4 v[84:87], v[78:79], off offset:16
	ds_bpermute_b32 v89, v177, v64
	ds_bpermute_b32 v90, v177, v65
	ds_bpermute_b32 v100, v177, v66
	ds_bpermute_b32 v102, v177, v67
	v_mov_b32_e32 v88, v64
	v_mov_b32_e32 v64, v66
	s_waitcnt lgkmcnt(3)
	v_cndmask_b32_e64 v91, v89, -v89, vcc
	s_waitcnt lgkmcnt(2)
	v_cndmask_b32_e64 v101, v90, -v90, vcc
	s_waitcnt lgkmcnt(1)
	v_cndmask_b32_e64 v103, v100, -v100, vcc
	s_waitcnt lgkmcnt(0)
	v_cndmask_b32_e64 v109, v102, -v102, vcc
	s_waitcnt vmcnt(1)
	v_mov_b32_e32 v89, v68
	s_waitcnt vmcnt(0)
;     __device__ __forceinline__ void operator()(const AccT& acc, const Unit& u, int wr, int wc, int fr, int fq) const {
;     ...
;         for (int ai = 0; ai < 2; ++ai) {
;             const int hh = 2 * ai + wr;
;             const float l2f = lgd[hh] * 1.4426950408889634f, l2b = lgd[4 + hh] * 1.4426950408889634f;
;             const float zf0 = exp2f((float)(127 - o0) * l2f), zfs = exp2f(-l2f), zb0 = exp2f((float)o0 * l2b), zbs = exp2f(l2b);
; #pragma unroll
;             for (int m = 0; m < 4; ++m) {
;                 const int r = rbase + ai * 128 + m * 16;
;                 const int d = 4 * (2 * m + (fr >> 3)) + j;
; #pragma unroll
;                 for (int bj = 0; bj < 2; ++bj) {
;                     const int t0 = tb + bj * 128;
;                     float v[8];
; #pragma unroll
;                     for (int jj = 0; jj < 4; ++jj) { v[jj] = acc[ai][bj][m][0][jj]; v[4 + jj] = acc[ai][bj][m][1][jj]; }
;                     if constexpr (ROPE) {
;                         const int t = t0 & 2047;
; #pragma unroll
;                         for (int hf = 0; hf < 2; ++hf) {
;                             f32x4 cs, sn;
;                             if (m < 2) { const float c1 = ropeA[(t >> 6) * 16 + d], s1 = ropeA[1024 + (t >> 6) * 16 + d]; cs = (f32x4){c1, c1, c1, c1}; sn = (f32x4){s1, s1, s1, s1}; }
;                             else { const float* cb = ropeA + 2048 + (d - 16) * 64 + (t & 63) + 4 * hf; cs = *(const f32x4*)(cb); sn = *(const f32x4*)(cb + 1024); }
; #pragma unroll
;                             for (int jj = 0; jj < 4; ++jj) { const float pr = __shfl_xor(v[4 * hf + jj], 4); v[4 * hf + jj] = v[4 * hf + jj] * cs[jj] + sgn * pr * sn[jj]; }
;                             __builtin_amdgcn_sched_barrier(0);
;                         }
;                     }
;                     float zf[8], zb[8]; zf[0] = zf0; zb[0] = zb0;
; #pragma unroll
;                     for (int jj = 1; jj < 8; ++jj) { zf[jj] = zf[jj - 1] * zfs; zb[jj] = zb[jj - 1] * zbs; }
;                     u32x4 wf, wb;
;                     wf.x = cvt_pk_bf16(v[0] * zf[0], v[1] * zf[1]); wf.y = cvt_pk_bf16(v[2] * zf[2], v[3] * zf[3]); wf.z = cvt_pk_bf16(v[4] * zf[4], v[5] * zf[5]); wf.w = cvt_pk_bf16(v[6] * zf[6], v[7] * zf[7]);
	v_mov_b32_e32 v90, v84
	v_mov_b32_e32 v68, v65
	v_mov_b32_e32 v100, v85
	v_mov_b32_e32 v65, v70
	v_mov_b32_e32 v102, v86
	v_mov_b32_e32 v70, v67
	v_mov_b32_e32 v108, v87
	v_pk_mul_f32 v[66:67], v[88:89], v[90:91]
	v_pk_mul_f32 v[68:69], v[68:69], v[100:101]
	v_pk_mul_f32 v[64:65], v[64:65], v[102:103]
	v_pk_mul_f32 v[70:71], v[70:71], v[108:109]
	v_add_f32_e32 v84, v66, v67
	v_add_f32_e32 v85, v68, v69
	v_add_f32_e32 v86, v64, v65
	v_add_f32_e32 v71, v70, v71
	v_mul_f32_e32 v64, v180, v110
	v_mul_f32_e32 v65, v181, v111
	v_cvt_pk_bf16_f32 v64, v64, v65
	v_mul_f32_e32 v65, v167, v116
	v_mul_f32_e32 v66, v183, v117
	v_cvt_pk_bf16_f32 v65, v65, v66
	v_mul_f32_e32 v66, v182, v84
	v_mul_f32_e32 v67, v185, v85
	v_cvt_pk_bf16_f32 v66, v66, v67
	v_mul_f32_e32 v67, v184, v86
	v_mul_f32_e32 v68, v159, v71
	v_cvt_pk_bf16_f32 v67, v67, v68
	v_mul_f32_e32 v68, v150, v110
	v_mul_f32_e32 v69, v152, v111
	v_cvt_pk_bf16_f32 v68, v68, v69
	v_mul_f32_e32 v69, v154, v116
	v_mul_f32_e32 v70, v156, v117
	v_cvt_pk_bf16_f32 v69, v69, v70
	v_mul_f32_e32 v70, v158, v84
	v_mul_f32_e32 v84, v160, v85
	v_mul_f32_e32 v71, v155, v71
	v_cvt_pk_bf16_f32 v70, v70, v84
	v_mul_f32_e32 v84, v151, v86
	v_cvt_pk_bf16_f32 v71, v84, v71
	global_store_dwordx4 v[72:73], v[64:67], off offset:256
	global_store_dwordx4 v[74:75], v[68:71], off offset:256
	global_load_dword v64, v137, s[22:23] offset:8
	s_nop 0
	global_load_dword v70, v137, s[22:23] offset:24
	global_load_dword v67, v[146:147], off
	global_load_dword v74, v[148:149], off
	ds_bpermute_b32 v65, v177, v60
	ds_bpermute_b32 v68, v177, v62
	v_mov_b32_e32 v66, v60
	ds_bpermute_b32 v60, v177, v61
	ds_bpermute_b32 v71, v177, v63
	s_waitcnt lgkmcnt(3)
	v_cndmask_b32_e64 v75, v65, -v65, vcc
	s_waitcnt lgkmcnt(2)
	v_cndmask_b32_e64 v65, v68, -v68, vcc
	s_waitcnt vmcnt(3)
	v_mul_f32_e32 v72, 0x3fb8aa3b, v64
	s_waitcnt vmcnt(2)
	v_mul_f32_e32 v73, 0x3fb8aa3b, v70
	v_mul_f32_e32 v84, v72, v179
	s_waitcnt vmcnt(0)
	v_pk_mul_f32 v[68:69], v[66:67], v[74:75]
	s_waitcnt lgkmcnt(1)
	v_cndmask_b32_e64 v75, v60, -v60, vcc
	v_mov_b32_e32 v66, v61
	v_cmp_lt_f32_e64 s[4:5], s60, v72
	v_mul_f32_e32 v87, v73, v178
	v_pk_mul_f32 v[60:61], v[66:67], v[74:75]
	s_waitcnt lgkmcnt(0)
	v_cndmask_b32_e64 v75, v71, -v71, vcc
	v_mov_b32_e32 v66, v63
	v_cmp_gt_f32_e64 s[8:9], s59, v84
	v_cndmask_b32_e64 v86, 0, v176, s[4:5]
	v_cmp_gt_f32_e64 s[6:7], s59, v73
	s_and_b64 s[0:1], s[4:5], exec
	v_cmp_gt_f32_e64 s[4:5], s59, v87
	v_add_f32_e32 v110, v60, v61
	v_pk_mul_f32 v[60:61], v[66:67], v[74:75]
	v_cndmask_b32_e64 v66, 0, v176, s[8:9]
	v_cndmask_b32_e64 v88, 0, v176, s[6:7]
	v_add_f32_e32 v89, v68, v69
	v_fmac_f32_e32 v86, 0xbfb8aa3b, v64
	v_cndmask_b32_e64 v69, 0, v176, s[4:5]
	v_fmac_f32_e32 v66, v72, v179
	v_fmac_f32_e32 v88, 0x3fb8aa3b, v70
	v_exp_f32_e32 v68, v86
	v_fmac_f32_e32 v69, v73, v178
	v_exp_f32_e32 v66, v66
	v_exp_f32_e32 v70, v88
	v_exp_f32_e32 v69, v69
	v_cndmask_b32_e64 v63, 0, v175, s[8:9]
	s_cselect_b32 s8, 0xffffffc0, 0
	s_and_b64 s[0:1], s[6:7], exec
	v_cndmask_b32_e64 v64, 0, v175, s[4:5]
	s_cselect_b32 s0, 0xffffffc0, 0
	v_ldexp_f32 v100, v68, s8
	v_ldexp_f32 v63, v66, v63
	v_mul_f32_e32 v85, v62, v74
	v_ldexp_f32 v90, v70, s0
	v_ldexp_f32 v64, v69, v64
	v_mul_f32_e32 v75, v100, v63
	v_add_f32_e32 v111, v60, v61
	global_load_dword v108, v[148:149], off
	global_load_dword v69, v[146:147], off
	ds_bpermute_b32 v61, v177, v57
	ds_bpermute_b32 v60, v177, v56
	v_mov_b32_e32 v68, v57
	ds_bpermute_b32 v57, v177, v59
	ds_bpermute_b32 v66, v177, v58
	s_waitcnt lgkmcnt(3)
	v_cndmask_b32_e64 v109, v61, -v61, vcc
	s_waitcnt lgkmcnt(2)
	v_cndmask_b32_e64 v70, v60, -v60, vcc
	s_waitcnt lgkmcnt(0)
	v_cndmask_b32_e64 v72, v66, -v66, vcc
	s_waitcnt vmcnt(1)
	v_mul_f32_e32 v71, v56, v108
	s_waitcnt vmcnt(0)
	v_pk_mul_f32 v[60:61], v[68:69], v[108:109]
	v_cndmask_b32_e64 v109, v57, -v57, vcc
	v_mov_b32_e32 v68, v59
	v_add_f32_e32 v57, v60, v61
	v_pk_mul_f32 v[60:61], v[68:69], v[108:109]
	s_nop 0
	v_add_f32_e32 v59, v60, v61
	v_mov_b32_e32 v91, v67
	v_pk_mul_f32 v[60:61], v[90:91], v[64:65]
	v_mov_b32_e32 v91, v85
	v_pk_mul_f32 v[66:67], v[90:91], v[60:61]
	v_mov_b32_e32 v91, v69
	v_mov_b32_e32 v67, v70
	v_mul_f32_e32 v84, v100, v75
	v_pk_mul_f32 v[68:69], v[90:91], v[66:67]
	v_mov_b32_e32 v70, v90
	v_mul_f32_e32 v86, v100, v84
	v_pk_mul_f32 v[70:71], v[70:71], v[68:69]
	v_mul_f32_e32 v85, v100, v86
	v_mov_b32_e32 v71, v72
	v_mul_f32_e32 v88, v100, v85
	v_pk_mul_f32 v[72:73], v[90:91], v[70:71]
	v_fma_f32 v61, v62, v74, v61
	v_mul_f32_e32 v87, v100, v88
	v_mul_f32_e32 v65, v90, v72
	v_mul_f32_e32 v62, v84, v61
	v_fma_f32 v56, v56, v108, v69
	v_mul_f32_e32 v71, v100, v87
	v_mul_f32_e32 v67, v90, v65
	v_mul_f32_e32 v90, v63, v89
	v_mul_f32_e32 v91, v75, v110
	v_cvt_pk_bf16_f32 v100, v90, v91
	v_mul_f32_e32 v74, v86, v111
	v_cvt_pk_bf16_f32 v101, v62, v74
	v_mul_f32_e32 v62, v85, v56
	v_fma_f32 v58, v58, v108, v73
	v_mul_f32_e32 v69, v88, v57
	v_cvt_pk_bf16_f32 v102, v62, v69
	v_mul_f32_e32 v62, v87, v58
	v_mul_f32_e32 v69, v71, v59
	v_cvt_pk_bf16_f32 v103, v62, v69
	v_mul_f32_e32 v62, v64, v89
	v_mul_f32_e32 v56, v70, v56
	v_mul_f32_e32 v57, v72, v57
	v_mul_f32_e32 v69, v60, v110
	v_cvt_pk_bf16_f32 v108, v62, v69
	v_mul_f32_e32 v61, v66, v61
	v_mul_f32_e32 v62, v68, v111
	v_cvt_pk_bf16_f32 v109, v61, v62
	v_cvt_pk_bf16_f32 v110, v56, v57
	v_mul_f32_e32 v56, v65, v58
	v_mul_f32_e32 v57, v67, v59
	s_mov_b64 s[0:1], 0x1000000
	v_cvt_pk_bf16_f32 v111, v56, v57
	v_lshl_add_u64 v[56:57], v[120:121], 0, s[0:1]
	s_mov_b32 s0, 0x1000000
	v_add_co_u32_e64 v58, s[4:5], s0, v120
	s_mov_b64 s[0:1], 0x3000000
	s_nop 0
	v_addc_co_u32_e64 v59, s[4:5], 0, v121, s[4:5]
	global_store_dwordx4 v[58:59], v[100:103], off
	v_lshl_add_u64 v[58:59], v[120:121], 0, s[0:1]
	s_mov_b32 s0, 0x3000000
	v_add_co_u32_e64 v90, s[4:5], s0, v120
	s_nop 1
	v_addc_co_u32_e64 v91, s[4:5], 0, v121, s[4:5]
	global_store_dwordx4 v[90:91], v[108:111], off
	global_load_dword v91, v[122:123], off
	s_nop 0
	global_load_dword v100, v[124:125], off
	ds_bpermute_b32 v61, v177, v52
	v_mov_b32_e32 v90, v52
	ds_bpermute_b32 v52, v177, v53
	ds_bpermute_b32 v62, v177, v54
	ds_bpermute_b32 v69, v177, v55
	s_waitcnt lgkmcnt(3)
; __device__ __forceinline__ unsigned cvt_pk_bf16(float lo, float hi) { unsigned r; asm volatile("v_cvt_pk_bf16_f32 %0, %1, %2" : "=v"(r) : "v"(lo), "v"(hi)); return r; }
;     __device__ __forceinline__ void operator()(const AccT& acc, const Unit& u, int wr, int wc, int fr, int fq) const {
;     ...
;                 const int r = rbase + ai * 128 + m * 16;
;                 const int d = 4 * (2 * m + (fr >> 3)) + j;
; #pragma unroll
;                 for (int bj = 0; bj < 2; ++bj) {
;                     const int t0 = tb + bj * 128;
;                     float v[8];
; #pragma unroll
;                     for (int jj = 0; jj < 4; ++jj) { v[jj] = acc[ai][bj][m][0][jj]; v[4 + jj] = acc[ai][bj][m][1][jj]; }
;                     if constexpr (ROPE) {
;                         const int t = t0 & 2047;
; #pragma unroll
;                         for (int hf = 0; hf < 2; ++hf) {
;                             f32x4 cs, sn;
;                             if (m < 2) { const float c1 = ropeA[(t >> 6) * 16 + d], s1 = ropeA[1024 + (t >> 6) * 16 + d]; cs = (f32x4){c1, c1, c1, c1}; sn = (f32x4){s1, s1, s1, s1}; }
;                             else { const float* cb = ropeA + 2048 + (d - 16) * 64 + (t & 63) + 4 * hf; cs = *(const f32x4*)(cb); sn = *(const f32x4*)(cb + 1024); }
; #pragma unroll
;                             for (int jj = 0; jj < 4; ++jj) { const float pr = __shfl_xor(v[4 * hf + jj], 4); v[4 * hf + jj] = v[4 * hf + jj] * cs[jj] + sgn * pr * sn[jj]; }
;                             __builtin_amdgcn_sched_barrier(0);
;                         }
;                     }
;                     float zf[8], zb[8]; zf[0] = zf0; zb[0] = zb0;
; #pragma unroll
;                     for (int jj = 1; jj < 8; ++jj) { zf[jj] = zf[jj - 1] * zfs; zb[jj] = zb[jj - 1] * zbs; }
;                     u32x4 wf, wb;
;                     wf.x = cvt_pk_bf16(v[0] * zf[0], v[1] * zf[1]); wf.y = cvt_pk_bf16(v[2] * zf[2], v[3] * zf[3]); wf.z = cvt_pk_bf16(v[4] * zf[4], v[5] * zf[5]); wf.w = cvt_pk_bf16(v[6] * zf[6], v[7] * zf[7]);
;                     wb.x = cvt_pk_bf16(v[0] * zb[0], v[1] * zb[1]); wb.y = cvt_pk_bf16(v[2] * zb[2], v[3] * zb[3]); wb.z = cvt_pk_bf16(v[4] * zb[4], v[5] * zb[5]); wb.w = cvt_pk_bf16(v[6] * zb[6], v[7] * zb[7]);
;                     *(u32x4*)(KTZ + (size_t)r * NT + t0) = wf;
;                     *(u32x4*)(KTZ + (size_t)(256 + r) * NT + t0) = wb;
	v_cndmask_b32_e64 v101, v61, -v61, vcc
	s_waitcnt vmcnt(0)
	v_pk_mul_f32 v[102:103], v[90:91], v[100:101]
	s_waitcnt lgkmcnt(2)
	v_cndmask_b32_e64 v101, v52, -v52, vcc
	v_mov_b32_e32 v90, v53
	v_pk_mul_f32 v[52:53], v[90:91], v[100:101]
	s_waitcnt lgkmcnt(1)
	v_cndmask_b32_e64 v101, v62, -v62, vcc
	v_mov_b32_e32 v90, v54
	v_add_f32_e32 v62, v52, v53
	v_pk_mul_f32 v[52:53], v[90:91], v[100:101]
	s_waitcnt lgkmcnt(0)
	v_cndmask_b32_e64 v101, v69, -v69, vcc
	v_mov_b32_e32 v90, v55
	v_add_f32_e32 v69, v52, v53
	v_pk_mul_f32 v[52:53], v[90:91], v[100:101]
	v_add_f32_e32 v61, v102, v103
	v_add_f32_e32 v73, v52, v53
	global_load_dword v53, v[122:123], off
	global_load_dword v54, v[124:125], off
	ds_bpermute_b32 v55, v177, v48
	v_mov_b32_e32 v52, v48
	ds_bpermute_b32 v48, v177, v49
	ds_bpermute_b32 v74, v177, v50
	ds_bpermute_b32 v89, v177, v51
	s_waitcnt lgkmcnt(3)
	v_cndmask_b32_e64 v55, v55, -v55, vcc
	s_waitcnt vmcnt(0)
	v_pk_mul_f32 v[90:91], v[52:53], v[54:55]
	s_waitcnt lgkmcnt(2)
	v_cndmask_b32_e64 v55, v48, -v48, vcc
	v_mov_b32_e32 v52, v49
	v_pk_mul_f32 v[48:49], v[52:53], v[54:55]
	s_waitcnt lgkmcnt(1)
	v_cndmask_b32_e64 v55, v74, -v74, vcc
	v_mov_b32_e32 v52, v50
	v_add_f32_e32 v74, v48, v49
	v_pk_mul_f32 v[48:49], v[52:53], v[54:55]
	s_waitcnt lgkmcnt(0)
	v_cndmask_b32_e64 v55, v89, -v89, vcc
	v_mov_b32_e32 v52, v51
	v_add_f32_e32 v89, v48, v49
	v_pk_mul_f32 v[48:49], v[52:53], v[54:55]
	v_add_f32_e32 v90, v90, v91
	v_add_f32_e32 v55, v48, v49
	v_mul_f32_e32 v48, v63, v61
	v_mul_f32_e32 v49, v75, v62
	v_cvt_pk_bf16_f32 v48, v48, v49
	v_mul_f32_e32 v49, v84, v69
	v_mul_f32_e32 v50, v86, v73
	v_cvt_pk_bf16_f32 v49, v49, v50
	v_mul_f32_e32 v50, v85, v90
	v_mul_f32_e32 v51, v88, v74
	v_cvt_pk_bf16_f32 v50, v50, v51
	v_mul_f32_e32 v51, v87, v89
	v_mul_f32_e32 v52, v71, v55
	v_cvt_pk_bf16_f32 v51, v51, v52
	v_mul_f32_e32 v52, v64, v61
	v_mul_f32_e32 v53, v60, v62
	v_cvt_pk_bf16_f32 v52, v52, v53
	v_mul_f32_e32 v53, v66, v69
	v_mul_f32_e32 v54, v68, v73
	v_cvt_pk_bf16_f32 v53, v53, v54
	v_mul_f32_e32 v54, v70, v90
	v_mul_f32_e32 v61, v72, v74
	v_mul_f32_e32 v55, v67, v55
	v_cvt_pk_bf16_f32 v54, v54, v61
	v_mul_f32_e32 v61, v65, v89
	v_cvt_pk_bf16_f32 v55, v61, v55
	global_store_dwordx4 v[56:57], v[48:51], off offset:256
	global_store_dwordx4 v[58:59], v[52:55], off offset:256
	global_load_dword v49, v[112:113], off
	s_nop 0
	global_load_dword v50, v[114:115], off
	ds_bpermute_b32 v51, v177, v44
	v_mov_b32_e32 v48, v44
	ds_bpermute_b32 v44, v177, v45
	ds_bpermute_b32 v54, v177, v46
	ds_bpermute_b32 v55, v177, v47
	s_waitcnt lgkmcnt(3)
	v_cndmask_b32_e64 v51, v51, -v51, vcc
	s_waitcnt vmcnt(0)
	v_pk_mul_f32 v[52:53], v[48:49], v[50:51]
	s_waitcnt lgkmcnt(2)
	v_cndmask_b32_e64 v51, v44, -v44, vcc
	v_mov_b32_e32 v48, v45
	v_pk_mul_f32 v[44:45], v[48:49], v[50:51]
	s_waitcnt lgkmcnt(1)
	v_cndmask_b32_e64 v51, v54, -v54, vcc
	v_mov_b32_e32 v48, v46
	v_add_f32_e32 v52, v52, v53
	v_add_f32_e32 v53, v44, v45
	v_pk_mul_f32 v[44:45], v[48:49], v[50:51]
	s_waitcnt lgkmcnt(0)
	v_cndmask_b32_e64 v51, v55, -v55, vcc
	v_mov_b32_e32 v48, v47
	v_add_f32_e32 v54, v44, v45
	v_pk_mul_f32 v[44:45], v[48:49], v[50:51]
	s_nop 0
	v_add_f32_e32 v50, v44, v45
	global_load_dword v45, v[112:113], off
	global_load_dword v46, v[114:115], off
	ds_bpermute_b32 v47, v177, v40
	v_mov_b32_e32 v44, v40
	ds_bpermute_b32 v40, v177, v41
	ds_bpermute_b32 v51, v177, v42
	ds_bpermute_b32 v55, v177, v43
	s_waitcnt lgkmcnt(3)
	v_cndmask_b32_e64 v47, v47, -v47, vcc
	s_waitcnt vmcnt(0)
	v_pk_mul_f32 v[48:49], v[44:45], v[46:47]
	s_waitcnt lgkmcnt(2)
	v_cndmask_b32_e64 v47, v40, -v40, vcc
	v_mov_b32_e32 v44, v41
	v_pk_mul_f32 v[40:41], v[44:45], v[46:47]
	s_waitcnt lgkmcnt(1)
	v_cndmask_b32_e64 v47, v51, -v51, vcc
	v_mov_b32_e32 v44, v42
	v_add_f32_e32 v48, v48, v49
	v_add_f32_e32 v49, v40, v41
	v_pk_mul_f32 v[40:41], v[44:45], v[46:47]
	s_waitcnt lgkmcnt(0)
	v_cndmask_b32_e64 v47, v55, -v55, vcc
	v_mov_b32_e32 v44, v43
	v_add_f32_e32 v51, v40, v41
	v_pk_mul_f32 v[40:41], v[44:45], v[46:47]
	s_nop 0
	v_add_f32_e32 v40, v40, v41
	v_mul_f32_e32 v41, v63, v52
	v_mul_f32_e32 v42, v75, v53
	v_cvt_pk_bf16_f32 v42, v41, v42
	v_mul_f32_e32 v41, v84, v54
	v_mul_f32_e32 v43, v86, v50
	v_cvt_pk_bf16_f32 v43, v41, v43
	v_mul_f32_e32 v41, v85, v48
	v_mul_f32_e32 v44, v88, v49
	v_cvt_pk_bf16_f32 v44, v41, v44
	v_mul_f32_e32 v41, v87, v51
	v_mul_f32_e32 v45, v71, v40
	v_cvt_pk_bf16_f32 v45, v41, v45
	v_mul_f32_e32 v41, v64, v52
	v_mul_f32_e32 v46, v60, v53
	v_cvt_pk_bf16_f32 v46, v41, v46
	v_mul_f32_e32 v41, v66, v54
	v_mul_f32_e32 v47, v68, v50
	v_cvt_pk_bf16_f32 v47, v41, v47
	v_mul_f32_e32 v41, v70, v48
	v_mul_f32_e32 v48, v72, v49
	v_cvt_pk_bf16_f32 v48, v41, v48
	v_mul_f32_e32 v41, v65, v51
	v_mul_f32_e32 v40, v67, v40
	s_mov_b64 s[0:1], 0x1200000
	v_cvt_pk_bf16_f32 v49, v41, v40
	v_lshl_add_u64 v[40:41], v[120:121], 0, s[0:1]
	s_mov_b32 s0, 0x1200000
	v_add_co_u32_e64 v50, s[4:5], s0, v120
	s_mov_b64 s[0:1], 0x3200000
	s_nop 0
	v_addc_co_u32_e64 v51, s[4:5], 0, v121, s[4:5]
	global_store_dwordx4 v[50:51], v[42:45], off
	s_nop 1
	v_lshl_add_u64 v[42:43], v[120:121], 0, s[0:1]
	s_mov_b32 s0, 0x3200000
	v_add_co_u32_e64 v44, s[4:5], s0, v120
	s_nop 1
	v_addc_co_u32_e64 v45, s[4:5], 0, v121, s[4:5]
	global_store_dwordx4 v[44:45], v[46:49], off
	global_load_dword v45, v[104:105], off
	s_nop 0
	global_load_dword v46, v[106:107], off
	ds_bpermute_b32 v47, v177, v36
	v_mov_b32_e32 v44, v36
	ds_bpermute_b32 v36, v177, v37
	ds_bpermute_b32 v50, v177, v38
	ds_bpermute_b32 v51, v177, v39
	s_waitcnt lgkmcnt(3)
	v_cndmask_b32_e64 v47, v47, -v47, vcc
	s_waitcnt vmcnt(0)
	v_pk_mul_f32 v[48:49], v[44:45], v[46:47]
	s_waitcnt lgkmcnt(2)
; __device__ __forceinline__ unsigned cvt_pk_bf16(float lo, float hi) { unsigned r; asm volatile("v_cvt_pk_bf16_f32 %0, %1, %2" : "=v"(r) : "v"(lo), "v"(hi)); return r; }
;     __device__ __forceinline__ void operator()(const AccT& acc, const Unit& u, int wr, int wc, int fr, int fq) const {
;     ...
;                 const int r = rbase + ai * 128 + m * 16;
;                 const int d = 4 * (2 * m + (fr >> 3)) + j;
; #pragma unroll
;                 for (int bj = 0; bj < 2; ++bj) {
;                     const int t0 = tb + bj * 128;
;                     float v[8];
; #pragma unroll
;                     for (int jj = 0; jj < 4; ++jj) { v[jj] = acc[ai][bj][m][0][jj]; v[4 + jj] = acc[ai][bj][m][1][jj]; }
;                     if constexpr (ROPE) {
;                         const int t = t0 & 2047;
; #pragma unroll
;                         for (int hf = 0; hf < 2; ++hf) {
;                             f32x4 cs, sn;
;                             if (m < 2) { const float c1 = ropeA[(t >> 6) * 16 + d], s1 = ropeA[1024 + (t >> 6) * 16 + d]; cs = (f32x4){c1, c1, c1, c1}; sn = (f32x4){s1, s1, s1, s1}; }
;                             else { const float* cb = ropeA + 2048 + (d - 16) * 64 + (t & 63) + 4 * hf; cs = *(const f32x4*)(cb); sn = *(const f32x4*)(cb + 1024); }
; #pragma unroll
;                             for (int jj = 0; jj < 4; ++jj) { const float pr = __shfl_xor(v[4 * hf + jj], 4); v[4 * hf + jj] = v[4 * hf + jj] * cs[jj] + sgn * pr * sn[jj]; }
;                             __builtin_amdgcn_sched_barrier(0);
;                         }
;                     }
;                     float zf[8], zb[8]; zf[0] = zf0; zb[0] = zb0;
; #pragma unroll
;                     for (int jj = 1; jj < 8; ++jj) { zf[jj] = zf[jj - 1] * zfs; zb[jj] = zb[jj - 1] * zbs; }
;                     u32x4 wf, wb;
;                     wf.x = cvt_pk_bf16(v[0] * zf[0], v[1] * zf[1]); wf.y = cvt_pk_bf16(v[2] * zf[2], v[3] * zf[3]); wf.z = cvt_pk_bf16(v[4] * zf[4], v[5] * zf[5]); wf.w = cvt_pk_bf16(v[6] * zf[6], v[7] * zf[7]);
;                     wb.x = cvt_pk_bf16(v[0] * zb[0], v[1] * zb[1]); wb.y = cvt_pk_bf16(v[2] * zb[2], v[3] * zb[3]); wb.z = cvt_pk_bf16(v[4] * zb[4], v[5] * zb[5]); wb.w = cvt_pk_bf16(v[6] * zb[6], v[7] * zb[7]);
;                     *(u32x4*)(KTZ + (size_t)r * NT + t0) = wf;
;                     *(u32x4*)(KTZ + (size_t)(256 + r) * NT + t0) = wb;
	v_cndmask_b32_e64 v47, v36, -v36, vcc
	v_mov_b32_e32 v44, v37
	v_pk_mul_f32 v[36:37], v[44:45], v[46:47]
	s_waitcnt lgkmcnt(1)
	v_cndmask_b32_e64 v47, v50, -v50, vcc
	v_mov_b32_e32 v44, v38
	v_add_f32_e32 v48, v48, v49
	v_add_f32_e32 v49, v36, v37
	v_pk_mul_f32 v[36:37], v[44:45], v[46:47]
	s_waitcnt lgkmcnt(0)
	v_cndmask_b32_e64 v47, v51, -v51, vcc
	v_mov_b32_e32 v44, v39
	v_add_f32_e32 v50, v36, v37
	v_pk_mul_f32 v[36:37], v[44:45], v[46:47]
	s_nop 0
	v_add_f32_e32 v46, v36, v37
	global_load_dword v37, v[104:105], off
	global_load_dword v38, v[106:107], off
	ds_bpermute_b32 v39, v177, v32
	v_mov_b32_e32 v36, v32
	ds_bpermute_b32 v32, v177, v33
	ds_bpermute_b32 v47, v177, v34
	ds_bpermute_b32 v51, v177, v35
	s_waitcnt lgkmcnt(3)
	v_cndmask_b32_e64 v39, v39, -v39, vcc
	s_waitcnt vmcnt(0)
	v_pk_mul_f32 v[44:45], v[36:37], v[38:39]
	s_waitcnt lgkmcnt(2)
	v_cndmask_b32_e64 v39, v32, -v32, vcc
	v_mov_b32_e32 v36, v33
	v_pk_mul_f32 v[32:33], v[36:37], v[38:39]
	s_waitcnt lgkmcnt(1)
	v_cndmask_b32_e64 v39, v47, -v47, vcc
	v_mov_b32_e32 v36, v34
	v_add_f32_e32 v44, v44, v45
	v_add_f32_e32 v45, v32, v33
	v_pk_mul_f32 v[32:33], v[36:37], v[38:39]
	s_waitcnt lgkmcnt(0)
	v_cndmask_b32_e64 v39, v51, -v51, vcc
	v_mov_b32_e32 v36, v35
	v_add_f32_e32 v47, v32, v33
	v_pk_mul_f32 v[32:33], v[36:37], v[38:39]
	s_nop 0
	v_add_f32_e32 v39, v32, v33
	v_mul_f32_e32 v32, v63, v48
	v_mul_f32_e32 v33, v75, v49
	v_cvt_pk_bf16_f32 v32, v32, v33
	v_mul_f32_e32 v33, v84, v50
	v_mul_f32_e32 v34, v86, v46
	v_cvt_pk_bf16_f32 v33, v33, v34
	v_mul_f32_e32 v34, v85, v44
	v_mul_f32_e32 v35, v88, v45
	v_cvt_pk_bf16_f32 v34, v34, v35
	v_mul_f32_e32 v35, v87, v47
	v_mul_f32_e32 v36, v71, v39
	v_cvt_pk_bf16_f32 v35, v35, v36
	v_mul_f32_e32 v36, v64, v48
	v_mul_f32_e32 v37, v60, v49
	v_cvt_pk_bf16_f32 v36, v36, v37
	v_mul_f32_e32 v37, v66, v50
	v_mul_f32_e32 v38, v68, v46
	v_cvt_pk_bf16_f32 v37, v37, v38
	v_mul_f32_e32 v38, v70, v44
	v_mul_f32_e32 v44, v72, v45
	v_mul_f32_e32 v39, v67, v39
	v_cvt_pk_bf16_f32 v38, v38, v44
	v_mul_f32_e32 v44, v65, v47
	v_cvt_pk_bf16_f32 v39, v44, v39
	global_store_dwordx4 v[40:41], v[32:35], off offset:256
	global_store_dwordx4 v[42:43], v[36:39], off offset:256
	global_load_dwordx4 v[32:35], v[98:99], off
	s_nop 0
	global_load_dwordx4 v[36:39], v[96:97], off
	ds_bpermute_b32 v41, v177, v28
	ds_bpermute_b32 v42, v177, v29
	ds_bpermute_b32 v44, v177, v30
	ds_bpermute_b32 v46, v177, v31
	v_mov_b32_e32 v40, v28
	v_mov_b32_e32 v28, v30
	s_waitcnt lgkmcnt(3)
	v_cndmask_b32_e64 v43, v41, -v41, vcc
	s_waitcnt lgkmcnt(2)
	v_cndmask_b32_e64 v45, v42, -v42, vcc
	s_waitcnt lgkmcnt(1)
	v_cndmask_b32_e64 v47, v44, -v44, vcc
	s_waitcnt lgkmcnt(0)
	v_cndmask_b32_e64 v49, v46, -v46, vcc
	s_waitcnt vmcnt(1)
	v_mov_b32_e32 v41, v32
	s_waitcnt vmcnt(0)
	v_mov_b32_e32 v42, v36
	v_mov_b32_e32 v32, v29
	v_mov_b32_e32 v44, v37
	v_mov_b32_e32 v29, v34
	v_mov_b32_e32 v46, v38
	v_mov_b32_e32 v34, v31
	v_mov_b32_e32 v48, v39
	v_pk_mul_f32 v[30:31], v[40:41], v[42:43]
	v_pk_mul_f32 v[32:33], v[32:33], v[44:45]
	v_pk_mul_f32 v[28:29], v[28:29], v[46:47]
	v_pk_mul_f32 v[34:35], v[34:35], v[48:49]
	v_add_f32_e32 v46, v30, v31
	v_add_f32_e32 v47, v32, v33
	v_add_f32_e32 v48, v28, v29
	v_add_f32_e32 v49, v34, v35
	global_load_dwordx4 v[28:31], v[92:93], off offset:16
	global_load_dwordx4 v[32:35], v[94:95], off offset:16
	ds_bpermute_b32 v37, v177, v24
	ds_bpermute_b32 v38, v177, v25
	ds_bpermute_b32 v40, v177, v26
	ds_bpermute_b32 v42, v177, v27
	v_mov_b32_e32 v36, v24
	v_mov_b32_e32 v24, v26
	s_waitcnt lgkmcnt(3)
	v_cndmask_b32_e64 v39, v37, -v37, vcc
	s_waitcnt lgkmcnt(2)
	v_cndmask_b32_e64 v41, v38, -v38, vcc
	s_waitcnt lgkmcnt(1)
	v_cndmask_b32_e64 v43, v40, -v40, vcc
	s_waitcnt lgkmcnt(0)
	v_cndmask_b32_e64 v45, v42, -v42, vcc
	s_waitcnt vmcnt(1)
	v_mov_b32_e32 v37, v28
	s_waitcnt vmcnt(0)
	v_mov_b32_e32 v38, v32
	v_mov_b32_e32 v28, v25
	v_mov_b32_e32 v40, v33
	v_mov_b32_e32 v25, v30
	v_mov_b32_e32 v42, v34
	v_mov_b32_e32 v30, v27
	v_mov_b32_e32 v44, v35
	v_pk_mul_f32 v[26:27], v[36:37], v[38:39]
	v_pk_mul_f32 v[28:29], v[28:29], v[40:41]
	v_pk_mul_f32 v[24:25], v[24:25], v[42:43]
	v_pk_mul_f32 v[30:31], v[30:31], v[44:45]
	v_add_f32_e32 v32, v26, v27
	v_add_f32_e32 v33, v28, v29
	v_add_f32_e32 v24, v24, v25
	v_add_f32_e32 v25, v30, v31
	v_mul_f32_e32 v26, v63, v46
	v_mul_f32_e32 v27, v75, v47
	v_cvt_pk_bf16_f32 v26, v26, v27
	v_mul_f32_e32 v27, v84, v48
	v_mul_f32_e32 v28, v86, v49
	v_cvt_pk_bf16_f32 v27, v27, v28
	v_mul_f32_e32 v28, v85, v32
	v_mul_f32_e32 v29, v88, v33
	v_cvt_pk_bf16_f32 v28, v28, v29
	v_mul_f32_e32 v29, v87, v24
	v_mul_f32_e32 v30, v71, v25
	v_cvt_pk_bf16_f32 v29, v29, v30
	v_mul_f32_e32 v30, v64, v46
	v_mul_f32_e32 v31, v60, v47
	v_cvt_pk_bf16_f32 v30, v30, v31
	v_mul_f32_e32 v31, v66, v48
	v_mul_f32_e32 v32, v70, v32
	v_mul_f32_e32 v33, v72, v33
	v_mul_f32_e32 v24, v65, v24
	v_mul_f32_e32 v25, v67, v25
	s_mov_b64 s[0:1], 0x1400000
	v_mul_f32_e32 v34, v68, v49
	v_cvt_pk_bf16_f32 v31, v31, v34
	v_cvt_pk_bf16_f32 v32, v32, v33
	v_cvt_pk_bf16_f32 v33, v24, v25
	v_lshl_add_u64 v[24:25], v[120:121], 0, s[0:1]
	s_mov_b32 s0, 0x1400000
	v_add_co_u32_e64 v34, s[4:5], s0, v120
	s_mov_b64 s[0:1], 0x3400000
	s_nop 0
	v_addc_co_u32_e64 v35, s[4:5], 0, v121, s[4:5]
	global_store_dwordx4 v[34:35], v[26:29], off
	s_nop 1
	v_lshl_add_u64 v[26:27], v[120:121], 0, s[0:1]
	s_mov_b32 s0, 0x3400000
	v_add_co_u32_e64 v28, s[4:5], s0, v120
	s_nop 1
	v_addc_co_u32_e64 v29, s[4:5], 0, v121, s[4:5]
	global_store_dwordx4 v[28:29], v[30:33], off
	global_load_dwordx4 v[28:31], v[98:99], off
	s_nop 0
	global_load_dwordx4 v[32:35], v[96:97], off
	ds_bpermute_b32 v37, v177, v20
	ds_bpermute_b32 v38, v177, v21
	ds_bpermute_b32 v40, v177, v22
	ds_bpermute_b32 v42, v177, v23
	v_mov_b32_e32 v36, v20
	v_mov_b32_e32 v20, v22
	s_waitcnt lgkmcnt(3)
; __device__ __forceinline__ unsigned cvt_pk_bf16(float lo, float hi) { unsigned r; asm volatile("v_cvt_pk_bf16_f32 %0, %1, %2" : "=v"(r) : "v"(lo), "v"(hi)); return r; }
;     __device__ __forceinline__ void operator()(const AccT& acc, const Unit& u, int wr, int wc, int fr, int fq) const {
;     ...
;                         const int t = t0 & 2047;
; #pragma unroll
;                         for (int hf = 0; hf < 2; ++hf) {
;                             f32x4 cs, sn;
;                             if (m < 2) { const float c1 = ropeA[(t >> 6) * 16 + d], s1 = ropeA[1024 + (t >> 6) * 16 + d]; cs = (f32x4){c1, c1, c1, c1}; sn = (f32x4){s1, s1, s1, s1}; }
;                             else { const float* cb = ropeA + 2048 + (d - 16) * 64 + (t & 63) + 4 * hf; cs = *(const f32x4*)(cb); sn = *(const f32x4*)(cb + 1024); }
; #pragma unroll
;                             for (int jj = 0; jj < 4; ++jj) { const float pr = __shfl_xor(v[4 * hf + jj], 4); v[4 * hf + jj] = v[4 * hf + jj] * cs[jj] + sgn * pr * sn[jj]; }
;                             __builtin_amdgcn_sched_barrier(0);
;                         }
;                     }
;                     float zf[8], zb[8]; zf[0] = zf0; zb[0] = zb0;
; #pragma unroll
;                     for (int jj = 1; jj < 8; ++jj) { zf[jj] = zf[jj - 1] * zfs; zb[jj] = zb[jj - 1] * zbs; }
;                     u32x4 wf, wb;
;                     wf.x = cvt_pk_bf16(v[0] * zf[0], v[1] * zf[1]); wf.y = cvt_pk_bf16(v[2] * zf[2], v[3] * zf[3]); wf.z = cvt_pk_bf16(v[4] * zf[4], v[5] * zf[5]); wf.w = cvt_pk_bf16(v[6] * zf[6], v[7] * zf[7]);
;                     wb.x = cvt_pk_bf16(v[0] * zb[0], v[1] * zb[1]); wb.y = cvt_pk_bf16(v[2] * zb[2], v[3] * zb[3]); wb.z = cvt_pk_bf16(v[4] * zb[4], v[5] * zb[5]); wb.w = cvt_pk_bf16(v[6] * zb[6], v[7] * zb[7]);
;                     *(u32x4*)(KTZ + (size_t)r * NT + t0) = wf;
;                     *(u32x4*)(KTZ + (size_t)(256 + r) * NT + t0) = wb;
	v_cndmask_b32_e64 v39, v37, -v37, vcc
	s_waitcnt lgkmcnt(2)
	v_cndmask_b32_e64 v41, v38, -v38, vcc
	s_waitcnt lgkmcnt(1)
	v_cndmask_b32_e64 v43, v40, -v40, vcc
	s_waitcnt lgkmcnt(0)
	v_cndmask_b32_e64 v45, v42, -v42, vcc
	s_waitcnt vmcnt(1)
	v_mov_b32_e32 v37, v28
	s_waitcnt vmcnt(0)
	v_mov_b32_e32 v38, v32
	v_mov_b32_e32 v28, v21
	v_mov_b32_e32 v40, v33
	v_mov_b32_e32 v21, v30
	v_mov_b32_e32 v42, v34
	v_mov_b32_e32 v30, v23
	v_mov_b32_e32 v44, v35
	v_pk_mul_f32 v[22:23], v[36:37], v[38:39]
	v_pk_mul_f32 v[28:29], v[28:29], v[40:41]
	v_pk_mul_f32 v[20:21], v[20:21], v[42:43]
	v_pk_mul_f32 v[30:31], v[30:31], v[44:45]
	v_add_f32_e32 v42, v22, v23
	v_add_f32_e32 v43, v28, v29
	v_add_f32_e32 v44, v20, v21
	v_add_f32_e32 v45, v30, v31
	global_load_dwordx4 v[20:23], v[92:93], off offset:16
	global_load_dwordx4 v[28:31], v[94:95], off offset:16
	ds_bpermute_b32 v33, v177, v16
	ds_bpermute_b32 v34, v177, v17
	ds_bpermute_b32 v36, v177, v18
	ds_bpermute_b32 v38, v177, v19
	v_mov_b32_e32 v32, v16
	v_mov_b32_e32 v16, v18
	s_waitcnt lgkmcnt(3)
	v_cndmask_b32_e64 v35, v33, -v33, vcc
	s_waitcnt lgkmcnt(2)
	v_cndmask_b32_e64 v37, v34, -v34, vcc
	s_waitcnt lgkmcnt(1)
	v_cndmask_b32_e64 v39, v36, -v36, vcc
	s_waitcnt lgkmcnt(0)
	v_cndmask_b32_e64 v41, v38, -v38, vcc
	s_waitcnt vmcnt(1)
	v_mov_b32_e32 v33, v20
	s_waitcnt vmcnt(0)
	v_mov_b32_e32 v34, v28
	v_mov_b32_e32 v20, v17
	v_mov_b32_e32 v36, v29
	v_mov_b32_e32 v17, v22
	v_mov_b32_e32 v38, v30
	v_mov_b32_e32 v22, v19
	v_mov_b32_e32 v40, v31
	v_pk_mul_f32 v[18:19], v[32:33], v[34:35]
	v_pk_mul_f32 v[20:21], v[20:21], v[36:37]
	v_pk_mul_f32 v[16:17], v[16:17], v[38:39]
	v_pk_mul_f32 v[22:23], v[22:23], v[40:41]
	v_add_f32_e32 v28, v18, v19
	v_add_f32_e32 v29, v20, v21
	v_add_f32_e32 v30, v16, v17
	v_add_f32_e32 v23, v22, v23
	v_mul_f32_e32 v16, v63, v42
	v_mul_f32_e32 v17, v75, v43
	v_cvt_pk_bf16_f32 v16, v16, v17
	v_mul_f32_e32 v17, v84, v44
	v_mul_f32_e32 v18, v86, v45
	v_cvt_pk_bf16_f32 v17, v17, v18
	v_mul_f32_e32 v18, v85, v28
	v_mul_f32_e32 v19, v88, v29
	v_cvt_pk_bf16_f32 v18, v18, v19
	v_mul_f32_e32 v19, v87, v30
	v_mul_f32_e32 v20, v71, v23
	v_cvt_pk_bf16_f32 v19, v19, v20
	v_mul_f32_e32 v20, v64, v42
	v_mul_f32_e32 v21, v60, v43
	v_cvt_pk_bf16_f32 v20, v20, v21
	v_mul_f32_e32 v21, v66, v44
	v_mul_f32_e32 v22, v68, v45
	v_cvt_pk_bf16_f32 v21, v21, v22
	v_mul_f32_e32 v22, v70, v28
	v_mul_f32_e32 v28, v72, v29
	v_mul_f32_e32 v23, v67, v23
	v_cvt_pk_bf16_f32 v22, v22, v28
	v_mul_f32_e32 v28, v65, v30
	v_cvt_pk_bf16_f32 v23, v28, v23
	global_store_dwordx4 v[24:25], v[16:19], off offset:256
	global_store_dwordx4 v[26:27], v[20:23], off offset:256
	global_load_dwordx4 v[16:19], v[82:83], off
	s_nop 0
	global_load_dwordx4 v[20:23], v[80:81], off
	ds_bpermute_b32 v25, v177, v12
	ds_bpermute_b32 v26, v177, v13
	ds_bpermute_b32 v28, v177, v14
	ds_bpermute_b32 v30, v177, v15
	v_mov_b32_e32 v24, v12
	v_mov_b32_e32 v12, v14
	s_waitcnt lgkmcnt(3)
	v_cndmask_b32_e64 v27, v25, -v25, vcc
	s_waitcnt lgkmcnt(2)
	v_cndmask_b32_e64 v29, v26, -v26, vcc
	s_waitcnt lgkmcnt(1)
	v_cndmask_b32_e64 v31, v28, -v28, vcc
	s_waitcnt lgkmcnt(0)
	v_cndmask_b32_e64 v33, v30, -v30, vcc
	s_waitcnt vmcnt(1)
	v_mov_b32_e32 v25, v16
	s_waitcnt vmcnt(0)
	v_mov_b32_e32 v26, v20
	v_mov_b32_e32 v16, v13
	v_mov_b32_e32 v28, v21
	v_mov_b32_e32 v13, v18
	v_mov_b32_e32 v30, v22
	v_mov_b32_e32 v18, v15
	v_mov_b32_e32 v32, v23
	v_pk_mul_f32 v[14:15], v[24:25], v[26:27]
	v_pk_mul_f32 v[16:17], v[16:17], v[28:29]
	v_pk_mul_f32 v[12:13], v[12:13], v[30:31]
	v_pk_mul_f32 v[18:19], v[18:19], v[32:33]
	v_add_f32_e32 v30, v14, v15
	v_add_f32_e32 v31, v16, v17
	v_add_f32_e32 v32, v12, v13
	v_add_f32_e32 v33, v18, v19
	global_load_dwordx4 v[12:15], v[76:77], off offset:16
	global_load_dwordx4 v[16:19], v[78:79], off offset:16
	ds_bpermute_b32 v21, v177, v8
	ds_bpermute_b32 v22, v177, v9
	ds_bpermute_b32 v24, v177, v10
	ds_bpermute_b32 v26, v177, v11
	v_mov_b32_e32 v20, v8
	v_mov_b32_e32 v8, v10
	s_waitcnt lgkmcnt(3)
	v_cndmask_b32_e64 v23, v21, -v21, vcc
	s_waitcnt lgkmcnt(2)
	v_cndmask_b32_e64 v25, v22, -v22, vcc
	s_waitcnt lgkmcnt(1)
	v_cndmask_b32_e64 v27, v24, -v24, vcc
	s_waitcnt lgkmcnt(0)
	v_cndmask_b32_e64 v29, v26, -v26, vcc
	s_waitcnt vmcnt(1)
	v_mov_b32_e32 v21, v12
	s_waitcnt vmcnt(0)
; template <class Epi, class Sched>
; __device__ __forceinline__ void gemm_phase(LAS unsigned char* lds, const Gemm g, const Sched& S, const Epi& E) {
;     ...
;         E(acc, cur, wr, wc, fr, fq);
;         if (!has_next) break;
; #pragma unroll
;         for (int a = 0; a < 2; ++a)
; #pragma unroll
;             for (int b = 0; b < 2; ++b)
; #pragma unroll
;                 for (int m = 0; m < 4; ++m)
; #pragma unroll
;                     for (int n = 0; n < 2; ++n) acc[a][b][m][n] = (f32x4){0.f, 0.f, 0.f, 0.f};
;         cur = nxt; cA = nA; cB = nB; ++ui;
;     }
;     PG8_WAIT_V(0);
;     if (wr == 0) PG8_BAR;
;     PG8_BAR;
;     __device__ __forceinline__ void operator()(const AccT& acc, const Unit& u, int wr, int wc, int fr, int fq) const {
;     ...
;                         const int t = t0 & 2047;
; #pragma unroll
;                         for (int hf = 0; hf < 2; ++hf) {
;                             f32x4 cs, sn;
;                             if (m < 2) { const float c1 = ropeA[(t >> 6) * 16 + d], s1 = ropeA[1024 + (t >> 6) * 16 + d]; cs = (f32x4){c1, c1, c1, c1}; sn = (f32x4){s1, s1, s1, s1}; }
;                             else { const float* cb = ropeA + 2048 + (d - 16) * 64 + (t & 63) + 4 * hf; cs = *(const f32x4*)(cb); sn = *(const f32x4*)(cb + 1024); }
; #pragma unroll
;                             for (int jj = 0; jj < 4; ++jj) { const float pr = __shfl_xor(v[4 * hf + jj], 4); v[4 * hf + jj] = v[4 * hf + jj] * cs[jj] + sgn * pr * sn[jj]; }
;                             __builtin_amdgcn_sched_barrier(0);
;                         }
;                     }
;                     float zf[8], zb[8]; zf[0] = zf0; zb[0] = zb0;
; #pragma unroll
;                     for (int jj = 1; jj < 8; ++jj) { zf[jj] = zf[jj - 1] * zfs; zb[jj] = zb[jj - 1] * zbs; }
;                     u32x4 wf, wb;
;                     wf.x = cvt_pk_bf16(v[0] * zf[0], v[1] * zf[1]); wf.y = cvt_pk_bf16(v[2] * zf[2], v[3] * zf[3]); wf.z = cvt_pk_bf16(v[4] * zf[4], v[5] * zf[5]); wf.w = cvt_pk_bf16(v[6] * zf[6], v[7] * zf[7]);
;                     wb.x = cvt_pk_bf16(v[0] * zb[0], v[1] * zb[1]); wb.y = cvt_pk_bf16(v[2] * zb[2], v[3] * zb[3]); wb.z = cvt_pk_bf16(v[4] * zb[4], v[5] * zb[5]); wb.w = cvt_pk_bf16(v[6] * zb[6], v[7] * zb[7]);
;                     *(u32x4*)(KTZ + (size_t)r * NT + t0) = wf;
;                     *(u32x4*)(KTZ + (size_t)(256 + r) * NT + t0) = wb;
	v_mov_b32_e32 v22, v16
	v_mov_b32_e32 v12, v9
	v_mov_b32_e32 v24, v17
	v_mov_b32_e32 v9, v14
	v_mov_b32_e32 v26, v18
	v_mov_b32_e32 v14, v11
	v_mov_b32_e32 v28, v19
	v_pk_mul_f32 v[10:11], v[20:21], v[22:23]
	v_pk_mul_f32 v[12:13], v[12:13], v[24:25]
	v_pk_mul_f32 v[8:9], v[8:9], v[26:27]
	v_pk_mul_f32 v[14:15], v[14:15], v[28:29]
	v_add_f32_e32 v16, v10, v11
	v_add_f32_e32 v17, v12, v13
	v_add_f32_e32 v8, v8, v9
	v_add_f32_e32 v9, v14, v15
	v_mul_f32_e32 v10, v63, v30
	v_mul_f32_e32 v11, v75, v31
	v_cvt_pk_bf16_f32 v10, v10, v11
	v_mul_f32_e32 v11, v84, v32
	v_mul_f32_e32 v12, v86, v33
	v_cvt_pk_bf16_f32 v11, v11, v12
	v_mul_f32_e32 v12, v85, v16
	v_mul_f32_e32 v13, v88, v17
	v_cvt_pk_bf16_f32 v12, v12, v13
	v_mul_f32_e32 v13, v87, v8
	v_mul_f32_e32 v14, v71, v9
	v_cvt_pk_bf16_f32 v13, v13, v14
	v_mul_f32_e32 v14, v64, v30
	v_mul_f32_e32 v15, v60, v31
	v_cvt_pk_bf16_f32 v14, v14, v15
	v_mul_f32_e32 v15, v66, v32
	v_mul_f32_e32 v18, v68, v33
	v_cvt_pk_bf16_f32 v15, v15, v18
	v_add_co_u32_e64 v18, s[4:5], s63, v120
	v_mul_f32_e32 v16, v70, v16
	v_mul_f32_e32 v17, v72, v17
	v_addc_co_u32_e64 v19, s[4:5], 0, v121, s[4:5]
	v_cvt_pk_bf16_f32 v16, v16, v17
	v_mul_f32_e32 v8, v65, v8
	v_mul_f32_e32 v9, v67, v9
	v_cvt_pk_bf16_f32 v17, v8, v9
	global_store_dwordx4 v[18:19], v[10:13], off
	v_lshl_add_u64 v[8:9], v[120:121], 0, s[26:27]
	s_nop 0
	v_add_co_u32_e64 v12, s[4:5], s64, v120
	v_lshl_add_u64 v[10:11], v[120:121], 0, s[28:29]
	s_nop 0
	v_addc_co_u32_e64 v13, s[4:5], 0, v121, s[4:5]
	global_store_dwordx4 v[12:13], v[14:17], off
	global_load_dwordx4 v[12:15], v[82:83], off
	s_nop 0
	global_load_dwordx4 v[16:19], v[80:81], off
	ds_bpermute_b32 v34, v177, v4
	ds_bpermute_b32 v32, v177, v5
	ds_bpermute_b32 v33, v177, v6
	ds_bpermute_b32 v28, v177, v7
	global_load_dwordx4 v[20:23], v[76:77], off offset:16
	global_load_dwordx4 v[24:27], v[78:79], off offset:16
	s_waitcnt lgkmcnt(0)
	v_cndmask_b32_e64 v29, v28, -v28, vcc
	v_mov_b32_e32 v30, v7
	s_waitcnt vmcnt(3)
	v_mov_b32_e32 v31, v15
	s_waitcnt vmcnt(2)
	v_mov_b32_e32 v28, v19
	v_cndmask_b32_e64 v19, v33, -v33, vcc
	v_mov_b32_e32 v7, v14
	v_cndmask_b32_e64 v15, v32, -v32, vcc
	v_mov_b32_e32 v32, v5
	v_mov_b32_e32 v33, v13
	v_mov_b32_e32 v14, v17
	v_cndmask_b32_e64 v17, v34, -v34, vcc
	v_mov_b32_e32 v5, v12
	ds_bpermute_b32 v13, v177, v0
	v_mov_b32_e32 v12, v0
	ds_bpermute_b32 v34, v177, v1
	ds_bpermute_b32 v35, v177, v2
	v_mov_b32_e32 v0, v2
	ds_bpermute_b32 v2, v177, v3
	v_pk_mul_f32 v[28:29], v[30:31], v[28:29]
	v_pk_mul_f32 v[6:7], v[6:7], v[18:19]
	v_pk_mul_f32 v[14:15], v[32:33], v[14:15]
	v_pk_mul_f32 v[4:5], v[4:5], v[16:17]
	v_add_f32_e32 v18, v28, v29
	v_add_f32_e32 v19, v6, v7
	v_add_f32_e32 v28, v14, v15
	v_add_f32_e32 v29, v4, v5
	s_waitcnt lgkmcnt(3)
	v_cndmask_b32_e64 v5, v13, -v13, vcc
	s_waitcnt lgkmcnt(2)
	v_cndmask_b32_e64 v7, v34, -v34, vcc
	s_waitcnt lgkmcnt(1)
	v_cndmask_b32_e64 v15, v35, -v35, vcc
	s_waitcnt lgkmcnt(0)
	v_cndmask_b32_e64 v17, v2, -v2, vcc
	s_waitcnt vmcnt(1)
	v_mov_b32_e32 v13, v20
	s_waitcnt vmcnt(0)
	v_mov_b32_e32 v4, v24
	v_mov_b32_e32 v20, v1
	v_mov_b32_e32 v6, v25
	v_mov_b32_e32 v1, v22
	v_mov_b32_e32 v14, v26
	v_mov_b32_e32 v22, v3
	v_mov_b32_e32 v16, v27
	v_pk_mul_f32 v[2:3], v[12:13], v[4:5]
	v_pk_mul_f32 v[4:5], v[20:21], v[6:7]
	v_pk_mul_f32 v[0:1], v[0:1], v[14:15]
	v_pk_mul_f32 v[6:7], v[22:23], v[16:17]
	v_add_f32_e32 v12, v2, v3
	v_add_f32_e32 v13, v4, v5
	v_add_f32_e32 v14, v0, v1
	v_add_f32_e32 v7, v6, v7
	v_mul_f32_e32 v0, v63, v29
	v_mul_f32_e32 v1, v75, v28
	v_cvt_pk_bf16_f32 v0, v0, v1
	v_mul_f32_e32 v1, v84, v19
	v_mul_f32_e32 v2, v86, v18
	v_cvt_pk_bf16_f32 v1, v1, v2
	v_mul_f32_e32 v2, v85, v12
	v_mul_f32_e32 v3, v88, v13
	v_cvt_pk_bf16_f32 v2, v2, v3
	v_mul_f32_e32 v3, v87, v14
	v_mul_f32_e32 v4, v71, v7
	v_cvt_pk_bf16_f32 v3, v3, v4
	v_mul_f32_e32 v4, v64, v29
	v_mul_f32_e32 v5, v60, v28
	v_cvt_pk_bf16_f32 v4, v4, v5
	v_mul_f32_e32 v5, v66, v19
	v_mul_f32_e32 v6, v68, v18
	v_cvt_pk_bf16_f32 v5, v5, v6
	v_mul_f32_e32 v6, v70, v12
	v_mul_f32_e32 v12, v72, v13
	v_mul_f32_e32 v7, v67, v7
	v_cvt_pk_bf16_f32 v6, v6, v12
	v_mul_f32_e32 v12, v65, v14
	v_cvt_pk_bf16_f32 v7, v12, v7
	global_store_dwordx4 v[8:9], v[0:3], off offset:256
	global_store_dwordx4 v[10:11], v[4:7], off offset:256
	s_and_b64 vcc, exec, s[2:3]
	s_mov_b32 s33, s30
	s_mov_b64 s[4:5], s[38:39]
	s_mov_b64 s[0:1], s[36:37]
	s_cbranch_vccz .LBB0_606
	s_waitcnt vmcnt(0)
	s_cmpk_gt_u32 s42, 0xff
	s_cbranch_scc1 .LBB0_617
	s_barrier

; #define PG8_STAGE(bufoff, gbase, voff) do { _Pragma("unroll") for (int _i = 0; _i < 2; ++_i) \
;         __builtin_amdgcn_global_load_lds((const unsigned*)((const char*)(gbase) + (voff)[_i]), (LAS unsigned*)(lds + (bufoff) + ldsw + _i * 8192), 16, 0, 0); } while (0)
; #define PG8_LDA(dst, b, h) do { _Pragma("unroll") for (int m = 0; m < 4; ++m) _Pragma("unroll") for (int k = 0; k < 2; ++k) dst[m][k] = *(const LAS bf16x8*)(lds + PG8_SA(b, h) + aoff + m * 2048 + k * 1024); } while (0)
; #define PG8_LDB(dst, b, h) do { _Pragma("unroll") for (int n = 0; n < 2; ++n) _Pragma("unroll") for (int k = 0; k < 2; ++k) dst[n][k] = *(const LAS bf16x8*)(lds + PG8_SB(b, h) + boff + n * 2048 + k * 1024); } while (0)
; #define PG8_MMA(ai, bj, At, Bt) do { __builtin_amdgcn_s_setprio(1); _Pragma("unroll") for (int m = 0; m < 4; ++m) _Pragma("unroll") for (int n = 0; n < 2; ++n) _Pragma("unroll") for (int k = 0; k < 2; ++k) \
;         acc[ai][bj][m][n] = __builtin_amdgcn_mfma_f32_16x16x32_bf16(Bt[n][k], At[m][k], acc[ai][bj][m][n], 0, 0, 0); __builtin_amdgcn_s_setprio(0); } while (0)
; #define PG8_WAIT_L(n) asm volatile("s_waitcnt lgkmcnt(" #n ")" ::: "memory")
; template <class Epi, class Sched>
; __device__ __forceinline__ void gemm_phase(LAS unsigned char* lds, const Gemm g, const Sched& S, const Epi& E) {
;     ...
;         const bool has_next = S.next(ui + 1, nxt);
;         const char* nA = has_next ? (const char*)g.A + (size_t)nxt.pm * tstep : cA; const char* nB = has_next ? (const char*)g.Bt + (size_t)nxt.pn * tstep : cB;
;         for (int t = 0; t < nt; t += 2) {
;             const bool last = (t == nt - 2);
;             const char* a1 = cA + (size_t)(t + 1) * kstep;
;             const char* a2 = last ? nA : cA + (size_t)(t + 2) * kstep; const char* b2 = last ? nB : cB + (size_t)(t + 2) * kstep;
;             const char* a3 = a2 + kstep; const char* b3 = b2 + kstep;
;             PG8_LDB(B0, 0, 0); PG8_SCHED; PG8_LDA(At, 0, 0); PG8_STAGE(PG8_SA(1, 1), a1 + hstep, voffA);
;             PG8_WAIT_L(8); PG8_BAR; PG8_WAIT_L(0); PG8_MMA(0, 0, At, B0); PG8_BAR; PG8_SCHED;
;             PG8_LDB(B1, 0, 1); PG8_STAGE(PG8_SB(0, 0), b2, voffB);
;             PG8_BAR; PG8_WAIT_L(0); PG8_MMA(0, 1, At, B1); PG8_BAR;
;             PG8_LDA(At, 0, 1); PG8_STAGE(PG8_SA(0, 0), a2, voffA);
;             PG8_BAR; PG8_WAIT_L(0); PG8_MMA(1, 0, At, B0); PG8_BAR; PG8_SCHED;
.LBB0_632:
	s_ashr_i32 s23, s22, 31
	v_cmp_lt_i64_e32 vcc, s[24:25], v[140:141]
	s_lshl_b64 s[24:25], s[22:23], 19
	s_add_u32 s24, s38, s24
	s_addc_u32 s25, s39, s25
	s_and_b64 s[26:27], vcc, exec
	s_cselect_b32 s23, s25, s31
	s_cselect_b32 s61, s24, s30
	s_ashr_i32 s21, s20, 31
	s_lshl_b64 s[26:27], s[20:21], 19
	s_add_u32 s26, s96, s26
	s_addc_u32 s27, s97, s27
	s_and_b64 s[36:37], vcc, exec
	s_cselect_b32 s21, s27, s35
	s_cselect_b32 s62, s26, s34
	s_add_u32 s30, s30, 0x40080
	s_addc_u32 s31, s31, 0
	s_add_u32 s63, s34, 0x100
	s_addc_u32 s64, s35, 0
	s_mov_b32 s65, -2
	s_waitcnt lgkmcnt(0)
	ds_read_b128 v[150:153], v147
	ds_read_b128 v[154:157], v147 offset:1024
	ds_read_b128 v[158:161], v147 offset:2048
	ds_read_b128 v[162:165], v147 offset:3072
	s_add_u32 s34, s30, 0xfffc0080
	s_addc_u32 s35, s31, -1
	s_cmp_eq_u32 s65, 12
	s_cselect_b32 s37, s23, s35
	s_cselect_b32 s36, s61, s34
	s_cselect_b32 s35, s21, s64
	s_cselect_b32 s34, s62, s63
	s_add_i32 m0, s29, 0xc000
	ds_read_b128 v[166:169], v148
	ds_read_b128 v[170:173], v148 offset:1024
	ds_read_b128 v[174:177], v148 offset:2048
	ds_read_b128 v[178:181], v148 offset:3072
	ds_read_b128 v[182:185], v148 offset:4096
	ds_read_b128 v[186:189], v148 offset:5120
	ds_read_b128 v[190:193], v148 offset:6144
	ds_read_b128 v[194:197], v148 offset:7168
	global_load_lds_dwordx4 v136, s[30:31]
	s_add_i32 m0, s29, 0xe000
	s_nop 0
	global_load_lds_dwordx4 v138, s[30:31]
	s_waitcnt lgkmcnt(8)
	s_waitcnt vmcnt(10)
	s_barrier
	s_waitcnt lgkmcnt(0)
	s_setprio 1
	s_waitcnt lgkmcnt(0)
	v_mfma_f32_16x16x32_bf16 v[124:127], v[150:153], v[166:169], 0
	v_mfma_f32_16x16x32_bf16 v[120:123], v[158:161], v[166:169], 0
	v_mfma_f32_16x16x32_bf16 v[116:119], v[150:153], v[174:177], 0
	v_mfma_f32_16x16x32_bf16 v[108:111], v[158:161], v[174:177], 0
	v_mfma_f32_16x16x32_bf16 v[100:103], v[150:153], v[182:185], 0
	v_mfma_f32_16x16x32_bf16 v[92:95], v[158:161], v[182:185], 0
	v_mfma_f32_16x16x32_bf16 v[84:87], v[150:153], v[190:193], 0
	v_mfma_f32_16x16x32_bf16 v[76:79], v[158:161], v[190:193], 0
	v_mfma_f32_16x16x32_bf16 v[124:127], v[154:157], v[170:173], v[124:127]
	v_mfma_f32_16x16x32_bf16 v[120:123], v[162:165], v[170:173], v[120:123]
	v_mfma_f32_16x16x32_bf16 v[116:119], v[154:157], v[178:181], v[116:119]
	v_mfma_f32_16x16x32_bf16 v[108:111], v[162:165], v[178:181], v[108:111]
	v_mfma_f32_16x16x32_bf16 v[100:103], v[154:157], v[186:189], v[100:103]
	v_mfma_f32_16x16x32_bf16 v[92:95], v[162:165], v[186:189], v[92:95]
	v_mfma_f32_16x16x32_bf16 v[84:87], v[154:157], v[194:197], v[84:87]
	v_mfma_f32_16x16x32_bf16 v[76:79], v[162:165], v[194:197], v[76:79]
	s_setprio 0
	s_barrier
	s_add_i32 s66, s54, s43
	s_mov_b32 m0, s66
	ds_read_b128 v[202:205], v149
	ds_read_b128 v[206:209], v149 offset:1024
	ds_read_b128 v[210:213], v149 offset:2048
	ds_read_b128 v[214:217], v149 offset:3072
	global_load_lds_dwordx4 v130, s[34:35]
	s_add_i32 m0, s66, 0x2000
	s_nop 0
	global_load_lds_dwordx4 v134, s[34:35]
	s_waitcnt vmcnt(10)
	s_barrier
	s_waitcnt lgkmcnt(0)
	s_setprio 1
	s_waitcnt lgkmcnt(0)
	v_mfma_f32_16x16x32_bf16 v[112:115], v[202:205], v[166:169], 0
	v_mfma_f32_16x16x32_bf16 v[104:107], v[210:213], v[166:169], 0
	v_mfma_f32_16x16x32_bf16 v[96:99], v[202:205], v[174:177], 0
	v_mfma_f32_16x16x32_bf16 v[88:91], v[210:213], v[174:177], 0
	v_mfma_f32_16x16x32_bf16 v[80:83], v[202:205], v[182:185], 0
	v_mfma_f32_16x16x32_bf16 v[72:75], v[210:213], v[182:185], 0
	v_mfma_f32_16x16x32_bf16 v[68:71], v[202:205], v[190:193], 0
	v_mfma_f32_16x16x32_bf16 v[64:67], v[210:213], v[190:193], 0
	v_mfma_f32_16x16x32_bf16 v[112:115], v[206:209], v[170:173], v[112:115]
	v_mfma_f32_16x16x32_bf16 v[104:107], v[214:217], v[170:173], v[104:107]
	v_mfma_f32_16x16x32_bf16 v[96:99], v[206:209], v[178:181], v[96:99]
	v_mfma_f32_16x16x32_bf16 v[88:91], v[214:217], v[178:181], v[88:91]
	v_mfma_f32_16x16x32_bf16 v[80:83], v[206:209], v[186:189], v[80:83]
	v_mfma_f32_16x16x32_bf16 v[72:75], v[214:217], v[186:189], v[72:75]
	v_mfma_f32_16x16x32_bf16 v[68:71], v[206:209], v[194:197], v[68:71]
	v_mfma_f32_16x16x32_bf16 v[64:67], v[214:217], v[194:197], v[64:67]
	s_setprio 0
	s_mov_b32 m0, s29
	v_lshl_add_u64 v[220:221], s[36:37], 0, v[128:129]
	s_barrier
	ds_read_b128 v[166:169], v148 offset:16384
	ds_read_b128 v[170:173], v148 offset:17408
	ds_read_b128 v[174:177], v148 offset:18432
	ds_read_b128 v[178:181], v148 offset:19456
	ds_read_b128 v[182:185], v148 offset:20480
	ds_read_b128 v[186:189], v148 offset:21504
	ds_read_b128 v[190:193], v148 offset:22528
	ds_read_b128 v[194:197], v148 offset:23552
	global_load_lds_dwordx4 v128, s[36:37]
	v_lshl_add_u64 v[222:223], s[36:37], 0, v[132:133]
	s_mov_b32 m0, s44
	s_nop 0
	global_load_lds_dwordx4 v132, s[36:37]
	s_barrier
	s_waitcnt lgkmcnt(0)
	s_setprio 1
	s_waitcnt lgkmcnt(0)
	v_mfma_f32_16x16x32_bf16 v[60:63], v[150:153], v[166:169], 0
	v_mfma_f32_16x16x32_bf16 v[56:59], v[158:161], v[166:169], 0
	v_mfma_f32_16x16x32_bf16 v[52:55], v[150:153], v[174:177], 0
	v_mfma_f32_16x16x32_bf16 v[44:47], v[158:161], v[174:177], 0
	v_mfma_f32_16x16x32_bf16 v[36:39], v[150:153], v[182:185], 0
	v_mfma_f32_16x16x32_bf16 v[28:31], v[158:161], v[182:185], 0
	v_mfma_f32_16x16x32_bf16 v[20:23], v[150:153], v[190:193], 0
	v_mfma_f32_16x16x32_bf16 v[12:15], v[158:161], v[190:193], 0
	v_mfma_f32_16x16x32_bf16 v[60:63], v[154:157], v[170:173], v[60:63]
	v_mfma_f32_16x16x32_bf16 v[56:59], v[162:165], v[170:173], v[56:59]
	v_mfma_f32_16x16x32_bf16 v[52:55], v[154:157], v[178:181], v[52:55]
	v_mfma_f32_16x16x32_bf16 v[44:47], v[162:165], v[178:181], v[44:47]
	v_mfma_f32_16x16x32_bf16 v[36:39], v[154:157], v[186:189], v[36:39]
	v_mfma_f32_16x16x32_bf16 v[28:31], v[162:165], v[186:189], v[28:31]
	v_mfma_f32_16x16x32_bf16 v[20:23], v[154:157], v[194:197], v[20:23]
	v_mfma_f32_16x16x32_bf16 v[12:15], v[162:165], v[194:197], v[12:15]
	s_setprio 0
	s_barrier
; #define PG8_STAGE(bufoff, gbase, voff) do { _Pragma("unroll") for (int _i = 0; _i < 2; ++_i) \
;         __builtin_amdgcn_global_load_lds((const unsigned*)((const char*)(gbase) + (voff)[_i]), (LAS unsigned*)(lds + (bufoff) + ldsw + _i * 8192), 16, 0, 0); } while (0)
; #define PG8_LDA(dst, b, h) do { _Pragma("unroll") for (int m = 0; m < 4; ++m) _Pragma("unroll") for (int k = 0; k < 2; ++k) dst[m][k] = *(const LAS bf16x8*)(lds + PG8_SA(b, h) + aoff + m * 2048 + k * 1024); } while (0)
; #define PG8_LDB(dst, b, h) do { _Pragma("unroll") for (int n = 0; n < 2; ++n) _Pragma("unroll") for (int k = 0; k < 2; ++k) dst[n][k] = *(const LAS bf16x8*)(lds + PG8_SB(b, h) + boff + n * 2048 + k * 1024); } while (0)
; #define PG8_MMA(ai, bj, At, Bt) do { __builtin_amdgcn_s_setprio(1); _Pragma("unroll") for (int m = 0; m < 4; ++m) _Pragma("unroll") for (int n = 0; n < 2; ++n) _Pragma("unroll") for (int k = 0; k < 2; ++k) \
;         acc[ai][bj][m][n] = __builtin_amdgcn_mfma_f32_16x16x32_bf16(Bt[n][k], At[m][k], acc[ai][bj][m][n], 0, 0, 0); __builtin_amdgcn_s_setprio(0); } while (0)
; #define PG8_WAIT_V(n) asm volatile("s_waitcnt vmcnt(" #n ")" ::: "memory")
; #define PG8_WAIT_L(n) asm volatile("s_waitcnt lgkmcnt(" #n ")" ::: "memory")
; #define PG8_BAR __builtin_amdgcn_s_barrier()
; #define PG8_SCHED __builtin_amdgcn_sched_barrier(0)
; template <class Epi, class Sched>
; __device__ __forceinline__ void gemm_phase(LAS unsigned char* lds, const Gemm g, const Sched& S, const Epi& E) {
;     ...
;             PG8_STAGE(PG8_SB(0, 1), b2 + hstep, voffB);
;             PG8_WAIT_V(6); PG8_BAR; PG8_MMA(1, 1, At, B1); PG8_BAR;
;             PG8_LDB(B0, 1, 0); PG8_SCHED; PG8_LDA(At, 1, 0); PG8_STAGE(PG8_SA(0, 1), a2 + hstep, voffA);
;             PG8_WAIT_L(8); PG8_BAR; PG8_WAIT_L(0); PG8_MMA(0, 0, At, B0); PG8_BAR; PG8_SCHED;
;             PG8_LDB(B1, 1, 1); PG8_STAGE(PG8_SB(1, 0), b3, voffB);
;             PG8_BAR; PG8_WAIT_L(0); PG8_MMA(0, 1, At, B1); PG8_BAR;
;             PG8_LDA(At, 1, 1); PG8_STAGE(PG8_SA(1, 0), a3, voffA);
	s_add_u32 s66, s34, 0x40000
	s_addc_u32 s67, s35, 0
	s_add_i32 s68, s55, s43
	s_mov_b32 m0, s68
	s_nop 0
	global_load_lds_dwordx4 v130, s[66:67]
	s_add_i32 m0, s68, 0x2000
	s_nop 0
	global_load_lds_dwordx4 v134, s[66:67]
	s_add_u32 s36, s36, 0x40000
	s_addc_u32 s37, s37, 0
	s_mov_b32 m0, s45
	s_nop 0
	global_load_lds_dwordx4 v128, s[36:37]
	s_mov_b32 m0, s46
	s_nop 0
	global_load_lds_dwordx4 v132, s[36:37]
	s_waitcnt vmcnt(12)
	s_barrier
	s_setprio 1
	v_mfma_f32_16x16x32_bf16 v[48:51], v[202:205], v[166:169], 0
	v_mfma_f32_16x16x32_bf16 v[40:43], v[210:213], v[166:169], 0
	v_mfma_f32_16x16x32_bf16 v[32:35], v[202:205], v[174:177], 0
	v_mfma_f32_16x16x32_bf16 v[24:27], v[210:213], v[174:177], 0
	v_mfma_f32_16x16x32_bf16 v[16:19], v[202:205], v[182:185], 0
	v_mfma_f32_16x16x32_bf16 v[8:11], v[210:213], v[182:185], 0
	v_mfma_f32_16x16x32_bf16 v[4:7], v[202:205], v[190:193], 0
	v_mfma_f32_16x16x32_bf16 v[0:3], v[210:213], v[190:193], 0
	v_mfma_f32_16x16x32_bf16 v[48:51], v[206:209], v[170:173], v[48:51]
	v_mfma_f32_16x16x32_bf16 v[40:43], v[214:217], v[170:173], v[40:43]
	v_mfma_f32_16x16x32_bf16 v[32:35], v[206:209], v[178:181], v[32:35]
	v_mfma_f32_16x16x32_bf16 v[24:27], v[214:217], v[178:181], v[24:27]
	v_mfma_f32_16x16x32_bf16 v[16:19], v[206:209], v[186:189], v[16:19]
	v_mfma_f32_16x16x32_bf16 v[8:11], v[214:217], v[186:189], v[8:11]
	v_mfma_f32_16x16x32_bf16 v[4:7], v[206:209], v[194:197], v[4:7]
	v_mfma_f32_16x16x32_bf16 v[0:3], v[214:217], v[194:197], v[0:3]
	s_setprio 0
	s_add_i32 s66, 0, 0x18000
	v_add_u32_e32 v162, s66, v146
	s_barrier
	ds_read_b128 v[150:153], v162
	ds_read_b128 v[154:157], v162 offset:1024
	ds_read_b128 v[158:161], v162 offset:2048
	ds_read_b128 v[162:165], v162 offset:3072
	ds_read_b128 v[166:169], v148 offset:32768
	ds_read_b128 v[170:173], v148 offset:33792
	ds_read_b128 v[174:177], v148 offset:34816
	ds_read_b128 v[178:181], v148 offset:35840
	ds_read_b128 v[182:185], v148 offset:36864
	ds_read_b128 v[186:189], v148 offset:37888
	ds_read_b128 v[190:193], v148 offset:38912
	ds_read_b128 v[194:197], v148 offset:39936
	s_waitcnt lgkmcnt(8)
	s_waitcnt vmcnt(10)
	s_barrier
	s_waitcnt lgkmcnt(0)
	s_setprio 1
	s_waitcnt lgkmcnt(0)
	v_mfma_f32_16x16x32_bf16 v[124:127], v[150:153], v[166:169], v[124:127]
	v_mfma_f32_16x16x32_bf16 v[120:123], v[158:161], v[166:169], v[120:123]
	v_mfma_f32_16x16x32_bf16 v[116:119], v[150:153], v[174:177], v[116:119]
	v_mfma_f32_16x16x32_bf16 v[108:111], v[158:161], v[174:177], v[108:111]
	v_mfma_f32_16x16x32_bf16 v[100:103], v[150:153], v[182:185], v[100:103]
	v_mfma_f32_16x16x32_bf16 v[92:95], v[158:161], v[182:185], v[92:95]
	v_mfma_f32_16x16x32_bf16 v[84:87], v[150:153], v[190:193], v[84:87]
	v_mfma_f32_16x16x32_bf16 v[76:79], v[158:161], v[190:193], v[76:79]
	v_mfma_f32_16x16x32_bf16 v[124:127], v[154:157], v[170:173], v[124:127]
	v_mfma_f32_16x16x32_bf16 v[120:123], v[162:165], v[170:173], v[120:123]
	v_mfma_f32_16x16x32_bf16 v[116:119], v[154:157], v[178:181], v[116:119]
	v_mfma_f32_16x16x32_bf16 v[108:111], v[162:165], v[178:181], v[108:111]
	v_mfma_f32_16x16x32_bf16 v[100:103], v[154:157], v[186:189], v[100:103]
	v_mfma_f32_16x16x32_bf16 v[92:95], v[162:165], v[186:189], v[92:95]
	v_mfma_f32_16x16x32_bf16 v[84:87], v[154:157], v[194:197], v[84:87]
	v_mfma_f32_16x16x32_bf16 v[76:79], v[162:165], v[194:197], v[76:79]
	s_setprio 0
	s_barrier
	s_add_i32 s36, 0, 0x1c000
	s_add_i32 s37, s66, s43
	v_add_u32_e32 v214, s36, v146
	s_add_u32 s4, s34, 0x80
	s_addc_u32 s5, s35, 0
	s_mov_b32 m0, s37
	ds_read_b128 v[202:205], v214
	ds_read_b128 v[206:209], v214 offset:1024
	ds_read_b128 v[210:213], v214 offset:2048
	ds_read_b128 v[214:217], v214 offset:3072
	global_load_lds_dwordx4 v130, s[4:5]
	s_add_i32 m0, s37, 0x2000
	s_nop 0
	global_load_lds_dwordx4 v134, s[4:5]
	s_waitcnt vmcnt(10)
	s_barrier
	s_waitcnt lgkmcnt(0)
	s_setprio 1
	s_waitcnt lgkmcnt(0)
	v_mfma_f32_16x16x32_bf16 v[112:115], v[202:205], v[166:169], v[112:115]
	v_mfma_f32_16x16x32_bf16 v[104:107], v[210:213], v[166:169], v[104:107]
	v_mfma_f32_16x16x32_bf16 v[96:99], v[202:205], v[174:177], v[96:99]
	v_mfma_f32_16x16x32_bf16 v[88:91], v[210:213], v[174:177], v[88:91]
	v_mfma_f32_16x16x32_bf16 v[80:83], v[202:205], v[182:185], v[80:83]
	v_mfma_f32_16x16x32_bf16 v[72:75], v[210:213], v[182:185], v[72:75]
	v_mfma_f32_16x16x32_bf16 v[68:71], v[202:205], v[190:193], v[68:71]
	v_mfma_f32_16x16x32_bf16 v[64:67], v[210:213], v[190:193], v[64:67]
	v_mfma_f32_16x16x32_bf16 v[112:115], v[206:209], v[170:173], v[112:115]
	v_mfma_f32_16x16x32_bf16 v[104:107], v[214:217], v[170:173], v[104:107]
	v_mfma_f32_16x16x32_bf16 v[96:99], v[206:209], v[178:181], v[96:99]
	v_mfma_f32_16x16x32_bf16 v[88:91], v[214:217], v[178:181], v[88:91]
	v_mfma_f32_16x16x32_bf16 v[80:83], v[206:209], v[186:189], v[80:83]
	v_mfma_f32_16x16x32_bf16 v[72:75], v[214:217], v[186:189], v[72:75]
	v_mfma_f32_16x16x32_bf16 v[68:71], v[206:209], v[194:197], v[68:71]
	v_mfma_f32_16x16x32_bf16 v[64:67], v[214:217], v[194:197], v[64:67]
	s_setprio 0
	s_mov_b32 m0, s51
	s_mov_b64 s[4:5], 0x80
	v_lshl_add_u64 v[198:199], v[220:221], 0, s[4:5]
	s_barrier
	ds_read_b128 v[166:169], v148 offset:49152
	ds_read_b128 v[170:173], v148 offset:50176
	ds_read_b128 v[174:177], v148 offset:51200
	ds_read_b128 v[178:181], v148 offset:52224
	ds_read_b128 v[182:185], v148 offset:53248
	ds_read_b128 v[186:189], v148 offset:54272
	ds_read_b128 v[190:193], v148 offset:55296
	ds_read_b128 v[194:197], v148 offset:56320
	global_load_lds_dwordx4 v[198:199], off
	v_lshl_add_u64 v[198:199], v[222:223], 0, s[4:5]
	s_mov_b32 m0, s52
	s_nop 0
	global_load_lds_dwordx4 v[198:199], off
	s_barrier
; #define PG8_STAGE(bufoff, gbase, voff) do { _Pragma("unroll") for (int _i = 0; _i < 2; ++_i) \
;         __builtin_amdgcn_global_load_lds((const unsigned*)((const char*)(gbase) + (voff)[_i]), (LAS unsigned*)(lds + (bufoff) + ldsw + _i * 8192), 16, 0, 0); } while (0)
; #define PG8_LDA(dst, b, h) do { _Pragma("unroll") for (int m = 0; m < 4; ++m) _Pragma("unroll") for (int k = 0; k < 2; ++k) dst[m][k] = *(const LAS bf16x8*)(lds + PG8_SA(b, h) + aoff + m * 2048 + k * 1024); } while (0)
; #define PG8_WAIT_V(n) asm volatile("s_waitcnt vmcnt(" #n ")" ::: "memory")
; #define PG8_WAIT_L(n) asm volatile("s_waitcnt lgkmcnt(" #n ")" ::: "memory")
; template <class Epi, class Sched>
; __device__ __forceinline__ void gemm_phase(LAS unsigned char* lds, const Gemm g, const Sched& S, const Epi& E) {
;     ...
;         for (int t = 0; t < nt; t += 2) {
;             const bool last = (t == nt - 2);
;             const char* a1 = cA + (size_t)(t + 1) * kstep;
;             const char* a2 = last ? nA : cA + (size_t)(t + 2) * kstep; const char* b2 = last ? nB : cB + (size_t)(t + 2) * kstep;
;             const char* a3 = a2 + kstep; const char* b3 = b2 + kstep;
;             PG8_LDB(B0, 0, 0); PG8_SCHED; PG8_LDA(At, 0, 0); PG8_STAGE(PG8_SA(1, 1), a1 + hstep, voffA);
;             PG8_WAIT_L(8); PG8_BAR; PG8_WAIT_L(0); PG8_MMA(0, 0, At, B0); PG8_BAR; PG8_SCHED;
;             PG8_LDB(B1, 0, 1); PG8_STAGE(PG8_SB(0, 0), b2, voffB);
;             PG8_BAR; PG8_WAIT_L(0); PG8_MMA(0, 1, At, B1); PG8_BAR;
;             PG8_LDA(At, 0, 1); PG8_STAGE(PG8_SA(0, 0), a2, voffA);
;             PG8_BAR; PG8_WAIT_L(0); PG8_MMA(1, 0, At, B0); PG8_BAR; PG8_SCHED;
;             PG8_STAGE(PG8_SB(0, 1), b2 + hstep, voffB);
;             PG8_WAIT_V(6); PG8_BAR; PG8_MMA(1, 1, At, B1); PG8_BAR;
;             PG8_LDB(B0, 1, 0); PG8_SCHED; PG8_LDA(At, 1, 0); PG8_STAGE(PG8_SA(0, 1), a2 + hstep, voffA);
;             PG8_WAIT_L(8); PG8_BAR; PG8_WAIT_L(0); PG8_MMA(0, 0, At, B0); PG8_BAR; PG8_SCHED;
;             PG8_LDB(B1, 1, 1); PG8_STAGE(PG8_SB(1, 0), b3, voffB);
;             PG8_BAR; PG8_WAIT_L(0); PG8_MMA(0, 1, At, B1); PG8_BAR;
;             PG8_LDA(At, 1, 1); PG8_STAGE(PG8_SA(1, 0), a3, voffA);
;             PG8_BAR; PG8_WAIT_L(0); PG8_MMA(1, 0, At, B0); PG8_BAR; PG8_SCHED;
;             PG8_STAGE(PG8_SB(1, 1), b3 + hstep, voffB);
;             PG8_WAIT_V(6); PG8_BAR; PG8_MMA(1, 1, At, B1); PG8_BAR;
	s_waitcnt lgkmcnt(0)
	s_setprio 1
	s_waitcnt lgkmcnt(0)
	v_mfma_f32_16x16x32_bf16 v[60:63], v[150:153], v[166:169], v[60:63]
	v_mfma_f32_16x16x32_bf16 v[56:59], v[158:161], v[166:169], v[56:59]
	v_mfma_f32_16x16x32_bf16 v[52:55], v[150:153], v[174:177], v[52:55]
	v_mfma_f32_16x16x32_bf16 v[44:47], v[158:161], v[174:177], v[44:47]
	v_mfma_f32_16x16x32_bf16 v[36:39], v[150:153], v[182:185], v[36:39]
	v_mfma_f32_16x16x32_bf16 v[28:31], v[158:161], v[182:185], v[28:31]
	v_mfma_f32_16x16x32_bf16 v[20:23], v[150:153], v[190:193], v[20:23]
	v_mfma_f32_16x16x32_bf16 v[12:15], v[158:161], v[190:193], v[12:15]
	v_mfma_f32_16x16x32_bf16 v[60:63], v[154:157], v[170:173], v[60:63]
	v_mfma_f32_16x16x32_bf16 v[56:59], v[162:165], v[170:173], v[56:59]
	v_mfma_f32_16x16x32_bf16 v[52:55], v[154:157], v[178:181], v[52:55]
	v_mfma_f32_16x16x32_bf16 v[44:47], v[162:165], v[178:181], v[44:47]
	v_mfma_f32_16x16x32_bf16 v[36:39], v[154:157], v[186:189], v[36:39]
	v_mfma_f32_16x16x32_bf16 v[28:31], v[162:165], v[186:189], v[28:31]
	v_mfma_f32_16x16x32_bf16 v[20:23], v[154:157], v[194:197], v[20:23]
	v_mfma_f32_16x16x32_bf16 v[12:15], v[162:165], v[194:197], v[12:15]
	s_setprio 0
	s_barrier
	s_add_u32 s34, s34, 0x40080
	s_addc_u32 s35, s35, 0
	s_add_i32 s36, s36, s43
	s_mov_b32 m0, s36
	s_nop 0
	global_load_lds_dwordx4 v130, s[34:35]
	s_add_i32 m0, s36, 0x2000
	s_nop 0
	global_load_lds_dwordx4 v134, s[34:35]
	s_waitcnt vmcnt(10)
	s_barrier
	s_setprio 1
	v_mfma_f32_16x16x32_bf16 v[48:51], v[202:205], v[166:169], v[48:51]
	v_mfma_f32_16x16x32_bf16 v[40:43], v[210:213], v[166:169], v[40:43]
	v_mfma_f32_16x16x32_bf16 v[32:35], v[202:205], v[174:177], v[32:35]
	v_mfma_f32_16x16x32_bf16 v[24:27], v[210:213], v[174:177], v[24:27]
	v_mfma_f32_16x16x32_bf16 v[16:19], v[202:205], v[182:185], v[16:19]
	v_mfma_f32_16x16x32_bf16 v[8:11], v[210:213], v[182:185], v[8:11]
	v_mfma_f32_16x16x32_bf16 v[4:7], v[202:205], v[190:193], v[4:7]
	v_mfma_f32_16x16x32_bf16 v[0:3], v[210:213], v[190:193], v[0:3]
	v_mfma_f32_16x16x32_bf16 v[48:51], v[206:209], v[170:173], v[48:51]
	v_mfma_f32_16x16x32_bf16 v[40:43], v[214:217], v[170:173], v[40:43]
	v_mfma_f32_16x16x32_bf16 v[32:35], v[206:209], v[178:181], v[32:35]
	v_mfma_f32_16x16x32_bf16 v[24:27], v[214:217], v[178:181], v[24:27]
	v_mfma_f32_16x16x32_bf16 v[16:19], v[206:209], v[186:189], v[16:19]
	v_mfma_f32_16x16x32_bf16 v[8:11], v[214:217], v[186:189], v[8:11]
	v_mfma_f32_16x16x32_bf16 v[4:7], v[206:209], v[194:197], v[4:7]
	v_mfma_f32_16x16x32_bf16 v[0:3], v[214:217], v[194:197], v[0:3]
	s_setprio 0
	s_add_i32 s65, s65, 2
	s_add_u32 s30, s30, 0x100
	s_addc_u32 s31, s31, 0
	s_add_u32 s63, s63, 0x100
	s_addc_u32 s64, s64, 0
	s_cmp_gt_u32 s65, 13
	s_barrier
.LBB0_633:
	ds_read_b128 v[150:153], v147
	ds_read_b128 v[154:157], v147 offset:1024
	ds_read_b128 v[158:161], v147 offset:2048
	ds_read_b128 v[162:165], v147 offset:3072
	s_add_u32 s34, s30, 0xfffc0080
	s_addc_u32 s35, s31, -1
	s_cmp_eq_u32 s65, 12
	s_cselect_b32 s37, s23, s35
	s_cselect_b32 s36, s61, s34
	s_cselect_b32 s35, s21, s64
	s_cselect_b32 s34, s62, s63
	s_add_i32 m0, s29, 0xc000
	ds_read_b128 v[166:169], v148
	ds_read_b128 v[170:173], v148 offset:1024
	ds_read_b128 v[174:177], v148 offset:2048
	ds_read_b128 v[178:181], v148 offset:3072
	ds_read_b128 v[182:185], v148 offset:4096
	ds_read_b128 v[186:189], v148 offset:5120
	ds_read_b128 v[190:193], v148 offset:6144
	ds_read_b128 v[194:197], v148 offset:7168
	global_load_lds_dwordx4 v136, s[30:31]
	s_add_i32 m0, s29, 0xe000
	s_nop 0
	global_load_lds_dwordx4 v138, s[30:31]
	s_waitcnt lgkmcnt(8)
	s_waitcnt vmcnt(10)
	s_barrier
	s_waitcnt lgkmcnt(0)
	s_setprio 1
	s_waitcnt lgkmcnt(0)
	v_mfma_f32_16x16x32_bf16 v[124:127], v[150:153], v[166:169], v[124:127]
	v_mfma_f32_16x16x32_bf16 v[120:123], v[158:161], v[166:169], v[120:123]
	v_mfma_f32_16x16x32_bf16 v[116:119], v[150:153], v[174:177], v[116:119]
	v_mfma_f32_16x16x32_bf16 v[108:111], v[158:161], v[174:177], v[108:111]
	v_mfma_f32_16x16x32_bf16 v[100:103], v[150:153], v[182:185], v[100:103]
	v_mfma_f32_16x16x32_bf16 v[92:95], v[158:161], v[182:185], v[92:95]
	v_mfma_f32_16x16x32_bf16 v[84:87], v[150:153], v[190:193], v[84:87]
	v_mfma_f32_16x16x32_bf16 v[76:79], v[158:161], v[190:193], v[76:79]
	v_mfma_f32_16x16x32_bf16 v[124:127], v[154:157], v[170:173], v[124:127]
	v_mfma_f32_16x16x32_bf16 v[120:123], v[162:165], v[170:173], v[120:123]
	v_mfma_f32_16x16x32_bf16 v[116:119], v[154:157], v[178:181], v[116:119]
	v_mfma_f32_16x16x32_bf16 v[108:111], v[162:165], v[178:181], v[108:111]
	v_mfma_f32_16x16x32_bf16 v[100:103], v[154:157], v[186:189], v[100:103]
	v_mfma_f32_16x16x32_bf16 v[92:95], v[162:165], v[186:189], v[92:95]
	v_mfma_f32_16x16x32_bf16 v[84:87], v[154:157], v[194:197], v[84:87]
	v_mfma_f32_16x16x32_bf16 v[76:79], v[162:165], v[194:197], v[76:79]
	s_setprio 0
	s_barrier
	s_add_i32 s66, s54, s43
	s_mov_b32 m0, s66
	ds_read_b128 v[202:205], v149
	ds_read_b128 v[206:209], v149 offset:1024
	ds_read_b128 v[210:213], v149 offset:2048
	ds_read_b128 v[214:217], v149 offset:3072
	global_load_lds_dwordx4 v130, s[34:35]
	s_add_i32 m0, s66, 0x2000
	s_nop 0
	global_load_lds_dwordx4 v134, s[34:35]
	s_waitcnt vmcnt(10)
	s_barrier
; #define PG8_STAGE(bufoff, gbase, voff) do { _Pragma("unroll") for (int _i = 0; _i < 2; ++_i) \
;         __builtin_amdgcn_global_load_lds((const unsigned*)((const char*)(gbase) + (voff)[_i]), (LAS unsigned*)(lds + (bufoff) + ldsw + _i * 8192), 16, 0, 0); } while (0)
; #define PG8_LDA(dst, b, h) do { _Pragma("unroll") for (int m = 0; m < 4; ++m) _Pragma("unroll") for (int k = 0; k < 2; ++k) dst[m][k] = *(const LAS bf16x8*)(lds + PG8_SA(b, h) + aoff + m * 2048 + k * 1024); } while (0)
; #define PG8_LDB(dst, b, h) do { _Pragma("unroll") for (int n = 0; n < 2; ++n) _Pragma("unroll") for (int k = 0; k < 2; ++k) dst[n][k] = *(const LAS bf16x8*)(lds + PG8_SB(b, h) + boff + n * 2048 + k * 1024); } while (0)
; #define PG8_MMA(ai, bj, At, Bt) do { __builtin_amdgcn_s_setprio(1); _Pragma("unroll") for (int m = 0; m < 4; ++m) _Pragma("unroll") for (int n = 0; n < 2; ++n) _Pragma("unroll") for (int k = 0; k < 2; ++k) \
;         acc[ai][bj][m][n] = __builtin_amdgcn_mfma_f32_16x16x32_bf16(Bt[n][k], At[m][k], acc[ai][bj][m][n], 0, 0, 0); __builtin_amdgcn_s_setprio(0); } while (0)
; #define PG8_WAIT_V(n) asm volatile("s_waitcnt vmcnt(" #n ")" ::: "memory")
; #define PG8_WAIT_L(n) asm volatile("s_waitcnt lgkmcnt(" #n ")" ::: "memory")
; #define PG8_BAR __builtin_amdgcn_s_barrier()
; #define PG8_SCHED __builtin_amdgcn_sched_barrier(0)
; template <class Epi, class Sched>
; __device__ __forceinline__ void gemm_phase(LAS unsigned char* lds, const Gemm g, const Sched& S, const Epi& E) {
;     ...
;             PG8_BAR; PG8_WAIT_L(0); PG8_MMA(0, 1, At, B1); PG8_BAR;
;             PG8_LDA(At, 0, 1); PG8_STAGE(PG8_SA(0, 0), a2, voffA);
;             PG8_BAR; PG8_WAIT_L(0); PG8_MMA(1, 0, At, B0); PG8_BAR; PG8_SCHED;
;             PG8_STAGE(PG8_SB(0, 1), b2 + hstep, voffB);
;             PG8_WAIT_V(6); PG8_BAR; PG8_MMA(1, 1, At, B1); PG8_BAR;
;             PG8_LDB(B0, 1, 0); PG8_SCHED; PG8_LDA(At, 1, 0); PG8_STAGE(PG8_SA(0, 1), a2 + hstep, voffA);
;             PG8_WAIT_L(8); PG8_BAR; PG8_WAIT_L(0); PG8_MMA(0, 0, At, B0); PG8_BAR; PG8_SCHED;
	s_waitcnt lgkmcnt(0)
	s_setprio 1
	s_waitcnt lgkmcnt(0)
	v_mfma_f32_16x16x32_bf16 v[112:115], v[202:205], v[166:169], v[112:115]
	v_mfma_f32_16x16x32_bf16 v[104:107], v[210:213], v[166:169], v[104:107]
	v_mfma_f32_16x16x32_bf16 v[96:99], v[202:205], v[174:177], v[96:99]
	v_mfma_f32_16x16x32_bf16 v[88:91], v[210:213], v[174:177], v[88:91]
	v_mfma_f32_16x16x32_bf16 v[80:83], v[202:205], v[182:185], v[80:83]
	v_mfma_f32_16x16x32_bf16 v[72:75], v[210:213], v[182:185], v[72:75]
	v_mfma_f32_16x16x32_bf16 v[68:71], v[202:205], v[190:193], v[68:71]
	v_mfma_f32_16x16x32_bf16 v[64:67], v[210:213], v[190:193], v[64:67]
	v_mfma_f32_16x16x32_bf16 v[112:115], v[206:209], v[170:173], v[112:115]
	v_mfma_f32_16x16x32_bf16 v[104:107], v[214:217], v[170:173], v[104:107]
	v_mfma_f32_16x16x32_bf16 v[96:99], v[206:209], v[178:181], v[96:99]
	v_mfma_f32_16x16x32_bf16 v[88:91], v[214:217], v[178:181], v[88:91]
	v_mfma_f32_16x16x32_bf16 v[80:83], v[206:209], v[186:189], v[80:83]
	v_mfma_f32_16x16x32_bf16 v[72:75], v[214:217], v[186:189], v[72:75]
	v_mfma_f32_16x16x32_bf16 v[68:71], v[206:209], v[194:197], v[68:71]
	v_mfma_f32_16x16x32_bf16 v[64:67], v[214:217], v[194:197], v[64:67]
	s_setprio 0
	s_mov_b32 m0, s29
	v_lshl_add_u64 v[220:221], s[36:37], 0, v[128:129]
	s_barrier
	ds_read_b128 v[166:169], v148 offset:16384
	ds_read_b128 v[170:173], v148 offset:17408
	ds_read_b128 v[174:177], v148 offset:18432
	ds_read_b128 v[178:181], v148 offset:19456
	ds_read_b128 v[182:185], v148 offset:20480
	ds_read_b128 v[186:189], v148 offset:21504
	ds_read_b128 v[190:193], v148 offset:22528
	ds_read_b128 v[194:197], v148 offset:23552
	global_load_lds_dwordx4 v128, s[36:37]
	v_lshl_add_u64 v[222:223], s[36:37], 0, v[132:133]
	s_mov_b32 m0, s44
	s_nop 0
	global_load_lds_dwordx4 v132, s[36:37]
	s_barrier
	s_waitcnt lgkmcnt(0)
	s_setprio 1
	s_waitcnt lgkmcnt(0)
	v_mfma_f32_16x16x32_bf16 v[60:63], v[150:153], v[166:169], v[60:63]
	v_mfma_f32_16x16x32_bf16 v[56:59], v[158:161], v[166:169], v[56:59]
	v_mfma_f32_16x16x32_bf16 v[52:55], v[150:153], v[174:177], v[52:55]
	v_mfma_f32_16x16x32_bf16 v[44:47], v[158:161], v[174:177], v[44:47]
	v_mfma_f32_16x16x32_bf16 v[36:39], v[150:153], v[182:185], v[36:39]
	v_mfma_f32_16x16x32_bf16 v[28:31], v[158:161], v[182:185], v[28:31]
	v_mfma_f32_16x16x32_bf16 v[20:23], v[150:153], v[190:193], v[20:23]
	v_mfma_f32_16x16x32_bf16 v[12:15], v[158:161], v[190:193], v[12:15]
	v_mfma_f32_16x16x32_bf16 v[60:63], v[154:157], v[170:173], v[60:63]
	v_mfma_f32_16x16x32_bf16 v[56:59], v[162:165], v[170:173], v[56:59]
	v_mfma_f32_16x16x32_bf16 v[52:55], v[154:157], v[178:181], v[52:55]
	v_mfma_f32_16x16x32_bf16 v[44:47], v[162:165], v[178:181], v[44:47]
	v_mfma_f32_16x16x32_bf16 v[36:39], v[154:157], v[186:189], v[36:39]
	v_mfma_f32_16x16x32_bf16 v[28:31], v[162:165], v[186:189], v[28:31]
	v_mfma_f32_16x16x32_bf16 v[20:23], v[154:157], v[194:197], v[20:23]
	v_mfma_f32_16x16x32_bf16 v[12:15], v[162:165], v[194:197], v[12:15]
	s_setprio 0
	s_barrier
	s_add_u32 s66, s34, 0x40000
	s_addc_u32 s67, s35, 0
	s_add_i32 s68, s55, s43
	s_mov_b32 m0, s68
	s_nop 0
	global_load_lds_dwordx4 v130, s[66:67]
	s_add_i32 m0, s68, 0x2000
	s_nop 0
	global_load_lds_dwordx4 v134, s[66:67]
	s_add_u32 s36, s36, 0x40000
	s_addc_u32 s37, s37, 0
	s_mov_b32 m0, s45
	s_nop 0
	global_load_lds_dwordx4 v128, s[36:37]
	s_mov_b32 m0, s46
	s_nop 0
	global_load_lds_dwordx4 v132, s[36:37]
	s_waitcnt vmcnt(12)
	s_barrier
	s_setprio 1
	v_mfma_f32_16x16x32_bf16 v[48:51], v[202:205], v[166:169], v[48:51]
	v_mfma_f32_16x16x32_bf16 v[40:43], v[210:213], v[166:169], v[40:43]
	v_mfma_f32_16x16x32_bf16 v[32:35], v[202:205], v[174:177], v[32:35]
	v_mfma_f32_16x16x32_bf16 v[24:27], v[210:213], v[174:177], v[24:27]
	v_mfma_f32_16x16x32_bf16 v[16:19], v[202:205], v[182:185], v[16:19]
	v_mfma_f32_16x16x32_bf16 v[8:11], v[210:213], v[182:185], v[8:11]
	v_mfma_f32_16x16x32_bf16 v[4:7], v[202:205], v[190:193], v[4:7]
	v_mfma_f32_16x16x32_bf16 v[0:3], v[210:213], v[190:193], v[0:3]
	v_mfma_f32_16x16x32_bf16 v[48:51], v[206:209], v[170:173], v[48:51]
	v_mfma_f32_16x16x32_bf16 v[40:43], v[214:217], v[170:173], v[40:43]
	v_mfma_f32_16x16x32_bf16 v[32:35], v[206:209], v[178:181], v[32:35]
	v_mfma_f32_16x16x32_bf16 v[24:27], v[214:217], v[178:181], v[24:27]
	v_mfma_f32_16x16x32_bf16 v[16:19], v[206:209], v[186:189], v[16:19]
	v_mfma_f32_16x16x32_bf16 v[8:11], v[214:217], v[186:189], v[8:11]
	v_mfma_f32_16x16x32_bf16 v[4:7], v[206:209], v[194:197], v[4:7]
	v_mfma_f32_16x16x32_bf16 v[0:3], v[214:217], v[194:197], v[0:3]
	s_setprio 0
	s_add_i32 s66, 0, 0x18000
	v_add_u32_e32 v162, s66, v146
	s_barrier
	ds_read_b128 v[150:153], v162
	ds_read_b128 v[154:157], v162 offset:1024
	ds_read_b128 v[158:161], v162 offset:2048
	ds_read_b128 v[162:165], v162 offset:3072
	ds_read_b128 v[166:169], v148 offset:32768
	ds_read_b128 v[170:173], v148 offset:33792
	ds_read_b128 v[174:177], v148 offset:34816
	ds_read_b128 v[178:181], v148 offset:35840
	ds_read_b128 v[182:185], v148 offset:36864
	ds_read_b128 v[186:189], v148 offset:37888
	ds_read_b128 v[190:193], v148 offset:38912
	ds_read_b128 v[194:197], v148 offset:39936
	s_waitcnt lgkmcnt(8)
	s_waitcnt vmcnt(10)
	s_barrier
; #define PG8_STAGE(bufoff, gbase, voff) do { _Pragma("unroll") for (int _i = 0; _i < 2; ++_i) \
;         __builtin_amdgcn_global_load_lds((const unsigned*)((const char*)(gbase) + (voff)[_i]), (LAS unsigned*)(lds + (bufoff) + ldsw + _i * 8192), 16, 0, 0); } while (0)
; #define PG8_LDA(dst, b, h) do { _Pragma("unroll") for (int m = 0; m < 4; ++m) _Pragma("unroll") for (int k = 0; k < 2; ++k) dst[m][k] = *(const LAS bf16x8*)(lds + PG8_SA(b, h) + aoff + m * 2048 + k * 1024); } while (0)
; #define PG8_LDB(dst, b, h) do { _Pragma("unroll") for (int n = 0; n < 2; ++n) _Pragma("unroll") for (int k = 0; k < 2; ++k) dst[n][k] = *(const LAS bf16x8*)(lds + PG8_SB(b, h) + boff + n * 2048 + k * 1024); } while (0)
; #define PG8_MMA(ai, bj, At, Bt) do { __builtin_amdgcn_s_setprio(1); _Pragma("unroll") for (int m = 0; m < 4; ++m) _Pragma("unroll") for (int n = 0; n < 2; ++n) _Pragma("unroll") for (int k = 0; k < 2; ++k) \
;         acc[ai][bj][m][n] = __builtin_amdgcn_mfma_f32_16x16x32_bf16(Bt[n][k], At[m][k], acc[ai][bj][m][n], 0, 0, 0); __builtin_amdgcn_s_setprio(0); } while (0)
; #define PG8_WAIT_V(n) asm volatile("s_waitcnt vmcnt(" #n ")" ::: "memory")
; #define PG8_WAIT_L(n) asm volatile("s_waitcnt lgkmcnt(" #n ")" ::: "memory")
; #define PG8_BAR __builtin_amdgcn_s_barrier()
; #define PG8_SCHED __builtin_amdgcn_sched_barrier(0)
; template <class Epi, class Sched>
; __device__ __forceinline__ void gemm_phase(LAS unsigned char* lds, const Gemm g, const Sched& S, const Epi& E) {
;     ...
;             PG8_WAIT_L(8); PG8_BAR; PG8_WAIT_L(0); PG8_MMA(0, 0, At, B0); PG8_BAR; PG8_SCHED;
;             PG8_LDB(B1, 1, 1); PG8_STAGE(PG8_SB(1, 0), b3, voffB);
;             PG8_BAR; PG8_WAIT_L(0); PG8_MMA(0, 1, At, B1); PG8_BAR;
;             PG8_LDA(At, 1, 1); PG8_STAGE(PG8_SA(1, 0), a3, voffA);
;             PG8_BAR; PG8_WAIT_L(0); PG8_MMA(1, 0, At, B0); PG8_BAR; PG8_SCHED;
;             PG8_STAGE(PG8_SB(1, 1), b3 + hstep, voffB);
;             PG8_WAIT_V(6); PG8_BAR; PG8_MMA(1, 1, At, B1); PG8_BAR;
	s_waitcnt lgkmcnt(0)
	s_setprio 1
	s_waitcnt lgkmcnt(0)
	v_mfma_f32_16x16x32_bf16 v[124:127], v[150:153], v[166:169], v[124:127]
	v_mfma_f32_16x16x32_bf16 v[120:123], v[158:161], v[166:169], v[120:123]
	v_mfma_f32_16x16x32_bf16 v[116:119], v[150:153], v[174:177], v[116:119]
	v_mfma_f32_16x16x32_bf16 v[108:111], v[158:161], v[174:177], v[108:111]
	v_mfma_f32_16x16x32_bf16 v[100:103], v[150:153], v[182:185], v[100:103]
	v_mfma_f32_16x16x32_bf16 v[92:95], v[158:161], v[182:185], v[92:95]
	v_mfma_f32_16x16x32_bf16 v[84:87], v[150:153], v[190:193], v[84:87]
	v_mfma_f32_16x16x32_bf16 v[76:79], v[158:161], v[190:193], v[76:79]
	v_mfma_f32_16x16x32_bf16 v[124:127], v[154:157], v[170:173], v[124:127]
	v_mfma_f32_16x16x32_bf16 v[120:123], v[162:165], v[170:173], v[120:123]
	v_mfma_f32_16x16x32_bf16 v[116:119], v[154:157], v[178:181], v[116:119]
	v_mfma_f32_16x16x32_bf16 v[108:111], v[162:165], v[178:181], v[108:111]
	v_mfma_f32_16x16x32_bf16 v[100:103], v[154:157], v[186:189], v[100:103]
	v_mfma_f32_16x16x32_bf16 v[92:95], v[162:165], v[186:189], v[92:95]
	v_mfma_f32_16x16x32_bf16 v[84:87], v[154:157], v[194:197], v[84:87]
	v_mfma_f32_16x16x32_bf16 v[76:79], v[162:165], v[194:197], v[76:79]
	s_setprio 0
	s_barrier
	s_add_i32 s36, 0, 0x1c000
	s_add_i32 s37, s66, s43
	v_add_u32_e32 v214, s36, v146
	s_add_u32 s4, s34, 0x80
	s_addc_u32 s5, s35, 0
	s_mov_b32 m0, s37
	ds_read_b128 v[202:205], v214
	ds_read_b128 v[206:209], v214 offset:1024
	ds_read_b128 v[210:213], v214 offset:2048
	ds_read_b128 v[214:217], v214 offset:3072
	global_load_lds_dwordx4 v130, s[4:5]
	s_add_i32 m0, s37, 0x2000
	s_nop 0
	global_load_lds_dwordx4 v134, s[4:5]
	s_waitcnt vmcnt(10)
	s_barrier
	s_waitcnt lgkmcnt(0)
	s_setprio 1
	s_waitcnt lgkmcnt(0)
	v_mfma_f32_16x16x32_bf16 v[112:115], v[202:205], v[166:169], v[112:115]
	v_mfma_f32_16x16x32_bf16 v[104:107], v[210:213], v[166:169], v[104:107]
	v_mfma_f32_16x16x32_bf16 v[96:99], v[202:205], v[174:177], v[96:99]
	v_mfma_f32_16x16x32_bf16 v[88:91], v[210:213], v[174:177], v[88:91]
	v_mfma_f32_16x16x32_bf16 v[80:83], v[202:205], v[182:185], v[80:83]
	v_mfma_f32_16x16x32_bf16 v[72:75], v[210:213], v[182:185], v[72:75]
	v_mfma_f32_16x16x32_bf16 v[68:71], v[202:205], v[190:193], v[68:71]
	v_mfma_f32_16x16x32_bf16 v[64:67], v[210:213], v[190:193], v[64:67]
	v_mfma_f32_16x16x32_bf16 v[112:115], v[206:209], v[170:173], v[112:115]
	v_mfma_f32_16x16x32_bf16 v[104:107], v[214:217], v[170:173], v[104:107]
	v_mfma_f32_16x16x32_bf16 v[96:99], v[206:209], v[178:181], v[96:99]
	v_mfma_f32_16x16x32_bf16 v[88:91], v[214:217], v[178:181], v[88:91]
	v_mfma_f32_16x16x32_bf16 v[80:83], v[206:209], v[186:189], v[80:83]
	v_mfma_f32_16x16x32_bf16 v[72:75], v[214:217], v[186:189], v[72:75]
	v_mfma_f32_16x16x32_bf16 v[68:71], v[206:209], v[194:197], v[68:71]
	v_mfma_f32_16x16x32_bf16 v[64:67], v[214:217], v[194:197], v[64:67]
	s_setprio 0
	s_mov_b32 m0, s51
	s_mov_b64 s[4:5], 0x80
	v_lshl_add_u64 v[198:199], v[220:221], 0, s[4:5]
	s_barrier
	ds_read_b128 v[166:169], v148 offset:49152
	ds_read_b128 v[170:173], v148 offset:50176
	ds_read_b128 v[174:177], v148 offset:51200
	ds_read_b128 v[178:181], v148 offset:52224
	ds_read_b128 v[182:185], v148 offset:53248
	ds_read_b128 v[186:189], v148 offset:54272
	ds_read_b128 v[190:193], v148 offset:55296
	ds_read_b128 v[194:197], v148 offset:56320
	global_load_lds_dwordx4 v[198:199], off
	v_lshl_add_u64 v[198:199], v[222:223], 0, s[4:5]
	s_mov_b32 m0, s52
	s_nop 0
	global_load_lds_dwordx4 v[198:199], off
	s_barrier
	s_waitcnt lgkmcnt(0)
	s_setprio 1
	s_waitcnt lgkmcnt(0)
	v_mfma_f32_16x16x32_bf16 v[60:63], v[150:153], v[166:169], v[60:63]
	v_mfma_f32_16x16x32_bf16 v[56:59], v[158:161], v[166:169], v[56:59]
	v_mfma_f32_16x16x32_bf16 v[52:55], v[150:153], v[174:177], v[52:55]
	v_mfma_f32_16x16x32_bf16 v[44:47], v[158:161], v[174:177], v[44:47]
	v_mfma_f32_16x16x32_bf16 v[36:39], v[150:153], v[182:185], v[36:39]
	v_mfma_f32_16x16x32_bf16 v[28:31], v[158:161], v[182:185], v[28:31]
	v_mfma_f32_16x16x32_bf16 v[20:23], v[150:153], v[190:193], v[20:23]
	v_mfma_f32_16x16x32_bf16 v[12:15], v[158:161], v[190:193], v[12:15]
	v_mfma_f32_16x16x32_bf16 v[60:63], v[154:157], v[170:173], v[60:63]
	v_mfma_f32_16x16x32_bf16 v[56:59], v[162:165], v[170:173], v[56:59]
	v_mfma_f32_16x16x32_bf16 v[52:55], v[154:157], v[178:181], v[52:55]
	v_mfma_f32_16x16x32_bf16 v[44:47], v[162:165], v[178:181], v[44:47]
	v_mfma_f32_16x16x32_bf16 v[36:39], v[154:157], v[186:189], v[36:39]
	v_mfma_f32_16x16x32_bf16 v[28:31], v[162:165], v[186:189], v[28:31]
	v_mfma_f32_16x16x32_bf16 v[20:23], v[154:157], v[194:197], v[20:23]
	v_mfma_f32_16x16x32_bf16 v[12:15], v[162:165], v[194:197], v[12:15]
	s_setprio 0
	s_barrier
	s_add_u32 s34, s34, 0x40080
	s_addc_u32 s35, s35, 0
	s_add_i32 s36, s36, s43
	s_mov_b32 m0, s36
	s_nop 0
	global_load_lds_dwordx4 v130, s[34:35]
	s_add_i32 m0, s36, 0x2000
	s_nop 0
	global_load_lds_dwordx4 v134, s[34:35]
	s_waitcnt vmcnt(10)
	s_barrier
; __device__ __forceinline__ unsigned cvt_pk_bf16(float lo, float hi) { unsigned r; asm volatile("v_cvt_pk_bf16_f32 %0, %1, %2" : "=v"(r) : "v"(lo), "v"(hi)); return r; }
; #define PG8_MMA(ai, bj, At, Bt) do { __builtin_amdgcn_s_setprio(1); _Pragma("unroll") for (int m = 0; m < 4; ++m) _Pragma("unroll") for (int n = 0; n < 2; ++n) _Pragma("unroll") for (int k = 0; k < 2; ++k) \
;         acc[ai][bj][m][n] = __builtin_amdgcn_mfma_f32_16x16x32_bf16(Bt[n][k], At[m][k], acc[ai][bj][m][n], 0, 0, 0); __builtin_amdgcn_s_setprio(0); } while (0)
; #define PG8_WAIT_V(n) asm volatile("s_waitcnt vmcnt(" #n ")" ::: "memory")
; #define PG8_BAR __builtin_amdgcn_s_barrier()
; template <class Epi, class Sched>
; __device__ __forceinline__ void gemm_phase(LAS unsigned char* lds, const Gemm g, const Sched& S, const Epi& E) {
;     ...
;             PG8_WAIT_V(6); PG8_BAR; PG8_MMA(1, 1, At, B1); PG8_BAR;
;         }
;         E(acc, cur, wr, wc, fr, fq);
;         if (!has_next) break;
;     __device__ __forceinline__ void operator()(const AccT& acc, const Unit& u, int wr, int wc, int fr, int fq) const {
;     ...
;         const int rbase = u.pm * 256 + wr * 64 + fr;
;         const int tb = u.pn * 256 + wc * 32 + 8 * fq;
; #pragma unroll
;         for (int ai = 0; ai < 2; ++ai)
; #pragma unroll
;             for (int m = 0; m < 4; ++m) {
;                 const int r = rbase + ai * 128 + m * 16;
; #pragma unroll
;                 for (int bj = 0; bj < 2; ++bj) {
;                     const int t0 = tb + bj * 128;
;                     const f32x4 v0 = acc[ai][bj][m][0], v1 = acc[ai][bj][m][1];
;                     u32x4 w; w.x = cvt_pk_bf16(v0[0], v0[1]); w.y = cvt_pk_bf16(v0[2], v0[3]); w.z = cvt_pk_bf16(v1[0], v1[1]); w.w = cvt_pk_bf16(v1[2], v1[3]);
;                     *(u32x4*)(VT + (size_t)r * NT + t0) = w;
;                 }
;             }
	s_setprio 1
	v_mfma_f32_16x16x32_bf16 v[48:51], v[202:205], v[166:169], v[48:51]
	v_mfma_f32_16x16x32_bf16 v[40:43], v[210:213], v[166:169], v[40:43]
	v_mfma_f32_16x16x32_bf16 v[32:35], v[202:205], v[174:177], v[32:35]
	v_mfma_f32_16x16x32_bf16 v[24:27], v[210:213], v[174:177], v[24:27]
	v_mfma_f32_16x16x32_bf16 v[16:19], v[202:205], v[182:185], v[16:19]
	v_mfma_f32_16x16x32_bf16 v[8:11], v[210:213], v[182:185], v[8:11]
	v_mfma_f32_16x16x32_bf16 v[4:7], v[202:205], v[190:193], v[4:7]
	v_mfma_f32_16x16x32_bf16 v[0:3], v[210:213], v[190:193], v[0:3]
	v_mfma_f32_16x16x32_bf16 v[48:51], v[206:209], v[170:173], v[48:51]
	v_mfma_f32_16x16x32_bf16 v[40:43], v[214:217], v[170:173], v[40:43]
	v_mfma_f32_16x16x32_bf16 v[32:35], v[206:209], v[178:181], v[32:35]
	v_mfma_f32_16x16x32_bf16 v[24:27], v[214:217], v[178:181], v[24:27]
	v_mfma_f32_16x16x32_bf16 v[16:19], v[206:209], v[186:189], v[16:19]
	v_mfma_f32_16x16x32_bf16 v[8:11], v[214:217], v[186:189], v[8:11]
	v_mfma_f32_16x16x32_bf16 v[4:7], v[206:209], v[194:197], v[4:7]
	v_mfma_f32_16x16x32_bf16 v[0:3], v[214:217], v[194:197], v[0:3]
	s_setprio 0
	s_add_i32 s65, s65, 2
	s_add_u32 s30, s30, 0x100
	s_addc_u32 s31, s31, 0
	s_add_u32 s63, s63, 0x100
	s_addc_u32 s64, s64, 0
	s_cmp_gt_u32 s65, 13
	s_barrier
	s_cbranch_scc0 .LBB0_633
	v_mov_b32_e32 v150, v144
	v_mov_b32_e32 v151, v145
	s_lshl_b32 s21, s28, 8
	s_add_i32 s21, s21, s48
	v_add_u32_e32 v150, s21, v150
	s_lshl_b32 s21, s60, 8
	s_or_b32 s21, s21, s49
	v_lshl_add_u32 v152, v151, 3, s21
	v_ashrrev_i32_e32 v151, 31, v150
	v_cvt_pk_bf16_f32 v124, v124, v125
	v_cvt_pk_bf16_f32 v125, v126, v127
	v_cvt_pk_bf16_f32 v126, v120, v121
	v_lshlrev_b64 v[120:121], 17, v[150:151]
	v_lshl_add_u64 v[120:121], s[0:1], 0, v[120:121]
	v_ashrrev_i32_e32 v153, 31, v152
	v_lshl_add_u64 v[120:121], v[152:153], 1, v[120:121]
	s_mov_b32 s21, 0x200000
	v_cvt_pk_bf16_f32 v127, v122, v123
	global_store_dwordx4 v[120:121], v[124:127], off
	v_cvt_pk_bf16_f32 v112, v112, v113
	v_cvt_pk_bf16_f32 v113, v114, v115
	v_cvt_pk_bf16_f32 v114, v104, v105
	v_cvt_pk_bf16_f32 v115, v106, v107
	global_store_dwordx4 v[120:121], v[112:115], off offset:256
	v_cvt_pk_bf16_f32 v104, v116, v117
	v_cvt_pk_bf16_f32 v105, v118, v119
	v_cvt_pk_bf16_f32 v106, v108, v109
	v_cvt_pk_bf16_f32 v107, v110, v111
	s_mov_b64 s[30:31], 0x200000
	v_add_co_u32_e32 v110, vcc, s21, v120
	v_lshl_add_u64 v[108:109], v[120:121], 0, s[30:31]
	s_nop 0
	v_addc_co_u32_e32 v111, vcc, 0, v121, vcc
	s_mov_b32 s21, 0x400000
	global_store_dwordx4 v[110:111], v[104:107], off
	v_cvt_pk_bf16_f32 v96, v96, v97
	v_cvt_pk_bf16_f32 v97, v98, v99
	v_cvt_pk_bf16_f32 v98, v88, v89
	v_cvt_pk_bf16_f32 v99, v90, v91
	global_store_dwordx4 v[108:109], v[96:99], off offset:256
	v_cvt_pk_bf16_f32 v88, v100, v101
	v_cvt_pk_bf16_f32 v89, v102, v103
	v_cvt_pk_bf16_f32 v90, v92, v93
	v_cvt_pk_bf16_f32 v91, v94, v95
	s_mov_b64 s[30:31], 0x400000
	v_add_co_u32_e32 v94, vcc, s21, v120
	v_lshl_add_u64 v[92:93], v[120:121], 0, s[30:31]
	s_nop 0
	v_addc_co_u32_e32 v95, vcc, 0, v121, vcc
	s_mov_b32 s21, 0x600000
	global_store_dwordx4 v[94:95], v[88:91], off
	v_cvt_pk_bf16_f32 v80, v80, v81
	v_cvt_pk_bf16_f32 v81, v82, v83
	v_cvt_pk_bf16_f32 v82, v72, v73
	v_cvt_pk_bf16_f32 v83, v74, v75
	global_store_dwordx4 v[92:93], v[80:83], off offset:256
	v_cvt_pk_bf16_f32 v72, v84, v85
	v_cvt_pk_bf16_f32 v73, v86, v87
	v_cvt_pk_bf16_f32 v74, v76, v77
	v_cvt_pk_bf16_f32 v75, v78, v79
	s_mov_b64 s[30:31], 0x600000
	v_add_co_u32_e32 v78, vcc, s21, v120
	v_lshl_add_u64 v[76:77], v[120:121], 0, s[30:31]
	s_nop 0
	v_addc_co_u32_e32 v79, vcc, 0, v121, vcc
	global_store_dwordx4 v[78:79], v[72:75], off
	v_cvt_pk_bf16_f32 v68, v68, v69
	v_cvt_pk_bf16_f32 v69, v70, v71
	v_cvt_pk_bf16_f32 v70, v64, v65
	v_cvt_pk_bf16_f32 v71, v66, v67
	global_store_dwordx4 v[76:77], v[68:71], off offset:256
	v_cvt_pk_bf16_f32 v60, v60, v61
	v_cvt_pk_bf16_f32 v61, v62, v63
	v_cvt_pk_bf16_f32 v62, v56, v57
	v_cvt_pk_bf16_f32 v63, v58, v59
	s_mov_b64 s[30:31], 0x1000000
	v_add_co_u32_e32 v58, vcc, s56, v120
	v_lshl_add_u64 v[56:57], v[120:121], 0, s[30:31]
	s_nop 0
	v_addc_co_u32_e32 v59, vcc, 0, v121, vcc
	global_store_dwordx4 v[58:59], v[60:63], off
	v_cvt_pk_bf16_f32 v48, v48, v49
	v_cvt_pk_bf16_f32 v49, v50, v51
	v_cvt_pk_bf16_f32 v50, v40, v41
	v_cvt_pk_bf16_f32 v51, v42, v43
	global_store_dwordx4 v[56:57], v[48:51], off offset:256
	v_cvt_pk_bf16_f32 v40, v52, v53
	v_cvt_pk_bf16_f32 v41, v54, v55
	v_cvt_pk_bf16_f32 v42, v44, v45
	v_cvt_pk_bf16_f32 v43, v46, v47
	v_add_co_u32_e32 v46, vcc, s57, v120
	v_lshl_add_u64 v[44:45], v[120:121], 0, s[6:7]
	s_nop 0
	v_addc_co_u32_e32 v47, vcc, 0, v121, vcc
	global_store_dwordx4 v[46:47], v[40:43], off
	v_cvt_pk_bf16_f32 v32, v32, v33
	v_cvt_pk_bf16_f32 v33, v34, v35
	v_cvt_pk_bf16_f32 v34, v24, v25
	v_cvt_pk_bf16_f32 v35, v26, v27
	global_store_dwordx4 v[44:45], v[32:35], off offset:256
	v_cvt_pk_bf16_f32 v24, v36, v37
	v_cvt_pk_bf16_f32 v25, v38, v39
	v_cvt_pk_bf16_f32 v26, v28, v29
	v_cvt_pk_bf16_f32 v27, v30, v31
	v_add_co_u32_e32 v30, vcc, s58, v120
	v_lshl_add_u64 v[28:29], v[120:121], 0, s[8:9]
	s_nop 0
	v_addc_co_u32_e32 v31, vcc, 0, v121, vcc
	global_store_dwordx4 v[30:31], v[24:27], off
	v_cvt_pk_bf16_f32 v16, v16, v17
	v_cvt_pk_bf16_f32 v17, v18, v19
	v_cvt_pk_bf16_f32 v18, v8, v9
	v_cvt_pk_bf16_f32 v19, v10, v11
	global_store_dwordx4 v[28:29], v[16:19], off offset:256
	v_cvt_pk_bf16_f32 v8, v20, v21
	v_cvt_pk_bf16_f32 v9, v22, v23
	v_cvt_pk_bf16_f32 v10, v12, v13
	v_cvt_pk_bf16_f32 v11, v14, v15
	v_add_co_u32_e32 v14, vcc, s59, v120
	v_lshl_add_u64 v[12:13], v[120:121], 0, s[16:17]
	s_nop 0
	v_addc_co_u32_e32 v15, vcc, 0, v121, vcc
	s_and_b64 vcc, exec, s[2:3]
	s_mov_b32 s60, s20
	s_mov_b32 s28, s22
	s_mov_b64 s[34:35], s[26:27]
	s_mov_b64 s[30:31], s[24:25]
	global_store_dwordx4 v[14:15], v[8:11], off
	v_cvt_pk_bf16_f32 v4, v4, v5
	v_cvt_pk_bf16_f32 v5, v6, v7
	v_cvt_pk_bf16_f32 v6, v0, v1
	v_cvt_pk_bf16_f32 v7, v2, v3
	global_store_dwordx4 v[12:13], v[4:7], off offset:256
	s_cbranch_vccz .LBB0_626
	s_waitcnt vmcnt(0)
	s_cmpk_gt_u32 s33, 0xff
	s_cbranch_scc1 .LBB0_637
	s_barrier

; #define PG8_STAGE(bufoff, gbase, voff) do { _Pragma("unroll") for (int _i = 0; _i < 2; ++_i) \
;         __builtin_amdgcn_global_load_lds((const unsigned*)((const char*)(gbase) + (voff)[_i]), (LAS unsigned*)(lds + (bufoff) + ldsw + _i * 8192), 16, 0, 0); } while (0)
; #define PG8_LDA(dst, b, h) do { _Pragma("unroll") for (int m = 0; m < 4; ++m) _Pragma("unroll") for (int k = 0; k < 2; ++k) dst[m][k] = *(const LAS bf16x8*)(lds + PG8_SA(b, h) + aoff + m * 2048 + k * 1024); } while (0)
; #define PG8_LDB(dst, b, h) do { _Pragma("unroll") for (int n = 0; n < 2; ++n) _Pragma("unroll") for (int k = 0; k < 2; ++k) dst[n][k] = *(const LAS bf16x8*)(lds + PG8_SB(b, h) + boff + n * 2048 + k * 1024); } while (0)
; #define PG8_MMA(ai, bj, At, Bt) do { __builtin_amdgcn_s_setprio(1); _Pragma("unroll") for (int m = 0; m < 4; ++m) _Pragma("unroll") for (int n = 0; n < 2; ++n) _Pragma("unroll") for (int k = 0; k < 2; ++k) \
;         acc[ai][bj][m][n] = __builtin_amdgcn_mfma_f32_16x16x32_bf16(Bt[n][k], At[m][k], acc[ai][bj][m][n], 0, 0, 0); __builtin_amdgcn_s_setprio(0); } while (0)
; #define PG8_WAIT_L(n) asm volatile("s_waitcnt lgkmcnt(" #n ")" ::: "memory")
; template <class Epi, class Sched>
; __device__ __forceinline__ void gemm_phase(LAS unsigned char* lds, const Gemm g, const Sched& S, const Epi& E) {
;     ...
;         const bool has_next = S.next(ui + 1, nxt);
;         const char* nA = has_next ? (const char*)g.A + (size_t)nxt.pm * tstep : cA; const char* nB = has_next ? (const char*)g.Bt + (size_t)nxt.pn * tstep : cB;
;         for (int t = 0; t < nt; t += 2) {
;             const bool last = (t == nt - 2);
;             const char* a1 = cA + (size_t)(t + 1) * kstep;
;             const char* a2 = last ? nA : cA + (size_t)(t + 2) * kstep; const char* b2 = last ? nB : cB + (size_t)(t + 2) * kstep;
;             const char* a3 = a2 + kstep; const char* b3 = b2 + kstep;
;             PG8_LDB(B0, 0, 0); PG8_SCHED; PG8_LDA(At, 0, 0); PG8_STAGE(PG8_SA(1, 1), a1 + hstep, voffA);
;             PG8_WAIT_L(8); PG8_BAR; PG8_WAIT_L(0); PG8_MMA(0, 0, At, B0); PG8_BAR; PG8_SCHED;
;             PG8_LDB(B1, 0, 1); PG8_STAGE(PG8_SB(0, 0), b2, voffB);
;             PG8_BAR; PG8_WAIT_L(0); PG8_MMA(0, 1, At, B1); PG8_BAR;
;             PG8_LDA(At, 0, 1); PG8_STAGE(PG8_SA(0, 0), a2, voffA);
;             PG8_BAR; PG8_WAIT_L(0); PG8_MMA(1, 0, At, B0); PG8_BAR; PG8_SCHED;
.LBB0_652:
	s_ashr_i32 s9, s8, 31
	v_cmp_lt_i64_e32 vcc, s[16:17], v[142:143]
	s_lshl_b64 s[16:17], s[8:9], 19
	s_add_u32 s16, s14, s16
	s_addc_u32 s17, s15, s17
	s_and_b64 s[18:19], vcc, exec
	s_cselect_b32 s9, s17, s23
	s_cselect_b32 s48, s16, s22
	s_ashr_i32 s7, s6, 31
	s_lshl_b64 s[18:19], s[6:7], 19
	s_add_u32 s18, s12, s18
	s_addc_u32 s19, s13, s19
	s_and_b64 s[26:27], vcc, exec
	s_cselect_b32 s7, s19, s25
	s_cselect_b32 s49, s18, s24
	s_add_u32 s22, s22, 0x40080
	s_addc_u32 s23, s23, 0
	s_add_u32 s51, s24, 0x100
	s_addc_u32 s52, s25, 0
	s_mov_b32 s53, -2
	s_waitcnt lgkmcnt(0)
	ds_read_b128 v[152:155], v149
	ds_read_b128 v[156:159], v149 offset:1024
	ds_read_b128 v[160:163], v149 offset:2048
	ds_read_b128 v[164:167], v149 offset:3072
	s_add_u32 s24, s22, 0xfffc0080
	s_addc_u32 s25, s23, -1
	s_cmp_eq_u32 s53, 12
	s_cselect_b32 s27, s9, s25
	s_cselect_b32 s26, s48, s24
	s_cselect_b32 s25, s7, s52
	s_cselect_b32 s24, s49, s51
	s_add_i32 m0, s21, 0xc000
	ds_read_b128 v[168:171], v150
	ds_read_b128 v[172:175], v150 offset:1024
	ds_read_b128 v[176:179], v150 offset:2048
	ds_read_b128 v[180:183], v150 offset:3072
	ds_read_b128 v[184:187], v150 offset:4096
	ds_read_b128 v[188:191], v150 offset:5120
	ds_read_b128 v[192:195], v150 offset:6144
	ds_read_b128 v[196:199], v150 offset:7168
	global_load_lds_dwordx4 v138, s[22:23]
	s_add_i32 m0, s21, 0xe000
	s_nop 0
	global_load_lds_dwordx4 v140, s[22:23]
	s_waitcnt lgkmcnt(8)
	s_waitcnt vmcnt(10)
	s_barrier
	s_waitcnt lgkmcnt(0)
	s_setprio 1
	s_waitcnt lgkmcnt(0)
	v_mfma_f32_16x16x32_bf16 v[124:127], v[152:155], v[168:171], 0
	v_mfma_f32_16x16x32_bf16 v[120:123], v[160:163], v[168:171], 0
	v_mfma_f32_16x16x32_bf16 v[112:115], v[152:155], v[176:179], 0
	v_mfma_f32_16x16x32_bf16 v[104:107], v[160:163], v[176:179], 0
	v_mfma_f32_16x16x32_bf16 v[96:99], v[152:155], v[184:187], 0
	v_mfma_f32_16x16x32_bf16 v[88:91], v[160:163], v[184:187], 0
	v_mfma_f32_16x16x32_bf16 v[80:83], v[152:155], v[192:195], 0
	v_mfma_f32_16x16x32_bf16 v[72:75], v[160:163], v[192:195], 0
	v_mfma_f32_16x16x32_bf16 v[124:127], v[156:159], v[172:175], v[124:127]
	v_mfma_f32_16x16x32_bf16 v[120:123], v[164:167], v[172:175], v[120:123]
	v_mfma_f32_16x16x32_bf16 v[112:115], v[156:159], v[180:183], v[112:115]
	v_mfma_f32_16x16x32_bf16 v[104:107], v[164:167], v[180:183], v[104:107]
	v_mfma_f32_16x16x32_bf16 v[96:99], v[156:159], v[188:191], v[96:99]
	v_mfma_f32_16x16x32_bf16 v[88:91], v[164:167], v[188:191], v[88:91]
	v_mfma_f32_16x16x32_bf16 v[80:83], v[156:159], v[196:199], v[80:83]
	v_mfma_f32_16x16x32_bf16 v[72:75], v[164:167], v[196:199], v[72:75]
	s_setprio 0
	s_barrier
	s_add_i32 s54, s45, s30
	s_mov_b32 m0, s54
	ds_read_b128 v[202:205], v151
	ds_read_b128 v[206:209], v151 offset:1024
	ds_read_b128 v[210:213], v151 offset:2048
	ds_read_b128 v[214:217], v151 offset:3072
	global_load_lds_dwordx4 v130, s[24:25]
	s_add_i32 m0, s54, 0x2000
	s_nop 0
	global_load_lds_dwordx4 v134, s[24:25]
	s_waitcnt vmcnt(10)
	s_barrier
	s_waitcnt lgkmcnt(0)
	s_setprio 1
	s_waitcnt lgkmcnt(0)
	v_mfma_f32_16x16x32_bf16 v[116:119], v[202:205], v[168:171], 0
	v_mfma_f32_16x16x32_bf16 v[108:111], v[210:213], v[168:171], 0
	v_mfma_f32_16x16x32_bf16 v[100:103], v[202:205], v[176:179], 0
	v_mfma_f32_16x16x32_bf16 v[92:95], v[210:213], v[176:179], 0
	v_mfma_f32_16x16x32_bf16 v[84:87], v[202:205], v[184:187], 0
	v_mfma_f32_16x16x32_bf16 v[76:79], v[210:213], v[184:187], 0
	v_mfma_f32_16x16x32_bf16 v[68:71], v[202:205], v[192:195], 0
	v_mfma_f32_16x16x32_bf16 v[64:67], v[210:213], v[192:195], 0
	v_mfma_f32_16x16x32_bf16 v[116:119], v[206:209], v[172:175], v[116:119]
	v_mfma_f32_16x16x32_bf16 v[108:111], v[214:217], v[172:175], v[108:111]
	v_mfma_f32_16x16x32_bf16 v[100:103], v[206:209], v[180:183], v[100:103]
	v_mfma_f32_16x16x32_bf16 v[92:95], v[214:217], v[180:183], v[92:95]
	v_mfma_f32_16x16x32_bf16 v[84:87], v[206:209], v[188:191], v[84:87]
	v_mfma_f32_16x16x32_bf16 v[76:79], v[214:217], v[188:191], v[76:79]
	v_mfma_f32_16x16x32_bf16 v[68:71], v[206:209], v[196:199], v[68:71]
	v_mfma_f32_16x16x32_bf16 v[64:67], v[214:217], v[196:199], v[64:67]
	s_setprio 0
	s_mov_b32 m0, s21
	v_lshl_add_u64 v[222:223], s[26:27], 0, v[128:129]
	s_barrier
	ds_read_b128 v[168:171], v150 offset:16384
	ds_read_b128 v[172:175], v150 offset:17408
	ds_read_b128 v[176:179], v150 offset:18432
	ds_read_b128 v[180:183], v150 offset:19456
	ds_read_b128 v[184:187], v150 offset:20480
	ds_read_b128 v[188:191], v150 offset:21504
	ds_read_b128 v[192:195], v150 offset:22528
	ds_read_b128 v[196:199], v150 offset:23552
	global_load_lds_dwordx4 v128, s[26:27]
	v_lshl_add_u64 v[224:225], s[26:27], 0, v[132:133]
	s_mov_b32 m0, s31
	s_nop 0
	global_load_lds_dwordx4 v132, s[26:27]
	s_barrier
	s_waitcnt lgkmcnt(0)
	s_setprio 1
	s_waitcnt lgkmcnt(0)
	v_mfma_f32_16x16x32_bf16 v[60:63], v[152:155], v[168:171], 0
	v_mfma_f32_16x16x32_bf16 v[56:59], v[160:163], v[168:171], 0
	v_mfma_f32_16x16x32_bf16 v[48:51], v[152:155], v[176:179], 0
	v_mfma_f32_16x16x32_bf16 v[40:43], v[160:163], v[176:179], 0
	v_mfma_f32_16x16x32_bf16 v[32:35], v[152:155], v[184:187], 0
	v_mfma_f32_16x16x32_bf16 v[24:27], v[160:163], v[184:187], 0
	v_mfma_f32_16x16x32_bf16 v[16:19], v[152:155], v[192:195], 0
	v_mfma_f32_16x16x32_bf16 v[8:11], v[160:163], v[192:195], 0
	v_mfma_f32_16x16x32_bf16 v[60:63], v[156:159], v[172:175], v[60:63]
	v_mfma_f32_16x16x32_bf16 v[56:59], v[164:167], v[172:175], v[56:59]
	v_mfma_f32_16x16x32_bf16 v[48:51], v[156:159], v[180:183], v[48:51]
	v_mfma_f32_16x16x32_bf16 v[40:43], v[164:167], v[180:183], v[40:43]
	v_mfma_f32_16x16x32_bf16 v[32:35], v[156:159], v[188:191], v[32:35]
	v_mfma_f32_16x16x32_bf16 v[24:27], v[164:167], v[188:191], v[24:27]
	v_mfma_f32_16x16x32_bf16 v[16:19], v[156:159], v[196:199], v[16:19]
	v_mfma_f32_16x16x32_bf16 v[8:11], v[164:167], v[196:199], v[8:11]
	s_setprio 0
	s_barrier
; #define PG8_STAGE(bufoff, gbase, voff) do { _Pragma("unroll") for (int _i = 0; _i < 2; ++_i) \
;         __builtin_amdgcn_global_load_lds((const unsigned*)((const char*)(gbase) + (voff)[_i]), (LAS unsigned*)(lds + (bufoff) + ldsw + _i * 8192), 16, 0, 0); } while (0)
; #define PG8_LDA(dst, b, h) do { _Pragma("unroll") for (int m = 0; m < 4; ++m) _Pragma("unroll") for (int k = 0; k < 2; ++k) dst[m][k] = *(const LAS bf16x8*)(lds + PG8_SA(b, h) + aoff + m * 2048 + k * 1024); } while (0)
; #define PG8_LDB(dst, b, h) do { _Pragma("unroll") for (int n = 0; n < 2; ++n) _Pragma("unroll") for (int k = 0; k < 2; ++k) dst[n][k] = *(const LAS bf16x8*)(lds + PG8_SB(b, h) + boff + n * 2048 + k * 1024); } while (0)
; #define PG8_MMA(ai, bj, At, Bt) do { __builtin_amdgcn_s_setprio(1); _Pragma("unroll") for (int m = 0; m < 4; ++m) _Pragma("unroll") for (int n = 0; n < 2; ++n) _Pragma("unroll") for (int k = 0; k < 2; ++k) \
;         acc[ai][bj][m][n] = __builtin_amdgcn_mfma_f32_16x16x32_bf16(Bt[n][k], At[m][k], acc[ai][bj][m][n], 0, 0, 0); __builtin_amdgcn_s_setprio(0); } while (0)
; #define PG8_WAIT_V(n) asm volatile("s_waitcnt vmcnt(" #n ")" ::: "memory")
; #define PG8_WAIT_L(n) asm volatile("s_waitcnt lgkmcnt(" #n ")" ::: "memory")
; #define PG8_BAR __builtin_amdgcn_s_barrier()
; #define PG8_SCHED __builtin_amdgcn_sched_barrier(0)
; template <class Epi, class Sched>
; __device__ __forceinline__ void gemm_phase(LAS unsigned char* lds, const Gemm g, const Sched& S, const Epi& E) {
;     ...
;             PG8_STAGE(PG8_SB(0, 1), b2 + hstep, voffB);
;             PG8_WAIT_V(6); PG8_BAR; PG8_MMA(1, 1, At, B1); PG8_BAR;
;             PG8_LDB(B0, 1, 0); PG8_SCHED; PG8_LDA(At, 1, 0); PG8_STAGE(PG8_SA(0, 1), a2 + hstep, voffA);
;             PG8_WAIT_L(8); PG8_BAR; PG8_WAIT_L(0); PG8_MMA(0, 0, At, B0); PG8_BAR; PG8_SCHED;
;             PG8_LDB(B1, 1, 1); PG8_STAGE(PG8_SB(1, 0), b3, voffB);
;             PG8_BAR; PG8_WAIT_L(0); PG8_MMA(0, 1, At, B1); PG8_BAR;
;             PG8_LDA(At, 1, 1); PG8_STAGE(PG8_SA(1, 0), a3, voffA);
	s_add_u32 s54, s24, 0x40000
	s_addc_u32 s55, s25, 0
	s_add_i32 s56, s46, s30
	s_mov_b32 m0, s56
	s_nop 0
	global_load_lds_dwordx4 v130, s[54:55]
	s_add_i32 m0, s56, 0x2000
	s_nop 0
	global_load_lds_dwordx4 v134, s[54:55]
	s_add_u32 s26, s26, 0x40000
	s_addc_u32 s27, s27, 0
	s_mov_b32 m0, s33
	s_nop 0
	global_load_lds_dwordx4 v128, s[26:27]
	s_mov_b32 m0, s34
	s_nop 0
	global_load_lds_dwordx4 v132, s[26:27]
	s_waitcnt vmcnt(12)
	s_barrier
	s_setprio 1
	v_mfma_f32_16x16x32_bf16 v[52:55], v[202:205], v[168:171], 0
	v_mfma_f32_16x16x32_bf16 v[44:47], v[210:213], v[168:171], 0
	v_mfma_f32_16x16x32_bf16 v[36:39], v[202:205], v[176:179], 0
	v_mfma_f32_16x16x32_bf16 v[28:31], v[210:213], v[176:179], 0
	v_mfma_f32_16x16x32_bf16 v[20:23], v[202:205], v[184:187], 0
	v_mfma_f32_16x16x32_bf16 v[12:15], v[210:213], v[184:187], 0
	v_mfma_f32_16x16x32_bf16 v[4:7], v[202:205], v[192:195], 0
	v_mfma_f32_16x16x32_bf16 v[0:3], v[210:213], v[192:195], 0
	v_mfma_f32_16x16x32_bf16 v[52:55], v[206:209], v[172:175], v[52:55]
	v_mfma_f32_16x16x32_bf16 v[44:47], v[214:217], v[172:175], v[44:47]
	v_mfma_f32_16x16x32_bf16 v[36:39], v[206:209], v[180:183], v[36:39]
	v_mfma_f32_16x16x32_bf16 v[28:31], v[214:217], v[180:183], v[28:31]
	v_mfma_f32_16x16x32_bf16 v[20:23], v[206:209], v[188:191], v[20:23]
	v_mfma_f32_16x16x32_bf16 v[12:15], v[214:217], v[188:191], v[12:15]
	v_mfma_f32_16x16x32_bf16 v[4:7], v[206:209], v[196:199], v[4:7]
	v_mfma_f32_16x16x32_bf16 v[0:3], v[214:217], v[196:199], v[0:3]
	s_setprio 0
	s_add_i32 s54, 0, 0x18000
	v_add_u32_e32 v136, s54, v148
	s_barrier
	ds_read_b128 v[152:155], v136
	ds_read_b128 v[156:159], v136 offset:1024
	ds_read_b128 v[160:163], v136 offset:2048
	ds_read_b128 v[164:167], v136 offset:3072
	ds_read_b128 v[168:171], v150 offset:32768
	ds_read_b128 v[172:175], v150 offset:33792
	ds_read_b128 v[176:179], v150 offset:34816
	ds_read_b128 v[180:183], v150 offset:35840
	ds_read_b128 v[184:187], v150 offset:36864
	ds_read_b128 v[188:191], v150 offset:37888
	ds_read_b128 v[192:195], v150 offset:38912
	ds_read_b128 v[196:199], v150 offset:39936
	s_waitcnt lgkmcnt(8)
	s_waitcnt vmcnt(10)
	s_barrier
	s_waitcnt lgkmcnt(0)
	s_setprio 1
	s_waitcnt lgkmcnt(0)
	v_mfma_f32_16x16x32_bf16 v[124:127], v[152:155], v[168:171], v[124:127]
	v_mfma_f32_16x16x32_bf16 v[120:123], v[160:163], v[168:171], v[120:123]
	v_mfma_f32_16x16x32_bf16 v[112:115], v[152:155], v[176:179], v[112:115]
	v_mfma_f32_16x16x32_bf16 v[104:107], v[160:163], v[176:179], v[104:107]
	v_mfma_f32_16x16x32_bf16 v[96:99], v[152:155], v[184:187], v[96:99]
	v_mfma_f32_16x16x32_bf16 v[88:91], v[160:163], v[184:187], v[88:91]
	v_mfma_f32_16x16x32_bf16 v[80:83], v[152:155], v[192:195], v[80:83]
	v_mfma_f32_16x16x32_bf16 v[72:75], v[160:163], v[192:195], v[72:75]
	v_mfma_f32_16x16x32_bf16 v[124:127], v[156:159], v[172:175], v[124:127]
	v_mfma_f32_16x16x32_bf16 v[120:123], v[164:167], v[172:175], v[120:123]
	v_mfma_f32_16x16x32_bf16 v[112:115], v[156:159], v[180:183], v[112:115]
	v_mfma_f32_16x16x32_bf16 v[104:107], v[164:167], v[180:183], v[104:107]
	v_mfma_f32_16x16x32_bf16 v[96:99], v[156:159], v[188:191], v[96:99]
	v_mfma_f32_16x16x32_bf16 v[88:91], v[164:167], v[188:191], v[88:91]
	v_mfma_f32_16x16x32_bf16 v[80:83], v[156:159], v[196:199], v[80:83]
	v_mfma_f32_16x16x32_bf16 v[72:75], v[164:167], v[196:199], v[72:75]
	s_setprio 0
	s_barrier
	s_add_i32 s26, 0, 0x1c000
	s_add_i32 s27, s54, s30
	v_add_u32_e32 v136, s26, v148
	s_add_u32 s0, s24, 0x80
	s_addc_u32 s1, s25, 0
	s_mov_b32 m0, s27
	ds_read_b128 v[202:205], v136
	ds_read_b128 v[206:209], v136 offset:1024
	ds_read_b128 v[210:213], v136 offset:2048
	ds_read_b128 v[214:217], v136 offset:3072
	global_load_lds_dwordx4 v130, s[0:1]
	s_add_i32 m0, s27, 0x2000
	s_nop 0
	global_load_lds_dwordx4 v134, s[0:1]
	s_waitcnt vmcnt(10)
	s_barrier
	s_waitcnt lgkmcnt(0)
	s_setprio 1
	s_waitcnt lgkmcnt(0)
	v_mfma_f32_16x16x32_bf16 v[116:119], v[202:205], v[168:171], v[116:119]
	v_mfma_f32_16x16x32_bf16 v[108:111], v[210:213], v[168:171], v[108:111]
	v_mfma_f32_16x16x32_bf16 v[100:103], v[202:205], v[176:179], v[100:103]
	v_mfma_f32_16x16x32_bf16 v[92:95], v[210:213], v[176:179], v[92:95]
	v_mfma_f32_16x16x32_bf16 v[84:87], v[202:205], v[184:187], v[84:87]
	v_mfma_f32_16x16x32_bf16 v[76:79], v[210:213], v[184:187], v[76:79]
	v_mfma_f32_16x16x32_bf16 v[68:71], v[202:205], v[192:195], v[68:71]
	v_mfma_f32_16x16x32_bf16 v[64:67], v[210:213], v[192:195], v[64:67]
	v_mfma_f32_16x16x32_bf16 v[116:119], v[206:209], v[172:175], v[116:119]
	v_mfma_f32_16x16x32_bf16 v[108:111], v[214:217], v[172:175], v[108:111]
	v_mfma_f32_16x16x32_bf16 v[100:103], v[206:209], v[180:183], v[100:103]
	v_mfma_f32_16x16x32_bf16 v[92:95], v[214:217], v[180:183], v[92:95]
	v_mfma_f32_16x16x32_bf16 v[84:87], v[206:209], v[188:191], v[84:87]
	v_mfma_f32_16x16x32_bf16 v[76:79], v[214:217], v[188:191], v[76:79]
	v_mfma_f32_16x16x32_bf16 v[68:71], v[206:209], v[196:199], v[68:71]
	v_mfma_f32_16x16x32_bf16 v[64:67], v[214:217], v[196:199], v[64:67]
	s_setprio 0
	s_mov_b32 m0, s42
	s_mov_b64 s[0:1], 0x80
	v_lshl_add_u64 v[218:219], v[222:223], 0, s[0:1]
	s_barrier
	ds_read_b128 v[168:171], v150 offset:49152
	ds_read_b128 v[172:175], v150 offset:50176
	ds_read_b128 v[176:179], v150 offset:51200
	ds_read_b128 v[180:183], v150 offset:52224
	ds_read_b128 v[184:187], v150 offset:53248
	ds_read_b128 v[188:191], v150 offset:54272
	ds_read_b128 v[192:195], v150 offset:55296
	ds_read_b128 v[196:199], v150 offset:56320
	global_load_lds_dwordx4 v[218:219], off
	v_lshl_add_u64 v[218:219], v[224:225], 0, s[0:1]
	s_mov_b32 m0, s43
	s_nop 0
	global_load_lds_dwordx4 v[218:219], off
	s_barrier
; #define PG8_STAGE(bufoff, gbase, voff) do { _Pragma("unroll") for (int _i = 0; _i < 2; ++_i) \
;         __builtin_amdgcn_global_load_lds((const unsigned*)((const char*)(gbase) + (voff)[_i]), (LAS unsigned*)(lds + (bufoff) + ldsw + _i * 8192), 16, 0, 0); } while (0)
; #define PG8_LDA(dst, b, h) do { _Pragma("unroll") for (int m = 0; m < 4; ++m) _Pragma("unroll") for (int k = 0; k < 2; ++k) dst[m][k] = *(const LAS bf16x8*)(lds + PG8_SA(b, h) + aoff + m * 2048 + k * 1024); } while (0)
; #define PG8_WAIT_V(n) asm volatile("s_waitcnt vmcnt(" #n ")" ::: "memory")
; #define PG8_WAIT_L(n) asm volatile("s_waitcnt lgkmcnt(" #n ")" ::: "memory")
; template <class Epi, class Sched>
; __device__ __forceinline__ void gemm_phase(LAS unsigned char* lds, const Gemm g, const Sched& S, const Epi& E) {
;     ...
;         for (int t = 0; t < nt; t += 2) {
;             const bool last = (t == nt - 2);
;             const char* a1 = cA + (size_t)(t + 1) * kstep;
;             const char* a2 = last ? nA : cA + (size_t)(t + 2) * kstep; const char* b2 = last ? nB : cB + (size_t)(t + 2) * kstep;
;             const char* a3 = a2 + kstep; const char* b3 = b2 + kstep;
;             PG8_LDB(B0, 0, 0); PG8_SCHED; PG8_LDA(At, 0, 0); PG8_STAGE(PG8_SA(1, 1), a1 + hstep, voffA);
;             PG8_WAIT_L(8); PG8_BAR; PG8_WAIT_L(0); PG8_MMA(0, 0, At, B0); PG8_BAR; PG8_SCHED;
;             PG8_LDB(B1, 0, 1); PG8_STAGE(PG8_SB(0, 0), b2, voffB);
;             PG8_BAR; PG8_WAIT_L(0); PG8_MMA(0, 1, At, B1); PG8_BAR;
;             PG8_LDA(At, 0, 1); PG8_STAGE(PG8_SA(0, 0), a2, voffA);
;             PG8_BAR; PG8_WAIT_L(0); PG8_MMA(1, 0, At, B0); PG8_BAR; PG8_SCHED;
;             PG8_STAGE(PG8_SB(0, 1), b2 + hstep, voffB);
;             PG8_WAIT_V(6); PG8_BAR; PG8_MMA(1, 1, At, B1); PG8_BAR;
;             PG8_LDB(B0, 1, 0); PG8_SCHED; PG8_LDA(At, 1, 0); PG8_STAGE(PG8_SA(0, 1), a2 + hstep, voffA);
;             PG8_WAIT_L(8); PG8_BAR; PG8_WAIT_L(0); PG8_MMA(0, 0, At, B0); PG8_BAR; PG8_SCHED;
;             PG8_LDB(B1, 1, 1); PG8_STAGE(PG8_SB(1, 0), b3, voffB);
;             PG8_BAR; PG8_WAIT_L(0); PG8_MMA(0, 1, At, B1); PG8_BAR;
;             PG8_LDA(At, 1, 1); PG8_STAGE(PG8_SA(1, 0), a3, voffA);
;             PG8_BAR; PG8_WAIT_L(0); PG8_MMA(1, 0, At, B0); PG8_BAR; PG8_SCHED;
;             PG8_STAGE(PG8_SB(1, 1), b3 + hstep, voffB);
;             PG8_WAIT_V(6); PG8_BAR; PG8_MMA(1, 1, At, B1); PG8_BAR;
	s_waitcnt lgkmcnt(0)
	s_setprio 1
	s_waitcnt lgkmcnt(0)
	v_mfma_f32_16x16x32_bf16 v[60:63], v[152:155], v[168:171], v[60:63]
	v_mfma_f32_16x16x32_bf16 v[56:59], v[160:163], v[168:171], v[56:59]
	v_mfma_f32_16x16x32_bf16 v[48:51], v[152:155], v[176:179], v[48:51]
	v_mfma_f32_16x16x32_bf16 v[40:43], v[160:163], v[176:179], v[40:43]
	v_mfma_f32_16x16x32_bf16 v[32:35], v[152:155], v[184:187], v[32:35]
	v_mfma_f32_16x16x32_bf16 v[24:27], v[160:163], v[184:187], v[24:27]
	v_mfma_f32_16x16x32_bf16 v[16:19], v[152:155], v[192:195], v[16:19]
	v_mfma_f32_16x16x32_bf16 v[8:11], v[160:163], v[192:195], v[8:11]
	v_mfma_f32_16x16x32_bf16 v[60:63], v[156:159], v[172:175], v[60:63]
	v_mfma_f32_16x16x32_bf16 v[56:59], v[164:167], v[172:175], v[56:59]
	v_mfma_f32_16x16x32_bf16 v[48:51], v[156:159], v[180:183], v[48:51]
	v_mfma_f32_16x16x32_bf16 v[40:43], v[164:167], v[180:183], v[40:43]
	v_mfma_f32_16x16x32_bf16 v[32:35], v[156:159], v[188:191], v[32:35]
	v_mfma_f32_16x16x32_bf16 v[24:27], v[164:167], v[188:191], v[24:27]
	v_mfma_f32_16x16x32_bf16 v[16:19], v[156:159], v[196:199], v[16:19]
	v_mfma_f32_16x16x32_bf16 v[8:11], v[164:167], v[196:199], v[8:11]
	s_setprio 0
	s_barrier
	s_add_u32 s24, s24, 0x40080
	s_addc_u32 s25, s25, 0
	s_add_i32 s26, s26, s30
	s_mov_b32 m0, s26
	s_nop 0
	global_load_lds_dwordx4 v130, s[24:25]
	s_add_i32 m0, s26, 0x2000
	s_nop 0
	global_load_lds_dwordx4 v134, s[24:25]
	s_waitcnt vmcnt(10)
	s_barrier
	s_setprio 1
	v_mfma_f32_16x16x32_bf16 v[52:55], v[202:205], v[168:171], v[52:55]
	v_mfma_f32_16x16x32_bf16 v[44:47], v[210:213], v[168:171], v[44:47]
	v_mfma_f32_16x16x32_bf16 v[36:39], v[202:205], v[176:179], v[36:39]
	v_mfma_f32_16x16x32_bf16 v[28:31], v[210:213], v[176:179], v[28:31]
	v_mfma_f32_16x16x32_bf16 v[20:23], v[202:205], v[184:187], v[20:23]
	v_mfma_f32_16x16x32_bf16 v[12:15], v[210:213], v[184:187], v[12:15]
	v_mfma_f32_16x16x32_bf16 v[4:7], v[202:205], v[192:195], v[4:7]
	v_mfma_f32_16x16x32_bf16 v[0:3], v[210:213], v[192:195], v[0:3]
	v_mfma_f32_16x16x32_bf16 v[52:55], v[206:209], v[172:175], v[52:55]
	v_mfma_f32_16x16x32_bf16 v[44:47], v[214:217], v[172:175], v[44:47]
	v_mfma_f32_16x16x32_bf16 v[36:39], v[206:209], v[180:183], v[36:39]
	v_mfma_f32_16x16x32_bf16 v[28:31], v[214:217], v[180:183], v[28:31]
	v_mfma_f32_16x16x32_bf16 v[20:23], v[206:209], v[188:191], v[20:23]
	v_mfma_f32_16x16x32_bf16 v[12:15], v[214:217], v[188:191], v[12:15]
	v_mfma_f32_16x16x32_bf16 v[4:7], v[206:209], v[196:199], v[4:7]
	v_mfma_f32_16x16x32_bf16 v[0:3], v[214:217], v[196:199], v[0:3]
	s_setprio 0
	s_add_i32 s53, s53, 2
	s_add_u32 s22, s22, 0x100
	s_addc_u32 s23, s23, 0
	s_add_u32 s51, s51, 0x100
	s_addc_u32 s52, s52, 0
	s_cmp_gt_u32 s53, 13
	s_barrier
.LBB0_653:
	ds_read_b128 v[152:155], v149
	ds_read_b128 v[156:159], v149 offset:1024
	ds_read_b128 v[160:163], v149 offset:2048
	ds_read_b128 v[164:167], v149 offset:3072
	s_add_u32 s24, s22, 0xfffc0080
	s_addc_u32 s25, s23, -1
	s_cmp_eq_u32 s53, 12
	s_cselect_b32 s27, s9, s25
	s_cselect_b32 s26, s48, s24
	s_cselect_b32 s25, s7, s52
	s_cselect_b32 s24, s49, s51
	s_add_i32 m0, s21, 0xc000
	ds_read_b128 v[168:171], v150
	ds_read_b128 v[172:175], v150 offset:1024
	ds_read_b128 v[176:179], v150 offset:2048
	ds_read_b128 v[180:183], v150 offset:3072
	ds_read_b128 v[184:187], v150 offset:4096
	ds_read_b128 v[188:191], v150 offset:5120
	ds_read_b128 v[192:195], v150 offset:6144
	ds_read_b128 v[196:199], v150 offset:7168
	global_load_lds_dwordx4 v138, s[22:23]
	s_add_i32 m0, s21, 0xe000
	s_nop 0
	global_load_lds_dwordx4 v140, s[22:23]
	s_waitcnt lgkmcnt(8)
	s_waitcnt vmcnt(10)
	s_barrier
	s_waitcnt lgkmcnt(0)
	s_setprio 1
	s_waitcnt lgkmcnt(0)
	v_mfma_f32_16x16x32_bf16 v[124:127], v[152:155], v[168:171], v[124:127]
	v_mfma_f32_16x16x32_bf16 v[120:123], v[160:163], v[168:171], v[120:123]
	v_mfma_f32_16x16x32_bf16 v[112:115], v[152:155], v[176:179], v[112:115]
	v_mfma_f32_16x16x32_bf16 v[104:107], v[160:163], v[176:179], v[104:107]
	v_mfma_f32_16x16x32_bf16 v[96:99], v[152:155], v[184:187], v[96:99]
	v_mfma_f32_16x16x32_bf16 v[88:91], v[160:163], v[184:187], v[88:91]
	v_mfma_f32_16x16x32_bf16 v[80:83], v[152:155], v[192:195], v[80:83]
	v_mfma_f32_16x16x32_bf16 v[72:75], v[160:163], v[192:195], v[72:75]
	v_mfma_f32_16x16x32_bf16 v[124:127], v[156:159], v[172:175], v[124:127]
	v_mfma_f32_16x16x32_bf16 v[120:123], v[164:167], v[172:175], v[120:123]
	v_mfma_f32_16x16x32_bf16 v[112:115], v[156:159], v[180:183], v[112:115]
	v_mfma_f32_16x16x32_bf16 v[104:107], v[164:167], v[180:183], v[104:107]
	v_mfma_f32_16x16x32_bf16 v[96:99], v[156:159], v[188:191], v[96:99]
	v_mfma_f32_16x16x32_bf16 v[88:91], v[164:167], v[188:191], v[88:91]
	v_mfma_f32_16x16x32_bf16 v[80:83], v[156:159], v[196:199], v[80:83]
	v_mfma_f32_16x16x32_bf16 v[72:75], v[164:167], v[196:199], v[72:75]
	s_setprio 0
	s_barrier
	s_add_i32 s54, s45, s30
	s_mov_b32 m0, s54
	ds_read_b128 v[202:205], v151
	ds_read_b128 v[206:209], v151 offset:1024
	ds_read_b128 v[210:213], v151 offset:2048
	ds_read_b128 v[214:217], v151 offset:3072
	global_load_lds_dwordx4 v130, s[24:25]
	s_add_i32 m0, s54, 0x2000
	s_nop 0
	global_load_lds_dwordx4 v134, s[24:25]
	s_waitcnt vmcnt(10)
	s_barrier
; #define PG8_STAGE(bufoff, gbase, voff) do { _Pragma("unroll") for (int _i = 0; _i < 2; ++_i) \
;         __builtin_amdgcn_global_load_lds((const unsigned*)((const char*)(gbase) + (voff)[_i]), (LAS unsigned*)(lds + (bufoff) + ldsw + _i * 8192), 16, 0, 0); } while (0)
; #define PG8_LDA(dst, b, h) do { _Pragma("unroll") for (int m = 0; m < 4; ++m) _Pragma("unroll") for (int k = 0; k < 2; ++k) dst[m][k] = *(const LAS bf16x8*)(lds + PG8_SA(b, h) + aoff + m * 2048 + k * 1024); } while (0)
; #define PG8_LDB(dst, b, h) do { _Pragma("unroll") for (int n = 0; n < 2; ++n) _Pragma("unroll") for (int k = 0; k < 2; ++k) dst[n][k] = *(const LAS bf16x8*)(lds + PG8_SB(b, h) + boff + n * 2048 + k * 1024); } while (0)
; #define PG8_MMA(ai, bj, At, Bt) do { __builtin_amdgcn_s_setprio(1); _Pragma("unroll") for (int m = 0; m < 4; ++m) _Pragma("unroll") for (int n = 0; n < 2; ++n) _Pragma("unroll") for (int k = 0; k < 2; ++k) \
;         acc[ai][bj][m][n] = __builtin_amdgcn_mfma_f32_16x16x32_bf16(Bt[n][k], At[m][k], acc[ai][bj][m][n], 0, 0, 0); __builtin_amdgcn_s_setprio(0); } while (0)
; #define PG8_WAIT_V(n) asm volatile("s_waitcnt vmcnt(" #n ")" ::: "memory")
; #define PG8_WAIT_L(n) asm volatile("s_waitcnt lgkmcnt(" #n ")" ::: "memory")
; #define PG8_BAR __builtin_amdgcn_s_barrier()
; #define PG8_SCHED __builtin_amdgcn_sched_barrier(0)
; template <class Epi, class Sched>
; __device__ __forceinline__ void gemm_phase(LAS unsigned char* lds, const Gemm g, const Sched& S, const Epi& E) {
;     ...
;             PG8_BAR; PG8_WAIT_L(0); PG8_MMA(0, 1, At, B1); PG8_BAR;
;             PG8_LDA(At, 0, 1); PG8_STAGE(PG8_SA(0, 0), a2, voffA);
;             PG8_BAR; PG8_WAIT_L(0); PG8_MMA(1, 0, At, B0); PG8_BAR; PG8_SCHED;
;             PG8_STAGE(PG8_SB(0, 1), b2 + hstep, voffB);
;             PG8_WAIT_V(6); PG8_BAR; PG8_MMA(1, 1, At, B1); PG8_BAR;
;             PG8_LDB(B0, 1, 0); PG8_SCHED; PG8_LDA(At, 1, 0); PG8_STAGE(PG8_SA(0, 1), a2 + hstep, voffA);
;             PG8_WAIT_L(8); PG8_BAR; PG8_WAIT_L(0); PG8_MMA(0, 0, At, B0); PG8_BAR; PG8_SCHED;
	s_waitcnt lgkmcnt(0)
	s_setprio 1
	s_waitcnt lgkmcnt(0)
	v_mfma_f32_16x16x32_bf16 v[116:119], v[202:205], v[168:171], v[116:119]
	v_mfma_f32_16x16x32_bf16 v[108:111], v[210:213], v[168:171], v[108:111]
	v_mfma_f32_16x16x32_bf16 v[100:103], v[202:205], v[176:179], v[100:103]
	v_mfma_f32_16x16x32_bf16 v[92:95], v[210:213], v[176:179], v[92:95]
	v_mfma_f32_16x16x32_bf16 v[84:87], v[202:205], v[184:187], v[84:87]
	v_mfma_f32_16x16x32_bf16 v[76:79], v[210:213], v[184:187], v[76:79]
	v_mfma_f32_16x16x32_bf16 v[68:71], v[202:205], v[192:195], v[68:71]
	v_mfma_f32_16x16x32_bf16 v[64:67], v[210:213], v[192:195], v[64:67]
	v_mfma_f32_16x16x32_bf16 v[116:119], v[206:209], v[172:175], v[116:119]
	v_mfma_f32_16x16x32_bf16 v[108:111], v[214:217], v[172:175], v[108:111]
	v_mfma_f32_16x16x32_bf16 v[100:103], v[206:209], v[180:183], v[100:103]
	v_mfma_f32_16x16x32_bf16 v[92:95], v[214:217], v[180:183], v[92:95]
	v_mfma_f32_16x16x32_bf16 v[84:87], v[206:209], v[188:191], v[84:87]
	v_mfma_f32_16x16x32_bf16 v[76:79], v[214:217], v[188:191], v[76:79]
	v_mfma_f32_16x16x32_bf16 v[68:71], v[206:209], v[196:199], v[68:71]
	v_mfma_f32_16x16x32_bf16 v[64:67], v[214:217], v[196:199], v[64:67]
	s_setprio 0
	s_mov_b32 m0, s21
	v_lshl_add_u64 v[222:223], s[26:27], 0, v[128:129]
	s_barrier
	ds_read_b128 v[168:171], v150 offset:16384
	ds_read_b128 v[172:175], v150 offset:17408
	ds_read_b128 v[176:179], v150 offset:18432
	ds_read_b128 v[180:183], v150 offset:19456
	ds_read_b128 v[184:187], v150 offset:20480
	ds_read_b128 v[188:191], v150 offset:21504
	ds_read_b128 v[192:195], v150 offset:22528
	ds_read_b128 v[196:199], v150 offset:23552
	global_load_lds_dwordx4 v128, s[26:27]
	v_lshl_add_u64 v[224:225], s[26:27], 0, v[132:133]
	s_mov_b32 m0, s31
	s_nop 0
	global_load_lds_dwordx4 v132, s[26:27]
	s_barrier
	s_waitcnt lgkmcnt(0)
	s_setprio 1
	s_waitcnt lgkmcnt(0)
	v_mfma_f32_16x16x32_bf16 v[60:63], v[152:155], v[168:171], v[60:63]
	v_mfma_f32_16x16x32_bf16 v[56:59], v[160:163], v[168:171], v[56:59]
	v_mfma_f32_16x16x32_bf16 v[48:51], v[152:155], v[176:179], v[48:51]
	v_mfma_f32_16x16x32_bf16 v[40:43], v[160:163], v[176:179], v[40:43]
	v_mfma_f32_16x16x32_bf16 v[32:35], v[152:155], v[184:187], v[32:35]
	v_mfma_f32_16x16x32_bf16 v[24:27], v[160:163], v[184:187], v[24:27]
	v_mfma_f32_16x16x32_bf16 v[16:19], v[152:155], v[192:195], v[16:19]
	v_mfma_f32_16x16x32_bf16 v[8:11], v[160:163], v[192:195], v[8:11]
	v_mfma_f32_16x16x32_bf16 v[60:63], v[156:159], v[172:175], v[60:63]
	v_mfma_f32_16x16x32_bf16 v[56:59], v[164:167], v[172:175], v[56:59]
	v_mfma_f32_16x16x32_bf16 v[48:51], v[156:159], v[180:183], v[48:51]
	v_mfma_f32_16x16x32_bf16 v[40:43], v[164:167], v[180:183], v[40:43]
	v_mfma_f32_16x16x32_bf16 v[32:35], v[156:159], v[188:191], v[32:35]
	v_mfma_f32_16x16x32_bf16 v[24:27], v[164:167], v[188:191], v[24:27]
	v_mfma_f32_16x16x32_bf16 v[16:19], v[156:159], v[196:199], v[16:19]
	v_mfma_f32_16x16x32_bf16 v[8:11], v[164:167], v[196:199], v[8:11]
	s_setprio 0
	s_barrier
	s_add_u32 s54, s24, 0x40000
	s_addc_u32 s55, s25, 0
	s_add_i32 s56, s46, s30
	s_mov_b32 m0, s56
	s_nop 0
	global_load_lds_dwordx4 v130, s[54:55]
	s_add_i32 m0, s56, 0x2000
	s_nop 0
	global_load_lds_dwordx4 v134, s[54:55]
	s_add_u32 s26, s26, 0x40000
	s_addc_u32 s27, s27, 0
	s_mov_b32 m0, s33
	s_nop 0
	global_load_lds_dwordx4 v128, s[26:27]
	s_mov_b32 m0, s34
	s_nop 0
	global_load_lds_dwordx4 v132, s[26:27]
	s_waitcnt vmcnt(12)
	s_barrier
	s_setprio 1
	v_mfma_f32_16x16x32_bf16 v[52:55], v[202:205], v[168:171], v[52:55]
	v_mfma_f32_16x16x32_bf16 v[44:47], v[210:213], v[168:171], v[44:47]
	v_mfma_f32_16x16x32_bf16 v[36:39], v[202:205], v[176:179], v[36:39]
	v_mfma_f32_16x16x32_bf16 v[28:31], v[210:213], v[176:179], v[28:31]
	v_mfma_f32_16x16x32_bf16 v[20:23], v[202:205], v[184:187], v[20:23]
	v_mfma_f32_16x16x32_bf16 v[12:15], v[210:213], v[184:187], v[12:15]
	v_mfma_f32_16x16x32_bf16 v[4:7], v[202:205], v[192:195], v[4:7]
	v_mfma_f32_16x16x32_bf16 v[0:3], v[210:213], v[192:195], v[0:3]
	v_mfma_f32_16x16x32_bf16 v[52:55], v[206:209], v[172:175], v[52:55]
	v_mfma_f32_16x16x32_bf16 v[44:47], v[214:217], v[172:175], v[44:47]
	v_mfma_f32_16x16x32_bf16 v[36:39], v[206:209], v[180:183], v[36:39]
	v_mfma_f32_16x16x32_bf16 v[28:31], v[214:217], v[180:183], v[28:31]
	v_mfma_f32_16x16x32_bf16 v[20:23], v[206:209], v[188:191], v[20:23]
	v_mfma_f32_16x16x32_bf16 v[12:15], v[214:217], v[188:191], v[12:15]
	v_mfma_f32_16x16x32_bf16 v[4:7], v[206:209], v[196:199], v[4:7]
	v_mfma_f32_16x16x32_bf16 v[0:3], v[214:217], v[196:199], v[0:3]
	s_setprio 0
	s_add_i32 s54, 0, 0x18000
	v_add_u32_e32 v136, s54, v148
	s_barrier
	ds_read_b128 v[152:155], v136
	ds_read_b128 v[156:159], v136 offset:1024
	ds_read_b128 v[160:163], v136 offset:2048
	ds_read_b128 v[164:167], v136 offset:3072
	ds_read_b128 v[168:171], v150 offset:32768
	ds_read_b128 v[172:175], v150 offset:33792
	ds_read_b128 v[176:179], v150 offset:34816
	ds_read_b128 v[180:183], v150 offset:35840
	ds_read_b128 v[184:187], v150 offset:36864
	ds_read_b128 v[188:191], v150 offset:37888
	ds_read_b128 v[192:195], v150 offset:38912
	ds_read_b128 v[196:199], v150 offset:39936
	s_waitcnt lgkmcnt(8)
	s_waitcnt vmcnt(10)
	s_barrier
; #define PG8_STAGE(bufoff, gbase, voff) do { _Pragma("unroll") for (int _i = 0; _i < 2; ++_i) \
;         __builtin_amdgcn_global_load_lds((const unsigned*)((const char*)(gbase) + (voff)[_i]), (LAS unsigned*)(lds + (bufoff) + ldsw + _i * 8192), 16, 0, 0); } while (0)
; #define PG8_LDA(dst, b, h) do { _Pragma("unroll") for (int m = 0; m < 4; ++m) _Pragma("unroll") for (int k = 0; k < 2; ++k) dst[m][k] = *(const LAS bf16x8*)(lds + PG8_SA(b, h) + aoff + m * 2048 + k * 1024); } while (0)
; #define PG8_LDB(dst, b, h) do { _Pragma("unroll") for (int n = 0; n < 2; ++n) _Pragma("unroll") for (int k = 0; k < 2; ++k) dst[n][k] = *(const LAS bf16x8*)(lds + PG8_SB(b, h) + boff + n * 2048 + k * 1024); } while (0)
; #define PG8_MMA(ai, bj, At, Bt) do { __builtin_amdgcn_s_setprio(1); _Pragma("unroll") for (int m = 0; m < 4; ++m) _Pragma("unroll") for (int n = 0; n < 2; ++n) _Pragma("unroll") for (int k = 0; k < 2; ++k) \
;         acc[ai][bj][m][n] = __builtin_amdgcn_mfma_f32_16x16x32_bf16(Bt[n][k], At[m][k], acc[ai][bj][m][n], 0, 0, 0); __builtin_amdgcn_s_setprio(0); } while (0)
; #define PG8_WAIT_V(n) asm volatile("s_waitcnt vmcnt(" #n ")" ::: "memory")
; #define PG8_WAIT_L(n) asm volatile("s_waitcnt lgkmcnt(" #n ")" ::: "memory")
; #define PG8_BAR __builtin_amdgcn_s_barrier()
; #define PG8_SCHED __builtin_amdgcn_sched_barrier(0)
; template <class Epi, class Sched>
; __device__ __forceinline__ void gemm_phase(LAS unsigned char* lds, const Gemm g, const Sched& S, const Epi& E) {
;     ...
;             PG8_WAIT_L(8); PG8_BAR; PG8_WAIT_L(0); PG8_MMA(0, 0, At, B0); PG8_BAR; PG8_SCHED;
;             PG8_LDB(B1, 1, 1); PG8_STAGE(PG8_SB(1, 0), b3, voffB);
;             PG8_BAR; PG8_WAIT_L(0); PG8_MMA(0, 1, At, B1); PG8_BAR;
;             PG8_LDA(At, 1, 1); PG8_STAGE(PG8_SA(1, 0), a3, voffA);
;             PG8_BAR; PG8_WAIT_L(0); PG8_MMA(1, 0, At, B0); PG8_BAR; PG8_SCHED;
;             PG8_STAGE(PG8_SB(1, 1), b3 + hstep, voffB);
;             PG8_WAIT_V(6); PG8_BAR; PG8_MMA(1, 1, At, B1); PG8_BAR;
	s_waitcnt lgkmcnt(0)
	s_setprio 1
	s_waitcnt lgkmcnt(0)
	v_mfma_f32_16x16x32_bf16 v[124:127], v[152:155], v[168:171], v[124:127]
	v_mfma_f32_16x16x32_bf16 v[120:123], v[160:163], v[168:171], v[120:123]
	v_mfma_f32_16x16x32_bf16 v[112:115], v[152:155], v[176:179], v[112:115]
	v_mfma_f32_16x16x32_bf16 v[104:107], v[160:163], v[176:179], v[104:107]
	v_mfma_f32_16x16x32_bf16 v[96:99], v[152:155], v[184:187], v[96:99]
	v_mfma_f32_16x16x32_bf16 v[88:91], v[160:163], v[184:187], v[88:91]
	v_mfma_f32_16x16x32_bf16 v[80:83], v[152:155], v[192:195], v[80:83]
	v_mfma_f32_16x16x32_bf16 v[72:75], v[160:163], v[192:195], v[72:75]
	v_mfma_f32_16x16x32_bf16 v[124:127], v[156:159], v[172:175], v[124:127]
	v_mfma_f32_16x16x32_bf16 v[120:123], v[164:167], v[172:175], v[120:123]
	v_mfma_f32_16x16x32_bf16 v[112:115], v[156:159], v[180:183], v[112:115]
	v_mfma_f32_16x16x32_bf16 v[104:107], v[164:167], v[180:183], v[104:107]
	v_mfma_f32_16x16x32_bf16 v[96:99], v[156:159], v[188:191], v[96:99]
	v_mfma_f32_16x16x32_bf16 v[88:91], v[164:167], v[188:191], v[88:91]
	v_mfma_f32_16x16x32_bf16 v[80:83], v[156:159], v[196:199], v[80:83]
	v_mfma_f32_16x16x32_bf16 v[72:75], v[164:167], v[196:199], v[72:75]
	s_setprio 0
	s_barrier
	s_add_i32 s26, 0, 0x1c000
	s_add_i32 s27, s54, s30
	v_add_u32_e32 v136, s26, v148
	s_add_u32 s0, s24, 0x80
	s_addc_u32 s1, s25, 0
	s_mov_b32 m0, s27
	ds_read_b128 v[202:205], v136
	ds_read_b128 v[206:209], v136 offset:1024
	ds_read_b128 v[210:213], v136 offset:2048
	ds_read_b128 v[214:217], v136 offset:3072
	global_load_lds_dwordx4 v130, s[0:1]
	s_add_i32 m0, s27, 0x2000
	s_nop 0
	global_load_lds_dwordx4 v134, s[0:1]
	s_waitcnt vmcnt(10)
	s_barrier
	s_waitcnt lgkmcnt(0)
	s_setprio 1
	s_waitcnt lgkmcnt(0)
	v_mfma_f32_16x16x32_bf16 v[116:119], v[202:205], v[168:171], v[116:119]
	v_mfma_f32_16x16x32_bf16 v[108:111], v[210:213], v[168:171], v[108:111]
	v_mfma_f32_16x16x32_bf16 v[100:103], v[202:205], v[176:179], v[100:103]
	v_mfma_f32_16x16x32_bf16 v[92:95], v[210:213], v[176:179], v[92:95]
	v_mfma_f32_16x16x32_bf16 v[84:87], v[202:205], v[184:187], v[84:87]
	v_mfma_f32_16x16x32_bf16 v[76:79], v[210:213], v[184:187], v[76:79]
	v_mfma_f32_16x16x32_bf16 v[68:71], v[202:205], v[192:195], v[68:71]
	v_mfma_f32_16x16x32_bf16 v[64:67], v[210:213], v[192:195], v[64:67]
	v_mfma_f32_16x16x32_bf16 v[116:119], v[206:209], v[172:175], v[116:119]
	v_mfma_f32_16x16x32_bf16 v[108:111], v[214:217], v[172:175], v[108:111]
	v_mfma_f32_16x16x32_bf16 v[100:103], v[206:209], v[180:183], v[100:103]
	v_mfma_f32_16x16x32_bf16 v[92:95], v[214:217], v[180:183], v[92:95]
	v_mfma_f32_16x16x32_bf16 v[84:87], v[206:209], v[188:191], v[84:87]
	v_mfma_f32_16x16x32_bf16 v[76:79], v[214:217], v[188:191], v[76:79]
	v_mfma_f32_16x16x32_bf16 v[68:71], v[206:209], v[196:199], v[68:71]
	v_mfma_f32_16x16x32_bf16 v[64:67], v[214:217], v[196:199], v[64:67]
	s_setprio 0
	s_mov_b32 m0, s42
	s_mov_b64 s[0:1], 0x80
	v_lshl_add_u64 v[218:219], v[222:223], 0, s[0:1]
	s_barrier
	ds_read_b128 v[168:171], v150 offset:49152
	ds_read_b128 v[172:175], v150 offset:50176
	ds_read_b128 v[176:179], v150 offset:51200
	ds_read_b128 v[180:183], v150 offset:52224
	ds_read_b128 v[184:187], v150 offset:53248
	ds_read_b128 v[188:191], v150 offset:54272
	ds_read_b128 v[192:195], v150 offset:55296
	ds_read_b128 v[196:199], v150 offset:56320
	global_load_lds_dwordx4 v[218:219], off
	v_lshl_add_u64 v[218:219], v[224:225], 0, s[0:1]
	s_mov_b32 m0, s43
	s_nop 0
	global_load_lds_dwordx4 v[218:219], off
	s_barrier
	s_waitcnt lgkmcnt(0)
	s_setprio 1
	s_waitcnt lgkmcnt(0)
	v_mfma_f32_16x16x32_bf16 v[60:63], v[152:155], v[168:171], v[60:63]
	v_mfma_f32_16x16x32_bf16 v[56:59], v[160:163], v[168:171], v[56:59]
	v_mfma_f32_16x16x32_bf16 v[48:51], v[152:155], v[176:179], v[48:51]
	v_mfma_f32_16x16x32_bf16 v[40:43], v[160:163], v[176:179], v[40:43]
	v_mfma_f32_16x16x32_bf16 v[32:35], v[152:155], v[184:187], v[32:35]
	v_mfma_f32_16x16x32_bf16 v[24:27], v[160:163], v[184:187], v[24:27]
	v_mfma_f32_16x16x32_bf16 v[16:19], v[152:155], v[192:195], v[16:19]
	v_mfma_f32_16x16x32_bf16 v[8:11], v[160:163], v[192:195], v[8:11]
	v_mfma_f32_16x16x32_bf16 v[60:63], v[156:159], v[172:175], v[60:63]
	v_mfma_f32_16x16x32_bf16 v[56:59], v[164:167], v[172:175], v[56:59]
	v_mfma_f32_16x16x32_bf16 v[48:51], v[156:159], v[180:183], v[48:51]
	v_mfma_f32_16x16x32_bf16 v[40:43], v[164:167], v[180:183], v[40:43]
	v_mfma_f32_16x16x32_bf16 v[32:35], v[156:159], v[188:191], v[32:35]
	v_mfma_f32_16x16x32_bf16 v[24:27], v[164:167], v[188:191], v[24:27]
	v_mfma_f32_16x16x32_bf16 v[16:19], v[156:159], v[196:199], v[16:19]
	v_mfma_f32_16x16x32_bf16 v[8:11], v[164:167], v[196:199], v[8:11]
	s_setprio 0
	s_barrier
	s_add_u32 s24, s24, 0x40080
	s_addc_u32 s25, s25, 0
	s_add_i32 s26, s26, s30
	s_mov_b32 m0, s26
	s_nop 0
	global_load_lds_dwordx4 v130, s[24:25]
	s_add_i32 m0, s26, 0x2000
	s_nop 0
	global_load_lds_dwordx4 v134, s[24:25]
	s_waitcnt vmcnt(10)
	s_barrier
	s_setprio 1
	v_mfma_f32_16x16x32_bf16 v[52:55], v[202:205], v[168:171], v[52:55]
	v_mfma_f32_16x16x32_bf16 v[44:47], v[210:213], v[168:171], v[44:47]
	v_mfma_f32_16x16x32_bf16 v[36:39], v[202:205], v[176:179], v[36:39]
	v_mfma_f32_16x16x32_bf16 v[28:31], v[210:213], v[176:179], v[28:31]
	v_mfma_f32_16x16x32_bf16 v[20:23], v[202:205], v[184:187], v[20:23]
	v_mfma_f32_16x16x32_bf16 v[12:15], v[210:213], v[184:187], v[12:15]
	v_mfma_f32_16x16x32_bf16 v[4:7], v[202:205], v[192:195], v[4:7]
	v_mfma_f32_16x16x32_bf16 v[0:3], v[210:213], v[192:195], v[0:3]
	v_mfma_f32_16x16x32_bf16 v[52:55], v[206:209], v[172:175], v[52:55]
	v_mfma_f32_16x16x32_bf16 v[44:47], v[214:217], v[172:175], v[44:47]
	v_mfma_f32_16x16x32_bf16 v[36:39], v[206:209], v[180:183], v[36:39]
	v_mfma_f32_16x16x32_bf16 v[28:31], v[214:217], v[180:183], v[28:31]
	v_mfma_f32_16x16x32_bf16 v[20:23], v[206:209], v[188:191], v[20:23]
	v_mfma_f32_16x16x32_bf16 v[12:15], v[214:217], v[188:191], v[12:15]
	v_mfma_f32_16x16x32_bf16 v[4:7], v[206:209], v[196:199], v[4:7]
	v_mfma_f32_16x16x32_bf16 v[0:3], v[214:217], v[196:199], v[0:3]
	s_setprio 0
	s_add_i32 s53, s53, 2
	s_add_u32 s22, s22, 0x100
	s_addc_u32 s23, s23, 0
	s_add_u32 s51, s51, 0x100
	s_addc_u32 s52, s52, 0
	s_cmp_gt_u32 s53, 13
	s_barrier
; __device__ __forceinline__ unsigned cvt_pk_bf16(float lo, float hi) { unsigned r; asm volatile("v_cvt_pk_bf16_f32 %0, %1, %2" : "=v"(r) : "v"(lo), "v"(hi)); return r; }
; #define PG8_MMA(ai, bj, At, Bt) do { __builtin_amdgcn_s_setprio(1); _Pragma("unroll") for (int m = 0; m < 4; ++m) _Pragma("unroll") for (int n = 0; n < 2; ++n) _Pragma("unroll") for (int k = 0; k < 2; ++k) \
;         acc[ai][bj][m][n] = __builtin_amdgcn_mfma_f32_16x16x32_bf16(Bt[n][k], At[m][k], acc[ai][bj][m][n], 0, 0, 0); __builtin_amdgcn_s_setprio(0); } while (0)
; #define PG8_WAIT_V(n) asm volatile("s_waitcnt vmcnt(" #n ")" ::: "memory")
; #define PG8_BAR __builtin_amdgcn_s_barrier()
; template <class Epi, class Sched>
; __device__ __forceinline__ void gemm_phase(LAS unsigned char* lds, const Gemm g, const Sched& S, const Epi& E) {
;     ...
;             PG8_WAIT_V(6); PG8_BAR; PG8_MMA(1, 1, At, B1); PG8_BAR;
;         }
;         E(acc, cur, wr, wc, fr, fq);
;         if (!has_next) break;
;     __device__ __forceinline__ void operator()(const AccT& acc, const Unit& u, int wr, int wc, int fr, int fq) const {
;     ...
;         const int rbase = u.pm * 256 + wr * 64 + fr;
;         const int tb = u.pn * 256 + wc * 32 + 8 * fq;
; #pragma unroll
;         for (int ai = 0; ai < 2; ++ai)
; #pragma unroll
;             for (int m = 0; m < 4; ++m) {
;                 const int gm = rbase + ai * 128 + m * 16;
; #pragma unroll
;                 for (int bj = 0; bj < 2; ++bj) {
;                     const int t0 = tb + bj * 128;
;                     const f32x4 v0 = acc[ai][bj][m][0], v1 = acc[ai][bj][m][1];
;                     u32x4 w; w.x = cvt_pk_bf16(v0[0], v0[1]); w.y = cvt_pk_bf16(v0[2], v0[3]); w.z = cvt_pk_bf16(v1[0], v1[1]); w.w = cvt_pk_bf16(v1[2], v1[3]);
;                     *(u32x4*)(YT + ((size_t)((t0 >> 10) * 512 + gm)) * 2048 + part * 1024 + (t0 & 1023)) = w;
;                 }
	s_cbranch_scc0 .LBB0_653
	v_mov_b32_e32 v136, v147
	v_mov_b32_e32 v152, v146
	s_lshl_b32 s7, s20, 8
	s_add_i32 s7, s7, s36
	v_add_u32_e32 v152, s7, v152
	s_lshl_b32 s7, s47, 8
	s_or_b32 s7, s7, s37
	v_lshl_add_u32 v153, v136, 3, s7
	v_cvt_pk_bf16_f32 v124, v124, v125
	v_cvt_pk_bf16_f32 v125, v126, v127
	v_cvt_pk_bf16_f32 v126, v120, v121
	v_ashrrev_i32_e32 v120, 1, v153
	v_cvt_pk_bf16_f32 v127, v122, v123
	v_and_b32_e32 v122, 0xfffffe00, v120
	v_add_u32_e32 v120, v122, v152
	v_ashrrev_i32_e32 v121, 31, v120
	v_lshlrev_b64 v[120:121], 12, v[120:121]
	v_and_b32_e32 v123, 0x3f8, v153
	v_lshl_add_u64 v[120:121], s[68:69], 0, v[120:121]
	v_lshlrev_b32_e32 v136, 1, v123
	v_lshl_add_u64 v[120:121], v[120:121], 0, v[136:137]
	global_store_dwordx4 v[120:121], v[124:127], off
	v_add_u32_e32 v120, 0x80, v153
	v_cvt_pk_bf16_f32 v116, v116, v117
	v_cvt_pk_bf16_f32 v117, v118, v119
	v_cvt_pk_bf16_f32 v118, v108, v109
	v_ashrrev_i32_e32 v108, 1, v120
	v_and_b32_e32 v121, 0xfffffe00, v108
	v_add_u32_e32 v108, v121, v152
	v_ashrrev_i32_e32 v109, 31, v108
	v_lshlrev_b64 v[108:109], 12, v[108:109]
	v_cvt_pk_bf16_f32 v119, v110, v111
	v_lshl_add_u64 v[110:111], s[68:69], 0, v[108:109]
	v_and_b32_e32 v108, 0x3f8, v120
	v_lshlrev_b32_e32 v108, 1, v108
	v_mov_b32_e32 v109, v137
	v_lshl_add_u64 v[110:111], v[110:111], 0, v[108:109]
	global_store_dwordx4 v[110:111], v[116:119], off
	v_cvt_pk_bf16_f32 v110, v112, v113
	v_cvt_pk_bf16_f32 v111, v114, v115
	v_cvt_pk_bf16_f32 v112, v104, v105
	v_cvt_pk_bf16_f32 v113, v106, v107
	s_and_b64 vcc, exec, s[4:5]
	s_nop 0
	v_add_u32_e32 v116, 16, v152
	v_add_u32_e32 v104, v122, v116
	v_ashrrev_i32_e32 v105, 31, v104
	v_lshlrev_b64 v[104:105], 12, v[104:105]
	v_lshl_add_u64 v[104:105], s[68:69], 0, v[104:105]
	v_lshl_add_u64 v[104:105], v[104:105], 0, v[136:137]
	global_store_dwordx4 v[104:105], v[110:113], off
	v_cvt_pk_bf16_f32 v100, v100, v101
	v_cvt_pk_bf16_f32 v101, v102, v103
	v_cvt_pk_bf16_f32 v102, v92, v93
	v_add_u32_e32 v92, v121, v116
	v_ashrrev_i32_e32 v93, 31, v92
	v_lshlrev_b64 v[92:93], 12, v[92:93]
	v_lshl_add_u64 v[92:93], s[68:69], 0, v[92:93]
	v_lshl_add_u64 v[92:93], v[92:93], 0, v[108:109]
	v_cvt_pk_bf16_f32 v103, v94, v95
	global_store_dwordx4 v[92:93], v[100:103], off
	v_cvt_pk_bf16_f32 v92, v96, v97
	v_cvt_pk_bf16_f32 v93, v98, v99
	v_cvt_pk_bf16_f32 v94, v88, v89
	v_cvt_pk_bf16_f32 v95, v90, v91
	s_mov_b32 s47, s6
	s_nop 0
	v_add_u32_e32 v100, 32, v152
	v_add_u32_e32 v88, v122, v100
	v_ashrrev_i32_e32 v89, 31, v88
	v_lshlrev_b64 v[88:89], 12, v[88:89]
	v_lshl_add_u64 v[88:89], s[68:69], 0, v[88:89]
	v_lshl_add_u64 v[88:89], v[88:89], 0, v[136:137]
	global_store_dwordx4 v[88:89], v[92:95], off
	v_cvt_pk_bf16_f32 v84, v84, v85
	v_cvt_pk_bf16_f32 v85, v86, v87
	v_cvt_pk_bf16_f32 v86, v76, v77
	v_add_u32_e32 v76, v121, v100
	v_ashrrev_i32_e32 v77, 31, v76
	v_lshlrev_b64 v[76:77], 12, v[76:77]
	v_lshl_add_u64 v[76:77], s[68:69], 0, v[76:77]
	v_lshl_add_u64 v[76:77], v[76:77], 0, v[108:109]
	v_cvt_pk_bf16_f32 v87, v78, v79
	global_store_dwordx4 v[76:77], v[84:87], off
	v_cvt_pk_bf16_f32 v76, v80, v81
	v_cvt_pk_bf16_f32 v77, v82, v83
	v_cvt_pk_bf16_f32 v78, v72, v73
	v_cvt_pk_bf16_f32 v79, v74, v75
	s_mov_b32 s20, s8
	s_nop 0
	v_add_u32_e32 v84, 48, v152
	v_add_u32_e32 v72, v122, v84
	v_ashrrev_i32_e32 v73, 31, v72
	v_lshlrev_b64 v[72:73], 12, v[72:73]
	v_lshl_add_u64 v[72:73], s[68:69], 0, v[72:73]
	v_lshl_add_u64 v[72:73], v[72:73], 0, v[136:137]
	global_store_dwordx4 v[72:73], v[76:79], off
	v_cvt_pk_bf16_f32 v68, v68, v69
	v_cvt_pk_bf16_f32 v69, v70, v71
; __device__ __forceinline__ unsigned cvt_pk_bf16(float lo, float hi) { unsigned r; asm volatile("v_cvt_pk_bf16_f32 %0, %1, %2" : "=v"(r) : "v"(lo), "v"(hi)); return r; }
;     __device__ __forceinline__ void operator()(const AccT& acc, const Unit& u, int wr, int wc, int fr, int fq) const {
;     ...
;                 const int gm = rbase + ai * 128 + m * 16;
; #pragma unroll
;                 for (int bj = 0; bj < 2; ++bj) {
;                     const int t0 = tb + bj * 128;
;                     const f32x4 v0 = acc[ai][bj][m][0], v1 = acc[ai][bj][m][1];
;                     u32x4 w; w.x = cvt_pk_bf16(v0[0], v0[1]); w.y = cvt_pk_bf16(v0[2], v0[3]); w.z = cvt_pk_bf16(v1[0], v1[1]); w.w = cvt_pk_bf16(v1[2], v1[3]);
;                     *(u32x4*)(YT + ((size_t)((t0 >> 10) * 512 + gm)) * 2048 + part * 1024 + (t0 & 1023)) = w;
;                 }
;             }
	v_cvt_pk_bf16_f32 v70, v64, v65
	v_add_u32_e32 v64, v121, v84
	v_ashrrev_i32_e32 v65, 31, v64
	v_lshlrev_b64 v[64:65], 12, v[64:65]
	v_lshl_add_u64 v[64:65], s[68:69], 0, v[64:65]
	v_lshl_add_u64 v[64:65], v[64:65], 0, v[108:109]
	v_cvt_pk_bf16_f32 v71, v66, v67
	global_store_dwordx4 v[64:65], v[68:71], off
	v_add_u32_e32 v64, 0x80, v152
	v_cvt_pk_bf16_f32 v60, v60, v61
	v_cvt_pk_bf16_f32 v61, v62, v63
	v_cvt_pk_bf16_f32 v62, v56, v57
	v_add_u32_e32 v56, v122, v64
	v_ashrrev_i32_e32 v57, 31, v56
	v_lshlrev_b64 v[56:57], 12, v[56:57]
	v_lshl_add_u64 v[56:57], s[68:69], 0, v[56:57]
	v_lshl_add_u64 v[56:57], v[56:57], 0, v[136:137]
	v_cvt_pk_bf16_f32 v63, v58, v59
	global_store_dwordx4 v[56:57], v[60:63], off
	v_cvt_pk_bf16_f32 v52, v52, v53
	v_cvt_pk_bf16_f32 v53, v54, v55
	v_cvt_pk_bf16_f32 v54, v44, v45
	v_add_u32_e32 v44, v121, v64
	v_ashrrev_i32_e32 v45, 31, v44
	v_lshlrev_b64 v[44:45], 12, v[44:45]
	v_lshl_add_u64 v[44:45], s[68:69], 0, v[44:45]
	v_lshl_add_u64 v[44:45], v[44:45], 0, v[108:109]
	v_cvt_pk_bf16_f32 v55, v46, v47
	global_store_dwordx4 v[44:45], v[52:55], off
	v_cvt_pk_bf16_f32 v44, v48, v49
	v_cvt_pk_bf16_f32 v45, v50, v51
	v_cvt_pk_bf16_f32 v46, v40, v41
	v_cvt_pk_bf16_f32 v47, v42, v43
	s_mov_b64 s[24:25], s[18:19]
	s_nop 0
	v_add_u32_e32 v52, 0x90, v152
	v_add_u32_e32 v40, v122, v52
	v_ashrrev_i32_e32 v41, 31, v40
	v_lshlrev_b64 v[40:41], 12, v[40:41]
	v_lshl_add_u64 v[40:41], s[68:69], 0, v[40:41]
	v_lshl_add_u64 v[40:41], v[40:41], 0, v[136:137]
	global_store_dwordx4 v[40:41], v[44:47], off
	v_cvt_pk_bf16_f32 v36, v36, v37
	v_cvt_pk_bf16_f32 v37, v38, v39
	v_cvt_pk_bf16_f32 v38, v28, v29
	v_add_u32_e32 v28, v121, v52
	v_ashrrev_i32_e32 v29, 31, v28
	v_lshlrev_b64 v[28:29], 12, v[28:29]
	v_lshl_add_u64 v[28:29], s[68:69], 0, v[28:29]
	v_lshl_add_u64 v[28:29], v[28:29], 0, v[108:109]
	v_cvt_pk_bf16_f32 v39, v30, v31
	global_store_dwordx4 v[28:29], v[36:39], off
	v_cvt_pk_bf16_f32 v28, v32, v33
	v_cvt_pk_bf16_f32 v29, v34, v35
	v_cvt_pk_bf16_f32 v30, v24, v25
	v_cvt_pk_bf16_f32 v31, v26, v27
	s_mov_b64 s[22:23], s[16:17]
	s_nop 0
	v_add_u32_e32 v36, 0xa0, v152
	v_add_u32_e32 v24, v122, v36
	v_ashrrev_i32_e32 v25, 31, v24
	v_lshlrev_b64 v[24:25], 12, v[24:25]
	v_lshl_add_u64 v[24:25], s[68:69], 0, v[24:25]
	v_lshl_add_u64 v[24:25], v[24:25], 0, v[136:137]
	global_store_dwordx4 v[24:25], v[28:31], off
	v_cvt_pk_bf16_f32 v20, v20, v21
	v_cvt_pk_bf16_f32 v21, v22, v23
	v_cvt_pk_bf16_f32 v22, v12, v13
	v_add_u32_e32 v12, v121, v36
	v_ashrrev_i32_e32 v13, 31, v12
	v_lshlrev_b64 v[12:13], 12, v[12:13]
	v_lshl_add_u64 v[12:13], s[68:69], 0, v[12:13]
	v_lshl_add_u64 v[12:13], v[12:13], 0, v[108:109]
	v_cvt_pk_bf16_f32 v23, v14, v15
	global_store_dwordx4 v[12:13], v[20:23], off
	v_cvt_pk_bf16_f32 v12, v16, v17
	v_cvt_pk_bf16_f32 v13, v18, v19
	v_cvt_pk_bf16_f32 v14, v8, v9
	v_cvt_pk_bf16_f32 v15, v10, v11
	s_nop 1
	v_add_u32_e32 v20, 0xb0, v152
	v_add_u32_e32 v8, v122, v20
	v_ashrrev_i32_e32 v9, 31, v8
	v_lshlrev_b64 v[8:9], 12, v[8:9]
	v_lshl_add_u64 v[8:9], s[68:69], 0, v[8:9]
	v_lshl_add_u64 v[8:9], v[8:9], 0, v[136:137]
	global_store_dwordx4 v[8:9], v[12:15], off
	v_cvt_pk_bf16_f32 v4, v4, v5
	v_cvt_pk_bf16_f32 v5, v6, v7
	v_cvt_pk_bf16_f32 v6, v0, v1
	v_add_u32_e32 v0, v121, v20
	v_ashrrev_i32_e32 v1, 31, v0
	v_lshlrev_b64 v[0:1], 12, v[0:1]
	v_lshl_add_u64 v[0:1], s[68:69], 0, v[0:1]
	v_lshl_add_u64 v[0:1], v[0:1], 0, v[108:109]
	v_cvt_pk_bf16_f32 v7, v2, v3
	global_store_dwordx4 v[0:1], v[4:7], off
	s_cbranch_vccz .LBB0_646
	s_waitcnt vmcnt(0)
	s_cmpk_gt_u32 s28, 0xff
	s_cbranch_scc1 .LBB0_657
	s_barrier

; #define PG8_STAGE(bufoff, gbase, voff) do { _Pragma("unroll") for (int _i = 0; _i < 2; ++_i) \
;         __builtin_amdgcn_global_load_lds((const unsigned*)((const char*)(gbase) + (voff)[_i]), (LAS unsigned*)(lds + (bufoff) + ldsw + _i * 8192), 16, 0, 0); } while (0)
; #define PG8_LDA(dst, b, h) do { _Pragma("unroll") for (int m = 0; m < 4; ++m) _Pragma("unroll") for (int k = 0; k < 2; ++k) dst[m][k] = *(const LAS bf16x8*)(lds + PG8_SA(b, h) + aoff + m * 2048 + k * 1024); } while (0)
; #define PG8_LDB(dst, b, h) do { _Pragma("unroll") for (int n = 0; n < 2; ++n) _Pragma("unroll") for (int k = 0; k < 2; ++k) dst[n][k] = *(const LAS bf16x8*)(lds + PG8_SB(b, h) + boff + n * 2048 + k * 1024); } while (0)
; #define PG8_MMA(ai, bj, At, Bt) do { __builtin_amdgcn_s_setprio(1); _Pragma("unroll") for (int m = 0; m < 4; ++m) _Pragma("unroll") for (int n = 0; n < 2; ++n) _Pragma("unroll") for (int k = 0; k < 2; ++k) \
;         acc[ai][bj][m][n] = __builtin_amdgcn_mfma_f32_16x16x32_bf16(Bt[n][k], At[m][k], acc[ai][bj][m][n], 0, 0, 0); __builtin_amdgcn_s_setprio(0); } while (0)
; #define PG8_WAIT_L(n) asm volatile("s_waitcnt lgkmcnt(" #n ")" ::: "memory")
; template <class Epi, class Sched>
; __device__ __forceinline__ void gemm_phase(LAS unsigned char* lds, const Gemm g, const Sched& S, const Epi& E) {
;     ...
;         const bool has_next = S.next(ui + 1, nxt);
;         const char* nA = has_next ? (const char*)g.A + (size_t)nxt.pm * tstep : cA; const char* nB = has_next ? (const char*)g.Bt + (size_t)nxt.pn * tstep : cB;
;         for (int t = 0; t < nt; t += 2) {
;             const bool last = (t == nt - 2);
;             const char* a1 = cA + (size_t)(t + 1) * kstep;
;             const char* a2 = last ? nA : cA + (size_t)(t + 2) * kstep; const char* b2 = last ? nB : cB + (size_t)(t + 2) * kstep;
;             const char* a3 = a2 + kstep; const char* b3 = b2 + kstep;
;             PG8_LDB(B0, 0, 0); PG8_SCHED; PG8_LDA(At, 0, 0); PG8_STAGE(PG8_SA(1, 1), a1 + hstep, voffA);
;             PG8_WAIT_L(8); PG8_BAR; PG8_WAIT_L(0); PG8_MMA(0, 0, At, B0); PG8_BAR; PG8_SCHED;
;             PG8_LDB(B1, 0, 1); PG8_STAGE(PG8_SB(0, 0), b2, voffB);
;             PG8_BAR; PG8_WAIT_L(0); PG8_MMA(0, 1, At, B1); PG8_BAR;
;             PG8_LDA(At, 0, 1); PG8_STAGE(PG8_SA(0, 0), a2, voffA);
;             PG8_BAR; PG8_WAIT_L(0); PG8_MMA(1, 0, At, B0); PG8_BAR; PG8_SCHED;
.LBB0_672:
	s_ashr_i32 s9, s8, 31
	v_cmp_lt_i64_e32 vcc, s[12:13], v[142:143]
	s_lshl_b64 s[12:13], s[8:9], 19
	s_add_u32 s12, s26, s12
	s_addc_u32 s13, s27, s13
	s_and_b64 s[14:15], vcc, exec
	s_cselect_b32 s9, s13, s19
	s_cselect_b32 s46, s12, s18
	s_ashr_i32 s7, s6, 31
	s_lshl_b64 s[14:15], s[6:7], 19
	s_add_u32 s14, s10, s14
	s_addc_u32 s15, s11, s15
	s_and_b64 s[22:23], vcc, exec
	s_cselect_b32 s7, s15, s21
	s_cselect_b32 s47, s14, s20
	s_add_u32 s18, s18, 0x40080
	s_addc_u32 s19, s19, 0
	s_add_u32 s48, s20, 0x100
	s_addc_u32 s49, s21, 0
	s_mov_b32 s51, -2
	s_waitcnt lgkmcnt(0)
	ds_read_b128 v[152:155], v149
	ds_read_b128 v[156:159], v149 offset:1024
	ds_read_b128 v[160:163], v149 offset:2048
	ds_read_b128 v[164:167], v149 offset:3072
	s_add_u32 s20, s18, 0xfffc0080
	s_addc_u32 s21, s19, -1
	s_cmp_eq_u32 s51, 12
	s_cselect_b32 s23, s9, s21
	s_cselect_b32 s22, s46, s20
	s_cselect_b32 s21, s7, s49
	s_cselect_b32 s20, s47, s48
	s_add_i32 m0, s17, 0xc000
	ds_read_b128 v[168:171], v150
	ds_read_b128 v[172:175], v150 offset:1024
	ds_read_b128 v[176:179], v150 offset:2048
	ds_read_b128 v[180:183], v150 offset:3072
	ds_read_b128 v[184:187], v150 offset:4096
	ds_read_b128 v[188:191], v150 offset:5120
	ds_read_b128 v[192:195], v150 offset:6144
	ds_read_b128 v[196:199], v150 offset:7168
	global_load_lds_dwordx4 v138, s[18:19]
	s_add_i32 m0, s17, 0xe000
	s_nop 0
	global_load_lds_dwordx4 v140, s[18:19]
	s_waitcnt lgkmcnt(8)
	s_waitcnt vmcnt(10)
	s_barrier
	s_waitcnt lgkmcnt(0)
	s_setprio 1
	s_waitcnt lgkmcnt(0)
	v_mfma_f32_16x16x32_bf16 v[124:127], v[152:155], v[168:171], 0
	v_mfma_f32_16x16x32_bf16 v[120:123], v[160:163], v[168:171], 0
	v_mfma_f32_16x16x32_bf16 v[112:115], v[152:155], v[176:179], 0
	v_mfma_f32_16x16x32_bf16 v[104:107], v[160:163], v[176:179], 0
	v_mfma_f32_16x16x32_bf16 v[96:99], v[152:155], v[184:187], 0
	v_mfma_f32_16x16x32_bf16 v[88:91], v[160:163], v[184:187], 0
	v_mfma_f32_16x16x32_bf16 v[80:83], v[152:155], v[192:195], 0
	v_mfma_f32_16x16x32_bf16 v[72:75], v[160:163], v[192:195], 0
	v_mfma_f32_16x16x32_bf16 v[124:127], v[156:159], v[172:175], v[124:127]
	v_mfma_f32_16x16x32_bf16 v[120:123], v[164:167], v[172:175], v[120:123]
	v_mfma_f32_16x16x32_bf16 v[112:115], v[156:159], v[180:183], v[112:115]
	v_mfma_f32_16x16x32_bf16 v[104:107], v[164:167], v[180:183], v[104:107]
	v_mfma_f32_16x16x32_bf16 v[96:99], v[156:159], v[188:191], v[96:99]
	v_mfma_f32_16x16x32_bf16 v[88:91], v[164:167], v[188:191], v[88:91]
	v_mfma_f32_16x16x32_bf16 v[80:83], v[156:159], v[196:199], v[80:83]
	v_mfma_f32_16x16x32_bf16 v[72:75], v[164:167], v[196:199], v[72:75]
	s_setprio 0
	s_barrier
	s_add_i32 s52, s43, s28
	s_mov_b32 m0, s52
	ds_read_b128 v[202:205], v151
	ds_read_b128 v[206:209], v151 offset:1024
	ds_read_b128 v[210:213], v151 offset:2048
	ds_read_b128 v[214:217], v151 offset:3072
	global_load_lds_dwordx4 v130, s[20:21]
	s_add_i32 m0, s52, 0x2000
	s_nop 0
	global_load_lds_dwordx4 v134, s[20:21]
	s_waitcnt vmcnt(10)
	s_barrier
	s_waitcnt lgkmcnt(0)
	s_setprio 1
	s_waitcnt lgkmcnt(0)
	v_mfma_f32_16x16x32_bf16 v[116:119], v[202:205], v[168:171], 0
	v_mfma_f32_16x16x32_bf16 v[108:111], v[210:213], v[168:171], 0
	v_mfma_f32_16x16x32_bf16 v[100:103], v[202:205], v[176:179], 0
	v_mfma_f32_16x16x32_bf16 v[92:95], v[210:213], v[176:179], 0
	v_mfma_f32_16x16x32_bf16 v[84:87], v[202:205], v[184:187], 0
	v_mfma_f32_16x16x32_bf16 v[76:79], v[210:213], v[184:187], 0
	v_mfma_f32_16x16x32_bf16 v[68:71], v[202:205], v[192:195], 0
	v_mfma_f32_16x16x32_bf16 v[64:67], v[210:213], v[192:195], 0
	v_mfma_f32_16x16x32_bf16 v[116:119], v[206:209], v[172:175], v[116:119]
	v_mfma_f32_16x16x32_bf16 v[108:111], v[214:217], v[172:175], v[108:111]
	v_mfma_f32_16x16x32_bf16 v[100:103], v[206:209], v[180:183], v[100:103]
	v_mfma_f32_16x16x32_bf16 v[92:95], v[214:217], v[180:183], v[92:95]
	v_mfma_f32_16x16x32_bf16 v[84:87], v[206:209], v[188:191], v[84:87]
	v_mfma_f32_16x16x32_bf16 v[76:79], v[214:217], v[188:191], v[76:79]
	v_mfma_f32_16x16x32_bf16 v[68:71], v[206:209], v[196:199], v[68:71]
	v_mfma_f32_16x16x32_bf16 v[64:67], v[214:217], v[196:199], v[64:67]
	s_setprio 0
	s_mov_b32 m0, s17
	v_lshl_add_u64 v[222:223], s[22:23], 0, v[128:129]
	s_barrier
	ds_read_b128 v[168:171], v150 offset:16384
	ds_read_b128 v[172:175], v150 offset:17408
	ds_read_b128 v[176:179], v150 offset:18432
	ds_read_b128 v[180:183], v150 offset:19456
	ds_read_b128 v[184:187], v150 offset:20480
	ds_read_b128 v[188:191], v150 offset:21504
	ds_read_b128 v[192:195], v150 offset:22528
	ds_read_b128 v[196:199], v150 offset:23552
	global_load_lds_dwordx4 v128, s[22:23]
	v_lshl_add_u64 v[224:225], s[22:23], 0, v[132:133]
	s_mov_b32 m0, s29
	s_nop 0
	global_load_lds_dwordx4 v132, s[22:23]
	s_barrier
	s_waitcnt lgkmcnt(0)
	s_setprio 1
	s_waitcnt lgkmcnt(0)
	v_mfma_f32_16x16x32_bf16 v[60:63], v[152:155], v[168:171], 0
	v_mfma_f32_16x16x32_bf16 v[56:59], v[160:163], v[168:171], 0
	v_mfma_f32_16x16x32_bf16 v[48:51], v[152:155], v[176:179], 0
	v_mfma_f32_16x16x32_bf16 v[40:43], v[160:163], v[176:179], 0
	v_mfma_f32_16x16x32_bf16 v[32:35], v[152:155], v[184:187], 0
	v_mfma_f32_16x16x32_bf16 v[24:27], v[160:163], v[184:187], 0
	v_mfma_f32_16x16x32_bf16 v[16:19], v[152:155], v[192:195], 0
	v_mfma_f32_16x16x32_bf16 v[8:11], v[160:163], v[192:195], 0
	v_mfma_f32_16x16x32_bf16 v[60:63], v[156:159], v[172:175], v[60:63]
	v_mfma_f32_16x16x32_bf16 v[56:59], v[164:167], v[172:175], v[56:59]
	v_mfma_f32_16x16x32_bf16 v[48:51], v[156:159], v[180:183], v[48:51]
	v_mfma_f32_16x16x32_bf16 v[40:43], v[164:167], v[180:183], v[40:43]
	v_mfma_f32_16x16x32_bf16 v[32:35], v[156:159], v[188:191], v[32:35]
	v_mfma_f32_16x16x32_bf16 v[24:27], v[164:167], v[188:191], v[24:27]
	v_mfma_f32_16x16x32_bf16 v[16:19], v[156:159], v[196:199], v[16:19]
	v_mfma_f32_16x16x32_bf16 v[8:11], v[164:167], v[196:199], v[8:11]
	s_setprio 0
	s_barrier
; #define PG8_STAGE(bufoff, gbase, voff) do { _Pragma("unroll") for (int _i = 0; _i < 2; ++_i) \
;         __builtin_amdgcn_global_load_lds((const unsigned*)((const char*)(gbase) + (voff)[_i]), (LAS unsigned*)(lds + (bufoff) + ldsw + _i * 8192), 16, 0, 0); } while (0)
; #define PG8_LDA(dst, b, h) do { _Pragma("unroll") for (int m = 0; m < 4; ++m) _Pragma("unroll") for (int k = 0; k < 2; ++k) dst[m][k] = *(const LAS bf16x8*)(lds + PG8_SA(b, h) + aoff + m * 2048 + k * 1024); } while (0)
; #define PG8_LDB(dst, b, h) do { _Pragma("unroll") for (int n = 0; n < 2; ++n) _Pragma("unroll") for (int k = 0; k < 2; ++k) dst[n][k] = *(const LAS bf16x8*)(lds + PG8_SB(b, h) + boff + n * 2048 + k * 1024); } while (0)
; #define PG8_MMA(ai, bj, At, Bt) do { __builtin_amdgcn_s_setprio(1); _Pragma("unroll") for (int m = 0; m < 4; ++m) _Pragma("unroll") for (int n = 0; n < 2; ++n) _Pragma("unroll") for (int k = 0; k < 2; ++k) \
;         acc[ai][bj][m][n] = __builtin_amdgcn_mfma_f32_16x16x32_bf16(Bt[n][k], At[m][k], acc[ai][bj][m][n], 0, 0, 0); __builtin_amdgcn_s_setprio(0); } while (0)
; #define PG8_WAIT_V(n) asm volatile("s_waitcnt vmcnt(" #n ")" ::: "memory")
; #define PG8_WAIT_L(n) asm volatile("s_waitcnt lgkmcnt(" #n ")" ::: "memory")
; #define PG8_BAR __builtin_amdgcn_s_barrier()
; #define PG8_SCHED __builtin_amdgcn_sched_barrier(0)
; template <class Epi, class Sched>
; __device__ __forceinline__ void gemm_phase(LAS unsigned char* lds, const Gemm g, const Sched& S, const Epi& E) {
;     ...
;             PG8_STAGE(PG8_SB(0, 1), b2 + hstep, voffB);
;             PG8_WAIT_V(6); PG8_BAR; PG8_MMA(1, 1, At, B1); PG8_BAR;
;             PG8_LDB(B0, 1, 0); PG8_SCHED; PG8_LDA(At, 1, 0); PG8_STAGE(PG8_SA(0, 1), a2 + hstep, voffA);
;             PG8_WAIT_L(8); PG8_BAR; PG8_WAIT_L(0); PG8_MMA(0, 0, At, B0); PG8_BAR; PG8_SCHED;
;             PG8_LDB(B1, 1, 1); PG8_STAGE(PG8_SB(1, 0), b3, voffB);
;             PG8_BAR; PG8_WAIT_L(0); PG8_MMA(0, 1, At, B1); PG8_BAR;
;             PG8_LDA(At, 1, 1); PG8_STAGE(PG8_SA(1, 0), a3, voffA);
;             PG8_BAR; PG8_WAIT_L(0); PG8_MMA(1, 0, At, B0); PG8_BAR; PG8_SCHED;
	s_add_u32 s52, s20, 0x40000
	s_addc_u32 s53, s21, 0
	s_add_i32 s54, s44, s28
	s_mov_b32 m0, s54
	s_nop 0
	global_load_lds_dwordx4 v130, s[52:53]
	s_add_i32 m0, s54, 0x2000
	s_nop 0
	global_load_lds_dwordx4 v134, s[52:53]
	s_add_u32 s22, s22, 0x40000
	s_addc_u32 s23, s23, 0
	s_mov_b32 m0, s30
	s_nop 0
	global_load_lds_dwordx4 v128, s[22:23]
	s_mov_b32 m0, s31
	s_nop 0
	global_load_lds_dwordx4 v132, s[22:23]
	s_waitcnt vmcnt(12)
	s_barrier
	s_setprio 1
	v_mfma_f32_16x16x32_bf16 v[52:55], v[202:205], v[168:171], 0
	v_mfma_f32_16x16x32_bf16 v[44:47], v[210:213], v[168:171], 0
	v_mfma_f32_16x16x32_bf16 v[36:39], v[202:205], v[176:179], 0
	v_mfma_f32_16x16x32_bf16 v[28:31], v[210:213], v[176:179], 0
	v_mfma_f32_16x16x32_bf16 v[20:23], v[202:205], v[184:187], 0
	v_mfma_f32_16x16x32_bf16 v[12:15], v[210:213], v[184:187], 0
	v_mfma_f32_16x16x32_bf16 v[4:7], v[202:205], v[192:195], 0
	v_mfma_f32_16x16x32_bf16 v[0:3], v[210:213], v[192:195], 0
	v_mfma_f32_16x16x32_bf16 v[52:55], v[206:209], v[172:175], v[52:55]
	v_mfma_f32_16x16x32_bf16 v[44:47], v[214:217], v[172:175], v[44:47]
	v_mfma_f32_16x16x32_bf16 v[36:39], v[206:209], v[180:183], v[36:39]
	v_mfma_f32_16x16x32_bf16 v[28:31], v[214:217], v[180:183], v[28:31]
	v_mfma_f32_16x16x32_bf16 v[20:23], v[206:209], v[188:191], v[20:23]
	v_mfma_f32_16x16x32_bf16 v[12:15], v[214:217], v[188:191], v[12:15]
	v_mfma_f32_16x16x32_bf16 v[4:7], v[206:209], v[196:199], v[4:7]
	v_mfma_f32_16x16x32_bf16 v[0:3], v[214:217], v[196:199], v[0:3]
	s_setprio 0
	s_add_i32 s52, 0, 0x18000
	v_add_u32_e32 v136, s52, v148
	s_barrier
	ds_read_b128 v[152:155], v136
	ds_read_b128 v[156:159], v136 offset:1024
	ds_read_b128 v[160:163], v136 offset:2048
	ds_read_b128 v[164:167], v136 offset:3072
	ds_read_b128 v[168:171], v150 offset:32768
	ds_read_b128 v[172:175], v150 offset:33792
	ds_read_b128 v[176:179], v150 offset:34816
	ds_read_b128 v[180:183], v150 offset:35840
	ds_read_b128 v[184:187], v150 offset:36864
	ds_read_b128 v[188:191], v150 offset:37888
	ds_read_b128 v[192:195], v150 offset:38912
	ds_read_b128 v[196:199], v150 offset:39936
	s_waitcnt lgkmcnt(8)
	s_waitcnt vmcnt(10)
	s_barrier
	s_waitcnt lgkmcnt(0)
	s_setprio 1
	s_waitcnt lgkmcnt(0)
	v_mfma_f32_16x16x32_bf16 v[124:127], v[152:155], v[168:171], v[124:127]
	v_mfma_f32_16x16x32_bf16 v[120:123], v[160:163], v[168:171], v[120:123]
	v_mfma_f32_16x16x32_bf16 v[112:115], v[152:155], v[176:179], v[112:115]
	v_mfma_f32_16x16x32_bf16 v[104:107], v[160:163], v[176:179], v[104:107]
	v_mfma_f32_16x16x32_bf16 v[96:99], v[152:155], v[184:187], v[96:99]
	v_mfma_f32_16x16x32_bf16 v[88:91], v[160:163], v[184:187], v[88:91]
	v_mfma_f32_16x16x32_bf16 v[80:83], v[152:155], v[192:195], v[80:83]
	v_mfma_f32_16x16x32_bf16 v[72:75], v[160:163], v[192:195], v[72:75]
	v_mfma_f32_16x16x32_bf16 v[124:127], v[156:159], v[172:175], v[124:127]
	v_mfma_f32_16x16x32_bf16 v[120:123], v[164:167], v[172:175], v[120:123]
	v_mfma_f32_16x16x32_bf16 v[112:115], v[156:159], v[180:183], v[112:115]
	v_mfma_f32_16x16x32_bf16 v[104:107], v[164:167], v[180:183], v[104:107]
	v_mfma_f32_16x16x32_bf16 v[96:99], v[156:159], v[188:191], v[96:99]
	v_mfma_f32_16x16x32_bf16 v[88:91], v[164:167], v[188:191], v[88:91]
	v_mfma_f32_16x16x32_bf16 v[80:83], v[156:159], v[196:199], v[80:83]
	v_mfma_f32_16x16x32_bf16 v[72:75], v[164:167], v[196:199], v[72:75]
	s_setprio 0
	s_barrier
	s_add_i32 s22, 0, 0x1c000
	s_add_i32 s23, s52, s28
	v_add_u32_e32 v136, s22, v148
	s_add_u32 s0, s20, 0x80
	s_addc_u32 s1, s21, 0
	s_mov_b32 m0, s23
	ds_read_b128 v[202:205], v136
	ds_read_b128 v[206:209], v136 offset:1024
	ds_read_b128 v[210:213], v136 offset:2048
	ds_read_b128 v[214:217], v136 offset:3072
	global_load_lds_dwordx4 v130, s[0:1]
	s_add_i32 m0, s23, 0x2000
	s_nop 0
	global_load_lds_dwordx4 v134, s[0:1]
	s_waitcnt vmcnt(10)
	s_barrier
	s_waitcnt lgkmcnt(0)
	s_setprio 1
	s_waitcnt lgkmcnt(0)
	v_mfma_f32_16x16x32_bf16 v[116:119], v[202:205], v[168:171], v[116:119]
	v_mfma_f32_16x16x32_bf16 v[108:111], v[210:213], v[168:171], v[108:111]
	v_mfma_f32_16x16x32_bf16 v[100:103], v[202:205], v[176:179], v[100:103]
	v_mfma_f32_16x16x32_bf16 v[92:95], v[210:213], v[176:179], v[92:95]
	v_mfma_f32_16x16x32_bf16 v[84:87], v[202:205], v[184:187], v[84:87]
	v_mfma_f32_16x16x32_bf16 v[76:79], v[210:213], v[184:187], v[76:79]
	v_mfma_f32_16x16x32_bf16 v[68:71], v[202:205], v[192:195], v[68:71]
	v_mfma_f32_16x16x32_bf16 v[64:67], v[210:213], v[192:195], v[64:67]
	v_mfma_f32_16x16x32_bf16 v[116:119], v[206:209], v[172:175], v[116:119]
	v_mfma_f32_16x16x32_bf16 v[108:111], v[214:217], v[172:175], v[108:111]
	v_mfma_f32_16x16x32_bf16 v[100:103], v[206:209], v[180:183], v[100:103]
	v_mfma_f32_16x16x32_bf16 v[92:95], v[214:217], v[180:183], v[92:95]
	v_mfma_f32_16x16x32_bf16 v[84:87], v[206:209], v[188:191], v[84:87]
	v_mfma_f32_16x16x32_bf16 v[76:79], v[214:217], v[188:191], v[76:79]
	v_mfma_f32_16x16x32_bf16 v[68:71], v[206:209], v[196:199], v[68:71]
	v_mfma_f32_16x16x32_bf16 v[64:67], v[214:217], v[196:199], v[64:67]
	s_setprio 0
	s_mov_b32 m0, s36
	s_mov_b64 s[0:1], 0x80
	v_lshl_add_u64 v[218:219], v[222:223], 0, s[0:1]
	s_barrier
	ds_read_b128 v[168:171], v150 offset:49152
	ds_read_b128 v[172:175], v150 offset:50176
	ds_read_b128 v[176:179], v150 offset:51200
	ds_read_b128 v[180:183], v150 offset:52224
	ds_read_b128 v[184:187], v150 offset:53248
	ds_read_b128 v[188:191], v150 offset:54272
	ds_read_b128 v[192:195], v150 offset:55296
	ds_read_b128 v[196:199], v150 offset:56320
	global_load_lds_dwordx4 v[218:219], off
	v_lshl_add_u64 v[218:219], v[224:225], 0, s[0:1]
	s_mov_b32 m0, s37
	s_nop 0
	global_load_lds_dwordx4 v[218:219], off
	s_barrier
; #define PG8_STAGE(bufoff, gbase, voff) do { _Pragma("unroll") for (int _i = 0; _i < 2; ++_i) \
;         __builtin_amdgcn_global_load_lds((const unsigned*)((const char*)(gbase) + (voff)[_i]), (LAS unsigned*)(lds + (bufoff) + ldsw + _i * 8192), 16, 0, 0); } while (0)
; #define PG8_LDA(dst, b, h) do { _Pragma("unroll") for (int m = 0; m < 4; ++m) _Pragma("unroll") for (int k = 0; k < 2; ++k) dst[m][k] = *(const LAS bf16x8*)(lds + PG8_SA(b, h) + aoff + m * 2048 + k * 1024); } while (0)
; #define PG8_LDB(dst, b, h) do { _Pragma("unroll") for (int n = 0; n < 2; ++n) _Pragma("unroll") for (int k = 0; k < 2; ++k) dst[n][k] = *(const LAS bf16x8*)(lds + PG8_SB(b, h) + boff + n * 2048 + k * 1024); } while (0)
; #define PG8_MMA(ai, bj, At, Bt) do { __builtin_amdgcn_s_setprio(1); _Pragma("unroll") for (int m = 0; m < 4; ++m) _Pragma("unroll") for (int n = 0; n < 2; ++n) _Pragma("unroll") for (int k = 0; k < 2; ++k) \
;         acc[ai][bj][m][n] = __builtin_amdgcn_mfma_f32_16x16x32_bf16(Bt[n][k], At[m][k], acc[ai][bj][m][n], 0, 0, 0); __builtin_amdgcn_s_setprio(0); } while (0)
; #define PG8_WAIT_V(n) asm volatile("s_waitcnt vmcnt(" #n ")" ::: "memory")
; #define PG8_WAIT_L(n) asm volatile("s_waitcnt lgkmcnt(" #n ")" ::: "memory")
; #define PG8_BAR __builtin_amdgcn_s_barrier()
; #define PG8_SCHED __builtin_amdgcn_sched_barrier(0)
; template <class Epi, class Sched>
; __device__ __forceinline__ void gemm_phase(LAS unsigned char* lds, const Gemm g, const Sched& S, const Epi& E) {
;     ...
;             PG8_LDB(B0, 0, 0); PG8_SCHED; PG8_LDA(At, 0, 0); PG8_STAGE(PG8_SA(1, 1), a1 + hstep, voffA);
;             PG8_WAIT_L(8); PG8_BAR; PG8_WAIT_L(0); PG8_MMA(0, 0, At, B0); PG8_BAR; PG8_SCHED;
;             PG8_LDB(B1, 0, 1); PG8_STAGE(PG8_SB(0, 0), b2, voffB);
;             PG8_BAR; PG8_WAIT_L(0); PG8_MMA(0, 1, At, B1); PG8_BAR;
;     ...
;             PG8_BAR; PG8_WAIT_L(0); PG8_MMA(1, 0, At, B0); PG8_BAR; PG8_SCHED;
;             PG8_STAGE(PG8_SB(1, 1), b3 + hstep, voffB);
;             PG8_WAIT_V(6); PG8_BAR; PG8_MMA(1, 1, At, B1); PG8_BAR;
	s_waitcnt lgkmcnt(0)
	s_setprio 1
	s_waitcnt lgkmcnt(0)
	v_mfma_f32_16x16x32_bf16 v[60:63], v[152:155], v[168:171], v[60:63]
	v_mfma_f32_16x16x32_bf16 v[56:59], v[160:163], v[168:171], v[56:59]
	v_mfma_f32_16x16x32_bf16 v[48:51], v[152:155], v[176:179], v[48:51]
	v_mfma_f32_16x16x32_bf16 v[40:43], v[160:163], v[176:179], v[40:43]
	v_mfma_f32_16x16x32_bf16 v[32:35], v[152:155], v[184:187], v[32:35]
	v_mfma_f32_16x16x32_bf16 v[24:27], v[160:163], v[184:187], v[24:27]
	v_mfma_f32_16x16x32_bf16 v[16:19], v[152:155], v[192:195], v[16:19]
	v_mfma_f32_16x16x32_bf16 v[8:11], v[160:163], v[192:195], v[8:11]
	v_mfma_f32_16x16x32_bf16 v[60:63], v[156:159], v[172:175], v[60:63]
	v_mfma_f32_16x16x32_bf16 v[56:59], v[164:167], v[172:175], v[56:59]
	v_mfma_f32_16x16x32_bf16 v[48:51], v[156:159], v[180:183], v[48:51]
	v_mfma_f32_16x16x32_bf16 v[40:43], v[164:167], v[180:183], v[40:43]
	v_mfma_f32_16x16x32_bf16 v[32:35], v[156:159], v[188:191], v[32:35]
	v_mfma_f32_16x16x32_bf16 v[24:27], v[164:167], v[188:191], v[24:27]
	v_mfma_f32_16x16x32_bf16 v[16:19], v[156:159], v[196:199], v[16:19]
	v_mfma_f32_16x16x32_bf16 v[8:11], v[164:167], v[196:199], v[8:11]
	s_setprio 0
	s_barrier
	s_add_u32 s20, s20, 0x40080
	s_addc_u32 s21, s21, 0
	s_add_i32 s22, s22, s28
	s_mov_b32 m0, s22
	s_nop 0
	global_load_lds_dwordx4 v130, s[20:21]
	s_add_i32 m0, s22, 0x2000
	s_nop 0
	global_load_lds_dwordx4 v134, s[20:21]
	s_waitcnt vmcnt(10)
	s_barrier
	s_setprio 1
	v_mfma_f32_16x16x32_bf16 v[52:55], v[202:205], v[168:171], v[52:55]
	v_mfma_f32_16x16x32_bf16 v[44:47], v[210:213], v[168:171], v[44:47]
	v_mfma_f32_16x16x32_bf16 v[36:39], v[202:205], v[176:179], v[36:39]
	v_mfma_f32_16x16x32_bf16 v[28:31], v[210:213], v[176:179], v[28:31]
	v_mfma_f32_16x16x32_bf16 v[20:23], v[202:205], v[184:187], v[20:23]
	v_mfma_f32_16x16x32_bf16 v[12:15], v[210:213], v[184:187], v[12:15]
	v_mfma_f32_16x16x32_bf16 v[4:7], v[202:205], v[192:195], v[4:7]
	v_mfma_f32_16x16x32_bf16 v[0:3], v[210:213], v[192:195], v[0:3]
	v_mfma_f32_16x16x32_bf16 v[52:55], v[206:209], v[172:175], v[52:55]
	v_mfma_f32_16x16x32_bf16 v[44:47], v[214:217], v[172:175], v[44:47]
	v_mfma_f32_16x16x32_bf16 v[36:39], v[206:209], v[180:183], v[36:39]
	v_mfma_f32_16x16x32_bf16 v[28:31], v[214:217], v[180:183], v[28:31]
	v_mfma_f32_16x16x32_bf16 v[20:23], v[206:209], v[188:191], v[20:23]
	v_mfma_f32_16x16x32_bf16 v[12:15], v[214:217], v[188:191], v[12:15]
	v_mfma_f32_16x16x32_bf16 v[4:7], v[206:209], v[196:199], v[4:7]
	v_mfma_f32_16x16x32_bf16 v[0:3], v[214:217], v[196:199], v[0:3]
	s_setprio 0
	s_add_i32 s51, s51, 2
	s_add_u32 s18, s18, 0x100
	s_addc_u32 s19, s19, 0
	s_add_u32 s48, s48, 0x100
	s_addc_u32 s49, s49, 0
	s_cmp_gt_u32 s51, 13
	s_barrier
.LBB0_673:
	ds_read_b128 v[152:155], v149
	ds_read_b128 v[156:159], v149 offset:1024
	ds_read_b128 v[160:163], v149 offset:2048
	ds_read_b128 v[164:167], v149 offset:3072
	s_add_u32 s20, s18, 0xfffc0080
	s_addc_u32 s21, s19, -1
	s_cmp_eq_u32 s51, 12
	s_cselect_b32 s23, s9, s21
	s_cselect_b32 s22, s46, s20
	s_cselect_b32 s21, s7, s49
	s_cselect_b32 s20, s47, s48
	s_add_i32 m0, s17, 0xc000
	ds_read_b128 v[168:171], v150
	ds_read_b128 v[172:175], v150 offset:1024
	ds_read_b128 v[176:179], v150 offset:2048
	ds_read_b128 v[180:183], v150 offset:3072
	ds_read_b128 v[184:187], v150 offset:4096
	ds_read_b128 v[188:191], v150 offset:5120
	ds_read_b128 v[192:195], v150 offset:6144
	ds_read_b128 v[196:199], v150 offset:7168
	global_load_lds_dwordx4 v138, s[18:19]
	s_add_i32 m0, s17, 0xe000
	s_nop 0
	global_load_lds_dwordx4 v140, s[18:19]
	s_waitcnt lgkmcnt(8)
	s_waitcnt vmcnt(10)
	s_barrier
	s_waitcnt lgkmcnt(0)
	s_setprio 1
	s_waitcnt lgkmcnt(0)
	v_mfma_f32_16x16x32_bf16 v[124:127], v[152:155], v[168:171], v[124:127]
	v_mfma_f32_16x16x32_bf16 v[120:123], v[160:163], v[168:171], v[120:123]
	v_mfma_f32_16x16x32_bf16 v[112:115], v[152:155], v[176:179], v[112:115]
	v_mfma_f32_16x16x32_bf16 v[104:107], v[160:163], v[176:179], v[104:107]
	v_mfma_f32_16x16x32_bf16 v[96:99], v[152:155], v[184:187], v[96:99]
	v_mfma_f32_16x16x32_bf16 v[88:91], v[160:163], v[184:187], v[88:91]
	v_mfma_f32_16x16x32_bf16 v[80:83], v[152:155], v[192:195], v[80:83]
	v_mfma_f32_16x16x32_bf16 v[72:75], v[160:163], v[192:195], v[72:75]
	v_mfma_f32_16x16x32_bf16 v[124:127], v[156:159], v[172:175], v[124:127]
	v_mfma_f32_16x16x32_bf16 v[120:123], v[164:167], v[172:175], v[120:123]
	v_mfma_f32_16x16x32_bf16 v[112:115], v[156:159], v[180:183], v[112:115]
	v_mfma_f32_16x16x32_bf16 v[104:107], v[164:167], v[180:183], v[104:107]
	v_mfma_f32_16x16x32_bf16 v[96:99], v[156:159], v[188:191], v[96:99]
	v_mfma_f32_16x16x32_bf16 v[88:91], v[164:167], v[188:191], v[88:91]
	v_mfma_f32_16x16x32_bf16 v[80:83], v[156:159], v[196:199], v[80:83]
	v_mfma_f32_16x16x32_bf16 v[72:75], v[164:167], v[196:199], v[72:75]
	s_setprio 0
	s_barrier
	s_add_i32 s52, s43, s28
	s_mov_b32 m0, s52
	ds_read_b128 v[202:205], v151
	ds_read_b128 v[206:209], v151 offset:1024
	ds_read_b128 v[210:213], v151 offset:2048
	ds_read_b128 v[214:217], v151 offset:3072
	global_load_lds_dwordx4 v130, s[20:21]
	s_add_i32 m0, s52, 0x2000
	s_nop 0
	global_load_lds_dwordx4 v134, s[20:21]
	s_waitcnt vmcnt(10)
	s_barrier
; #define PG8_STAGE(bufoff, gbase, voff) do { _Pragma("unroll") for (int _i = 0; _i < 2; ++_i) \
;         __builtin_amdgcn_global_load_lds((const unsigned*)((const char*)(gbase) + (voff)[_i]), (LAS unsigned*)(lds + (bufoff) + ldsw + _i * 8192), 16, 0, 0); } while (0)
; #define PG8_LDA(dst, b, h) do { _Pragma("unroll") for (int m = 0; m < 4; ++m) _Pragma("unroll") for (int k = 0; k < 2; ++k) dst[m][k] = *(const LAS bf16x8*)(lds + PG8_SA(b, h) + aoff + m * 2048 + k * 1024); } while (0)
; #define PG8_LDB(dst, b, h) do { _Pragma("unroll") for (int n = 0; n < 2; ++n) _Pragma("unroll") for (int k = 0; k < 2; ++k) dst[n][k] = *(const LAS bf16x8*)(lds + PG8_SB(b, h) + boff + n * 2048 + k * 1024); } while (0)
; #define PG8_MMA(ai, bj, At, Bt) do { __builtin_amdgcn_s_setprio(1); _Pragma("unroll") for (int m = 0; m < 4; ++m) _Pragma("unroll") for (int n = 0; n < 2; ++n) _Pragma("unroll") for (int k = 0; k < 2; ++k) \
;         acc[ai][bj][m][n] = __builtin_amdgcn_mfma_f32_16x16x32_bf16(Bt[n][k], At[m][k], acc[ai][bj][m][n], 0, 0, 0); __builtin_amdgcn_s_setprio(0); } while (0)
; #define PG8_WAIT_V(n) asm volatile("s_waitcnt vmcnt(" #n ")" ::: "memory")
; #define PG8_WAIT_L(n) asm volatile("s_waitcnt lgkmcnt(" #n ")" ::: "memory")
; #define PG8_BAR __builtin_amdgcn_s_barrier()
; #define PG8_SCHED __builtin_amdgcn_sched_barrier(0)
; template <class Epi, class Sched>
; __device__ __forceinline__ void gemm_phase(LAS unsigned char* lds, const Gemm g, const Sched& S, const Epi& E) {
;     ...
;             PG8_LDA(At, 0, 1); PG8_STAGE(PG8_SA(0, 0), a2, voffA);
;             PG8_BAR; PG8_WAIT_L(0); PG8_MMA(1, 0, At, B0); PG8_BAR; PG8_SCHED;
;             PG8_STAGE(PG8_SB(0, 1), b2 + hstep, voffB);
;             PG8_WAIT_V(6); PG8_BAR; PG8_MMA(1, 1, At, B1); PG8_BAR;
;             PG8_LDB(B0, 1, 0); PG8_SCHED; PG8_LDA(At, 1, 0); PG8_STAGE(PG8_SA(0, 1), a2 + hstep, voffA);
;             PG8_WAIT_L(8); PG8_BAR; PG8_WAIT_L(0); PG8_MMA(0, 0, At, B0); PG8_BAR; PG8_SCHED;
	s_waitcnt lgkmcnt(0)
	s_setprio 1
	s_waitcnt lgkmcnt(0)
	v_mfma_f32_16x16x32_bf16 v[116:119], v[202:205], v[168:171], v[116:119]
	v_mfma_f32_16x16x32_bf16 v[108:111], v[210:213], v[168:171], v[108:111]
	v_mfma_f32_16x16x32_bf16 v[100:103], v[202:205], v[176:179], v[100:103]
	v_mfma_f32_16x16x32_bf16 v[92:95], v[210:213], v[176:179], v[92:95]
	v_mfma_f32_16x16x32_bf16 v[84:87], v[202:205], v[184:187], v[84:87]
	v_mfma_f32_16x16x32_bf16 v[76:79], v[210:213], v[184:187], v[76:79]
	v_mfma_f32_16x16x32_bf16 v[68:71], v[202:205], v[192:195], v[68:71]
	v_mfma_f32_16x16x32_bf16 v[64:67], v[210:213], v[192:195], v[64:67]
	v_mfma_f32_16x16x32_bf16 v[116:119], v[206:209], v[172:175], v[116:119]
	v_mfma_f32_16x16x32_bf16 v[108:111], v[214:217], v[172:175], v[108:111]
	v_mfma_f32_16x16x32_bf16 v[100:103], v[206:209], v[180:183], v[100:103]
	v_mfma_f32_16x16x32_bf16 v[92:95], v[214:217], v[180:183], v[92:95]
	v_mfma_f32_16x16x32_bf16 v[84:87], v[206:209], v[188:191], v[84:87]
	v_mfma_f32_16x16x32_bf16 v[76:79], v[214:217], v[188:191], v[76:79]
	v_mfma_f32_16x16x32_bf16 v[68:71], v[206:209], v[196:199], v[68:71]
	v_mfma_f32_16x16x32_bf16 v[64:67], v[214:217], v[196:199], v[64:67]
	s_setprio 0
	s_mov_b32 m0, s17
	v_lshl_add_u64 v[222:223], s[22:23], 0, v[128:129]
	s_barrier
	ds_read_b128 v[168:171], v150 offset:16384
	ds_read_b128 v[172:175], v150 offset:17408
	ds_read_b128 v[176:179], v150 offset:18432
	ds_read_b128 v[180:183], v150 offset:19456
	ds_read_b128 v[184:187], v150 offset:20480
	ds_read_b128 v[188:191], v150 offset:21504
	ds_read_b128 v[192:195], v150 offset:22528
	ds_read_b128 v[196:199], v150 offset:23552
	global_load_lds_dwordx4 v128, s[22:23]
	v_lshl_add_u64 v[224:225], s[22:23], 0, v[132:133]
	s_mov_b32 m0, s29
	s_nop 0
	global_load_lds_dwordx4 v132, s[22:23]
	s_barrier
	s_waitcnt lgkmcnt(0)
	s_setprio 1
	s_waitcnt lgkmcnt(0)
	v_mfma_f32_16x16x32_bf16 v[60:63], v[152:155], v[168:171], v[60:63]
	v_mfma_f32_16x16x32_bf16 v[56:59], v[160:163], v[168:171], v[56:59]
	v_mfma_f32_16x16x32_bf16 v[48:51], v[152:155], v[176:179], v[48:51]
	v_mfma_f32_16x16x32_bf16 v[40:43], v[160:163], v[176:179], v[40:43]
	v_mfma_f32_16x16x32_bf16 v[32:35], v[152:155], v[184:187], v[32:35]
	v_mfma_f32_16x16x32_bf16 v[24:27], v[160:163], v[184:187], v[24:27]
	v_mfma_f32_16x16x32_bf16 v[16:19], v[152:155], v[192:195], v[16:19]
	v_mfma_f32_16x16x32_bf16 v[8:11], v[160:163], v[192:195], v[8:11]
	v_mfma_f32_16x16x32_bf16 v[60:63], v[156:159], v[172:175], v[60:63]
	v_mfma_f32_16x16x32_bf16 v[56:59], v[164:167], v[172:175], v[56:59]
	v_mfma_f32_16x16x32_bf16 v[48:51], v[156:159], v[180:183], v[48:51]
	v_mfma_f32_16x16x32_bf16 v[40:43], v[164:167], v[180:183], v[40:43]
	v_mfma_f32_16x16x32_bf16 v[32:35], v[156:159], v[188:191], v[32:35]
	v_mfma_f32_16x16x32_bf16 v[24:27], v[164:167], v[188:191], v[24:27]
	v_mfma_f32_16x16x32_bf16 v[16:19], v[156:159], v[196:199], v[16:19]
	v_mfma_f32_16x16x32_bf16 v[8:11], v[164:167], v[196:199], v[8:11]
	s_setprio 0
	s_barrier
	s_add_u32 s52, s20, 0x40000
	s_addc_u32 s53, s21, 0
	s_add_i32 s54, s44, s28
	s_mov_b32 m0, s54
	s_nop 0
	global_load_lds_dwordx4 v130, s[52:53]
	s_add_i32 m0, s54, 0x2000
	s_nop 0
	global_load_lds_dwordx4 v134, s[52:53]
	s_add_u32 s22, s22, 0x40000
	s_addc_u32 s23, s23, 0
	s_mov_b32 m0, s30
	s_nop 0
	global_load_lds_dwordx4 v128, s[22:23]
	s_mov_b32 m0, s31
	s_nop 0
	global_load_lds_dwordx4 v132, s[22:23]
	s_waitcnt vmcnt(12)
	s_barrier
	s_setprio 1
	v_mfma_f32_16x16x32_bf16 v[52:55], v[202:205], v[168:171], v[52:55]
	v_mfma_f32_16x16x32_bf16 v[44:47], v[210:213], v[168:171], v[44:47]
	v_mfma_f32_16x16x32_bf16 v[36:39], v[202:205], v[176:179], v[36:39]
	v_mfma_f32_16x16x32_bf16 v[28:31], v[210:213], v[176:179], v[28:31]
	v_mfma_f32_16x16x32_bf16 v[20:23], v[202:205], v[184:187], v[20:23]
	v_mfma_f32_16x16x32_bf16 v[12:15], v[210:213], v[184:187], v[12:15]
	v_mfma_f32_16x16x32_bf16 v[4:7], v[202:205], v[192:195], v[4:7]
	v_mfma_f32_16x16x32_bf16 v[0:3], v[210:213], v[192:195], v[0:3]
	v_mfma_f32_16x16x32_bf16 v[52:55], v[206:209], v[172:175], v[52:55]
	v_mfma_f32_16x16x32_bf16 v[44:47], v[214:217], v[172:175], v[44:47]
	v_mfma_f32_16x16x32_bf16 v[36:39], v[206:209], v[180:183], v[36:39]
	v_mfma_f32_16x16x32_bf16 v[28:31], v[214:217], v[180:183], v[28:31]
	v_mfma_f32_16x16x32_bf16 v[20:23], v[206:209], v[188:191], v[20:23]
	v_mfma_f32_16x16x32_bf16 v[12:15], v[214:217], v[188:191], v[12:15]
	v_mfma_f32_16x16x32_bf16 v[4:7], v[206:209], v[196:199], v[4:7]
	v_mfma_f32_16x16x32_bf16 v[0:3], v[214:217], v[196:199], v[0:3]
	s_setprio 0
	s_add_i32 s52, 0, 0x18000
	v_add_u32_e32 v136, s52, v148
	s_barrier
	ds_read_b128 v[152:155], v136
	ds_read_b128 v[156:159], v136 offset:1024
	ds_read_b128 v[160:163], v136 offset:2048
	ds_read_b128 v[164:167], v136 offset:3072
	ds_read_b128 v[168:171], v150 offset:32768
	ds_read_b128 v[172:175], v150 offset:33792
	ds_read_b128 v[176:179], v150 offset:34816
	ds_read_b128 v[180:183], v150 offset:35840
	ds_read_b128 v[184:187], v150 offset:36864
	ds_read_b128 v[188:191], v150 offset:37888
	ds_read_b128 v[192:195], v150 offset:38912
	ds_read_b128 v[196:199], v150 offset:39936
	s_waitcnt lgkmcnt(8)
	s_waitcnt vmcnt(10)
	s_barrier
; #define PG8_STAGE(bufoff, gbase, voff) do { _Pragma("unroll") for (int _i = 0; _i < 2; ++_i) \
;         __builtin_amdgcn_global_load_lds((const unsigned*)((const char*)(gbase) + (voff)[_i]), (LAS unsigned*)(lds + (bufoff) + ldsw + _i * 8192), 16, 0, 0); } while (0)
; #define PG8_LDA(dst, b, h) do { _Pragma("unroll") for (int m = 0; m < 4; ++m) _Pragma("unroll") for (int k = 0; k < 2; ++k) dst[m][k] = *(const LAS bf16x8*)(lds + PG8_SA(b, h) + aoff + m * 2048 + k * 1024); } while (0)
; #define PG8_LDB(dst, b, h) do { _Pragma("unroll") for (int n = 0; n < 2; ++n) _Pragma("unroll") for (int k = 0; k < 2; ++k) dst[n][k] = *(const LAS bf16x8*)(lds + PG8_SB(b, h) + boff + n * 2048 + k * 1024); } while (0)
; #define PG8_MMA(ai, bj, At, Bt) do { __builtin_amdgcn_s_setprio(1); _Pragma("unroll") for (int m = 0; m < 4; ++m) _Pragma("unroll") for (int n = 0; n < 2; ++n) _Pragma("unroll") for (int k = 0; k < 2; ++k) \
;         acc[ai][bj][m][n] = __builtin_amdgcn_mfma_f32_16x16x32_bf16(Bt[n][k], At[m][k], acc[ai][bj][m][n], 0, 0, 0); __builtin_amdgcn_s_setprio(0); } while (0)
; #define PG8_WAIT_V(n) asm volatile("s_waitcnt vmcnt(" #n ")" ::: "memory")
; #define PG8_WAIT_L(n) asm volatile("s_waitcnt lgkmcnt(" #n ")" ::: "memory")
; #define PG8_BAR __builtin_amdgcn_s_barrier()
; #define PG8_SCHED __builtin_amdgcn_sched_barrier(0)
; template <class Epi, class Sched>
; __device__ __forceinline__ void gemm_phase(LAS unsigned char* lds, const Gemm g, const Sched& S, const Epi& E) {
;     ...
;             PG8_WAIT_L(8); PG8_BAR; PG8_WAIT_L(0); PG8_MMA(0, 0, At, B0); PG8_BAR; PG8_SCHED;
;             PG8_LDB(B1, 1, 1); PG8_STAGE(PG8_SB(1, 0), b3, voffB);
;             PG8_BAR; PG8_WAIT_L(0); PG8_MMA(0, 1, At, B1); PG8_BAR;
;             PG8_LDA(At, 1, 1); PG8_STAGE(PG8_SA(1, 0), a3, voffA);
;             PG8_BAR; PG8_WAIT_L(0); PG8_MMA(1, 0, At, B0); PG8_BAR; PG8_SCHED;
;             PG8_STAGE(PG8_SB(1, 1), b3 + hstep, voffB);
;             PG8_WAIT_V(6); PG8_BAR; PG8_MMA(1, 1, At, B1); PG8_BAR;
	s_waitcnt lgkmcnt(0)
	s_setprio 1
	s_waitcnt lgkmcnt(0)
	v_mfma_f32_16x16x32_bf16 v[124:127], v[152:155], v[168:171], v[124:127]
	v_mfma_f32_16x16x32_bf16 v[120:123], v[160:163], v[168:171], v[120:123]
	v_mfma_f32_16x16x32_bf16 v[112:115], v[152:155], v[176:179], v[112:115]
	v_mfma_f32_16x16x32_bf16 v[104:107], v[160:163], v[176:179], v[104:107]
	v_mfma_f32_16x16x32_bf16 v[96:99], v[152:155], v[184:187], v[96:99]
	v_mfma_f32_16x16x32_bf16 v[88:91], v[160:163], v[184:187], v[88:91]
	v_mfma_f32_16x16x32_bf16 v[80:83], v[152:155], v[192:195], v[80:83]
	v_mfma_f32_16x16x32_bf16 v[72:75], v[160:163], v[192:195], v[72:75]
	v_mfma_f32_16x16x32_bf16 v[124:127], v[156:159], v[172:175], v[124:127]
	v_mfma_f32_16x16x32_bf16 v[120:123], v[164:167], v[172:175], v[120:123]
	v_mfma_f32_16x16x32_bf16 v[112:115], v[156:159], v[180:183], v[112:115]
	v_mfma_f32_16x16x32_bf16 v[104:107], v[164:167], v[180:183], v[104:107]
	v_mfma_f32_16x16x32_bf16 v[96:99], v[156:159], v[188:191], v[96:99]
	v_mfma_f32_16x16x32_bf16 v[88:91], v[164:167], v[188:191], v[88:91]
	v_mfma_f32_16x16x32_bf16 v[80:83], v[156:159], v[196:199], v[80:83]
	v_mfma_f32_16x16x32_bf16 v[72:75], v[164:167], v[196:199], v[72:75]
	s_setprio 0
	s_barrier
	s_add_i32 s22, 0, 0x1c000
	s_add_i32 s23, s52, s28
	v_add_u32_e32 v136, s22, v148
	s_add_u32 s0, s20, 0x80
	s_addc_u32 s1, s21, 0
	s_mov_b32 m0, s23
	ds_read_b128 v[202:205], v136
	ds_read_b128 v[206:209], v136 offset:1024
	ds_read_b128 v[210:213], v136 offset:2048
	ds_read_b128 v[214:217], v136 offset:3072
	global_load_lds_dwordx4 v130, s[0:1]
	s_add_i32 m0, s23, 0x2000
	s_nop 0
	global_load_lds_dwordx4 v134, s[0:1]
	s_waitcnt vmcnt(10)
	s_barrier
	s_waitcnt lgkmcnt(0)
	s_setprio 1
	s_waitcnt lgkmcnt(0)
	v_mfma_f32_16x16x32_bf16 v[116:119], v[202:205], v[168:171], v[116:119]
	v_mfma_f32_16x16x32_bf16 v[108:111], v[210:213], v[168:171], v[108:111]
	v_mfma_f32_16x16x32_bf16 v[100:103], v[202:205], v[176:179], v[100:103]
	v_mfma_f32_16x16x32_bf16 v[92:95], v[210:213], v[176:179], v[92:95]
	v_mfma_f32_16x16x32_bf16 v[84:87], v[202:205], v[184:187], v[84:87]
	v_mfma_f32_16x16x32_bf16 v[76:79], v[210:213], v[184:187], v[76:79]
	v_mfma_f32_16x16x32_bf16 v[68:71], v[202:205], v[192:195], v[68:71]
	v_mfma_f32_16x16x32_bf16 v[64:67], v[210:213], v[192:195], v[64:67]
	v_mfma_f32_16x16x32_bf16 v[116:119], v[206:209], v[172:175], v[116:119]
	v_mfma_f32_16x16x32_bf16 v[108:111], v[214:217], v[172:175], v[108:111]
	v_mfma_f32_16x16x32_bf16 v[100:103], v[206:209], v[180:183], v[100:103]
	v_mfma_f32_16x16x32_bf16 v[92:95], v[214:217], v[180:183], v[92:95]
	v_mfma_f32_16x16x32_bf16 v[84:87], v[206:209], v[188:191], v[84:87]
	v_mfma_f32_16x16x32_bf16 v[76:79], v[214:217], v[188:191], v[76:79]
	v_mfma_f32_16x16x32_bf16 v[68:71], v[206:209], v[196:199], v[68:71]
	v_mfma_f32_16x16x32_bf16 v[64:67], v[214:217], v[196:199], v[64:67]
	s_setprio 0
	s_mov_b32 m0, s36
	s_mov_b64 s[0:1], 0x80
	v_lshl_add_u64 v[218:219], v[222:223], 0, s[0:1]
	s_barrier
	ds_read_b128 v[168:171], v150 offset:49152
	ds_read_b128 v[172:175], v150 offset:50176
	ds_read_b128 v[176:179], v150 offset:51200
	ds_read_b128 v[180:183], v150 offset:52224
	ds_read_b128 v[184:187], v150 offset:53248
	ds_read_b128 v[188:191], v150 offset:54272
	ds_read_b128 v[192:195], v150 offset:55296
	ds_read_b128 v[196:199], v150 offset:56320
	global_load_lds_dwordx4 v[218:219], off
	v_lshl_add_u64 v[218:219], v[224:225], 0, s[0:1]
	s_mov_b32 m0, s37
	s_nop 0
	global_load_lds_dwordx4 v[218:219], off
	s_barrier
	s_waitcnt lgkmcnt(0)
	s_setprio 1
	s_waitcnt lgkmcnt(0)
	v_mfma_f32_16x16x32_bf16 v[60:63], v[152:155], v[168:171], v[60:63]
	v_mfma_f32_16x16x32_bf16 v[56:59], v[160:163], v[168:171], v[56:59]
	v_mfma_f32_16x16x32_bf16 v[48:51], v[152:155], v[176:179], v[48:51]
	v_mfma_f32_16x16x32_bf16 v[40:43], v[160:163], v[176:179], v[40:43]
	v_mfma_f32_16x16x32_bf16 v[32:35], v[152:155], v[184:187], v[32:35]
	v_mfma_f32_16x16x32_bf16 v[24:27], v[160:163], v[184:187], v[24:27]
	v_mfma_f32_16x16x32_bf16 v[16:19], v[152:155], v[192:195], v[16:19]
	v_mfma_f32_16x16x32_bf16 v[8:11], v[160:163], v[192:195], v[8:11]
	v_mfma_f32_16x16x32_bf16 v[60:63], v[156:159], v[172:175], v[60:63]
	v_mfma_f32_16x16x32_bf16 v[56:59], v[164:167], v[172:175], v[56:59]
	v_mfma_f32_16x16x32_bf16 v[48:51], v[156:159], v[180:183], v[48:51]
	v_mfma_f32_16x16x32_bf16 v[40:43], v[164:167], v[180:183], v[40:43]
	v_mfma_f32_16x16x32_bf16 v[32:35], v[156:159], v[188:191], v[32:35]
	v_mfma_f32_16x16x32_bf16 v[24:27], v[164:167], v[188:191], v[24:27]
	v_mfma_f32_16x16x32_bf16 v[16:19], v[156:159], v[196:199], v[16:19]
	v_mfma_f32_16x16x32_bf16 v[8:11], v[164:167], v[196:199], v[8:11]
	s_setprio 0
	s_barrier
	s_add_u32 s20, s20, 0x40080
	s_addc_u32 s21, s21, 0
	s_add_i32 s22, s22, s28
	s_mov_b32 m0, s22
	s_nop 0
	global_load_lds_dwordx4 v130, s[20:21]
	s_add_i32 m0, s22, 0x2000
	s_nop 0
	global_load_lds_dwordx4 v134, s[20:21]
	s_waitcnt vmcnt(10)
	s_barrier
	s_setprio 1
	v_mfma_f32_16x16x32_bf16 v[52:55], v[202:205], v[168:171], v[52:55]
	v_mfma_f32_16x16x32_bf16 v[44:47], v[210:213], v[168:171], v[44:47]
	v_mfma_f32_16x16x32_bf16 v[36:39], v[202:205], v[176:179], v[36:39]
	v_mfma_f32_16x16x32_bf16 v[28:31], v[210:213], v[176:179], v[28:31]
	v_mfma_f32_16x16x32_bf16 v[20:23], v[202:205], v[184:187], v[20:23]
	v_mfma_f32_16x16x32_bf16 v[12:15], v[210:213], v[184:187], v[12:15]
	v_mfma_f32_16x16x32_bf16 v[4:7], v[202:205], v[192:195], v[4:7]
	v_mfma_f32_16x16x32_bf16 v[0:3], v[210:213], v[192:195], v[0:3]
	v_mfma_f32_16x16x32_bf16 v[52:55], v[206:209], v[172:175], v[52:55]
	v_mfma_f32_16x16x32_bf16 v[44:47], v[214:217], v[172:175], v[44:47]
	v_mfma_f32_16x16x32_bf16 v[36:39], v[206:209], v[180:183], v[36:39]
	v_mfma_f32_16x16x32_bf16 v[28:31], v[214:217], v[180:183], v[28:31]
	v_mfma_f32_16x16x32_bf16 v[20:23], v[206:209], v[188:191], v[20:23]
	v_mfma_f32_16x16x32_bf16 v[12:15], v[214:217], v[188:191], v[12:15]
	v_mfma_f32_16x16x32_bf16 v[4:7], v[206:209], v[196:199], v[4:7]
	v_mfma_f32_16x16x32_bf16 v[0:3], v[214:217], v[196:199], v[0:3]
	s_setprio 0
	s_add_i32 s51, s51, 2
	s_add_u32 s18, s18, 0x100
	s_addc_u32 s19, s19, 0
	s_add_u32 s48, s48, 0x100
	s_addc_u32 s49, s49, 0
	s_cmp_gt_u32 s51, 13
	s_barrier
; __device__ __forceinline__ unsigned cvt_pk_bf16(float lo, float hi) { unsigned r; asm volatile("v_cvt_pk_bf16_f32 %0, %1, %2" : "=v"(r) : "v"(lo), "v"(hi)); return r; }
;     __device__ __forceinline__ void operator()(const AccT& acc, const Unit& u, int wr, int wc, int fr, int fq) const {
;     ...
;         const int rbase = u.pm * 256 + wr * 64 + fr;
;         const int tb = u.pn * 256 + wc * 32 + 8 * fq;
; #pragma unroll
;         for (int ai = 0; ai < 2; ++ai)
; #pragma unroll
;             for (int m = 0; m < 4; ++m) {
;                 const int gm = rbase + ai * 128 + m * 16;
; #pragma unroll
;                 for (int bj = 0; bj < 2; ++bj) {
;                     const int t0 = tb + bj * 128;
;                     const f32x4 v0 = acc[ai][bj][m][0], v1 = acc[ai][bj][m][1];
;                     u32x4 w; w.x = cvt_pk_bf16(v0[0], v0[1]); w.y = cvt_pk_bf16(v0[2], v0[3]); w.z = cvt_pk_bf16(v1[0], v1[1]); w.w = cvt_pk_bf16(v1[2], v1[3]);
;                     *(u32x4*)(YT + ((size_t)((t0 >> 10) * 512 + gm)) * 2048 + part * 1024 + (t0 & 1023)) = w;
;                 }
;             }
	s_cbranch_scc0 .LBB0_673
	v_mov_b32_e32 v136, v147
	v_mov_b32_e32 v152, v146
	s_lshl_b32 s7, s16, 8
	s_add_i32 s7, s7, s34
	v_add_u32_e32 v152, s7, v152
	s_lshl_b32 s7, s45, 8
	s_or_b32 s7, s7, s35
	v_lshl_add_u32 v153, v136, 3, s7
	v_cvt_pk_bf16_f32 v124, v124, v125
	v_cvt_pk_bf16_f32 v125, v126, v127
	v_cvt_pk_bf16_f32 v126, v120, v121
	v_ashrrev_i32_e32 v120, 1, v153
	v_cvt_pk_bf16_f32 v127, v122, v123
	v_and_b32_e32 v122, 0xfffffe00, v120
	v_add_u32_e32 v120, v122, v152
	v_ashrrev_i32_e32 v121, 31, v120
	v_lshlrev_b64 v[120:121], 12, v[120:121]
	v_and_b32_e32 v123, 0x3f8, v153
	v_lshl_add_u64 v[120:121], s[4:5], 0, v[120:121]
	v_lshlrev_b32_e32 v136, 1, v123
	v_lshl_add_u64 v[120:121], v[120:121], 0, v[136:137]
	global_store_dwordx4 v[120:121], v[124:127], off
	v_add_u32_e32 v120, 0x80, v153
	v_cvt_pk_bf16_f32 v116, v116, v117
	v_cvt_pk_bf16_f32 v117, v118, v119
	v_cvt_pk_bf16_f32 v118, v108, v109
	v_ashrrev_i32_e32 v108, 1, v120
	v_and_b32_e32 v121, 0xfffffe00, v108
	v_add_u32_e32 v108, v121, v152
	v_ashrrev_i32_e32 v109, 31, v108
	v_lshlrev_b64 v[108:109], 12, v[108:109]
	v_cvt_pk_bf16_f32 v119, v110, v111
	v_lshl_add_u64 v[110:111], s[4:5], 0, v[108:109]
	v_and_b32_e32 v108, 0x3f8, v120
	v_lshlrev_b32_e32 v108, 1, v108
	v_mov_b32_e32 v109, v137
	v_lshl_add_u64 v[110:111], v[110:111], 0, v[108:109]
	global_store_dwordx4 v[110:111], v[116:119], off
	v_cvt_pk_bf16_f32 v110, v112, v113
	v_cvt_pk_bf16_f32 v111, v114, v115
	v_cvt_pk_bf16_f32 v112, v104, v105
	v_cvt_pk_bf16_f32 v113, v106, v107
	s_and_b64 vcc, exec, s[2:3]
	s_nop 0
	v_add_u32_e32 v116, 16, v152
	v_add_u32_e32 v104, v122, v116
	v_ashrrev_i32_e32 v105, 31, v104
	v_lshlrev_b64 v[104:105], 12, v[104:105]
	v_lshl_add_u64 v[104:105], s[4:5], 0, v[104:105]
	v_lshl_add_u64 v[104:105], v[104:105], 0, v[136:137]
	global_store_dwordx4 v[104:105], v[110:113], off
	v_cvt_pk_bf16_f32 v100, v100, v101
	v_cvt_pk_bf16_f32 v101, v102, v103
	v_cvt_pk_bf16_f32 v102, v92, v93
	v_add_u32_e32 v92, v121, v116
	v_ashrrev_i32_e32 v93, 31, v92
	v_lshlrev_b64 v[92:93], 12, v[92:93]
	v_lshl_add_u64 v[92:93], s[4:5], 0, v[92:93]
	v_lshl_add_u64 v[92:93], v[92:93], 0, v[108:109]
	v_cvt_pk_bf16_f32 v103, v94, v95
	global_store_dwordx4 v[92:93], v[100:103], off
	v_cvt_pk_bf16_f32 v92, v96, v97
	v_cvt_pk_bf16_f32 v93, v98, v99
	v_cvt_pk_bf16_f32 v94, v88, v89
	v_cvt_pk_bf16_f32 v95, v90, v91
	s_mov_b32 s45, s6
	s_nop 0
	v_add_u32_e32 v100, 32, v152
	v_add_u32_e32 v88, v122, v100
	v_ashrrev_i32_e32 v89, 31, v88
	v_lshlrev_b64 v[88:89], 12, v[88:89]
	v_lshl_add_u64 v[88:89], s[4:5], 0, v[88:89]
	v_lshl_add_u64 v[88:89], v[88:89], 0, v[136:137]
	global_store_dwordx4 v[88:89], v[92:95], off
	v_cvt_pk_bf16_f32 v84, v84, v85
	v_cvt_pk_bf16_f32 v85, v86, v87
	v_cvt_pk_bf16_f32 v86, v76, v77
	v_add_u32_e32 v76, v121, v100
	v_ashrrev_i32_e32 v77, 31, v76
	v_lshlrev_b64 v[76:77], 12, v[76:77]
	v_lshl_add_u64 v[76:77], s[4:5], 0, v[76:77]
	v_lshl_add_u64 v[76:77], v[76:77], 0, v[108:109]
	v_cvt_pk_bf16_f32 v87, v78, v79
	global_store_dwordx4 v[76:77], v[84:87], off
	v_cvt_pk_bf16_f32 v76, v80, v81
	v_cvt_pk_bf16_f32 v77, v82, v83
	v_cvt_pk_bf16_f32 v78, v72, v73
	v_cvt_pk_bf16_f32 v79, v74, v75
	s_mov_b32 s16, s8
	s_nop 0
	v_add_u32_e32 v84, 48, v152
	v_add_u32_e32 v72, v122, v84
	v_ashrrev_i32_e32 v73, 31, v72
	v_lshlrev_b64 v[72:73], 12, v[72:73]
	v_lshl_add_u64 v[72:73], s[4:5], 0, v[72:73]
	v_lshl_add_u64 v[72:73], v[72:73], 0, v[136:137]
	global_store_dwordx4 v[72:73], v[76:79], off
	v_cvt_pk_bf16_f32 v68, v68, v69
	v_cvt_pk_bf16_f32 v69, v70, v71
	v_cvt_pk_bf16_f32 v70, v64, v65
	v_add_u32_e32 v64, v121, v84
	v_ashrrev_i32_e32 v65, 31, v64
	v_lshlrev_b64 v[64:65], 12, v[64:65]
	v_lshl_add_u64 v[64:65], s[4:5], 0, v[64:65]
	v_lshl_add_u64 v[64:65], v[64:65], 0, v[108:109]
	v_cvt_pk_bf16_f32 v71, v66, v67
	global_store_dwordx4 v[64:65], v[68:71], off
	v_add_u32_e32 v64, 0x80, v152
	v_cvt_pk_bf16_f32 v60, v60, v61
	v_cvt_pk_bf16_f32 v61, v62, v63
	v_cvt_pk_bf16_f32 v62, v56, v57
	v_add_u32_e32 v56, v122, v64
	v_ashrrev_i32_e32 v57, 31, v56
	v_lshlrev_b64 v[56:57], 12, v[56:57]
	v_lshl_add_u64 v[56:57], s[4:5], 0, v[56:57]
	v_lshl_add_u64 v[56:57], v[56:57], 0, v[136:137]
	v_cvt_pk_bf16_f32 v63, v58, v59
	global_store_dwordx4 v[56:57], v[60:63], off
	v_cvt_pk_bf16_f32 v52, v52, v53
	v_cvt_pk_bf16_f32 v53, v54, v55
	v_cvt_pk_bf16_f32 v54, v44, v45
	v_add_u32_e32 v44, v121, v64
	v_ashrrev_i32_e32 v45, 31, v44
	v_lshlrev_b64 v[44:45], 12, v[44:45]
	v_lshl_add_u64 v[44:45], s[4:5], 0, v[44:45]
	v_lshl_add_u64 v[44:45], v[44:45], 0, v[108:109]
	v_cvt_pk_bf16_f32 v55, v46, v47
	global_store_dwordx4 v[44:45], v[52:55], off
	v_cvt_pk_bf16_f32 v44, v48, v49
	v_cvt_pk_bf16_f32 v45, v50, v51
	v_cvt_pk_bf16_f32 v46, v40, v41
	v_cvt_pk_bf16_f32 v47, v42, v43
	s_mov_b64 s[20:21], s[14:15]
	s_nop 0
	v_add_u32_e32 v52, 0x90, v152
	v_add_u32_e32 v40, v122, v52
	v_ashrrev_i32_e32 v41, 31, v40
	v_lshlrev_b64 v[40:41], 12, v[40:41]
	v_lshl_add_u64 v[40:41], s[4:5], 0, v[40:41]
	v_lshl_add_u64 v[40:41], v[40:41], 0, v[136:137]
	global_store_dwordx4 v[40:41], v[44:47], off
	v_cvt_pk_bf16_f32 v36, v36, v37
	v_cvt_pk_bf16_f32 v37, v38, v39
	v_cvt_pk_bf16_f32 v38, v28, v29
	v_add_u32_e32 v28, v121, v52
	v_ashrrev_i32_e32 v29, 31, v28
	v_lshlrev_b64 v[28:29], 12, v[28:29]
	v_lshl_add_u64 v[28:29], s[4:5], 0, v[28:29]
	v_lshl_add_u64 v[28:29], v[28:29], 0, v[108:109]
	v_cvt_pk_bf16_f32 v39, v30, v31
	global_store_dwordx4 v[28:29], v[36:39], off
	v_cvt_pk_bf16_f32 v28, v32, v33
	v_cvt_pk_bf16_f32 v29, v34, v35
	v_cvt_pk_bf16_f32 v30, v24, v25
	v_cvt_pk_bf16_f32 v31, v26, v27
	s_mov_b64 s[18:19], s[12:13]
	s_nop 0
	v_add_u32_e32 v36, 0xa0, v152
	v_add_u32_e32 v24, v122, v36
	v_ashrrev_i32_e32 v25, 31, v24
	v_lshlrev_b64 v[24:25], 12, v[24:25]
	v_lshl_add_u64 v[24:25], s[4:5], 0, v[24:25]
	v_lshl_add_u64 v[24:25], v[24:25], 0, v[136:137]
	global_store_dwordx4 v[24:25], v[28:31], off
	v_cvt_pk_bf16_f32 v20, v20, v21
	v_cvt_pk_bf16_f32 v21, v22, v23
	v_cvt_pk_bf16_f32 v22, v12, v13
	v_add_u32_e32 v12, v121, v36
	v_ashrrev_i32_e32 v13, 31, v12
	v_lshlrev_b64 v[12:13], 12, v[12:13]
	v_lshl_add_u64 v[12:13], s[4:5], 0, v[12:13]
	v_lshl_add_u64 v[12:13], v[12:13], 0, v[108:109]
	v_cvt_pk_bf16_f32 v23, v14, v15
	global_store_dwordx4 v[12:13], v[20:23], off
	v_cvt_pk_bf16_f32 v12, v16, v17
	v_cvt_pk_bf16_f32 v13, v18, v19
	v_cvt_pk_bf16_f32 v14, v8, v9
	v_cvt_pk_bf16_f32 v15, v10, v11
	s_nop 1
	v_add_u32_e32 v20, 0xb0, v152
	v_add_u32_e32 v8, v122, v20
	v_ashrrev_i32_e32 v9, 31, v8
	v_lshlrev_b64 v[8:9], 12, v[8:9]
	v_lshl_add_u64 v[8:9], s[4:5], 0, v[8:9]
	v_lshl_add_u64 v[8:9], v[8:9], 0, v[136:137]
	global_store_dwordx4 v[8:9], v[12:15], off
	v_cvt_pk_bf16_f32 v4, v4, v5
	v_cvt_pk_bf16_f32 v5, v6, v7
	v_cvt_pk_bf16_f32 v6, v0, v1
	v_add_u32_e32 v0, v121, v20
	v_ashrrev_i32_e32 v1, 31, v0
	v_lshlrev_b64 v[0:1], 12, v[0:1]
	v_lshl_add_u64 v[0:1], s[4:5], 0, v[0:1]
	v_lshl_add_u64 v[0:1], v[0:1], 0, v[108:109]
	v_cvt_pk_bf16_f32 v7, v2, v3
	global_store_dwordx4 v[0:1], v[4:7], off
	s_cbranch_vccz .LBB0_666
; #define PG8_WAIT_V(n) asm volatile("s_waitcnt vmcnt(" #n ")" ::: "memory")
; #define PG8_BAR __builtin_amdgcn_s_barrier()
; template <class Epi, class Sched>
; __device__ __forceinline__ void gemm_phase(LAS unsigned char* lds, const Gemm g, const Sched& S, const Epi& E) {
;     ...
;     PG8_WAIT_V(0);
;     if (wr == 0) PG8_BAR;
;     PG8_BAR;
	s_waitcnt vmcnt(0)
	s_cmpk_gt_u32 s24, 0xff
	s_cbranch_scc1 .LBB0_677
	s_barrier

; #define PG8_STAGE(bufoff, gbase, voff) do { _Pragma("unroll") for (int _i = 0; _i < 2; ++_i) \
;         __builtin_amdgcn_global_load_lds((const unsigned*)((const char*)(gbase) + (voff)[_i]), (LAS unsigned*)(lds + (bufoff) + ldsw + _i * 8192), 16, 0, 0); } while (0)
; #define PG8_LDA(dst, b, h) do { _Pragma("unroll") for (int m = 0; m < 4; ++m) _Pragma("unroll") for (int k = 0; k < 2; ++k) dst[m][k] = *(const LAS bf16x8*)(lds + PG8_SA(b, h) + aoff + m * 2048 + k * 1024); } while (0)
; #define PG8_LDB(dst, b, h) do { _Pragma("unroll") for (int n = 0; n < 2; ++n) _Pragma("unroll") for (int k = 0; k < 2; ++k) dst[n][k] = *(const LAS bf16x8*)(lds + PG8_SB(b, h) + boff + n * 2048 + k * 1024); } while (0)
; #define PG8_MMA(ai, bj, At, Bt) do { __builtin_amdgcn_s_setprio(1); _Pragma("unroll") for (int m = 0; m < 4; ++m) _Pragma("unroll") for (int n = 0; n < 2; ++n) _Pragma("unroll") for (int k = 0; k < 2; ++k) \
;         acc[ai][bj][m][n] = __builtin_amdgcn_mfma_f32_16x16x32_bf16(Bt[n][k], At[m][k], acc[ai][bj][m][n], 0, 0, 0); __builtin_amdgcn_s_setprio(0); } while (0)
; #define PG8_WAIT_L(n) asm volatile("s_waitcnt lgkmcnt(" #n ")" ::: "memory")
; template <class Epi, class Sched>
; __device__ __forceinline__ void gemm_phase(LAS unsigned char* lds, const Gemm g, const Sched& S, const Epi& E) {
;     ...
;         const bool has_next = S.next(ui + 1, nxt);
;         const char* nA = has_next ? (const char*)g.A + (size_t)nxt.pm * tstep : cA; const char* nB = has_next ? (const char*)g.Bt + (size_t)nxt.pn * tstep : cB;
;         for (int t = 0; t < nt; t += 2) {
;             const bool last = (t == nt - 2);
;             const char* a1 = cA + (size_t)(t + 1) * kstep;
;             const char* a2 = last ? nA : cA + (size_t)(t + 2) * kstep; const char* b2 = last ? nB : cB + (size_t)(t + 2) * kstep;
;             const char* a3 = a2 + kstep; const char* b3 = b2 + kstep;
;             PG8_LDB(B0, 0, 0); PG8_SCHED; PG8_LDA(At, 0, 0); PG8_STAGE(PG8_SA(1, 1), a1 + hstep, voffA);
;             PG8_WAIT_L(8); PG8_BAR; PG8_WAIT_L(0); PG8_MMA(0, 0, At, B0); PG8_BAR; PG8_SCHED;
;             PG8_LDB(B1, 0, 1); PG8_STAGE(PG8_SB(0, 0), b2, voffB);
;             PG8_BAR; PG8_WAIT_L(0); PG8_MMA(0, 1, At, B1); PG8_BAR;
;             PG8_LDA(At, 0, 1); PG8_STAGE(PG8_SA(0, 0), a2, voffA);
;             PG8_BAR; PG8_WAIT_L(0); PG8_MMA(1, 0, At, B0); PG8_BAR; PG8_SCHED;
.LBB0_692:
	s_ashr_i32 s19, s18, 31
	v_cmp_lt_i64_e64 s[24:25], s[20:21], 32
	s_lshl_b64 s[20:21], s[18:19], 19
	s_add_u32 s20, s40, s20
	s_addc_u32 s21, s41, s21
	s_and_b64 s[22:23], s[24:25], exec
	s_cselect_b32 s19, s21, s3
	s_cselect_b32 s57, s20, s2
	s_ashr_i32 s17, s16, 31
	s_lshl_b64 s[22:23], s[16:17], 19
	s_add_u32 s22, s28, s22
	s_addc_u32 s23, s29, s23
	s_and_b64 s[24:25], s[24:25], exec
	s_cselect_b32 s17, s23, s5
	s_cselect_b32 s58, s22, s4
	s_add_u32 s2, s2, 0x40080
	s_addc_u32 s3, s3, 0
	s_add_u32 s59, s4, 0x100
	s_addc_u32 s60, s5, 0
	s_mov_b32 s61, -2
	s_waitcnt lgkmcnt(0)
	ds_read_b128 v[140:143], v149
	ds_read_b128 v[154:157], v149 offset:1024
	ds_read_b128 v[158:161], v149 offset:2048
	ds_read_b128 v[162:165], v149 offset:3072
	s_add_u32 s4, s2, 0xfffc0080
	s_addc_u32 s5, s3, -1
	s_cmp_eq_u32 s61, 12
	s_cselect_b32 s25, s19, s5
	s_cselect_b32 s24, s57, s4
	s_cselect_b32 s5, s17, s60
	s_cselect_b32 s4, s58, s59
	s_add_i32 m0, s33, 0xc000
	ds_read_b128 v[166:169], v150
	ds_read_b128 v[170:173], v150 offset:1024
	ds_read_b128 v[174:177], v150 offset:2048
	ds_read_b128 v[178:181], v150 offset:3072
	ds_read_b128 v[182:185], v150 offset:4096
	ds_read_b128 v[186:189], v150 offset:5120
	ds_read_b128 v[190:193], v150 offset:6144
	ds_read_b128 v[194:197], v150 offset:7168
	global_load_lds_dwordx4 v136, s[2:3]
	s_add_i32 m0, s33, 0xe000
	s_nop 0
	global_load_lds_dwordx4 v138, s[2:3]
	s_waitcnt lgkmcnt(8)
	s_waitcnt vmcnt(10)
	s_barrier
	s_waitcnt lgkmcnt(0)
	s_setprio 1
	s_waitcnt lgkmcnt(0)
	v_mfma_f32_16x16x32_bf16 v[124:127], v[140:143], v[166:169], 0
	v_mfma_f32_16x16x32_bf16 v[120:123], v[158:161], v[166:169], 0
	v_mfma_f32_16x16x32_bf16 v[108:111], v[140:143], v[174:177], 0
	v_mfma_f32_16x16x32_bf16 v[104:107], v[158:161], v[174:177], 0
	v_mfma_f32_16x16x32_bf16 v[92:95], v[140:143], v[182:185], 0
	v_mfma_f32_16x16x32_bf16 v[88:91], v[158:161], v[182:185], 0
	v_mfma_f32_16x16x32_bf16 v[76:79], v[140:143], v[190:193], 0
	v_mfma_f32_16x16x32_bf16 v[72:75], v[158:161], v[190:193], 0
	v_mfma_f32_16x16x32_bf16 v[124:127], v[154:157], v[170:173], v[124:127]
	v_mfma_f32_16x16x32_bf16 v[120:123], v[162:165], v[170:173], v[120:123]
	v_mfma_f32_16x16x32_bf16 v[108:111], v[154:157], v[178:181], v[108:111]
	v_mfma_f32_16x16x32_bf16 v[104:107], v[162:165], v[178:181], v[104:107]
	v_mfma_f32_16x16x32_bf16 v[92:95], v[154:157], v[186:189], v[92:95]
	v_mfma_f32_16x16x32_bf16 v[88:91], v[162:165], v[186:189], v[88:91]
	v_mfma_f32_16x16x32_bf16 v[76:79], v[154:157], v[194:197], v[76:79]
	v_mfma_f32_16x16x32_bf16 v[72:75], v[162:165], v[194:197], v[72:75]
	s_setprio 0
	s_barrier
	s_add_i32 s62, s47, s31
	s_mov_b32 m0, s62
	ds_read_b128 v[202:205], v151
	ds_read_b128 v[206:209], v151 offset:1024
	ds_read_b128 v[210:213], v151 offset:2048
	ds_read_b128 v[214:217], v151 offset:3072
	global_load_lds_dwordx4 v130, s[4:5]
	s_add_i32 m0, s62, 0x2000
	s_nop 0
	global_load_lds_dwordx4 v134, s[4:5]
	s_waitcnt vmcnt(10)
	s_barrier
	s_waitcnt lgkmcnt(0)
	s_setprio 1
	s_waitcnt lgkmcnt(0)
	v_mfma_f32_16x16x32_bf16 v[116:119], v[202:205], v[166:169], 0
	v_mfma_f32_16x16x32_bf16 v[112:115], v[210:213], v[166:169], 0
	v_mfma_f32_16x16x32_bf16 v[100:103], v[202:205], v[174:177], 0
	v_mfma_f32_16x16x32_bf16 v[96:99], v[210:213], v[174:177], 0
	v_mfma_f32_16x16x32_bf16 v[84:87], v[202:205], v[182:185], 0
	v_mfma_f32_16x16x32_bf16 v[80:83], v[210:213], v[182:185], 0
	v_mfma_f32_16x16x32_bf16 v[68:71], v[202:205], v[190:193], 0
	v_mfma_f32_16x16x32_bf16 v[64:67], v[210:213], v[190:193], 0
	v_mfma_f32_16x16x32_bf16 v[116:119], v[206:209], v[170:173], v[116:119]
	v_mfma_f32_16x16x32_bf16 v[112:115], v[214:217], v[170:173], v[112:115]
	v_mfma_f32_16x16x32_bf16 v[100:103], v[206:209], v[178:181], v[100:103]
	v_mfma_f32_16x16x32_bf16 v[96:99], v[214:217], v[178:181], v[96:99]
	v_mfma_f32_16x16x32_bf16 v[84:87], v[206:209], v[186:189], v[84:87]
	v_mfma_f32_16x16x32_bf16 v[80:83], v[214:217], v[186:189], v[80:83]
	v_mfma_f32_16x16x32_bf16 v[68:71], v[206:209], v[194:197], v[68:71]
	v_mfma_f32_16x16x32_bf16 v[64:67], v[214:217], v[194:197], v[64:67]
	s_setprio 0
	s_mov_b32 m0, s33
	v_lshl_add_u64 v[218:219], s[24:25], 0, v[128:129]
	s_barrier
	ds_read_b128 v[166:169], v150 offset:16384
	ds_read_b128 v[170:173], v150 offset:17408
	ds_read_b128 v[174:177], v150 offset:18432
	ds_read_b128 v[178:181], v150 offset:19456
	ds_read_b128 v[182:185], v150 offset:20480
	ds_read_b128 v[186:189], v150 offset:21504
	ds_read_b128 v[190:193], v150 offset:22528
	ds_read_b128 v[194:197], v150 offset:23552
	global_load_lds_dwordx4 v128, s[24:25]
	v_lshl_add_u64 v[220:221], s[24:25], 0, v[132:133]
	s_mov_b32 m0, s34
	s_nop 0
	global_load_lds_dwordx4 v132, s[24:25]
	s_barrier
	s_waitcnt lgkmcnt(0)
	s_setprio 1
	s_waitcnt lgkmcnt(0)
	v_mfma_f32_16x16x32_bf16 v[60:63], v[140:143], v[166:169], 0
	v_mfma_f32_16x16x32_bf16 v[56:59], v[158:161], v[166:169], 0
	v_mfma_f32_16x16x32_bf16 v[44:47], v[140:143], v[174:177], 0
	v_mfma_f32_16x16x32_bf16 v[40:43], v[158:161], v[174:177], 0
	v_mfma_f32_16x16x32_bf16 v[28:31], v[140:143], v[182:185], 0
	v_mfma_f32_16x16x32_bf16 v[24:27], v[158:161], v[182:185], 0
	v_mfma_f32_16x16x32_bf16 v[12:15], v[140:143], v[190:193], 0
	v_mfma_f32_16x16x32_bf16 v[8:11], v[158:161], v[190:193], 0
	v_mfma_f32_16x16x32_bf16 v[60:63], v[154:157], v[170:173], v[60:63]
	v_mfma_f32_16x16x32_bf16 v[56:59], v[162:165], v[170:173], v[56:59]
	v_mfma_f32_16x16x32_bf16 v[44:47], v[154:157], v[178:181], v[44:47]
	v_mfma_f32_16x16x32_bf16 v[40:43], v[162:165], v[178:181], v[40:43]
	v_mfma_f32_16x16x32_bf16 v[28:31], v[154:157], v[186:189], v[28:31]
	v_mfma_f32_16x16x32_bf16 v[24:27], v[162:165], v[186:189], v[24:27]
	v_mfma_f32_16x16x32_bf16 v[12:15], v[154:157], v[194:197], v[12:15]
	v_mfma_f32_16x16x32_bf16 v[8:11], v[162:165], v[194:197], v[8:11]
	s_setprio 0
	s_barrier
; #define PG8_STAGE(bufoff, gbase, voff) do { _Pragma("unroll") for (int _i = 0; _i < 2; ++_i) \
;         __builtin_amdgcn_global_load_lds((const unsigned*)((const char*)(gbase) + (voff)[_i]), (LAS unsigned*)(lds + (bufoff) + ldsw + _i * 8192), 16, 0, 0); } while (0)
; #define PG8_LDA(dst, b, h) do { _Pragma("unroll") for (int m = 0; m < 4; ++m) _Pragma("unroll") for (int k = 0; k < 2; ++k) dst[m][k] = *(const LAS bf16x8*)(lds + PG8_SA(b, h) + aoff + m * 2048 + k * 1024); } while (0)
; #define PG8_LDB(dst, b, h) do { _Pragma("unroll") for (int n = 0; n < 2; ++n) _Pragma("unroll") for (int k = 0; k < 2; ++k) dst[n][k] = *(const LAS bf16x8*)(lds + PG8_SB(b, h) + boff + n * 2048 + k * 1024); } while (0)
; #define PG8_MMA(ai, bj, At, Bt) do { __builtin_amdgcn_s_setprio(1); _Pragma("unroll") for (int m = 0; m < 4; ++m) _Pragma("unroll") for (int n = 0; n < 2; ++n) _Pragma("unroll") for (int k = 0; k < 2; ++k) \
;         acc[ai][bj][m][n] = __builtin_amdgcn_mfma_f32_16x16x32_bf16(Bt[n][k], At[m][k], acc[ai][bj][m][n], 0, 0, 0); __builtin_amdgcn_s_setprio(0); } while (0)
; #define PG8_WAIT_V(n) asm volatile("s_waitcnt vmcnt(" #n ")" ::: "memory")
; #define PG8_WAIT_L(n) asm volatile("s_waitcnt lgkmcnt(" #n ")" ::: "memory")
; #define PG8_BAR __builtin_amdgcn_s_barrier()
; #define PG8_SCHED __builtin_amdgcn_sched_barrier(0)
; template <class Epi, class Sched>
; __device__ __forceinline__ void gemm_phase(LAS unsigned char* lds, const Gemm g, const Sched& S, const Epi& E) {
;     ...
;             PG8_STAGE(PG8_SB(0, 1), b2 + hstep, voffB);
;             PG8_WAIT_V(6); PG8_BAR; PG8_MMA(1, 1, At, B1); PG8_BAR;
;             PG8_LDB(B0, 1, 0); PG8_SCHED; PG8_LDA(At, 1, 0); PG8_STAGE(PG8_SA(0, 1), a2 + hstep, voffA);
;             PG8_WAIT_L(8); PG8_BAR; PG8_WAIT_L(0); PG8_MMA(0, 0, At, B0); PG8_BAR; PG8_SCHED;
;             PG8_LDB(B1, 1, 1); PG8_STAGE(PG8_SB(1, 0), b3, voffB);
;             PG8_BAR; PG8_WAIT_L(0); PG8_MMA(0, 1, At, B1); PG8_BAR;
;             PG8_LDA(At, 1, 1); PG8_STAGE(PG8_SA(1, 0), a3, voffA);
;             PG8_BAR; PG8_WAIT_L(0); PG8_MMA(1, 0, At, B0); PG8_BAR; PG8_SCHED;
	s_add_u32 s62, s4, 0x40000
	s_addc_u32 s63, s5, 0
	s_add_i32 s64, s48, s31
	s_mov_b32 m0, s64
	s_nop 0
	global_load_lds_dwordx4 v130, s[62:63]
	s_add_i32 m0, s64, 0x2000
	s_nop 0
	global_load_lds_dwordx4 v134, s[62:63]
	s_add_u32 s24, s24, 0x40000
	s_addc_u32 s25, s25, 0
	s_mov_b32 m0, s35
	s_nop 0
	global_load_lds_dwordx4 v128, s[24:25]
	s_mov_b32 m0, s36
	s_nop 0
	global_load_lds_dwordx4 v132, s[24:25]
	s_waitcnt vmcnt(12)
	s_barrier
	s_setprio 1
	v_mfma_f32_16x16x32_bf16 v[52:55], v[202:205], v[166:169], 0
	v_mfma_f32_16x16x32_bf16 v[48:51], v[210:213], v[166:169], 0
	v_mfma_f32_16x16x32_bf16 v[36:39], v[202:205], v[174:177], 0
	v_mfma_f32_16x16x32_bf16 v[32:35], v[210:213], v[174:177], 0
	v_mfma_f32_16x16x32_bf16 v[20:23], v[202:205], v[182:185], 0
	v_mfma_f32_16x16x32_bf16 v[16:19], v[210:213], v[182:185], 0
	v_mfma_f32_16x16x32_bf16 v[4:7], v[202:205], v[190:193], 0
	v_mfma_f32_16x16x32_bf16 v[0:3], v[210:213], v[190:193], 0
	v_mfma_f32_16x16x32_bf16 v[52:55], v[206:209], v[170:173], v[52:55]
	v_mfma_f32_16x16x32_bf16 v[48:51], v[214:217], v[170:173], v[48:51]
	v_mfma_f32_16x16x32_bf16 v[36:39], v[206:209], v[178:181], v[36:39]
	v_mfma_f32_16x16x32_bf16 v[32:35], v[214:217], v[178:181], v[32:35]
	v_mfma_f32_16x16x32_bf16 v[20:23], v[206:209], v[186:189], v[20:23]
	v_mfma_f32_16x16x32_bf16 v[16:19], v[214:217], v[186:189], v[16:19]
	v_mfma_f32_16x16x32_bf16 v[4:7], v[206:209], v[194:197], v[4:7]
	v_mfma_f32_16x16x32_bf16 v[0:3], v[214:217], v[194:197], v[0:3]
	s_setprio 0
	s_add_i32 s62, 0, 0x18000
	v_add_u32_e32 v162, s62, v148
	s_barrier
	ds_read_b128 v[140:143], v162
	ds_read_b128 v[154:157], v162 offset:1024
	ds_read_b128 v[158:161], v162 offset:2048
	ds_read_b128 v[162:165], v162 offset:3072
	ds_read_b128 v[166:169], v150 offset:32768
	ds_read_b128 v[170:173], v150 offset:33792
	ds_read_b128 v[174:177], v150 offset:34816
	ds_read_b128 v[178:181], v150 offset:35840
	ds_read_b128 v[182:185], v150 offset:36864
	ds_read_b128 v[186:189], v150 offset:37888
	ds_read_b128 v[190:193], v150 offset:38912
	ds_read_b128 v[194:197], v150 offset:39936
	s_waitcnt lgkmcnt(8)
	s_waitcnt vmcnt(10)
	s_barrier
	s_waitcnt lgkmcnt(0)
	s_setprio 1
	s_waitcnt lgkmcnt(0)
	v_mfma_f32_16x16x32_bf16 v[124:127], v[140:143], v[166:169], v[124:127]
	v_mfma_f32_16x16x32_bf16 v[120:123], v[158:161], v[166:169], v[120:123]
	v_mfma_f32_16x16x32_bf16 v[108:111], v[140:143], v[174:177], v[108:111]
	v_mfma_f32_16x16x32_bf16 v[104:107], v[158:161], v[174:177], v[104:107]
	v_mfma_f32_16x16x32_bf16 v[92:95], v[140:143], v[182:185], v[92:95]
	v_mfma_f32_16x16x32_bf16 v[88:91], v[158:161], v[182:185], v[88:91]
	v_mfma_f32_16x16x32_bf16 v[76:79], v[140:143], v[190:193], v[76:79]
	v_mfma_f32_16x16x32_bf16 v[72:75], v[158:161], v[190:193], v[72:75]
	v_mfma_f32_16x16x32_bf16 v[124:127], v[154:157], v[170:173], v[124:127]
	v_mfma_f32_16x16x32_bf16 v[120:123], v[162:165], v[170:173], v[120:123]
	v_mfma_f32_16x16x32_bf16 v[108:111], v[154:157], v[178:181], v[108:111]
	v_mfma_f32_16x16x32_bf16 v[104:107], v[162:165], v[178:181], v[104:107]
	v_mfma_f32_16x16x32_bf16 v[92:95], v[154:157], v[186:189], v[92:95]
	v_mfma_f32_16x16x32_bf16 v[88:91], v[162:165], v[186:189], v[88:91]
	v_mfma_f32_16x16x32_bf16 v[76:79], v[154:157], v[194:197], v[76:79]
	v_mfma_f32_16x16x32_bf16 v[72:75], v[162:165], v[194:197], v[72:75]
	s_setprio 0
	s_barrier
	s_add_i32 s24, 0, 0x1c000
	s_add_i32 s25, s62, s31
	v_add_u32_e32 v214, s24, v148
	s_add_u32 s0, s4, 0x80
	s_addc_u32 s1, s5, 0
	s_mov_b32 m0, s25
	ds_read_b128 v[202:205], v214
	ds_read_b128 v[206:209], v214 offset:1024
	ds_read_b128 v[210:213], v214 offset:2048
	ds_read_b128 v[214:217], v214 offset:3072
	global_load_lds_dwordx4 v130, s[0:1]
	s_add_i32 m0, s25, 0x2000
	s_nop 0
	global_load_lds_dwordx4 v134, s[0:1]
	s_waitcnt vmcnt(10)
	s_barrier
	s_waitcnt lgkmcnt(0)
	s_setprio 1
	s_waitcnt lgkmcnt(0)
	v_mfma_f32_16x16x32_bf16 v[116:119], v[202:205], v[166:169], v[116:119]
	v_mfma_f32_16x16x32_bf16 v[112:115], v[210:213], v[166:169], v[112:115]
	v_mfma_f32_16x16x32_bf16 v[100:103], v[202:205], v[174:177], v[100:103]
	v_mfma_f32_16x16x32_bf16 v[96:99], v[210:213], v[174:177], v[96:99]
	v_mfma_f32_16x16x32_bf16 v[84:87], v[202:205], v[182:185], v[84:87]
	v_mfma_f32_16x16x32_bf16 v[80:83], v[210:213], v[182:185], v[80:83]
	v_mfma_f32_16x16x32_bf16 v[68:71], v[202:205], v[190:193], v[68:71]
	v_mfma_f32_16x16x32_bf16 v[64:67], v[210:213], v[190:193], v[64:67]
	v_mfma_f32_16x16x32_bf16 v[116:119], v[206:209], v[170:173], v[116:119]
	v_mfma_f32_16x16x32_bf16 v[112:115], v[214:217], v[170:173], v[112:115]
	v_mfma_f32_16x16x32_bf16 v[100:103], v[206:209], v[178:181], v[100:103]
	v_mfma_f32_16x16x32_bf16 v[96:99], v[214:217], v[178:181], v[96:99]
	v_mfma_f32_16x16x32_bf16 v[84:87], v[206:209], v[186:189], v[84:87]
	v_mfma_f32_16x16x32_bf16 v[80:83], v[214:217], v[186:189], v[80:83]
	v_mfma_f32_16x16x32_bf16 v[68:71], v[206:209], v[194:197], v[68:71]
	v_mfma_f32_16x16x32_bf16 v[64:67], v[214:217], v[194:197], v[64:67]
	s_setprio 0
	s_mov_b32 m0, s44
	s_mov_b64 s[0:1], 0x80
	v_lshl_add_u64 v[144:145], v[218:219], 0, s[0:1]
	s_barrier
	ds_read_b128 v[166:169], v150 offset:49152
	ds_read_b128 v[170:173], v150 offset:50176
	ds_read_b128 v[174:177], v150 offset:51200
	ds_read_b128 v[178:181], v150 offset:52224
	ds_read_b128 v[182:185], v150 offset:53248
	ds_read_b128 v[186:189], v150 offset:54272
	ds_read_b128 v[190:193], v150 offset:55296
	ds_read_b128 v[194:197], v150 offset:56320
	global_load_lds_dwordx4 v[144:145], off
	v_lshl_add_u64 v[144:145], v[220:221], 0, s[0:1]
	s_mov_b32 m0, s45
	s_nop 0
	global_load_lds_dwordx4 v[144:145], off
	s_barrier
; #define PG8_STAGE(bufoff, gbase, voff) do { _Pragma("unroll") for (int _i = 0; _i < 2; ++_i) \
;         __builtin_amdgcn_global_load_lds((const unsigned*)((const char*)(gbase) + (voff)[_i]), (LAS unsigned*)(lds + (bufoff) + ldsw + _i * 8192), 16, 0, 0); } while (0)
; #define PG8_LDA(dst, b, h) do { _Pragma("unroll") for (int m = 0; m < 4; ++m) _Pragma("unroll") for (int k = 0; k < 2; ++k) dst[m][k] = *(const LAS bf16x8*)(lds + PG8_SA(b, h) + aoff + m * 2048 + k * 1024); } while (0)
; #define PG8_LDB(dst, b, h) do { _Pragma("unroll") for (int n = 0; n < 2; ++n) _Pragma("unroll") for (int k = 0; k < 2; ++k) dst[n][k] = *(const LAS bf16x8*)(lds + PG8_SB(b, h) + boff + n * 2048 + k * 1024); } while (0)
; #define PG8_MMA(ai, bj, At, Bt) do { __builtin_amdgcn_s_setprio(1); _Pragma("unroll") for (int m = 0; m < 4; ++m) _Pragma("unroll") for (int n = 0; n < 2; ++n) _Pragma("unroll") for (int k = 0; k < 2; ++k) \
;         acc[ai][bj][m][n] = __builtin_amdgcn_mfma_f32_16x16x32_bf16(Bt[n][k], At[m][k], acc[ai][bj][m][n], 0, 0, 0); __builtin_amdgcn_s_setprio(0); } while (0)
; #define PG8_WAIT_V(n) asm volatile("s_waitcnt vmcnt(" #n ")" ::: "memory")
; #define PG8_WAIT_L(n) asm volatile("s_waitcnt lgkmcnt(" #n ")" ::: "memory")
; #define PG8_BAR __builtin_amdgcn_s_barrier()
; #define PG8_SCHED __builtin_amdgcn_sched_barrier(0)
; template <class Epi, class Sched>
; __device__ __forceinline__ void gemm_phase(LAS unsigned char* lds, const Gemm g, const Sched& S, const Epi& E) {
;     ...
;             PG8_LDB(B0, 0, 0); PG8_SCHED; PG8_LDA(At, 0, 0); PG8_STAGE(PG8_SA(1, 1), a1 + hstep, voffA);
;             PG8_WAIT_L(8); PG8_BAR; PG8_WAIT_L(0); PG8_MMA(0, 0, At, B0); PG8_BAR; PG8_SCHED;
;             PG8_LDB(B1, 0, 1); PG8_STAGE(PG8_SB(0, 0), b2, voffB);
;             PG8_BAR; PG8_WAIT_L(0); PG8_MMA(0, 1, At, B1); PG8_BAR;
;     ...
;             PG8_BAR; PG8_WAIT_L(0); PG8_MMA(1, 0, At, B0); PG8_BAR; PG8_SCHED;
;             PG8_STAGE(PG8_SB(1, 1), b3 + hstep, voffB);
;             PG8_WAIT_V(6); PG8_BAR; PG8_MMA(1, 1, At, B1); PG8_BAR;
	s_waitcnt lgkmcnt(0)
	s_setprio 1
	s_waitcnt lgkmcnt(0)
	v_mfma_f32_16x16x32_bf16 v[60:63], v[140:143], v[166:169], v[60:63]
	v_mfma_f32_16x16x32_bf16 v[56:59], v[158:161], v[166:169], v[56:59]
	v_mfma_f32_16x16x32_bf16 v[44:47], v[140:143], v[174:177], v[44:47]
	v_mfma_f32_16x16x32_bf16 v[40:43], v[158:161], v[174:177], v[40:43]
	v_mfma_f32_16x16x32_bf16 v[28:31], v[140:143], v[182:185], v[28:31]
	v_mfma_f32_16x16x32_bf16 v[24:27], v[158:161], v[182:185], v[24:27]
	v_mfma_f32_16x16x32_bf16 v[12:15], v[140:143], v[190:193], v[12:15]
	v_mfma_f32_16x16x32_bf16 v[8:11], v[158:161], v[190:193], v[8:11]
	v_mfma_f32_16x16x32_bf16 v[60:63], v[154:157], v[170:173], v[60:63]
	v_mfma_f32_16x16x32_bf16 v[56:59], v[162:165], v[170:173], v[56:59]
	v_mfma_f32_16x16x32_bf16 v[44:47], v[154:157], v[178:181], v[44:47]
	v_mfma_f32_16x16x32_bf16 v[40:43], v[162:165], v[178:181], v[40:43]
	v_mfma_f32_16x16x32_bf16 v[28:31], v[154:157], v[186:189], v[28:31]
	v_mfma_f32_16x16x32_bf16 v[24:27], v[162:165], v[186:189], v[24:27]
	v_mfma_f32_16x16x32_bf16 v[12:15], v[154:157], v[194:197], v[12:15]
	v_mfma_f32_16x16x32_bf16 v[8:11], v[162:165], v[194:197], v[8:11]
	s_setprio 0
	s_barrier
	s_add_u32 s4, s4, 0x40080
	s_addc_u32 s5, s5, 0
	s_add_i32 s24, s24, s31
	s_mov_b32 m0, s24
	s_nop 0
	global_load_lds_dwordx4 v130, s[4:5]
	s_add_i32 m0, s24, 0x2000
	s_nop 0
	global_load_lds_dwordx4 v134, s[4:5]
	s_waitcnt vmcnt(10)
	s_barrier
	s_setprio 1
	v_mfma_f32_16x16x32_bf16 v[52:55], v[202:205], v[166:169], v[52:55]
	v_mfma_f32_16x16x32_bf16 v[48:51], v[210:213], v[166:169], v[48:51]
	v_mfma_f32_16x16x32_bf16 v[36:39], v[202:205], v[174:177], v[36:39]
	v_mfma_f32_16x16x32_bf16 v[32:35], v[210:213], v[174:177], v[32:35]
	v_mfma_f32_16x16x32_bf16 v[20:23], v[202:205], v[182:185], v[20:23]
	v_mfma_f32_16x16x32_bf16 v[16:19], v[210:213], v[182:185], v[16:19]
	v_mfma_f32_16x16x32_bf16 v[4:7], v[202:205], v[190:193], v[4:7]
	v_mfma_f32_16x16x32_bf16 v[0:3], v[210:213], v[190:193], v[0:3]
	v_mfma_f32_16x16x32_bf16 v[52:55], v[206:209], v[170:173], v[52:55]
	v_mfma_f32_16x16x32_bf16 v[48:51], v[214:217], v[170:173], v[48:51]
	v_mfma_f32_16x16x32_bf16 v[36:39], v[206:209], v[178:181], v[36:39]
	v_mfma_f32_16x16x32_bf16 v[32:35], v[214:217], v[178:181], v[32:35]
	v_mfma_f32_16x16x32_bf16 v[20:23], v[206:209], v[186:189], v[20:23]
	v_mfma_f32_16x16x32_bf16 v[16:19], v[214:217], v[186:189], v[16:19]
	v_mfma_f32_16x16x32_bf16 v[4:7], v[206:209], v[194:197], v[4:7]
	v_mfma_f32_16x16x32_bf16 v[0:3], v[214:217], v[194:197], v[0:3]
	s_setprio 0
	s_add_i32 s61, s61, 2
	s_add_u32 s2, s2, 0x100
	s_addc_u32 s3, s3, 0
	s_add_u32 s59, s59, 0x100
	s_addc_u32 s60, s60, 0
	s_cmp_gt_u32 s61, 13
	s_barrier
.LBB0_693:
	ds_read_b128 v[140:143], v149
	ds_read_b128 v[154:157], v149 offset:1024
	ds_read_b128 v[158:161], v149 offset:2048
	ds_read_b128 v[162:165], v149 offset:3072
	s_add_u32 s4, s2, 0xfffc0080
	s_addc_u32 s5, s3, -1
	s_cmp_eq_u32 s61, 12
	s_cselect_b32 s25, s19, s5
	s_cselect_b32 s24, s57, s4
	s_cselect_b32 s5, s17, s60
	s_cselect_b32 s4, s58, s59
	s_add_i32 m0, s33, 0xc000
	ds_read_b128 v[166:169], v150
	ds_read_b128 v[170:173], v150 offset:1024
	ds_read_b128 v[174:177], v150 offset:2048
	ds_read_b128 v[178:181], v150 offset:3072
	ds_read_b128 v[182:185], v150 offset:4096
	ds_read_b128 v[186:189], v150 offset:5120
	ds_read_b128 v[190:193], v150 offset:6144
	ds_read_b128 v[194:197], v150 offset:7168
	global_load_lds_dwordx4 v136, s[2:3]
	s_add_i32 m0, s33, 0xe000
	s_nop 0
	global_load_lds_dwordx4 v138, s[2:3]
	s_waitcnt lgkmcnt(8)
	s_waitcnt vmcnt(10)
	s_barrier
	s_waitcnt lgkmcnt(0)
	s_setprio 1
	s_waitcnt lgkmcnt(0)
	v_mfma_f32_16x16x32_bf16 v[124:127], v[140:143], v[166:169], v[124:127]
	v_mfma_f32_16x16x32_bf16 v[120:123], v[158:161], v[166:169], v[120:123]
	v_mfma_f32_16x16x32_bf16 v[108:111], v[140:143], v[174:177], v[108:111]
	v_mfma_f32_16x16x32_bf16 v[104:107], v[158:161], v[174:177], v[104:107]
	v_mfma_f32_16x16x32_bf16 v[92:95], v[140:143], v[182:185], v[92:95]
	v_mfma_f32_16x16x32_bf16 v[88:91], v[158:161], v[182:185], v[88:91]
	v_mfma_f32_16x16x32_bf16 v[76:79], v[140:143], v[190:193], v[76:79]
	v_mfma_f32_16x16x32_bf16 v[72:75], v[158:161], v[190:193], v[72:75]
	v_mfma_f32_16x16x32_bf16 v[124:127], v[154:157], v[170:173], v[124:127]
	v_mfma_f32_16x16x32_bf16 v[120:123], v[162:165], v[170:173], v[120:123]
	v_mfma_f32_16x16x32_bf16 v[108:111], v[154:157], v[178:181], v[108:111]
	v_mfma_f32_16x16x32_bf16 v[104:107], v[162:165], v[178:181], v[104:107]
	v_mfma_f32_16x16x32_bf16 v[92:95], v[154:157], v[186:189], v[92:95]
	v_mfma_f32_16x16x32_bf16 v[88:91], v[162:165], v[186:189], v[88:91]
	v_mfma_f32_16x16x32_bf16 v[76:79], v[154:157], v[194:197], v[76:79]
	v_mfma_f32_16x16x32_bf16 v[72:75], v[162:165], v[194:197], v[72:75]
	s_setprio 0
	s_barrier
	s_add_i32 s62, s47, s31
	s_mov_b32 m0, s62
	ds_read_b128 v[202:205], v151
	ds_read_b128 v[206:209], v151 offset:1024
	ds_read_b128 v[210:213], v151 offset:2048
	ds_read_b128 v[214:217], v151 offset:3072
	global_load_lds_dwordx4 v130, s[4:5]
	s_add_i32 m0, s62, 0x2000
	s_nop 0
	global_load_lds_dwordx4 v134, s[4:5]
	s_waitcnt vmcnt(10)
	s_barrier
; #define PG8_STAGE(bufoff, gbase, voff) do { _Pragma("unroll") for (int _i = 0; _i < 2; ++_i) \
;         __builtin_amdgcn_global_load_lds((const unsigned*)((const char*)(gbase) + (voff)[_i]), (LAS unsigned*)(lds + (bufoff) + ldsw + _i * 8192), 16, 0, 0); } while (0)
; #define PG8_LDA(dst, b, h) do { _Pragma("unroll") for (int m = 0; m < 4; ++m) _Pragma("unroll") for (int k = 0; k < 2; ++k) dst[m][k] = *(const LAS bf16x8*)(lds + PG8_SA(b, h) + aoff + m * 2048 + k * 1024); } while (0)
; #define PG8_LDB(dst, b, h) do { _Pragma("unroll") for (int n = 0; n < 2; ++n) _Pragma("unroll") for (int k = 0; k < 2; ++k) dst[n][k] = *(const LAS bf16x8*)(lds + PG8_SB(b, h) + boff + n * 2048 + k * 1024); } while (0)
; #define PG8_MMA(ai, bj, At, Bt) do { __builtin_amdgcn_s_setprio(1); _Pragma("unroll") for (int m = 0; m < 4; ++m) _Pragma("unroll") for (int n = 0; n < 2; ++n) _Pragma("unroll") for (int k = 0; k < 2; ++k) \
;         acc[ai][bj][m][n] = __builtin_amdgcn_mfma_f32_16x16x32_bf16(Bt[n][k], At[m][k], acc[ai][bj][m][n], 0, 0, 0); __builtin_amdgcn_s_setprio(0); } while (0)
; #define PG8_WAIT_V(n) asm volatile("s_waitcnt vmcnt(" #n ")" ::: "memory")
; #define PG8_WAIT_L(n) asm volatile("s_waitcnt lgkmcnt(" #n ")" ::: "memory")
; #define PG8_BAR __builtin_amdgcn_s_barrier()
; #define PG8_SCHED __builtin_amdgcn_sched_barrier(0)
; template <class Epi, class Sched>
; __device__ __forceinline__ void gemm_phase(LAS unsigned char* lds, const Gemm g, const Sched& S, const Epi& E) {
;     ...
;             PG8_LDA(At, 0, 1); PG8_STAGE(PG8_SA(0, 0), a2, voffA);
;             PG8_BAR; PG8_WAIT_L(0); PG8_MMA(1, 0, At, B0); PG8_BAR; PG8_SCHED;
;             PG8_STAGE(PG8_SB(0, 1), b2 + hstep, voffB);
;             PG8_WAIT_V(6); PG8_BAR; PG8_MMA(1, 1, At, B1); PG8_BAR;
;             PG8_LDB(B0, 1, 0); PG8_SCHED; PG8_LDA(At, 1, 0); PG8_STAGE(PG8_SA(0, 1), a2 + hstep, voffA);
;             PG8_WAIT_L(8); PG8_BAR; PG8_WAIT_L(0); PG8_MMA(0, 0, At, B0); PG8_BAR; PG8_SCHED;
	s_waitcnt lgkmcnt(0)
	s_setprio 1
	s_waitcnt lgkmcnt(0)
	v_mfma_f32_16x16x32_bf16 v[116:119], v[202:205], v[166:169], v[116:119]
	v_mfma_f32_16x16x32_bf16 v[112:115], v[210:213], v[166:169], v[112:115]
	v_mfma_f32_16x16x32_bf16 v[100:103], v[202:205], v[174:177], v[100:103]
	v_mfma_f32_16x16x32_bf16 v[96:99], v[210:213], v[174:177], v[96:99]
	v_mfma_f32_16x16x32_bf16 v[84:87], v[202:205], v[182:185], v[84:87]
	v_mfma_f32_16x16x32_bf16 v[80:83], v[210:213], v[182:185], v[80:83]
	v_mfma_f32_16x16x32_bf16 v[68:71], v[202:205], v[190:193], v[68:71]
	v_mfma_f32_16x16x32_bf16 v[64:67], v[210:213], v[190:193], v[64:67]
	v_mfma_f32_16x16x32_bf16 v[116:119], v[206:209], v[170:173], v[116:119]
	v_mfma_f32_16x16x32_bf16 v[112:115], v[214:217], v[170:173], v[112:115]
	v_mfma_f32_16x16x32_bf16 v[100:103], v[206:209], v[178:181], v[100:103]
	v_mfma_f32_16x16x32_bf16 v[96:99], v[214:217], v[178:181], v[96:99]
	v_mfma_f32_16x16x32_bf16 v[84:87], v[206:209], v[186:189], v[84:87]
	v_mfma_f32_16x16x32_bf16 v[80:83], v[214:217], v[186:189], v[80:83]
	v_mfma_f32_16x16x32_bf16 v[68:71], v[206:209], v[194:197], v[68:71]
	v_mfma_f32_16x16x32_bf16 v[64:67], v[214:217], v[194:197], v[64:67]
	s_setprio 0
	s_mov_b32 m0, s33
	v_lshl_add_u64 v[218:219], s[24:25], 0, v[128:129]
	s_barrier
	ds_read_b128 v[166:169], v150 offset:16384
	ds_read_b128 v[170:173], v150 offset:17408
	ds_read_b128 v[174:177], v150 offset:18432
	ds_read_b128 v[178:181], v150 offset:19456
	ds_read_b128 v[182:185], v150 offset:20480
	ds_read_b128 v[186:189], v150 offset:21504
	ds_read_b128 v[190:193], v150 offset:22528
	ds_read_b128 v[194:197], v150 offset:23552
	global_load_lds_dwordx4 v128, s[24:25]
	v_lshl_add_u64 v[220:221], s[24:25], 0, v[132:133]
	s_mov_b32 m0, s34
	s_nop 0
	global_load_lds_dwordx4 v132, s[24:25]
	s_barrier
	s_waitcnt lgkmcnt(0)
	s_setprio 1
	s_waitcnt lgkmcnt(0)
	v_mfma_f32_16x16x32_bf16 v[60:63], v[140:143], v[166:169], v[60:63]
	v_mfma_f32_16x16x32_bf16 v[56:59], v[158:161], v[166:169], v[56:59]
	v_mfma_f32_16x16x32_bf16 v[44:47], v[140:143], v[174:177], v[44:47]
	v_mfma_f32_16x16x32_bf16 v[40:43], v[158:161], v[174:177], v[40:43]
	v_mfma_f32_16x16x32_bf16 v[28:31], v[140:143], v[182:185], v[28:31]
	v_mfma_f32_16x16x32_bf16 v[24:27], v[158:161], v[182:185], v[24:27]
	v_mfma_f32_16x16x32_bf16 v[12:15], v[140:143], v[190:193], v[12:15]
	v_mfma_f32_16x16x32_bf16 v[8:11], v[158:161], v[190:193], v[8:11]
	v_mfma_f32_16x16x32_bf16 v[60:63], v[154:157], v[170:173], v[60:63]
	v_mfma_f32_16x16x32_bf16 v[56:59], v[162:165], v[170:173], v[56:59]
	v_mfma_f32_16x16x32_bf16 v[44:47], v[154:157], v[178:181], v[44:47]
	v_mfma_f32_16x16x32_bf16 v[40:43], v[162:165], v[178:181], v[40:43]
	v_mfma_f32_16x16x32_bf16 v[28:31], v[154:157], v[186:189], v[28:31]
	v_mfma_f32_16x16x32_bf16 v[24:27], v[162:165], v[186:189], v[24:27]
	v_mfma_f32_16x16x32_bf16 v[12:15], v[154:157], v[194:197], v[12:15]
	v_mfma_f32_16x16x32_bf16 v[8:11], v[162:165], v[194:197], v[8:11]
	s_setprio 0
	s_barrier
	s_add_u32 s62, s4, 0x40000
	s_addc_u32 s63, s5, 0
	s_add_i32 s64, s48, s31
	s_mov_b32 m0, s64
	s_nop 0
	global_load_lds_dwordx4 v130, s[62:63]
	s_add_i32 m0, s64, 0x2000
	s_nop 0
	global_load_lds_dwordx4 v134, s[62:63]
	s_add_u32 s24, s24, 0x40000
	s_addc_u32 s25, s25, 0
	s_mov_b32 m0, s35
	s_nop 0
	global_load_lds_dwordx4 v128, s[24:25]
	s_mov_b32 m0, s36
	s_nop 0
	global_load_lds_dwordx4 v132, s[24:25]
	s_waitcnt vmcnt(12)
	s_barrier
	s_setprio 1
	v_mfma_f32_16x16x32_bf16 v[52:55], v[202:205], v[166:169], v[52:55]
	v_mfma_f32_16x16x32_bf16 v[48:51], v[210:213], v[166:169], v[48:51]
	v_mfma_f32_16x16x32_bf16 v[36:39], v[202:205], v[174:177], v[36:39]
	v_mfma_f32_16x16x32_bf16 v[32:35], v[210:213], v[174:177], v[32:35]
	v_mfma_f32_16x16x32_bf16 v[20:23], v[202:205], v[182:185], v[20:23]
	v_mfma_f32_16x16x32_bf16 v[16:19], v[210:213], v[182:185], v[16:19]
	v_mfma_f32_16x16x32_bf16 v[4:7], v[202:205], v[190:193], v[4:7]
	v_mfma_f32_16x16x32_bf16 v[0:3], v[210:213], v[190:193], v[0:3]
	v_mfma_f32_16x16x32_bf16 v[52:55], v[206:209], v[170:173], v[52:55]
	v_mfma_f32_16x16x32_bf16 v[48:51], v[214:217], v[170:173], v[48:51]
	v_mfma_f32_16x16x32_bf16 v[36:39], v[206:209], v[178:181], v[36:39]
	v_mfma_f32_16x16x32_bf16 v[32:35], v[214:217], v[178:181], v[32:35]
	v_mfma_f32_16x16x32_bf16 v[20:23], v[206:209], v[186:189], v[20:23]
	v_mfma_f32_16x16x32_bf16 v[16:19], v[214:217], v[186:189], v[16:19]
	v_mfma_f32_16x16x32_bf16 v[4:7], v[206:209], v[194:197], v[4:7]
	v_mfma_f32_16x16x32_bf16 v[0:3], v[214:217], v[194:197], v[0:3]
	s_setprio 0
	s_add_i32 s62, 0, 0x18000
	v_add_u32_e32 v162, s62, v148
	s_barrier
	ds_read_b128 v[140:143], v162
	ds_read_b128 v[154:157], v162 offset:1024
	ds_read_b128 v[158:161], v162 offset:2048
	ds_read_b128 v[162:165], v162 offset:3072
	ds_read_b128 v[166:169], v150 offset:32768
	ds_read_b128 v[170:173], v150 offset:33792
	ds_read_b128 v[174:177], v150 offset:34816
	ds_read_b128 v[178:181], v150 offset:35840
	ds_read_b128 v[182:185], v150 offset:36864
	ds_read_b128 v[186:189], v150 offset:37888
	ds_read_b128 v[190:193], v150 offset:38912
	ds_read_b128 v[194:197], v150 offset:39936
	s_waitcnt lgkmcnt(8)
	s_waitcnt vmcnt(10)
	s_barrier
; #define PG8_STAGE(bufoff, gbase, voff) do { _Pragma("unroll") for (int _i = 0; _i < 2; ++_i) \
;         __builtin_amdgcn_global_load_lds((const unsigned*)((const char*)(gbase) + (voff)[_i]), (LAS unsigned*)(lds + (bufoff) + ldsw + _i * 8192), 16, 0, 0); } while (0)
; #define PG8_LDA(dst, b, h) do { _Pragma("unroll") for (int m = 0; m < 4; ++m) _Pragma("unroll") for (int k = 0; k < 2; ++k) dst[m][k] = *(const LAS bf16x8*)(lds + PG8_SA(b, h) + aoff + m * 2048 + k * 1024); } while (0)
; #define PG8_LDB(dst, b, h) do { _Pragma("unroll") for (int n = 0; n < 2; ++n) _Pragma("unroll") for (int k = 0; k < 2; ++k) dst[n][k] = *(const LAS bf16x8*)(lds + PG8_SB(b, h) + boff + n * 2048 + k * 1024); } while (0)
; #define PG8_MMA(ai, bj, At, Bt) do { __builtin_amdgcn_s_setprio(1); _Pragma("unroll") for (int m = 0; m < 4; ++m) _Pragma("unroll") for (int n = 0; n < 2; ++n) _Pragma("unroll") for (int k = 0; k < 2; ++k) \
;         acc[ai][bj][m][n] = __builtin_amdgcn_mfma_f32_16x16x32_bf16(Bt[n][k], At[m][k], acc[ai][bj][m][n], 0, 0, 0); __builtin_amdgcn_s_setprio(0); } while (0)
; #define PG8_WAIT_V(n) asm volatile("s_waitcnt vmcnt(" #n ")" ::: "memory")
; #define PG8_WAIT_L(n) asm volatile("s_waitcnt lgkmcnt(" #n ")" ::: "memory")
; #define PG8_BAR __builtin_amdgcn_s_barrier()
; #define PG8_SCHED __builtin_amdgcn_sched_barrier(0)
; template <class Epi, class Sched>
; __device__ __forceinline__ void gemm_phase(LAS unsigned char* lds, const Gemm g, const Sched& S, const Epi& E) {
;     ...
;             PG8_WAIT_L(8); PG8_BAR; PG8_WAIT_L(0); PG8_MMA(0, 0, At, B0); PG8_BAR; PG8_SCHED;
;             PG8_LDB(B1, 1, 1); PG8_STAGE(PG8_SB(1, 0), b3, voffB);
;             PG8_BAR; PG8_WAIT_L(0); PG8_MMA(0, 1, At, B1); PG8_BAR;
;             PG8_LDA(At, 1, 1); PG8_STAGE(PG8_SA(1, 0), a3, voffA);
;             PG8_BAR; PG8_WAIT_L(0); PG8_MMA(1, 0, At, B0); PG8_BAR; PG8_SCHED;
;             PG8_STAGE(PG8_SB(1, 1), b3 + hstep, voffB);
;             PG8_WAIT_V(6); PG8_BAR; PG8_MMA(1, 1, At, B1); PG8_BAR;
	s_waitcnt lgkmcnt(0)
	s_setprio 1
	s_waitcnt lgkmcnt(0)
	v_mfma_f32_16x16x32_bf16 v[124:127], v[140:143], v[166:169], v[124:127]
	v_mfma_f32_16x16x32_bf16 v[120:123], v[158:161], v[166:169], v[120:123]
	v_mfma_f32_16x16x32_bf16 v[108:111], v[140:143], v[174:177], v[108:111]
	v_mfma_f32_16x16x32_bf16 v[104:107], v[158:161], v[174:177], v[104:107]
	v_mfma_f32_16x16x32_bf16 v[92:95], v[140:143], v[182:185], v[92:95]
	v_mfma_f32_16x16x32_bf16 v[88:91], v[158:161], v[182:185], v[88:91]
	v_mfma_f32_16x16x32_bf16 v[76:79], v[140:143], v[190:193], v[76:79]
	v_mfma_f32_16x16x32_bf16 v[72:75], v[158:161], v[190:193], v[72:75]
	v_mfma_f32_16x16x32_bf16 v[124:127], v[154:157], v[170:173], v[124:127]
	v_mfma_f32_16x16x32_bf16 v[120:123], v[162:165], v[170:173], v[120:123]
	v_mfma_f32_16x16x32_bf16 v[108:111], v[154:157], v[178:181], v[108:111]
	v_mfma_f32_16x16x32_bf16 v[104:107], v[162:165], v[178:181], v[104:107]
	v_mfma_f32_16x16x32_bf16 v[92:95], v[154:157], v[186:189], v[92:95]
	v_mfma_f32_16x16x32_bf16 v[88:91], v[162:165], v[186:189], v[88:91]
	v_mfma_f32_16x16x32_bf16 v[76:79], v[154:157], v[194:197], v[76:79]
	v_mfma_f32_16x16x32_bf16 v[72:75], v[162:165], v[194:197], v[72:75]
	s_setprio 0
	s_barrier
	s_add_i32 s24, 0, 0x1c000
	s_add_i32 s25, s62, s31
	v_add_u32_e32 v214, s24, v148
	s_add_u32 s0, s4, 0x80
	s_addc_u32 s1, s5, 0
	s_mov_b32 m0, s25
	ds_read_b128 v[202:205], v214
	ds_read_b128 v[206:209], v214 offset:1024
	ds_read_b128 v[210:213], v214 offset:2048
	ds_read_b128 v[214:217], v214 offset:3072
	global_load_lds_dwordx4 v130, s[0:1]
	s_add_i32 m0, s25, 0x2000
	s_nop 0
	global_load_lds_dwordx4 v134, s[0:1]
	s_waitcnt vmcnt(10)
	s_barrier
	s_waitcnt lgkmcnt(0)
	s_setprio 1
	s_waitcnt lgkmcnt(0)
	v_mfma_f32_16x16x32_bf16 v[116:119], v[202:205], v[166:169], v[116:119]
	v_mfma_f32_16x16x32_bf16 v[112:115], v[210:213], v[166:169], v[112:115]
	v_mfma_f32_16x16x32_bf16 v[100:103], v[202:205], v[174:177], v[100:103]
	v_mfma_f32_16x16x32_bf16 v[96:99], v[210:213], v[174:177], v[96:99]
	v_mfma_f32_16x16x32_bf16 v[84:87], v[202:205], v[182:185], v[84:87]
	v_mfma_f32_16x16x32_bf16 v[80:83], v[210:213], v[182:185], v[80:83]
	v_mfma_f32_16x16x32_bf16 v[68:71], v[202:205], v[190:193], v[68:71]
	v_mfma_f32_16x16x32_bf16 v[64:67], v[210:213], v[190:193], v[64:67]
	v_mfma_f32_16x16x32_bf16 v[116:119], v[206:209], v[170:173], v[116:119]
	v_mfma_f32_16x16x32_bf16 v[112:115], v[214:217], v[170:173], v[112:115]
	v_mfma_f32_16x16x32_bf16 v[100:103], v[206:209], v[178:181], v[100:103]
	v_mfma_f32_16x16x32_bf16 v[96:99], v[214:217], v[178:181], v[96:99]
	v_mfma_f32_16x16x32_bf16 v[84:87], v[206:209], v[186:189], v[84:87]
	v_mfma_f32_16x16x32_bf16 v[80:83], v[214:217], v[186:189], v[80:83]
	v_mfma_f32_16x16x32_bf16 v[68:71], v[206:209], v[194:197], v[68:71]
	v_mfma_f32_16x16x32_bf16 v[64:67], v[214:217], v[194:197], v[64:67]
	s_setprio 0
	s_mov_b32 m0, s44
	s_mov_b64 s[0:1], 0x80
	v_lshl_add_u64 v[144:145], v[218:219], 0, s[0:1]
	s_barrier
	ds_read_b128 v[166:169], v150 offset:49152
	ds_read_b128 v[170:173], v150 offset:50176
	ds_read_b128 v[174:177], v150 offset:51200
	ds_read_b128 v[178:181], v150 offset:52224
	ds_read_b128 v[182:185], v150 offset:53248
	ds_read_b128 v[186:189], v150 offset:54272
	ds_read_b128 v[190:193], v150 offset:55296
	ds_read_b128 v[194:197], v150 offset:56320
	global_load_lds_dwordx4 v[144:145], off
	v_lshl_add_u64 v[144:145], v[220:221], 0, s[0:1]
	s_mov_b32 m0, s45
	s_nop 0
	global_load_lds_dwordx4 v[144:145], off
	s_barrier
	s_waitcnt lgkmcnt(0)
	s_setprio 1
	s_waitcnt lgkmcnt(0)
	v_mfma_f32_16x16x32_bf16 v[60:63], v[140:143], v[166:169], v[60:63]
	v_mfma_f32_16x16x32_bf16 v[56:59], v[158:161], v[166:169], v[56:59]
	v_mfma_f32_16x16x32_bf16 v[44:47], v[140:143], v[174:177], v[44:47]
	v_mfma_f32_16x16x32_bf16 v[40:43], v[158:161], v[174:177], v[40:43]
	v_mfma_f32_16x16x32_bf16 v[28:31], v[140:143], v[182:185], v[28:31]
	v_mfma_f32_16x16x32_bf16 v[24:27], v[158:161], v[182:185], v[24:27]
	v_mfma_f32_16x16x32_bf16 v[12:15], v[140:143], v[190:193], v[12:15]
	v_mfma_f32_16x16x32_bf16 v[8:11], v[158:161], v[190:193], v[8:11]
	v_mfma_f32_16x16x32_bf16 v[60:63], v[154:157], v[170:173], v[60:63]
	v_mfma_f32_16x16x32_bf16 v[56:59], v[162:165], v[170:173], v[56:59]
	v_mfma_f32_16x16x32_bf16 v[44:47], v[154:157], v[178:181], v[44:47]
	v_mfma_f32_16x16x32_bf16 v[40:43], v[162:165], v[178:181], v[40:43]
	v_mfma_f32_16x16x32_bf16 v[28:31], v[154:157], v[186:189], v[28:31]
	v_mfma_f32_16x16x32_bf16 v[24:27], v[162:165], v[186:189], v[24:27]
	v_mfma_f32_16x16x32_bf16 v[12:15], v[154:157], v[194:197], v[12:15]
	v_mfma_f32_16x16x32_bf16 v[8:11], v[162:165], v[194:197], v[8:11]
	s_setprio 0
	s_barrier
	s_add_u32 s4, s4, 0x40080
	s_addc_u32 s5, s5, 0
	s_add_i32 s24, s24, s31
	s_mov_b32 m0, s24
	s_nop 0
	global_load_lds_dwordx4 v130, s[4:5]
	s_add_i32 m0, s24, 0x2000
	s_nop 0
	global_load_lds_dwordx4 v134, s[4:5]
	s_waitcnt vmcnt(10)
	s_barrier
	s_setprio 1
	v_mfma_f32_16x16x32_bf16 v[52:55], v[202:205], v[166:169], v[52:55]
	v_mfma_f32_16x16x32_bf16 v[48:51], v[210:213], v[166:169], v[48:51]
	v_mfma_f32_16x16x32_bf16 v[36:39], v[202:205], v[174:177], v[36:39]
	v_mfma_f32_16x16x32_bf16 v[32:35], v[210:213], v[174:177], v[32:35]
	v_mfma_f32_16x16x32_bf16 v[20:23], v[202:205], v[182:185], v[20:23]
	v_mfma_f32_16x16x32_bf16 v[16:19], v[210:213], v[182:185], v[16:19]
	v_mfma_f32_16x16x32_bf16 v[4:7], v[202:205], v[190:193], v[4:7]
	v_mfma_f32_16x16x32_bf16 v[0:3], v[210:213], v[190:193], v[0:3]
	v_mfma_f32_16x16x32_bf16 v[52:55], v[206:209], v[170:173], v[52:55]
	v_mfma_f32_16x16x32_bf16 v[48:51], v[214:217], v[170:173], v[48:51]
	v_mfma_f32_16x16x32_bf16 v[36:39], v[206:209], v[178:181], v[36:39]
	v_mfma_f32_16x16x32_bf16 v[32:35], v[214:217], v[178:181], v[32:35]
	v_mfma_f32_16x16x32_bf16 v[20:23], v[206:209], v[186:189], v[20:23]
	v_mfma_f32_16x16x32_bf16 v[16:19], v[214:217], v[186:189], v[16:19]
	v_mfma_f32_16x16x32_bf16 v[4:7], v[206:209], v[194:197], v[4:7]
	v_mfma_f32_16x16x32_bf16 v[0:3], v[214:217], v[194:197], v[0:3]
	s_setprio 0
	s_add_i32 s61, s61, 2
	s_add_u32 s2, s2, 0x100
	s_addc_u32 s3, s3, 0
	s_add_u32 s59, s59, 0x100
	s_addc_u32 s60, s60, 0
	s_cmp_gt_u32 s61, 13
	s_barrier
;     __device__ __forceinline__ void operator()(const AccT& acc, const Unit& u, int wr, int wc, int fr, int fq) const {
;     ...
;         const int rbase = wr * 64 + fr;
;         const int tb = u.pn * 256 + wc * 32 + 8 * fq;
;         const int o0 = wc * 32 + 8 * fq;
;         const int j = fr & 3; const float sgn = ((fr >> 2) & 1) ? 1.0f : -1.0f;
; #pragma unroll
;         for (int ai = 0; ai < 2; ++ai) {
;             const int hh = 2 * ai + wr;
;             const float l2f = lgd[hh] * 1.4426950408889634f, l2b = lgd[4 + hh] * 1.4426950408889634f;
;             const float zf0 = exp2f((float)(127 - o0) * l2f), zfs = exp2f(-l2f), zb0 = exp2f((float)o0 * l2b), zbs = exp2f(l2b);
; #pragma unroll
;             for (int m = 0; m < 4; ++m) {
;                 const int r = rbase + ai * 128 + m * 16;
;                 const int d = 4 * (2 * m + (fr >> 3)) + j;
; #pragma unroll
;                 for (int bj = 0; bj < 2; ++bj) {
;                     const int t0 = tb + bj * 128;
;                     float v[8];
; #pragma unroll
;                     for (int jj = 0; jj < 4; ++jj) { v[jj] = acc[ai][bj][m][0][jj]; v[4 + jj] = acc[ai][bj][m][1][jj]; }
;                     if constexpr (ROPE) {
;                         const int t = t0 & 2047;
; #pragma unroll
;                         for (int hf = 0; hf < 2; ++hf) {
;                             f32x4 cs, sn;
;                             if (m < 2) { const float c1 = ropeA[(t >> 6) * 16 + d], s1 = ropeA[1024 + (t >> 6) * 16 + d]; cs = (f32x4){c1, c1, c1, c1}; sn = (f32x4){s1, s1, s1, s1}; }
;                             else { const float* cb = ropeA + 2048 + (d - 16) * 64 + (t & 63) + 4 * hf; cs = *(const f32x4*)(cb); sn = *(const f32x4*)(cb + 1024); }
; #pragma unroll
;                             for (int jj = 0; jj < 4; ++jj) { const float pr = __shfl_xor(v[4 * hf + jj], 4); v[4 * hf + jj] = v[4 * hf + jj] * cs[jj] + sgn * pr * sn[jj]; }
;                             __builtin_amdgcn_sched_barrier(0);
;                         }
;                     }
;                     float zf[8], zb[8]; zf[0] = zf0; zb[0] = zb0;
; #pragma unroll
;                     for (int jj = 1; jj < 8; ++jj) { zf[jj] = zf[jj - 1] * zfs; zb[jj] = zb[jj - 1] * zbs; }
;                     u32x4 wf, wb;
	s_cbranch_scc0 .LBB0_693
	v_mov_b32_e32 v141, v147
	v_mov_b32_e32 v140, v146
	global_load_dword v156, v131, s[6:7]
	global_load_dword v157, v131, s[6:7] offset:16
	s_lshl_b32 s2, s56, 8
	s_or_b32 s2, s2, s43
	v_add_u32_e32 v140, s42, v140
	v_lshlrev_b32_e32 v141, 3, v141
	v_add_u32_e32 v142, s2, v141
	v_add_u32_e32 v143, s43, v141
	v_ashrrev_i32_e32 v141, 31, v140
	v_sub_u32_e32 v144, 0x7f, v143
	v_lshlrev_b64 v[140:141], 14, v[140:141]
	v_cvt_f32_i32_e32 v154, v143
	v_ashrrev_i32_e32 v143, 31, v142
	v_cvt_f32_i32_e32 v155, v144
	v_lshl_add_u64 v[140:141], s[70:71], 0, v[140:141]
	s_mov_b32 s3, 0x400000
	v_lshl_add_u64 v[140:141], v[142:143], 1, v[140:141]
	v_add_co_u32_e32 v144, vcc, s3, v140
	s_mov_b64 s[4:5], 0x400000
	s_nop 0
	v_addc_co_u32_e32 v145, vcc, 0, v141, vcc
	v_lshl_add_u64 v[142:143], v[140:141], 0, s[4:5]
	s_waitcnt vmcnt(0)
	v_mul_f32_e32 v158, 0x3fb8aa3b, v156
	v_mul_f32_e32 v159, 0x3fb8aa3b, v157
	v_mul_f32_e32 v160, v158, v155
	v_cmp_lt_f32_e32 vcc, s51, v158
	v_mul_f32_e32 v162, v159, v154
	v_cmp_gt_f32_e64 s[2:3], s49, v159
	v_cndmask_b32_e32 v161, 0, v153, vcc
	v_cmp_gt_f32_e64 s[4:5], s49, v160
	v_cndmask_b32_e64 v163, 0, v153, s[2:3]
	s_and_b64 s[24:25], vcc, exec
	v_cmp_gt_f32_e32 vcc, s49, v162
	v_fmac_f32_e32 v163, 0x3fb8aa3b, v157
	v_cndmask_b32_e64 v157, 0, v153, s[4:5]
	v_cndmask_b32_e32 v162, 0, v153, vcc
	v_fmac_f32_e32 v161, 0xbfb8aa3b, v156
	v_fmac_f32_e32 v157, v158, v155
	v_fmac_f32_e32 v162, v159, v154
	v_exp_f32_e32 v161, v161
	v_exp_f32_e32 v163, v163
	v_exp_f32_e32 v157, v157
	v_exp_f32_e32 v158, v162
	v_cndmask_b32_e64 v160, 0, v152, s[4:5]
	s_cselect_b32 s4, 0xffffffc0, 0
	s_and_b64 s[2:3], s[2:3], exec
	v_cndmask_b32_e32 v156, 0, v152, vcc
	s_cselect_b32 s2, 0xffffffc0, 0
	v_ldexp_f32 v161, v161, s4
	v_ldexp_f32 v162, v163, s2
	v_ldexp_f32 v163, v157, v160
	v_ldexp_f32 v156, v158, v156
	v_mul_f32_e32 v164, v161, v163
	v_mul_f32_e32 v157, v162, v156
	v_mul_f32_e32 v158, v124, v163
	v_mul_f32_e32 v165, v124, v156
	v_mul_f32_e32 v166, v161, v164
	v_mul_f32_e32 v124, v162, v157
	v_mul_f32_e32 v159, v125, v164
	v_mul_f32_e32 v167, v125, v157
	v_mul_f32_e32 v168, v161, v166
	v_mul_f32_e32 v125, v162, v124
	v_cvt_pk_bf16_f32 v158, v158, v159
	v_mul_f32_e32 v159, v126, v166
	v_mul_f32_e32 v169, v126, v124
	v_mul_f32_e32 v170, v161, v168
	v_mul_f32_e32 v126, v162, v125
	v_mul_f32_e32 v171, v161, v170
	v_mul_f32_e32 v172, v162, v126
	v_mul_f32_e32 v160, v127, v168
	v_mul_f32_e32 v174, v161, v171
	v_mul_f32_e32 v175, v162, v172
	v_cvt_pk_bf16_f32 v159, v159, v160
	v_mul_f32_e32 v160, v120, v170
	v_mul_f32_e32 v173, v120, v126
	v_mul_f32_e32 v120, v121, v171
	v_mul_f32_e32 v177, v161, v174
	v_mul_f32_e32 v162, v162, v175
	v_mul_f32_e32 v176, v121, v172
	v_cvt_pk_bf16_f32 v160, v160, v120
	v_mul_f32_e32 v120, v122, v174
	v_mul_f32_e32 v121, v123, v177
	v_mul_f32_e32 v123, v123, v162
	v_cvt_pk_bf16_f32 v161, v120, v121
	v_mul_f32_e32 v127, v127, v125
	v_mul_f32_e32 v178, v122, v175
	v_cvt_pk_bf16_f32 v120, v165, v167
	v_cvt_pk_bf16_f32 v121, v169, v127
	v_cvt_pk_bf16_f32 v122, v173, v176
	v_cvt_pk_bf16_f32 v123, v178, v123
	global_store_dwordx4 v[140:141], v[158:161], off
	global_store_dwordx4 v[144:145], v[120:123], off
	s_nop 1
	v_mul_f32_e32 v120, v116, v163
	v_mul_f32_e32 v121, v117, v164
	v_cvt_pk_bf16_f32 v120, v120, v121
	v_mul_f32_e32 v121, v118, v166
	v_mul_f32_e32 v122, v119, v168
	v_cvt_pk_bf16_f32 v121, v121, v122
	v_mul_f32_e32 v122, v112, v170
	v_mul_f32_e32 v123, v113, v171
	v_cvt_pk_bf16_f32 v122, v122, v123
	v_mul_f32_e32 v123, v114, v174
	v_mul_f32_e32 v116, v116, v156
	v_mul_f32_e32 v117, v117, v157
	v_mul_f32_e32 v127, v115, v177
	v_cvt_pk_bf16_f32 v123, v123, v127
	v_cvt_pk_bf16_f32 v116, v116, v117
	v_mul_f32_e32 v117, v118, v124
	v_mul_f32_e32 v118, v119, v125
	v_mul_f32_e32 v112, v112, v126
	v_mul_f32_e32 v113, v113, v172
	v_cvt_pk_bf16_f32 v117, v117, v118
	v_cvt_pk_bf16_f32 v118, v112, v113
	v_mul_f32_e32 v112, v114, v175
	v_mul_f32_e32 v113, v115, v162
	v_cvt_pk_bf16_f32 v119, v112, v113
	global_store_dwordx4 v[140:141], v[120:123], off offset:256
	global_store_dwordx4 v[142:143], v[116:119], off offset:256
	v_mul_f32_e32 v112, v108, v163
	v_mul_f32_e32 v113, v109, v164
	v_cvt_pk_bf16_f32 v112, v112, v113
	v_mul_f32_e32 v113, v110, v166
	v_mul_f32_e32 v114, v111, v168
	v_cvt_pk_bf16_f32 v113, v113, v114
	v_mul_f32_e32 v114, v104, v170
	v_mul_f32_e32 v115, v105, v171
	v_cvt_pk_bf16_f32 v114, v114, v115
	v_mul_f32_e32 v115, v106, v174
	v_mul_f32_e32 v108, v108, v156
	v_mul_f32_e32 v109, v109, v157
	v_mul_f32_e32 v116, v107, v177
	v_cvt_pk_bf16_f32 v115, v115, v116
	v_cvt_pk_bf16_f32 v108, v108, v109
	v_mul_f32_e32 v109, v110, v124
	v_mul_f32_e32 v110, v111, v125
	v_mul_f32_e32 v104, v104, v126
	s_mov_b64 s[2:3], 0x40000
	v_cvt_pk_bf16_f32 v109, v109, v110
	v_mul_f32_e32 v105, v105, v172
	v_cvt_pk_bf16_f32 v110, v104, v105
	v_mul_f32_e32 v104, v106, v175
	v_lshl_add_u64 v[116:117], v[140:141], 0, s[2:3]
	s_mov_b32 s2, 0x40000
	v_mul_f32_e32 v105, v107, v162
	v_cvt_pk_bf16_f32 v111, v104, v105
	v_add_co_u32_e32 v104, vcc, s2, v140
	s_mov_b64 s[2:3], 0x440000
	s_nop 0
	v_addc_co_u32_e32 v105, vcc, 0, v141, vcc
	global_store_dwordx4 v[104:105], v[112:115], off
	s_nop 1
	v_lshl_add_u64 v[112:113], v[140:141], 0, s[2:3]
	s_mov_b32 s2, 0x440000
	v_add_co_u32_e32 v104, vcc, s2, v140
	s_nop 1
	v_addc_co_u32_e32 v105, vcc, 0, v141, vcc
	global_store_dwordx4 v[104:105], v[108:111], off
	v_mul_f32_e32 v104, v100, v163
	v_mul_f32_e32 v105, v101, v164
	v_cvt_pk_bf16_f32 v104, v104, v105
	v_mul_f32_e32 v105, v102, v166
	v_mul_f32_e32 v106, v103, v168
	v_cvt_pk_bf16_f32 v105, v105, v106
;     __device__ __forceinline__ void operator()(const AccT& acc, const Unit& u, int wr, int wc, int fr, int fq) const {
;     ...
;             for (int m = 0; m < 4; ++m) {
;                 const int r = rbase + ai * 128 + m * 16;
;                 const int d = 4 * (2 * m + (fr >> 3)) + j;
; #pragma unroll
;                 for (int bj = 0; bj < 2; ++bj) {
;                     const int t0 = tb + bj * 128;
;                     float v[8];
; #pragma unroll
;                     for (int jj = 0; jj < 4; ++jj) { v[jj] = acc[ai][bj][m][0][jj]; v[4 + jj] = acc[ai][bj][m][1][jj]; }
;                     if constexpr (ROPE) {
;                         const int t = t0 & 2047;
; #pragma unroll
;                         for (int hf = 0; hf < 2; ++hf) {
;                             f32x4 cs, sn;
;                             if (m < 2) { const float c1 = ropeA[(t >> 6) * 16 + d], s1 = ropeA[1024 + (t >> 6) * 16 + d]; cs = (f32x4){c1, c1, c1, c1}; sn = (f32x4){s1, s1, s1, s1}; }
;                             else { const float* cb = ropeA + 2048 + (d - 16) * 64 + (t & 63) + 4 * hf; cs = *(const f32x4*)(cb); sn = *(const f32x4*)(cb + 1024); }
; #pragma unroll
;                             for (int jj = 0; jj < 4; ++jj) { const float pr = __shfl_xor(v[4 * hf + jj], 4); v[4 * hf + jj] = v[4 * hf + jj] * cs[jj] + sgn * pr * sn[jj]; }
;                             __builtin_amdgcn_sched_barrier(0);
;                         }
;                     }
;                     float zf[8], zb[8]; zf[0] = zf0; zb[0] = zb0;
; #pragma unroll
;                     for (int jj = 1; jj < 8; ++jj) { zf[jj] = zf[jj - 1] * zfs; zb[jj] = zb[jj - 1] * zbs; }
;                     u32x4 wf, wb;
;                     wf.x = cvt_pk_bf16(v[0] * zf[0], v[1] * zf[1]); wf.y = cvt_pk_bf16(v[2] * zf[2], v[3] * zf[3]); wf.z = cvt_pk_bf16(v[4] * zf[4], v[5] * zf[5]); wf.w = cvt_pk_bf16(v[6] * zf[6], v[7] * zf[7]);
;                     wb.x = cvt_pk_bf16(v[0] * zb[0], v[1] * zb[1]); wb.y = cvt_pk_bf16(v[2] * zb[2], v[3] * zb[3]); wb.z = cvt_pk_bf16(v[4] * zb[4], v[5] * zb[5]); wb.w = cvt_pk_bf16(v[6] * zb[6], v[7] * zb[7]);
;                     *(u32x4*)(KTZ + (size_t)r * NT + t0) = wf;
;                     *(u32x4*)(KTZ + (size_t)(256 + r) * NT + t0) = wb;
	v_mul_f32_e32 v106, v96, v170
	v_mul_f32_e32 v107, v97, v171
	v_cvt_pk_bf16_f32 v106, v106, v107
	v_mul_f32_e32 v107, v98, v174
	v_mul_f32_e32 v100, v100, v156
	v_mul_f32_e32 v101, v101, v157
	v_mul_f32_e32 v108, v99, v177
	v_cvt_pk_bf16_f32 v107, v107, v108
	v_cvt_pk_bf16_f32 v100, v100, v101
	v_mul_f32_e32 v101, v102, v124
	v_mul_f32_e32 v102, v103, v125
	v_mul_f32_e32 v96, v96, v126
	v_mul_f32_e32 v97, v97, v172
	v_cvt_pk_bf16_f32 v101, v101, v102
	v_cvt_pk_bf16_f32 v102, v96, v97
	v_mul_f32_e32 v96, v98, v175
	v_mul_f32_e32 v97, v99, v162
	v_cvt_pk_bf16_f32 v103, v96, v97
	global_store_dwordx4 v[116:117], v[104:107], off offset:256
	global_store_dwordx4 v[112:113], v[100:103], off offset:256
	v_mul_f32_e32 v96, v92, v163
	v_mul_f32_e32 v97, v93, v164
	v_cvt_pk_bf16_f32 v96, v96, v97
	v_mul_f32_e32 v97, v94, v166
	v_mul_f32_e32 v98, v95, v168
	v_cvt_pk_bf16_f32 v97, v97, v98
	v_mul_f32_e32 v98, v88, v170
	v_mul_f32_e32 v99, v89, v171
	v_cvt_pk_bf16_f32 v98, v98, v99
	v_mul_f32_e32 v99, v90, v174
	v_mul_f32_e32 v92, v92, v156
	v_mul_f32_e32 v93, v93, v157
	v_mul_f32_e32 v100, v91, v177
	v_cvt_pk_bf16_f32 v99, v99, v100
	v_cvt_pk_bf16_f32 v92, v92, v93
	v_mul_f32_e32 v93, v94, v124
	v_mul_f32_e32 v94, v95, v125
	v_mul_f32_e32 v88, v88, v126
	s_mov_b64 s[2:3], 0x80000
	v_cvt_pk_bf16_f32 v93, v93, v94
	v_mul_f32_e32 v89, v89, v172
	v_cvt_pk_bf16_f32 v94, v88, v89
	v_mul_f32_e32 v88, v90, v175
	v_lshl_add_u64 v[100:101], v[140:141], 0, s[2:3]
	s_mov_b32 s2, 0x80000
	v_mul_f32_e32 v89, v91, v162
	v_cvt_pk_bf16_f32 v95, v88, v89
	v_add_co_u32_e32 v88, vcc, s2, v140
	s_mov_b64 s[2:3], 0x480000
	s_nop 0
	v_addc_co_u32_e32 v89, vcc, 0, v141, vcc
	global_store_dwordx4 v[88:89], v[96:99], off
	s_nop 1
	v_lshl_add_u64 v[96:97], v[140:141], 0, s[2:3]
	s_mov_b32 s2, 0x480000
	v_add_co_u32_e32 v88, vcc, s2, v140
	s_nop 1
	v_addc_co_u32_e32 v89, vcc, 0, v141, vcc
	global_store_dwordx4 v[88:89], v[92:95], off
	v_mul_f32_e32 v88, v84, v163
	v_mul_f32_e32 v89, v85, v164
	v_cvt_pk_bf16_f32 v88, v88, v89
	v_mul_f32_e32 v89, v86, v166
	v_mul_f32_e32 v90, v87, v168
	v_cvt_pk_bf16_f32 v89, v89, v90
	v_mul_f32_e32 v90, v80, v170
	v_mul_f32_e32 v91, v81, v171
	v_cvt_pk_bf16_f32 v90, v90, v91
	v_mul_f32_e32 v91, v82, v174
	v_mul_f32_e32 v84, v84, v156
	v_mul_f32_e32 v85, v85, v157
	v_mul_f32_e32 v92, v83, v177
	v_cvt_pk_bf16_f32 v91, v91, v92
	v_cvt_pk_bf16_f32 v84, v84, v85
	v_mul_f32_e32 v85, v86, v124
	v_mul_f32_e32 v86, v87, v125
	v_mul_f32_e32 v80, v80, v126
	v_mul_f32_e32 v81, v81, v172
	v_cvt_pk_bf16_f32 v85, v85, v86
	v_cvt_pk_bf16_f32 v86, v80, v81
	v_mul_f32_e32 v80, v82, v175
	v_mul_f32_e32 v81, v83, v162
	v_cvt_pk_bf16_f32 v87, v80, v81
	global_store_dwordx4 v[100:101], v[88:91], off offset:256
	global_store_dwordx4 v[96:97], v[84:87], off offset:256
	v_mul_f32_e32 v80, v76, v163
	v_mul_f32_e32 v81, v77, v164
	v_cvt_pk_bf16_f32 v80, v80, v81
	v_mul_f32_e32 v81, v78, v166
	v_mul_f32_e32 v82, v79, v168
	v_cvt_pk_bf16_f32 v81, v81, v82
	v_mul_f32_e32 v82, v72, v170
	v_mul_f32_e32 v83, v73, v171
	v_cvt_pk_bf16_f32 v82, v82, v83
	v_mul_f32_e32 v83, v74, v174
	v_mul_f32_e32 v76, v76, v156
	v_mul_f32_e32 v77, v77, v157
	v_mul_f32_e32 v84, v75, v177
	v_cvt_pk_bf16_f32 v83, v83, v84
	v_cvt_pk_bf16_f32 v76, v76, v77
	v_mul_f32_e32 v77, v78, v124
	v_mul_f32_e32 v78, v79, v125
	v_mul_f32_e32 v72, v72, v126
	s_mov_b64 s[2:3], 0xc0000
	v_cvt_pk_bf16_f32 v77, v77, v78
	v_mul_f32_e32 v73, v73, v172
	v_cvt_pk_bf16_f32 v78, v72, v73
	v_mul_f32_e32 v72, v74, v175
	v_lshl_add_u64 v[84:85], v[140:141], 0, s[2:3]
	s_mov_b32 s2, 0xc0000
	v_mul_f32_e32 v73, v75, v162
	v_cvt_pk_bf16_f32 v79, v72, v73
	v_add_co_u32_e32 v72, vcc, s2, v140
	s_mov_b64 s[2:3], 0x4c0000
	s_nop 0
	v_addc_co_u32_e32 v73, vcc, 0, v141, vcc
	global_store_dwordx4 v[72:73], v[80:83], off
	s_nop 1
	v_lshl_add_u64 v[80:81], v[140:141], 0, s[2:3]
	s_mov_b32 s2, 0x4c0000
	v_add_co_u32_e32 v72, vcc, s2, v140
	s_nop 1
	v_addc_co_u32_e32 v73, vcc, 0, v141, vcc
	global_store_dwordx4 v[72:73], v[76:79], off
	v_mul_f32_e32 v72, v68, v163
	v_mul_f32_e32 v73, v69, v164
	v_cvt_pk_bf16_f32 v72, v72, v73
	v_mul_f32_e32 v73, v70, v166
	v_mul_f32_e32 v74, v71, v168
	v_cvt_pk_bf16_f32 v73, v73, v74
	v_mul_f32_e32 v74, v64, v170
	v_mul_f32_e32 v75, v65, v171
	v_cvt_pk_bf16_f32 v74, v74, v75
	v_mul_f32_e32 v75, v66, v174
	v_mul_f32_e32 v68, v68, v156
	v_mul_f32_e32 v69, v69, v157
	v_mul_f32_e32 v76, v67, v177
	v_cvt_pk_bf16_f32 v75, v75, v76
	v_cvt_pk_bf16_f32 v68, v68, v69
	v_mul_f32_e32 v69, v70, v124
	v_mul_f32_e32 v70, v71, v125
	v_mul_f32_e32 v64, v64, v126
	v_mul_f32_e32 v65, v65, v172
	v_cvt_pk_bf16_f32 v69, v69, v70
	v_cvt_pk_bf16_f32 v70, v64, v65
	v_mul_f32_e32 v64, v66, v175
	v_mul_f32_e32 v65, v67, v162
	v_cvt_pk_bf16_f32 v71, v64, v65
	global_store_dwordx4 v[84:85], v[72:75], off offset:256
	global_store_dwordx4 v[80:81], v[68:71], off offset:256
	global_load_dword v70, v131, s[6:7] offset:8
	s_nop 0
	global_load_dword v71, v131, s[6:7] offset:24
	s_mov_b32 s17, 0x200000
	v_add_co_u32_e32 v76, vcc, s17, v140
	s_mov_b32 s19, 0x600000
	s_nop 0
	v_addc_co_u32_e32 v77, vcc, 0, v141, vcc
	v_add_co_u32_e32 v68, vcc, s19, v140
	s_mov_b64 s[2:3], 0x200000
	s_nop 0
	v_addc_co_u32_e32 v69, vcc, 0, v141, vcc
	s_mov_b64 s[4:5], 0x600000
	v_lshl_add_u64 v[64:65], v[140:141], 0, s[2:3]
	v_lshl_add_u64 v[66:67], v[140:141], 0, s[4:5]
	s_waitcnt vmcnt(0)
;     __device__ __forceinline__ void operator()(const AccT& acc, const Unit& u, int wr, int wc, int fr, int fq) const {
;     ...
;         for (int ai = 0; ai < 2; ++ai) {
;             const int hh = 2 * ai + wr;
;             const float l2f = lgd[hh] * 1.4426950408889634f, l2b = lgd[4 + hh] * 1.4426950408889634f;
;             const float zf0 = exp2f((float)(127 - o0) * l2f), zfs = exp2f(-l2f), zb0 = exp2f((float)o0 * l2b), zbs = exp2f(l2b);
; #pragma unroll
;             for (int m = 0; m < 4; ++m) {
;                 const int r = rbase + ai * 128 + m * 16;
;                 const int d = 4 * (2 * m + (fr >> 3)) + j;
; #pragma unroll
;                 for (int bj = 0; bj < 2; ++bj) {
;                     const int t0 = tb + bj * 128;
;                     float v[8];
; #pragma unroll
;                     for (int jj = 0; jj < 4; ++jj) { v[jj] = acc[ai][bj][m][0][jj]; v[4 + jj] = acc[ai][bj][m][1][jj]; }
;                     if constexpr (ROPE) {
;                         const int t = t0 & 2047;
; #pragma unroll
;                         for (int hf = 0; hf < 2; ++hf) {
;                             f32x4 cs, sn;
;                             if (m < 2) { const float c1 = ropeA[(t >> 6) * 16 + d], s1 = ropeA[1024 + (t >> 6) * 16 + d]; cs = (f32x4){c1, c1, c1, c1}; sn = (f32x4){s1, s1, s1, s1}; }
;                             else { const float* cb = ropeA + 2048 + (d - 16) * 64 + (t & 63) + 4 * hf; cs = *(const f32x4*)(cb); sn = *(const f32x4*)(cb + 1024); }
; #pragma unroll
;                             for (int jj = 0; jj < 4; ++jj) { const float pr = __shfl_xor(v[4 * hf + jj], 4); v[4 * hf + jj] = v[4 * hf + jj] * cs[jj] + sgn * pr * sn[jj]; }
;                             __builtin_amdgcn_sched_barrier(0);
;                         }
;                     }
;                     float zf[8], zb[8]; zf[0] = zf0; zb[0] = zb0;
; #pragma unroll
;                     for (int jj = 1; jj < 8; ++jj) { zf[jj] = zf[jj - 1] * zfs; zb[jj] = zb[jj - 1] * zbs; }
;                     u32x4 wf, wb;
;                     wf.x = cvt_pk_bf16(v[0] * zf[0], v[1] * zf[1]); wf.y = cvt_pk_bf16(v[2] * zf[2], v[3] * zf[3]); wf.z = cvt_pk_bf16(v[4] * zf[4], v[5] * zf[5]); wf.w = cvt_pk_bf16(v[6] * zf[6], v[7] * zf[7]);
	v_mul_f32_e32 v72, 0x3fb8aa3b, v70
	v_mul_f32_e32 v73, 0x3fb8aa3b, v71
	v_mul_f32_e32 v74, v72, v155
	v_cmp_lt_f32_e32 vcc, s51, v72
	v_mul_f32_e32 v78, v73, v154
	v_cmp_gt_f32_e64 s[2:3], s49, v73
	v_cndmask_b32_e32 v75, 0, v153, vcc
	v_cmp_gt_f32_e64 s[4:5], s49, v74
	v_cndmask_b32_e64 v79, 0, v153, s[2:3]
	s_and_b64 s[24:25], vcc, exec
	v_cmp_gt_f32_e32 vcc, s49, v78
	v_fmac_f32_e32 v79, 0x3fb8aa3b, v71
	v_cndmask_b32_e64 v71, 0, v153, s[4:5]
	v_cndmask_b32_e32 v78, 0, v153, vcc
	v_fmac_f32_e32 v75, 0xbfb8aa3b, v70
	v_fmac_f32_e32 v71, v72, v155
	v_fmac_f32_e32 v78, v73, v154
	v_exp_f32_e32 v75, v75
	v_exp_f32_e32 v79, v79
	v_exp_f32_e32 v71, v71
	v_exp_f32_e32 v72, v78
	v_cndmask_b32_e64 v74, 0, v152, s[4:5]
	s_cselect_b32 s4, 0xffffffc0, 0
	s_and_b64 s[2:3], s[2:3], exec
	v_cndmask_b32_e32 v70, 0, v152, vcc
	s_cselect_b32 s2, 0xffffffc0, 0
	v_ldexp_f32 v75, v75, s4
	v_ldexp_f32 v78, v79, s2
	v_ldexp_f32 v79, v71, v74
	v_ldexp_f32 v70, v72, v70
	v_mul_f32_e32 v80, v75, v79
	v_mul_f32_e32 v71, v78, v70
	v_mul_f32_e32 v72, v60, v79
	v_mul_f32_e32 v81, v60, v70
	v_mul_f32_e32 v82, v75, v80
	v_mul_f32_e32 v60, v78, v71
	v_mul_f32_e32 v83, v75, v82
	v_mul_f32_e32 v84, v78, v60
	v_mul_f32_e32 v85, v75, v83
	v_mul_f32_e32 v86, v78, v84
	v_mul_f32_e32 v73, v61, v80
	v_mul_f32_e32 v87, v75, v85
	v_mul_f32_e32 v88, v78, v86
	v_cvt_pk_bf16_f32 v72, v72, v73
	v_mul_f32_e32 v73, v62, v82
	v_mul_f32_e32 v74, v63, v83
	v_mul_f32_e32 v90, v75, v87
	v_mul_f32_e32 v91, v78, v88
	v_cvt_pk_bf16_f32 v73, v73, v74
	v_mul_f32_e32 v74, v56, v85
	v_mul_f32_e32 v89, v56, v86
	v_mul_f32_e32 v56, v57, v87
	v_mul_f32_e32 v93, v75, v90
	v_mul_f32_e32 v78, v78, v91
	v_mul_f32_e32 v92, v57, v88
	v_cvt_pk_bf16_f32 v74, v74, v56
	v_mul_f32_e32 v56, v58, v90
	v_mul_f32_e32 v57, v59, v93
	v_mul_f32_e32 v59, v59, v78
	v_cvt_pk_bf16_f32 v75, v56, v57
	v_mul_f32_e32 v61, v61, v71
	v_mul_f32_e32 v62, v62, v60
	v_mul_f32_e32 v63, v63, v84
	v_mul_f32_e32 v94, v58, v91
	v_cvt_pk_bf16_f32 v56, v81, v61
	v_cvt_pk_bf16_f32 v57, v62, v63
	v_cvt_pk_bf16_f32 v58, v89, v92
	v_cvt_pk_bf16_f32 v59, v94, v59
	global_store_dwordx4 v[76:77], v[72:75], off
	global_store_dwordx4 v[68:69], v[56:59], off
	s_nop 1
	v_mul_f32_e32 v56, v52, v79
	v_mul_f32_e32 v57, v53, v80
	v_cvt_pk_bf16_f32 v56, v56, v57
	v_mul_f32_e32 v57, v54, v82
	v_mul_f32_e32 v58, v55, v83
	v_cvt_pk_bf16_f32 v57, v57, v58
	v_mul_f32_e32 v58, v48, v85
	v_mul_f32_e32 v59, v49, v87
	v_cvt_pk_bf16_f32 v58, v58, v59
	v_mul_f32_e32 v59, v50, v90
	v_mul_f32_e32 v52, v52, v70
	v_mul_f32_e32 v53, v53, v71
	v_mul_f32_e32 v61, v51, v93
	v_cvt_pk_bf16_f32 v59, v59, v61
	v_cvt_pk_bf16_f32 v52, v52, v53
	v_mul_f32_e32 v53, v54, v60
	v_mul_f32_e32 v54, v55, v84
	v_mul_f32_e32 v48, v48, v86
	v_mul_f32_e32 v49, v49, v88
	v_cvt_pk_bf16_f32 v53, v53, v54
	v_cvt_pk_bf16_f32 v54, v48, v49
	v_mul_f32_e32 v48, v50, v91
	v_mul_f32_e32 v49, v51, v78
	v_cvt_pk_bf16_f32 v55, v48, v49
	global_store_dwordx4 v[64:65], v[56:59], off offset:256
	global_store_dwordx4 v[66:67], v[52:55], off offset:256
	v_mul_f32_e32 v48, v44, v79
	v_mul_f32_e32 v49, v45, v80
	v_cvt_pk_bf16_f32 v48, v48, v49
	v_mul_f32_e32 v49, v46, v82
	v_mul_f32_e32 v50, v47, v83
	v_cvt_pk_bf16_f32 v49, v49, v50
	v_mul_f32_e32 v50, v40, v85
	v_mul_f32_e32 v51, v41, v87
	v_cvt_pk_bf16_f32 v50, v50, v51
	v_mul_f32_e32 v51, v42, v90
	v_mul_f32_e32 v44, v44, v70
	v_mul_f32_e32 v45, v45, v71
	v_mul_f32_e32 v52, v43, v93
	v_cvt_pk_bf16_f32 v51, v51, v52
	v_cvt_pk_bf16_f32 v44, v44, v45
	v_mul_f32_e32 v45, v46, v60
	v_mul_f32_e32 v46, v47, v84
	v_mul_f32_e32 v40, v40, v86
	s_mov_b64 s[2:3], 0x240000
	v_cvt_pk_bf16_f32 v45, v45, v46
	v_mul_f32_e32 v41, v41, v88
	v_cvt_pk_bf16_f32 v46, v40, v41
	v_mul_f32_e32 v40, v42, v91
	v_lshl_add_u64 v[52:53], v[140:141], 0, s[2:3]
	s_mov_b32 s2, 0x240000
	v_mul_f32_e32 v41, v43, v78
	v_cvt_pk_bf16_f32 v47, v40, v41
	v_add_co_u32_e32 v40, vcc, s2, v140
	s_mov_b64 s[2:3], 0x640000
	s_nop 0
	v_addc_co_u32_e32 v41, vcc, 0, v141, vcc
	global_store_dwordx4 v[40:41], v[48:51], off
	s_nop 1
	v_lshl_add_u64 v[48:49], v[140:141], 0, s[2:3]
	s_mov_b32 s2, 0x640000
	v_add_co_u32_e32 v40, vcc, s2, v140
	s_nop 1
	v_addc_co_u32_e32 v41, vcc, 0, v141, vcc
	global_store_dwordx4 v[40:41], v[44:47], off
	v_mul_f32_e32 v40, v36, v79
	v_mul_f32_e32 v41, v37, v80
	v_cvt_pk_bf16_f32 v40, v40, v41
	v_mul_f32_e32 v41, v38, v82
	v_mul_f32_e32 v42, v39, v83
	v_cvt_pk_bf16_f32 v41, v41, v42
	v_mul_f32_e32 v42, v32, v85
	v_mul_f32_e32 v43, v33, v87
	v_cvt_pk_bf16_f32 v42, v42, v43
	v_mul_f32_e32 v43, v34, v90
	v_mul_f32_e32 v36, v36, v70
; __device__ __forceinline__ unsigned cvt_pk_bf16(float lo, float hi) { unsigned r; asm volatile("v_cvt_pk_bf16_f32 %0, %1, %2" : "=v"(r) : "v"(lo), "v"(hi)); return r; }
; #define PG8_WAIT_V(n) asm volatile("s_waitcnt vmcnt(" #n ")" ::: "memory")
; #define PG8_BAR __builtin_amdgcn_s_barrier()
; template <class Epi, class Sched>
; __device__ __forceinline__ void gemm_phase(LAS unsigned char* lds, const Gemm g, const Sched& S, const Epi& E) {
;     ...
;         E(acc, cur, wr, wc, fr, fq);
;         if (!has_next) break;
; #pragma unroll
;         for (int a = 0; a < 2; ++a)
; #pragma unroll
;             for (int b = 0; b < 2; ++b)
; #pragma unroll
;                 for (int m = 0; m < 4; ++m)
; #pragma unroll
;                     for (int n = 0; n < 2; ++n) acc[a][b][m][n] = (f32x4){0.f, 0.f, 0.f, 0.f};
;         cur = nxt; cA = nA; cB = nB; ++ui;
;     }
;     PG8_WAIT_V(0);
;     if (wr == 0) PG8_BAR;
;     PG8_BAR;
;     __device__ __forceinline__ void operator()(const AccT& acc, const Unit& u, int wr, int wc, int fr, int fq) const {
;     ...
;                     for (int jj = 1; jj < 8; ++jj) { zf[jj] = zf[jj - 1] * zfs; zb[jj] = zb[jj - 1] * zbs; }
;                     u32x4 wf, wb;
;                     wf.x = cvt_pk_bf16(v[0] * zf[0], v[1] * zf[1]); wf.y = cvt_pk_bf16(v[2] * zf[2], v[3] * zf[3]); wf.z = cvt_pk_bf16(v[4] * zf[4], v[5] * zf[5]); wf.w = cvt_pk_bf16(v[6] * zf[6], v[7] * zf[7]);
;                     wb.x = cvt_pk_bf16(v[0] * zb[0], v[1] * zb[1]); wb.y = cvt_pk_bf16(v[2] * zb[2], v[3] * zb[3]); wb.z = cvt_pk_bf16(v[4] * zb[4], v[5] * zb[5]); wb.w = cvt_pk_bf16(v[6] * zb[6], v[7] * zb[7]);
;                     *(u32x4*)(KTZ + (size_t)r * NT + t0) = wf;
;                     *(u32x4*)(KTZ + (size_t)(256 + r) * NT + t0) = wb;
;                     __builtin_amdgcn_sched_barrier(0);
;                 }
	v_mul_f32_e32 v37, v37, v71
	v_mul_f32_e32 v44, v35, v93
	v_cvt_pk_bf16_f32 v43, v43, v44
	v_cvt_pk_bf16_f32 v36, v36, v37
	v_mul_f32_e32 v37, v38, v60
	v_mul_f32_e32 v38, v39, v84
	v_mul_f32_e32 v32, v32, v86
	v_mul_f32_e32 v33, v33, v88
	v_cvt_pk_bf16_f32 v37, v37, v38
	v_cvt_pk_bf16_f32 v38, v32, v33
	v_mul_f32_e32 v32, v34, v91
	v_mul_f32_e32 v33, v35, v78
	v_cvt_pk_bf16_f32 v39, v32, v33
	global_store_dwordx4 v[52:53], v[40:43], off offset:256
	global_store_dwordx4 v[48:49], v[36:39], off offset:256
	v_mul_f32_e32 v32, v28, v79
	v_mul_f32_e32 v33, v29, v80
	v_cvt_pk_bf16_f32 v32, v32, v33
	v_mul_f32_e32 v33, v30, v82
	v_mul_f32_e32 v34, v31, v83
	v_cvt_pk_bf16_f32 v33, v33, v34
	v_mul_f32_e32 v34, v24, v85
	v_mul_f32_e32 v35, v25, v87
	v_cvt_pk_bf16_f32 v34, v34, v35
	v_mul_f32_e32 v35, v26, v90
	v_mul_f32_e32 v28, v28, v70
	v_mul_f32_e32 v29, v29, v71
	v_mul_f32_e32 v36, v27, v93
	v_cvt_pk_bf16_f32 v35, v35, v36
	v_cvt_pk_bf16_f32 v28, v28, v29
	v_mul_f32_e32 v29, v30, v60
	v_mul_f32_e32 v30, v31, v84
	v_mul_f32_e32 v24, v24, v86
	v_cvt_pk_bf16_f32 v29, v29, v30
	v_mul_f32_e32 v25, v25, v88
	v_cvt_pk_bf16_f32 v30, v24, v25
	v_mul_f32_e32 v24, v26, v91
	v_mul_f32_e32 v25, v27, v78
	v_cvt_pk_bf16_f32 v31, v24, v25
	v_add_co_u32_e32 v24, vcc, s52, v140
	s_mov_b64 s[2:3], 0x280000
	s_nop 0
	v_addc_co_u32_e32 v25, vcc, 0, v141, vcc
	global_store_dwordx4 v[24:25], v[32:35], off
	v_add_co_u32_e32 v24, vcc, s53, v140
	v_lshl_add_u64 v[36:37], v[140:141], 0, s[2:3]
	s_nop 0
	v_addc_co_u32_e32 v25, vcc, 0, v141, vcc
	v_lshl_add_u64 v[32:33], v[140:141], 0, s[8:9]
	global_store_dwordx4 v[24:25], v[28:31], off
	v_mul_f32_e32 v24, v20, v79
	v_mul_f32_e32 v25, v21, v80
	v_cvt_pk_bf16_f32 v24, v24, v25
	v_mul_f32_e32 v25, v22, v82
	v_mul_f32_e32 v26, v23, v83
	v_cvt_pk_bf16_f32 v25, v25, v26
	v_mul_f32_e32 v26, v16, v85
	v_mul_f32_e32 v27, v17, v87
	v_cvt_pk_bf16_f32 v26, v26, v27
	v_mul_f32_e32 v27, v18, v90
	v_mul_f32_e32 v20, v20, v70
	v_mul_f32_e32 v21, v21, v71
	v_mul_f32_e32 v28, v19, v93
	v_cvt_pk_bf16_f32 v27, v27, v28
	v_cvt_pk_bf16_f32 v20, v20, v21
	v_mul_f32_e32 v21, v22, v60
	v_mul_f32_e32 v22, v23, v84
	v_mul_f32_e32 v16, v16, v86
	v_mul_f32_e32 v17, v17, v88
	v_cvt_pk_bf16_f32 v21, v21, v22
	v_cvt_pk_bf16_f32 v22, v16, v17
	v_mul_f32_e32 v16, v18, v91
	v_mul_f32_e32 v17, v19, v78
	v_cvt_pk_bf16_f32 v23, v16, v17
	global_store_dwordx4 v[36:37], v[24:27], off offset:256
	global_store_dwordx4 v[32:33], v[20:23], off offset:256
	v_mul_f32_e32 v16, v12, v79
	v_mul_f32_e32 v17, v13, v80
	v_cvt_pk_bf16_f32 v16, v16, v17
	v_mul_f32_e32 v17, v14, v82
	v_mul_f32_e32 v18, v15, v83
	v_cvt_pk_bf16_f32 v17, v17, v18
	v_mul_f32_e32 v18, v8, v85
	v_mul_f32_e32 v19, v9, v87
	v_cvt_pk_bf16_f32 v18, v18, v19
	v_mul_f32_e32 v19, v10, v90
	v_mul_f32_e32 v12, v12, v70
	v_mul_f32_e32 v13, v13, v71
	v_mul_f32_e32 v20, v11, v93
	v_cvt_pk_bf16_f32 v19, v19, v20
	v_cvt_pk_bf16_f32 v12, v12, v13
	v_mul_f32_e32 v13, v14, v60
	v_mul_f32_e32 v14, v15, v84
	v_mul_f32_e32 v8, v8, v86
	v_cvt_pk_bf16_f32 v13, v13, v14
	v_mul_f32_e32 v9, v9, v88
	v_cvt_pk_bf16_f32 v14, v8, v9
	v_mul_f32_e32 v8, v10, v91
	v_mul_f32_e32 v9, v11, v78
	v_cvt_pk_bf16_f32 v15, v8, v9
	v_add_co_u32_e32 v8, vcc, s54, v140
	v_lshl_add_u64 v[20:21], v[140:141], 0, s[10:11]
	s_nop 0
	v_addc_co_u32_e32 v9, vcc, 0, v141, vcc
	global_store_dwordx4 v[8:9], v[16:19], off
	v_add_co_u32_e32 v8, vcc, s55, v140
	s_nop 0
	v_lshl_add_u64 v[16:17], v[140:141], 0, s[12:13]
	v_addc_co_u32_e32 v9, vcc, 0, v141, vcc
	global_store_dwordx4 v[8:9], v[12:15], off
	v_mul_f32_e32 v8, v4, v79
	v_mul_f32_e32 v9, v5, v80
	v_cvt_pk_bf16_f32 v8, v8, v9
	v_mul_f32_e32 v9, v6, v82
	v_mul_f32_e32 v10, v7, v83
	v_cvt_pk_bf16_f32 v9, v9, v10
	v_mul_f32_e32 v10, v0, v85
	v_mul_f32_e32 v11, v1, v87
	v_cvt_pk_bf16_f32 v10, v10, v11
	v_mul_f32_e32 v11, v2, v90
	v_mul_f32_e32 v4, v4, v70
	v_mul_f32_e32 v5, v5, v71
	v_mul_f32_e32 v12, v3, v93
	v_cvt_pk_bf16_f32 v11, v11, v12
	v_cvt_pk_bf16_f32 v4, v4, v5
	v_mul_f32_e32 v5, v6, v60
	v_mul_f32_e32 v6, v7, v84
	v_mul_f32_e32 v0, v0, v86
	v_mul_f32_e32 v1, v1, v88
	v_cvt_pk_bf16_f32 v5, v5, v6
	v_cvt_pk_bf16_f32 v6, v0, v1
	v_mul_f32_e32 v0, v2, v91
	v_mul_f32_e32 v1, v3, v78
	v_cvt_pk_bf16_f32 v7, v0, v1
	global_store_dwordx4 v[20:21], v[8:11], off offset:256
	global_store_dwordx4 v[16:17], v[4:7], off offset:256
	s_and_b64 vcc, exec, s[14:15]
	s_mov_b32 s56, s16
	s_mov_b64 s[4:5], s[22:23]
	s_mov_b64 s[2:3], s[20:21]
	s_cbranch_vccz .LBB0_686
	s_waitcnt vmcnt(0)
	s_cmpk_gt_u32 s27, 0xff
	s_cbranch_scc1 .LBB0_697
	s_barrier

; #define PG8_STAGE(bufoff, gbase, voff) do { _Pragma("unroll") for (int _i = 0; _i < 2; ++_i) \
;         __builtin_amdgcn_global_load_lds((const unsigned*)((const char*)(gbase) + (voff)[_i]), (LAS unsigned*)(lds + (bufoff) + ldsw + _i * 8192), 16, 0, 0); } while (0)
; #define PG8_LDA(dst, b, h) do { _Pragma("unroll") for (int m = 0; m < 4; ++m) _Pragma("unroll") for (int k = 0; k < 2; ++k) dst[m][k] = *(const LAS bf16x8*)(lds + PG8_SA(b, h) + aoff + m * 2048 + k * 1024); } while (0)
; #define PG8_LDB(dst, b, h) do { _Pragma("unroll") for (int n = 0; n < 2; ++n) _Pragma("unroll") for (int k = 0; k < 2; ++k) dst[n][k] = *(const LAS bf16x8*)(lds + PG8_SB(b, h) + boff + n * 2048 + k * 1024); } while (0)
; #define PG8_MMA(ai, bj, At, Bt) do { __builtin_amdgcn_s_setprio(1); _Pragma("unroll") for (int m = 0; m < 4; ++m) _Pragma("unroll") for (int n = 0; n < 2; ++n) _Pragma("unroll") for (int k = 0; k < 2; ++k) \
;         acc[ai][bj][m][n] = __builtin_amdgcn_mfma_f32_16x16x32_bf16(Bt[n][k], At[m][k], acc[ai][bj][m][n], 0, 0, 0); __builtin_amdgcn_s_setprio(0); } while (0)
; #define PG8_WAIT_L(n) asm volatile("s_waitcnt lgkmcnt(" #n ")" ::: "memory")
; template <class Epi, class Sched>
; __device__ __forceinline__ void gemm_phase(LAS unsigned char* lds, const Gemm g, const Sched& S, const Epi& E) {
;     ...
;         const bool has_next = S.next(ui + 1, nxt);
;         const char* nA = has_next ? (const char*)g.A + (size_t)nxt.pm * tstep : cA; const char* nB = has_next ? (const char*)g.Bt + (size_t)nxt.pn * tstep : cB;
;         for (int t = 0; t < nt; t += 2) {
;             const bool last = (t == nt - 2);
;             const char* a1 = cA + (size_t)(t + 1) * kstep;
;             const char* a2 = last ? nA : cA + (size_t)(t + 2) * kstep; const char* b2 = last ? nB : cB + (size_t)(t + 2) * kstep;
;             const char* a3 = a2 + kstep; const char* b3 = b2 + kstep;
;             PG8_LDB(B0, 0, 0); PG8_SCHED; PG8_LDA(At, 0, 0); PG8_STAGE(PG8_SA(1, 1), a1 + hstep, voffA);
;             PG8_WAIT_L(8); PG8_BAR; PG8_WAIT_L(0); PG8_MMA(0, 0, At, B0); PG8_BAR; PG8_SCHED;
;             PG8_LDB(B1, 0, 1); PG8_STAGE(PG8_SB(0, 0), b2, voffB);
;             PG8_BAR; PG8_WAIT_L(0); PG8_MMA(0, 1, At, B1); PG8_BAR;
;             PG8_LDA(At, 0, 1); PG8_STAGE(PG8_SA(0, 0), a2, voffA);
;             PG8_BAR; PG8_WAIT_L(0); PG8_MMA(1, 0, At, B0); PG8_BAR; PG8_SCHED;
.LBB0_712:
	s_ashr_i32 s15, s14, 31
	v_cmp_lt_i64_e64 s[26:27], s[16:17], 64
	s_lshl_b64 s[16:17], s[14:15], 19
	s_add_u32 s16, s38, s16
	s_addc_u32 s17, s39, s17
	s_and_b64 s[18:19], s[26:27], exec
	s_cselect_b32 s15, s17, s23
	s_cselect_b32 s54, s16, s22
	s_ashr_i32 s13, s12, 31
	s_lshl_b64 s[18:19], s[12:13], 19
	s_add_u32 s18, s28, s18
	s_addc_u32 s19, s29, s19
	s_and_b64 s[26:27], s[26:27], exec
	s_cselect_b32 s13, s19, s25
	s_cselect_b32 s55, s18, s24
	s_add_u32 s22, s22, 0x40080
	s_addc_u32 s23, s23, 0
	s_add_u32 s56, s24, 0x100
	s_addc_u32 s57, s25, 0
	s_mov_b32 s58, -2
	s_waitcnt lgkmcnt(0)
	ds_read_b128 v[146:149], v143
	ds_read_b128 v[150:153], v143 offset:1024
	ds_read_b128 v[154:157], v143 offset:2048
	ds_read_b128 v[158:161], v143 offset:3072
	s_add_u32 s24, s22, 0xfffc0080
	s_addc_u32 s25, s23, -1
	s_cmp_eq_u32 s58, 12
	s_cselect_b32 s27, s15, s25
	s_cselect_b32 s26, s54, s24
	s_cselect_b32 s25, s13, s57
	s_cselect_b32 s24, s55, s56
	s_add_i32 m0, s21, 0xc000
	ds_read_b128 v[162:165], v144
	ds_read_b128 v[166:169], v144 offset:1024
	ds_read_b128 v[170:173], v144 offset:2048
	ds_read_b128 v[174:177], v144 offset:3072
	ds_read_b128 v[178:181], v144 offset:4096
	ds_read_b128 v[182:185], v144 offset:5120
	ds_read_b128 v[186:189], v144 offset:6144
	ds_read_b128 v[190:193], v144 offset:7168
	global_load_lds_dwordx4 v136, s[22:23]
	s_add_i32 m0, s21, 0xe000
	s_nop 0
	global_load_lds_dwordx4 v138, s[22:23]
	s_waitcnt lgkmcnt(8)
	s_waitcnt vmcnt(10)
	s_barrier
	s_waitcnt lgkmcnt(0)
	s_setprio 1
	s_waitcnt lgkmcnt(0)
	v_mfma_f32_16x16x32_bf16 v[124:127], v[146:149], v[162:165], 0
	v_mfma_f32_16x16x32_bf16 v[120:123], v[154:157], v[162:165], 0
	v_mfma_f32_16x16x32_bf16 v[116:119], v[146:149], v[170:173], 0
	v_mfma_f32_16x16x32_bf16 v[108:111], v[154:157], v[170:173], 0
	v_mfma_f32_16x16x32_bf16 v[100:103], v[146:149], v[178:181], 0
	v_mfma_f32_16x16x32_bf16 v[92:95], v[154:157], v[178:181], 0
	v_mfma_f32_16x16x32_bf16 v[84:87], v[146:149], v[186:189], 0
	v_mfma_f32_16x16x32_bf16 v[76:79], v[154:157], v[186:189], 0
	v_mfma_f32_16x16x32_bf16 v[124:127], v[150:153], v[166:169], v[124:127]
	v_mfma_f32_16x16x32_bf16 v[120:123], v[158:161], v[166:169], v[120:123]
	v_mfma_f32_16x16x32_bf16 v[116:119], v[150:153], v[174:177], v[116:119]
	v_mfma_f32_16x16x32_bf16 v[108:111], v[158:161], v[174:177], v[108:111]
	v_mfma_f32_16x16x32_bf16 v[100:103], v[150:153], v[182:185], v[100:103]
	v_mfma_f32_16x16x32_bf16 v[92:95], v[158:161], v[182:185], v[92:95]
	v_mfma_f32_16x16x32_bf16 v[84:87], v[150:153], v[190:193], v[84:87]
	v_mfma_f32_16x16x32_bf16 v[76:79], v[158:161], v[190:193], v[76:79]
	s_setprio 0
	s_barrier
	s_add_i32 s59, s46, s34
	s_mov_b32 m0, s59
	ds_read_b128 v[194:197], v145
	ds_read_b128 v[202:205], v145 offset:1024
	ds_read_b128 v[206:209], v145 offset:2048
	ds_read_b128 v[210:213], v145 offset:3072
	global_load_lds_dwordx4 v130, s[24:25]
	s_add_i32 m0, s59, 0x2000
	s_nop 0
	global_load_lds_dwordx4 v134, s[24:25]
	s_waitcnt vmcnt(10)
	s_barrier
	s_waitcnt lgkmcnt(0)
	s_setprio 1
	s_waitcnt lgkmcnt(0)
	v_mfma_f32_16x16x32_bf16 v[112:115], v[194:197], v[162:165], 0
	v_mfma_f32_16x16x32_bf16 v[104:107], v[206:209], v[162:165], 0
	v_mfma_f32_16x16x32_bf16 v[96:99], v[194:197], v[170:173], 0
	v_mfma_f32_16x16x32_bf16 v[88:91], v[206:209], v[170:173], 0
	v_mfma_f32_16x16x32_bf16 v[80:83], v[194:197], v[178:181], 0
	v_mfma_f32_16x16x32_bf16 v[72:75], v[206:209], v[178:181], 0
	v_mfma_f32_16x16x32_bf16 v[68:71], v[194:197], v[186:189], 0
	v_mfma_f32_16x16x32_bf16 v[64:67], v[206:209], v[186:189], 0
	v_mfma_f32_16x16x32_bf16 v[112:115], v[202:205], v[166:169], v[112:115]
	v_mfma_f32_16x16x32_bf16 v[104:107], v[210:213], v[166:169], v[104:107]
	v_mfma_f32_16x16x32_bf16 v[96:99], v[202:205], v[174:177], v[96:99]
	v_mfma_f32_16x16x32_bf16 v[88:91], v[210:213], v[174:177], v[88:91]
	v_mfma_f32_16x16x32_bf16 v[80:83], v[202:205], v[182:185], v[80:83]
	v_mfma_f32_16x16x32_bf16 v[72:75], v[210:213], v[182:185], v[72:75]
	v_mfma_f32_16x16x32_bf16 v[68:71], v[202:205], v[190:193], v[68:71]
	v_mfma_f32_16x16x32_bf16 v[64:67], v[210:213], v[190:193], v[64:67]
	s_setprio 0
	s_mov_b32 m0, s21
	v_lshl_add_u64 v[216:217], s[26:27], 0, v[128:129]
	s_barrier
	ds_read_b128 v[162:165], v144 offset:16384
	ds_read_b128 v[166:169], v144 offset:17408
	ds_read_b128 v[170:173], v144 offset:18432
	ds_read_b128 v[174:177], v144 offset:19456
	ds_read_b128 v[178:181], v144 offset:20480
	ds_read_b128 v[182:185], v144 offset:21504
	ds_read_b128 v[186:189], v144 offset:22528
	ds_read_b128 v[190:193], v144 offset:23552
	global_load_lds_dwordx4 v128, s[26:27]
	v_lshl_add_u64 v[218:219], s[26:27], 0, v[132:133]
	s_mov_b32 m0, s35
	s_nop 0
	global_load_lds_dwordx4 v132, s[26:27]
	s_barrier
	s_waitcnt lgkmcnt(0)
	s_setprio 1
	s_waitcnt lgkmcnt(0)
	v_mfma_f32_16x16x32_bf16 v[60:63], v[146:149], v[162:165], 0
	v_mfma_f32_16x16x32_bf16 v[56:59], v[154:157], v[162:165], 0
	v_mfma_f32_16x16x32_bf16 v[52:55], v[146:149], v[170:173], 0
	v_mfma_f32_16x16x32_bf16 v[44:47], v[154:157], v[170:173], 0
	v_mfma_f32_16x16x32_bf16 v[36:39], v[146:149], v[178:181], 0
	v_mfma_f32_16x16x32_bf16 v[28:31], v[154:157], v[178:181], 0
	v_mfma_f32_16x16x32_bf16 v[20:23], v[146:149], v[186:189], 0
	v_mfma_f32_16x16x32_bf16 v[12:15], v[154:157], v[186:189], 0
	v_mfma_f32_16x16x32_bf16 v[60:63], v[150:153], v[166:169], v[60:63]
	v_mfma_f32_16x16x32_bf16 v[56:59], v[158:161], v[166:169], v[56:59]
	v_mfma_f32_16x16x32_bf16 v[52:55], v[150:153], v[174:177], v[52:55]
	v_mfma_f32_16x16x32_bf16 v[44:47], v[158:161], v[174:177], v[44:47]
	v_mfma_f32_16x16x32_bf16 v[36:39], v[150:153], v[182:185], v[36:39]
	v_mfma_f32_16x16x32_bf16 v[28:31], v[158:161], v[182:185], v[28:31]
	v_mfma_f32_16x16x32_bf16 v[20:23], v[150:153], v[190:193], v[20:23]
	v_mfma_f32_16x16x32_bf16 v[12:15], v[158:161], v[190:193], v[12:15]
	s_setprio 0
	s_barrier
; #define PG8_STAGE(bufoff, gbase, voff) do { _Pragma("unroll") for (int _i = 0; _i < 2; ++_i) \
;         __builtin_amdgcn_global_load_lds((const unsigned*)((const char*)(gbase) + (voff)[_i]), (LAS unsigned*)(lds + (bufoff) + ldsw + _i * 8192), 16, 0, 0); } while (0)
; #define PG8_LDA(dst, b, h) do { _Pragma("unroll") for (int m = 0; m < 4; ++m) _Pragma("unroll") for (int k = 0; k < 2; ++k) dst[m][k] = *(const LAS bf16x8*)(lds + PG8_SA(b, h) + aoff + m * 2048 + k * 1024); } while (0)
; #define PG8_LDB(dst, b, h) do { _Pragma("unroll") for (int n = 0; n < 2; ++n) _Pragma("unroll") for (int k = 0; k < 2; ++k) dst[n][k] = *(const LAS bf16x8*)(lds + PG8_SB(b, h) + boff + n * 2048 + k * 1024); } while (0)
; #define PG8_MMA(ai, bj, At, Bt) do { __builtin_amdgcn_s_setprio(1); _Pragma("unroll") for (int m = 0; m < 4; ++m) _Pragma("unroll") for (int n = 0; n < 2; ++n) _Pragma("unroll") for (int k = 0; k < 2; ++k) \
;         acc[ai][bj][m][n] = __builtin_amdgcn_mfma_f32_16x16x32_bf16(Bt[n][k], At[m][k], acc[ai][bj][m][n], 0, 0, 0); __builtin_amdgcn_s_setprio(0); } while (0)
; #define PG8_WAIT_V(n) asm volatile("s_waitcnt vmcnt(" #n ")" ::: "memory")
; #define PG8_WAIT_L(n) asm volatile("s_waitcnt lgkmcnt(" #n ")" ::: "memory")
; #define PG8_BAR __builtin_amdgcn_s_barrier()
; #define PG8_SCHED __builtin_amdgcn_sched_barrier(0)
; template <class Epi, class Sched>
; __device__ __forceinline__ void gemm_phase(LAS unsigned char* lds, const Gemm g, const Sched& S, const Epi& E) {
;     ...
;             PG8_STAGE(PG8_SB(0, 1), b2 + hstep, voffB);
;             PG8_WAIT_V(6); PG8_BAR; PG8_MMA(1, 1, At, B1); PG8_BAR;
;             PG8_LDB(B0, 1, 0); PG8_SCHED; PG8_LDA(At, 1, 0); PG8_STAGE(PG8_SA(0, 1), a2 + hstep, voffA);
;             PG8_WAIT_L(8); PG8_BAR; PG8_WAIT_L(0); PG8_MMA(0, 0, At, B0); PG8_BAR; PG8_SCHED;
;             PG8_LDB(B1, 1, 1); PG8_STAGE(PG8_SB(1, 0), b3, voffB);
;             PG8_BAR; PG8_WAIT_L(0); PG8_MMA(0, 1, At, B1); PG8_BAR;
;             PG8_LDA(At, 1, 1); PG8_STAGE(PG8_SA(1, 0), a3, voffA);
;             PG8_BAR; PG8_WAIT_L(0); PG8_MMA(1, 0, At, B0); PG8_BAR; PG8_SCHED;
	s_add_u32 s60, s24, 0x40000
	s_addc_u32 s61, s25, 0
	s_add_i32 s59, s47, s34
	s_mov_b32 m0, s59
	s_nop 0
	global_load_lds_dwordx4 v130, s[60:61]
	s_add_i32 m0, s59, 0x2000
	s_nop 0
	global_load_lds_dwordx4 v134, s[60:61]
	s_add_u32 s26, s26, 0x40000
	s_addc_u32 s27, s27, 0
	s_mov_b32 m0, s36
	s_nop 0
	global_load_lds_dwordx4 v128, s[26:27]
	s_mov_b32 m0, s37
	s_nop 0
	global_load_lds_dwordx4 v132, s[26:27]
	s_waitcnt vmcnt(12)
	s_barrier
	s_setprio 1
	v_mfma_f32_16x16x32_bf16 v[48:51], v[194:197], v[162:165], 0
	v_mfma_f32_16x16x32_bf16 v[40:43], v[206:209], v[162:165], 0
	v_mfma_f32_16x16x32_bf16 v[32:35], v[194:197], v[170:173], 0
	v_mfma_f32_16x16x32_bf16 v[24:27], v[206:209], v[170:173], 0
	v_mfma_f32_16x16x32_bf16 v[16:19], v[194:197], v[178:181], 0
	v_mfma_f32_16x16x32_bf16 v[8:11], v[206:209], v[178:181], 0
	v_mfma_f32_16x16x32_bf16 v[4:7], v[194:197], v[186:189], 0
	v_mfma_f32_16x16x32_bf16 v[0:3], v[206:209], v[186:189], 0
	v_mfma_f32_16x16x32_bf16 v[48:51], v[202:205], v[166:169], v[48:51]
	v_mfma_f32_16x16x32_bf16 v[40:43], v[210:213], v[166:169], v[40:43]
	v_mfma_f32_16x16x32_bf16 v[32:35], v[202:205], v[174:177], v[32:35]
	v_mfma_f32_16x16x32_bf16 v[24:27], v[210:213], v[174:177], v[24:27]
	v_mfma_f32_16x16x32_bf16 v[16:19], v[202:205], v[182:185], v[16:19]
	v_mfma_f32_16x16x32_bf16 v[8:11], v[210:213], v[182:185], v[8:11]
	v_mfma_f32_16x16x32_bf16 v[4:7], v[202:205], v[190:193], v[4:7]
	v_mfma_f32_16x16x32_bf16 v[0:3], v[210:213], v[190:193], v[0:3]
	s_setprio 0
	s_add_i32 s59, 0, 0x18000
	v_add_u32_e32 v158, s59, v142
	s_barrier
	ds_read_b128 v[146:149], v158
	ds_read_b128 v[150:153], v158 offset:1024
	ds_read_b128 v[154:157], v158 offset:2048
	ds_read_b128 v[158:161], v158 offset:3072
	ds_read_b128 v[162:165], v144 offset:32768
	ds_read_b128 v[166:169], v144 offset:33792
	ds_read_b128 v[170:173], v144 offset:34816
	ds_read_b128 v[174:177], v144 offset:35840
	ds_read_b128 v[178:181], v144 offset:36864
	ds_read_b128 v[182:185], v144 offset:37888
	ds_read_b128 v[186:189], v144 offset:38912
	ds_read_b128 v[190:193], v144 offset:39936
	s_waitcnt lgkmcnt(8)
	s_waitcnt vmcnt(10)
	s_barrier
	s_waitcnt lgkmcnt(0)
	s_setprio 1
	s_waitcnt lgkmcnt(0)
	v_mfma_f32_16x16x32_bf16 v[124:127], v[146:149], v[162:165], v[124:127]
	v_mfma_f32_16x16x32_bf16 v[120:123], v[154:157], v[162:165], v[120:123]
	v_mfma_f32_16x16x32_bf16 v[116:119], v[146:149], v[170:173], v[116:119]
	v_mfma_f32_16x16x32_bf16 v[108:111], v[154:157], v[170:173], v[108:111]
	v_mfma_f32_16x16x32_bf16 v[100:103], v[146:149], v[178:181], v[100:103]
	v_mfma_f32_16x16x32_bf16 v[92:95], v[154:157], v[178:181], v[92:95]
	v_mfma_f32_16x16x32_bf16 v[84:87], v[146:149], v[186:189], v[84:87]
	v_mfma_f32_16x16x32_bf16 v[76:79], v[154:157], v[186:189], v[76:79]
	v_mfma_f32_16x16x32_bf16 v[124:127], v[150:153], v[166:169], v[124:127]
	v_mfma_f32_16x16x32_bf16 v[120:123], v[158:161], v[166:169], v[120:123]
	v_mfma_f32_16x16x32_bf16 v[116:119], v[150:153], v[174:177], v[116:119]
	v_mfma_f32_16x16x32_bf16 v[108:111], v[158:161], v[174:177], v[108:111]
	v_mfma_f32_16x16x32_bf16 v[100:103], v[150:153], v[182:185], v[100:103]
	v_mfma_f32_16x16x32_bf16 v[92:95], v[158:161], v[182:185], v[92:95]
	v_mfma_f32_16x16x32_bf16 v[84:87], v[150:153], v[190:193], v[84:87]
	v_mfma_f32_16x16x32_bf16 v[76:79], v[158:161], v[190:193], v[76:79]
	s_setprio 0
	s_barrier
	s_add_i32 s26, 0, 0x1c000
	s_add_i32 s27, s59, s34
	v_add_u32_e32 v210, s26, v142
	s_add_u32 s0, s24, 0x80
	s_addc_u32 s1, s25, 0
	s_mov_b32 m0, s27
	ds_read_b128 v[194:197], v210
	ds_read_b128 v[202:205], v210 offset:1024
	ds_read_b128 v[206:209], v210 offset:2048
	ds_read_b128 v[210:213], v210 offset:3072
	global_load_lds_dwordx4 v130, s[0:1]
	s_add_i32 m0, s27, 0x2000
	s_nop 0
	global_load_lds_dwordx4 v134, s[0:1]
	s_waitcnt vmcnt(10)
	s_barrier
	s_waitcnt lgkmcnt(0)
	s_setprio 1
	s_waitcnt lgkmcnt(0)
	v_mfma_f32_16x16x32_bf16 v[112:115], v[194:197], v[162:165], v[112:115]
	v_mfma_f32_16x16x32_bf16 v[104:107], v[206:209], v[162:165], v[104:107]
	v_mfma_f32_16x16x32_bf16 v[96:99], v[194:197], v[170:173], v[96:99]
	v_mfma_f32_16x16x32_bf16 v[88:91], v[206:209], v[170:173], v[88:91]
	v_mfma_f32_16x16x32_bf16 v[80:83], v[194:197], v[178:181], v[80:83]
	v_mfma_f32_16x16x32_bf16 v[72:75], v[206:209], v[178:181], v[72:75]
	v_mfma_f32_16x16x32_bf16 v[68:71], v[194:197], v[186:189], v[68:71]
	v_mfma_f32_16x16x32_bf16 v[64:67], v[206:209], v[186:189], v[64:67]
	v_mfma_f32_16x16x32_bf16 v[112:115], v[202:205], v[166:169], v[112:115]
	v_mfma_f32_16x16x32_bf16 v[104:107], v[210:213], v[166:169], v[104:107]
	v_mfma_f32_16x16x32_bf16 v[96:99], v[202:205], v[174:177], v[96:99]
	v_mfma_f32_16x16x32_bf16 v[88:91], v[210:213], v[174:177], v[88:91]
	v_mfma_f32_16x16x32_bf16 v[80:83], v[202:205], v[182:185], v[80:83]
	v_mfma_f32_16x16x32_bf16 v[72:75], v[210:213], v[182:185], v[72:75]
	v_mfma_f32_16x16x32_bf16 v[68:71], v[202:205], v[190:193], v[68:71]
	v_mfma_f32_16x16x32_bf16 v[64:67], v[210:213], v[190:193], v[64:67]
	s_setprio 0
	s_mov_b32 m0, s43
	s_mov_b64 s[0:1], 0x80
	v_lshl_add_u64 v[198:199], v[216:217], 0, s[0:1]
	s_barrier
	ds_read_b128 v[162:165], v144 offset:49152
	ds_read_b128 v[166:169], v144 offset:50176
	ds_read_b128 v[170:173], v144 offset:51200
	ds_read_b128 v[174:177], v144 offset:52224
	ds_read_b128 v[178:181], v144 offset:53248
	ds_read_b128 v[182:185], v144 offset:54272
	ds_read_b128 v[186:189], v144 offset:55296
	ds_read_b128 v[190:193], v144 offset:56320
	global_load_lds_dwordx4 v[198:199], off
	v_lshl_add_u64 v[198:199], v[218:219], 0, s[0:1]
	s_mov_b32 m0, s44
	s_nop 0
	global_load_lds_dwordx4 v[198:199], off
	s_barrier
; #define PG8_STAGE(bufoff, gbase, voff) do { _Pragma("unroll") for (int _i = 0; _i < 2; ++_i) \
;         __builtin_amdgcn_global_load_lds((const unsigned*)((const char*)(gbase) + (voff)[_i]), (LAS unsigned*)(lds + (bufoff) + ldsw + _i * 8192), 16, 0, 0); } while (0)
; #define PG8_LDA(dst, b, h) do { _Pragma("unroll") for (int m = 0; m < 4; ++m) _Pragma("unroll") for (int k = 0; k < 2; ++k) dst[m][k] = *(const LAS bf16x8*)(lds + PG8_SA(b, h) + aoff + m * 2048 + k * 1024); } while (0)
; #define PG8_LDB(dst, b, h) do { _Pragma("unroll") for (int n = 0; n < 2; ++n) _Pragma("unroll") for (int k = 0; k < 2; ++k) dst[n][k] = *(const LAS bf16x8*)(lds + PG8_SB(b, h) + boff + n * 2048 + k * 1024); } while (0)
; #define PG8_MMA(ai, bj, At, Bt) do { __builtin_amdgcn_s_setprio(1); _Pragma("unroll") for (int m = 0; m < 4; ++m) _Pragma("unroll") for (int n = 0; n < 2; ++n) _Pragma("unroll") for (int k = 0; k < 2; ++k) \
;         acc[ai][bj][m][n] = __builtin_amdgcn_mfma_f32_16x16x32_bf16(Bt[n][k], At[m][k], acc[ai][bj][m][n], 0, 0, 0); __builtin_amdgcn_s_setprio(0); } while (0)
; #define PG8_WAIT_V(n) asm volatile("s_waitcnt vmcnt(" #n ")" ::: "memory")
; #define PG8_WAIT_L(n) asm volatile("s_waitcnt lgkmcnt(" #n ")" ::: "memory")
; #define PG8_BAR __builtin_amdgcn_s_barrier()
; #define PG8_SCHED __builtin_amdgcn_sched_barrier(0)
; template <class Epi, class Sched>
; __device__ __forceinline__ void gemm_phase(LAS unsigned char* lds, const Gemm g, const Sched& S, const Epi& E) {
;     ...
;             PG8_LDB(B0, 0, 0); PG8_SCHED; PG8_LDA(At, 0, 0); PG8_STAGE(PG8_SA(1, 1), a1 + hstep, voffA);
;             PG8_WAIT_L(8); PG8_BAR; PG8_WAIT_L(0); PG8_MMA(0, 0, At, B0); PG8_BAR; PG8_SCHED;
;             PG8_LDB(B1, 0, 1); PG8_STAGE(PG8_SB(0, 0), b2, voffB);
;             PG8_BAR; PG8_WAIT_L(0); PG8_MMA(0, 1, At, B1); PG8_BAR;
;     ...
;             PG8_BAR; PG8_WAIT_L(0); PG8_MMA(1, 0, At, B0); PG8_BAR; PG8_SCHED;
;             PG8_STAGE(PG8_SB(1, 1), b3 + hstep, voffB);
;             PG8_WAIT_V(6); PG8_BAR; PG8_MMA(1, 1, At, B1); PG8_BAR;
	s_waitcnt lgkmcnt(0)
	s_setprio 1
	s_waitcnt lgkmcnt(0)
	v_mfma_f32_16x16x32_bf16 v[60:63], v[146:149], v[162:165], v[60:63]
	v_mfma_f32_16x16x32_bf16 v[56:59], v[154:157], v[162:165], v[56:59]
	v_mfma_f32_16x16x32_bf16 v[52:55], v[146:149], v[170:173], v[52:55]
	v_mfma_f32_16x16x32_bf16 v[44:47], v[154:157], v[170:173], v[44:47]
	v_mfma_f32_16x16x32_bf16 v[36:39], v[146:149], v[178:181], v[36:39]
	v_mfma_f32_16x16x32_bf16 v[28:31], v[154:157], v[178:181], v[28:31]
	v_mfma_f32_16x16x32_bf16 v[20:23], v[146:149], v[186:189], v[20:23]
	v_mfma_f32_16x16x32_bf16 v[12:15], v[154:157], v[186:189], v[12:15]
	v_mfma_f32_16x16x32_bf16 v[60:63], v[150:153], v[166:169], v[60:63]
	v_mfma_f32_16x16x32_bf16 v[56:59], v[158:161], v[166:169], v[56:59]
	v_mfma_f32_16x16x32_bf16 v[52:55], v[150:153], v[174:177], v[52:55]
	v_mfma_f32_16x16x32_bf16 v[44:47], v[158:161], v[174:177], v[44:47]
	v_mfma_f32_16x16x32_bf16 v[36:39], v[150:153], v[182:185], v[36:39]
	v_mfma_f32_16x16x32_bf16 v[28:31], v[158:161], v[182:185], v[28:31]
	v_mfma_f32_16x16x32_bf16 v[20:23], v[150:153], v[190:193], v[20:23]
	v_mfma_f32_16x16x32_bf16 v[12:15], v[158:161], v[190:193], v[12:15]
	s_setprio 0
	s_barrier
	s_add_u32 s24, s24, 0x40080
	s_addc_u32 s25, s25, 0
	s_add_i32 s26, s26, s34
	s_mov_b32 m0, s26
	s_nop 0
	global_load_lds_dwordx4 v130, s[24:25]
	s_add_i32 m0, s26, 0x2000
	s_nop 0
	global_load_lds_dwordx4 v134, s[24:25]
	s_waitcnt vmcnt(10)
	s_barrier
	s_setprio 1
	v_mfma_f32_16x16x32_bf16 v[48:51], v[194:197], v[162:165], v[48:51]
	v_mfma_f32_16x16x32_bf16 v[40:43], v[206:209], v[162:165], v[40:43]
	v_mfma_f32_16x16x32_bf16 v[32:35], v[194:197], v[170:173], v[32:35]
	v_mfma_f32_16x16x32_bf16 v[24:27], v[206:209], v[170:173], v[24:27]
	v_mfma_f32_16x16x32_bf16 v[16:19], v[194:197], v[178:181], v[16:19]
	v_mfma_f32_16x16x32_bf16 v[8:11], v[206:209], v[178:181], v[8:11]
	v_mfma_f32_16x16x32_bf16 v[4:7], v[194:197], v[186:189], v[4:7]
	v_mfma_f32_16x16x32_bf16 v[0:3], v[206:209], v[186:189], v[0:3]
	v_mfma_f32_16x16x32_bf16 v[48:51], v[202:205], v[166:169], v[48:51]
	v_mfma_f32_16x16x32_bf16 v[40:43], v[210:213], v[166:169], v[40:43]
	v_mfma_f32_16x16x32_bf16 v[32:35], v[202:205], v[174:177], v[32:35]
	v_mfma_f32_16x16x32_bf16 v[24:27], v[210:213], v[174:177], v[24:27]
	v_mfma_f32_16x16x32_bf16 v[16:19], v[202:205], v[182:185], v[16:19]
	v_mfma_f32_16x16x32_bf16 v[8:11], v[210:213], v[182:185], v[8:11]
	v_mfma_f32_16x16x32_bf16 v[4:7], v[202:205], v[190:193], v[4:7]
	v_mfma_f32_16x16x32_bf16 v[0:3], v[210:213], v[190:193], v[0:3]
	s_setprio 0
	s_add_i32 s58, s58, 2
	s_add_u32 s22, s22, 0x100
	s_addc_u32 s23, s23, 0
	s_add_u32 s56, s56, 0x100
	s_addc_u32 s57, s57, 0
	s_cmp_gt_u32 s58, 13
	s_barrier
.LBB0_713:
	ds_read_b128 v[146:149], v143
	ds_read_b128 v[150:153], v143 offset:1024
	ds_read_b128 v[154:157], v143 offset:2048
	ds_read_b128 v[158:161], v143 offset:3072
	s_add_u32 s24, s22, 0xfffc0080
	s_addc_u32 s25, s23, -1
	s_cmp_eq_u32 s58, 12
	s_cselect_b32 s27, s15, s25
	s_cselect_b32 s26, s54, s24
	s_cselect_b32 s25, s13, s57
	s_cselect_b32 s24, s55, s56
	s_add_i32 m0, s21, 0xc000
	ds_read_b128 v[162:165], v144
	ds_read_b128 v[166:169], v144 offset:1024
	ds_read_b128 v[170:173], v144 offset:2048
	ds_read_b128 v[174:177], v144 offset:3072
	ds_read_b128 v[178:181], v144 offset:4096
	ds_read_b128 v[182:185], v144 offset:5120
	ds_read_b128 v[186:189], v144 offset:6144
	ds_read_b128 v[190:193], v144 offset:7168
	global_load_lds_dwordx4 v136, s[22:23]
	s_add_i32 m0, s21, 0xe000
	s_nop 0
	global_load_lds_dwordx4 v138, s[22:23]
	s_waitcnt lgkmcnt(8)
	s_waitcnt vmcnt(10)
	s_barrier
	s_waitcnt lgkmcnt(0)
	s_setprio 1
	s_waitcnt lgkmcnt(0)
	v_mfma_f32_16x16x32_bf16 v[124:127], v[146:149], v[162:165], v[124:127]
	v_mfma_f32_16x16x32_bf16 v[120:123], v[154:157], v[162:165], v[120:123]
	v_mfma_f32_16x16x32_bf16 v[116:119], v[146:149], v[170:173], v[116:119]
	v_mfma_f32_16x16x32_bf16 v[108:111], v[154:157], v[170:173], v[108:111]
	v_mfma_f32_16x16x32_bf16 v[100:103], v[146:149], v[178:181], v[100:103]
	v_mfma_f32_16x16x32_bf16 v[92:95], v[154:157], v[178:181], v[92:95]
	v_mfma_f32_16x16x32_bf16 v[84:87], v[146:149], v[186:189], v[84:87]
	v_mfma_f32_16x16x32_bf16 v[76:79], v[154:157], v[186:189], v[76:79]
	v_mfma_f32_16x16x32_bf16 v[124:127], v[150:153], v[166:169], v[124:127]
	v_mfma_f32_16x16x32_bf16 v[120:123], v[158:161], v[166:169], v[120:123]
	v_mfma_f32_16x16x32_bf16 v[116:119], v[150:153], v[174:177], v[116:119]
	v_mfma_f32_16x16x32_bf16 v[108:111], v[158:161], v[174:177], v[108:111]
	v_mfma_f32_16x16x32_bf16 v[100:103], v[150:153], v[182:185], v[100:103]
	v_mfma_f32_16x16x32_bf16 v[92:95], v[158:161], v[182:185], v[92:95]
	v_mfma_f32_16x16x32_bf16 v[84:87], v[150:153], v[190:193], v[84:87]
	v_mfma_f32_16x16x32_bf16 v[76:79], v[158:161], v[190:193], v[76:79]
	s_setprio 0
	s_barrier
	s_add_i32 s59, s46, s34
	s_mov_b32 m0, s59
	ds_read_b128 v[194:197], v145
	ds_read_b128 v[202:205], v145 offset:1024
	ds_read_b128 v[206:209], v145 offset:2048
	ds_read_b128 v[210:213], v145 offset:3072
	global_load_lds_dwordx4 v130, s[24:25]
	s_add_i32 m0, s59, 0x2000
	s_nop 0
	global_load_lds_dwordx4 v134, s[24:25]
	s_waitcnt vmcnt(10)
	s_barrier
; #define PG8_STAGE(bufoff, gbase, voff) do { _Pragma("unroll") for (int _i = 0; _i < 2; ++_i) \
;         __builtin_amdgcn_global_load_lds((const unsigned*)((const char*)(gbase) + (voff)[_i]), (LAS unsigned*)(lds + (bufoff) + ldsw + _i * 8192), 16, 0, 0); } while (0)
; #define PG8_LDA(dst, b, h) do { _Pragma("unroll") for (int m = 0; m < 4; ++m) _Pragma("unroll") for (int k = 0; k < 2; ++k) dst[m][k] = *(const LAS bf16x8*)(lds + PG8_SA(b, h) + aoff + m * 2048 + k * 1024); } while (0)
; #define PG8_LDB(dst, b, h) do { _Pragma("unroll") for (int n = 0; n < 2; ++n) _Pragma("unroll") for (int k = 0; k < 2; ++k) dst[n][k] = *(const LAS bf16x8*)(lds + PG8_SB(b, h) + boff + n * 2048 + k * 1024); } while (0)
; #define PG8_MMA(ai, bj, At, Bt) do { __builtin_amdgcn_s_setprio(1); _Pragma("unroll") for (int m = 0; m < 4; ++m) _Pragma("unroll") for (int n = 0; n < 2; ++n) _Pragma("unroll") for (int k = 0; k < 2; ++k) \
;         acc[ai][bj][m][n] = __builtin_amdgcn_mfma_f32_16x16x32_bf16(Bt[n][k], At[m][k], acc[ai][bj][m][n], 0, 0, 0); __builtin_amdgcn_s_setprio(0); } while (0)
; #define PG8_WAIT_V(n) asm volatile("s_waitcnt vmcnt(" #n ")" ::: "memory")
; #define PG8_WAIT_L(n) asm volatile("s_waitcnt lgkmcnt(" #n ")" ::: "memory")
; #define PG8_BAR __builtin_amdgcn_s_barrier()
; #define PG8_SCHED __builtin_amdgcn_sched_barrier(0)
; template <class Epi, class Sched>
; __device__ __forceinline__ void gemm_phase(LAS unsigned char* lds, const Gemm g, const Sched& S, const Epi& E) {
;     ...
;             PG8_LDA(At, 0, 1); PG8_STAGE(PG8_SA(0, 0), a2, voffA);
;             PG8_BAR; PG8_WAIT_L(0); PG8_MMA(1, 0, At, B0); PG8_BAR; PG8_SCHED;
;             PG8_STAGE(PG8_SB(0, 1), b2 + hstep, voffB);
;             PG8_WAIT_V(6); PG8_BAR; PG8_MMA(1, 1, At, B1); PG8_BAR;
;             PG8_LDB(B0, 1, 0); PG8_SCHED; PG8_LDA(At, 1, 0); PG8_STAGE(PG8_SA(0, 1), a2 + hstep, voffA);
;             PG8_WAIT_L(8); PG8_BAR; PG8_WAIT_L(0); PG8_MMA(0, 0, At, B0); PG8_BAR; PG8_SCHED;
	s_waitcnt lgkmcnt(0)
	s_setprio 1
	s_waitcnt lgkmcnt(0)
	v_mfma_f32_16x16x32_bf16 v[112:115], v[194:197], v[162:165], v[112:115]
	v_mfma_f32_16x16x32_bf16 v[104:107], v[206:209], v[162:165], v[104:107]
	v_mfma_f32_16x16x32_bf16 v[96:99], v[194:197], v[170:173], v[96:99]
	v_mfma_f32_16x16x32_bf16 v[88:91], v[206:209], v[170:173], v[88:91]
	v_mfma_f32_16x16x32_bf16 v[80:83], v[194:197], v[178:181], v[80:83]
	v_mfma_f32_16x16x32_bf16 v[72:75], v[206:209], v[178:181], v[72:75]
	v_mfma_f32_16x16x32_bf16 v[68:71], v[194:197], v[186:189], v[68:71]
	v_mfma_f32_16x16x32_bf16 v[64:67], v[206:209], v[186:189], v[64:67]
	v_mfma_f32_16x16x32_bf16 v[112:115], v[202:205], v[166:169], v[112:115]
	v_mfma_f32_16x16x32_bf16 v[104:107], v[210:213], v[166:169], v[104:107]
	v_mfma_f32_16x16x32_bf16 v[96:99], v[202:205], v[174:177], v[96:99]
	v_mfma_f32_16x16x32_bf16 v[88:91], v[210:213], v[174:177], v[88:91]
	v_mfma_f32_16x16x32_bf16 v[80:83], v[202:205], v[182:185], v[80:83]
	v_mfma_f32_16x16x32_bf16 v[72:75], v[210:213], v[182:185], v[72:75]
	v_mfma_f32_16x16x32_bf16 v[68:71], v[202:205], v[190:193], v[68:71]
	v_mfma_f32_16x16x32_bf16 v[64:67], v[210:213], v[190:193], v[64:67]
	s_setprio 0
	s_mov_b32 m0, s21
	v_lshl_add_u64 v[216:217], s[26:27], 0, v[128:129]
	s_barrier
	ds_read_b128 v[162:165], v144 offset:16384
	ds_read_b128 v[166:169], v144 offset:17408
	ds_read_b128 v[170:173], v144 offset:18432
	ds_read_b128 v[174:177], v144 offset:19456
	ds_read_b128 v[178:181], v144 offset:20480
	ds_read_b128 v[182:185], v144 offset:21504
	ds_read_b128 v[186:189], v144 offset:22528
	ds_read_b128 v[190:193], v144 offset:23552
	global_load_lds_dwordx4 v128, s[26:27]
	v_lshl_add_u64 v[218:219], s[26:27], 0, v[132:133]
	s_mov_b32 m0, s35
	s_nop 0
	global_load_lds_dwordx4 v132, s[26:27]
	s_barrier
	s_waitcnt lgkmcnt(0)
	s_setprio 1
	s_waitcnt lgkmcnt(0)
	v_mfma_f32_16x16x32_bf16 v[60:63], v[146:149], v[162:165], v[60:63]
	v_mfma_f32_16x16x32_bf16 v[56:59], v[154:157], v[162:165], v[56:59]
	v_mfma_f32_16x16x32_bf16 v[52:55], v[146:149], v[170:173], v[52:55]
	v_mfma_f32_16x16x32_bf16 v[44:47], v[154:157], v[170:173], v[44:47]
	v_mfma_f32_16x16x32_bf16 v[36:39], v[146:149], v[178:181], v[36:39]
	v_mfma_f32_16x16x32_bf16 v[28:31], v[154:157], v[178:181], v[28:31]
	v_mfma_f32_16x16x32_bf16 v[20:23], v[146:149], v[186:189], v[20:23]
	v_mfma_f32_16x16x32_bf16 v[12:15], v[154:157], v[186:189], v[12:15]
	v_mfma_f32_16x16x32_bf16 v[60:63], v[150:153], v[166:169], v[60:63]
	v_mfma_f32_16x16x32_bf16 v[56:59], v[158:161], v[166:169], v[56:59]
	v_mfma_f32_16x16x32_bf16 v[52:55], v[150:153], v[174:177], v[52:55]
	v_mfma_f32_16x16x32_bf16 v[44:47], v[158:161], v[174:177], v[44:47]
	v_mfma_f32_16x16x32_bf16 v[36:39], v[150:153], v[182:185], v[36:39]
	v_mfma_f32_16x16x32_bf16 v[28:31], v[158:161], v[182:185], v[28:31]
	v_mfma_f32_16x16x32_bf16 v[20:23], v[150:153], v[190:193], v[20:23]
	v_mfma_f32_16x16x32_bf16 v[12:15], v[158:161], v[190:193], v[12:15]
	s_setprio 0
	s_barrier
	s_add_u32 s60, s24, 0x40000
	s_addc_u32 s61, s25, 0
	s_add_i32 s59, s47, s34
	s_mov_b32 m0, s59
	s_nop 0
	global_load_lds_dwordx4 v130, s[60:61]
	s_add_i32 m0, s59, 0x2000
	s_nop 0
	global_load_lds_dwordx4 v134, s[60:61]
	s_add_u32 s26, s26, 0x40000
	s_addc_u32 s27, s27, 0
	s_mov_b32 m0, s36
	s_nop 0
	global_load_lds_dwordx4 v128, s[26:27]
	s_mov_b32 m0, s37
	s_nop 0
	global_load_lds_dwordx4 v132, s[26:27]
	s_waitcnt vmcnt(12)
	s_barrier
	s_setprio 1
	v_mfma_f32_16x16x32_bf16 v[48:51], v[194:197], v[162:165], v[48:51]
	v_mfma_f32_16x16x32_bf16 v[40:43], v[206:209], v[162:165], v[40:43]
	v_mfma_f32_16x16x32_bf16 v[32:35], v[194:197], v[170:173], v[32:35]
	v_mfma_f32_16x16x32_bf16 v[24:27], v[206:209], v[170:173], v[24:27]
	v_mfma_f32_16x16x32_bf16 v[16:19], v[194:197], v[178:181], v[16:19]
	v_mfma_f32_16x16x32_bf16 v[8:11], v[206:209], v[178:181], v[8:11]
	v_mfma_f32_16x16x32_bf16 v[4:7], v[194:197], v[186:189], v[4:7]
	v_mfma_f32_16x16x32_bf16 v[0:3], v[206:209], v[186:189], v[0:3]
	v_mfma_f32_16x16x32_bf16 v[48:51], v[202:205], v[166:169], v[48:51]
	v_mfma_f32_16x16x32_bf16 v[40:43], v[210:213], v[166:169], v[40:43]
	v_mfma_f32_16x16x32_bf16 v[32:35], v[202:205], v[174:177], v[32:35]
	v_mfma_f32_16x16x32_bf16 v[24:27], v[210:213], v[174:177], v[24:27]
	v_mfma_f32_16x16x32_bf16 v[16:19], v[202:205], v[182:185], v[16:19]
	v_mfma_f32_16x16x32_bf16 v[8:11], v[210:213], v[182:185], v[8:11]
	v_mfma_f32_16x16x32_bf16 v[4:7], v[202:205], v[190:193], v[4:7]
	v_mfma_f32_16x16x32_bf16 v[0:3], v[210:213], v[190:193], v[0:3]
	s_setprio 0
	s_add_i32 s59, 0, 0x18000
	v_add_u32_e32 v158, s59, v142
	s_barrier
	ds_read_b128 v[146:149], v158
	ds_read_b128 v[150:153], v158 offset:1024
	ds_read_b128 v[154:157], v158 offset:2048
	ds_read_b128 v[158:161], v158 offset:3072
	ds_read_b128 v[162:165], v144 offset:32768
	ds_read_b128 v[166:169], v144 offset:33792
	ds_read_b128 v[170:173], v144 offset:34816
	ds_read_b128 v[174:177], v144 offset:35840
	ds_read_b128 v[178:181], v144 offset:36864
	ds_read_b128 v[182:185], v144 offset:37888
	ds_read_b128 v[186:189], v144 offset:38912
	ds_read_b128 v[190:193], v144 offset:39936
	s_waitcnt lgkmcnt(8)
	s_waitcnt vmcnt(10)
	s_barrier
; #define PG8_STAGE(bufoff, gbase, voff) do { _Pragma("unroll") for (int _i = 0; _i < 2; ++_i) \
;         __builtin_amdgcn_global_load_lds((const unsigned*)((const char*)(gbase) + (voff)[_i]), (LAS unsigned*)(lds + (bufoff) + ldsw + _i * 8192), 16, 0, 0); } while (0)
; #define PG8_LDA(dst, b, h) do { _Pragma("unroll") for (int m = 0; m < 4; ++m) _Pragma("unroll") for (int k = 0; k < 2; ++k) dst[m][k] = *(const LAS bf16x8*)(lds + PG8_SA(b, h) + aoff + m * 2048 + k * 1024); } while (0)
; #define PG8_LDB(dst, b, h) do { _Pragma("unroll") for (int n = 0; n < 2; ++n) _Pragma("unroll") for (int k = 0; k < 2; ++k) dst[n][k] = *(const LAS bf16x8*)(lds + PG8_SB(b, h) + boff + n * 2048 + k * 1024); } while (0)
; #define PG8_MMA(ai, bj, At, Bt) do { __builtin_amdgcn_s_setprio(1); _Pragma("unroll") for (int m = 0; m < 4; ++m) _Pragma("unroll") for (int n = 0; n < 2; ++n) _Pragma("unroll") for (int k = 0; k < 2; ++k) \
;         acc[ai][bj][m][n] = __builtin_amdgcn_mfma_f32_16x16x32_bf16(Bt[n][k], At[m][k], acc[ai][bj][m][n], 0, 0, 0); __builtin_amdgcn_s_setprio(0); } while (0)
; #define PG8_WAIT_V(n) asm volatile("s_waitcnt vmcnt(" #n ")" ::: "memory")
; #define PG8_WAIT_L(n) asm volatile("s_waitcnt lgkmcnt(" #n ")" ::: "memory")
; #define PG8_BAR __builtin_amdgcn_s_barrier()
; #define PG8_SCHED __builtin_amdgcn_sched_barrier(0)
; template <class Epi, class Sched>
; __device__ __forceinline__ void gemm_phase(LAS unsigned char* lds, const Gemm g, const Sched& S, const Epi& E) {
;     ...
;             PG8_WAIT_L(8); PG8_BAR; PG8_WAIT_L(0); PG8_MMA(0, 0, At, B0); PG8_BAR; PG8_SCHED;
;             PG8_LDB(B1, 1, 1); PG8_STAGE(PG8_SB(1, 0), b3, voffB);
;             PG8_BAR; PG8_WAIT_L(0); PG8_MMA(0, 1, At, B1); PG8_BAR;
;             PG8_LDA(At, 1, 1); PG8_STAGE(PG8_SA(1, 0), a3, voffA);
;             PG8_BAR; PG8_WAIT_L(0); PG8_MMA(1, 0, At, B0); PG8_BAR; PG8_SCHED;
;             PG8_STAGE(PG8_SB(1, 1), b3 + hstep, voffB);
;             PG8_WAIT_V(6); PG8_BAR; PG8_MMA(1, 1, At, B1); PG8_BAR;
	s_waitcnt lgkmcnt(0)
	s_setprio 1
	s_waitcnt lgkmcnt(0)
	v_mfma_f32_16x16x32_bf16 v[124:127], v[146:149], v[162:165], v[124:127]
	v_mfma_f32_16x16x32_bf16 v[120:123], v[154:157], v[162:165], v[120:123]
	v_mfma_f32_16x16x32_bf16 v[116:119], v[146:149], v[170:173], v[116:119]
	v_mfma_f32_16x16x32_bf16 v[108:111], v[154:157], v[170:173], v[108:111]
	v_mfma_f32_16x16x32_bf16 v[100:103], v[146:149], v[178:181], v[100:103]
	v_mfma_f32_16x16x32_bf16 v[92:95], v[154:157], v[178:181], v[92:95]
	v_mfma_f32_16x16x32_bf16 v[84:87], v[146:149], v[186:189], v[84:87]
	v_mfma_f32_16x16x32_bf16 v[76:79], v[154:157], v[186:189], v[76:79]
	v_mfma_f32_16x16x32_bf16 v[124:127], v[150:153], v[166:169], v[124:127]
	v_mfma_f32_16x16x32_bf16 v[120:123], v[158:161], v[166:169], v[120:123]
	v_mfma_f32_16x16x32_bf16 v[116:119], v[150:153], v[174:177], v[116:119]
	v_mfma_f32_16x16x32_bf16 v[108:111], v[158:161], v[174:177], v[108:111]
	v_mfma_f32_16x16x32_bf16 v[100:103], v[150:153], v[182:185], v[100:103]
	v_mfma_f32_16x16x32_bf16 v[92:95], v[158:161], v[182:185], v[92:95]
	v_mfma_f32_16x16x32_bf16 v[84:87], v[150:153], v[190:193], v[84:87]
	v_mfma_f32_16x16x32_bf16 v[76:79], v[158:161], v[190:193], v[76:79]
	s_setprio 0
	s_barrier
	s_add_i32 s26, 0, 0x1c000
	s_add_i32 s27, s59, s34
	v_add_u32_e32 v210, s26, v142
	s_add_u32 s0, s24, 0x80
	s_addc_u32 s1, s25, 0
	s_mov_b32 m0, s27
	ds_read_b128 v[194:197], v210
	ds_read_b128 v[202:205], v210 offset:1024
	ds_read_b128 v[206:209], v210 offset:2048
	ds_read_b128 v[210:213], v210 offset:3072
	global_load_lds_dwordx4 v130, s[0:1]
	s_add_i32 m0, s27, 0x2000
	s_nop 0
	global_load_lds_dwordx4 v134, s[0:1]
	s_waitcnt vmcnt(10)
	s_barrier
	s_waitcnt lgkmcnt(0)
	s_setprio 1
	s_waitcnt lgkmcnt(0)
	v_mfma_f32_16x16x32_bf16 v[112:115], v[194:197], v[162:165], v[112:115]
	v_mfma_f32_16x16x32_bf16 v[104:107], v[206:209], v[162:165], v[104:107]
	v_mfma_f32_16x16x32_bf16 v[96:99], v[194:197], v[170:173], v[96:99]
	v_mfma_f32_16x16x32_bf16 v[88:91], v[206:209], v[170:173], v[88:91]
	v_mfma_f32_16x16x32_bf16 v[80:83], v[194:197], v[178:181], v[80:83]
	v_mfma_f32_16x16x32_bf16 v[72:75], v[206:209], v[178:181], v[72:75]
	v_mfma_f32_16x16x32_bf16 v[68:71], v[194:197], v[186:189], v[68:71]
	v_mfma_f32_16x16x32_bf16 v[64:67], v[206:209], v[186:189], v[64:67]
	v_mfma_f32_16x16x32_bf16 v[112:115], v[202:205], v[166:169], v[112:115]
	v_mfma_f32_16x16x32_bf16 v[104:107], v[210:213], v[166:169], v[104:107]
	v_mfma_f32_16x16x32_bf16 v[96:99], v[202:205], v[174:177], v[96:99]
	v_mfma_f32_16x16x32_bf16 v[88:91], v[210:213], v[174:177], v[88:91]
	v_mfma_f32_16x16x32_bf16 v[80:83], v[202:205], v[182:185], v[80:83]
	v_mfma_f32_16x16x32_bf16 v[72:75], v[210:213], v[182:185], v[72:75]
	v_mfma_f32_16x16x32_bf16 v[68:71], v[202:205], v[190:193], v[68:71]
	v_mfma_f32_16x16x32_bf16 v[64:67], v[210:213], v[190:193], v[64:67]
	s_setprio 0
	s_mov_b32 m0, s43
	s_mov_b64 s[0:1], 0x80
	v_lshl_add_u64 v[198:199], v[216:217], 0, s[0:1]
	s_barrier
	ds_read_b128 v[162:165], v144 offset:49152
	ds_read_b128 v[166:169], v144 offset:50176
	ds_read_b128 v[170:173], v144 offset:51200
	ds_read_b128 v[174:177], v144 offset:52224
	ds_read_b128 v[178:181], v144 offset:53248
	ds_read_b128 v[182:185], v144 offset:54272
	ds_read_b128 v[186:189], v144 offset:55296
	ds_read_b128 v[190:193], v144 offset:56320
	global_load_lds_dwordx4 v[198:199], off
	v_lshl_add_u64 v[198:199], v[218:219], 0, s[0:1]
	s_mov_b32 m0, s44
	s_nop 0
	global_load_lds_dwordx4 v[198:199], off
	s_barrier
	s_waitcnt lgkmcnt(0)
	s_setprio 1
	s_waitcnt lgkmcnt(0)
	v_mfma_f32_16x16x32_bf16 v[60:63], v[146:149], v[162:165], v[60:63]
	v_mfma_f32_16x16x32_bf16 v[56:59], v[154:157], v[162:165], v[56:59]
	v_mfma_f32_16x16x32_bf16 v[52:55], v[146:149], v[170:173], v[52:55]
	v_mfma_f32_16x16x32_bf16 v[44:47], v[154:157], v[170:173], v[44:47]
	v_mfma_f32_16x16x32_bf16 v[36:39], v[146:149], v[178:181], v[36:39]
	v_mfma_f32_16x16x32_bf16 v[28:31], v[154:157], v[178:181], v[28:31]
	v_mfma_f32_16x16x32_bf16 v[20:23], v[146:149], v[186:189], v[20:23]
	v_mfma_f32_16x16x32_bf16 v[12:15], v[154:157], v[186:189], v[12:15]
	v_mfma_f32_16x16x32_bf16 v[60:63], v[150:153], v[166:169], v[60:63]
	v_mfma_f32_16x16x32_bf16 v[56:59], v[158:161], v[166:169], v[56:59]
	v_mfma_f32_16x16x32_bf16 v[52:55], v[150:153], v[174:177], v[52:55]
	v_mfma_f32_16x16x32_bf16 v[44:47], v[158:161], v[174:177], v[44:47]
	v_mfma_f32_16x16x32_bf16 v[36:39], v[150:153], v[182:185], v[36:39]
	v_mfma_f32_16x16x32_bf16 v[28:31], v[158:161], v[182:185], v[28:31]
	v_mfma_f32_16x16x32_bf16 v[20:23], v[150:153], v[190:193], v[20:23]
	v_mfma_f32_16x16x32_bf16 v[12:15], v[158:161], v[190:193], v[12:15]
	s_setprio 0
	s_barrier
	s_add_u32 s24, s24, 0x40080
	s_addc_u32 s25, s25, 0
	s_add_i32 s26, s26, s34
	s_mov_b32 m0, s26
	s_nop 0
	global_load_lds_dwordx4 v130, s[24:25]
	s_add_i32 m0, s26, 0x2000
	s_nop 0
	global_load_lds_dwordx4 v134, s[24:25]
	s_waitcnt vmcnt(10)
	s_barrier
; __device__ __forceinline__ unsigned cvt_pk_bf16(float lo, float hi) { unsigned r; asm volatile("v_cvt_pk_bf16_f32 %0, %1, %2" : "=v"(r) : "v"(lo), "v"(hi)); return r; }
; #define PG8_MMA(ai, bj, At, Bt) do { __builtin_amdgcn_s_setprio(1); _Pragma("unroll") for (int m = 0; m < 4; ++m) _Pragma("unroll") for (int n = 0; n < 2; ++n) _Pragma("unroll") for (int k = 0; k < 2; ++k) \
;         acc[ai][bj][m][n] = __builtin_amdgcn_mfma_f32_16x16x32_bf16(Bt[n][k], At[m][k], acc[ai][bj][m][n], 0, 0, 0); __builtin_amdgcn_s_setprio(0); } while (0)
; #define PG8_WAIT_V(n) asm volatile("s_waitcnt vmcnt(" #n ")" ::: "memory")
; #define PG8_BAR __builtin_amdgcn_s_barrier()
; template <class Epi, class Sched>
; __device__ __forceinline__ void gemm_phase(LAS unsigned char* lds, const Gemm g, const Sched& S, const Epi& E) {
;     ...
;             PG8_WAIT_V(6); PG8_BAR; PG8_MMA(1, 1, At, B1); PG8_BAR;
;         }
;         E(acc, cur, wr, wc, fr, fq);
;         if (!has_next) break;
; #pragma unroll
;         for (int a = 0; a < 2; ++a)
; #pragma unroll
;             for (int b = 0; b < 2; ++b)
; #pragma unroll
;                 for (int m = 0; m < 4; ++m)
; #pragma unroll
;                     for (int n = 0; n < 2; ++n) acc[a][b][m][n] = (f32x4){0.f, 0.f, 0.f, 0.f};
;         cur = nxt; cA = nA; cB = nB; ++ui;
;     }
;     PG8_WAIT_V(0);
;     if (wr == 0) PG8_BAR;
;     PG8_BAR;
;     __device__ __forceinline__ void operator()(const AccT& acc, const Unit& u, int wr, int wc, int fr, int fq) const {
;     ...
;         const int rbase = u.pm * 256 + wr * 64 + fr;
;         const int tb = u.pn * 256 + wc * 32 + 8 * fq;
; #pragma unroll
;         for (int ai = 0; ai < 2; ++ai)
; #pragma unroll
;             for (int m = 0; m < 4; ++m) {
;                 const int r = rbase + ai * 128 + m * 16;
; #pragma unroll
;                 for (int bj = 0; bj < 2; ++bj) {
;                     const int t0 = tb + bj * 128;
;                     const f32x4 v0 = acc[ai][bj][m][0], v1 = acc[ai][bj][m][1];
;                     u32x4 w; w.x = cvt_pk_bf16(v0[0], v0[1]); w.y = cvt_pk_bf16(v0[2], v0[3]); w.z = cvt_pk_bf16(v1[0], v1[1]); w.w = cvt_pk_bf16(v1[2], v1[3]);
;                     *(u32x4*)(VT + (size_t)r * NT + t0) = w;
;                 }
	s_setprio 1
	v_mfma_f32_16x16x32_bf16 v[48:51], v[194:197], v[162:165], v[48:51]
	v_mfma_f32_16x16x32_bf16 v[40:43], v[206:209], v[162:165], v[40:43]
	v_mfma_f32_16x16x32_bf16 v[32:35], v[194:197], v[170:173], v[32:35]
	v_mfma_f32_16x16x32_bf16 v[24:27], v[206:209], v[170:173], v[24:27]
	v_mfma_f32_16x16x32_bf16 v[16:19], v[194:197], v[178:181], v[16:19]
	v_mfma_f32_16x16x32_bf16 v[8:11], v[206:209], v[178:181], v[8:11]
	v_mfma_f32_16x16x32_bf16 v[4:7], v[194:197], v[186:189], v[4:7]
	v_mfma_f32_16x16x32_bf16 v[0:3], v[206:209], v[186:189], v[0:3]
	v_mfma_f32_16x16x32_bf16 v[48:51], v[202:205], v[166:169], v[48:51]
	v_mfma_f32_16x16x32_bf16 v[40:43], v[210:213], v[166:169], v[40:43]
	v_mfma_f32_16x16x32_bf16 v[32:35], v[202:205], v[174:177], v[32:35]
	v_mfma_f32_16x16x32_bf16 v[24:27], v[210:213], v[174:177], v[24:27]
	v_mfma_f32_16x16x32_bf16 v[16:19], v[202:205], v[182:185], v[16:19]
	v_mfma_f32_16x16x32_bf16 v[8:11], v[210:213], v[182:185], v[8:11]
	v_mfma_f32_16x16x32_bf16 v[4:7], v[202:205], v[190:193], v[4:7]
	v_mfma_f32_16x16x32_bf16 v[0:3], v[210:213], v[190:193], v[0:3]
	s_setprio 0
	s_add_i32 s58, s58, 2
	s_add_u32 s22, s22, 0x100
	s_addc_u32 s23, s23, 0
	s_add_u32 s56, s56, 0x100
	s_addc_u32 s57, s57, 0
	s_cmp_gt_u32 s58, 13
	s_barrier
	s_cbranch_scc0 .LBB0_713
	v_mov_b32_e32 v146, v140
	v_mov_b32_e32 v147, v141
	s_lshl_b32 s13, s20, 8
	s_add_i32 s13, s13, s41
	v_add_u32_e32 v146, s13, v146
	s_lshl_b32 s13, s53, 8
	s_or_b32 s13, s13, s42
	v_lshl_add_u32 v148, v147, 3, s13
	v_ashrrev_i32_e32 v147, 31, v146
	v_cvt_pk_bf16_f32 v124, v124, v125
	v_cvt_pk_bf16_f32 v125, v126, v127
	v_cvt_pk_bf16_f32 v126, v120, v121
	v_lshlrev_b64 v[120:121], 14, v[146:147]
	v_lshl_add_u64 v[120:121], s[62:63], 0, v[120:121]
	v_ashrrev_i32_e32 v149, 31, v148
	v_lshl_add_u64 v[120:121], v[148:149], 1, v[120:121]
	s_mov_b32 s13, 0x40000
	v_cvt_pk_bf16_f32 v127, v122, v123
	global_store_dwordx4 v[120:121], v[124:127], off
	v_cvt_pk_bf16_f32 v112, v112, v113
	v_cvt_pk_bf16_f32 v113, v114, v115
	v_cvt_pk_bf16_f32 v114, v104, v105
	v_cvt_pk_bf16_f32 v115, v106, v107
	global_store_dwordx4 v[120:121], v[112:115], off offset:256
	v_cvt_pk_bf16_f32 v104, v116, v117
	v_cvt_pk_bf16_f32 v105, v118, v119
	v_cvt_pk_bf16_f32 v106, v108, v109
	v_cvt_pk_bf16_f32 v107, v110, v111
	s_mov_b64 s[22:23], 0x40000
	v_add_co_u32_e32 v110, vcc, s13, v120
	v_lshl_add_u64 v[108:109], v[120:121], 0, s[22:23]
	s_nop 0
	v_addc_co_u32_e32 v111, vcc, 0, v121, vcc
	s_mov_b32 s13, 0x80000
	global_store_dwordx4 v[110:111], v[104:107], off
	v_cvt_pk_bf16_f32 v96, v96, v97
	v_cvt_pk_bf16_f32 v97, v98, v99
	v_cvt_pk_bf16_f32 v98, v88, v89
	v_cvt_pk_bf16_f32 v99, v90, v91
	global_store_dwordx4 v[108:109], v[96:99], off offset:256
	v_cvt_pk_bf16_f32 v88, v100, v101
	v_cvt_pk_bf16_f32 v89, v102, v103
	v_cvt_pk_bf16_f32 v90, v92, v93
	v_cvt_pk_bf16_f32 v91, v94, v95
	s_mov_b64 s[22:23], 0x80000
	v_add_co_u32_e32 v94, vcc, s13, v120
	v_lshl_add_u64 v[92:93], v[120:121], 0, s[22:23]
	s_nop 0
	v_addc_co_u32_e32 v95, vcc, 0, v121, vcc
	global_store_dwordx4 v[94:95], v[88:91], off
	v_cvt_pk_bf16_f32 v80, v80, v81
	v_cvt_pk_bf16_f32 v81, v82, v83
	v_cvt_pk_bf16_f32 v82, v72, v73
	v_cvt_pk_bf16_f32 v83, v74, v75
	global_store_dwordx4 v[92:93], v[80:83], off offset:256
	v_cvt_pk_bf16_f32 v72, v84, v85
	v_cvt_pk_bf16_f32 v73, v86, v87
	v_cvt_pk_bf16_f32 v74, v76, v77
	v_cvt_pk_bf16_f32 v75, v78, v79
	s_mov_b64 s[22:23], 0xc0000
	v_add_co_u32_e32 v78, vcc, s48, v120
	v_lshl_add_u64 v[76:77], v[120:121], 0, s[22:23]
	s_nop 0
	v_addc_co_u32_e32 v79, vcc, 0, v121, vcc
	global_store_dwordx4 v[78:79], v[72:75], off
	v_cvt_pk_bf16_f32 v68, v68, v69
	v_cvt_pk_bf16_f32 v69, v70, v71
	v_cvt_pk_bf16_f32 v70, v64, v65
	v_cvt_pk_bf16_f32 v71, v66, v67
	global_store_dwordx4 v[76:77], v[68:71], off offset:256
	v_cvt_pk_bf16_f32 v60, v60, v61
	v_cvt_pk_bf16_f32 v61, v62, v63
	v_cvt_pk_bf16_f32 v62, v56, v57
	v_cvt_pk_bf16_f32 v63, v58, v59
	v_add_co_u32_e32 v58, vcc, s49, v120
	v_lshl_add_u64 v[56:57], v[120:121], 0, s[2:3]
	s_nop 0
	v_addc_co_u32_e32 v59, vcc, 0, v121, vcc
	global_store_dwordx4 v[58:59], v[60:63], off
	v_cvt_pk_bf16_f32 v48, v48, v49
	v_cvt_pk_bf16_f32 v49, v50, v51
	v_cvt_pk_bf16_f32 v50, v40, v41
	v_cvt_pk_bf16_f32 v51, v42, v43
	global_store_dwordx4 v[56:57], v[48:51], off offset:256
	v_cvt_pk_bf16_f32 v40, v52, v53
	v_cvt_pk_bf16_f32 v41, v54, v55
	v_cvt_pk_bf16_f32 v42, v44, v45
	v_cvt_pk_bf16_f32 v43, v46, v47
	v_add_co_u32_e32 v46, vcc, s50, v120
	v_lshl_add_u64 v[44:45], v[120:121], 0, s[4:5]
	s_nop 0
	v_addc_co_u32_e32 v47, vcc, 0, v121, vcc
	global_store_dwordx4 v[46:47], v[40:43], off
	v_cvt_pk_bf16_f32 v32, v32, v33
	v_cvt_pk_bf16_f32 v33, v34, v35
	v_cvt_pk_bf16_f32 v34, v24, v25
	v_cvt_pk_bf16_f32 v35, v26, v27
	global_store_dwordx4 v[44:45], v[32:35], off offset:256
	v_cvt_pk_bf16_f32 v24, v36, v37
	v_cvt_pk_bf16_f32 v25, v38, v39
	v_cvt_pk_bf16_f32 v26, v28, v29
	v_cvt_pk_bf16_f32 v27, v30, v31
	v_add_co_u32_e32 v30, vcc, s51, v120
	v_lshl_add_u64 v[28:29], v[120:121], 0, s[6:7]
	s_nop 0
	v_addc_co_u32_e32 v31, vcc, 0, v121, vcc
	global_store_dwordx4 v[30:31], v[24:27], off
	v_cvt_pk_bf16_f32 v16, v16, v17
	v_cvt_pk_bf16_f32 v17, v18, v19
	v_cvt_pk_bf16_f32 v18, v8, v9
	v_cvt_pk_bf16_f32 v19, v10, v11
	global_store_dwordx4 v[28:29], v[16:19], off offset:256
	v_cvt_pk_bf16_f32 v8, v20, v21
	v_cvt_pk_bf16_f32 v9, v22, v23
	v_cvt_pk_bf16_f32 v10, v12, v13
	v_cvt_pk_bf16_f32 v11, v14, v15
	v_add_co_u32_e32 v14, vcc, s52, v120
	v_lshl_add_u64 v[12:13], v[120:121], 0, s[8:9]
	s_nop 0
	v_addc_co_u32_e32 v15, vcc, 0, v121, vcc
	s_and_b64 vcc, exec, s[10:11]
	s_mov_b32 s53, s12
	s_mov_b32 s20, s14
	s_mov_b64 s[24:25], s[18:19]
	s_mov_b64 s[22:23], s[16:17]
	global_store_dwordx4 v[14:15], v[8:11], off
	v_cvt_pk_bf16_f32 v4, v4, v5
	v_cvt_pk_bf16_f32 v5, v6, v7
	v_cvt_pk_bf16_f32 v6, v0, v1
	v_cvt_pk_bf16_f32 v7, v2, v3
	global_store_dwordx4 v[12:13], v[4:7], off offset:256
	s_cbranch_vccz .LBB0_706
	s_waitcnt vmcnt(0)
	s_cmpk_gt_u32 s31, 0xff
	s_cbranch_scc1 .LBB0_717
	s_barrier

; #define PG8_STAGE(bufoff, gbase, voff) do { _Pragma("unroll") for (int _i = 0; _i < 2; ++_i) \
;         __builtin_amdgcn_global_load_lds((const unsigned*)((const char*)(gbase) + (voff)[_i]), (LAS unsigned*)(lds + (bufoff) + ldsw + _i * 8192), 16, 0, 0); } while (0)
; #define PG8_LDA(dst, b, h) do { _Pragma("unroll") for (int m = 0; m < 4; ++m) _Pragma("unroll") for (int k = 0; k < 2; ++k) dst[m][k] = *(const LAS bf16x8*)(lds + PG8_SA(b, h) + aoff + m * 2048 + k * 1024); } while (0)
; #define PG8_LDB(dst, b, h) do { _Pragma("unroll") for (int n = 0; n < 2; ++n) _Pragma("unroll") for (int k = 0; k < 2; ++k) dst[n][k] = *(const LAS bf16x8*)(lds + PG8_SB(b, h) + boff + n * 2048 + k * 1024); } while (0)
; #define PG8_MMA(ai, bj, At, Bt) do { __builtin_amdgcn_s_setprio(1); _Pragma("unroll") for (int m = 0; m < 4; ++m) _Pragma("unroll") for (int n = 0; n < 2; ++n) _Pragma("unroll") for (int k = 0; k < 2; ++k) \
;         acc[ai][bj][m][n] = __builtin_amdgcn_mfma_f32_16x16x32_bf16(Bt[n][k], At[m][k], acc[ai][bj][m][n], 0, 0, 0); __builtin_amdgcn_s_setprio(0); } while (0)
; #define PG8_WAIT_L(n) asm volatile("s_waitcnt lgkmcnt(" #n ")" ::: "memory")
; template <class Epi, class Sched>
; __device__ __forceinline__ void gemm_phase(LAS unsigned char* lds, const Gemm g, const Sched& S, const Epi& E) {
;     ...
;         const bool has_next = S.next(ui + 1, nxt);
;         const char* nA = has_next ? (const char*)g.A + (size_t)nxt.pm * tstep : cA; const char* nB = has_next ? (const char*)g.Bt + (size_t)nxt.pn * tstep : cB;
;         for (int t = 0; t < nt; t += 2) {
;             const bool last = (t == nt - 2);
;             const char* a1 = cA + (size_t)(t + 1) * kstep;
;             const char* a2 = last ? nA : cA + (size_t)(t + 2) * kstep; const char* b2 = last ? nB : cB + (size_t)(t + 2) * kstep;
;             const char* a3 = a2 + kstep; const char* b3 = b2 + kstep;
;             PG8_LDB(B0, 0, 0); PG8_SCHED; PG8_LDA(At, 0, 0); PG8_STAGE(PG8_SA(1, 1), a1 + hstep, voffA);
;             PG8_WAIT_L(8); PG8_BAR; PG8_WAIT_L(0); PG8_MMA(0, 0, At, B0); PG8_BAR; PG8_SCHED;
;             PG8_LDB(B1, 0, 1); PG8_STAGE(PG8_SB(0, 0), b2, voffB);
;             PG8_BAR; PG8_WAIT_L(0); PG8_MMA(0, 1, At, B1); PG8_BAR;
;             PG8_LDA(At, 0, 1); PG8_STAGE(PG8_SA(0, 0), a2, voffA);
;             PG8_BAR; PG8_WAIT_L(0); PG8_MMA(1, 0, At, B0); PG8_BAR; PG8_SCHED;
.LBB0_825:
	s_ashr_i32 s7, s6, 31
	v_cmp_lt_i64_e32 vcc, s[8:9], v[156:157]
	s_lshl_b64 s[8:9], s[6:7], 20
	s_add_u32 s8, s22, s8
	s_addc_u32 s9, s23, s9
	s_and_b64 s[10:11], vcc, exec
	s_cselect_b32 s7, s9, s15
	s_cselect_b32 s39, s8, s14
	s_ashr_i32 s5, s4, 31
	s_lshl_b64 s[10:11], s[4:5], 20
	s_add_u32 s10, s50, s10
	s_addc_u32 s11, s51, s11
	s_and_b64 s[18:19], vcc, exec
	s_cselect_b32 s5, s11, s17
	s_cselect_b32 s40, s10, s16
	s_add_u32 s14, s14, 0x80080
	s_addc_u32 s15, s15, 0
	s_add_u32 s41, s16, 0x100
	s_addc_u32 s42, s17, 0
	s_mov_b32 s43, -2
	ds_read_b128 v[128:131], v168
	ds_read_b128 v[132:135], v168 offset:1024
	ds_read_b128 v[136:139], v168 offset:2048
	ds_read_b128 v[140:143], v168 offset:3072
	s_add_u32 s16, s14, 0xfff80080
	s_addc_u32 s17, s15, -1
	s_cmp_eq_u32 s43, 28
	s_cselect_b32 s19, s7, s17
	s_cselect_b32 s18, s39, s16
	s_cselect_b32 s17, s5, s42
	s_cselect_b32 s16, s40, s41
	s_add_i32 m0, s13, 0xc000
	ds_read_b128 v[162:165], v169
	ds_read_b128 v[172:175], v169 offset:1024
	ds_read_b128 v[176:179], v169 offset:2048
	ds_read_b128 v[180:183], v169 offset:3072
	ds_read_b128 v[184:187], v169 offset:4096
	ds_read_b128 v[188:191], v169 offset:5120
	ds_read_b128 v[192:195], v169 offset:6144
	ds_read_b128 v[196:199], v169 offset:7168
	global_load_lds_dwordx4 v152, s[14:15]
	s_add_i32 m0, s13, 0xe000
	s_nop 0
	global_load_lds_dwordx4 v154, s[14:15]
	s_waitcnt lgkmcnt(8)
	s_waitcnt vmcnt(10)
	s_barrier
	s_waitcnt lgkmcnt(0)
	s_setprio 1
	s_waitcnt lgkmcnt(0)
	v_mfma_f32_16x16x32_bf16 v[124:127], v[128:131], v[162:165], 0
	v_mfma_f32_16x16x32_bf16 v[120:123], v[136:139], v[162:165], 0
	v_mfma_f32_16x16x32_bf16 v[116:119], v[128:131], v[176:179], 0
	v_mfma_f32_16x16x32_bf16 v[112:115], v[136:139], v[176:179], 0
	v_mfma_f32_16x16x32_bf16 v[108:111], v[128:131], v[184:187], 0
	v_mfma_f32_16x16x32_bf16 v[100:103], v[136:139], v[184:187], 0
	v_mfma_f32_16x16x32_bf16 v[76:79], v[128:131], v[192:195], 0
	v_mfma_f32_16x16x32_bf16 v[72:75], v[136:139], v[192:195], 0
	v_mfma_f32_16x16x32_bf16 v[124:127], v[132:135], v[172:175], v[124:127]
	v_mfma_f32_16x16x32_bf16 v[120:123], v[140:143], v[172:175], v[120:123]
	v_mfma_f32_16x16x32_bf16 v[116:119], v[132:135], v[180:183], v[116:119]
	v_mfma_f32_16x16x32_bf16 v[112:115], v[140:143], v[180:183], v[112:115]
	v_mfma_f32_16x16x32_bf16 v[108:111], v[132:135], v[188:191], v[108:111]
	v_mfma_f32_16x16x32_bf16 v[100:103], v[140:143], v[188:191], v[100:103]
	v_mfma_f32_16x16x32_bf16 v[76:79], v[132:135], v[196:199], v[76:79]
	v_mfma_f32_16x16x32_bf16 v[72:75], v[140:143], v[196:199], v[72:75]
	s_setprio 0
	s_barrier
	s_add_i32 s44, s35, s24
	s_mov_b32 m0, s44
	ds_read_b128 v[202:205], v170
	ds_read_b128 v[206:209], v170 offset:1024
	ds_read_b128 v[210:213], v170 offset:2048
	ds_read_b128 v[214:217], v170 offset:3072
	global_load_lds_dwordx4 v146, s[16:17]
	s_add_i32 m0, s44, 0x2000
	s_nop 0
	global_load_lds_dwordx4 v150, s[16:17]
	s_waitcnt vmcnt(10)
	s_barrier
	s_waitcnt lgkmcnt(0)
	s_setprio 1
	s_waitcnt lgkmcnt(0)
	v_mfma_f32_16x16x32_bf16 v[104:107], v[202:205], v[162:165], 0
	v_mfma_f32_16x16x32_bf16 v[96:99], v[210:213], v[162:165], 0
	v_mfma_f32_16x16x32_bf16 v[92:95], v[202:205], v[176:179], 0
	v_mfma_f32_16x16x32_bf16 v[88:91], v[210:213], v[176:179], 0
	v_mfma_f32_16x16x32_bf16 v[84:87], v[202:205], v[184:187], 0
	v_mfma_f32_16x16x32_bf16 v[80:83], v[210:213], v[184:187], 0
	v_mfma_f32_16x16x32_bf16 v[68:71], v[202:205], v[192:195], 0
	v_mfma_f32_16x16x32_bf16 v[64:67], v[210:213], v[192:195], 0
	v_mfma_f32_16x16x32_bf16 v[104:107], v[206:209], v[172:175], v[104:107]
	v_mfma_f32_16x16x32_bf16 v[96:99], v[214:217], v[172:175], v[96:99]
	v_mfma_f32_16x16x32_bf16 v[92:95], v[206:209], v[180:183], v[92:95]
	v_mfma_f32_16x16x32_bf16 v[88:91], v[214:217], v[180:183], v[88:91]
	v_mfma_f32_16x16x32_bf16 v[84:87], v[206:209], v[188:191], v[84:87]
	v_mfma_f32_16x16x32_bf16 v[80:83], v[214:217], v[188:191], v[80:83]
	v_mfma_f32_16x16x32_bf16 v[68:71], v[206:209], v[196:199], v[68:71]
	v_mfma_f32_16x16x32_bf16 v[64:67], v[214:217], v[196:199], v[64:67]
	s_setprio 0
	s_mov_b32 m0, s13
	v_lshl_add_u64 v[222:223], s[18:19], 0, v[144:145]
	s_barrier
	ds_read_b128 v[162:165], v169 offset:16384
	ds_read_b128 v[172:175], v169 offset:17408
	ds_read_b128 v[176:179], v169 offset:18432
	ds_read_b128 v[180:183], v169 offset:19456
	ds_read_b128 v[184:187], v169 offset:20480
	ds_read_b128 v[188:191], v169 offset:21504
	ds_read_b128 v[192:195], v169 offset:22528
	ds_read_b128 v[196:199], v169 offset:23552
	global_load_lds_dwordx4 v144, s[18:19]
	v_lshl_add_u64 v[224:225], s[18:19], 0, v[148:149]
	s_mov_b32 m0, s25
	s_nop 0
	global_load_lds_dwordx4 v148, s[18:19]
	s_barrier
	s_waitcnt lgkmcnt(0)
	s_setprio 1
	s_waitcnt lgkmcnt(0)
	v_mfma_f32_16x16x32_bf16 v[60:63], v[128:131], v[162:165], 0
	v_mfma_f32_16x16x32_bf16 v[56:59], v[136:139], v[162:165], 0
	v_mfma_f32_16x16x32_bf16 v[48:51], v[128:131], v[176:179], 0
	v_mfma_f32_16x16x32_bf16 v[40:43], v[136:139], v[176:179], 0
	v_mfma_f32_16x16x32_bf16 v[32:35], v[128:131], v[184:187], 0
	v_mfma_f32_16x16x32_bf16 v[24:27], v[136:139], v[184:187], 0
	v_mfma_f32_16x16x32_bf16 v[16:19], v[128:131], v[192:195], 0
	v_mfma_f32_16x16x32_bf16 v[8:11], v[136:139], v[192:195], 0
	v_mfma_f32_16x16x32_bf16 v[60:63], v[132:135], v[172:175], v[60:63]
	v_mfma_f32_16x16x32_bf16 v[56:59], v[140:143], v[172:175], v[56:59]
	v_mfma_f32_16x16x32_bf16 v[48:51], v[132:135], v[180:183], v[48:51]
	v_mfma_f32_16x16x32_bf16 v[40:43], v[140:143], v[180:183], v[40:43]
	v_mfma_f32_16x16x32_bf16 v[32:35], v[132:135], v[188:191], v[32:35]
	v_mfma_f32_16x16x32_bf16 v[24:27], v[140:143], v[188:191], v[24:27]
	v_mfma_f32_16x16x32_bf16 v[16:19], v[132:135], v[196:199], v[16:19]
	v_mfma_f32_16x16x32_bf16 v[8:11], v[140:143], v[196:199], v[8:11]
	s_setprio 0
	s_barrier
; #define PG8_STAGE(bufoff, gbase, voff) do { _Pragma("unroll") for (int _i = 0; _i < 2; ++_i) \
;         __builtin_amdgcn_global_load_lds((const unsigned*)((const char*)(gbase) + (voff)[_i]), (LAS unsigned*)(lds + (bufoff) + ldsw + _i * 8192), 16, 0, 0); } while (0)
; #define PG8_LDA(dst, b, h) do { _Pragma("unroll") for (int m = 0; m < 4; ++m) _Pragma("unroll") for (int k = 0; k < 2; ++k) dst[m][k] = *(const LAS bf16x8*)(lds + PG8_SA(b, h) + aoff + m * 2048 + k * 1024); } while (0)
; #define PG8_LDB(dst, b, h) do { _Pragma("unroll") for (int n = 0; n < 2; ++n) _Pragma("unroll") for (int k = 0; k < 2; ++k) dst[n][k] = *(const LAS bf16x8*)(lds + PG8_SB(b, h) + boff + n * 2048 + k * 1024); } while (0)
; #define PG8_MMA(ai, bj, At, Bt) do { __builtin_amdgcn_s_setprio(1); _Pragma("unroll") for (int m = 0; m < 4; ++m) _Pragma("unroll") for (int n = 0; n < 2; ++n) _Pragma("unroll") for (int k = 0; k < 2; ++k) \
;         acc[ai][bj][m][n] = __builtin_amdgcn_mfma_f32_16x16x32_bf16(Bt[n][k], At[m][k], acc[ai][bj][m][n], 0, 0, 0); __builtin_amdgcn_s_setprio(0); } while (0)
; #define PG8_WAIT_V(n) asm volatile("s_waitcnt vmcnt(" #n ")" ::: "memory")
; #define PG8_WAIT_L(n) asm volatile("s_waitcnt lgkmcnt(" #n ")" ::: "memory")
; #define PG8_BAR __builtin_amdgcn_s_barrier()
; #define PG8_SCHED __builtin_amdgcn_sched_barrier(0)
; template <class Epi, class Sched>
; __device__ __forceinline__ void gemm_phase(LAS unsigned char* lds, const Gemm g, const Sched& S, const Epi& E) {
;     ...
;             PG8_STAGE(PG8_SB(0, 1), b2 + hstep, voffB);
;             PG8_WAIT_V(6); PG8_BAR; PG8_MMA(1, 1, At, B1); PG8_BAR;
;             PG8_LDB(B0, 1, 0); PG8_SCHED; PG8_LDA(At, 1, 0); PG8_STAGE(PG8_SA(0, 1), a2 + hstep, voffA);
;             PG8_WAIT_L(8); PG8_BAR; PG8_WAIT_L(0); PG8_MMA(0, 0, At, B0); PG8_BAR; PG8_SCHED;
;             PG8_LDB(B1, 1, 1); PG8_STAGE(PG8_SB(1, 0), b3, voffB);
;             PG8_BAR; PG8_WAIT_L(0); PG8_MMA(0, 1, At, B1); PG8_BAR;
;             PG8_LDA(At, 1, 1); PG8_STAGE(PG8_SA(1, 0), a3, voffA);
	s_add_u32 s44, s16, 0x80000
	s_addc_u32 s45, s17, 0
	s_add_i32 s46, s36, s24
	s_mov_b32 m0, s46
	s_nop 0
	global_load_lds_dwordx4 v146, s[44:45]
	s_add_i32 m0, s46, 0x2000
	s_nop 0
	global_load_lds_dwordx4 v150, s[44:45]
	s_add_u32 s18, s18, 0x80000
	s_addc_u32 s19, s19, 0
	s_mov_b32 m0, s26
	s_nop 0
	global_load_lds_dwordx4 v144, s[18:19]
	s_mov_b32 m0, s27
	s_nop 0
	global_load_lds_dwordx4 v148, s[18:19]
	s_waitcnt vmcnt(12)
	s_barrier
	s_setprio 1
	v_mfma_f32_16x16x32_bf16 v[52:55], v[202:205], v[162:165], 0
	v_mfma_f32_16x16x32_bf16 v[44:47], v[210:213], v[162:165], 0
	v_mfma_f32_16x16x32_bf16 v[36:39], v[202:205], v[176:179], 0
	v_mfma_f32_16x16x32_bf16 v[28:31], v[210:213], v[176:179], 0
	v_mfma_f32_16x16x32_bf16 v[20:23], v[202:205], v[184:187], 0
	v_mfma_f32_16x16x32_bf16 v[12:15], v[210:213], v[184:187], 0
	v_mfma_f32_16x16x32_bf16 v[4:7], v[202:205], v[192:195], 0
	v_mfma_f32_16x16x32_bf16 v[0:3], v[210:213], v[192:195], 0
	v_mfma_f32_16x16x32_bf16 v[52:55], v[206:209], v[172:175], v[52:55]
	v_mfma_f32_16x16x32_bf16 v[44:47], v[214:217], v[172:175], v[44:47]
	v_mfma_f32_16x16x32_bf16 v[36:39], v[206:209], v[180:183], v[36:39]
	v_mfma_f32_16x16x32_bf16 v[28:31], v[214:217], v[180:183], v[28:31]
	v_mfma_f32_16x16x32_bf16 v[20:23], v[206:209], v[188:191], v[20:23]
	v_mfma_f32_16x16x32_bf16 v[12:15], v[214:217], v[188:191], v[12:15]
	v_mfma_f32_16x16x32_bf16 v[4:7], v[206:209], v[196:199], v[4:7]
	v_mfma_f32_16x16x32_bf16 v[0:3], v[214:217], v[196:199], v[0:3]
	s_setprio 0
	s_add_i32 s44, 0, 0x18000
	v_add_u32_e32 v140, s44, v167
	s_barrier
	ds_read_b128 v[128:131], v140
	ds_read_b128 v[132:135], v140 offset:1024
	ds_read_b128 v[136:139], v140 offset:2048
	ds_read_b128 v[140:143], v140 offset:3072
	ds_read_b128 v[162:165], v169 offset:32768
	ds_read_b128 v[172:175], v169 offset:33792
	ds_read_b128 v[176:179], v169 offset:34816
	ds_read_b128 v[180:183], v169 offset:35840
	ds_read_b128 v[184:187], v169 offset:36864
	ds_read_b128 v[188:191], v169 offset:37888
	ds_read_b128 v[192:195], v169 offset:38912
	ds_read_b128 v[196:199], v169 offset:39936
	s_waitcnt lgkmcnt(8)
	s_waitcnt vmcnt(10)
	s_barrier
	s_waitcnt lgkmcnt(0)
	s_setprio 1
	s_waitcnt lgkmcnt(0)
	v_mfma_f32_16x16x32_bf16 v[124:127], v[128:131], v[162:165], v[124:127]
	v_mfma_f32_16x16x32_bf16 v[120:123], v[136:139], v[162:165], v[120:123]
	v_mfma_f32_16x16x32_bf16 v[116:119], v[128:131], v[176:179], v[116:119]
	v_mfma_f32_16x16x32_bf16 v[112:115], v[136:139], v[176:179], v[112:115]
	v_mfma_f32_16x16x32_bf16 v[108:111], v[128:131], v[184:187], v[108:111]
	v_mfma_f32_16x16x32_bf16 v[100:103], v[136:139], v[184:187], v[100:103]
	v_mfma_f32_16x16x32_bf16 v[76:79], v[128:131], v[192:195], v[76:79]
	v_mfma_f32_16x16x32_bf16 v[72:75], v[136:139], v[192:195], v[72:75]
	v_mfma_f32_16x16x32_bf16 v[124:127], v[132:135], v[172:175], v[124:127]
	v_mfma_f32_16x16x32_bf16 v[120:123], v[140:143], v[172:175], v[120:123]
	v_mfma_f32_16x16x32_bf16 v[116:119], v[132:135], v[180:183], v[116:119]
	v_mfma_f32_16x16x32_bf16 v[112:115], v[140:143], v[180:183], v[112:115]
	v_mfma_f32_16x16x32_bf16 v[108:111], v[132:135], v[188:191], v[108:111]
	v_mfma_f32_16x16x32_bf16 v[100:103], v[140:143], v[188:191], v[100:103]
	v_mfma_f32_16x16x32_bf16 v[76:79], v[132:135], v[196:199], v[76:79]
	v_mfma_f32_16x16x32_bf16 v[72:75], v[140:143], v[196:199], v[72:75]
	s_setprio 0
	s_barrier
	s_add_i32 s18, 0, 0x1c000
	s_add_i32 s19, s44, s24
	v_add_u32_e32 v160, s18, v167
	s_add_u32 s0, s16, 0x80
	s_addc_u32 s1, s17, 0
	s_mov_b32 m0, s19
	ds_read_b128 v[202:205], v160
	ds_read_b128 v[206:209], v160 offset:1024
	ds_read_b128 v[210:213], v160 offset:2048
	ds_read_b128 v[214:217], v160 offset:3072
	global_load_lds_dwordx4 v146, s[0:1]
	s_add_i32 m0, s19, 0x2000
	s_nop 0
	global_load_lds_dwordx4 v150, s[0:1]
	s_waitcnt vmcnt(10)
	s_barrier
	s_waitcnt lgkmcnt(0)
	s_setprio 1
	s_waitcnt lgkmcnt(0)
	v_mfma_f32_16x16x32_bf16 v[104:107], v[202:205], v[162:165], v[104:107]
	v_mfma_f32_16x16x32_bf16 v[96:99], v[210:213], v[162:165], v[96:99]
	v_mfma_f32_16x16x32_bf16 v[92:95], v[202:205], v[176:179], v[92:95]
	v_mfma_f32_16x16x32_bf16 v[88:91], v[210:213], v[176:179], v[88:91]
	v_mfma_f32_16x16x32_bf16 v[84:87], v[202:205], v[184:187], v[84:87]
	v_mfma_f32_16x16x32_bf16 v[80:83], v[210:213], v[184:187], v[80:83]
	v_mfma_f32_16x16x32_bf16 v[68:71], v[202:205], v[192:195], v[68:71]
	v_mfma_f32_16x16x32_bf16 v[64:67], v[210:213], v[192:195], v[64:67]
	v_mfma_f32_16x16x32_bf16 v[104:107], v[206:209], v[172:175], v[104:107]
	v_mfma_f32_16x16x32_bf16 v[96:99], v[214:217], v[172:175], v[96:99]
	v_mfma_f32_16x16x32_bf16 v[92:95], v[206:209], v[180:183], v[92:95]
	v_mfma_f32_16x16x32_bf16 v[88:91], v[214:217], v[180:183], v[88:91]
	v_mfma_f32_16x16x32_bf16 v[84:87], v[206:209], v[188:191], v[84:87]
	v_mfma_f32_16x16x32_bf16 v[80:83], v[214:217], v[188:191], v[80:83]
	v_mfma_f32_16x16x32_bf16 v[68:71], v[206:209], v[196:199], v[68:71]
	v_mfma_f32_16x16x32_bf16 v[64:67], v[214:217], v[196:199], v[64:67]
	s_setprio 0
	s_mov_b32 m0, s31
	s_mov_b64 s[0:1], 0x80
	v_lshl_add_u64 v[218:219], v[222:223], 0, s[0:1]
	s_barrier
	ds_read_b128 v[162:165], v169 offset:49152
	ds_read_b128 v[172:175], v169 offset:50176
	ds_read_b128 v[176:179], v169 offset:51200
	ds_read_b128 v[180:183], v169 offset:52224
	ds_read_b128 v[184:187], v169 offset:53248
	ds_read_b128 v[188:191], v169 offset:54272
	ds_read_b128 v[192:195], v169 offset:55296
	ds_read_b128 v[196:199], v169 offset:56320
	global_load_lds_dwordx4 v[218:219], off
	v_lshl_add_u64 v[218:219], v[224:225], 0, s[0:1]
	s_mov_b32 m0, s33
	s_nop 0
	global_load_lds_dwordx4 v[218:219], off
	s_barrier
; #define PG8_STAGE(bufoff, gbase, voff) do { _Pragma("unroll") for (int _i = 0; _i < 2; ++_i) \
;         __builtin_amdgcn_global_load_lds((const unsigned*)((const char*)(gbase) + (voff)[_i]), (LAS unsigned*)(lds + (bufoff) + ldsw + _i * 8192), 16, 0, 0); } while (0)
; #define PG8_LDA(dst, b, h) do { _Pragma("unroll") for (int m = 0; m < 4; ++m) _Pragma("unroll") for (int k = 0; k < 2; ++k) dst[m][k] = *(const LAS bf16x8*)(lds + PG8_SA(b, h) + aoff + m * 2048 + k * 1024); } while (0)
; #define PG8_LDB(dst, b, h) do { _Pragma("unroll") for (int n = 0; n < 2; ++n) _Pragma("unroll") for (int k = 0; k < 2; ++k) dst[n][k] = *(const LAS bf16x8*)(lds + PG8_SB(b, h) + boff + n * 2048 + k * 1024); } while (0)
; #define PG8_MMA(ai, bj, At, Bt) do { __builtin_amdgcn_s_setprio(1); _Pragma("unroll") for (int m = 0; m < 4; ++m) _Pragma("unroll") for (int n = 0; n < 2; ++n) _Pragma("unroll") for (int k = 0; k < 2; ++k) \
;         acc[ai][bj][m][n] = __builtin_amdgcn_mfma_f32_16x16x32_bf16(Bt[n][k], At[m][k], acc[ai][bj][m][n], 0, 0, 0); __builtin_amdgcn_s_setprio(0); } while (0)
; #define PG8_WAIT_V(n) asm volatile("s_waitcnt vmcnt(" #n ")" ::: "memory")
; #define PG8_WAIT_L(n) asm volatile("s_waitcnt lgkmcnt(" #n ")" ::: "memory")
; template <class Epi, class Sched>
; __device__ __forceinline__ void gemm_phase(LAS unsigned char* lds, const Gemm g, const Sched& S, const Epi& E) {
;     ...
;         for (int t = 0; t < nt; t += 2) {
;             const bool last = (t == nt - 2);
;             const char* a1 = cA + (size_t)(t + 1) * kstep;
;             const char* a2 = last ? nA : cA + (size_t)(t + 2) * kstep; const char* b2 = last ? nB : cB + (size_t)(t + 2) * kstep;
;             const char* a3 = a2 + kstep; const char* b3 = b2 + kstep;
;             PG8_LDB(B0, 0, 0); PG8_SCHED; PG8_LDA(At, 0, 0); PG8_STAGE(PG8_SA(1, 1), a1 + hstep, voffA);
;             PG8_WAIT_L(8); PG8_BAR; PG8_WAIT_L(0); PG8_MMA(0, 0, At, B0); PG8_BAR; PG8_SCHED;
;             PG8_LDB(B1, 0, 1); PG8_STAGE(PG8_SB(0, 0), b2, voffB);
;             PG8_BAR; PG8_WAIT_L(0); PG8_MMA(0, 1, At, B1); PG8_BAR;
;     ...
;             PG8_LDA(At, 1, 1); PG8_STAGE(PG8_SA(1, 0), a3, voffA);
;             PG8_BAR; PG8_WAIT_L(0); PG8_MMA(1, 0, At, B0); PG8_BAR; PG8_SCHED;
;             PG8_STAGE(PG8_SB(1, 1), b3 + hstep, voffB);
;             PG8_WAIT_V(6); PG8_BAR; PG8_MMA(1, 1, At, B1); PG8_BAR;
	s_waitcnt lgkmcnt(0)
	s_setprio 1
	s_waitcnt lgkmcnt(0)
	v_mfma_f32_16x16x32_bf16 v[60:63], v[128:131], v[162:165], v[60:63]
	v_mfma_f32_16x16x32_bf16 v[56:59], v[136:139], v[162:165], v[56:59]
	v_mfma_f32_16x16x32_bf16 v[48:51], v[128:131], v[176:179], v[48:51]
	v_mfma_f32_16x16x32_bf16 v[40:43], v[136:139], v[176:179], v[40:43]
	v_mfma_f32_16x16x32_bf16 v[32:35], v[128:131], v[184:187], v[32:35]
	v_mfma_f32_16x16x32_bf16 v[24:27], v[136:139], v[184:187], v[24:27]
	v_mfma_f32_16x16x32_bf16 v[16:19], v[128:131], v[192:195], v[16:19]
	v_mfma_f32_16x16x32_bf16 v[8:11], v[136:139], v[192:195], v[8:11]
	v_mfma_f32_16x16x32_bf16 v[60:63], v[132:135], v[172:175], v[60:63]
	v_mfma_f32_16x16x32_bf16 v[56:59], v[140:143], v[172:175], v[56:59]
	v_mfma_f32_16x16x32_bf16 v[48:51], v[132:135], v[180:183], v[48:51]
	v_mfma_f32_16x16x32_bf16 v[40:43], v[140:143], v[180:183], v[40:43]
	v_mfma_f32_16x16x32_bf16 v[32:35], v[132:135], v[188:191], v[32:35]
	v_mfma_f32_16x16x32_bf16 v[24:27], v[140:143], v[188:191], v[24:27]
	v_mfma_f32_16x16x32_bf16 v[16:19], v[132:135], v[196:199], v[16:19]
	v_mfma_f32_16x16x32_bf16 v[8:11], v[140:143], v[196:199], v[8:11]
	s_setprio 0
	s_barrier
	s_add_u32 s16, s16, 0x80080
	s_addc_u32 s17, s17, 0
	s_add_i32 s18, s18, s24
	s_mov_b32 m0, s18
	s_nop 0
	global_load_lds_dwordx4 v146, s[16:17]
	s_add_i32 m0, s18, 0x2000
	s_nop 0
	global_load_lds_dwordx4 v150, s[16:17]
	s_waitcnt vmcnt(10)
	s_barrier
	s_setprio 1
	v_mfma_f32_16x16x32_bf16 v[52:55], v[202:205], v[162:165], v[52:55]
	v_mfma_f32_16x16x32_bf16 v[44:47], v[210:213], v[162:165], v[44:47]
	v_mfma_f32_16x16x32_bf16 v[36:39], v[202:205], v[176:179], v[36:39]
	v_mfma_f32_16x16x32_bf16 v[28:31], v[210:213], v[176:179], v[28:31]
	v_mfma_f32_16x16x32_bf16 v[20:23], v[202:205], v[184:187], v[20:23]
	v_mfma_f32_16x16x32_bf16 v[12:15], v[210:213], v[184:187], v[12:15]
	v_mfma_f32_16x16x32_bf16 v[4:7], v[202:205], v[192:195], v[4:7]
	v_mfma_f32_16x16x32_bf16 v[0:3], v[210:213], v[192:195], v[0:3]
	v_mfma_f32_16x16x32_bf16 v[52:55], v[206:209], v[172:175], v[52:55]
	v_mfma_f32_16x16x32_bf16 v[44:47], v[214:217], v[172:175], v[44:47]
	v_mfma_f32_16x16x32_bf16 v[36:39], v[206:209], v[180:183], v[36:39]
	v_mfma_f32_16x16x32_bf16 v[28:31], v[214:217], v[180:183], v[28:31]
	v_mfma_f32_16x16x32_bf16 v[20:23], v[206:209], v[188:191], v[20:23]
	v_mfma_f32_16x16x32_bf16 v[12:15], v[214:217], v[188:191], v[12:15]
	v_mfma_f32_16x16x32_bf16 v[4:7], v[206:209], v[196:199], v[4:7]
	v_mfma_f32_16x16x32_bf16 v[0:3], v[214:217], v[196:199], v[0:3]
	s_setprio 0
	s_add_i32 s43, s43, 2
	s_add_u32 s14, s14, 0x100
	s_addc_u32 s15, s15, 0
	s_add_u32 s41, s41, 0x100
	s_addc_u32 s42, s42, 0
	s_cmp_gt_u32 s43, 29
	s_barrier
.LBB0_826:
	ds_read_b128 v[128:131], v168
	ds_read_b128 v[132:135], v168 offset:1024
	ds_read_b128 v[136:139], v168 offset:2048
	ds_read_b128 v[140:143], v168 offset:3072
	s_add_u32 s16, s14, 0xfff80080
	s_addc_u32 s17, s15, -1
	s_cmp_eq_u32 s43, 28
	s_cselect_b32 s19, s7, s17
	s_cselect_b32 s18, s39, s16
	s_cselect_b32 s17, s5, s42
	s_cselect_b32 s16, s40, s41
	s_add_i32 m0, s13, 0xc000
	ds_read_b128 v[162:165], v169
	ds_read_b128 v[172:175], v169 offset:1024
	ds_read_b128 v[176:179], v169 offset:2048
	ds_read_b128 v[180:183], v169 offset:3072
	ds_read_b128 v[184:187], v169 offset:4096
	ds_read_b128 v[188:191], v169 offset:5120
	ds_read_b128 v[192:195], v169 offset:6144
	ds_read_b128 v[196:199], v169 offset:7168
	global_load_lds_dwordx4 v152, s[14:15]
	s_add_i32 m0, s13, 0xe000
	s_nop 0
	global_load_lds_dwordx4 v154, s[14:15]
	s_waitcnt lgkmcnt(8)
	s_waitcnt vmcnt(10)
	s_barrier
	s_waitcnt lgkmcnt(0)
	s_setprio 1
	s_waitcnt lgkmcnt(0)
	v_mfma_f32_16x16x32_bf16 v[124:127], v[128:131], v[162:165], v[124:127]
	v_mfma_f32_16x16x32_bf16 v[120:123], v[136:139], v[162:165], v[120:123]
	v_mfma_f32_16x16x32_bf16 v[116:119], v[128:131], v[176:179], v[116:119]
	v_mfma_f32_16x16x32_bf16 v[112:115], v[136:139], v[176:179], v[112:115]
	v_mfma_f32_16x16x32_bf16 v[108:111], v[128:131], v[184:187], v[108:111]
	v_mfma_f32_16x16x32_bf16 v[100:103], v[136:139], v[184:187], v[100:103]
	v_mfma_f32_16x16x32_bf16 v[76:79], v[128:131], v[192:195], v[76:79]
	v_mfma_f32_16x16x32_bf16 v[72:75], v[136:139], v[192:195], v[72:75]
	v_mfma_f32_16x16x32_bf16 v[124:127], v[132:135], v[172:175], v[124:127]
	v_mfma_f32_16x16x32_bf16 v[120:123], v[140:143], v[172:175], v[120:123]
	v_mfma_f32_16x16x32_bf16 v[116:119], v[132:135], v[180:183], v[116:119]
	v_mfma_f32_16x16x32_bf16 v[112:115], v[140:143], v[180:183], v[112:115]
	v_mfma_f32_16x16x32_bf16 v[108:111], v[132:135], v[188:191], v[108:111]
	v_mfma_f32_16x16x32_bf16 v[100:103], v[140:143], v[188:191], v[100:103]
	v_mfma_f32_16x16x32_bf16 v[76:79], v[132:135], v[196:199], v[76:79]
	v_mfma_f32_16x16x32_bf16 v[72:75], v[140:143], v[196:199], v[72:75]
	s_setprio 0
	s_barrier
	s_add_i32 s44, s35, s24
	s_mov_b32 m0, s44
	ds_read_b128 v[202:205], v170
	ds_read_b128 v[206:209], v170 offset:1024
	ds_read_b128 v[210:213], v170 offset:2048
	ds_read_b128 v[214:217], v170 offset:3072
	global_load_lds_dwordx4 v146, s[16:17]
	s_add_i32 m0, s44, 0x2000
	s_nop 0
	global_load_lds_dwordx4 v150, s[16:17]
	s_waitcnt vmcnt(10)
	s_barrier
; #define PG8_STAGE(bufoff, gbase, voff) do { _Pragma("unroll") for (int _i = 0; _i < 2; ++_i) \
;         __builtin_amdgcn_global_load_lds((const unsigned*)((const char*)(gbase) + (voff)[_i]), (LAS unsigned*)(lds + (bufoff) + ldsw + _i * 8192), 16, 0, 0); } while (0)
; #define PG8_LDA(dst, b, h) do { _Pragma("unroll") for (int m = 0; m < 4; ++m) _Pragma("unroll") for (int k = 0; k < 2; ++k) dst[m][k] = *(const LAS bf16x8*)(lds + PG8_SA(b, h) + aoff + m * 2048 + k * 1024); } while (0)
; #define PG8_LDB(dst, b, h) do { _Pragma("unroll") for (int n = 0; n < 2; ++n) _Pragma("unroll") for (int k = 0; k < 2; ++k) dst[n][k] = *(const LAS bf16x8*)(lds + PG8_SB(b, h) + boff + n * 2048 + k * 1024); } while (0)
; #define PG8_MMA(ai, bj, At, Bt) do { __builtin_amdgcn_s_setprio(1); _Pragma("unroll") for (int m = 0; m < 4; ++m) _Pragma("unroll") for (int n = 0; n < 2; ++n) _Pragma("unroll") for (int k = 0; k < 2; ++k) \
;         acc[ai][bj][m][n] = __builtin_amdgcn_mfma_f32_16x16x32_bf16(Bt[n][k], At[m][k], acc[ai][bj][m][n], 0, 0, 0); __builtin_amdgcn_s_setprio(0); } while (0)
; #define PG8_WAIT_V(n) asm volatile("s_waitcnt vmcnt(" #n ")" ::: "memory")
; #define PG8_WAIT_L(n) asm volatile("s_waitcnt lgkmcnt(" #n ")" ::: "memory")
; #define PG8_BAR __builtin_amdgcn_s_barrier()
; #define PG8_SCHED __builtin_amdgcn_sched_barrier(0)
; template <class Epi, class Sched>
; __device__ __forceinline__ void gemm_phase(LAS unsigned char* lds, const Gemm g, const Sched& S, const Epi& E) {
;     ...
;             PG8_BAR; PG8_WAIT_L(0); PG8_MMA(0, 1, At, B1); PG8_BAR;
;             PG8_LDA(At, 0, 1); PG8_STAGE(PG8_SA(0, 0), a2, voffA);
;             PG8_BAR; PG8_WAIT_L(0); PG8_MMA(1, 0, At, B0); PG8_BAR; PG8_SCHED;
;             PG8_STAGE(PG8_SB(0, 1), b2 + hstep, voffB);
;             PG8_WAIT_V(6); PG8_BAR; PG8_MMA(1, 1, At, B1); PG8_BAR;
;             PG8_LDB(B0, 1, 0); PG8_SCHED; PG8_LDA(At, 1, 0); PG8_STAGE(PG8_SA(0, 1), a2 + hstep, voffA);
;             PG8_WAIT_L(8); PG8_BAR; PG8_WAIT_L(0); PG8_MMA(0, 0, At, B0); PG8_BAR; PG8_SCHED;
	s_waitcnt lgkmcnt(0)
	s_setprio 1
	s_waitcnt lgkmcnt(0)
	v_mfma_f32_16x16x32_bf16 v[104:107], v[202:205], v[162:165], v[104:107]
	v_mfma_f32_16x16x32_bf16 v[96:99], v[210:213], v[162:165], v[96:99]
	v_mfma_f32_16x16x32_bf16 v[92:95], v[202:205], v[176:179], v[92:95]
	v_mfma_f32_16x16x32_bf16 v[88:91], v[210:213], v[176:179], v[88:91]
	v_mfma_f32_16x16x32_bf16 v[84:87], v[202:205], v[184:187], v[84:87]
	v_mfma_f32_16x16x32_bf16 v[80:83], v[210:213], v[184:187], v[80:83]
	v_mfma_f32_16x16x32_bf16 v[68:71], v[202:205], v[192:195], v[68:71]
	v_mfma_f32_16x16x32_bf16 v[64:67], v[210:213], v[192:195], v[64:67]
	v_mfma_f32_16x16x32_bf16 v[104:107], v[206:209], v[172:175], v[104:107]
	v_mfma_f32_16x16x32_bf16 v[96:99], v[214:217], v[172:175], v[96:99]
	v_mfma_f32_16x16x32_bf16 v[92:95], v[206:209], v[180:183], v[92:95]
	v_mfma_f32_16x16x32_bf16 v[88:91], v[214:217], v[180:183], v[88:91]
	v_mfma_f32_16x16x32_bf16 v[84:87], v[206:209], v[188:191], v[84:87]
	v_mfma_f32_16x16x32_bf16 v[80:83], v[214:217], v[188:191], v[80:83]
	v_mfma_f32_16x16x32_bf16 v[68:71], v[206:209], v[196:199], v[68:71]
	v_mfma_f32_16x16x32_bf16 v[64:67], v[214:217], v[196:199], v[64:67]
	s_setprio 0
	s_mov_b32 m0, s13
	v_lshl_add_u64 v[222:223], s[18:19], 0, v[144:145]
	s_barrier
	ds_read_b128 v[162:165], v169 offset:16384
	ds_read_b128 v[172:175], v169 offset:17408
	ds_read_b128 v[176:179], v169 offset:18432
	ds_read_b128 v[180:183], v169 offset:19456
	ds_read_b128 v[184:187], v169 offset:20480
	ds_read_b128 v[188:191], v169 offset:21504
	ds_read_b128 v[192:195], v169 offset:22528
	ds_read_b128 v[196:199], v169 offset:23552
	global_load_lds_dwordx4 v144, s[18:19]
	v_lshl_add_u64 v[224:225], s[18:19], 0, v[148:149]
	s_mov_b32 m0, s25
	s_nop 0
	global_load_lds_dwordx4 v148, s[18:19]
	s_barrier
	s_waitcnt lgkmcnt(0)
	s_setprio 1
	s_waitcnt lgkmcnt(0)
	v_mfma_f32_16x16x32_bf16 v[60:63], v[128:131], v[162:165], v[60:63]
	v_mfma_f32_16x16x32_bf16 v[56:59], v[136:139], v[162:165], v[56:59]
	v_mfma_f32_16x16x32_bf16 v[48:51], v[128:131], v[176:179], v[48:51]
	v_mfma_f32_16x16x32_bf16 v[40:43], v[136:139], v[176:179], v[40:43]
	v_mfma_f32_16x16x32_bf16 v[32:35], v[128:131], v[184:187], v[32:35]
	v_mfma_f32_16x16x32_bf16 v[24:27], v[136:139], v[184:187], v[24:27]
	v_mfma_f32_16x16x32_bf16 v[16:19], v[128:131], v[192:195], v[16:19]
	v_mfma_f32_16x16x32_bf16 v[8:11], v[136:139], v[192:195], v[8:11]
	v_mfma_f32_16x16x32_bf16 v[60:63], v[132:135], v[172:175], v[60:63]
	v_mfma_f32_16x16x32_bf16 v[56:59], v[140:143], v[172:175], v[56:59]
	v_mfma_f32_16x16x32_bf16 v[48:51], v[132:135], v[180:183], v[48:51]
	v_mfma_f32_16x16x32_bf16 v[40:43], v[140:143], v[180:183], v[40:43]
	v_mfma_f32_16x16x32_bf16 v[32:35], v[132:135], v[188:191], v[32:35]
	v_mfma_f32_16x16x32_bf16 v[24:27], v[140:143], v[188:191], v[24:27]
	v_mfma_f32_16x16x32_bf16 v[16:19], v[132:135], v[196:199], v[16:19]
	v_mfma_f32_16x16x32_bf16 v[8:11], v[140:143], v[196:199], v[8:11]
	s_setprio 0
	s_barrier
	s_add_u32 s44, s16, 0x80000
	s_addc_u32 s45, s17, 0
	s_add_i32 s46, s36, s24
	s_mov_b32 m0, s46
	s_nop 0
	global_load_lds_dwordx4 v146, s[44:45]
	s_add_i32 m0, s46, 0x2000
	s_nop 0
	global_load_lds_dwordx4 v150, s[44:45]
	s_add_u32 s18, s18, 0x80000
	s_addc_u32 s19, s19, 0
	s_mov_b32 m0, s26
	s_nop 0
	global_load_lds_dwordx4 v144, s[18:19]
	s_mov_b32 m0, s27
	s_nop 0
	global_load_lds_dwordx4 v148, s[18:19]
	s_waitcnt vmcnt(12)
	s_barrier
	s_setprio 1
	v_mfma_f32_16x16x32_bf16 v[52:55], v[202:205], v[162:165], v[52:55]
	v_mfma_f32_16x16x32_bf16 v[44:47], v[210:213], v[162:165], v[44:47]
	v_mfma_f32_16x16x32_bf16 v[36:39], v[202:205], v[176:179], v[36:39]
	v_mfma_f32_16x16x32_bf16 v[28:31], v[210:213], v[176:179], v[28:31]
	v_mfma_f32_16x16x32_bf16 v[20:23], v[202:205], v[184:187], v[20:23]
	v_mfma_f32_16x16x32_bf16 v[12:15], v[210:213], v[184:187], v[12:15]
	v_mfma_f32_16x16x32_bf16 v[4:7], v[202:205], v[192:195], v[4:7]
	v_mfma_f32_16x16x32_bf16 v[0:3], v[210:213], v[192:195], v[0:3]
	v_mfma_f32_16x16x32_bf16 v[52:55], v[206:209], v[172:175], v[52:55]
	v_mfma_f32_16x16x32_bf16 v[44:47], v[214:217], v[172:175], v[44:47]
	v_mfma_f32_16x16x32_bf16 v[36:39], v[206:209], v[180:183], v[36:39]
	v_mfma_f32_16x16x32_bf16 v[28:31], v[214:217], v[180:183], v[28:31]
	v_mfma_f32_16x16x32_bf16 v[20:23], v[206:209], v[188:191], v[20:23]
	v_mfma_f32_16x16x32_bf16 v[12:15], v[214:217], v[188:191], v[12:15]
	v_mfma_f32_16x16x32_bf16 v[4:7], v[206:209], v[196:199], v[4:7]
	v_mfma_f32_16x16x32_bf16 v[0:3], v[214:217], v[196:199], v[0:3]
	s_setprio 0
	s_add_i32 s44, 0, 0x18000
	v_add_u32_e32 v140, s44, v167
	s_barrier
	ds_read_b128 v[128:131], v140
	ds_read_b128 v[132:135], v140 offset:1024
	ds_read_b128 v[136:139], v140 offset:2048
	ds_read_b128 v[140:143], v140 offset:3072
	ds_read_b128 v[162:165], v169 offset:32768
	ds_read_b128 v[172:175], v169 offset:33792
	ds_read_b128 v[176:179], v169 offset:34816
	ds_read_b128 v[180:183], v169 offset:35840
	ds_read_b128 v[184:187], v169 offset:36864
	ds_read_b128 v[188:191], v169 offset:37888
	ds_read_b128 v[192:195], v169 offset:38912
	ds_read_b128 v[196:199], v169 offset:39936
	s_waitcnt lgkmcnt(8)
	s_waitcnt vmcnt(10)
	s_barrier
; #define PG8_STAGE(bufoff, gbase, voff) do { _Pragma("unroll") for (int _i = 0; _i < 2; ++_i) \
;         __builtin_amdgcn_global_load_lds((const unsigned*)((const char*)(gbase) + (voff)[_i]), (LAS unsigned*)(lds + (bufoff) + ldsw + _i * 8192), 16, 0, 0); } while (0)
; #define PG8_LDA(dst, b, h) do { _Pragma("unroll") for (int m = 0; m < 4; ++m) _Pragma("unroll") for (int k = 0; k < 2; ++k) dst[m][k] = *(const LAS bf16x8*)(lds + PG8_SA(b, h) + aoff + m * 2048 + k * 1024); } while (0)
; #define PG8_LDB(dst, b, h) do { _Pragma("unroll") for (int n = 0; n < 2; ++n) _Pragma("unroll") for (int k = 0; k < 2; ++k) dst[n][k] = *(const LAS bf16x8*)(lds + PG8_SB(b, h) + boff + n * 2048 + k * 1024); } while (0)
; #define PG8_MMA(ai, bj, At, Bt) do { __builtin_amdgcn_s_setprio(1); _Pragma("unroll") for (int m = 0; m < 4; ++m) _Pragma("unroll") for (int n = 0; n < 2; ++n) _Pragma("unroll") for (int k = 0; k < 2; ++k) \
;         acc[ai][bj][m][n] = __builtin_amdgcn_mfma_f32_16x16x32_bf16(Bt[n][k], At[m][k], acc[ai][bj][m][n], 0, 0, 0); __builtin_amdgcn_s_setprio(0); } while (0)
; #define PG8_WAIT_V(n) asm volatile("s_waitcnt vmcnt(" #n ")" ::: "memory")
; #define PG8_WAIT_L(n) asm volatile("s_waitcnt lgkmcnt(" #n ")" ::: "memory")
; #define PG8_BAR __builtin_amdgcn_s_barrier()
; #define PG8_SCHED __builtin_amdgcn_sched_barrier(0)
; template <class Epi, class Sched>
; __device__ __forceinline__ void gemm_phase(LAS unsigned char* lds, const Gemm g, const Sched& S, const Epi& E) {
;     ...
;             PG8_WAIT_L(8); PG8_BAR; PG8_WAIT_L(0); PG8_MMA(0, 0, At, B0); PG8_BAR; PG8_SCHED;
;             PG8_LDB(B1, 1, 1); PG8_STAGE(PG8_SB(1, 0), b3, voffB);
;             PG8_BAR; PG8_WAIT_L(0); PG8_MMA(0, 1, At, B1); PG8_BAR;
;             PG8_LDA(At, 1, 1); PG8_STAGE(PG8_SA(1, 0), a3, voffA);
;             PG8_BAR; PG8_WAIT_L(0); PG8_MMA(1, 0, At, B0); PG8_BAR; PG8_SCHED;
;             PG8_STAGE(PG8_SB(1, 1), b3 + hstep, voffB);
;             PG8_WAIT_V(6); PG8_BAR; PG8_MMA(1, 1, At, B1); PG8_BAR;
	s_waitcnt lgkmcnt(0)
	s_setprio 1
	s_waitcnt lgkmcnt(0)
	v_mfma_f32_16x16x32_bf16 v[124:127], v[128:131], v[162:165], v[124:127]
	v_mfma_f32_16x16x32_bf16 v[120:123], v[136:139], v[162:165], v[120:123]
	v_mfma_f32_16x16x32_bf16 v[116:119], v[128:131], v[176:179], v[116:119]
	v_mfma_f32_16x16x32_bf16 v[112:115], v[136:139], v[176:179], v[112:115]
	v_mfma_f32_16x16x32_bf16 v[108:111], v[128:131], v[184:187], v[108:111]
	v_mfma_f32_16x16x32_bf16 v[100:103], v[136:139], v[184:187], v[100:103]
	v_mfma_f32_16x16x32_bf16 v[76:79], v[128:131], v[192:195], v[76:79]
	v_mfma_f32_16x16x32_bf16 v[72:75], v[136:139], v[192:195], v[72:75]
	v_mfma_f32_16x16x32_bf16 v[124:127], v[132:135], v[172:175], v[124:127]
	v_mfma_f32_16x16x32_bf16 v[120:123], v[140:143], v[172:175], v[120:123]
	v_mfma_f32_16x16x32_bf16 v[116:119], v[132:135], v[180:183], v[116:119]
	v_mfma_f32_16x16x32_bf16 v[112:115], v[140:143], v[180:183], v[112:115]
	v_mfma_f32_16x16x32_bf16 v[108:111], v[132:135], v[188:191], v[108:111]
	v_mfma_f32_16x16x32_bf16 v[100:103], v[140:143], v[188:191], v[100:103]
	v_mfma_f32_16x16x32_bf16 v[76:79], v[132:135], v[196:199], v[76:79]
	v_mfma_f32_16x16x32_bf16 v[72:75], v[140:143], v[196:199], v[72:75]
	s_setprio 0
	s_barrier
	s_add_i32 s18, 0, 0x1c000
	s_add_i32 s19, s44, s24
	v_add_u32_e32 v160, s18, v167
	s_add_u32 s0, s16, 0x80
	s_addc_u32 s1, s17, 0
	s_mov_b32 m0, s19
	ds_read_b128 v[202:205], v160
	ds_read_b128 v[206:209], v160 offset:1024
	ds_read_b128 v[210:213], v160 offset:2048
	ds_read_b128 v[214:217], v160 offset:3072
	global_load_lds_dwordx4 v146, s[0:1]
	s_add_i32 m0, s19, 0x2000
	s_nop 0
	global_load_lds_dwordx4 v150, s[0:1]
	s_waitcnt vmcnt(10)
	s_barrier
	s_waitcnt lgkmcnt(0)
	s_setprio 1
	s_waitcnt lgkmcnt(0)
	v_mfma_f32_16x16x32_bf16 v[104:107], v[202:205], v[162:165], v[104:107]
	v_mfma_f32_16x16x32_bf16 v[96:99], v[210:213], v[162:165], v[96:99]
	v_mfma_f32_16x16x32_bf16 v[92:95], v[202:205], v[176:179], v[92:95]
	v_mfma_f32_16x16x32_bf16 v[88:91], v[210:213], v[176:179], v[88:91]
	v_mfma_f32_16x16x32_bf16 v[84:87], v[202:205], v[184:187], v[84:87]
	v_mfma_f32_16x16x32_bf16 v[80:83], v[210:213], v[184:187], v[80:83]
	v_mfma_f32_16x16x32_bf16 v[68:71], v[202:205], v[192:195], v[68:71]
	v_mfma_f32_16x16x32_bf16 v[64:67], v[210:213], v[192:195], v[64:67]
	v_mfma_f32_16x16x32_bf16 v[104:107], v[206:209], v[172:175], v[104:107]
	v_mfma_f32_16x16x32_bf16 v[96:99], v[214:217], v[172:175], v[96:99]
	v_mfma_f32_16x16x32_bf16 v[92:95], v[206:209], v[180:183], v[92:95]
	v_mfma_f32_16x16x32_bf16 v[88:91], v[214:217], v[180:183], v[88:91]
	v_mfma_f32_16x16x32_bf16 v[84:87], v[206:209], v[188:191], v[84:87]
	v_mfma_f32_16x16x32_bf16 v[80:83], v[214:217], v[188:191], v[80:83]
	v_mfma_f32_16x16x32_bf16 v[68:71], v[206:209], v[196:199], v[68:71]
	v_mfma_f32_16x16x32_bf16 v[64:67], v[214:217], v[196:199], v[64:67]
	s_setprio 0
	s_mov_b32 m0, s31
	s_mov_b64 s[0:1], 0x80
	v_lshl_add_u64 v[218:219], v[222:223], 0, s[0:1]
	s_barrier
	ds_read_b128 v[162:165], v169 offset:49152
	ds_read_b128 v[172:175], v169 offset:50176
	ds_read_b128 v[176:179], v169 offset:51200
	ds_read_b128 v[180:183], v169 offset:52224
	ds_read_b128 v[184:187], v169 offset:53248
	ds_read_b128 v[188:191], v169 offset:54272
	ds_read_b128 v[192:195], v169 offset:55296
	ds_read_b128 v[196:199], v169 offset:56320
	global_load_lds_dwordx4 v[218:219], off
	v_lshl_add_u64 v[218:219], v[224:225], 0, s[0:1]
	s_mov_b32 m0, s33
	s_nop 0
	global_load_lds_dwordx4 v[218:219], off
	s_barrier
	s_waitcnt lgkmcnt(0)
	s_setprio 1
	s_waitcnt lgkmcnt(0)
	v_mfma_f32_16x16x32_bf16 v[60:63], v[128:131], v[162:165], v[60:63]
	v_mfma_f32_16x16x32_bf16 v[56:59], v[136:139], v[162:165], v[56:59]
	v_mfma_f32_16x16x32_bf16 v[48:51], v[128:131], v[176:179], v[48:51]
	v_mfma_f32_16x16x32_bf16 v[40:43], v[136:139], v[176:179], v[40:43]
	v_mfma_f32_16x16x32_bf16 v[32:35], v[128:131], v[184:187], v[32:35]
	v_mfma_f32_16x16x32_bf16 v[24:27], v[136:139], v[184:187], v[24:27]
	v_mfma_f32_16x16x32_bf16 v[16:19], v[128:131], v[192:195], v[16:19]
	v_mfma_f32_16x16x32_bf16 v[8:11], v[136:139], v[192:195], v[8:11]
	v_mfma_f32_16x16x32_bf16 v[60:63], v[132:135], v[172:175], v[60:63]
	v_mfma_f32_16x16x32_bf16 v[56:59], v[140:143], v[172:175], v[56:59]
	v_mfma_f32_16x16x32_bf16 v[48:51], v[132:135], v[180:183], v[48:51]
	v_mfma_f32_16x16x32_bf16 v[40:43], v[140:143], v[180:183], v[40:43]
	v_mfma_f32_16x16x32_bf16 v[32:35], v[132:135], v[188:191], v[32:35]
	v_mfma_f32_16x16x32_bf16 v[24:27], v[140:143], v[188:191], v[24:27]
	v_mfma_f32_16x16x32_bf16 v[16:19], v[132:135], v[196:199], v[16:19]
	v_mfma_f32_16x16x32_bf16 v[8:11], v[140:143], v[196:199], v[8:11]
	s_setprio 0
	s_barrier
	s_add_u32 s16, s16, 0x80080
	s_addc_u32 s17, s17, 0
	s_add_i32 s18, s18, s24
	s_mov_b32 m0, s18
	s_nop 0
	global_load_lds_dwordx4 v146, s[16:17]
	s_add_i32 m0, s18, 0x2000
	s_nop 0
	global_load_lds_dwordx4 v150, s[16:17]
	s_waitcnt vmcnt(10)
	s_barrier
	s_setprio 1
	v_mfma_f32_16x16x32_bf16 v[52:55], v[202:205], v[162:165], v[52:55]
	v_mfma_f32_16x16x32_bf16 v[44:47], v[210:213], v[162:165], v[44:47]
	v_mfma_f32_16x16x32_bf16 v[36:39], v[202:205], v[176:179], v[36:39]
	v_mfma_f32_16x16x32_bf16 v[28:31], v[210:213], v[176:179], v[28:31]
	v_mfma_f32_16x16x32_bf16 v[20:23], v[202:205], v[184:187], v[20:23]
	v_mfma_f32_16x16x32_bf16 v[12:15], v[210:213], v[184:187], v[12:15]
	v_mfma_f32_16x16x32_bf16 v[4:7], v[202:205], v[192:195], v[4:7]
	v_mfma_f32_16x16x32_bf16 v[0:3], v[210:213], v[192:195], v[0:3]
	v_mfma_f32_16x16x32_bf16 v[52:55], v[206:209], v[172:175], v[52:55]
	v_mfma_f32_16x16x32_bf16 v[44:47], v[214:217], v[172:175], v[44:47]
	v_mfma_f32_16x16x32_bf16 v[36:39], v[206:209], v[180:183], v[36:39]
	v_mfma_f32_16x16x32_bf16 v[28:31], v[214:217], v[180:183], v[28:31]
	v_mfma_f32_16x16x32_bf16 v[20:23], v[206:209], v[188:191], v[20:23]
	v_mfma_f32_16x16x32_bf16 v[12:15], v[214:217], v[188:191], v[12:15]
	v_mfma_f32_16x16x32_bf16 v[4:7], v[206:209], v[196:199], v[4:7]
	v_mfma_f32_16x16x32_bf16 v[0:3], v[214:217], v[196:199], v[0:3]
	s_setprio 0
	s_add_i32 s43, s43, 2
	s_add_u32 s14, s14, 0x100
	s_addc_u32 s15, s15, 0
	s_add_u32 s41, s41, 0x100
	s_addc_u32 s42, s42, 0
	s_cmp_gt_u32 s43, 29
	s_barrier
; __device__ __forceinline__ unsigned cvt_pk_bf16(float lo, float hi) { unsigned r; asm volatile("v_cvt_pk_bf16_f32 %0, %1, %2" : "=v"(r) : "v"(lo), "v"(hi)); return r; }
;     __device__ __forceinline__ void operator()(const AccT& acc, const Unit& u, int wr, int wc, int fr, int fq) const {
;         asm volatile("" : "+v"(fr), "+v"(fq));
;         const int row0 = u.pm * 256 + wr * 64 + fr; const int b = u.pn >> 1, ch0 = (u.pn & 1) * 256 + wc * 32 + 8 * fq;
;         const float sg = (fr & 1) ? -1.0f : 1.0f;
;         f32x4 yh[2][2];
; #pragma unroll
;         for (int bj = 0; bj < 2; ++bj)
; #pragma unroll
;             for (int n = 0; n < 2; ++n) yh[bj][n] = *(const f32x4*)(YCH + b * 512 + ch0 + bj * 128 + 4 * n) * sg;
; #pragma unroll
;         for (int ai = 0; ai < 2; ++ai)
; #pragma unroll
;             for (int m = 0; m < 4; ++m) {
;                 const int k = row0 + ai * 128 + m * 16;
; #pragma unroll
;                 for (int bj = 0; bj < 2; ++bj) {
;                     const f32x4 v0 = acc[ai][bj][m][0] + yh[bj][0], v1 = acc[ai][bj][m][1] + yh[bj][1];
;                     u32x4 w; w.x = cvt_pk_bf16(v0[0], v0[1]); w.y = cvt_pk_bf16(v0[2], v0[3]); w.z = cvt_pk_bf16(v1[0], v1[1]); w.w = cvt_pk_bf16(v1[2], v1[3]);
;                     *(u32x4*)(CAT + (size_t)(b * 2048 + k) * CATW + 1024 + ch0 + bj * 128) = w;
;                 }
	s_cbranch_scc0 .LBB0_826
	s_ashr_i32 s5, s38, 1
	s_lshl_b32 s7, s38, 8
	s_lshl_b32 s14, s5, 9
	s_and_b32 s7, s7, 0x100
	s_ashr_i32 s15, s14, 31
	v_mov_b32_e32 v171, v161
	v_mov_b32_e32 v128, v166
	s_or_b32 s7, s7, s30
	s_lshl_b64 s[14:15], s[14:15], 2
	s_add_u32 s14, s48, s14
	v_lshl_add_u32 v164, v128, 3, s7
	s_addc_u32 s15, s49, s15
	v_ashrrev_i32_e32 v165, 31, v164
	v_lshl_add_u64 v[128:129], v[164:165], 2, s[14:15]
	global_load_dwordx4 v[140:143], v[128:129], off
	global_load_dwordx4 v[136:139], v[128:129], off offset:16
	global_load_dwordx4 v[132:135], v[128:129], off offset:512
	s_nop 0
	global_load_dwordx4 v[128:131], v[128:129], off offset:528
	s_lshl_b32 s7, s12, 8
	s_lshl_b32 s5, s5, 11
	s_add_i32 s7, s7, s29
	v_and_b32_e32 v160, 1, v171
	s_add_i32 s7, s7, s5
	v_mov_b64_e32 v[162:163], s[96:97]
	v_cmp_eq_u32_e32 vcc, 0, v160
	v_add_u32_e32 v171, s7, v171
	v_lshlrev_b64 v[164:165], 1, v[164:165]
	v_cndmask_b32_e64 v160, -1.0, 1.0, vcc
	v_mad_i64_i32 v[172:173], s[14:15], v171, s37, v[162:163]
	v_add_u32_e32 v174, 16, v171
	v_lshl_add_u64 v[172:173], v[172:173], 0, v[164:165]
	v_mad_i64_i32 v[174:175], s[14:15], v174, s37, v[162:163]
	v_add_u32_e32 v176, 32, v171
	v_lshl_add_u64 v[174:175], v[174:175], 0, v[164:165]
	v_mad_i64_i32 v[176:177], s[14:15], v176, s37, v[162:163]
	v_lshl_add_u64 v[176:177], v[176:177], 0, v[164:165]
	v_add_u32_e32 v182, 48, v171
	s_and_b64 vcc, exec, s[2:3]
	s_mov_b32 s38, s4
	s_mov_b32 s12, s6
	s_mov_b64 s[16:17], s[10:11]
	s_waitcnt vmcnt(0)
	v_pk_fma_f32 v[126:127], v[142:143], v[160:161], v[126:127] op_sel_hi:[1,0,1]
	v_pk_fma_f32 v[124:125], v[140:141], v[160:161], v[124:125] op_sel_hi:[1,0,1]
	v_pk_fma_f32 v[122:123], v[138:139], v[160:161], v[122:123] op_sel_hi:[1,0,1]
	v_pk_fma_f32 v[180:181], v[128:129], v[160:161], v[80:81] op_sel_hi:[1,0,1]
	v_cvt_pk_bf16_f32 v80, v124, v125
	v_cvt_pk_bf16_f32 v81, v126, v127
	v_pk_fma_f32 v[120:121], v[136:137], v[160:161], v[120:121] op_sel_hi:[1,0,1]
	v_pk_fma_f32 v[106:107], v[134:135], v[160:161], v[106:107] op_sel_hi:[1,0,1]
	v_pk_fma_f32 v[104:105], v[132:133], v[160:161], v[104:105] op_sel_hi:[1,0,1]
	v_pk_fma_f32 v[178:179], v[130:131], v[160:161], v[82:83] op_sel_hi:[1,0,1]
	v_cvt_pk_bf16_f32 v82, v120, v121
	v_cvt_pk_bf16_f32 v83, v122, v123
	global_store_dwordx4 v[172:173], v[80:83], off offset:2048
	v_pk_fma_f32 v[98:99], v[130:131], v[160:161], v[98:99] op_sel_hi:[1,0,1]
	v_pk_fma_f32 v[96:97], v[128:129], v[160:161], v[96:97] op_sel_hi:[1,0,1]
	v_cvt_pk_bf16_f32 v80, v104, v105
	v_cvt_pk_bf16_f32 v81, v106, v107
	v_pk_fma_f32 v[118:119], v[142:143], v[160:161], v[118:119] op_sel_hi:[1,0,1]
	v_pk_fma_f32 v[116:117], v[140:141], v[160:161], v[116:117] op_sel_hi:[1,0,1]
	v_cvt_pk_bf16_f32 v82, v96, v97
	v_cvt_pk_bf16_f32 v83, v98, v99
	global_store_dwordx4 v[172:173], v[80:83], off offset:2304
	v_pk_fma_f32 v[114:115], v[138:139], v[160:161], v[114:115] op_sel_hi:[1,0,1]
	v_pk_fma_f32 v[112:113], v[136:137], v[160:161], v[112:113] op_sel_hi:[1,0,1]
	v_cvt_pk_bf16_f32 v80, v116, v117
	v_cvt_pk_bf16_f32 v81, v118, v119
	v_pk_fma_f32 v[94:95], v[134:135], v[160:161], v[94:95] op_sel_hi:[1,0,1]
	v_pk_fma_f32 v[92:93], v[132:133], v[160:161], v[92:93] op_sel_hi:[1,0,1]
	v_cvt_pk_bf16_f32 v82, v112, v113
	v_cvt_pk_bf16_f32 v83, v114, v115
	global_store_dwordx4 v[174:175], v[80:83], off offset:2048
	v_pk_fma_f32 v[90:91], v[130:131], v[160:161], v[90:91] op_sel_hi:[1,0,1]
	v_pk_fma_f32 v[88:89], v[128:129], v[160:161], v[88:89] op_sel_hi:[1,0,1]
	v_cvt_pk_bf16_f32 v80, v92, v93
	v_cvt_pk_bf16_f32 v81, v94, v95
	v_pk_fma_f32 v[110:111], v[142:143], v[160:161], v[110:111] op_sel_hi:[1,0,1]
	v_pk_fma_f32 v[108:109], v[140:141], v[160:161], v[108:109] op_sel_hi:[1,0,1]
	v_cvt_pk_bf16_f32 v82, v88, v89
	v_cvt_pk_bf16_f32 v83, v90, v91
	global_store_dwordx4 v[174:175], v[80:83], off offset:2304
	v_pk_fma_f32 v[102:103], v[138:139], v[160:161], v[102:103] op_sel_hi:[1,0,1]
	v_pk_fma_f32 v[100:101], v[136:137], v[160:161], v[100:101] op_sel_hi:[1,0,1]
	v_cvt_pk_bf16_f32 v80, v108, v109
	v_cvt_pk_bf16_f32 v81, v110, v111
	v_pk_fma_f32 v[86:87], v[134:135], v[160:161], v[86:87] op_sel_hi:[1,0,1]
	v_pk_fma_f32 v[84:85], v[132:133], v[160:161], v[84:85] op_sel_hi:[1,0,1]
	v_cvt_pk_bf16_f32 v82, v100, v101
	v_cvt_pk_bf16_f32 v83, v102, v103
	global_store_dwordx4 v[176:177], v[80:83], off offset:2048
	v_pk_fma_f32 v[76:77], v[140:141], v[160:161], v[76:77] op_sel_hi:[1,0,1]
	v_pk_fma_f32 v[78:79], v[142:143], v[160:161], v[78:79] op_sel_hi:[1,0,1]
	v_cvt_pk_bf16_f32 v80, v84, v85
	v_cvt_pk_bf16_f32 v81, v86, v87
	v_cvt_pk_bf16_f32 v82, v180, v181
	v_cvt_pk_bf16_f32 v83, v178, v179
	global_store_dwordx4 v[176:177], v[80:83], off offset:2304
	v_pk_fma_f32 v[70:71], v[134:135], v[160:161], v[70:71] op_sel_hi:[1,0,1]
	v_pk_fma_f32 v[68:69], v[132:133], v[160:161], v[68:69] op_sel_hi:[1,0,1]
	v_pk_fma_f32 v[80:81], v[138:139], v[160:161], v[74:75] op_sel_hi:[1,0,1]
	v_pk_fma_f32 v[74:75], v[136:137], v[160:161], v[72:73] op_sel_hi:[1,0,1]
	v_cvt_pk_bf16_f32 v72, v76, v77
	v_mad_i64_i32 v[76:77], s[14:15], v182, s37, v[162:163]
	v_cvt_pk_bf16_f32 v73, v78, v79
; __device__ __forceinline__ unsigned cvt_pk_bf16(float lo, float hi) { unsigned r; asm volatile("v_cvt_pk_bf16_f32 %0, %1, %2" : "=v"(r) : "v"(lo), "v"(hi)); return r; }
; #define PG8_WAIT_V(n) asm volatile("s_waitcnt vmcnt(" #n ")" ::: "memory")
; #define PG8_BAR __builtin_amdgcn_s_barrier()
; template <class Epi, class Sched>
; __device__ __forceinline__ void gemm_phase(LAS unsigned char* lds, const Gemm g, const Sched& S, const Epi& E) {
;     ...
;         if (!has_next) break;
; #pragma unroll
;         for (int a = 0; a < 2; ++a)
; #pragma unroll
;             for (int b = 0; b < 2; ++b)
; #pragma unroll
;                 for (int m = 0; m < 4; ++m)
; #pragma unroll
;                     for (int n = 0; n < 2; ++n) acc[a][b][m][n] = (f32x4){0.f, 0.f, 0.f, 0.f};
;         cur = nxt; cA = nA; cB = nB; ++ui;
;     }
;     PG8_WAIT_V(0);
;     if (wr == 0) PG8_BAR;
;     PG8_BAR;
;     __device__ __forceinline__ void operator()(const AccT& acc, const Unit& u, int wr, int wc, int fr, int fq) const {
;     ...
;         for (int ai = 0; ai < 2; ++ai)
; #pragma unroll
;             for (int m = 0; m < 4; ++m) {
;                 const int k = row0 + ai * 128 + m * 16;
; #pragma unroll
;                 for (int bj = 0; bj < 2; ++bj) {
;                     const f32x4 v0 = acc[ai][bj][m][0] + yh[bj][0], v1 = acc[ai][bj][m][1] + yh[bj][1];
;                     u32x4 w; w.x = cvt_pk_bf16(v0[0], v0[1]); w.y = cvt_pk_bf16(v0[2], v0[3]); w.z = cvt_pk_bf16(v1[0], v1[1]); w.w = cvt_pk_bf16(v1[2], v1[3]);
;                     *(u32x4*)(CAT + (size_t)(b * 2048 + k) * CATW + 1024 + ch0 + bj * 128) = w;
;                 }
	v_lshl_add_u64 v[76:77], v[76:77], 0, v[164:165]
	v_cvt_pk_bf16_f32 v74, v74, v75
	v_cvt_pk_bf16_f32 v75, v80, v81
	global_store_dwordx4 v[76:77], v[72:75], off offset:2048
	v_pk_fma_f32 v[60:61], v[140:141], v[160:161], v[60:61] op_sel_hi:[1,0,1]
	v_pk_fma_f32 v[62:63], v[142:143], v[160:161], v[62:63] op_sel_hi:[1,0,1]
	v_pk_fma_f32 v[72:73], v[130:131], v[160:161], v[66:67] op_sel_hi:[1,0,1]
	v_pk_fma_f32 v[66:67], v[128:129], v[160:161], v[64:65] op_sel_hi:[1,0,1]
	v_cvt_pk_bf16_f32 v64, v68, v69
	v_cvt_pk_bf16_f32 v65, v70, v71
	v_pk_fma_f32 v[54:55], v[134:135], v[160:161], v[54:55] op_sel_hi:[1,0,1]
	v_cvt_pk_bf16_f32 v66, v66, v67
	v_cvt_pk_bf16_f32 v67, v72, v73
	global_store_dwordx4 v[76:77], v[64:67], off offset:2304
	v_pk_fma_f32 v[52:53], v[132:133], v[160:161], v[52:53] op_sel_hi:[1,0,1]
	v_pk_fma_f32 v[38:39], v[134:135], v[160:161], v[38:39] op_sel_hi:[1,0,1]
	v_add_u32_e32 v66, 0x80, v171
	v_pk_fma_f32 v[64:65], v[138:139], v[160:161], v[58:59] op_sel_hi:[1,0,1]
	v_pk_fma_f32 v[58:59], v[136:137], v[160:161], v[56:57] op_sel_hi:[1,0,1]
	v_cvt_pk_bf16_f32 v56, v60, v61
	v_mad_i64_i32 v[60:61], s[14:15], v66, s37, v[162:163]
	v_cvt_pk_bf16_f32 v57, v62, v63
	v_lshl_add_u64 v[60:61], v[60:61], 0, v[164:165]
	v_cvt_pk_bf16_f32 v58, v58, v59
	v_cvt_pk_bf16_f32 v59, v64, v65
	global_store_dwordx4 v[60:61], v[56:59], off offset:2048
	v_pk_fma_f32 v[36:37], v[132:133], v[160:161], v[36:37] op_sel_hi:[1,0,1]
	v_pk_fma_f32 v[22:23], v[134:135], v[160:161], v[22:23] op_sel_hi:[1,0,1]
	v_pk_fma_f32 v[56:57], v[130:131], v[160:161], v[46:47] op_sel_hi:[1,0,1]
	v_pk_fma_f32 v[46:47], v[128:129], v[160:161], v[44:45] op_sel_hi:[1,0,1]
	v_cvt_pk_bf16_f32 v44, v52, v53
	v_cvt_pk_bf16_f32 v45, v54, v55
	v_add_u32_e32 v52, 0x90, v171
	v_cvt_pk_bf16_f32 v46, v46, v47
	v_cvt_pk_bf16_f32 v47, v56, v57
	global_store_dwordx4 v[60:61], v[44:47], off offset:2304
	v_pk_fma_f32 v[20:21], v[132:133], v[160:161], v[20:21] op_sel_hi:[1,0,1]
	v_pk_fma_f32 v[6:7], v[134:135], v[160:161], v[6:7] op_sel_hi:[1,0,1]
	v_pk_fma_f32 v[44:45], v[142:143], v[160:161], v[50:51] op_sel_hi:[1,0,1]
	v_pk_fma_f32 v[46:47], v[140:141], v[160:161], v[48:49] op_sel_hi:[1,0,1]
	v_pk_fma_f32 v[48:49], v[138:139], v[160:161], v[42:43] op_sel_hi:[1,0,1]
	v_pk_fma_f32 v[42:43], v[136:137], v[160:161], v[40:41] op_sel_hi:[1,0,1]
	v_cvt_pk_bf16_f32 v40, v46, v47
	v_cvt_pk_bf16_f32 v41, v44, v45
	v_mad_i64_i32 v[44:45], s[14:15], v52, s37, v[162:163]
	v_lshl_add_u64 v[44:45], v[44:45], 0, v[164:165]
	v_cvt_pk_bf16_f32 v42, v42, v43
	v_cvt_pk_bf16_f32 v43, v48, v49
	global_store_dwordx4 v[44:45], v[40:43], off offset:2048
	v_pk_fma_f32 v[4:5], v[132:133], v[160:161], v[4:5] op_sel_hi:[1,0,1]
	s_nop 0
	v_pk_fma_f32 v[40:41], v[130:131], v[160:161], v[30:31] op_sel_hi:[1,0,1]
	v_pk_fma_f32 v[30:31], v[128:129], v[160:161], v[28:29] op_sel_hi:[1,0,1]
	v_cvt_pk_bf16_f32 v28, v36, v37
	v_cvt_pk_bf16_f32 v29, v38, v39
	v_add_u32_e32 v36, 0xa0, v171
	v_cvt_pk_bf16_f32 v30, v30, v31
	v_cvt_pk_bf16_f32 v31, v40, v41
	global_store_dwordx4 v[44:45], v[28:31], off offset:2304
	s_nop 1
	v_pk_fma_f32 v[28:29], v[142:143], v[160:161], v[34:35] op_sel_hi:[1,0,1]
	v_pk_fma_f32 v[30:31], v[140:141], v[160:161], v[32:33] op_sel_hi:[1,0,1]
	v_pk_fma_f32 v[32:33], v[138:139], v[160:161], v[26:27] op_sel_hi:[1,0,1]
	v_pk_fma_f32 v[26:27], v[136:137], v[160:161], v[24:25] op_sel_hi:[1,0,1]
	v_cvt_pk_bf16_f32 v24, v30, v31
	v_cvt_pk_bf16_f32 v25, v28, v29
	v_mad_i64_i32 v[28:29], s[14:15], v36, s37, v[162:163]
	v_lshl_add_u64 v[28:29], v[28:29], 0, v[164:165]
	v_cvt_pk_bf16_f32 v26, v26, v27
	v_cvt_pk_bf16_f32 v27, v32, v33
	global_store_dwordx4 v[28:29], v[24:27], off offset:2048
	s_nop 1
	v_pk_fma_f32 v[24:25], v[130:131], v[160:161], v[14:15] op_sel_hi:[1,0,1]
	v_pk_fma_f32 v[14:15], v[128:129], v[160:161], v[12:13] op_sel_hi:[1,0,1]
	v_cvt_pk_bf16_f32 v12, v20, v21
	v_cvt_pk_bf16_f32 v13, v22, v23
	v_add_u32_e32 v20, 0xb0, v171
	v_cvt_pk_bf16_f32 v14, v14, v15
	v_cvt_pk_bf16_f32 v15, v24, v25
	global_store_dwordx4 v[28:29], v[12:15], off offset:2304
	s_nop 1
	v_pk_fma_f32 v[12:13], v[142:143], v[160:161], v[18:19] op_sel_hi:[1,0,1]
	v_pk_fma_f32 v[14:15], v[140:141], v[160:161], v[16:17] op_sel_hi:[1,0,1]
	v_pk_fma_f32 v[16:17], v[138:139], v[160:161], v[10:11] op_sel_hi:[1,0,1]
	v_pk_fma_f32 v[10:11], v[136:137], v[160:161], v[8:9] op_sel_hi:[1,0,1]
	v_cvt_pk_bf16_f32 v8, v14, v15
	v_cvt_pk_bf16_f32 v9, v12, v13
	v_mad_i64_i32 v[12:13], s[14:15], v20, s37, v[162:163]
	v_lshl_add_u64 v[12:13], v[12:13], 0, v[164:165]
	v_cvt_pk_bf16_f32 v10, v10, v11
	v_cvt_pk_bf16_f32 v11, v16, v17
	global_store_dwordx4 v[12:13], v[8:11], off offset:2048
	s_mov_b64 s[14:15], s[8:9]
	s_nop 0
	v_pk_fma_f32 v[8:9], v[130:131], v[160:161], v[2:3] op_sel_hi:[1,0,1]
	v_pk_fma_f32 v[2:3], v[128:129], v[160:161], v[0:1] op_sel_hi:[1,0,1]
	v_cvt_pk_bf16_f32 v0, v4, v5
	v_cvt_pk_bf16_f32 v1, v6, v7
	s_nop 0
	v_cvt_pk_bf16_f32 v2, v2, v3
	v_cvt_pk_bf16_f32 v3, v8, v9
	global_store_dwordx4 v[12:13], v[0:3], off offset:2304
	s_cbranch_vccz .LBB0_819
	s_waitcnt vmcnt(0)
	s_cmpk_gt_u32 s20, 0xff
	s_cbranch_scc1 .LBB0_830
	s_barrier

; #define PG8_STAGE(bufoff, gbase, voff) do { _Pragma("unroll") for (int _i = 0; _i < 2; ++_i) \
;         __builtin_amdgcn_global_load_lds((const unsigned*)((const char*)(gbase) + (voff)[_i]), (LAS unsigned*)(lds + (bufoff) + ldsw + _i * 8192), 16, 0, 0); } while (0)
; #define PG8_LDA(dst, b, h) do { _Pragma("unroll") for (int m = 0; m < 4; ++m) _Pragma("unroll") for (int k = 0; k < 2; ++k) dst[m][k] = *(const LAS bf16x8*)(lds + PG8_SA(b, h) + aoff + m * 2048 + k * 1024); } while (0)
; #define PG8_LDB(dst, b, h) do { _Pragma("unroll") for (int n = 0; n < 2; ++n) _Pragma("unroll") for (int k = 0; k < 2; ++k) dst[n][k] = *(const LAS bf16x8*)(lds + PG8_SB(b, h) + boff + n * 2048 + k * 1024); } while (0)
; #define PG8_MMA(ai, bj, At, Bt) do { __builtin_amdgcn_s_setprio(1); _Pragma("unroll") for (int m = 0; m < 4; ++m) _Pragma("unroll") for (int n = 0; n < 2; ++n) _Pragma("unroll") for (int k = 0; k < 2; ++k) \
;         acc[ai][bj][m][n] = __builtin_amdgcn_mfma_f32_16x16x32_bf16(Bt[n][k], At[m][k], acc[ai][bj][m][n], 0, 0, 0); __builtin_amdgcn_s_setprio(0); } while (0)
; #define PG8_WAIT_L(n) asm volatile("s_waitcnt lgkmcnt(" #n ")" ::: "memory")
; template <class Epi, class Sched>
; __device__ __forceinline__ void gemm_phase(LAS unsigned char* lds, const Gemm g, const Sched& S, const Epi& E) {
;     ...
;         const bool has_next = S.next(ui + 1, nxt);
;         const char* nA = has_next ? (const char*)g.A + (size_t)nxt.pm * tstep : cA; const char* nB = has_next ? (const char*)g.Bt + (size_t)nxt.pn * tstep : cB;
;         for (int t = 0; t < nt; t += 2) {
;             const bool last = (t == nt - 2);
;             const char* a1 = cA + (size_t)(t + 1) * kstep;
;             const char* a2 = last ? nA : cA + (size_t)(t + 2) * kstep; const char* b2 = last ? nB : cB + (size_t)(t + 2) * kstep;
;             const char* a3 = a2 + kstep; const char* b3 = b2 + kstep;
;             PG8_LDB(B0, 0, 0); PG8_SCHED; PG8_LDA(At, 0, 0); PG8_STAGE(PG8_SA(1, 1), a1 + hstep, voffA);
;             PG8_WAIT_L(8); PG8_BAR; PG8_WAIT_L(0); PG8_MMA(0, 0, At, B0); PG8_BAR; PG8_SCHED;
;             PG8_LDB(B1, 0, 1); PG8_STAGE(PG8_SB(0, 0), b2, voffB);
;             PG8_BAR; PG8_WAIT_L(0); PG8_MMA(0, 1, At, B1); PG8_BAR;
;             PG8_LDA(At, 0, 1); PG8_STAGE(PG8_SA(0, 0), a2, voffA);
;             PG8_BAR; PG8_WAIT_L(0); PG8_MMA(1, 0, At, B0); PG8_BAR; PG8_SCHED;
.LBB0_901:
	s_add_u32 s56, s26, 0x100
	s_addc_u32 s57, s27, 0
	s_mov_b32 s58, -2
	s_waitcnt vmcnt(0)
	ds_read_b128 v[128:131], v237
	ds_read_b128 v[132:135], v237 offset:1024
	ds_read_b128 v[136:139], v237 offset:2048
	ds_read_b128 v[140:143], v237 offset:3072
	s_add_u32 s26, s24, 0x100
	s_addc_u32 s27, s25, 0
	s_cmp_eq_u32 s58, 20
	s_cselect_b32 s31, s5, s27
	s_cselect_b32 s30, s4, s26
	s_cselect_b32 s29, s7, s57
	s_cselect_b32 s28, s6, s56
	v_lshl_add_u64 v[176:177], s[24:25], 0, v[210:211]
	s_add_i32 m0, s38, 0xc000
	ds_read_b128 v[144:147], v238
	ds_read_b128 v[148:151], v238 offset:1024
	ds_read_b128 v[152:155], v238 offset:2048
	ds_read_b128 v[156:159], v238 offset:3072
	ds_read_b128 v[160:163], v238 offset:4096
	ds_read_b128 v[164:167], v238 offset:5120
	ds_read_b128 v[168:171], v238 offset:6144
	ds_read_b128 v[172:175], v238 offset:7168
	global_load_lds_dwordx4 v[176:177], off
	v_lshl_add_u64 v[176:177], s[24:25], 0, v[212:213]
	s_add_i32 m0, s38, 0xe000
	s_nop 0
	global_load_lds_dwordx4 v[176:177], off
	s_waitcnt lgkmcnt(8)
	s_waitcnt vmcnt(10)
	s_barrier
	s_waitcnt lgkmcnt(0)
	s_setprio 1
	s_waitcnt lgkmcnt(0)
	v_mfma_f32_16x16x32_bf16 v[124:127], v[128:131], v[144:147], 0
	v_mfma_f32_16x16x32_bf16 v[120:123], v[136:139], v[144:147], 0
	v_mfma_f32_16x16x32_bf16 v[108:111], v[128:131], v[152:155], 0
	v_mfma_f32_16x16x32_bf16 v[104:107], v[136:139], v[152:155], 0
	v_mfma_f32_16x16x32_bf16 v[92:95], v[128:131], v[160:163], 0
	v_mfma_f32_16x16x32_bf16 v[88:91], v[136:139], v[160:163], 0
	v_mfma_f32_16x16x32_bf16 v[76:79], v[128:131], v[168:171], 0
	v_mfma_f32_16x16x32_bf16 v[72:75], v[136:139], v[168:171], 0
	v_mfma_f32_16x16x32_bf16 v[124:127], v[132:135], v[148:151], v[124:127]
	v_mfma_f32_16x16x32_bf16 v[120:123], v[140:143], v[148:151], v[120:123]
	v_mfma_f32_16x16x32_bf16 v[108:111], v[132:135], v[156:159], v[108:111]
	v_mfma_f32_16x16x32_bf16 v[104:107], v[140:143], v[156:159], v[104:107]
	v_mfma_f32_16x16x32_bf16 v[92:95], v[132:135], v[164:167], v[92:95]
	v_mfma_f32_16x16x32_bf16 v[88:91], v[140:143], v[164:167], v[88:91]
	v_mfma_f32_16x16x32_bf16 v[76:79], v[132:135], v[172:175], v[76:79]
	v_mfma_f32_16x16x32_bf16 v[72:75], v[140:143], v[172:175], v[72:75]
	s_setprio 0
	s_barrier
	s_add_i32 s24, s50, s37
	s_mov_b32 m0, s24
	ds_read_b128 v[176:179], v239
	ds_read_b128 v[180:183], v239 offset:1024
	ds_read_b128 v[184:187], v239 offset:2048
	ds_read_b128 v[188:191], v239 offset:3072
	global_load_lds_dwordx4 v204, s[28:29]
	s_add_i32 m0, s24, 0x2000
	s_nop 0
	global_load_lds_dwordx4 v208, s[28:29]
	s_waitcnt vmcnt(10)
	s_barrier
	s_waitcnt lgkmcnt(0)
	s_setprio 1
	s_waitcnt lgkmcnt(0)
	v_mfma_f32_16x16x32_bf16 v[116:119], v[176:179], v[144:147], 0
	v_mfma_f32_16x16x32_bf16 v[112:115], v[184:187], v[144:147], 0
	v_mfma_f32_16x16x32_bf16 v[100:103], v[176:179], v[152:155], 0
	v_mfma_f32_16x16x32_bf16 v[96:99], v[184:187], v[152:155], 0
	v_mfma_f32_16x16x32_bf16 v[84:87], v[176:179], v[160:163], 0
	v_mfma_f32_16x16x32_bf16 v[80:83], v[184:187], v[160:163], 0
	v_mfma_f32_16x16x32_bf16 v[68:71], v[176:179], v[168:171], 0
	v_mfma_f32_16x16x32_bf16 v[64:67], v[184:187], v[168:171], 0
	v_mfma_f32_16x16x32_bf16 v[116:119], v[180:183], v[148:151], v[116:119]
	v_mfma_f32_16x16x32_bf16 v[112:115], v[188:191], v[148:151], v[112:115]
	v_mfma_f32_16x16x32_bf16 v[100:103], v[180:183], v[156:159], v[100:103]
	v_mfma_f32_16x16x32_bf16 v[96:99], v[188:191], v[156:159], v[96:99]
	v_mfma_f32_16x16x32_bf16 v[84:87], v[180:183], v[164:167], v[84:87]
	v_mfma_f32_16x16x32_bf16 v[80:83], v[188:191], v[164:167], v[80:83]
	v_mfma_f32_16x16x32_bf16 v[68:71], v[180:183], v[172:175], v[68:71]
	v_mfma_f32_16x16x32_bf16 v[64:67], v[188:191], v[172:175], v[64:67]
	s_setprio 0
	s_mov_b32 m0, s38
	v_lshl_add_u64 v[196:197], s[30:31], 0, v[202:203]
	s_barrier
	ds_read_b128 v[144:147], v238 offset:16384
	ds_read_b128 v[148:151], v238 offset:17408
	ds_read_b128 v[152:155], v238 offset:18432
	ds_read_b128 v[156:159], v238 offset:19456
	ds_read_b128 v[160:163], v238 offset:20480
	ds_read_b128 v[164:167], v238 offset:21504
	ds_read_b128 v[168:171], v238 offset:22528
	ds_read_b128 v[172:175], v238 offset:23552
	global_load_lds_dwordx4 v202, s[30:31]
	v_lshl_add_u64 v[198:199], s[30:31], 0, v[206:207]
	s_mov_b32 m0, s39
	s_nop 0
	global_load_lds_dwordx4 v206, s[30:31]
	s_barrier
	s_waitcnt lgkmcnt(0)
	s_setprio 1
	s_waitcnt lgkmcnt(0)
	v_mfma_f32_16x16x32_bf16 v[60:63], v[128:131], v[144:147], 0
	v_mfma_f32_16x16x32_bf16 v[56:59], v[136:139], v[144:147], 0
	v_mfma_f32_16x16x32_bf16 v[44:47], v[128:131], v[152:155], 0
	v_mfma_f32_16x16x32_bf16 v[40:43], v[136:139], v[152:155], 0
	v_mfma_f32_16x16x32_bf16 v[28:31], v[128:131], v[160:163], 0
	v_mfma_f32_16x16x32_bf16 v[24:27], v[136:139], v[160:163], 0
	v_mfma_f32_16x16x32_bf16 v[12:15], v[128:131], v[168:171], 0
	v_mfma_f32_16x16x32_bf16 v[8:11], v[136:139], v[168:171], 0
	v_mfma_f32_16x16x32_bf16 v[60:63], v[132:135], v[148:151], v[60:63]
	v_mfma_f32_16x16x32_bf16 v[56:59], v[140:143], v[148:151], v[56:59]
	v_mfma_f32_16x16x32_bf16 v[44:47], v[132:135], v[156:159], v[44:47]
	v_mfma_f32_16x16x32_bf16 v[40:43], v[140:143], v[156:159], v[40:43]
	v_mfma_f32_16x16x32_bf16 v[28:31], v[132:135], v[164:167], v[28:31]
	v_mfma_f32_16x16x32_bf16 v[24:27], v[140:143], v[164:167], v[24:27]
	v_mfma_f32_16x16x32_bf16 v[12:15], v[132:135], v[172:175], v[12:15]
	v_mfma_f32_16x16x32_bf16 v[8:11], v[140:143], v[172:175], v[8:11]
	s_setprio 0
	s_barrier
; #define PG8_STAGE(bufoff, gbase, voff) do { _Pragma("unroll") for (int _i = 0; _i < 2; ++_i) \
;         __builtin_amdgcn_global_load_lds((const unsigned*)((const char*)(gbase) + (voff)[_i]), (LAS unsigned*)(lds + (bufoff) + ldsw + _i * 8192), 16, 0, 0); } while (0)
; #define PG8_LDA(dst, b, h) do { _Pragma("unroll") for (int m = 0; m < 4; ++m) _Pragma("unroll") for (int k = 0; k < 2; ++k) dst[m][k] = *(const LAS bf16x8*)(lds + PG8_SA(b, h) + aoff + m * 2048 + k * 1024); } while (0)
; #define PG8_LDB(dst, b, h) do { _Pragma("unroll") for (int n = 0; n < 2; ++n) _Pragma("unroll") for (int k = 0; k < 2; ++k) dst[n][k] = *(const LAS bf16x8*)(lds + PG8_SB(b, h) + boff + n * 2048 + k * 1024); } while (0)
; #define PG8_MMA(ai, bj, At, Bt) do { __builtin_amdgcn_s_setprio(1); _Pragma("unroll") for (int m = 0; m < 4; ++m) _Pragma("unroll") for (int n = 0; n < 2; ++n) _Pragma("unroll") for (int k = 0; k < 2; ++k) \
;         acc[ai][bj][m][n] = __builtin_amdgcn_mfma_f32_16x16x32_bf16(Bt[n][k], At[m][k], acc[ai][bj][m][n], 0, 0, 0); __builtin_amdgcn_s_setprio(0); } while (0)
; #define PG8_WAIT_V(n) asm volatile("s_waitcnt vmcnt(" #n ")" ::: "memory")
; #define PG8_WAIT_L(n) asm volatile("s_waitcnt lgkmcnt(" #n ")" ::: "memory")
; #define PG8_BAR __builtin_amdgcn_s_barrier()
; #define PG8_SCHED __builtin_amdgcn_sched_barrier(0)
; template <class Epi, class Sched>
; __device__ __forceinline__ void gemm_phase(LAS unsigned char* lds, const Gemm g, const Sched& S, const Epi& E) {
;     ...
;             PG8_STAGE(PG8_SB(0, 1), b2 + hstep, voffB);
;             PG8_WAIT_V(6); PG8_BAR; PG8_MMA(1, 1, At, B1); PG8_BAR;
;             PG8_LDB(B0, 1, 0); PG8_SCHED; PG8_LDA(At, 1, 0); PG8_STAGE(PG8_SA(0, 1), a2 + hstep, voffA);
;             PG8_WAIT_L(8); PG8_BAR; PG8_WAIT_L(0); PG8_MMA(0, 0, At, B0); PG8_BAR; PG8_SCHED;
;             PG8_LDB(B1, 1, 1); PG8_STAGE(PG8_SB(1, 0), b3, voffB);
;             PG8_BAR; PG8_WAIT_L(0); PG8_MMA(0, 1, At, B1); PG8_BAR;
;             PG8_LDA(At, 1, 1); PG8_STAGE(PG8_SA(1, 0), a3, voffA);
	s_add_u32 s24, s28, 0x60000
	s_addc_u32 s25, s29, 0
	s_add_i32 s59, s51, s37
	s_mov_b32 m0, s59
	s_nop 0
	global_load_lds_dwordx4 v204, s[24:25]
	s_add_i32 m0, s59, 0x2000
	s_nop 0
	global_load_lds_dwordx4 v208, s[24:25]
	s_add_u32 s24, s30, 0x60000
	s_addc_u32 s25, s31, 0
	s_mov_b32 m0, s40
	s_nop 0
	global_load_lds_dwordx4 v202, s[24:25]
	s_mov_b32 m0, s41
	s_nop 0
	global_load_lds_dwordx4 v206, s[24:25]
	s_waitcnt vmcnt(12)
	s_barrier
	s_setprio 1
	v_mfma_f32_16x16x32_bf16 v[52:55], v[176:179], v[144:147], 0
	v_mfma_f32_16x16x32_bf16 v[48:51], v[184:187], v[144:147], 0
	v_mfma_f32_16x16x32_bf16 v[36:39], v[176:179], v[152:155], 0
	v_mfma_f32_16x16x32_bf16 v[32:35], v[184:187], v[152:155], 0
	v_mfma_f32_16x16x32_bf16 v[20:23], v[176:179], v[160:163], 0
	v_mfma_f32_16x16x32_bf16 v[16:19], v[184:187], v[160:163], 0
	v_mfma_f32_16x16x32_bf16 v[4:7], v[176:179], v[168:171], 0
	v_mfma_f32_16x16x32_bf16 v[0:3], v[184:187], v[168:171], 0
	v_mfma_f32_16x16x32_bf16 v[52:55], v[180:183], v[148:151], v[52:55]
	v_mfma_f32_16x16x32_bf16 v[48:51], v[188:191], v[148:151], v[48:51]
	v_mfma_f32_16x16x32_bf16 v[36:39], v[180:183], v[156:159], v[36:39]
	v_mfma_f32_16x16x32_bf16 v[32:35], v[188:191], v[156:159], v[32:35]
	v_mfma_f32_16x16x32_bf16 v[20:23], v[180:183], v[164:167], v[20:23]
	v_mfma_f32_16x16x32_bf16 v[16:19], v[188:191], v[164:167], v[16:19]
	v_mfma_f32_16x16x32_bf16 v[4:7], v[180:183], v[172:175], v[4:7]
	v_mfma_f32_16x16x32_bf16 v[0:3], v[188:191], v[172:175], v[0:3]
	s_setprio 0
	s_add_i32 s59, 0, 0x18000
	v_add_u32_e32 v140, s59, v236
	s_barrier
	ds_read_b128 v[128:131], v140
	ds_read_b128 v[132:135], v140 offset:1024
	ds_read_b128 v[136:139], v140 offset:2048
	ds_read_b128 v[140:143], v140 offset:3072
	ds_read_b128 v[144:147], v238 offset:32768
	ds_read_b128 v[148:151], v238 offset:33792
	ds_read_b128 v[152:155], v238 offset:34816
	ds_read_b128 v[156:159], v238 offset:35840
	ds_read_b128 v[160:163], v238 offset:36864
	ds_read_b128 v[164:167], v238 offset:37888
	ds_read_b128 v[168:171], v238 offset:38912
	ds_read_b128 v[172:175], v238 offset:39936
	s_waitcnt lgkmcnt(8)
	s_waitcnt vmcnt(10)
	s_barrier
	s_waitcnt lgkmcnt(0)
	s_setprio 1
	s_waitcnt lgkmcnt(0)
	v_mfma_f32_16x16x32_bf16 v[124:127], v[128:131], v[144:147], v[124:127]
	v_mfma_f32_16x16x32_bf16 v[120:123], v[136:139], v[144:147], v[120:123]
	v_mfma_f32_16x16x32_bf16 v[108:111], v[128:131], v[152:155], v[108:111]
	v_mfma_f32_16x16x32_bf16 v[104:107], v[136:139], v[152:155], v[104:107]
	v_mfma_f32_16x16x32_bf16 v[92:95], v[128:131], v[160:163], v[92:95]
	v_mfma_f32_16x16x32_bf16 v[88:91], v[136:139], v[160:163], v[88:91]
	v_mfma_f32_16x16x32_bf16 v[76:79], v[128:131], v[168:171], v[76:79]
	v_mfma_f32_16x16x32_bf16 v[72:75], v[136:139], v[168:171], v[72:75]
	v_mfma_f32_16x16x32_bf16 v[124:127], v[132:135], v[148:151], v[124:127]
	v_mfma_f32_16x16x32_bf16 v[120:123], v[140:143], v[148:151], v[120:123]
	v_mfma_f32_16x16x32_bf16 v[108:111], v[132:135], v[156:159], v[108:111]
	v_mfma_f32_16x16x32_bf16 v[104:107], v[140:143], v[156:159], v[104:107]
	v_mfma_f32_16x16x32_bf16 v[92:95], v[132:135], v[164:167], v[92:95]
	v_mfma_f32_16x16x32_bf16 v[88:91], v[140:143], v[164:167], v[88:91]
	v_mfma_f32_16x16x32_bf16 v[76:79], v[132:135], v[172:175], v[76:79]
	v_mfma_f32_16x16x32_bf16 v[72:75], v[140:143], v[172:175], v[72:75]
	s_setprio 0
	s_barrier
	s_add_i32 s30, 0, 0x1c000
	s_add_i32 s24, s59, s37
	v_add_u32_e32 v188, s30, v236
	s_add_u32 s0, s28, 0x80
	s_addc_u32 s1, s29, 0
	s_mov_b32 m0, s24
	ds_read_b128 v[176:179], v188
	ds_read_b128 v[180:183], v188 offset:1024
	ds_read_b128 v[184:187], v188 offset:2048
	ds_read_b128 v[188:191], v188 offset:3072
	global_load_lds_dwordx4 v204, s[0:1]
	s_add_i32 m0, s24, 0x2000
	s_nop 0
	global_load_lds_dwordx4 v208, s[0:1]
	s_waitcnt vmcnt(10)
	s_barrier
	s_waitcnt lgkmcnt(0)
	s_setprio 1
	s_waitcnt lgkmcnt(0)
	v_mfma_f32_16x16x32_bf16 v[116:119], v[176:179], v[144:147], v[116:119]
	v_mfma_f32_16x16x32_bf16 v[112:115], v[184:187], v[144:147], v[112:115]
	v_mfma_f32_16x16x32_bf16 v[100:103], v[176:179], v[152:155], v[100:103]
	v_mfma_f32_16x16x32_bf16 v[96:99], v[184:187], v[152:155], v[96:99]
	v_mfma_f32_16x16x32_bf16 v[84:87], v[176:179], v[160:163], v[84:87]
	v_mfma_f32_16x16x32_bf16 v[80:83], v[184:187], v[160:163], v[80:83]
	v_mfma_f32_16x16x32_bf16 v[68:71], v[176:179], v[168:171], v[68:71]
	v_mfma_f32_16x16x32_bf16 v[64:67], v[184:187], v[168:171], v[64:67]
	v_mfma_f32_16x16x32_bf16 v[116:119], v[180:183], v[148:151], v[116:119]
	v_mfma_f32_16x16x32_bf16 v[112:115], v[188:191], v[148:151], v[112:115]
	v_mfma_f32_16x16x32_bf16 v[100:103], v[180:183], v[156:159], v[100:103]
	v_mfma_f32_16x16x32_bf16 v[96:99], v[188:191], v[156:159], v[96:99]
	v_mfma_f32_16x16x32_bf16 v[84:87], v[180:183], v[164:167], v[84:87]
	v_mfma_f32_16x16x32_bf16 v[80:83], v[188:191], v[164:167], v[80:83]
	v_mfma_f32_16x16x32_bf16 v[68:71], v[180:183], v[172:175], v[68:71]
	v_mfma_f32_16x16x32_bf16 v[64:67], v[188:191], v[172:175], v[64:67]
	s_setprio 0
	s_mov_b32 m0, s47
	s_mov_b64 s[0:1], 0x80
	v_lshl_add_u64 v[192:193], v[196:197], 0, s[0:1]
	s_barrier
	ds_read_b128 v[144:147], v238 offset:49152
	ds_read_b128 v[148:151], v238 offset:50176
	ds_read_b128 v[152:155], v238 offset:51200
	ds_read_b128 v[156:159], v238 offset:52224
	ds_read_b128 v[160:163], v238 offset:53248
	ds_read_b128 v[164:167], v238 offset:54272
	ds_read_b128 v[168:171], v238 offset:55296
	ds_read_b128 v[172:175], v238 offset:56320
	global_load_lds_dwordx4 v[192:193], off
	v_lshl_add_u64 v[192:193], v[198:199], 0, s[0:1]
	s_mov_b32 m0, s48
	s_nop 0
	global_load_lds_dwordx4 v[192:193], off
	s_barrier
; #define PG8_STAGE(bufoff, gbase, voff) do { _Pragma("unroll") for (int _i = 0; _i < 2; ++_i) \
;         __builtin_amdgcn_global_load_lds((const unsigned*)((const char*)(gbase) + (voff)[_i]), (LAS unsigned*)(lds + (bufoff) + ldsw + _i * 8192), 16, 0, 0); } while (0)
; #define PG8_LDA(dst, b, h) do { _Pragma("unroll") for (int m = 0; m < 4; ++m) _Pragma("unroll") for (int k = 0; k < 2; ++k) dst[m][k] = *(const LAS bf16x8*)(lds + PG8_SA(b, h) + aoff + m * 2048 + k * 1024); } while (0)
; #define PG8_LDB(dst, b, h) do { _Pragma("unroll") for (int n = 0; n < 2; ++n) _Pragma("unroll") for (int k = 0; k < 2; ++k) dst[n][k] = *(const LAS bf16x8*)(lds + PG8_SB(b, h) + boff + n * 2048 + k * 1024); } while (0)
; #define PG8_MMA(ai, bj, At, Bt) do { __builtin_amdgcn_s_setprio(1); _Pragma("unroll") for (int m = 0; m < 4; ++m) _Pragma("unroll") for (int n = 0; n < 2; ++n) _Pragma("unroll") for (int k = 0; k < 2; ++k) \
;         acc[ai][bj][m][n] = __builtin_amdgcn_mfma_f32_16x16x32_bf16(Bt[n][k], At[m][k], acc[ai][bj][m][n], 0, 0, 0); __builtin_amdgcn_s_setprio(0); } while (0)
; #define PG8_WAIT_V(n) asm volatile("s_waitcnt vmcnt(" #n ")" ::: "memory")
; #define PG8_WAIT_L(n) asm volatile("s_waitcnt lgkmcnt(" #n ")" ::: "memory")
; template <class Epi, class Sched>
; __device__ __forceinline__ void gemm_phase(LAS unsigned char* lds, const Gemm g, const Sched& S, const Epi& E) {
;     ...
;         for (int t = 0; t < nt; t += 2) {
;             const bool last = (t == nt - 2);
;             const char* a1 = cA + (size_t)(t + 1) * kstep;
;             const char* a2 = last ? nA : cA + (size_t)(t + 2) * kstep; const char* b2 = last ? nB : cB + (size_t)(t + 2) * kstep;
;             const char* a3 = a2 + kstep; const char* b3 = b2 + kstep;
;             PG8_LDB(B0, 0, 0); PG8_SCHED; PG8_LDA(At, 0, 0); PG8_STAGE(PG8_SA(1, 1), a1 + hstep, voffA);
;             PG8_WAIT_L(8); PG8_BAR; PG8_WAIT_L(0); PG8_MMA(0, 0, At, B0); PG8_BAR; PG8_SCHED;
;             PG8_LDB(B1, 0, 1); PG8_STAGE(PG8_SB(0, 0), b2, voffB);
;             PG8_BAR; PG8_WAIT_L(0); PG8_MMA(0, 1, At, B1); PG8_BAR;
;     ...
;             PG8_LDA(At, 1, 1); PG8_STAGE(PG8_SA(1, 0), a3, voffA);
;             PG8_BAR; PG8_WAIT_L(0); PG8_MMA(1, 0, At, B0); PG8_BAR; PG8_SCHED;
;             PG8_STAGE(PG8_SB(1, 1), b3 + hstep, voffB);
;             PG8_WAIT_V(6); PG8_BAR; PG8_MMA(1, 1, At, B1); PG8_BAR;
	s_waitcnt lgkmcnt(0)
	s_setprio 1
	s_waitcnt lgkmcnt(0)
	v_mfma_f32_16x16x32_bf16 v[60:63], v[128:131], v[144:147], v[60:63]
	v_mfma_f32_16x16x32_bf16 v[56:59], v[136:139], v[144:147], v[56:59]
	v_mfma_f32_16x16x32_bf16 v[44:47], v[128:131], v[152:155], v[44:47]
	v_mfma_f32_16x16x32_bf16 v[40:43], v[136:139], v[152:155], v[40:43]
	v_mfma_f32_16x16x32_bf16 v[28:31], v[128:131], v[160:163], v[28:31]
	v_mfma_f32_16x16x32_bf16 v[24:27], v[136:139], v[160:163], v[24:27]
	v_mfma_f32_16x16x32_bf16 v[12:15], v[128:131], v[168:171], v[12:15]
	v_mfma_f32_16x16x32_bf16 v[8:11], v[136:139], v[168:171], v[8:11]
	v_mfma_f32_16x16x32_bf16 v[60:63], v[132:135], v[148:151], v[60:63]
	v_mfma_f32_16x16x32_bf16 v[56:59], v[140:143], v[148:151], v[56:59]
	v_mfma_f32_16x16x32_bf16 v[44:47], v[132:135], v[156:159], v[44:47]
	v_mfma_f32_16x16x32_bf16 v[40:43], v[140:143], v[156:159], v[40:43]
	v_mfma_f32_16x16x32_bf16 v[28:31], v[132:135], v[164:167], v[28:31]
	v_mfma_f32_16x16x32_bf16 v[24:27], v[140:143], v[164:167], v[24:27]
	v_mfma_f32_16x16x32_bf16 v[12:15], v[132:135], v[172:175], v[12:15]
	v_mfma_f32_16x16x32_bf16 v[8:11], v[140:143], v[172:175], v[8:11]
	s_setprio 0
	s_barrier
	s_add_u32 s24, s28, 0x60080
	s_addc_u32 s25, s29, 0
	s_add_i32 s28, s30, s37
	s_mov_b32 m0, s28
	s_nop 0
	global_load_lds_dwordx4 v204, s[24:25]
	s_add_i32 m0, s28, 0x2000
	s_nop 0
	global_load_lds_dwordx4 v208, s[24:25]
	s_waitcnt vmcnt(10)
	s_barrier
	s_setprio 1
	v_mfma_f32_16x16x32_bf16 v[52:55], v[176:179], v[144:147], v[52:55]
	v_mfma_f32_16x16x32_bf16 v[48:51], v[184:187], v[144:147], v[48:51]
	v_mfma_f32_16x16x32_bf16 v[36:39], v[176:179], v[152:155], v[36:39]
	v_mfma_f32_16x16x32_bf16 v[32:35], v[184:187], v[152:155], v[32:35]
	v_mfma_f32_16x16x32_bf16 v[20:23], v[176:179], v[160:163], v[20:23]
	v_mfma_f32_16x16x32_bf16 v[16:19], v[184:187], v[160:163], v[16:19]
	v_mfma_f32_16x16x32_bf16 v[4:7], v[176:179], v[168:171], v[4:7]
	v_mfma_f32_16x16x32_bf16 v[0:3], v[184:187], v[168:171], v[0:3]
	v_mfma_f32_16x16x32_bf16 v[52:55], v[180:183], v[148:151], v[52:55]
	v_mfma_f32_16x16x32_bf16 v[48:51], v[188:191], v[148:151], v[48:51]
	v_mfma_f32_16x16x32_bf16 v[36:39], v[180:183], v[156:159], v[36:39]
	v_mfma_f32_16x16x32_bf16 v[32:35], v[188:191], v[156:159], v[32:35]
	v_mfma_f32_16x16x32_bf16 v[20:23], v[180:183], v[164:167], v[20:23]
	v_mfma_f32_16x16x32_bf16 v[16:19], v[188:191], v[164:167], v[16:19]
	v_mfma_f32_16x16x32_bf16 v[4:7], v[180:183], v[172:175], v[4:7]
	v_mfma_f32_16x16x32_bf16 v[0:3], v[188:191], v[172:175], v[0:3]
	s_setprio 0
	s_add_i32 s58, s58, 2
	s_add_u32 s56, s56, 0x100
	s_addc_u32 s57, s57, 0
	s_cmp_gt_u32 s58, 21
	s_mov_b64 s[24:25], s[26:27]
	s_barrier
.LBB0_902:
	ds_read_b128 v[128:131], v237
	ds_read_b128 v[132:135], v237 offset:1024
	ds_read_b128 v[136:139], v237 offset:2048
	ds_read_b128 v[140:143], v237 offset:3072
	s_add_u32 s26, s24, 0x100
	s_addc_u32 s27, s25, 0
	s_cmp_eq_u32 s58, 20
	s_cselect_b32 s31, s5, s27
	s_cselect_b32 s30, s4, s26
	s_cselect_b32 s29, s7, s57
	s_cselect_b32 s28, s6, s56
	v_lshl_add_u64 v[176:177], s[24:25], 0, v[210:211]
	s_add_i32 m0, s38, 0xc000
	ds_read_b128 v[144:147], v238
	ds_read_b128 v[148:151], v238 offset:1024
	ds_read_b128 v[152:155], v238 offset:2048
	ds_read_b128 v[156:159], v238 offset:3072
	ds_read_b128 v[160:163], v238 offset:4096
	ds_read_b128 v[164:167], v238 offset:5120
	ds_read_b128 v[168:171], v238 offset:6144
	ds_read_b128 v[172:175], v238 offset:7168
	global_load_lds_dwordx4 v[176:177], off
	v_lshl_add_u64 v[176:177], s[24:25], 0, v[212:213]
	s_add_i32 m0, s38, 0xe000
	s_nop 0
	global_load_lds_dwordx4 v[176:177], off
	s_waitcnt lgkmcnt(8)
	s_waitcnt vmcnt(10)
	s_barrier
	s_waitcnt lgkmcnt(0)
	s_setprio 1
	s_waitcnt lgkmcnt(0)
	v_mfma_f32_16x16x32_bf16 v[124:127], v[128:131], v[144:147], v[124:127]
	v_mfma_f32_16x16x32_bf16 v[120:123], v[136:139], v[144:147], v[120:123]
	v_mfma_f32_16x16x32_bf16 v[108:111], v[128:131], v[152:155], v[108:111]
	v_mfma_f32_16x16x32_bf16 v[104:107], v[136:139], v[152:155], v[104:107]
	v_mfma_f32_16x16x32_bf16 v[92:95], v[128:131], v[160:163], v[92:95]
	v_mfma_f32_16x16x32_bf16 v[88:91], v[136:139], v[160:163], v[88:91]
	v_mfma_f32_16x16x32_bf16 v[76:79], v[128:131], v[168:171], v[76:79]
	v_mfma_f32_16x16x32_bf16 v[72:75], v[136:139], v[168:171], v[72:75]
	v_mfma_f32_16x16x32_bf16 v[124:127], v[132:135], v[148:151], v[124:127]
	v_mfma_f32_16x16x32_bf16 v[120:123], v[140:143], v[148:151], v[120:123]
	v_mfma_f32_16x16x32_bf16 v[108:111], v[132:135], v[156:159], v[108:111]
	v_mfma_f32_16x16x32_bf16 v[104:107], v[140:143], v[156:159], v[104:107]
	v_mfma_f32_16x16x32_bf16 v[92:95], v[132:135], v[164:167], v[92:95]
	v_mfma_f32_16x16x32_bf16 v[88:91], v[140:143], v[164:167], v[88:91]
	v_mfma_f32_16x16x32_bf16 v[76:79], v[132:135], v[172:175], v[76:79]
	v_mfma_f32_16x16x32_bf16 v[72:75], v[140:143], v[172:175], v[72:75]
	s_setprio 0
	s_barrier
	s_add_i32 s24, s50, s37
	s_mov_b32 m0, s24
	ds_read_b128 v[176:179], v239
	ds_read_b128 v[180:183], v239 offset:1024
	ds_read_b128 v[184:187], v239 offset:2048
	ds_read_b128 v[188:191], v239 offset:3072
	global_load_lds_dwordx4 v204, s[28:29]
	s_add_i32 m0, s24, 0x2000
	s_nop 0
	global_load_lds_dwordx4 v208, s[28:29]
	s_waitcnt vmcnt(10)
	s_barrier
; #define PG8_STAGE(bufoff, gbase, voff) do { _Pragma("unroll") for (int _i = 0; _i < 2; ++_i) \
;         __builtin_amdgcn_global_load_lds((const unsigned*)((const char*)(gbase) + (voff)[_i]), (LAS unsigned*)(lds + (bufoff) + ldsw + _i * 8192), 16, 0, 0); } while (0)
; #define PG8_LDA(dst, b, h) do { _Pragma("unroll") for (int m = 0; m < 4; ++m) _Pragma("unroll") for (int k = 0; k < 2; ++k) dst[m][k] = *(const LAS bf16x8*)(lds + PG8_SA(b, h) + aoff + m * 2048 + k * 1024); } while (0)
; #define PG8_LDB(dst, b, h) do { _Pragma("unroll") for (int n = 0; n < 2; ++n) _Pragma("unroll") for (int k = 0; k < 2; ++k) dst[n][k] = *(const LAS bf16x8*)(lds + PG8_SB(b, h) + boff + n * 2048 + k * 1024); } while (0)
; #define PG8_MMA(ai, bj, At, Bt) do { __builtin_amdgcn_s_setprio(1); _Pragma("unroll") for (int m = 0; m < 4; ++m) _Pragma("unroll") for (int n = 0; n < 2; ++n) _Pragma("unroll") for (int k = 0; k < 2; ++k) \
;         acc[ai][bj][m][n] = __builtin_amdgcn_mfma_f32_16x16x32_bf16(Bt[n][k], At[m][k], acc[ai][bj][m][n], 0, 0, 0); __builtin_amdgcn_s_setprio(0); } while (0)
; #define PG8_WAIT_V(n) asm volatile("s_waitcnt vmcnt(" #n ")" ::: "memory")
; #define PG8_WAIT_L(n) asm volatile("s_waitcnt lgkmcnt(" #n ")" ::: "memory")
; #define PG8_BAR __builtin_amdgcn_s_barrier()
; #define PG8_SCHED __builtin_amdgcn_sched_barrier(0)
; template <class Epi, class Sched>
; __device__ __forceinline__ void gemm_phase(LAS unsigned char* lds, const Gemm g, const Sched& S, const Epi& E) {
;     ...
;             PG8_BAR; PG8_WAIT_L(0); PG8_MMA(0, 1, At, B1); PG8_BAR;
;             PG8_LDA(At, 0, 1); PG8_STAGE(PG8_SA(0, 0), a2, voffA);
;             PG8_BAR; PG8_WAIT_L(0); PG8_MMA(1, 0, At, B0); PG8_BAR; PG8_SCHED;
;             PG8_STAGE(PG8_SB(0, 1), b2 + hstep, voffB);
;             PG8_WAIT_V(6); PG8_BAR; PG8_MMA(1, 1, At, B1); PG8_BAR;
;             PG8_LDB(B0, 1, 0); PG8_SCHED; PG8_LDA(At, 1, 0); PG8_STAGE(PG8_SA(0, 1), a2 + hstep, voffA);
;             PG8_WAIT_L(8); PG8_BAR; PG8_WAIT_L(0); PG8_MMA(0, 0, At, B0); PG8_BAR; PG8_SCHED;
	s_waitcnt lgkmcnt(0)
	s_setprio 1
	s_waitcnt lgkmcnt(0)
	v_mfma_f32_16x16x32_bf16 v[116:119], v[176:179], v[144:147], v[116:119]
	v_mfma_f32_16x16x32_bf16 v[112:115], v[184:187], v[144:147], v[112:115]
	v_mfma_f32_16x16x32_bf16 v[100:103], v[176:179], v[152:155], v[100:103]
	v_mfma_f32_16x16x32_bf16 v[96:99], v[184:187], v[152:155], v[96:99]
	v_mfma_f32_16x16x32_bf16 v[84:87], v[176:179], v[160:163], v[84:87]
	v_mfma_f32_16x16x32_bf16 v[80:83], v[184:187], v[160:163], v[80:83]
	v_mfma_f32_16x16x32_bf16 v[68:71], v[176:179], v[168:171], v[68:71]
	v_mfma_f32_16x16x32_bf16 v[64:67], v[184:187], v[168:171], v[64:67]
	v_mfma_f32_16x16x32_bf16 v[116:119], v[180:183], v[148:151], v[116:119]
	v_mfma_f32_16x16x32_bf16 v[112:115], v[188:191], v[148:151], v[112:115]
	v_mfma_f32_16x16x32_bf16 v[100:103], v[180:183], v[156:159], v[100:103]
	v_mfma_f32_16x16x32_bf16 v[96:99], v[188:191], v[156:159], v[96:99]
	v_mfma_f32_16x16x32_bf16 v[84:87], v[180:183], v[164:167], v[84:87]
	v_mfma_f32_16x16x32_bf16 v[80:83], v[188:191], v[164:167], v[80:83]
	v_mfma_f32_16x16x32_bf16 v[68:71], v[180:183], v[172:175], v[68:71]
	v_mfma_f32_16x16x32_bf16 v[64:67], v[188:191], v[172:175], v[64:67]
	s_setprio 0
	s_mov_b32 m0, s38
	v_lshl_add_u64 v[196:197], s[30:31], 0, v[202:203]
	s_barrier
	ds_read_b128 v[144:147], v238 offset:16384
	ds_read_b128 v[148:151], v238 offset:17408
	ds_read_b128 v[152:155], v238 offset:18432
	ds_read_b128 v[156:159], v238 offset:19456
	ds_read_b128 v[160:163], v238 offset:20480
	ds_read_b128 v[164:167], v238 offset:21504
	ds_read_b128 v[168:171], v238 offset:22528
	ds_read_b128 v[172:175], v238 offset:23552
	global_load_lds_dwordx4 v202, s[30:31]
	v_lshl_add_u64 v[198:199], s[30:31], 0, v[206:207]
	s_mov_b32 m0, s39
	s_nop 0
	global_load_lds_dwordx4 v206, s[30:31]
	s_barrier
	s_waitcnt lgkmcnt(0)
	s_setprio 1
	s_waitcnt lgkmcnt(0)
	v_mfma_f32_16x16x32_bf16 v[60:63], v[128:131], v[144:147], v[60:63]
	v_mfma_f32_16x16x32_bf16 v[56:59], v[136:139], v[144:147], v[56:59]
	v_mfma_f32_16x16x32_bf16 v[44:47], v[128:131], v[152:155], v[44:47]
	v_mfma_f32_16x16x32_bf16 v[40:43], v[136:139], v[152:155], v[40:43]
	v_mfma_f32_16x16x32_bf16 v[28:31], v[128:131], v[160:163], v[28:31]
	v_mfma_f32_16x16x32_bf16 v[24:27], v[136:139], v[160:163], v[24:27]
	v_mfma_f32_16x16x32_bf16 v[12:15], v[128:131], v[168:171], v[12:15]
	v_mfma_f32_16x16x32_bf16 v[8:11], v[136:139], v[168:171], v[8:11]
	v_mfma_f32_16x16x32_bf16 v[60:63], v[132:135], v[148:151], v[60:63]
	v_mfma_f32_16x16x32_bf16 v[56:59], v[140:143], v[148:151], v[56:59]
	v_mfma_f32_16x16x32_bf16 v[44:47], v[132:135], v[156:159], v[44:47]
	v_mfma_f32_16x16x32_bf16 v[40:43], v[140:143], v[156:159], v[40:43]
	v_mfma_f32_16x16x32_bf16 v[28:31], v[132:135], v[164:167], v[28:31]
	v_mfma_f32_16x16x32_bf16 v[24:27], v[140:143], v[164:167], v[24:27]
	v_mfma_f32_16x16x32_bf16 v[12:15], v[132:135], v[172:175], v[12:15]
	v_mfma_f32_16x16x32_bf16 v[8:11], v[140:143], v[172:175], v[8:11]
	s_setprio 0
	s_barrier
	s_add_u32 s24, s28, 0x60000
	s_addc_u32 s25, s29, 0
	s_add_i32 s59, s51, s37
	s_mov_b32 m0, s59
	s_nop 0
	global_load_lds_dwordx4 v204, s[24:25]
	s_add_i32 m0, s59, 0x2000
	s_nop 0
	global_load_lds_dwordx4 v208, s[24:25]
	s_add_u32 s24, s30, 0x60000
	s_addc_u32 s25, s31, 0
	s_mov_b32 m0, s40
	s_nop 0
	global_load_lds_dwordx4 v202, s[24:25]
	s_mov_b32 m0, s41
	s_nop 0
	global_load_lds_dwordx4 v206, s[24:25]
	s_waitcnt vmcnt(12)
	s_barrier
	s_setprio 1
	v_mfma_f32_16x16x32_bf16 v[52:55], v[176:179], v[144:147], v[52:55]
	v_mfma_f32_16x16x32_bf16 v[48:51], v[184:187], v[144:147], v[48:51]
	v_mfma_f32_16x16x32_bf16 v[36:39], v[176:179], v[152:155], v[36:39]
	v_mfma_f32_16x16x32_bf16 v[32:35], v[184:187], v[152:155], v[32:35]
	v_mfma_f32_16x16x32_bf16 v[20:23], v[176:179], v[160:163], v[20:23]
	v_mfma_f32_16x16x32_bf16 v[16:19], v[184:187], v[160:163], v[16:19]
	v_mfma_f32_16x16x32_bf16 v[4:7], v[176:179], v[168:171], v[4:7]
	v_mfma_f32_16x16x32_bf16 v[0:3], v[184:187], v[168:171], v[0:3]
	v_mfma_f32_16x16x32_bf16 v[52:55], v[180:183], v[148:151], v[52:55]
	v_mfma_f32_16x16x32_bf16 v[48:51], v[188:191], v[148:151], v[48:51]
	v_mfma_f32_16x16x32_bf16 v[36:39], v[180:183], v[156:159], v[36:39]
	v_mfma_f32_16x16x32_bf16 v[32:35], v[188:191], v[156:159], v[32:35]
	v_mfma_f32_16x16x32_bf16 v[20:23], v[180:183], v[164:167], v[20:23]
	v_mfma_f32_16x16x32_bf16 v[16:19], v[188:191], v[164:167], v[16:19]
	v_mfma_f32_16x16x32_bf16 v[4:7], v[180:183], v[172:175], v[4:7]
	v_mfma_f32_16x16x32_bf16 v[0:3], v[188:191], v[172:175], v[0:3]
	s_setprio 0
	s_add_i32 s59, 0, 0x18000
	v_add_u32_e32 v140, s59, v236
	s_barrier
	ds_read_b128 v[128:131], v140
	ds_read_b128 v[132:135], v140 offset:1024
	ds_read_b128 v[136:139], v140 offset:2048
	ds_read_b128 v[140:143], v140 offset:3072
	ds_read_b128 v[144:147], v238 offset:32768
	ds_read_b128 v[148:151], v238 offset:33792
	ds_read_b128 v[152:155], v238 offset:34816
	ds_read_b128 v[156:159], v238 offset:35840
	ds_read_b128 v[160:163], v238 offset:36864
	ds_read_b128 v[164:167], v238 offset:37888
	ds_read_b128 v[168:171], v238 offset:38912
	ds_read_b128 v[172:175], v238 offset:39936
	s_waitcnt lgkmcnt(8)
	s_waitcnt vmcnt(10)
	s_barrier
; #define PG8_STAGE(bufoff, gbase, voff) do { _Pragma("unroll") for (int _i = 0; _i < 2; ++_i) \
;         __builtin_amdgcn_global_load_lds((const unsigned*)((const char*)(gbase) + (voff)[_i]), (LAS unsigned*)(lds + (bufoff) + ldsw + _i * 8192), 16, 0, 0); } while (0)
; #define PG8_LDA(dst, b, h) do { _Pragma("unroll") for (int m = 0; m < 4; ++m) _Pragma("unroll") for (int k = 0; k < 2; ++k) dst[m][k] = *(const LAS bf16x8*)(lds + PG8_SA(b, h) + aoff + m * 2048 + k * 1024); } while (0)
; #define PG8_LDB(dst, b, h) do { _Pragma("unroll") for (int n = 0; n < 2; ++n) _Pragma("unroll") for (int k = 0; k < 2; ++k) dst[n][k] = *(const LAS bf16x8*)(lds + PG8_SB(b, h) + boff + n * 2048 + k * 1024); } while (0)
; #define PG8_MMA(ai, bj, At, Bt) do { __builtin_amdgcn_s_setprio(1); _Pragma("unroll") for (int m = 0; m < 4; ++m) _Pragma("unroll") for (int n = 0; n < 2; ++n) _Pragma("unroll") for (int k = 0; k < 2; ++k) \
;         acc[ai][bj][m][n] = __builtin_amdgcn_mfma_f32_16x16x32_bf16(Bt[n][k], At[m][k], acc[ai][bj][m][n], 0, 0, 0); __builtin_amdgcn_s_setprio(0); } while (0)
; #define PG8_WAIT_V(n) asm volatile("s_waitcnt vmcnt(" #n ")" ::: "memory")
; #define PG8_WAIT_L(n) asm volatile("s_waitcnt lgkmcnt(" #n ")" ::: "memory")
; #define PG8_BAR __builtin_amdgcn_s_barrier()
; #define PG8_SCHED __builtin_amdgcn_sched_barrier(0)
; template <class Epi, class Sched>
; __device__ __forceinline__ void gemm_phase(LAS unsigned char* lds, const Gemm g, const Sched& S, const Epi& E) {
;     ...
;             PG8_WAIT_L(8); PG8_BAR; PG8_WAIT_L(0); PG8_MMA(0, 0, At, B0); PG8_BAR; PG8_SCHED;
;             PG8_LDB(B1, 1, 1); PG8_STAGE(PG8_SB(1, 0), b3, voffB);
;             PG8_BAR; PG8_WAIT_L(0); PG8_MMA(0, 1, At, B1); PG8_BAR;
;             PG8_LDA(At, 1, 1); PG8_STAGE(PG8_SA(1, 0), a3, voffA);
;             PG8_BAR; PG8_WAIT_L(0); PG8_MMA(1, 0, At, B0); PG8_BAR; PG8_SCHED;
;             PG8_STAGE(PG8_SB(1, 1), b3 + hstep, voffB);
;             PG8_WAIT_V(6); PG8_BAR; PG8_MMA(1, 1, At, B1); PG8_BAR;
	s_waitcnt lgkmcnt(0)
	s_setprio 1
	s_waitcnt lgkmcnt(0)
	v_mfma_f32_16x16x32_bf16 v[124:127], v[128:131], v[144:147], v[124:127]
	v_mfma_f32_16x16x32_bf16 v[120:123], v[136:139], v[144:147], v[120:123]
	v_mfma_f32_16x16x32_bf16 v[108:111], v[128:131], v[152:155], v[108:111]
	v_mfma_f32_16x16x32_bf16 v[104:107], v[136:139], v[152:155], v[104:107]
	v_mfma_f32_16x16x32_bf16 v[92:95], v[128:131], v[160:163], v[92:95]
	v_mfma_f32_16x16x32_bf16 v[88:91], v[136:139], v[160:163], v[88:91]
	v_mfma_f32_16x16x32_bf16 v[76:79], v[128:131], v[168:171], v[76:79]
	v_mfma_f32_16x16x32_bf16 v[72:75], v[136:139], v[168:171], v[72:75]
	v_mfma_f32_16x16x32_bf16 v[124:127], v[132:135], v[148:151], v[124:127]
	v_mfma_f32_16x16x32_bf16 v[120:123], v[140:143], v[148:151], v[120:123]
	v_mfma_f32_16x16x32_bf16 v[108:111], v[132:135], v[156:159], v[108:111]
	v_mfma_f32_16x16x32_bf16 v[104:107], v[140:143], v[156:159], v[104:107]
	v_mfma_f32_16x16x32_bf16 v[92:95], v[132:135], v[164:167], v[92:95]
	v_mfma_f32_16x16x32_bf16 v[88:91], v[140:143], v[164:167], v[88:91]
	v_mfma_f32_16x16x32_bf16 v[76:79], v[132:135], v[172:175], v[76:79]
	v_mfma_f32_16x16x32_bf16 v[72:75], v[140:143], v[172:175], v[72:75]
	s_setprio 0
	s_barrier
	s_add_i32 s30, 0, 0x1c000
	s_add_i32 s24, s59, s37
	v_add_u32_e32 v188, s30, v236
	s_add_u32 s0, s28, 0x80
	s_addc_u32 s1, s29, 0
	s_mov_b32 m0, s24
	ds_read_b128 v[176:179], v188
	ds_read_b128 v[180:183], v188 offset:1024
	ds_read_b128 v[184:187], v188 offset:2048
	ds_read_b128 v[188:191], v188 offset:3072
	global_load_lds_dwordx4 v204, s[0:1]
	s_add_i32 m0, s24, 0x2000
	s_nop 0
	global_load_lds_dwordx4 v208, s[0:1]
	s_waitcnt vmcnt(10)
	s_barrier
	s_waitcnt lgkmcnt(0)
	s_setprio 1
	s_waitcnt lgkmcnt(0)
	v_mfma_f32_16x16x32_bf16 v[116:119], v[176:179], v[144:147], v[116:119]
	v_mfma_f32_16x16x32_bf16 v[112:115], v[184:187], v[144:147], v[112:115]
	v_mfma_f32_16x16x32_bf16 v[100:103], v[176:179], v[152:155], v[100:103]
	v_mfma_f32_16x16x32_bf16 v[96:99], v[184:187], v[152:155], v[96:99]
	v_mfma_f32_16x16x32_bf16 v[84:87], v[176:179], v[160:163], v[84:87]
	v_mfma_f32_16x16x32_bf16 v[80:83], v[184:187], v[160:163], v[80:83]
	v_mfma_f32_16x16x32_bf16 v[68:71], v[176:179], v[168:171], v[68:71]
	v_mfma_f32_16x16x32_bf16 v[64:67], v[184:187], v[168:171], v[64:67]
	v_mfma_f32_16x16x32_bf16 v[116:119], v[180:183], v[148:151], v[116:119]
	v_mfma_f32_16x16x32_bf16 v[112:115], v[188:191], v[148:151], v[112:115]
	v_mfma_f32_16x16x32_bf16 v[100:103], v[180:183], v[156:159], v[100:103]
	v_mfma_f32_16x16x32_bf16 v[96:99], v[188:191], v[156:159], v[96:99]
	v_mfma_f32_16x16x32_bf16 v[84:87], v[180:183], v[164:167], v[84:87]
	v_mfma_f32_16x16x32_bf16 v[80:83], v[188:191], v[164:167], v[80:83]
	v_mfma_f32_16x16x32_bf16 v[68:71], v[180:183], v[172:175], v[68:71]
	v_mfma_f32_16x16x32_bf16 v[64:67], v[188:191], v[172:175], v[64:67]
	s_setprio 0
	s_mov_b32 m0, s47
	s_mov_b64 s[0:1], 0x80
	v_lshl_add_u64 v[192:193], v[196:197], 0, s[0:1]
	s_barrier
	ds_read_b128 v[144:147], v238 offset:49152
	ds_read_b128 v[148:151], v238 offset:50176
	ds_read_b128 v[152:155], v238 offset:51200
	ds_read_b128 v[156:159], v238 offset:52224
	ds_read_b128 v[160:163], v238 offset:53248
	ds_read_b128 v[164:167], v238 offset:54272
	ds_read_b128 v[168:171], v238 offset:55296
	ds_read_b128 v[172:175], v238 offset:56320
	global_load_lds_dwordx4 v[192:193], off
	v_lshl_add_u64 v[192:193], v[198:199], 0, s[0:1]
	s_mov_b32 m0, s48
	s_nop 0
	global_load_lds_dwordx4 v[192:193], off
	s_barrier
	s_waitcnt lgkmcnt(0)
	s_setprio 1
	s_waitcnt lgkmcnt(0)
	v_mfma_f32_16x16x32_bf16 v[60:63], v[128:131], v[144:147], v[60:63]
	v_mfma_f32_16x16x32_bf16 v[56:59], v[136:139], v[144:147], v[56:59]
	v_mfma_f32_16x16x32_bf16 v[44:47], v[128:131], v[152:155], v[44:47]
	v_mfma_f32_16x16x32_bf16 v[40:43], v[136:139], v[152:155], v[40:43]
	v_mfma_f32_16x16x32_bf16 v[28:31], v[128:131], v[160:163], v[28:31]
	v_mfma_f32_16x16x32_bf16 v[24:27], v[136:139], v[160:163], v[24:27]
	v_mfma_f32_16x16x32_bf16 v[12:15], v[128:131], v[168:171], v[12:15]
	v_mfma_f32_16x16x32_bf16 v[8:11], v[136:139], v[168:171], v[8:11]
	v_mfma_f32_16x16x32_bf16 v[60:63], v[132:135], v[148:151], v[60:63]
	v_mfma_f32_16x16x32_bf16 v[56:59], v[140:143], v[148:151], v[56:59]
	v_mfma_f32_16x16x32_bf16 v[44:47], v[132:135], v[156:159], v[44:47]
	v_mfma_f32_16x16x32_bf16 v[40:43], v[140:143], v[156:159], v[40:43]
	v_mfma_f32_16x16x32_bf16 v[28:31], v[132:135], v[164:167], v[28:31]
	v_mfma_f32_16x16x32_bf16 v[24:27], v[140:143], v[164:167], v[24:27]
	v_mfma_f32_16x16x32_bf16 v[12:15], v[132:135], v[172:175], v[12:15]
	v_mfma_f32_16x16x32_bf16 v[8:11], v[140:143], v[172:175], v[8:11]
	s_setprio 0
	s_barrier
	s_add_u32 s24, s28, 0x60080
	s_addc_u32 s25, s29, 0
	s_add_i32 s28, s30, s37
	s_mov_b32 m0, s28
	s_nop 0
	global_load_lds_dwordx4 v204, s[24:25]
	s_add_i32 m0, s28, 0x2000
	s_nop 0
	global_load_lds_dwordx4 v208, s[24:25]
	s_waitcnt vmcnt(10)
	s_barrier
	s_setprio 1
	v_mfma_f32_16x16x32_bf16 v[52:55], v[176:179], v[144:147], v[52:55]
	v_mfma_f32_16x16x32_bf16 v[48:51], v[184:187], v[144:147], v[48:51]
	v_mfma_f32_16x16x32_bf16 v[36:39], v[176:179], v[152:155], v[36:39]
	v_mfma_f32_16x16x32_bf16 v[32:35], v[184:187], v[152:155], v[32:35]
	v_mfma_f32_16x16x32_bf16 v[20:23], v[176:179], v[160:163], v[20:23]
	v_mfma_f32_16x16x32_bf16 v[16:19], v[184:187], v[160:163], v[16:19]
	v_mfma_f32_16x16x32_bf16 v[4:7], v[176:179], v[168:171], v[4:7]
	v_mfma_f32_16x16x32_bf16 v[0:3], v[184:187], v[168:171], v[0:3]
	v_mfma_f32_16x16x32_bf16 v[52:55], v[180:183], v[148:151], v[52:55]
	v_mfma_f32_16x16x32_bf16 v[48:51], v[188:191], v[148:151], v[48:51]
	v_mfma_f32_16x16x32_bf16 v[36:39], v[180:183], v[156:159], v[36:39]
	v_mfma_f32_16x16x32_bf16 v[32:35], v[188:191], v[156:159], v[32:35]
	v_mfma_f32_16x16x32_bf16 v[20:23], v[180:183], v[164:167], v[20:23]
	v_mfma_f32_16x16x32_bf16 v[16:19], v[188:191], v[164:167], v[16:19]
	v_mfma_f32_16x16x32_bf16 v[4:7], v[180:183], v[172:175], v[4:7]
	v_mfma_f32_16x16x32_bf16 v[0:3], v[188:191], v[172:175], v[0:3]
	s_setprio 0
	s_add_i32 s58, s58, 2
	s_add_u32 s56, s56, 0x100
	s_addc_u32 s57, s57, 0
	s_cmp_gt_u32 s58, 21
	s_mov_b64 s[24:25], s[26:27]
	s_barrier
; __device__ __forceinline__ unsigned cvt_pk_bf16(float lo, float hi) { unsigned r; asm volatile("v_cvt_pk_bf16_f32 %0, %1, %2" : "=v"(r) : "v"(lo), "v"(hi)); return r; }
; __device__ __forceinline__ float bf_lo(unsigned u) { return __uint_as_float(u << 16); }
; __device__ __forceinline__ float bf_hi(unsigned u) { return __uint_as_float(u & 0xffff0000u); }
;     __device__ __forceinline__ void operator()(const AccT& acc, const Unit& u, int wr, int wc, int fr, int fq) const {
;         asm volatile("" : "+v"(fr), "+v"(fq));
;         const int rowt = u.pm * 256; const int b = rowt >> 11;
;         const bf16_t* res = res_b + (size_t)rowt * DM; bf16_t* out = hb + (size_t)rowt * DM;
;         const int col0 = u.pn * 256 + wc * 32 + 8 * fq;
;         f32x4 gv[2][2];
; #pragma unroll
;         for (int bj = 0; bj < 2; ++bj)
; #pragma unroll
;             for (int n = 0; n < 2; ++n) gv[bj][n] = *(const f32x4*)(gate + (size_t)b * NMOD + col0 + bj * 128 + n * 4) * gs;
;         u32x4 r[2][4][2];
; #pragma unroll
;         for (int ai = 0; ai < 2; ++ai)
; #pragma unroll
;             for (int m = 0; m < 4; ++m)
; #pragma unroll
;                 for (int bj = 0; bj < 2; ++bj) r[ai][m][bj] = *(const u32x4*)(res + (size_t)(wr * 64 + fr + ai * 128 + m * 16) * DM + col0 + bj * 128);
; #pragma unroll
;         for (int ai = 0; ai < 2; ++ai)
; #pragma unroll
;             for (int m = 0; m < 4; ++m)
; #pragma unroll
;                 for (int bj = 0; bj < 2; ++bj) {
;                     const u32x4 q = r[ai][m][bj];
;                     const f32x4 r0 = {bf_lo(q.x), bf_hi(q.x), bf_lo(q.y), bf_hi(q.y)}, r1 = {bf_lo(q.z), bf_hi(q.z), bf_lo(q.w), bf_hi(q.w)};
;                     const f32x4 h0 = r0 + gv[bj][0] * acc[ai][bj][m][0], h1 = r1 + gv[bj][1] * acc[ai][bj][m][1];
;                     u32x4 w; w.x = cvt_pk_bf16(h0[0], h0[1]); w.y = cvt_pk_bf16(h0[2], h0[3]); w.z = cvt_pk_bf16(h1[0], h1[1]); w.w = cvt_pk_bf16(h1[2], h1[3]);
;                     *(u32x4*)(out + (size_t)(wr * 64 + fr + ai * 128 + m * 16) * DM + col0 + bj * 128) = w;
;                 }
	s_cbranch_scc0 .LBB0_902
	s_lshl_b32 s27, s55, 8
	v_mov_b32_e32 v146, v235
	v_mov_b32_e32 v128, v234
	s_lshl_b32 s24, s54, 8
	s_ashr_i32 s26, s54, 3
	s_or_b32 s27, s27, s46
	s_ashr_i32 s25, s24, 31
	v_lshl_add_u32 v144, v128, 3, s27
	s_mul_hi_i32 s27, s26, 0x9000
	s_mul_i32 s26, s26, 0x9000
	s_add_u32 s26, s43, s26
	s_addc_u32 s27, s44, s27
	v_ashrrev_i32_e32 v145, 31, v144
	s_lshl_b64 s[24:25], s[24:25], 11
	v_lshl_add_u64 v[132:133], v[144:145], 2, s[26:27]
	s_add_u32 s26, s62, s24
	v_add_u32_e32 v146, s45, v146
	s_addc_u32 s27, s63, s25
	v_lshlrev_b64 v[222:223], 1, v[144:145]
	v_ashrrev_i32_e32 v147, 31, v146
	v_lshl_add_u64 v[144:145], s[26:27], 0, v[222:223]
	v_lshlrev_b64 v[248:249], 11, v[146:147]
	v_lshl_add_u64 v[146:147], v[144:145], 0, v[248:249]
	global_load_dwordx4 v[136:139], v[132:133], off offset:16
	global_load_dwordx4 v[140:143], v[132:133], off
	global_load_dwordx4 v[128:131], v[132:133], off offset:528
	s_nop 0
	global_load_dwordx4 v[132:135], v[132:133], off offset:512
	s_nop 0
	global_load_dwordx4 v[240:243], v[146:147], off
	global_load_dwordx4 v[244:247], v[146:147], off offset:256
	v_lshl_add_u64 v[232:233], v[248:249], 0, s[10:11]
	v_lshl_add_u64 v[146:147], v[144:145], 0, v[232:233]
	global_load_dwordx4 v[196:199], v[146:147], off
	global_load_dwordx4 v[192:195], v[146:147], off offset:256
	v_lshl_add_u64 v[230:231], v[248:249], 0, s[12:13]
	v_lshl_add_u64 v[146:147], v[144:145], 0, v[230:231]
	global_load_dwordx4 v[188:191], v[146:147], off
	global_load_dwordx4 v[184:187], v[146:147], off offset:256
	v_lshl_add_u64 v[228:229], v[248:249], 0, s[14:15]
	v_lshl_add_u64 v[146:147], v[144:145], 0, v[228:229]
	global_load_dwordx4 v[180:183], v[146:147], off
	global_load_dwordx4 v[176:179], v[146:147], off offset:256
	v_lshl_add_u64 v[226:227], v[248:249], 0, s[16:17]
	v_lshl_add_u64 v[146:147], v[144:145], 0, v[226:227]
	global_load_dwordx4 v[172:175], v[146:147], off
	global_load_dwordx4 v[168:171], v[146:147], off offset:256
	v_lshl_add_u64 v[224:225], v[248:249], 0, s[18:19]
	v_lshl_add_u64 v[146:147], v[144:145], 0, v[224:225]
	global_load_dwordx4 v[164:167], v[146:147], off
	global_load_dwordx4 v[160:163], v[146:147], off offset:256
	v_lshl_add_u64 v[220:221], v[248:249], 0, s[20:21]
	v_lshl_add_u64 v[146:147], v[144:145], 0, v[220:221]
	global_load_dwordx4 v[156:159], v[146:147], off
	global_load_dwordx4 v[152:155], v[146:147], off offset:256
	v_lshl_add_u64 v[218:219], v[248:249], 0, s[22:23]
	v_lshl_add_u64 v[144:145], v[144:145], 0, v[218:219]
	global_load_dwordx4 v[148:151], v[144:145], off
	s_nop 0
	global_load_dwordx4 v[144:147], v[144:145], off offset:256
	s_add_u32 s24, s80, s24
	s_addc_u32 s25, s81, s25
	v_lshl_add_u64 v[222:223], s[24:25], 0, v[222:223]
	v_lshl_add_u64 v[248:249], v[222:223], 0, v[248:249]
	s_and_b64 vcc, exec, s[2:3]
	s_mov_b32 s55, s52
	s_mov_b32 s54, s53
	s_mov_b64 s[26:27], s[6:7]
	s_mov_b64 s[24:25], s[4:5]
	s_waitcnt vmcnt(0)
	v_lshlrev_b32_e32 v250, 16, v240
	v_and_b32_e32 v251, 0xffff0000, v240
	v_lshlrev_b32_e32 v240, 16, v241
	v_and_b32_e32 v241, 0xffff0000, v241
	v_lshlrev_b32_e32 v252, 16, v242
	v_and_b32_e32 v253, 0xffff0000, v242
	v_lshlrev_b32_e32 v242, 16, v243
	v_and_b32_e32 v243, 0xffff0000, v243
	v_pk_fma_f32 v[126:127], v[126:127], v[142:143], v[240:241]
	v_pk_fma_f32 v[124:125], v[124:125], v[140:141], v[250:251]
	v_pk_fma_f32 v[240:241], v[122:123], v[138:139], v[242:243]
	v_pk_fma_f32 v[122:123], v[120:121], v[136:137], v[252:253]
	v_cvt_pk_bf16_f32 v120, v124, v125
	v_cvt_pk_bf16_f32 v121, v126, v127
	v_lshlrev_b32_e32 v124, 16, v246
	v_cvt_pk_bf16_f32 v122, v122, v123
	v_cvt_pk_bf16_f32 v123, v240, v241
	global_store_dwordx4 v[248:249], v[120:123], off
	v_and_b32_e32 v125, 0xffff0000, v246
	v_lshlrev_b32_e32 v126, 16, v247
	v_lshlrev_b32_e32 v120, 16, v244
	v_and_b32_e32 v121, 0xffff0000, v244
	v_and_b32_e32 v127, 0xffff0000, v247
	v_lshlrev_b32_e32 v122, 16, v245
	v_and_b32_e32 v123, 0xffff0000, v245
	v_pk_fma_f32 v[116:117], v[116:117], v[132:133], v[120:121]
	v_pk_fma_f32 v[120:121], v[114:115], v[130:131], v[126:127]
	v_pk_fma_f32 v[114:115], v[112:113], v[128:129], v[124:125]
	v_pk_fma_f32 v[118:119], v[118:119], v[134:135], v[122:123]
	v_cvt_pk_bf16_f32 v112, v116, v117
	v_lshlrev_b32_e32 v116, 16, v197
	v_cvt_pk_bf16_f32 v113, v118, v119
	v_cvt_pk_bf16_f32 v114, v114, v115
	v_cvt_pk_bf16_f32 v115, v120, v121
	global_store_dwordx4 v[248:249], v[112:115], off offset:256
	v_and_b32_e32 v117, 0xffff0000, v197
	v_lshlrev_b32_e32 v118, 16, v198
	v_lshlrev_b32_e32 v114, 16, v196
	v_and_b32_e32 v115, 0xffff0000, v196
	v_and_b32_e32 v119, 0xffff0000, v198
	v_lshlrev_b32_e32 v120, 16, v199
	v_and_b32_e32 v121, 0xffff0000, v199
	v_lshl_add_u64 v[112:113], v[222:223], 0, v[232:233]
	v_pk_fma_f32 v[110:111], v[110:111], v[142:143], v[116:117]
	v_pk_fma_f32 v[108:109], v[108:109], v[140:141], v[114:115]
	v_pk_fma_f32 v[114:115], v[106:107], v[138:139], v[120:121]
	v_pk_fma_f32 v[106:107], v[104:105], v[136:137], v[118:119]
	v_cvt_pk_bf16_f32 v104, v108, v109
	v_cvt_pk_bf16_f32 v105, v110, v111
	v_lshlrev_b32_e32 v108, 16, v194
	v_cvt_pk_bf16_f32 v106, v106, v107
	v_cvt_pk_bf16_f32 v107, v114, v115
	global_store_dwordx4 v[112:113], v[104:107], off
	v_and_b32_e32 v109, 0xffff0000, v194
	v_lshlrev_b32_e32 v110, 16, v195
	v_lshlrev_b32_e32 v104, 16, v192
	v_and_b32_e32 v105, 0xffff0000, v192
	v_and_b32_e32 v111, 0xffff0000, v195
	v_lshlrev_b32_e32 v106, 16, v193
	v_and_b32_e32 v107, 0xffff0000, v193
	v_pk_fma_f32 v[100:101], v[100:101], v[132:133], v[104:105]
	v_pk_fma_f32 v[104:105], v[98:99], v[130:131], v[110:111]
	v_pk_fma_f32 v[98:99], v[96:97], v[128:129], v[108:109]
; __device__ __forceinline__ unsigned cvt_pk_bf16(float lo, float hi) { unsigned r; asm volatile("v_cvt_pk_bf16_f32 %0, %1, %2" : "=v"(r) : "v"(lo), "v"(hi)); return r; }
; __device__ __forceinline__ float bf_lo(unsigned u) { return __uint_as_float(u << 16); }
; __device__ __forceinline__ float bf_hi(unsigned u) { return __uint_as_float(u & 0xffff0000u); }
;     __device__ __forceinline__ void operator()(const AccT& acc, const Unit& u, int wr, int wc, int fr, int fq) const {
;     ...
;         for (int ai = 0; ai < 2; ++ai)
; #pragma unroll
;             for (int m = 0; m < 4; ++m)
; #pragma unroll
;                 for (int bj = 0; bj < 2; ++bj) {
;                     const u32x4 q = r[ai][m][bj];
;                     const f32x4 r0 = {bf_lo(q.x), bf_hi(q.x), bf_lo(q.y), bf_hi(q.y)}, r1 = {bf_lo(q.z), bf_hi(q.z), bf_lo(q.w), bf_hi(q.w)};
;                     const f32x4 h0 = r0 + gv[bj][0] * acc[ai][bj][m][0], h1 = r1 + gv[bj][1] * acc[ai][bj][m][1];
;                     u32x4 w; w.x = cvt_pk_bf16(h0[0], h0[1]); w.y = cvt_pk_bf16(h0[2], h0[3]); w.z = cvt_pk_bf16(h1[0], h1[1]); w.w = cvt_pk_bf16(h1[2], h1[3]);
;                     *(u32x4*)(out + (size_t)(wr * 64 + fr + ai * 128 + m * 16) * DM + col0 + bj * 128) = w;
;                 }
	v_pk_fma_f32 v[102:103], v[102:103], v[134:135], v[106:107]
	v_cvt_pk_bf16_f32 v96, v100, v101
	v_lshlrev_b32_e32 v100, 16, v189
	v_cvt_pk_bf16_f32 v97, v102, v103
	v_cvt_pk_bf16_f32 v98, v98, v99
	v_cvt_pk_bf16_f32 v99, v104, v105
	global_store_dwordx4 v[112:113], v[96:99], off offset:256
	v_and_b32_e32 v101, 0xffff0000, v189
	v_lshlrev_b32_e32 v102, 16, v190
	v_lshlrev_b32_e32 v98, 16, v188
	v_and_b32_e32 v99, 0xffff0000, v188
	v_and_b32_e32 v103, 0xffff0000, v190
	v_lshlrev_b32_e32 v104, 16, v191
	v_and_b32_e32 v105, 0xffff0000, v191
	v_lshl_add_u64 v[96:97], v[222:223], 0, v[230:231]
	v_pk_fma_f32 v[94:95], v[94:95], v[142:143], v[100:101]
	v_pk_fma_f32 v[92:93], v[92:93], v[140:141], v[98:99]
	v_pk_fma_f32 v[98:99], v[90:91], v[138:139], v[104:105]
	v_pk_fma_f32 v[90:91], v[88:89], v[136:137], v[102:103]
	v_cvt_pk_bf16_f32 v88, v92, v93
	v_cvt_pk_bf16_f32 v89, v94, v95
	v_lshlrev_b32_e32 v92, 16, v186
	v_cvt_pk_bf16_f32 v90, v90, v91
	v_cvt_pk_bf16_f32 v91, v98, v99
	global_store_dwordx4 v[96:97], v[88:91], off
	v_and_b32_e32 v93, 0xffff0000, v186
	v_lshlrev_b32_e32 v94, 16, v187
	v_lshlrev_b32_e32 v88, 16, v184
	v_and_b32_e32 v89, 0xffff0000, v184
	v_and_b32_e32 v95, 0xffff0000, v187
	v_lshlrev_b32_e32 v90, 16, v185
	v_and_b32_e32 v91, 0xffff0000, v185
	v_pk_fma_f32 v[84:85], v[84:85], v[132:133], v[88:89]
	v_pk_fma_f32 v[88:89], v[82:83], v[130:131], v[94:95]
	v_pk_fma_f32 v[82:83], v[80:81], v[128:129], v[92:93]
	v_pk_fma_f32 v[86:87], v[86:87], v[134:135], v[90:91]
	v_cvt_pk_bf16_f32 v80, v84, v85
	v_lshlrev_b32_e32 v84, 16, v181
	v_cvt_pk_bf16_f32 v81, v86, v87
	v_cvt_pk_bf16_f32 v82, v82, v83
	v_cvt_pk_bf16_f32 v83, v88, v89
	global_store_dwordx4 v[96:97], v[80:83], off offset:256
	v_and_b32_e32 v85, 0xffff0000, v181
	v_lshlrev_b32_e32 v86, 16, v182
	v_lshlrev_b32_e32 v82, 16, v180
	v_and_b32_e32 v83, 0xffff0000, v180
	v_and_b32_e32 v87, 0xffff0000, v182
	v_lshlrev_b32_e32 v88, 16, v183
	v_and_b32_e32 v89, 0xffff0000, v183
	v_lshl_add_u64 v[80:81], v[222:223], 0, v[228:229]
	v_pk_fma_f32 v[78:79], v[78:79], v[142:143], v[84:85]
	v_pk_fma_f32 v[76:77], v[76:77], v[140:141], v[82:83]
	v_pk_fma_f32 v[82:83], v[74:75], v[138:139], v[88:89]
	v_pk_fma_f32 v[74:75], v[72:73], v[136:137], v[86:87]
	v_cvt_pk_bf16_f32 v72, v76, v77
	v_cvt_pk_bf16_f32 v73, v78, v79
	v_lshlrev_b32_e32 v76, 16, v178
	v_cvt_pk_bf16_f32 v74, v74, v75
	v_cvt_pk_bf16_f32 v75, v82, v83
	global_store_dwordx4 v[80:81], v[72:75], off
	v_and_b32_e32 v77, 0xffff0000, v178
	v_lshlrev_b32_e32 v78, 16, v179
	v_lshlrev_b32_e32 v72, 16, v176
	v_and_b32_e32 v73, 0xffff0000, v176
	v_and_b32_e32 v79, 0xffff0000, v179
	v_lshlrev_b32_e32 v74, 16, v177
	v_and_b32_e32 v75, 0xffff0000, v177
	v_pk_fma_f32 v[68:69], v[68:69], v[132:133], v[72:73]
	v_pk_fma_f32 v[72:73], v[66:67], v[130:131], v[78:79]
	v_pk_fma_f32 v[66:67], v[64:65], v[128:129], v[76:77]
	v_pk_fma_f32 v[70:71], v[70:71], v[134:135], v[74:75]
	v_cvt_pk_bf16_f32 v64, v68, v69
	v_lshlrev_b32_e32 v68, 16, v173
	v_cvt_pk_bf16_f32 v65, v70, v71
	v_cvt_pk_bf16_f32 v66, v66, v67
	v_cvt_pk_bf16_f32 v67, v72, v73
	global_store_dwordx4 v[80:81], v[64:67], off offset:256
	v_and_b32_e32 v69, 0xffff0000, v173
	v_lshlrev_b32_e32 v70, 16, v174
	v_lshlrev_b32_e32 v66, 16, v172
	v_and_b32_e32 v67, 0xffff0000, v172
	v_and_b32_e32 v71, 0xffff0000, v174
	v_lshlrev_b32_e32 v72, 16, v175
	v_and_b32_e32 v73, 0xffff0000, v175
	v_lshl_add_u64 v[64:65], v[222:223], 0, v[226:227]
	v_pk_fma_f32 v[62:63], v[62:63], v[142:143], v[68:69]
	v_pk_fma_f32 v[60:61], v[60:61], v[140:141], v[66:67]
	v_pk_fma_f32 v[66:67], v[58:59], v[138:139], v[72:73]
	v_pk_fma_f32 v[58:59], v[56:57], v[136:137], v[70:71]
	v_cvt_pk_bf16_f32 v56, v60, v61
	v_cvt_pk_bf16_f32 v57, v62, v63
	v_lshlrev_b32_e32 v60, 16, v170
	v_cvt_pk_bf16_f32 v58, v58, v59
	v_cvt_pk_bf16_f32 v59, v66, v67
	global_store_dwordx4 v[64:65], v[56:59], off
	v_and_b32_e32 v61, 0xffff0000, v170
	v_lshlrev_b32_e32 v62, 16, v171
	v_lshlrev_b32_e32 v56, 16, v168
	v_and_b32_e32 v57, 0xffff0000, v168
	v_and_b32_e32 v63, 0xffff0000, v171
	v_lshlrev_b32_e32 v58, 16, v169
	v_and_b32_e32 v59, 0xffff0000, v169
	v_pk_fma_f32 v[52:53], v[52:53], v[132:133], v[56:57]
	v_pk_fma_f32 v[56:57], v[50:51], v[130:131], v[62:63]
	v_pk_fma_f32 v[50:51], v[48:49], v[128:129], v[60:61]
	v_pk_fma_f32 v[54:55], v[54:55], v[134:135], v[58:59]
	v_cvt_pk_bf16_f32 v48, v52, v53
	v_lshlrev_b32_e32 v52, 16, v165
	v_cvt_pk_bf16_f32 v49, v54, v55
; __device__ __forceinline__ unsigned cvt_pk_bf16(float lo, float hi) { unsigned r; asm volatile("v_cvt_pk_bf16_f32 %0, %1, %2" : "=v"(r) : "v"(lo), "v"(hi)); return r; }
; __device__ __forceinline__ float bf_lo(unsigned u) { return __uint_as_float(u << 16); }
; __device__ __forceinline__ float bf_hi(unsigned u) { return __uint_as_float(u & 0xffff0000u); }
; #define PG8_WAIT_V(n) asm volatile("s_waitcnt vmcnt(" #n ")" ::: "memory")
; #define PG8_BAR __builtin_amdgcn_s_barrier()
; template <class Epi, class Sched>
; __device__ __forceinline__ void gemm_phase(LAS unsigned char* lds, const Gemm g, const Sched& S, const Epi& E) {
;     ...
;         if (!has_next) break;
; #pragma unroll
;         for (int a = 0; a < 2; ++a)
; #pragma unroll
;             for (int b = 0; b < 2; ++b)
; #pragma unroll
;                 for (int m = 0; m < 4; ++m)
; #pragma unroll
;                     for (int n = 0; n < 2; ++n) acc[a][b][m][n] = (f32x4){0.f, 0.f, 0.f, 0.f};
;         cur = nxt; cA = nA; cB = nB; ++ui;
;     }
;     PG8_WAIT_V(0);
;     if (wr == 0) PG8_BAR;
;     PG8_BAR;
;     __device__ __forceinline__ void operator()(const AccT& acc, const Unit& u, int wr, int wc, int fr, int fq) const {
;     ...
;         for (int ai = 0; ai < 2; ++ai)
; #pragma unroll
;             for (int m = 0; m < 4; ++m)
; #pragma unroll
;                 for (int bj = 0; bj < 2; ++bj) {
;                     const u32x4 q = r[ai][m][bj];
;                     const f32x4 r0 = {bf_lo(q.x), bf_hi(q.x), bf_lo(q.y), bf_hi(q.y)}, r1 = {bf_lo(q.z), bf_hi(q.z), bf_lo(q.w), bf_hi(q.w)};
;                     const f32x4 h0 = r0 + gv[bj][0] * acc[ai][bj][m][0], h1 = r1 + gv[bj][1] * acc[ai][bj][m][1];
;                     u32x4 w; w.x = cvt_pk_bf16(h0[0], h0[1]); w.y = cvt_pk_bf16(h0[2], h0[3]); w.z = cvt_pk_bf16(h1[0], h1[1]); w.w = cvt_pk_bf16(h1[2], h1[3]);
;                     *(u32x4*)(out + (size_t)(wr * 64 + fr + ai * 128 + m * 16) * DM + col0 + bj * 128) = w;
;                 }
	v_cvt_pk_bf16_f32 v50, v50, v51
	v_cvt_pk_bf16_f32 v51, v56, v57
	global_store_dwordx4 v[64:65], v[48:51], off offset:256
	v_and_b32_e32 v53, 0xffff0000, v165
	v_lshlrev_b32_e32 v54, 16, v166
	v_lshlrev_b32_e32 v50, 16, v164
	v_and_b32_e32 v51, 0xffff0000, v164
	v_and_b32_e32 v55, 0xffff0000, v166
	v_lshlrev_b32_e32 v56, 16, v167
	v_and_b32_e32 v57, 0xffff0000, v167
	v_lshl_add_u64 v[48:49], v[222:223], 0, v[224:225]
	v_pk_fma_f32 v[46:47], v[46:47], v[142:143], v[52:53]
	v_pk_fma_f32 v[44:45], v[44:45], v[140:141], v[50:51]
	v_pk_fma_f32 v[50:51], v[42:43], v[138:139], v[56:57]
	v_pk_fma_f32 v[42:43], v[40:41], v[136:137], v[54:55]
	v_cvt_pk_bf16_f32 v40, v44, v45
	v_cvt_pk_bf16_f32 v41, v46, v47
	v_lshlrev_b32_e32 v44, 16, v162
	v_cvt_pk_bf16_f32 v42, v42, v43
	v_cvt_pk_bf16_f32 v43, v50, v51
	global_store_dwordx4 v[48:49], v[40:43], off
	v_and_b32_e32 v45, 0xffff0000, v162
	v_lshlrev_b32_e32 v46, 16, v163
	v_lshlrev_b32_e32 v40, 16, v160
	v_and_b32_e32 v41, 0xffff0000, v160
	v_and_b32_e32 v47, 0xffff0000, v163
	v_lshlrev_b32_e32 v42, 16, v161
	v_and_b32_e32 v43, 0xffff0000, v161
	v_pk_fma_f32 v[36:37], v[36:37], v[132:133], v[40:41]
	v_pk_fma_f32 v[40:41], v[34:35], v[130:131], v[46:47]
	v_pk_fma_f32 v[34:35], v[32:33], v[128:129], v[44:45]
	v_pk_fma_f32 v[38:39], v[38:39], v[134:135], v[42:43]
	v_cvt_pk_bf16_f32 v32, v36, v37
	v_lshlrev_b32_e32 v36, 16, v157
	v_cvt_pk_bf16_f32 v33, v38, v39
	v_cvt_pk_bf16_f32 v34, v34, v35
	v_cvt_pk_bf16_f32 v35, v40, v41
	global_store_dwordx4 v[48:49], v[32:35], off offset:256
	v_and_b32_e32 v37, 0xffff0000, v157
	v_lshlrev_b32_e32 v38, 16, v158
	v_lshlrev_b32_e32 v34, 16, v156
	v_and_b32_e32 v35, 0xffff0000, v156
	v_and_b32_e32 v39, 0xffff0000, v158
	v_lshlrev_b32_e32 v40, 16, v159
	v_and_b32_e32 v41, 0xffff0000, v159
	v_lshl_add_u64 v[32:33], v[222:223], 0, v[220:221]
	v_pk_fma_f32 v[30:31], v[30:31], v[142:143], v[36:37]
	v_pk_fma_f32 v[28:29], v[28:29], v[140:141], v[34:35]
	v_pk_fma_f32 v[34:35], v[26:27], v[138:139], v[40:41]
	v_pk_fma_f32 v[26:27], v[24:25], v[136:137], v[38:39]
	v_cvt_pk_bf16_f32 v24, v28, v29
	v_cvt_pk_bf16_f32 v25, v30, v31
	v_lshlrev_b32_e32 v28, 16, v154
	v_cvt_pk_bf16_f32 v26, v26, v27
	v_cvt_pk_bf16_f32 v27, v34, v35
	global_store_dwordx4 v[32:33], v[24:27], off
	v_and_b32_e32 v29, 0xffff0000, v154
	v_lshlrev_b32_e32 v30, 16, v155
	v_lshlrev_b32_e32 v24, 16, v152
	v_and_b32_e32 v25, 0xffff0000, v152
	v_and_b32_e32 v31, 0xffff0000, v155
	v_lshlrev_b32_e32 v26, 16, v153
	v_and_b32_e32 v27, 0xffff0000, v153
	v_pk_fma_f32 v[20:21], v[20:21], v[132:133], v[24:25]
	v_pk_fma_f32 v[24:25], v[18:19], v[130:131], v[30:31]
	v_pk_fma_f32 v[18:19], v[16:17], v[128:129], v[28:29]
	v_pk_fma_f32 v[22:23], v[22:23], v[134:135], v[26:27]
	v_cvt_pk_bf16_f32 v16, v20, v21
	v_lshlrev_b32_e32 v20, 16, v149
	v_cvt_pk_bf16_f32 v17, v22, v23
	v_cvt_pk_bf16_f32 v18, v18, v19
	v_cvt_pk_bf16_f32 v19, v24, v25
	global_store_dwordx4 v[32:33], v[16:19], off offset:256
	v_and_b32_e32 v21, 0xffff0000, v149
	v_lshlrev_b32_e32 v22, 16, v150
	v_lshlrev_b32_e32 v18, 16, v148
	v_and_b32_e32 v19, 0xffff0000, v148
	v_and_b32_e32 v23, 0xffff0000, v150
	v_lshlrev_b32_e32 v24, 16, v151
	v_and_b32_e32 v25, 0xffff0000, v151
	v_lshl_add_u64 v[16:17], v[222:223], 0, v[218:219]
	v_pk_fma_f32 v[14:15], v[14:15], v[142:143], v[20:21]
	v_pk_fma_f32 v[12:13], v[12:13], v[140:141], v[18:19]
	v_pk_fma_f32 v[18:19], v[10:11], v[138:139], v[24:25]
	v_pk_fma_f32 v[10:11], v[8:9], v[136:137], v[22:23]
	v_cvt_pk_bf16_f32 v8, v12, v13
	v_cvt_pk_bf16_f32 v9, v14, v15
	v_lshlrev_b32_e32 v12, 16, v146
	v_cvt_pk_bf16_f32 v10, v10, v11
	v_cvt_pk_bf16_f32 v11, v18, v19
	global_store_dwordx4 v[16:17], v[8:11], off
	v_and_b32_e32 v13, 0xffff0000, v146
	v_lshlrev_b32_e32 v14, 16, v147
	v_lshlrev_b32_e32 v8, 16, v144
	v_and_b32_e32 v9, 0xffff0000, v144
	v_and_b32_e32 v15, 0xffff0000, v147
	v_lshlrev_b32_e32 v10, 16, v145
	v_and_b32_e32 v11, 0xffff0000, v145
	v_pk_fma_f32 v[4:5], v[4:5], v[132:133], v[8:9]
	v_pk_fma_f32 v[8:9], v[2:3], v[130:131], v[14:15]
	v_pk_fma_f32 v[2:3], v[0:1], v[128:129], v[12:13]
	v_pk_fma_f32 v[6:7], v[6:7], v[134:135], v[10:11]
	v_cvt_pk_bf16_f32 v0, v4, v5
	s_nop 0
	v_cvt_pk_bf16_f32 v1, v6, v7
	v_cvt_pk_bf16_f32 v2, v2, v3
	v_cvt_pk_bf16_f32 v3, v8, v9
	global_store_dwordx4 v[16:17], v[0:3], off offset:256
	s_cbranch_vccz .LBB0_891
	s_waitcnt vmcnt(0)
	s_cmpk_gt_u32 s33, 0xff
	s_cbranch_scc1 .LBB0_906
	s_barrier

; #define PG8_STAGE(bufoff, gbase, voff) do { _Pragma("unroll") for (int _i = 0; _i < 2; ++_i) \
;         __builtin_amdgcn_global_load_lds((const unsigned*)((const char*)(gbase) + (voff)[_i]), (LAS unsigned*)(lds + (bufoff) + ldsw + _i * 8192), 16, 0, 0); } while (0)
; #define PG8_LDA(dst, b, h) do { _Pragma("unroll") for (int m = 0; m < 4; ++m) _Pragma("unroll") for (int k = 0; k < 2; ++k) dst[m][k] = *(const LAS bf16x8*)(lds + PG8_SA(b, h) + aoff + m * 2048 + k * 1024); } while (0)
; #define PG8_LDB(dst, b, h) do { _Pragma("unroll") for (int n = 0; n < 2; ++n) _Pragma("unroll") for (int k = 0; k < 2; ++k) dst[n][k] = *(const LAS bf16x8*)(lds + PG8_SB(b, h) + boff + n * 2048 + k * 1024); } while (0)
; #define PG8_MMA(ai, bj, At, Bt) do { __builtin_amdgcn_s_setprio(1); _Pragma("unroll") for (int m = 0; m < 4; ++m) _Pragma("unroll") for (int n = 0; n < 2; ++n) _Pragma("unroll") for (int k = 0; k < 2; ++k) \
;         acc[ai][bj][m][n] = __builtin_amdgcn_mfma_f32_16x16x32_bf16(Bt[n][k], At[m][k], acc[ai][bj][m][n], 0, 0, 0); __builtin_amdgcn_s_setprio(0); } while (0)
; #define PG8_WAIT_L(n) asm volatile("s_waitcnt lgkmcnt(" #n ")" ::: "memory")
; template <class Epi, class Sched>
; __device__ __forceinline__ void gemm_phase(LAS unsigned char* lds, const Gemm g, const Sched& S, const Epi& E) {
;     ...
;         const bool has_next = S.next(ui + 1, nxt);
;         const char* nA = has_next ? (const char*)g.A + (size_t)nxt.pm * tstep : cA; const char* nB = has_next ? (const char*)g.Bt + (size_t)nxt.pn * tstep : cB;
;         for (int t = 0; t < nt; t += 2) {
;             const bool last = (t == nt - 2);
;             const char* a1 = cA + (size_t)(t + 1) * kstep;
;             const char* a2 = last ? nA : cA + (size_t)(t + 2) * kstep; const char* b2 = last ? nB : cB + (size_t)(t + 2) * kstep;
;             const char* a3 = a2 + kstep; const char* b3 = b2 + kstep;
;             PG8_LDB(B0, 0, 0); PG8_SCHED; PG8_LDA(At, 0, 0); PG8_STAGE(PG8_SA(1, 1), a1 + hstep, voffA);
;             PG8_WAIT_L(8); PG8_BAR; PG8_WAIT_L(0); PG8_MMA(0, 0, At, B0); PG8_BAR; PG8_SCHED;
;             PG8_LDB(B1, 0, 1); PG8_STAGE(PG8_SB(0, 0), b2, voffB);
;             PG8_BAR; PG8_WAIT_L(0); PG8_MMA(0, 1, At, B1); PG8_BAR;
;             PG8_LDA(At, 0, 1); PG8_STAGE(PG8_SA(0, 0), a2, voffA);
;             PG8_BAR; PG8_WAIT_L(0); PG8_MMA(1, 0, At, B0); PG8_BAR; PG8_SCHED;
.LBB0_1020:
	s_ashr_i32 s7, s6, 31
	v_cmp_lt_i64_e32 vcc, s[10:11], v[140:141]
	s_lshl_b64 s[10:11], s[6:7], 19
	s_add_u32 s10, s96, s10
	s_addc_u32 s11, s97, s11
	s_and_b64 s[12:13], vcc, exec
	s_cselect_b32 s7, s11, s17
	s_cselect_b32 s42, s10, s16
	s_ashr_i32 s5, s4, 31
	s_lshl_b64 s[12:13], s[4:5], 19
	s_add_u32 s12, s23, s12
	s_addc_u32 s13, s24, s13
	s_and_b64 s[20:21], vcc, exec
	s_cselect_b32 s5, s13, s19
	s_cselect_b32 s43, s12, s18
	s_add_u32 s16, s16, 0x40080
	s_addc_u32 s17, s17, 0
	s_add_u32 s44, s18, 0x100
	s_addc_u32 s45, s19, 0
	s_mov_b32 s46, -2
	ds_read_b128 v[150:153], v147
	ds_read_b128 v[154:157], v147 offset:1024
	ds_read_b128 v[158:161], v147 offset:2048
	ds_read_b128 v[162:165], v147 offset:3072
	s_add_u32 s18, s16, 0xfffc0080
	s_addc_u32 s19, s17, -1
	s_cmp_eq_u32 s46, 12
	s_cselect_b32 s21, s7, s19
	s_cselect_b32 s20, s42, s18
	s_cselect_b32 s19, s5, s45
	s_cselect_b32 s18, s43, s44
	s_add_i32 m0, s15, 0xc000
	ds_read_b128 v[166:169], v148
	ds_read_b128 v[170:173], v148 offset:1024
	ds_read_b128 v[174:177], v148 offset:2048
	ds_read_b128 v[178:181], v148 offset:3072
	ds_read_b128 v[182:185], v148 offset:4096
	ds_read_b128 v[186:189], v148 offset:5120
	ds_read_b128 v[190:193], v148 offset:6144
	ds_read_b128 v[194:197], v148 offset:7168
	global_load_lds_dwordx4 v136, s[16:17]
	s_add_i32 m0, s15, 0xe000
	s_nop 0
	global_load_lds_dwordx4 v138, s[16:17]
	s_waitcnt lgkmcnt(8)
	s_waitcnt vmcnt(10)
	s_barrier
	s_waitcnt lgkmcnt(0)
	s_setprio 1
	s_waitcnt lgkmcnt(0)
	v_mfma_f32_16x16x32_bf16 v[124:127], v[150:153], v[166:169], 0
	v_mfma_f32_16x16x32_bf16 v[116:119], v[158:161], v[166:169], 0
	v_mfma_f32_16x16x32_bf16 v[108:111], v[150:153], v[174:177], 0
	v_mfma_f32_16x16x32_bf16 v[100:103], v[158:161], v[174:177], 0
	v_mfma_f32_16x16x32_bf16 v[92:95], v[150:153], v[182:185], 0
	v_mfma_f32_16x16x32_bf16 v[84:87], v[158:161], v[182:185], 0
	v_mfma_f32_16x16x32_bf16 v[76:79], v[150:153], v[190:193], 0
	v_mfma_f32_16x16x32_bf16 v[68:71], v[158:161], v[190:193], 0
	v_mfma_f32_16x16x32_bf16 v[124:127], v[154:157], v[170:173], v[124:127]
	v_mfma_f32_16x16x32_bf16 v[116:119], v[162:165], v[170:173], v[116:119]
	v_mfma_f32_16x16x32_bf16 v[108:111], v[154:157], v[178:181], v[108:111]
	v_mfma_f32_16x16x32_bf16 v[100:103], v[162:165], v[178:181], v[100:103]
	v_mfma_f32_16x16x32_bf16 v[92:95], v[154:157], v[186:189], v[92:95]
	v_mfma_f32_16x16x32_bf16 v[84:87], v[162:165], v[186:189], v[84:87]
	v_mfma_f32_16x16x32_bf16 v[76:79], v[154:157], v[194:197], v[76:79]
	v_mfma_f32_16x16x32_bf16 v[68:71], v[162:165], v[194:197], v[68:71]
	s_setprio 0
	s_barrier
	s_add_i32 s47, s38, s25
	s_mov_b32 m0, s47
	ds_read_b128 v[202:205], v149
	ds_read_b128 v[206:209], v149 offset:1024
	ds_read_b128 v[210:213], v149 offset:2048
	ds_read_b128 v[214:217], v149 offset:3072
	global_load_lds_dwordx4 v132, s[18:19]
	s_add_i32 m0, s47, 0x2000
	s_nop 0
	global_load_lds_dwordx4 v128, s[18:19]
	s_waitcnt vmcnt(10)
	s_barrier
	s_waitcnt lgkmcnt(0)
	s_setprio 1
	s_waitcnt lgkmcnt(0)
	v_mfma_f32_16x16x32_bf16 v[120:123], v[202:205], v[166:169], 0
	v_mfma_f32_16x16x32_bf16 v[112:115], v[210:213], v[166:169], 0
	v_mfma_f32_16x16x32_bf16 v[104:107], v[202:205], v[174:177], 0
	v_mfma_f32_16x16x32_bf16 v[96:99], v[210:213], v[174:177], 0
	v_mfma_f32_16x16x32_bf16 v[88:91], v[202:205], v[182:185], 0
	v_mfma_f32_16x16x32_bf16 v[80:83], v[210:213], v[182:185], 0
	v_mfma_f32_16x16x32_bf16 v[72:75], v[202:205], v[190:193], 0
	v_mfma_f32_16x16x32_bf16 v[64:67], v[210:213], v[190:193], 0
	v_mfma_f32_16x16x32_bf16 v[120:123], v[206:209], v[170:173], v[120:123]
	v_mfma_f32_16x16x32_bf16 v[112:115], v[214:217], v[170:173], v[112:115]
	v_mfma_f32_16x16x32_bf16 v[104:107], v[206:209], v[178:181], v[104:107]
	v_mfma_f32_16x16x32_bf16 v[96:99], v[214:217], v[178:181], v[96:99]
	v_mfma_f32_16x16x32_bf16 v[88:91], v[206:209], v[186:189], v[88:91]
	v_mfma_f32_16x16x32_bf16 v[80:83], v[214:217], v[186:189], v[80:83]
	v_mfma_f32_16x16x32_bf16 v[72:75], v[206:209], v[194:197], v[72:75]
	v_mfma_f32_16x16x32_bf16 v[64:67], v[214:217], v[194:197], v[64:67]
	s_setprio 0
	s_mov_b32 m0, s15
	v_lshl_add_u64 v[220:221], s[20:21], 0, v[134:135]
	s_barrier
	ds_read_b128 v[166:169], v148 offset:16384
	ds_read_b128 v[170:173], v148 offset:17408
	ds_read_b128 v[174:177], v148 offset:18432
	ds_read_b128 v[178:181], v148 offset:19456
	ds_read_b128 v[182:185], v148 offset:20480
	ds_read_b128 v[186:189], v148 offset:21504
	ds_read_b128 v[190:193], v148 offset:22528
	ds_read_b128 v[194:197], v148 offset:23552
	global_load_lds_dwordx4 v134, s[20:21]
	v_lshl_add_u64 v[222:223], s[20:21], 0, v[130:131]
	s_mov_b32 m0, s28
	s_nop 0
	global_load_lds_dwordx4 v130, s[20:21]
	s_barrier
	s_waitcnt lgkmcnt(0)
	s_setprio 1
	s_waitcnt lgkmcnt(0)
	v_mfma_f32_16x16x32_bf16 v[60:63], v[150:153], v[166:169], 0
	v_mfma_f32_16x16x32_bf16 v[56:59], v[158:161], v[166:169], 0
	v_mfma_f32_16x16x32_bf16 v[44:47], v[150:153], v[174:177], 0
	v_mfma_f32_16x16x32_bf16 v[40:43], v[158:161], v[174:177], 0
	v_mfma_f32_16x16x32_bf16 v[28:31], v[150:153], v[182:185], 0
	v_mfma_f32_16x16x32_bf16 v[24:27], v[158:161], v[182:185], 0
	v_mfma_f32_16x16x32_bf16 v[12:15], v[150:153], v[190:193], 0
	v_mfma_f32_16x16x32_bf16 v[8:11], v[158:161], v[190:193], 0
	v_mfma_f32_16x16x32_bf16 v[60:63], v[154:157], v[170:173], v[60:63]
	v_mfma_f32_16x16x32_bf16 v[56:59], v[162:165], v[170:173], v[56:59]
	v_mfma_f32_16x16x32_bf16 v[44:47], v[154:157], v[178:181], v[44:47]
	v_mfma_f32_16x16x32_bf16 v[40:43], v[162:165], v[178:181], v[40:43]
	v_mfma_f32_16x16x32_bf16 v[28:31], v[154:157], v[186:189], v[28:31]
	v_mfma_f32_16x16x32_bf16 v[24:27], v[162:165], v[186:189], v[24:27]
	v_mfma_f32_16x16x32_bf16 v[12:15], v[154:157], v[194:197], v[12:15]
	v_mfma_f32_16x16x32_bf16 v[8:11], v[162:165], v[194:197], v[8:11]
	s_setprio 0
	s_barrier
; #define PG8_STAGE(bufoff, gbase, voff) do { _Pragma("unroll") for (int _i = 0; _i < 2; ++_i) \
;         __builtin_amdgcn_global_load_lds((const unsigned*)((const char*)(gbase) + (voff)[_i]), (LAS unsigned*)(lds + (bufoff) + ldsw + _i * 8192), 16, 0, 0); } while (0)
; #define PG8_LDA(dst, b, h) do { _Pragma("unroll") for (int m = 0; m < 4; ++m) _Pragma("unroll") for (int k = 0; k < 2; ++k) dst[m][k] = *(const LAS bf16x8*)(lds + PG8_SA(b, h) + aoff + m * 2048 + k * 1024); } while (0)
; #define PG8_LDB(dst, b, h) do { _Pragma("unroll") for (int n = 0; n < 2; ++n) _Pragma("unroll") for (int k = 0; k < 2; ++k) dst[n][k] = *(const LAS bf16x8*)(lds + PG8_SB(b, h) + boff + n * 2048 + k * 1024); } while (0)
; #define PG8_MMA(ai, bj, At, Bt) do { __builtin_amdgcn_s_setprio(1); _Pragma("unroll") for (int m = 0; m < 4; ++m) _Pragma("unroll") for (int n = 0; n < 2; ++n) _Pragma("unroll") for (int k = 0; k < 2; ++k) \
;         acc[ai][bj][m][n] = __builtin_amdgcn_mfma_f32_16x16x32_bf16(Bt[n][k], At[m][k], acc[ai][bj][m][n], 0, 0, 0); __builtin_amdgcn_s_setprio(0); } while (0)
; #define PG8_WAIT_V(n) asm volatile("s_waitcnt vmcnt(" #n ")" ::: "memory")
; #define PG8_WAIT_L(n) asm volatile("s_waitcnt lgkmcnt(" #n ")" ::: "memory")
; #define PG8_BAR __builtin_amdgcn_s_barrier()
; #define PG8_SCHED __builtin_amdgcn_sched_barrier(0)
; template <class Epi, class Sched>
; __device__ __forceinline__ void gemm_phase(LAS unsigned char* lds, const Gemm g, const Sched& S, const Epi& E) {
;     ...
;             PG8_STAGE(PG8_SB(0, 1), b2 + hstep, voffB);
;             PG8_WAIT_V(6); PG8_BAR; PG8_MMA(1, 1, At, B1); PG8_BAR;
;             PG8_LDB(B0, 1, 0); PG8_SCHED; PG8_LDA(At, 1, 0); PG8_STAGE(PG8_SA(0, 1), a2 + hstep, voffA);
;             PG8_WAIT_L(8); PG8_BAR; PG8_WAIT_L(0); PG8_MMA(0, 0, At, B0); PG8_BAR; PG8_SCHED;
;             PG8_LDB(B1, 1, 1); PG8_STAGE(PG8_SB(1, 0), b3, voffB);
;             PG8_BAR; PG8_WAIT_L(0); PG8_MMA(0, 1, At, B1); PG8_BAR;
;             PG8_LDA(At, 1, 1); PG8_STAGE(PG8_SA(1, 0), a3, voffA);
	s_add_u32 s48, s18, 0x40000
	s_addc_u32 s49, s19, 0
	s_add_i32 s47, s39, s25
	s_mov_b32 m0, s47
	s_nop 0
	global_load_lds_dwordx4 v132, s[48:49]
	s_add_i32 m0, s47, 0x2000
	s_nop 0
	global_load_lds_dwordx4 v128, s[48:49]
	s_add_u32 s20, s20, 0x40000
	s_addc_u32 s21, s21, 0
	s_mov_b32 m0, s29
	s_nop 0
	global_load_lds_dwordx4 v134, s[20:21]
	s_mov_b32 m0, s30
	s_nop 0
	global_load_lds_dwordx4 v130, s[20:21]
	s_waitcnt vmcnt(12)
	s_barrier
	s_setprio 1
	v_mfma_f32_16x16x32_bf16 v[52:55], v[202:205], v[166:169], 0
	v_mfma_f32_16x16x32_bf16 v[48:51], v[210:213], v[166:169], 0
	v_mfma_f32_16x16x32_bf16 v[36:39], v[202:205], v[174:177], 0
	v_mfma_f32_16x16x32_bf16 v[32:35], v[210:213], v[174:177], 0
	v_mfma_f32_16x16x32_bf16 v[20:23], v[202:205], v[182:185], 0
	v_mfma_f32_16x16x32_bf16 v[16:19], v[210:213], v[182:185], 0
	v_mfma_f32_16x16x32_bf16 v[4:7], v[202:205], v[190:193], 0
	v_mfma_f32_16x16x32_bf16 v[0:3], v[210:213], v[190:193], 0
	v_mfma_f32_16x16x32_bf16 v[52:55], v[206:209], v[170:173], v[52:55]
	v_mfma_f32_16x16x32_bf16 v[48:51], v[214:217], v[170:173], v[48:51]
	v_mfma_f32_16x16x32_bf16 v[36:39], v[206:209], v[178:181], v[36:39]
	v_mfma_f32_16x16x32_bf16 v[32:35], v[214:217], v[178:181], v[32:35]
	v_mfma_f32_16x16x32_bf16 v[20:23], v[206:209], v[186:189], v[20:23]
	v_mfma_f32_16x16x32_bf16 v[16:19], v[214:217], v[186:189], v[16:19]
	v_mfma_f32_16x16x32_bf16 v[4:7], v[206:209], v[194:197], v[4:7]
	v_mfma_f32_16x16x32_bf16 v[0:3], v[214:217], v[194:197], v[0:3]
	s_setprio 0
	s_add_i32 s47, 0, 0x18000
	v_add_u32_e32 v162, s47, v146
	s_barrier
	ds_read_b128 v[150:153], v162
	ds_read_b128 v[154:157], v162 offset:1024
	ds_read_b128 v[158:161], v162 offset:2048
	ds_read_b128 v[162:165], v162 offset:3072
	ds_read_b128 v[166:169], v148 offset:32768
	ds_read_b128 v[170:173], v148 offset:33792
	ds_read_b128 v[174:177], v148 offset:34816
	ds_read_b128 v[178:181], v148 offset:35840
	ds_read_b128 v[182:185], v148 offset:36864
	ds_read_b128 v[186:189], v148 offset:37888
	ds_read_b128 v[190:193], v148 offset:38912
	ds_read_b128 v[194:197], v148 offset:39936
	s_waitcnt lgkmcnt(8)
	s_waitcnt vmcnt(10)
	s_barrier
	s_waitcnt lgkmcnt(0)
	s_setprio 1
	s_waitcnt lgkmcnt(0)
	v_mfma_f32_16x16x32_bf16 v[124:127], v[150:153], v[166:169], v[124:127]
	v_mfma_f32_16x16x32_bf16 v[116:119], v[158:161], v[166:169], v[116:119]
	v_mfma_f32_16x16x32_bf16 v[108:111], v[150:153], v[174:177], v[108:111]
	v_mfma_f32_16x16x32_bf16 v[100:103], v[158:161], v[174:177], v[100:103]
	v_mfma_f32_16x16x32_bf16 v[92:95], v[150:153], v[182:185], v[92:95]
	v_mfma_f32_16x16x32_bf16 v[84:87], v[158:161], v[182:185], v[84:87]
	v_mfma_f32_16x16x32_bf16 v[76:79], v[150:153], v[190:193], v[76:79]
	v_mfma_f32_16x16x32_bf16 v[68:71], v[158:161], v[190:193], v[68:71]
	v_mfma_f32_16x16x32_bf16 v[124:127], v[154:157], v[170:173], v[124:127]
	v_mfma_f32_16x16x32_bf16 v[116:119], v[162:165], v[170:173], v[116:119]
	v_mfma_f32_16x16x32_bf16 v[108:111], v[154:157], v[178:181], v[108:111]
	v_mfma_f32_16x16x32_bf16 v[100:103], v[162:165], v[178:181], v[100:103]
	v_mfma_f32_16x16x32_bf16 v[92:95], v[154:157], v[186:189], v[92:95]
	v_mfma_f32_16x16x32_bf16 v[84:87], v[162:165], v[186:189], v[84:87]
	v_mfma_f32_16x16x32_bf16 v[76:79], v[154:157], v[194:197], v[76:79]
	v_mfma_f32_16x16x32_bf16 v[68:71], v[162:165], v[194:197], v[68:71]
	s_setprio 0
	s_barrier
	s_add_i32 s20, 0, 0x1c000
	s_add_i32 s21, s47, s25
	v_add_u32_e32 v214, s20, v146
	s_add_u32 s0, s18, 0x80
	s_addc_u32 s1, s19, 0
	s_mov_b32 m0, s21
	ds_read_b128 v[202:205], v214
	ds_read_b128 v[206:209], v214 offset:1024
	ds_read_b128 v[210:213], v214 offset:2048
	ds_read_b128 v[214:217], v214 offset:3072
	global_load_lds_dwordx4 v132, s[0:1]
	s_add_i32 m0, s21, 0x2000
	s_nop 0
	global_load_lds_dwordx4 v128, s[0:1]
	s_waitcnt vmcnt(10)
	s_barrier
	s_waitcnt lgkmcnt(0)
	s_setprio 1
	s_waitcnt lgkmcnt(0)
	v_mfma_f32_16x16x32_bf16 v[120:123], v[202:205], v[166:169], v[120:123]
	v_mfma_f32_16x16x32_bf16 v[112:115], v[210:213], v[166:169], v[112:115]
	v_mfma_f32_16x16x32_bf16 v[104:107], v[202:205], v[174:177], v[104:107]
	v_mfma_f32_16x16x32_bf16 v[96:99], v[210:213], v[174:177], v[96:99]
	v_mfma_f32_16x16x32_bf16 v[88:91], v[202:205], v[182:185], v[88:91]
	v_mfma_f32_16x16x32_bf16 v[80:83], v[210:213], v[182:185], v[80:83]
	v_mfma_f32_16x16x32_bf16 v[72:75], v[202:205], v[190:193], v[72:75]
	v_mfma_f32_16x16x32_bf16 v[64:67], v[210:213], v[190:193], v[64:67]
	v_mfma_f32_16x16x32_bf16 v[120:123], v[206:209], v[170:173], v[120:123]
	v_mfma_f32_16x16x32_bf16 v[112:115], v[214:217], v[170:173], v[112:115]
	v_mfma_f32_16x16x32_bf16 v[104:107], v[206:209], v[178:181], v[104:107]
	v_mfma_f32_16x16x32_bf16 v[96:99], v[214:217], v[178:181], v[96:99]
	v_mfma_f32_16x16x32_bf16 v[88:91], v[206:209], v[186:189], v[88:91]
	v_mfma_f32_16x16x32_bf16 v[80:83], v[214:217], v[186:189], v[80:83]
	v_mfma_f32_16x16x32_bf16 v[72:75], v[206:209], v[194:197], v[72:75]
	v_mfma_f32_16x16x32_bf16 v[64:67], v[214:217], v[194:197], v[64:67]
	s_setprio 0
	s_mov_b32 m0, s35
	s_mov_b64 s[0:1], 0x80
	v_lshl_add_u64 v[198:199], v[220:221], 0, s[0:1]
	s_barrier
	ds_read_b128 v[166:169], v148 offset:49152
	ds_read_b128 v[170:173], v148 offset:50176
	ds_read_b128 v[174:177], v148 offset:51200
	ds_read_b128 v[178:181], v148 offset:52224
	ds_read_b128 v[182:185], v148 offset:53248
	ds_read_b128 v[186:189], v148 offset:54272
	ds_read_b128 v[190:193], v148 offset:55296
	ds_read_b128 v[194:197], v148 offset:56320
	global_load_lds_dwordx4 v[198:199], off
	v_lshl_add_u64 v[198:199], v[222:223], 0, s[0:1]
	s_mov_b32 m0, s36
	s_nop 0
	global_load_lds_dwordx4 v[198:199], off
	s_barrier
; #define PG8_STAGE(bufoff, gbase, voff) do { _Pragma("unroll") for (int _i = 0; _i < 2; ++_i) \
;         __builtin_amdgcn_global_load_lds((const unsigned*)((const char*)(gbase) + (voff)[_i]), (LAS unsigned*)(lds + (bufoff) + ldsw + _i * 8192), 16, 0, 0); } while (0)
; #define PG8_LDA(dst, b, h) do { _Pragma("unroll") for (int m = 0; m < 4; ++m) _Pragma("unroll") for (int k = 0; k < 2; ++k) dst[m][k] = *(const LAS bf16x8*)(lds + PG8_SA(b, h) + aoff + m * 2048 + k * 1024); } while (0)
; #define PG8_LDB(dst, b, h) do { _Pragma("unroll") for (int n = 0; n < 2; ++n) _Pragma("unroll") for (int k = 0; k < 2; ++k) dst[n][k] = *(const LAS bf16x8*)(lds + PG8_SB(b, h) + boff + n * 2048 + k * 1024); } while (0)
; #define PG8_MMA(ai, bj, At, Bt) do { __builtin_amdgcn_s_setprio(1); _Pragma("unroll") for (int m = 0; m < 4; ++m) _Pragma("unroll") for (int n = 0; n < 2; ++n) _Pragma("unroll") for (int k = 0; k < 2; ++k) \
;         acc[ai][bj][m][n] = __builtin_amdgcn_mfma_f32_16x16x32_bf16(Bt[n][k], At[m][k], acc[ai][bj][m][n], 0, 0, 0); __builtin_amdgcn_s_setprio(0); } while (0)
; #define PG8_WAIT_V(n) asm volatile("s_waitcnt vmcnt(" #n ")" ::: "memory")
; #define PG8_WAIT_L(n) asm volatile("s_waitcnt lgkmcnt(" #n ")" ::: "memory")
; template <class Epi, class Sched>
; __device__ __forceinline__ void gemm_phase(LAS unsigned char* lds, const Gemm g, const Sched& S, const Epi& E) {
;     ...
;         for (int t = 0; t < nt; t += 2) {
;             const bool last = (t == nt - 2);
;             const char* a1 = cA + (size_t)(t + 1) * kstep;
;             const char* a2 = last ? nA : cA + (size_t)(t + 2) * kstep; const char* b2 = last ? nB : cB + (size_t)(t + 2) * kstep;
;             const char* a3 = a2 + kstep; const char* b3 = b2 + kstep;
;             PG8_LDB(B0, 0, 0); PG8_SCHED; PG8_LDA(At, 0, 0); PG8_STAGE(PG8_SA(1, 1), a1 + hstep, voffA);
;             PG8_WAIT_L(8); PG8_BAR; PG8_WAIT_L(0); PG8_MMA(0, 0, At, B0); PG8_BAR; PG8_SCHED;
;             PG8_LDB(B1, 0, 1); PG8_STAGE(PG8_SB(0, 0), b2, voffB);
;             PG8_BAR; PG8_WAIT_L(0); PG8_MMA(0, 1, At, B1); PG8_BAR;
;     ...
;             PG8_LDA(At, 1, 1); PG8_STAGE(PG8_SA(1, 0), a3, voffA);
;             PG8_BAR; PG8_WAIT_L(0); PG8_MMA(1, 0, At, B0); PG8_BAR; PG8_SCHED;
;             PG8_STAGE(PG8_SB(1, 1), b3 + hstep, voffB);
;             PG8_WAIT_V(6); PG8_BAR; PG8_MMA(1, 1, At, B1); PG8_BAR;
	s_waitcnt lgkmcnt(0)
	s_setprio 1
	s_waitcnt lgkmcnt(0)
	v_mfma_f32_16x16x32_bf16 v[60:63], v[150:153], v[166:169], v[60:63]
	v_mfma_f32_16x16x32_bf16 v[56:59], v[158:161], v[166:169], v[56:59]
	v_mfma_f32_16x16x32_bf16 v[44:47], v[150:153], v[174:177], v[44:47]
	v_mfma_f32_16x16x32_bf16 v[40:43], v[158:161], v[174:177], v[40:43]
	v_mfma_f32_16x16x32_bf16 v[28:31], v[150:153], v[182:185], v[28:31]
	v_mfma_f32_16x16x32_bf16 v[24:27], v[158:161], v[182:185], v[24:27]
	v_mfma_f32_16x16x32_bf16 v[12:15], v[150:153], v[190:193], v[12:15]
	v_mfma_f32_16x16x32_bf16 v[8:11], v[158:161], v[190:193], v[8:11]
	v_mfma_f32_16x16x32_bf16 v[60:63], v[154:157], v[170:173], v[60:63]
	v_mfma_f32_16x16x32_bf16 v[56:59], v[162:165], v[170:173], v[56:59]
	v_mfma_f32_16x16x32_bf16 v[44:47], v[154:157], v[178:181], v[44:47]
	v_mfma_f32_16x16x32_bf16 v[40:43], v[162:165], v[178:181], v[40:43]
	v_mfma_f32_16x16x32_bf16 v[28:31], v[154:157], v[186:189], v[28:31]
	v_mfma_f32_16x16x32_bf16 v[24:27], v[162:165], v[186:189], v[24:27]
	v_mfma_f32_16x16x32_bf16 v[12:15], v[154:157], v[194:197], v[12:15]
	v_mfma_f32_16x16x32_bf16 v[8:11], v[162:165], v[194:197], v[8:11]
	s_setprio 0
	s_barrier
	s_add_u32 s18, s18, 0x40080
	s_addc_u32 s19, s19, 0
	s_add_i32 s20, s20, s25
	s_mov_b32 m0, s20
	s_nop 0
	global_load_lds_dwordx4 v132, s[18:19]
	s_add_i32 m0, s20, 0x2000
	s_nop 0
	global_load_lds_dwordx4 v128, s[18:19]
	s_waitcnt vmcnt(10)
	s_barrier
	s_setprio 1
	v_mfma_f32_16x16x32_bf16 v[52:55], v[202:205], v[166:169], v[52:55]
	v_mfma_f32_16x16x32_bf16 v[48:51], v[210:213], v[166:169], v[48:51]
	v_mfma_f32_16x16x32_bf16 v[36:39], v[202:205], v[174:177], v[36:39]
	v_mfma_f32_16x16x32_bf16 v[32:35], v[210:213], v[174:177], v[32:35]
	v_mfma_f32_16x16x32_bf16 v[20:23], v[202:205], v[182:185], v[20:23]
	v_mfma_f32_16x16x32_bf16 v[16:19], v[210:213], v[182:185], v[16:19]
	v_mfma_f32_16x16x32_bf16 v[4:7], v[202:205], v[190:193], v[4:7]
	v_mfma_f32_16x16x32_bf16 v[0:3], v[210:213], v[190:193], v[0:3]
	v_mfma_f32_16x16x32_bf16 v[52:55], v[206:209], v[170:173], v[52:55]
	v_mfma_f32_16x16x32_bf16 v[48:51], v[214:217], v[170:173], v[48:51]
	v_mfma_f32_16x16x32_bf16 v[36:39], v[206:209], v[178:181], v[36:39]
	v_mfma_f32_16x16x32_bf16 v[32:35], v[214:217], v[178:181], v[32:35]
	v_mfma_f32_16x16x32_bf16 v[20:23], v[206:209], v[186:189], v[20:23]
	v_mfma_f32_16x16x32_bf16 v[16:19], v[214:217], v[186:189], v[16:19]
	v_mfma_f32_16x16x32_bf16 v[4:7], v[206:209], v[194:197], v[4:7]
	v_mfma_f32_16x16x32_bf16 v[0:3], v[214:217], v[194:197], v[0:3]
	s_setprio 0
	s_add_i32 s46, s46, 2
	s_add_u32 s16, s16, 0x100
	s_addc_u32 s17, s17, 0
	s_add_u32 s44, s44, 0x100
	s_addc_u32 s45, s45, 0
	s_cmp_gt_u32 s46, 13
	s_barrier
.LBB0_1021:
	ds_read_b128 v[150:153], v147
	ds_read_b128 v[154:157], v147 offset:1024
	ds_read_b128 v[158:161], v147 offset:2048
	ds_read_b128 v[162:165], v147 offset:3072
	s_add_u32 s18, s16, 0xfffc0080
	s_addc_u32 s19, s17, -1
	s_cmp_eq_u32 s46, 12
	s_cselect_b32 s21, s7, s19
	s_cselect_b32 s20, s42, s18
	s_cselect_b32 s19, s5, s45
	s_cselect_b32 s18, s43, s44
	s_add_i32 m0, s15, 0xc000
	ds_read_b128 v[166:169], v148
	ds_read_b128 v[170:173], v148 offset:1024
	ds_read_b128 v[174:177], v148 offset:2048
	ds_read_b128 v[178:181], v148 offset:3072
	ds_read_b128 v[182:185], v148 offset:4096
	ds_read_b128 v[186:189], v148 offset:5120
	ds_read_b128 v[190:193], v148 offset:6144
	ds_read_b128 v[194:197], v148 offset:7168
	global_load_lds_dwordx4 v136, s[16:17]
	s_add_i32 m0, s15, 0xe000
	s_nop 0
	global_load_lds_dwordx4 v138, s[16:17]
	s_waitcnt lgkmcnt(8)
	s_waitcnt vmcnt(10)
	s_barrier
	s_waitcnt lgkmcnt(0)
	s_setprio 1
	s_waitcnt lgkmcnt(0)
	v_mfma_f32_16x16x32_bf16 v[124:127], v[150:153], v[166:169], v[124:127]
	v_mfma_f32_16x16x32_bf16 v[116:119], v[158:161], v[166:169], v[116:119]
	v_mfma_f32_16x16x32_bf16 v[108:111], v[150:153], v[174:177], v[108:111]
	v_mfma_f32_16x16x32_bf16 v[100:103], v[158:161], v[174:177], v[100:103]
	v_mfma_f32_16x16x32_bf16 v[92:95], v[150:153], v[182:185], v[92:95]
	v_mfma_f32_16x16x32_bf16 v[84:87], v[158:161], v[182:185], v[84:87]
	v_mfma_f32_16x16x32_bf16 v[76:79], v[150:153], v[190:193], v[76:79]
	v_mfma_f32_16x16x32_bf16 v[68:71], v[158:161], v[190:193], v[68:71]
	v_mfma_f32_16x16x32_bf16 v[124:127], v[154:157], v[170:173], v[124:127]
	v_mfma_f32_16x16x32_bf16 v[116:119], v[162:165], v[170:173], v[116:119]
	v_mfma_f32_16x16x32_bf16 v[108:111], v[154:157], v[178:181], v[108:111]
	v_mfma_f32_16x16x32_bf16 v[100:103], v[162:165], v[178:181], v[100:103]
	v_mfma_f32_16x16x32_bf16 v[92:95], v[154:157], v[186:189], v[92:95]
	v_mfma_f32_16x16x32_bf16 v[84:87], v[162:165], v[186:189], v[84:87]
	v_mfma_f32_16x16x32_bf16 v[76:79], v[154:157], v[194:197], v[76:79]
	v_mfma_f32_16x16x32_bf16 v[68:71], v[162:165], v[194:197], v[68:71]
	s_setprio 0
	s_barrier
	s_add_i32 s47, s38, s25
	s_mov_b32 m0, s47
	ds_read_b128 v[202:205], v149
	ds_read_b128 v[206:209], v149 offset:1024
	ds_read_b128 v[210:213], v149 offset:2048
	ds_read_b128 v[214:217], v149 offset:3072
	global_load_lds_dwordx4 v132, s[18:19]
	s_add_i32 m0, s47, 0x2000
	s_nop 0
	global_load_lds_dwordx4 v128, s[18:19]
	s_waitcnt vmcnt(10)
	s_barrier
; #define PG8_STAGE(bufoff, gbase, voff) do { _Pragma("unroll") for (int _i = 0; _i < 2; ++_i) \
;         __builtin_amdgcn_global_load_lds((const unsigned*)((const char*)(gbase) + (voff)[_i]), (LAS unsigned*)(lds + (bufoff) + ldsw + _i * 8192), 16, 0, 0); } while (0)
; #define PG8_LDA(dst, b, h) do { _Pragma("unroll") for (int m = 0; m < 4; ++m) _Pragma("unroll") for (int k = 0; k < 2; ++k) dst[m][k] = *(const LAS bf16x8*)(lds + PG8_SA(b, h) + aoff + m * 2048 + k * 1024); } while (0)
; #define PG8_LDB(dst, b, h) do { _Pragma("unroll") for (int n = 0; n < 2; ++n) _Pragma("unroll") for (int k = 0; k < 2; ++k) dst[n][k] = *(const LAS bf16x8*)(lds + PG8_SB(b, h) + boff + n * 2048 + k * 1024); } while (0)
; #define PG8_MMA(ai, bj, At, Bt) do { __builtin_amdgcn_s_setprio(1); _Pragma("unroll") for (int m = 0; m < 4; ++m) _Pragma("unroll") for (int n = 0; n < 2; ++n) _Pragma("unroll") for (int k = 0; k < 2; ++k) \
;         acc[ai][bj][m][n] = __builtin_amdgcn_mfma_f32_16x16x32_bf16(Bt[n][k], At[m][k], acc[ai][bj][m][n], 0, 0, 0); __builtin_amdgcn_s_setprio(0); } while (0)
; #define PG8_WAIT_V(n) asm volatile("s_waitcnt vmcnt(" #n ")" ::: "memory")
; #define PG8_WAIT_L(n) asm volatile("s_waitcnt lgkmcnt(" #n ")" ::: "memory")
; #define PG8_BAR __builtin_amdgcn_s_barrier()
; #define PG8_SCHED __builtin_amdgcn_sched_barrier(0)
; template <class Epi, class Sched>
; __device__ __forceinline__ void gemm_phase(LAS unsigned char* lds, const Gemm g, const Sched& S, const Epi& E) {
;     ...
;             PG8_BAR; PG8_WAIT_L(0); PG8_MMA(0, 1, At, B1); PG8_BAR;
;             PG8_LDA(At, 0, 1); PG8_STAGE(PG8_SA(0, 0), a2, voffA);
;             PG8_BAR; PG8_WAIT_L(0); PG8_MMA(1, 0, At, B0); PG8_BAR; PG8_SCHED;
;             PG8_STAGE(PG8_SB(0, 1), b2 + hstep, voffB);
;             PG8_WAIT_V(6); PG8_BAR; PG8_MMA(1, 1, At, B1); PG8_BAR;
;             PG8_LDB(B0, 1, 0); PG8_SCHED; PG8_LDA(At, 1, 0); PG8_STAGE(PG8_SA(0, 1), a2 + hstep, voffA);
;             PG8_WAIT_L(8); PG8_BAR; PG8_WAIT_L(0); PG8_MMA(0, 0, At, B0); PG8_BAR; PG8_SCHED;
	s_waitcnt lgkmcnt(0)
	s_setprio 1
	s_waitcnt lgkmcnt(0)
	v_mfma_f32_16x16x32_bf16 v[120:123], v[202:205], v[166:169], v[120:123]
	v_mfma_f32_16x16x32_bf16 v[112:115], v[210:213], v[166:169], v[112:115]
	v_mfma_f32_16x16x32_bf16 v[104:107], v[202:205], v[174:177], v[104:107]
	v_mfma_f32_16x16x32_bf16 v[96:99], v[210:213], v[174:177], v[96:99]
	v_mfma_f32_16x16x32_bf16 v[88:91], v[202:205], v[182:185], v[88:91]
	v_mfma_f32_16x16x32_bf16 v[80:83], v[210:213], v[182:185], v[80:83]
	v_mfma_f32_16x16x32_bf16 v[72:75], v[202:205], v[190:193], v[72:75]
	v_mfma_f32_16x16x32_bf16 v[64:67], v[210:213], v[190:193], v[64:67]
	v_mfma_f32_16x16x32_bf16 v[120:123], v[206:209], v[170:173], v[120:123]
	v_mfma_f32_16x16x32_bf16 v[112:115], v[214:217], v[170:173], v[112:115]
	v_mfma_f32_16x16x32_bf16 v[104:107], v[206:209], v[178:181], v[104:107]
	v_mfma_f32_16x16x32_bf16 v[96:99], v[214:217], v[178:181], v[96:99]
	v_mfma_f32_16x16x32_bf16 v[88:91], v[206:209], v[186:189], v[88:91]
	v_mfma_f32_16x16x32_bf16 v[80:83], v[214:217], v[186:189], v[80:83]
	v_mfma_f32_16x16x32_bf16 v[72:75], v[206:209], v[194:197], v[72:75]
	v_mfma_f32_16x16x32_bf16 v[64:67], v[214:217], v[194:197], v[64:67]
	s_setprio 0
	s_mov_b32 m0, s15
	v_lshl_add_u64 v[220:221], s[20:21], 0, v[134:135]
	s_barrier
	ds_read_b128 v[166:169], v148 offset:16384
	ds_read_b128 v[170:173], v148 offset:17408
	ds_read_b128 v[174:177], v148 offset:18432
	ds_read_b128 v[178:181], v148 offset:19456
	ds_read_b128 v[182:185], v148 offset:20480
	ds_read_b128 v[186:189], v148 offset:21504
	ds_read_b128 v[190:193], v148 offset:22528
	ds_read_b128 v[194:197], v148 offset:23552
	global_load_lds_dwordx4 v134, s[20:21]
	v_lshl_add_u64 v[222:223], s[20:21], 0, v[130:131]
	s_mov_b32 m0, s28
	s_nop 0
	global_load_lds_dwordx4 v130, s[20:21]
	s_barrier
	s_waitcnt lgkmcnt(0)
	s_setprio 1
	s_waitcnt lgkmcnt(0)
	v_mfma_f32_16x16x32_bf16 v[60:63], v[150:153], v[166:169], v[60:63]
	v_mfma_f32_16x16x32_bf16 v[56:59], v[158:161], v[166:169], v[56:59]
	v_mfma_f32_16x16x32_bf16 v[44:47], v[150:153], v[174:177], v[44:47]
	v_mfma_f32_16x16x32_bf16 v[40:43], v[158:161], v[174:177], v[40:43]
	v_mfma_f32_16x16x32_bf16 v[28:31], v[150:153], v[182:185], v[28:31]
	v_mfma_f32_16x16x32_bf16 v[24:27], v[158:161], v[182:185], v[24:27]
	v_mfma_f32_16x16x32_bf16 v[12:15], v[150:153], v[190:193], v[12:15]
	v_mfma_f32_16x16x32_bf16 v[8:11], v[158:161], v[190:193], v[8:11]
	v_mfma_f32_16x16x32_bf16 v[60:63], v[154:157], v[170:173], v[60:63]
	v_mfma_f32_16x16x32_bf16 v[56:59], v[162:165], v[170:173], v[56:59]
	v_mfma_f32_16x16x32_bf16 v[44:47], v[154:157], v[178:181], v[44:47]
	v_mfma_f32_16x16x32_bf16 v[40:43], v[162:165], v[178:181], v[40:43]
	v_mfma_f32_16x16x32_bf16 v[28:31], v[154:157], v[186:189], v[28:31]
	v_mfma_f32_16x16x32_bf16 v[24:27], v[162:165], v[186:189], v[24:27]
	v_mfma_f32_16x16x32_bf16 v[12:15], v[154:157], v[194:197], v[12:15]
	v_mfma_f32_16x16x32_bf16 v[8:11], v[162:165], v[194:197], v[8:11]
	s_setprio 0
	s_barrier
	s_add_u32 s48, s18, 0x40000
	s_addc_u32 s49, s19, 0
	s_add_i32 s47, s39, s25
	s_mov_b32 m0, s47
	s_nop 0
	global_load_lds_dwordx4 v132, s[48:49]
	s_add_i32 m0, s47, 0x2000
	s_nop 0
	global_load_lds_dwordx4 v128, s[48:49]
	s_add_u32 s20, s20, 0x40000
	s_addc_u32 s21, s21, 0
	s_mov_b32 m0, s29
	s_nop 0
	global_load_lds_dwordx4 v134, s[20:21]
	s_mov_b32 m0, s30
	s_nop 0
	global_load_lds_dwordx4 v130, s[20:21]
	s_waitcnt vmcnt(12)
	s_barrier
	s_setprio 1
	v_mfma_f32_16x16x32_bf16 v[52:55], v[202:205], v[166:169], v[52:55]
	v_mfma_f32_16x16x32_bf16 v[48:51], v[210:213], v[166:169], v[48:51]
	v_mfma_f32_16x16x32_bf16 v[36:39], v[202:205], v[174:177], v[36:39]
	v_mfma_f32_16x16x32_bf16 v[32:35], v[210:213], v[174:177], v[32:35]
	v_mfma_f32_16x16x32_bf16 v[20:23], v[202:205], v[182:185], v[20:23]
	v_mfma_f32_16x16x32_bf16 v[16:19], v[210:213], v[182:185], v[16:19]
	v_mfma_f32_16x16x32_bf16 v[4:7], v[202:205], v[190:193], v[4:7]
	v_mfma_f32_16x16x32_bf16 v[0:3], v[210:213], v[190:193], v[0:3]
	v_mfma_f32_16x16x32_bf16 v[52:55], v[206:209], v[170:173], v[52:55]
	v_mfma_f32_16x16x32_bf16 v[48:51], v[214:217], v[170:173], v[48:51]
	v_mfma_f32_16x16x32_bf16 v[36:39], v[206:209], v[178:181], v[36:39]
	v_mfma_f32_16x16x32_bf16 v[32:35], v[214:217], v[178:181], v[32:35]
	v_mfma_f32_16x16x32_bf16 v[20:23], v[206:209], v[186:189], v[20:23]
	v_mfma_f32_16x16x32_bf16 v[16:19], v[214:217], v[186:189], v[16:19]
	v_mfma_f32_16x16x32_bf16 v[4:7], v[206:209], v[194:197], v[4:7]
	v_mfma_f32_16x16x32_bf16 v[0:3], v[214:217], v[194:197], v[0:3]
	s_setprio 0
	s_add_i32 s47, 0, 0x18000
	v_add_u32_e32 v162, s47, v146
	s_barrier
	ds_read_b128 v[150:153], v162
	ds_read_b128 v[154:157], v162 offset:1024
	ds_read_b128 v[158:161], v162 offset:2048
	ds_read_b128 v[162:165], v162 offset:3072
	ds_read_b128 v[166:169], v148 offset:32768
	ds_read_b128 v[170:173], v148 offset:33792
	ds_read_b128 v[174:177], v148 offset:34816
	ds_read_b128 v[178:181], v148 offset:35840
	ds_read_b128 v[182:185], v148 offset:36864
	ds_read_b128 v[186:189], v148 offset:37888
	ds_read_b128 v[190:193], v148 offset:38912
	ds_read_b128 v[194:197], v148 offset:39936
	s_waitcnt lgkmcnt(8)
	s_waitcnt vmcnt(10)
	s_barrier
; #define PG8_STAGE(bufoff, gbase, voff) do { _Pragma("unroll") for (int _i = 0; _i < 2; ++_i) \
;         __builtin_amdgcn_global_load_lds((const unsigned*)((const char*)(gbase) + (voff)[_i]), (LAS unsigned*)(lds + (bufoff) + ldsw + _i * 8192), 16, 0, 0); } while (0)
; #define PG8_LDA(dst, b, h) do { _Pragma("unroll") for (int m = 0; m < 4; ++m) _Pragma("unroll") for (int k = 0; k < 2; ++k) dst[m][k] = *(const LAS bf16x8*)(lds + PG8_SA(b, h) + aoff + m * 2048 + k * 1024); } while (0)
; #define PG8_LDB(dst, b, h) do { _Pragma("unroll") for (int n = 0; n < 2; ++n) _Pragma("unroll") for (int k = 0; k < 2; ++k) dst[n][k] = *(const LAS bf16x8*)(lds + PG8_SB(b, h) + boff + n * 2048 + k * 1024); } while (0)
; #define PG8_MMA(ai, bj, At, Bt) do { __builtin_amdgcn_s_setprio(1); _Pragma("unroll") for (int m = 0; m < 4; ++m) _Pragma("unroll") for (int n = 0; n < 2; ++n) _Pragma("unroll") for (int k = 0; k < 2; ++k) \
;         acc[ai][bj][m][n] = __builtin_amdgcn_mfma_f32_16x16x32_bf16(Bt[n][k], At[m][k], acc[ai][bj][m][n], 0, 0, 0); __builtin_amdgcn_s_setprio(0); } while (0)
; #define PG8_WAIT_V(n) asm volatile("s_waitcnt vmcnt(" #n ")" ::: "memory")
; #define PG8_WAIT_L(n) asm volatile("s_waitcnt lgkmcnt(" #n ")" ::: "memory")
; #define PG8_BAR __builtin_amdgcn_s_barrier()
; #define PG8_SCHED __builtin_amdgcn_sched_barrier(0)
; template <class Epi, class Sched>
; __device__ __forceinline__ void gemm_phase(LAS unsigned char* lds, const Gemm g, const Sched& S, const Epi& E) {
;     ...
;             PG8_WAIT_L(8); PG8_BAR; PG8_WAIT_L(0); PG8_MMA(0, 0, At, B0); PG8_BAR; PG8_SCHED;
;             PG8_LDB(B1, 1, 1); PG8_STAGE(PG8_SB(1, 0), b3, voffB);
;             PG8_BAR; PG8_WAIT_L(0); PG8_MMA(0, 1, At, B1); PG8_BAR;
;             PG8_LDA(At, 1, 1); PG8_STAGE(PG8_SA(1, 0), a3, voffA);
;             PG8_BAR; PG8_WAIT_L(0); PG8_MMA(1, 0, At, B0); PG8_BAR; PG8_SCHED;
;             PG8_STAGE(PG8_SB(1, 1), b3 + hstep, voffB);
;             PG8_WAIT_V(6); PG8_BAR; PG8_MMA(1, 1, At, B1); PG8_BAR;
	s_waitcnt lgkmcnt(0)
	s_setprio 1
	s_waitcnt lgkmcnt(0)
	v_mfma_f32_16x16x32_bf16 v[124:127], v[150:153], v[166:169], v[124:127]
	v_mfma_f32_16x16x32_bf16 v[116:119], v[158:161], v[166:169], v[116:119]
	v_mfma_f32_16x16x32_bf16 v[108:111], v[150:153], v[174:177], v[108:111]
	v_mfma_f32_16x16x32_bf16 v[100:103], v[158:161], v[174:177], v[100:103]
	v_mfma_f32_16x16x32_bf16 v[92:95], v[150:153], v[182:185], v[92:95]
	v_mfma_f32_16x16x32_bf16 v[84:87], v[158:161], v[182:185], v[84:87]
	v_mfma_f32_16x16x32_bf16 v[76:79], v[150:153], v[190:193], v[76:79]
	v_mfma_f32_16x16x32_bf16 v[68:71], v[158:161], v[190:193], v[68:71]
	v_mfma_f32_16x16x32_bf16 v[124:127], v[154:157], v[170:173], v[124:127]
	v_mfma_f32_16x16x32_bf16 v[116:119], v[162:165], v[170:173], v[116:119]
	v_mfma_f32_16x16x32_bf16 v[108:111], v[154:157], v[178:181], v[108:111]
	v_mfma_f32_16x16x32_bf16 v[100:103], v[162:165], v[178:181], v[100:103]
	v_mfma_f32_16x16x32_bf16 v[92:95], v[154:157], v[186:189], v[92:95]
	v_mfma_f32_16x16x32_bf16 v[84:87], v[162:165], v[186:189], v[84:87]
	v_mfma_f32_16x16x32_bf16 v[76:79], v[154:157], v[194:197], v[76:79]
	v_mfma_f32_16x16x32_bf16 v[68:71], v[162:165], v[194:197], v[68:71]
	s_setprio 0
	s_barrier
	s_add_i32 s20, 0, 0x1c000
	s_add_i32 s21, s47, s25
	v_add_u32_e32 v214, s20, v146
	s_add_u32 s0, s18, 0x80
	s_addc_u32 s1, s19, 0
	s_mov_b32 m0, s21
	ds_read_b128 v[202:205], v214
	ds_read_b128 v[206:209], v214 offset:1024
	ds_read_b128 v[210:213], v214 offset:2048
	ds_read_b128 v[214:217], v214 offset:3072
	global_load_lds_dwordx4 v132, s[0:1]
	s_add_i32 m0, s21, 0x2000
	s_nop 0
	global_load_lds_dwordx4 v128, s[0:1]
	s_waitcnt vmcnt(10)
	s_barrier
	s_waitcnt lgkmcnt(0)
	s_setprio 1
	s_waitcnt lgkmcnt(0)
	v_mfma_f32_16x16x32_bf16 v[120:123], v[202:205], v[166:169], v[120:123]
	v_mfma_f32_16x16x32_bf16 v[112:115], v[210:213], v[166:169], v[112:115]
	v_mfma_f32_16x16x32_bf16 v[104:107], v[202:205], v[174:177], v[104:107]
	v_mfma_f32_16x16x32_bf16 v[96:99], v[210:213], v[174:177], v[96:99]
	v_mfma_f32_16x16x32_bf16 v[88:91], v[202:205], v[182:185], v[88:91]
	v_mfma_f32_16x16x32_bf16 v[80:83], v[210:213], v[182:185], v[80:83]
	v_mfma_f32_16x16x32_bf16 v[72:75], v[202:205], v[190:193], v[72:75]
	v_mfma_f32_16x16x32_bf16 v[64:67], v[210:213], v[190:193], v[64:67]
	v_mfma_f32_16x16x32_bf16 v[120:123], v[206:209], v[170:173], v[120:123]
	v_mfma_f32_16x16x32_bf16 v[112:115], v[214:217], v[170:173], v[112:115]
	v_mfma_f32_16x16x32_bf16 v[104:107], v[206:209], v[178:181], v[104:107]
	v_mfma_f32_16x16x32_bf16 v[96:99], v[214:217], v[178:181], v[96:99]
	v_mfma_f32_16x16x32_bf16 v[88:91], v[206:209], v[186:189], v[88:91]
	v_mfma_f32_16x16x32_bf16 v[80:83], v[214:217], v[186:189], v[80:83]
	v_mfma_f32_16x16x32_bf16 v[72:75], v[206:209], v[194:197], v[72:75]
	v_mfma_f32_16x16x32_bf16 v[64:67], v[214:217], v[194:197], v[64:67]
	s_setprio 0
	s_mov_b32 m0, s35
	s_mov_b64 s[0:1], 0x80
	v_lshl_add_u64 v[198:199], v[220:221], 0, s[0:1]
	s_barrier
	ds_read_b128 v[166:169], v148 offset:49152
	ds_read_b128 v[170:173], v148 offset:50176
	ds_read_b128 v[174:177], v148 offset:51200
	ds_read_b128 v[178:181], v148 offset:52224
	ds_read_b128 v[182:185], v148 offset:53248
	ds_read_b128 v[186:189], v148 offset:54272
	ds_read_b128 v[190:193], v148 offset:55296
	ds_read_b128 v[194:197], v148 offset:56320
	global_load_lds_dwordx4 v[198:199], off
	v_lshl_add_u64 v[198:199], v[222:223], 0, s[0:1]
	s_mov_b32 m0, s36
	s_nop 0
	global_load_lds_dwordx4 v[198:199], off
	s_barrier
	s_waitcnt lgkmcnt(0)
	s_setprio 1
	s_waitcnt lgkmcnt(0)
	v_mfma_f32_16x16x32_bf16 v[60:63], v[150:153], v[166:169], v[60:63]
	v_mfma_f32_16x16x32_bf16 v[56:59], v[158:161], v[166:169], v[56:59]
	v_mfma_f32_16x16x32_bf16 v[44:47], v[150:153], v[174:177], v[44:47]
	v_mfma_f32_16x16x32_bf16 v[40:43], v[158:161], v[174:177], v[40:43]
	v_mfma_f32_16x16x32_bf16 v[28:31], v[150:153], v[182:185], v[28:31]
	v_mfma_f32_16x16x32_bf16 v[24:27], v[158:161], v[182:185], v[24:27]
	v_mfma_f32_16x16x32_bf16 v[12:15], v[150:153], v[190:193], v[12:15]
	v_mfma_f32_16x16x32_bf16 v[8:11], v[158:161], v[190:193], v[8:11]
	v_mfma_f32_16x16x32_bf16 v[60:63], v[154:157], v[170:173], v[60:63]
	v_mfma_f32_16x16x32_bf16 v[56:59], v[162:165], v[170:173], v[56:59]
	v_mfma_f32_16x16x32_bf16 v[44:47], v[154:157], v[178:181], v[44:47]
	v_mfma_f32_16x16x32_bf16 v[40:43], v[162:165], v[178:181], v[40:43]
	v_mfma_f32_16x16x32_bf16 v[28:31], v[154:157], v[186:189], v[28:31]
	v_mfma_f32_16x16x32_bf16 v[24:27], v[162:165], v[186:189], v[24:27]
	v_mfma_f32_16x16x32_bf16 v[12:15], v[154:157], v[194:197], v[12:15]
	v_mfma_f32_16x16x32_bf16 v[8:11], v[162:165], v[194:197], v[8:11]
	s_setprio 0
	s_barrier
	s_add_u32 s18, s18, 0x40080
	s_addc_u32 s19, s19, 0
	s_add_i32 s20, s20, s25
	s_mov_b32 m0, s20
	s_nop 0
	global_load_lds_dwordx4 v132, s[18:19]
	s_add_i32 m0, s20, 0x2000
	s_nop 0
	global_load_lds_dwordx4 v128, s[18:19]
	s_waitcnt vmcnt(10)
	s_barrier
	s_setprio 1
	v_mfma_f32_16x16x32_bf16 v[52:55], v[202:205], v[166:169], v[52:55]
	v_mfma_f32_16x16x32_bf16 v[48:51], v[210:213], v[166:169], v[48:51]
	v_mfma_f32_16x16x32_bf16 v[36:39], v[202:205], v[174:177], v[36:39]
	v_mfma_f32_16x16x32_bf16 v[32:35], v[210:213], v[174:177], v[32:35]
	v_mfma_f32_16x16x32_bf16 v[20:23], v[202:205], v[182:185], v[20:23]
	v_mfma_f32_16x16x32_bf16 v[16:19], v[210:213], v[182:185], v[16:19]
	v_mfma_f32_16x16x32_bf16 v[4:7], v[202:205], v[190:193], v[4:7]
	v_mfma_f32_16x16x32_bf16 v[0:3], v[210:213], v[190:193], v[0:3]
	v_mfma_f32_16x16x32_bf16 v[52:55], v[206:209], v[170:173], v[52:55]
	v_mfma_f32_16x16x32_bf16 v[48:51], v[214:217], v[170:173], v[48:51]
	v_mfma_f32_16x16x32_bf16 v[36:39], v[206:209], v[178:181], v[36:39]
	v_mfma_f32_16x16x32_bf16 v[32:35], v[214:217], v[178:181], v[32:35]
	v_mfma_f32_16x16x32_bf16 v[20:23], v[206:209], v[186:189], v[20:23]
	v_mfma_f32_16x16x32_bf16 v[16:19], v[214:217], v[186:189], v[16:19]
	v_mfma_f32_16x16x32_bf16 v[4:7], v[206:209], v[194:197], v[4:7]
	v_mfma_f32_16x16x32_bf16 v[0:3], v[214:217], v[194:197], v[0:3]
	s_setprio 0
	s_add_i32 s46, s46, 2
	s_add_u32 s16, s16, 0x100
	s_addc_u32 s17, s17, 0
	s_add_u32 s44, s44, 0x100
	s_addc_u32 s45, s45, 0
	s_cmp_gt_u32 s46, 13
	s_barrier
; __device__ __forceinline__ unsigned cvt_pk_bf16(float lo, float hi) { unsigned r; asm volatile("v_cvt_pk_bf16_f32 %0, %1, %2" : "=v"(r) : "v"(lo), "v"(hi)); return r; }
; __device__ __forceinline__ float silu_f(float a) { return a * __builtin_amdgcn_rcpf(1.0f + __expf(-a)); }
;     __device__ __forceinline__ void operator()(const AccT& acc, const Unit& u, int wr, int wc, int fr, int fq) const {
;         asm volatile("" : "+v"(fr), "+v"(fq));
;         const int row0 = u.pm * 256 + wr * 64 + fr, hc0 = u.pn * 128 + wc * 32 + 8 * fq;
; #pragma unroll
;         for (int ai = 0; ai < 2; ++ai)
; #pragma unroll
;             for (int m = 0; m < 4; ++m) {
;                 const f32x4 a0 = acc[ai][0][m][0], a1 = acc[ai][0][m][1], b0 = acc[ai][1][m][0], b1 = acc[ai][1][m][1];
;                 u32x4 w;
;                 w.x = cvt_pk_bf16(silu_f(a0[0]) * b0[0], silu_f(a0[1]) * b0[1]); w.y = cvt_pk_bf16(silu_f(a0[2]) * b0[2], silu_f(a0[3]) * b0[3]);
;                 w.z = cvt_pk_bf16(silu_f(a1[0]) * b1[0], silu_f(a1[1]) * b1[1]); w.w = cvt_pk_bf16(silu_f(a1[2]) * b1[2], silu_f(a1[3]) * b1[3]);
;                 *(u32x4*)(H + (size_t)(row0 + ai * 128 + m * 16) * DFF + hc0) = w;
;             }
	s_cbranch_scc0 .LBB0_1021
	v_mul_f32_e32 v152, 0xbfb8aa3b, v124
	v_mov_b32_e32 v150, v144
	v_mov_b32_e32 v151, v145
	s_lshl_b32 s5, s14, 8
	v_exp_f32_e32 v153, v152
	v_mul_f32_e32 v152, 0xbfb8aa3b, v125
	s_add_i32 s5, s5, s33
	v_exp_f32_e32 v154, v152
	v_add_u32_e32 v150, s5, v150
	s_lshl_b32 s5, s41, 7
	s_or_b32 s5, s5, s34
	v_lshl_add_u32 v152, v151, 3, s5
	v_add_f32_e32 v151, 1.0, v153
	v_rcp_f32_e32 v151, v151
	v_add_f32_e32 v153, 1.0, v154
	v_rcp_f32_e32 v154, v153
	v_ashrrev_i32_e32 v153, 31, v152
	v_mul_f32_e32 v124, v124, v151
	v_mul_f32_e32 v120, v124, v120
	v_mul_f32_e32 v124, v125, v154
	v_mul_f32_e32 v125, 0xbfb8aa3b, v126
	v_exp_f32_e32 v125, v125
	v_mul_f32_e32 v151, 0xbfb8aa3b, v127
	v_exp_f32_e32 v151, v151
	v_mul_f32_e32 v121, v124, v121
	v_add_f32_e32 v124, 1.0, v125
	v_rcp_f32_e32 v124, v124
	v_add_f32_e32 v125, 1.0, v151
	v_rcp_f32_e32 v125, v125
	v_cvt_pk_bf16_f32 v120, v120, v121
	v_mul_f32_e32 v121, v126, v124
	v_mul_f32_e32 v124, 0xbfb8aa3b, v116
	v_mul_f32_e32 v121, v121, v122
	v_mul_f32_e32 v122, v127, v125
	v_exp_f32_e32 v124, v124
	v_mul_f32_e32 v125, 0xbfb8aa3b, v117
	v_exp_f32_e32 v125, v125
	v_mul_f32_e32 v122, v122, v123
	v_add_f32_e32 v123, 1.0, v124
	v_rcp_f32_e32 v123, v123
	v_add_f32_e32 v124, 1.0, v125
	v_rcp_f32_e32 v124, v124
	v_cvt_pk_bf16_f32 v121, v121, v122
	v_mul_f32_e32 v116, v116, v123
	v_mul_f32_e32 v112, v116, v112
	v_mul_f32_e32 v116, v117, v124
	v_mul_f32_e32 v117, 0xbfb8aa3b, v118
	v_exp_f32_e32 v117, v117
	v_mul_f32_e32 v122, 0xbfb8aa3b, v119
	v_exp_f32_e32 v122, v122
	v_mul_f32_e32 v113, v116, v113
	v_add_f32_e32 v116, 1.0, v117
	v_rcp_f32_e32 v116, v116
	v_add_f32_e32 v117, 1.0, v122
	v_rcp_f32_e32 v117, v117
	v_cvt_pk_bf16_f32 v122, v112, v113
	v_mul_f32_e32 v112, v118, v116
	v_mul_f32_e32 v118, 0xbfb8aa3b, v108
	v_mul_f32_e32 v113, v119, v117
	v_exp_f32_e32 v118, v118
	v_mul_f32_e32 v119, 0xbfb8aa3b, v109
	v_exp_f32_e32 v119, v119
	v_mul_f32_e32 v112, v112, v114
	v_add_f32_e32 v118, 1.0, v118
	v_rcp_f32_e32 v118, v118
	v_add_f32_e32 v119, 1.0, v119
	v_rcp_f32_e32 v119, v119
	v_mul_f32_e32 v113, v113, v115
	v_cvt_pk_bf16_f32 v123, v112, v113
	v_mov_b64_e32 v[112:113], s[82:83]
	v_mad_i64_i32 v[116:117], s[16:17], v150, s40, v[112:113]
	v_lshlrev_b64 v[114:115], 1, v[152:153]
	v_mul_f32_e32 v108, v108, v118
	v_lshl_add_u64 v[116:117], v[116:117], 0, v[114:115]
	v_mul_f32_e32 v104, v108, v104
	v_mul_f32_e32 v108, v109, v119
	v_mul_f32_e32 v109, 0xbfb8aa3b, v110
	global_store_dwordx4 v[116:117], v[120:123], off
	v_exp_f32_e32 v109, v109
	v_mul_f32_e32 v116, 0xbfb8aa3b, v111
	v_exp_f32_e32 v116, v116
	v_mul_f32_e32 v105, v108, v105
	v_add_f32_e32 v108, 1.0, v109
	v_rcp_f32_e32 v108, v108
	v_add_f32_e32 v109, 1.0, v116
	v_rcp_f32_e32 v109, v109
	v_cvt_pk_bf16_f32 v104, v104, v105
	v_mul_f32_e32 v105, v110, v108
	v_mul_f32_e32 v108, 0xbfb8aa3b, v100
	v_mul_f32_e32 v105, v105, v106
	v_mul_f32_e32 v106, v111, v109
	v_exp_f32_e32 v108, v108
	v_mul_f32_e32 v109, 0xbfb8aa3b, v101
	v_exp_f32_e32 v109, v109
	v_mul_f32_e32 v106, v106, v107
	v_add_f32_e32 v107, 1.0, v108
	v_rcp_f32_e32 v107, v107
	v_add_f32_e32 v108, 1.0, v109
	v_rcp_f32_e32 v108, v108
	v_cvt_pk_bf16_f32 v105, v105, v106
	v_mul_f32_e32 v100, v100, v107
	v_mul_f32_e32 v96, v100, v96
	v_mul_f32_e32 v100, v101, v108
	v_mul_f32_e32 v101, 0xbfb8aa3b, v102
	v_exp_f32_e32 v101, v101
	v_mul_f32_e32 v106, 0xbfb8aa3b, v103
	v_exp_f32_e32 v106, v106
	v_mul_f32_e32 v97, v100, v97
	v_add_f32_e32 v100, 1.0, v101
	v_rcp_f32_e32 v100, v100
	v_add_f32_e32 v101, 1.0, v106
	v_rcp_f32_e32 v101, v101
	v_cvt_pk_bf16_f32 v106, v96, v97
	v_mul_f32_e32 v96, v102, v100
	v_mul_f32_e32 v96, v96, v98
	v_mul_f32_e32 v97, v103, v101
	v_mul_f32_e32 v98, 0xbfb8aa3b, v92
	v_mul_f32_e32 v97, v97, v99
	v_exp_f32_e32 v98, v98
	v_mul_f32_e32 v99, 0xbfb8aa3b, v93
	v_exp_f32_e32 v99, v99
	v_cvt_pk_bf16_f32 v107, v96, v97
	v_add_f32_e32 v98, 1.0, v98
	v_rcp_f32_e32 v98, v98
	v_add_f32_e32 v99, 1.0, v99
	v_rcp_f32_e32 v99, v99
	v_add_u32_e32 v96, 16, v150
	v_mad_i64_i32 v[96:97], s[16:17], v96, s40, v[112:113]
	v_mul_f32_e32 v92, v92, v98
	v_lshl_add_u64 v[96:97], v[96:97], 0, v[114:115]
	v_mul_f32_e32 v88, v92, v88
	v_mul_f32_e32 v92, v93, v99
	v_mul_f32_e32 v93, 0xbfb8aa3b, v94
	global_store_dwordx4 v[96:97], v[104:107], off
	v_exp_f32_e32 v93, v93
	v_mul_f32_e32 v96, 0xbfb8aa3b, v95
	v_exp_f32_e32 v96, v96
	v_mul_f32_e32 v89, v92, v89
	v_add_f32_e32 v92, 1.0, v93
	v_rcp_f32_e32 v92, v92
	v_add_f32_e32 v93, 1.0, v96
	v_rcp_f32_e32 v93, v93
	v_cvt_pk_bf16_f32 v88, v88, v89
	v_mul_f32_e32 v89, v94, v92
	v_mul_f32_e32 v92, 0xbfb8aa3b, v84
	v_mul_f32_e32 v89, v89, v90
	v_mul_f32_e32 v90, v95, v93
	v_exp_f32_e32 v92, v92
	v_mul_f32_e32 v93, 0xbfb8aa3b, v85
	v_exp_f32_e32 v93, v93
	v_mul_f32_e32 v90, v90, v91
	v_add_f32_e32 v91, 1.0, v92
	v_rcp_f32_e32 v91, v91
	v_add_f32_e32 v92, 1.0, v93
	v_rcp_f32_e32 v92, v92
	v_cvt_pk_bf16_f32 v89, v89, v90
	v_mul_f32_e32 v84, v84, v91
	v_mul_f32_e32 v80, v84, v80
	v_mul_f32_e32 v84, v85, v92
	v_mul_f32_e32 v85, 0xbfb8aa3b, v86
	v_exp_f32_e32 v85, v85
	v_mul_f32_e32 v90, 0xbfb8aa3b, v87
	v_exp_f32_e32 v90, v90
	v_mul_f32_e32 v81, v84, v81
	v_add_f32_e32 v84, 1.0, v85
	v_rcp_f32_e32 v84, v84
	v_add_f32_e32 v85, 1.0, v90
	v_rcp_f32_e32 v85, v85
	v_cvt_pk_bf16_f32 v90, v80, v81
	v_mul_f32_e32 v80, v86, v84
	v_mul_f32_e32 v80, v80, v82
	v_mul_f32_e32 v81, v87, v85
	v_mul_f32_e32 v82, 0xbfb8aa3b, v76
	v_mul_f32_e32 v81, v81, v83
	v_exp_f32_e32 v82, v82
	v_mul_f32_e32 v83, 0xbfb8aa3b, v77
	v_exp_f32_e32 v83, v83
	v_cvt_pk_bf16_f32 v91, v80, v81
	v_add_f32_e32 v82, 1.0, v82
	v_rcp_f32_e32 v82, v82
	v_add_f32_e32 v83, 1.0, v83
	v_rcp_f32_e32 v83, v83
; __device__ __forceinline__ unsigned cvt_pk_bf16(float lo, float hi) { unsigned r; asm volatile("v_cvt_pk_bf16_f32 %0, %1, %2" : "=v"(r) : "v"(lo), "v"(hi)); return r; }
; __device__ __forceinline__ float silu_f(float a) { return a * __builtin_amdgcn_rcpf(1.0f + __expf(-a)); }
;     __device__ __forceinline__ void operator()(const AccT& acc, const Unit& u, int wr, int wc, int fr, int fq) const {
;     ...
;         const int row0 = u.pm * 256 + wr * 64 + fr, hc0 = u.pn * 128 + wc * 32 + 8 * fq;
; #pragma unroll
;         for (int ai = 0; ai < 2; ++ai)
; #pragma unroll
;             for (int m = 0; m < 4; ++m) {
;                 const f32x4 a0 = acc[ai][0][m][0], a1 = acc[ai][0][m][1], b0 = acc[ai][1][m][0], b1 = acc[ai][1][m][1];
;                 u32x4 w;
;                 w.x = cvt_pk_bf16(silu_f(a0[0]) * b0[0], silu_f(a0[1]) * b0[1]); w.y = cvt_pk_bf16(silu_f(a0[2]) * b0[2], silu_f(a0[3]) * b0[3]);
;                 w.z = cvt_pk_bf16(silu_f(a1[0]) * b1[0], silu_f(a1[1]) * b1[1]); w.w = cvt_pk_bf16(silu_f(a1[2]) * b1[2], silu_f(a1[3]) * b1[3]);
;                 *(u32x4*)(H + (size_t)(row0 + ai * 128 + m * 16) * DFF + hc0) = w;
;             }
	v_add_u32_e32 v80, 32, v150
	v_mad_i64_i32 v[80:81], s[16:17], v80, s40, v[112:113]
	v_mul_f32_e32 v76, v76, v82
	v_lshl_add_u64 v[80:81], v[80:81], 0, v[114:115]
	v_mul_f32_e32 v72, v76, v72
	v_mul_f32_e32 v76, v77, v83
	v_mul_f32_e32 v77, 0xbfb8aa3b, v78
	global_store_dwordx4 v[80:81], v[88:91], off
	v_exp_f32_e32 v77, v77
	v_mul_f32_e32 v80, 0xbfb8aa3b, v79
	v_exp_f32_e32 v80, v80
	v_mul_f32_e32 v73, v76, v73
	v_add_f32_e32 v76, 1.0, v77
	v_rcp_f32_e32 v76, v76
	v_add_f32_e32 v77, 1.0, v80
	v_rcp_f32_e32 v77, v77
	v_cvt_pk_bf16_f32 v72, v72, v73
	v_mul_f32_e32 v73, v78, v76
	v_mul_f32_e32 v76, 0xbfb8aa3b, v68
	v_mul_f32_e32 v73, v73, v74
	v_mul_f32_e32 v74, v79, v77
	v_exp_f32_e32 v76, v76
	v_mul_f32_e32 v77, 0xbfb8aa3b, v69
	v_exp_f32_e32 v77, v77
	v_mul_f32_e32 v74, v74, v75
	v_add_f32_e32 v75, 1.0, v76
	v_rcp_f32_e32 v75, v75
	v_add_f32_e32 v76, 1.0, v77
	v_rcp_f32_e32 v76, v76
	v_cvt_pk_bf16_f32 v73, v73, v74
	v_mul_f32_e32 v68, v68, v75
	v_mul_f32_e32 v64, v68, v64
	v_mul_f32_e32 v68, v69, v76
	v_mul_f32_e32 v69, 0xbfb8aa3b, v70
	v_exp_f32_e32 v69, v69
	v_mul_f32_e32 v74, 0xbfb8aa3b, v71
	v_exp_f32_e32 v74, v74
	v_mul_f32_e32 v65, v68, v65
	v_add_f32_e32 v68, 1.0, v69
	v_rcp_f32_e32 v68, v68
	v_add_f32_e32 v69, 1.0, v74
	v_rcp_f32_e32 v69, v69
	v_cvt_pk_bf16_f32 v74, v64, v65
	v_mul_f32_e32 v64, v70, v68
	v_mul_f32_e32 v64, v64, v66
	v_mul_f32_e32 v65, v71, v69
	v_mul_f32_e32 v66, 0xbfb8aa3b, v60
	v_mul_f32_e32 v65, v65, v67
	v_exp_f32_e32 v66, v66
	v_mul_f32_e32 v67, 0xbfb8aa3b, v61
	v_cvt_pk_bf16_f32 v75, v64, v65
	v_add_u32_e32 v64, 48, v150
	v_exp_f32_e32 v67, v67
	v_mad_i64_i32 v[64:65], s[16:17], v64, s40, v[112:113]
	v_lshl_add_u64 v[64:65], v[64:65], 0, v[114:115]
	global_store_dwordx4 v[64:65], v[72:75], off
	v_add_f32_e32 v64, 1.0, v66
	v_rcp_f32_e32 v64, v64
	v_add_f32_e32 v65, 1.0, v67
	v_rcp_f32_e32 v65, v65
	v_add_u32_e32 v66, 0x80, v150
	v_mul_f32_e32 v60, v60, v64
	v_mul_f32_e32 v52, v60, v52
	v_mul_f32_e32 v60, v61, v65
	v_mul_f32_e32 v61, 0xbfb8aa3b, v62
	v_exp_f32_e32 v61, v61
	v_mul_f32_e32 v64, 0xbfb8aa3b, v63
	v_exp_f32_e32 v64, v64
	v_mul_f32_e32 v53, v60, v53
	v_add_f32_e32 v60, 1.0, v61
	v_rcp_f32_e32 v60, v60
	v_add_f32_e32 v61, 1.0, v64
	v_rcp_f32_e32 v61, v61
	v_cvt_pk_bf16_f32 v52, v52, v53
	v_mul_f32_e32 v53, v62, v60
	v_mul_f32_e32 v60, 0xbfb8aa3b, v56
	v_exp_f32_e32 v60, v60
	v_mul_f32_e32 v53, v53, v54
	v_mul_f32_e32 v54, v63, v61
	v_mul_f32_e32 v61, 0xbfb8aa3b, v57
	v_exp_f32_e32 v61, v61
	v_mul_f32_e32 v54, v54, v55
	v_add_f32_e32 v55, 1.0, v60
	v_rcp_f32_e32 v55, v55
	v_add_f32_e32 v60, 1.0, v61
	v_rcp_f32_e32 v60, v60
	v_cvt_pk_bf16_f32 v53, v53, v54
	v_mul_f32_e32 v54, v56, v55
	v_mul_f32_e32 v55, 0xbfb8aa3b, v58
	v_exp_f32_e32 v55, v55
	v_mul_f32_e32 v56, 0xbfb8aa3b, v59
	v_exp_f32_e32 v56, v56
	v_mul_f32_e32 v48, v54, v48
	v_mul_f32_e32 v54, v57, v60
	v_mul_f32_e32 v49, v54, v49
	v_add_f32_e32 v54, 1.0, v55
	v_rcp_f32_e32 v55, v54
	v_add_f32_e32 v54, 1.0, v56
	v_rcp_f32_e32 v56, v54
	v_cvt_pk_bf16_f32 v54, v48, v49
	v_mul_f32_e32 v48, v58, v55
	v_mul_f32_e32 v48, v48, v50
	v_mul_f32_e32 v49, v59, v56
	v_mul_f32_e32 v50, 0xbfb8aa3b, v44
	v_mul_f32_e32 v49, v49, v51
	v_exp_f32_e32 v50, v50
	v_mul_f32_e32 v51, 0xbfb8aa3b, v45
	v_exp_f32_e32 v51, v51
	v_cvt_pk_bf16_f32 v55, v48, v49
	v_add_f32_e32 v50, 1.0, v50
	v_rcp_f32_e32 v50, v50
	v_add_f32_e32 v51, 1.0, v51
	v_rcp_f32_e32 v51, v51
	v_mad_i64_i32 v[48:49], s[16:17], v66, s40, v[112:113]
	v_mul_f32_e32 v44, v44, v50
	v_mul_f32_e32 v36, v44, v36
	v_mul_f32_e32 v44, v45, v51
	v_mul_f32_e32 v45, 0xbfb8aa3b, v46
	v_exp_f32_e32 v45, v45
	v_lshl_add_u64 v[48:49], v[48:49], 0, v[114:115]
	global_store_dwordx4 v[48:49], v[52:55], off
	v_mul_f32_e32 v48, 0xbfb8aa3b, v47
	v_exp_f32_e32 v48, v48
	v_mul_f32_e32 v37, v44, v37
	v_add_f32_e32 v44, 1.0, v45
	v_rcp_f32_e32 v44, v44
	v_add_f32_e32 v45, 1.0, v48
	v_rcp_f32_e32 v45, v45
	v_cvt_pk_bf16_f32 v36, v36, v37
	v_mul_f32_e32 v37, v46, v44
	v_mul_f32_e32 v44, 0xbfb8aa3b, v40
	v_exp_f32_e32 v44, v44
	v_mul_f32_e32 v37, v37, v38
	v_mul_f32_e32 v38, v47, v45
	v_mul_f32_e32 v45, 0xbfb8aa3b, v41
	v_exp_f32_e32 v45, v45
	v_mul_f32_e32 v38, v38, v39
	v_add_f32_e32 v39, 1.0, v44
	v_rcp_f32_e32 v39, v39
	v_add_f32_e32 v44, 1.0, v45
	v_rcp_f32_e32 v44, v44
; __device__ __forceinline__ unsigned cvt_pk_bf16(float lo, float hi) { unsigned r; asm volatile("v_cvt_pk_bf16_f32 %0, %1, %2" : "=v"(r) : "v"(lo), "v"(hi)); return r; }
; __device__ __forceinline__ float silu_f(float a) { return a * __builtin_amdgcn_rcpf(1.0f + __expf(-a)); }
; #define PG8_WAIT_V(n) asm volatile("s_waitcnt vmcnt(" #n ")" ::: "memory")
; #define PG8_BAR __builtin_amdgcn_s_barrier()
; template <class Epi, class Sched>
; __device__ __forceinline__ void gemm_phase(LAS unsigned char* lds, const Gemm g, const Sched& S, const Epi& E) {
;     ...
;     PG8_WAIT_V(0);
;     if (wr == 0) PG8_BAR;
;     PG8_BAR;
;     __device__ __forceinline__ void operator()(const AccT& acc, const Unit& u, int wr, int wc, int fr, int fq) const {
;     ...
;         for (int ai = 0; ai < 2; ++ai)
; #pragma unroll
;             for (int m = 0; m < 4; ++m) {
;                 const f32x4 a0 = acc[ai][0][m][0], a1 = acc[ai][0][m][1], b0 = acc[ai][1][m][0], b1 = acc[ai][1][m][1];
;                 u32x4 w;
;                 w.x = cvt_pk_bf16(silu_f(a0[0]) * b0[0], silu_f(a0[1]) * b0[1]); w.y = cvt_pk_bf16(silu_f(a0[2]) * b0[2], silu_f(a0[3]) * b0[3]);
;                 w.z = cvt_pk_bf16(silu_f(a1[0]) * b1[0], silu_f(a1[1]) * b1[1]); w.w = cvt_pk_bf16(silu_f(a1[2]) * b1[2], silu_f(a1[3]) * b1[3]);
;                 *(u32x4*)(H + (size_t)(row0 + ai * 128 + m * 16) * DFF + hc0) = w;
;             }
	v_cvt_pk_bf16_f32 v37, v37, v38
	v_mul_f32_e32 v38, v40, v39
	v_mul_f32_e32 v39, 0xbfb8aa3b, v42
	v_exp_f32_e32 v39, v39
	v_mul_f32_e32 v40, 0xbfb8aa3b, v43
	v_exp_f32_e32 v40, v40
	v_mul_f32_e32 v32, v38, v32
	v_mul_f32_e32 v38, v41, v44
	v_mul_f32_e32 v33, v38, v33
	v_add_f32_e32 v38, 1.0, v39
	v_rcp_f32_e32 v39, v38
	v_add_f32_e32 v38, 1.0, v40
	v_rcp_f32_e32 v40, v38
	v_cvt_pk_bf16_f32 v38, v32, v33
	v_mul_f32_e32 v32, v42, v39
	v_mul_f32_e32 v32, v32, v34
	v_mul_f32_e32 v33, v43, v40
	v_mul_f32_e32 v34, 0xbfb8aa3b, v28
	v_mul_f32_e32 v33, v33, v35
	v_exp_f32_e32 v34, v34
	v_mul_f32_e32 v35, 0xbfb8aa3b, v29
	v_exp_f32_e32 v35, v35
	v_cvt_pk_bf16_f32 v39, v32, v33
	v_add_f32_e32 v34, 1.0, v34
	v_rcp_f32_e32 v34, v34
	v_add_f32_e32 v35, 1.0, v35
	v_rcp_f32_e32 v35, v35
	v_add_u32_e32 v32, 0x90, v150
	v_mul_f32_e32 v28, v28, v34
	v_mul_f32_e32 v20, v28, v20
	v_mul_f32_e32 v28, v29, v35
	v_mul_f32_e32 v29, 0xbfb8aa3b, v30
	v_exp_f32_e32 v29, v29
	v_mad_i64_i32 v[32:33], s[16:17], v32, s40, v[112:113]
	v_lshl_add_u64 v[32:33], v[32:33], 0, v[114:115]
	global_store_dwordx4 v[32:33], v[36:39], off
	v_mul_f32_e32 v32, 0xbfb8aa3b, v31
	v_exp_f32_e32 v32, v32
	v_mul_f32_e32 v21, v28, v21
	v_add_f32_e32 v28, 1.0, v29
	v_rcp_f32_e32 v28, v28
	v_add_f32_e32 v29, 1.0, v32
	v_rcp_f32_e32 v29, v29
	v_cvt_pk_bf16_f32 v20, v20, v21
	v_mul_f32_e32 v21, v30, v28
	v_mul_f32_e32 v28, 0xbfb8aa3b, v24
	v_exp_f32_e32 v28, v28
	v_mul_f32_e32 v21, v21, v22
	v_mul_f32_e32 v22, v31, v29
	v_mul_f32_e32 v29, 0xbfb8aa3b, v25
	v_exp_f32_e32 v29, v29
	v_mul_f32_e32 v22, v22, v23
	v_add_f32_e32 v23, 1.0, v28
	v_rcp_f32_e32 v23, v23
	v_add_f32_e32 v28, 1.0, v29
	v_rcp_f32_e32 v28, v28
	v_cvt_pk_bf16_f32 v21, v21, v22
	v_mul_f32_e32 v22, v24, v23
	v_mul_f32_e32 v23, 0xbfb8aa3b, v26
	v_exp_f32_e32 v23, v23
	v_mul_f32_e32 v24, 0xbfb8aa3b, v27
	v_exp_f32_e32 v24, v24
	v_mul_f32_e32 v16, v22, v16
	v_mul_f32_e32 v22, v25, v28
	v_mul_f32_e32 v17, v22, v17
	v_add_f32_e32 v22, 1.0, v23
	v_rcp_f32_e32 v23, v22
	v_add_f32_e32 v22, 1.0, v24
	v_rcp_f32_e32 v24, v22
	v_cvt_pk_bf16_f32 v22, v16, v17
	v_mul_f32_e32 v16, v26, v23
	v_mul_f32_e32 v16, v16, v18
	v_mul_f32_e32 v17, v27, v24
	v_mul_f32_e32 v18, 0xbfb8aa3b, v12
	v_mul_f32_e32 v17, v17, v19
	v_exp_f32_e32 v18, v18
	v_mul_f32_e32 v19, 0xbfb8aa3b, v13
	v_exp_f32_e32 v19, v19
	v_cvt_pk_bf16_f32 v23, v16, v17
	v_add_f32_e32 v18, 1.0, v18
	v_rcp_f32_e32 v18, v18
	v_add_f32_e32 v19, 1.0, v19
	v_rcp_f32_e32 v19, v19
	v_add_u32_e32 v16, 0xa0, v150
	v_mul_f32_e32 v12, v12, v18
	v_mul_f32_e32 v4, v12, v4
	v_mul_f32_e32 v12, v13, v19
	v_mul_f32_e32 v13, 0xbfb8aa3b, v14
	v_exp_f32_e32 v13, v13
	v_mad_i64_i32 v[16:17], s[16:17], v16, s40, v[112:113]
	v_lshl_add_u64 v[16:17], v[16:17], 0, v[114:115]
	global_store_dwordx4 v[16:17], v[20:23], off
	v_mul_f32_e32 v16, 0xbfb8aa3b, v15
	v_exp_f32_e32 v16, v16
	v_mul_f32_e32 v5, v12, v5
	v_add_f32_e32 v12, 1.0, v13
	v_rcp_f32_e32 v12, v12
	v_add_f32_e32 v13, 1.0, v16
	v_rcp_f32_e32 v13, v13
	v_cvt_pk_bf16_f32 v4, v4, v5
	v_mul_f32_e32 v5, v14, v12
	v_mul_f32_e32 v12, 0xbfb8aa3b, v8
	v_exp_f32_e32 v12, v12
	v_mul_f32_e32 v5, v5, v6
	v_mul_f32_e32 v6, v15, v13
	v_mul_f32_e32 v13, 0xbfb8aa3b, v9
	v_exp_f32_e32 v13, v13
	v_mul_f32_e32 v6, v6, v7
	v_add_f32_e32 v7, 1.0, v12
	v_rcp_f32_e32 v7, v7
	v_add_f32_e32 v12, 1.0, v13
	v_rcp_f32_e32 v12, v12
	v_cvt_pk_bf16_f32 v5, v5, v6
	v_mul_f32_e32 v6, v8, v7
	v_mul_f32_e32 v7, 0xbfb8aa3b, v10
	v_exp_f32_e32 v7, v7
	v_mul_f32_e32 v8, 0xbfb8aa3b, v11
	v_exp_f32_e32 v8, v8
	v_mul_f32_e32 v0, v6, v0
	v_mul_f32_e32 v6, v9, v12
	v_mul_f32_e32 v1, v6, v1
	v_add_f32_e32 v6, 1.0, v7
	v_rcp_f32_e32 v7, v6
	v_add_f32_e32 v6, 1.0, v8
	v_rcp_f32_e32 v8, v6
	v_cvt_pk_bf16_f32 v6, v0, v1
	v_mul_f32_e32 v0, v10, v7
	v_mul_f32_e32 v0, v0, v2
	v_mul_f32_e32 v1, v11, v8
	v_mul_f32_e32 v1, v1, v3
	v_cvt_pk_bf16_f32 v7, v0, v1
	v_add_u32_e32 v0, 0xb0, v150
	v_mad_i64_i32 v[0:1], s[16:17], v0, s40, v[112:113]
	v_lshl_add_u64 v[0:1], v[0:1], 0, v[114:115]
	s_and_b64 vcc, exec, s[2:3]
	s_mov_b32 s41, s4
	s_mov_b32 s14, s6
	s_mov_b64 s[18:19], s[12:13]
	s_mov_b64 s[16:17], s[10:11]
	global_store_dwordx4 v[0:1], v[4:7], off
	s_cbranch_vccz .LBB0_1018
	s_waitcnt vmcnt(0)
	s_cmpk_gt_u32 s22, 0xff
	s_cbranch_scc1 .LBB0_1025
	s_barrier

; #define PG8_STAGE(bufoff, gbase, voff) do { _Pragma("unroll") for (int _i = 0; _i < 2; ++_i) \
;         __builtin_amdgcn_global_load_lds((const unsigned*)((const char*)(gbase) + (voff)[_i]), (LAS unsigned*)(lds + (bufoff) + ldsw + _i * 8192), 16, 0, 0); } while (0)
; #define PG8_LDA(dst, b, h) do { _Pragma("unroll") for (int m = 0; m < 4; ++m) _Pragma("unroll") for (int k = 0; k < 2; ++k) dst[m][k] = *(const LAS bf16x8*)(lds + PG8_SA(b, h) + aoff + m * 2048 + k * 1024); } while (0)
; #define PG8_LDB(dst, b, h) do { _Pragma("unroll") for (int n = 0; n < 2; ++n) _Pragma("unroll") for (int k = 0; k < 2; ++k) dst[n][k] = *(const LAS bf16x8*)(lds + PG8_SB(b, h) + boff + n * 2048 + k * 1024); } while (0)
; #define PG8_MMA(ai, bj, At, Bt) do { __builtin_amdgcn_s_setprio(1); _Pragma("unroll") for (int m = 0; m < 4; ++m) _Pragma("unroll") for (int n = 0; n < 2; ++n) _Pragma("unroll") for (int k = 0; k < 2; ++k) \
;         acc[ai][bj][m][n] = __builtin_amdgcn_mfma_f32_16x16x32_bf16(Bt[n][k], At[m][k], acc[ai][bj][m][n], 0, 0, 0); __builtin_amdgcn_s_setprio(0); } while (0)
; #define PG8_WAIT_V(n) asm volatile("s_waitcnt vmcnt(" #n ")" ::: "memory")
; #define PG8_WAIT_L(n) asm volatile("s_waitcnt lgkmcnt(" #n ")" ::: "memory")
; template <class Epi, class Sched>
; __device__ __forceinline__ void gemm_phase(LAS unsigned char* lds, const Gemm g, const Sched& S, const Epi& E) {
;     ...
;         for (int t = 0; t < nt; t += 2) {
;             const bool last = (t == nt - 2);
;             const char* a1 = cA + (size_t)(t + 1) * kstep;
;             const char* a2 = last ? nA : cA + (size_t)(t + 2) * kstep; const char* b2 = last ? nB : cB + (size_t)(t + 2) * kstep;
;             const char* a3 = a2 + kstep; const char* b3 = b2 + kstep;
;             PG8_LDB(B0, 0, 0); PG8_SCHED; PG8_LDA(At, 0, 0); PG8_STAGE(PG8_SA(1, 1), a1 + hstep, voffA);
;             PG8_WAIT_L(8); PG8_BAR; PG8_WAIT_L(0); PG8_MMA(0, 0, At, B0); PG8_BAR; PG8_SCHED;
;             PG8_LDB(B1, 0, 1); PG8_STAGE(PG8_SB(0, 0), b2, voffB);
;             PG8_BAR; PG8_WAIT_L(0); PG8_MMA(0, 1, At, B1); PG8_BAR;
;             PG8_LDA(At, 0, 1); PG8_STAGE(PG8_SA(0, 0), a2, voffA);
;             PG8_BAR; PG8_WAIT_L(0); PG8_MMA(1, 0, At, B0); PG8_BAR; PG8_SCHED;
;             PG8_STAGE(PG8_SB(0, 1), b2 + hstep, voffB);
;             PG8_WAIT_V(6); PG8_BAR; PG8_MMA(1, 1, At, B1); PG8_BAR;
.LBB0_1096:
	s_add_u32 s54, s24, 0x100
	s_addc_u32 s55, s25, 0
	s_mov_b32 s56, -2
	ds_read_b128 v[128:131], v241
	ds_read_b128 v[132:135], v241 offset:1024
	ds_read_b128 v[136:139], v241 offset:2048
	ds_read_b128 v[140:143], v241 offset:3072
	s_add_u32 s24, s22, 0x100
	s_addc_u32 s25, s23, 0
	s_cmp_eq_u32 s56, 40
	s_cselect_b32 s29, s5, s25
	s_cselect_b32 s28, s4, s24
	s_cselect_b32 s27, s7, s55
	s_cselect_b32 s26, s6, s54
	v_lshl_add_u64 v[176:177], s[22:23], 0, v[196:197]
	s_add_i32 m0, s35, 0xc000
	ds_read_b128 v[144:147], v242
	ds_read_b128 v[148:151], v242 offset:1024
	ds_read_b128 v[152:155], v242 offset:2048
	ds_read_b128 v[156:159], v242 offset:3072
	ds_read_b128 v[160:163], v242 offset:4096
	ds_read_b128 v[164:167], v242 offset:5120
	ds_read_b128 v[168:171], v242 offset:6144
	ds_read_b128 v[172:175], v242 offset:7168
	global_load_lds_dwordx4 v[176:177], off
	v_lshl_add_u64 v[176:177], s[22:23], 0, v[198:199]
	s_add_i32 m0, s35, 0xe000
	s_nop 0
	global_load_lds_dwordx4 v[176:177], off
	s_waitcnt lgkmcnt(8)
	s_waitcnt vmcnt(10)
	s_barrier
	s_waitcnt lgkmcnt(0)
	s_setprio 1
	s_waitcnt lgkmcnt(0)
	v_mfma_f32_16x16x32_bf16 v[124:127], v[128:131], v[144:147], 0
	v_mfma_f32_16x16x32_bf16 v[120:123], v[136:139], v[144:147], 0
	v_mfma_f32_16x16x32_bf16 v[108:111], v[128:131], v[152:155], 0
	v_mfma_f32_16x16x32_bf16 v[104:107], v[136:139], v[152:155], 0
	v_mfma_f32_16x16x32_bf16 v[92:95], v[128:131], v[160:163], 0
	v_mfma_f32_16x16x32_bf16 v[88:91], v[136:139], v[160:163], 0
	v_mfma_f32_16x16x32_bf16 v[76:79], v[128:131], v[168:171], 0
	v_mfma_f32_16x16x32_bf16 v[72:75], v[136:139], v[168:171], 0
	v_mfma_f32_16x16x32_bf16 v[124:127], v[132:135], v[148:151], v[124:127]
	v_mfma_f32_16x16x32_bf16 v[120:123], v[140:143], v[148:151], v[120:123]
	v_mfma_f32_16x16x32_bf16 v[108:111], v[132:135], v[156:159], v[108:111]
	v_mfma_f32_16x16x32_bf16 v[104:107], v[140:143], v[156:159], v[104:107]
	v_mfma_f32_16x16x32_bf16 v[92:95], v[132:135], v[164:167], v[92:95]
	v_mfma_f32_16x16x32_bf16 v[88:91], v[140:143], v[164:167], v[88:91]
	v_mfma_f32_16x16x32_bf16 v[76:79], v[132:135], v[172:175], v[76:79]
	v_mfma_f32_16x16x32_bf16 v[72:75], v[140:143], v[172:175], v[72:75]
	s_setprio 0
	s_barrier
	s_add_i32 s22, s48, s34
	s_mov_b32 m0, s22
	ds_read_b128 v[176:179], v243
	ds_read_b128 v[180:183], v243 offset:1024
	ds_read_b128 v[184:187], v243 offset:2048
	ds_read_b128 v[206:209], v243 offset:3072
	global_load_lds_dwordx4 v190, s[26:27]
	s_add_i32 m0, s22, 0x2000
	s_nop 0
	global_load_lds_dwordx4 v194, s[26:27]
	s_waitcnt vmcnt(10)
	s_barrier
	s_waitcnt lgkmcnt(0)
	s_setprio 1
	s_waitcnt lgkmcnt(0)
	v_mfma_f32_16x16x32_bf16 v[116:119], v[176:179], v[144:147], 0
	v_mfma_f32_16x16x32_bf16 v[112:115], v[184:187], v[144:147], 0
	v_mfma_f32_16x16x32_bf16 v[100:103], v[176:179], v[152:155], 0
	v_mfma_f32_16x16x32_bf16 v[96:99], v[184:187], v[152:155], 0
	v_mfma_f32_16x16x32_bf16 v[84:87], v[176:179], v[160:163], 0
	v_mfma_f32_16x16x32_bf16 v[80:83], v[184:187], v[160:163], 0
	v_mfma_f32_16x16x32_bf16 v[68:71], v[176:179], v[168:171], 0
	v_mfma_f32_16x16x32_bf16 v[64:67], v[184:187], v[168:171], 0
	v_mfma_f32_16x16x32_bf16 v[116:119], v[180:183], v[148:151], v[116:119]
	v_mfma_f32_16x16x32_bf16 v[112:115], v[206:209], v[148:151], v[112:115]
	v_mfma_f32_16x16x32_bf16 v[100:103], v[180:183], v[156:159], v[100:103]
	v_mfma_f32_16x16x32_bf16 v[96:99], v[206:209], v[156:159], v[96:99]
	v_mfma_f32_16x16x32_bf16 v[84:87], v[180:183], v[164:167], v[84:87]
	v_mfma_f32_16x16x32_bf16 v[80:83], v[206:209], v[164:167], v[80:83]
	v_mfma_f32_16x16x32_bf16 v[68:71], v[180:183], v[172:175], v[68:71]
	v_mfma_f32_16x16x32_bf16 v[64:67], v[206:209], v[172:175], v[64:67]
	s_setprio 0
	s_mov_b32 m0, s35
	v_lshl_add_u64 v[214:215], s[28:29], 0, v[188:189]
	s_barrier
	ds_read_b128 v[144:147], v242 offset:16384
	ds_read_b128 v[148:151], v242 offset:17408
	ds_read_b128 v[152:155], v242 offset:18432
	ds_read_b128 v[156:159], v242 offset:19456
	ds_read_b128 v[160:163], v242 offset:20480
	ds_read_b128 v[164:167], v242 offset:21504
	ds_read_b128 v[168:171], v242 offset:22528
	ds_read_b128 v[172:175], v242 offset:23552
	global_load_lds_dwordx4 v188, s[28:29]
	v_lshl_add_u64 v[216:217], s[28:29], 0, v[192:193]
	s_mov_b32 m0, s36
	s_nop 0
	global_load_lds_dwordx4 v192, s[28:29]
	s_barrier
	s_waitcnt lgkmcnt(0)
	s_setprio 1
	s_waitcnt lgkmcnt(0)
	v_mfma_f32_16x16x32_bf16 v[60:63], v[128:131], v[144:147], 0
	v_mfma_f32_16x16x32_bf16 v[56:59], v[136:139], v[144:147], 0
	v_mfma_f32_16x16x32_bf16 v[44:47], v[128:131], v[152:155], 0
	v_mfma_f32_16x16x32_bf16 v[40:43], v[136:139], v[152:155], 0
	v_mfma_f32_16x16x32_bf16 v[28:31], v[128:131], v[160:163], 0
	v_mfma_f32_16x16x32_bf16 v[24:27], v[136:139], v[160:163], 0
	v_mfma_f32_16x16x32_bf16 v[12:15], v[128:131], v[168:171], 0
	v_mfma_f32_16x16x32_bf16 v[8:11], v[136:139], v[168:171], 0
	v_mfma_f32_16x16x32_bf16 v[60:63], v[132:135], v[148:151], v[60:63]
	v_mfma_f32_16x16x32_bf16 v[56:59], v[140:143], v[148:151], v[56:59]
	v_mfma_f32_16x16x32_bf16 v[44:47], v[132:135], v[156:159], v[44:47]
	v_mfma_f32_16x16x32_bf16 v[40:43], v[140:143], v[156:159], v[40:43]
	v_mfma_f32_16x16x32_bf16 v[28:31], v[132:135], v[164:167], v[28:31]
	v_mfma_f32_16x16x32_bf16 v[24:27], v[140:143], v[164:167], v[24:27]
	v_mfma_f32_16x16x32_bf16 v[12:15], v[132:135], v[172:175], v[12:15]
	v_mfma_f32_16x16x32_bf16 v[8:11], v[140:143], v[172:175], v[8:11]
	s_setprio 0
	s_barrier
; #define PG8_STAGE(bufoff, gbase, voff) do { _Pragma("unroll") for (int _i = 0; _i < 2; ++_i) \
;         __builtin_amdgcn_global_load_lds((const unsigned*)((const char*)(gbase) + (voff)[_i]), (LAS unsigned*)(lds + (bufoff) + ldsw + _i * 8192), 16, 0, 0); } while (0)
; #define PG8_LDA(dst, b, h) do { _Pragma("unroll") for (int m = 0; m < 4; ++m) _Pragma("unroll") for (int k = 0; k < 2; ++k) dst[m][k] = *(const LAS bf16x8*)(lds + PG8_SA(b, h) + aoff + m * 2048 + k * 1024); } while (0)
; #define PG8_LDB(dst, b, h) do { _Pragma("unroll") for (int n = 0; n < 2; ++n) _Pragma("unroll") for (int k = 0; k < 2; ++k) dst[n][k] = *(const LAS bf16x8*)(lds + PG8_SB(b, h) + boff + n * 2048 + k * 1024); } while (0)
; #define PG8_MMA(ai, bj, At, Bt) do { __builtin_amdgcn_s_setprio(1); _Pragma("unroll") for (int m = 0; m < 4; ++m) _Pragma("unroll") for (int n = 0; n < 2; ++n) _Pragma("unroll") for (int k = 0; k < 2; ++k) \
;         acc[ai][bj][m][n] = __builtin_amdgcn_mfma_f32_16x16x32_bf16(Bt[n][k], At[m][k], acc[ai][bj][m][n], 0, 0, 0); __builtin_amdgcn_s_setprio(0); } while (0)
; #define PG8_WAIT_V(n) asm volatile("s_waitcnt vmcnt(" #n ")" ::: "memory")
; #define PG8_WAIT_L(n) asm volatile("s_waitcnt lgkmcnt(" #n ")" ::: "memory")
; #define PG8_BAR __builtin_amdgcn_s_barrier()
; #define PG8_SCHED __builtin_amdgcn_sched_barrier(0)
; template <class Epi, class Sched>
; __device__ __forceinline__ void gemm_phase(LAS unsigned char* lds, const Gemm g, const Sched& S, const Epi& E) {
;     ...
;             PG8_STAGE(PG8_SB(0, 1), b2 + hstep, voffB);
;             PG8_WAIT_V(6); PG8_BAR; PG8_MMA(1, 1, At, B1); PG8_BAR;
;             PG8_LDB(B0, 1, 0); PG8_SCHED; PG8_LDA(At, 1, 0); PG8_STAGE(PG8_SA(0, 1), a2 + hstep, voffA);
;             PG8_WAIT_L(8); PG8_BAR; PG8_WAIT_L(0); PG8_MMA(0, 0, At, B0); PG8_BAR; PG8_SCHED;
;             PG8_LDB(B1, 1, 1); PG8_STAGE(PG8_SB(1, 0), b3, voffB);
;             PG8_BAR; PG8_WAIT_L(0); PG8_MMA(0, 1, At, B1); PG8_BAR;
;             PG8_LDA(At, 1, 1); PG8_STAGE(PG8_SA(1, 0), a3, voffA);
;             PG8_BAR; PG8_WAIT_L(0); PG8_MMA(1, 0, At, B0); PG8_BAR; PG8_SCHED;
	s_add_u32 s22, s26, 0xb0000
	s_addc_u32 s23, s27, 0
	s_add_i32 s57, s49, s34
	s_mov_b32 m0, s57
	s_nop 0
	global_load_lds_dwordx4 v190, s[22:23]
	s_add_i32 m0, s57, 0x2000
	s_nop 0
	global_load_lds_dwordx4 v194, s[22:23]
	s_add_u32 s22, s28, 0xb0000
	s_addc_u32 s23, s29, 0
	s_mov_b32 m0, s37
	s_nop 0
	global_load_lds_dwordx4 v188, s[22:23]
	s_mov_b32 m0, s38
	s_nop 0
	global_load_lds_dwordx4 v192, s[22:23]
	s_waitcnt vmcnt(12)
	s_barrier
	s_setprio 1
	v_mfma_f32_16x16x32_bf16 v[52:55], v[176:179], v[144:147], 0
	v_mfma_f32_16x16x32_bf16 v[48:51], v[184:187], v[144:147], 0
	v_mfma_f32_16x16x32_bf16 v[36:39], v[176:179], v[152:155], 0
	v_mfma_f32_16x16x32_bf16 v[32:35], v[184:187], v[152:155], 0
	v_mfma_f32_16x16x32_bf16 v[20:23], v[176:179], v[160:163], 0
	v_mfma_f32_16x16x32_bf16 v[16:19], v[184:187], v[160:163], 0
	v_mfma_f32_16x16x32_bf16 v[4:7], v[176:179], v[168:171], 0
	v_mfma_f32_16x16x32_bf16 v[0:3], v[184:187], v[168:171], 0
	v_mfma_f32_16x16x32_bf16 v[52:55], v[180:183], v[148:151], v[52:55]
	v_mfma_f32_16x16x32_bf16 v[48:51], v[206:209], v[148:151], v[48:51]
	v_mfma_f32_16x16x32_bf16 v[36:39], v[180:183], v[156:159], v[36:39]
	v_mfma_f32_16x16x32_bf16 v[32:35], v[206:209], v[156:159], v[32:35]
	v_mfma_f32_16x16x32_bf16 v[20:23], v[180:183], v[164:167], v[20:23]
	v_mfma_f32_16x16x32_bf16 v[16:19], v[206:209], v[164:167], v[16:19]
	v_mfma_f32_16x16x32_bf16 v[4:7], v[180:183], v[172:175], v[4:7]
	v_mfma_f32_16x16x32_bf16 v[0:3], v[206:209], v[172:175], v[0:3]
	s_setprio 0
	s_add_i32 s57, 0, 0x18000
	v_add_u32_e32 v140, s57, v240
	s_barrier
	ds_read_b128 v[128:131], v140
	ds_read_b128 v[132:135], v140 offset:1024
	ds_read_b128 v[136:139], v140 offset:2048
	ds_read_b128 v[140:143], v140 offset:3072
	ds_read_b128 v[144:147], v242 offset:32768
	ds_read_b128 v[148:151], v242 offset:33792
	ds_read_b128 v[152:155], v242 offset:34816
	ds_read_b128 v[156:159], v242 offset:35840
	ds_read_b128 v[160:163], v242 offset:36864
	ds_read_b128 v[164:167], v242 offset:37888
	ds_read_b128 v[168:171], v242 offset:38912
	ds_read_b128 v[172:175], v242 offset:39936
	s_waitcnt lgkmcnt(8)
	s_waitcnt vmcnt(10)
	s_barrier
	s_waitcnt lgkmcnt(0)
	s_setprio 1
	s_waitcnt lgkmcnt(0)
	v_mfma_f32_16x16x32_bf16 v[124:127], v[128:131], v[144:147], v[124:127]
	v_mfma_f32_16x16x32_bf16 v[120:123], v[136:139], v[144:147], v[120:123]
	v_mfma_f32_16x16x32_bf16 v[108:111], v[128:131], v[152:155], v[108:111]
	v_mfma_f32_16x16x32_bf16 v[104:107], v[136:139], v[152:155], v[104:107]
	v_mfma_f32_16x16x32_bf16 v[92:95], v[128:131], v[160:163], v[92:95]
	v_mfma_f32_16x16x32_bf16 v[88:91], v[136:139], v[160:163], v[88:91]
	v_mfma_f32_16x16x32_bf16 v[76:79], v[128:131], v[168:171], v[76:79]
	v_mfma_f32_16x16x32_bf16 v[72:75], v[136:139], v[168:171], v[72:75]
	v_mfma_f32_16x16x32_bf16 v[124:127], v[132:135], v[148:151], v[124:127]
	v_mfma_f32_16x16x32_bf16 v[120:123], v[140:143], v[148:151], v[120:123]
	v_mfma_f32_16x16x32_bf16 v[108:111], v[132:135], v[156:159], v[108:111]
	v_mfma_f32_16x16x32_bf16 v[104:107], v[140:143], v[156:159], v[104:107]
	v_mfma_f32_16x16x32_bf16 v[92:95], v[132:135], v[164:167], v[92:95]
	v_mfma_f32_16x16x32_bf16 v[88:91], v[140:143], v[164:167], v[88:91]
	v_mfma_f32_16x16x32_bf16 v[76:79], v[132:135], v[172:175], v[76:79]
	v_mfma_f32_16x16x32_bf16 v[72:75], v[140:143], v[172:175], v[72:75]
	s_setprio 0
	s_barrier
	s_add_i32 s28, 0, 0x1c000
	s_add_i32 s22, s57, s34
	v_add_u32_e32 v206, s28, v240
	s_add_u32 s0, s26, 0x80
	s_addc_u32 s1, s27, 0
	s_mov_b32 m0, s22
	ds_read_b128 v[176:179], v206
	ds_read_b128 v[180:183], v206 offset:1024
	ds_read_b128 v[184:187], v206 offset:2048
	ds_read_b128 v[206:209], v206 offset:3072
	global_load_lds_dwordx4 v190, s[0:1]
	s_add_i32 m0, s22, 0x2000
	s_nop 0
	global_load_lds_dwordx4 v194, s[0:1]
	s_waitcnt vmcnt(10)
	s_barrier
	s_waitcnt lgkmcnt(0)
	s_setprio 1
	s_waitcnt lgkmcnt(0)
	v_mfma_f32_16x16x32_bf16 v[116:119], v[176:179], v[144:147], v[116:119]
	v_mfma_f32_16x16x32_bf16 v[112:115], v[184:187], v[144:147], v[112:115]
	v_mfma_f32_16x16x32_bf16 v[100:103], v[176:179], v[152:155], v[100:103]
	v_mfma_f32_16x16x32_bf16 v[96:99], v[184:187], v[152:155], v[96:99]
	v_mfma_f32_16x16x32_bf16 v[84:87], v[176:179], v[160:163], v[84:87]
	v_mfma_f32_16x16x32_bf16 v[80:83], v[184:187], v[160:163], v[80:83]
	v_mfma_f32_16x16x32_bf16 v[68:71], v[176:179], v[168:171], v[68:71]
	v_mfma_f32_16x16x32_bf16 v[64:67], v[184:187], v[168:171], v[64:67]
	v_mfma_f32_16x16x32_bf16 v[116:119], v[180:183], v[148:151], v[116:119]
	v_mfma_f32_16x16x32_bf16 v[112:115], v[206:209], v[148:151], v[112:115]
	v_mfma_f32_16x16x32_bf16 v[100:103], v[180:183], v[156:159], v[100:103]
	v_mfma_f32_16x16x32_bf16 v[96:99], v[206:209], v[156:159], v[96:99]
	v_mfma_f32_16x16x32_bf16 v[84:87], v[180:183], v[164:167], v[84:87]
	v_mfma_f32_16x16x32_bf16 v[80:83], v[206:209], v[164:167], v[80:83]
	v_mfma_f32_16x16x32_bf16 v[68:71], v[180:183], v[172:175], v[68:71]
	v_mfma_f32_16x16x32_bf16 v[64:67], v[206:209], v[172:175], v[64:67]
	s_setprio 0
	s_mov_b32 m0, s44
	s_mov_b64 s[0:1], 0x80
	v_lshl_add_u64 v[210:211], v[214:215], 0, s[0:1]
	s_barrier
	ds_read_b128 v[144:147], v242 offset:49152
	ds_read_b128 v[148:151], v242 offset:50176
	ds_read_b128 v[152:155], v242 offset:51200
	ds_read_b128 v[156:159], v242 offset:52224
	ds_read_b128 v[160:163], v242 offset:53248
	ds_read_b128 v[164:167], v242 offset:54272
	ds_read_b128 v[168:171], v242 offset:55296
	ds_read_b128 v[172:175], v242 offset:56320
	global_load_lds_dwordx4 v[210:211], off
	v_lshl_add_u64 v[210:211], v[216:217], 0, s[0:1]
	s_mov_b32 m0, s45
	s_nop 0
	global_load_lds_dwordx4 v[210:211], off
	s_barrier
; #define PG8_STAGE(bufoff, gbase, voff) do { _Pragma("unroll") for (int _i = 0; _i < 2; ++_i) \
;         __builtin_amdgcn_global_load_lds((const unsigned*)((const char*)(gbase) + (voff)[_i]), (LAS unsigned*)(lds + (bufoff) + ldsw + _i * 8192), 16, 0, 0); } while (0)
; #define PG8_LDA(dst, b, h) do { _Pragma("unroll") for (int m = 0; m < 4; ++m) _Pragma("unroll") for (int k = 0; k < 2; ++k) dst[m][k] = *(const LAS bf16x8*)(lds + PG8_SA(b, h) + aoff + m * 2048 + k * 1024); } while (0)
; #define PG8_LDB(dst, b, h) do { _Pragma("unroll") for (int n = 0; n < 2; ++n) _Pragma("unroll") for (int k = 0; k < 2; ++k) dst[n][k] = *(const LAS bf16x8*)(lds + PG8_SB(b, h) + boff + n * 2048 + k * 1024); } while (0)
; #define PG8_WAIT_V(n) asm volatile("s_waitcnt vmcnt(" #n ")" ::: "memory")
; #define PG8_WAIT_L(n) asm volatile("s_waitcnt lgkmcnt(" #n ")" ::: "memory")
; #define PG8_BAR __builtin_amdgcn_s_barrier()
; #define PG8_SCHED __builtin_amdgcn_sched_barrier(0)
; template <class Epi, class Sched>
; __device__ __forceinline__ void gemm_phase(LAS unsigned char* lds, const Gemm g, const Sched& S, const Epi& E) {
;     ...
;             PG8_LDB(B0, 0, 0); PG8_SCHED; PG8_LDA(At, 0, 0); PG8_STAGE(PG8_SA(1, 1), a1 + hstep, voffA);
;             PG8_WAIT_L(8); PG8_BAR; PG8_WAIT_L(0); PG8_MMA(0, 0, At, B0); PG8_BAR; PG8_SCHED;
;             PG8_LDB(B1, 0, 1); PG8_STAGE(PG8_SB(0, 0), b2, voffB);
;             PG8_BAR; PG8_WAIT_L(0); PG8_MMA(0, 1, At, B1); PG8_BAR;
;             PG8_LDA(At, 0, 1); PG8_STAGE(PG8_SA(0, 0), a2, voffA);
;             PG8_BAR; PG8_WAIT_L(0); PG8_MMA(1, 0, At, B0); PG8_BAR; PG8_SCHED;
;             PG8_STAGE(PG8_SB(0, 1), b2 + hstep, voffB);
;             PG8_WAIT_V(6); PG8_BAR; PG8_MMA(1, 1, At, B1); PG8_BAR;
;             PG8_LDB(B0, 1, 0); PG8_SCHED; PG8_LDA(At, 1, 0); PG8_STAGE(PG8_SA(0, 1), a2 + hstep, voffA);
;             PG8_WAIT_L(8); PG8_BAR; PG8_WAIT_L(0); PG8_MMA(0, 0, At, B0); PG8_BAR; PG8_SCHED;
;             PG8_LDB(B1, 1, 1); PG8_STAGE(PG8_SB(1, 0), b3, voffB);
;             PG8_BAR; PG8_WAIT_L(0); PG8_MMA(0, 1, At, B1); PG8_BAR;
;             PG8_LDA(At, 1, 1); PG8_STAGE(PG8_SA(1, 0), a3, voffA);
;             PG8_BAR; PG8_WAIT_L(0); PG8_MMA(1, 0, At, B0); PG8_BAR; PG8_SCHED;
;             PG8_STAGE(PG8_SB(1, 1), b3 + hstep, voffB);
;             PG8_WAIT_V(6); PG8_BAR; PG8_MMA(1, 1, At, B1); PG8_BAR;
	s_waitcnt lgkmcnt(0)
	s_setprio 1
	s_waitcnt lgkmcnt(0)
	v_mfma_f32_16x16x32_bf16 v[60:63], v[128:131], v[144:147], v[60:63]
	v_mfma_f32_16x16x32_bf16 v[56:59], v[136:139], v[144:147], v[56:59]
	v_mfma_f32_16x16x32_bf16 v[44:47], v[128:131], v[152:155], v[44:47]
	v_mfma_f32_16x16x32_bf16 v[40:43], v[136:139], v[152:155], v[40:43]
	v_mfma_f32_16x16x32_bf16 v[28:31], v[128:131], v[160:163], v[28:31]
	v_mfma_f32_16x16x32_bf16 v[24:27], v[136:139], v[160:163], v[24:27]
	v_mfma_f32_16x16x32_bf16 v[12:15], v[128:131], v[168:171], v[12:15]
	v_mfma_f32_16x16x32_bf16 v[8:11], v[136:139], v[168:171], v[8:11]
	v_mfma_f32_16x16x32_bf16 v[60:63], v[132:135], v[148:151], v[60:63]
	v_mfma_f32_16x16x32_bf16 v[56:59], v[140:143], v[148:151], v[56:59]
	v_mfma_f32_16x16x32_bf16 v[44:47], v[132:135], v[156:159], v[44:47]
	v_mfma_f32_16x16x32_bf16 v[40:43], v[140:143], v[156:159], v[40:43]
	v_mfma_f32_16x16x32_bf16 v[28:31], v[132:135], v[164:167], v[28:31]
	v_mfma_f32_16x16x32_bf16 v[24:27], v[140:143], v[164:167], v[24:27]
	v_mfma_f32_16x16x32_bf16 v[12:15], v[132:135], v[172:175], v[12:15]
	v_mfma_f32_16x16x32_bf16 v[8:11], v[140:143], v[172:175], v[8:11]
	s_setprio 0
	s_barrier
	s_add_u32 s22, s26, 0xb0080
	s_addc_u32 s23, s27, 0
	s_add_i32 s26, s28, s34
	s_mov_b32 m0, s26
	s_nop 0
	global_load_lds_dwordx4 v190, s[22:23]
	s_add_i32 m0, s26, 0x2000
	s_nop 0
	global_load_lds_dwordx4 v194, s[22:23]
	s_waitcnt vmcnt(10)
	s_barrier
	s_setprio 1
	v_mfma_f32_16x16x32_bf16 v[52:55], v[176:179], v[144:147], v[52:55]
	v_mfma_f32_16x16x32_bf16 v[48:51], v[184:187], v[144:147], v[48:51]
	v_mfma_f32_16x16x32_bf16 v[36:39], v[176:179], v[152:155], v[36:39]
	v_mfma_f32_16x16x32_bf16 v[32:35], v[184:187], v[152:155], v[32:35]
	v_mfma_f32_16x16x32_bf16 v[20:23], v[176:179], v[160:163], v[20:23]
	v_mfma_f32_16x16x32_bf16 v[16:19], v[184:187], v[160:163], v[16:19]
	v_mfma_f32_16x16x32_bf16 v[4:7], v[176:179], v[168:171], v[4:7]
	v_mfma_f32_16x16x32_bf16 v[0:3], v[184:187], v[168:171], v[0:3]
	v_mfma_f32_16x16x32_bf16 v[52:55], v[180:183], v[148:151], v[52:55]
	v_mfma_f32_16x16x32_bf16 v[48:51], v[206:209], v[148:151], v[48:51]
	v_mfma_f32_16x16x32_bf16 v[36:39], v[180:183], v[156:159], v[36:39]
	v_mfma_f32_16x16x32_bf16 v[32:35], v[206:209], v[156:159], v[32:35]
	v_mfma_f32_16x16x32_bf16 v[20:23], v[180:183], v[164:167], v[20:23]
	v_mfma_f32_16x16x32_bf16 v[16:19], v[206:209], v[164:167], v[16:19]
	v_mfma_f32_16x16x32_bf16 v[4:7], v[180:183], v[172:175], v[4:7]
	v_mfma_f32_16x16x32_bf16 v[0:3], v[206:209], v[172:175], v[0:3]
	s_setprio 0
	s_add_i32 s56, s56, 2
	s_add_u32 s54, s54, 0x100
	s_addc_u32 s55, s55, 0
	s_cmp_gt_u32 s56, 41
	s_mov_b64 s[22:23], s[24:25]
	s_barrier
.LBB0_1097:
	ds_read_b128 v[128:131], v241
	ds_read_b128 v[132:135], v241 offset:1024
	ds_read_b128 v[136:139], v241 offset:2048
	ds_read_b128 v[140:143], v241 offset:3072
	s_add_u32 s24, s22, 0x100
	s_addc_u32 s25, s23, 0
	s_cmp_eq_u32 s56, 40
	s_cselect_b32 s29, s5, s25
	s_cselect_b32 s28, s4, s24
	s_cselect_b32 s27, s7, s55
	s_cselect_b32 s26, s6, s54
	v_lshl_add_u64 v[176:177], s[22:23], 0, v[196:197]
	s_add_i32 m0, s35, 0xc000
	ds_read_b128 v[144:147], v242
	ds_read_b128 v[148:151], v242 offset:1024
	ds_read_b128 v[152:155], v242 offset:2048
	ds_read_b128 v[156:159], v242 offset:3072
	ds_read_b128 v[160:163], v242 offset:4096
	ds_read_b128 v[164:167], v242 offset:5120
	ds_read_b128 v[168:171], v242 offset:6144
	ds_read_b128 v[172:175], v242 offset:7168
	global_load_lds_dwordx4 v[176:177], off
	v_lshl_add_u64 v[176:177], s[22:23], 0, v[198:199]
	s_add_i32 m0, s35, 0xe000
	s_nop 0
	global_load_lds_dwordx4 v[176:177], off
	s_waitcnt lgkmcnt(8)
	s_waitcnt vmcnt(10)
	s_barrier
	s_waitcnt lgkmcnt(0)
	s_setprio 1
	s_waitcnt lgkmcnt(0)
	v_mfma_f32_16x16x32_bf16 v[124:127], v[128:131], v[144:147], v[124:127]
	v_mfma_f32_16x16x32_bf16 v[120:123], v[136:139], v[144:147], v[120:123]
	v_mfma_f32_16x16x32_bf16 v[108:111], v[128:131], v[152:155], v[108:111]
	v_mfma_f32_16x16x32_bf16 v[104:107], v[136:139], v[152:155], v[104:107]
	v_mfma_f32_16x16x32_bf16 v[92:95], v[128:131], v[160:163], v[92:95]
	v_mfma_f32_16x16x32_bf16 v[88:91], v[136:139], v[160:163], v[88:91]
	v_mfma_f32_16x16x32_bf16 v[76:79], v[128:131], v[168:171], v[76:79]
	v_mfma_f32_16x16x32_bf16 v[72:75], v[136:139], v[168:171], v[72:75]
	v_mfma_f32_16x16x32_bf16 v[124:127], v[132:135], v[148:151], v[124:127]
	v_mfma_f32_16x16x32_bf16 v[120:123], v[140:143], v[148:151], v[120:123]
	v_mfma_f32_16x16x32_bf16 v[108:111], v[132:135], v[156:159], v[108:111]
	v_mfma_f32_16x16x32_bf16 v[104:107], v[140:143], v[156:159], v[104:107]
	v_mfma_f32_16x16x32_bf16 v[92:95], v[132:135], v[164:167], v[92:95]
	v_mfma_f32_16x16x32_bf16 v[88:91], v[140:143], v[164:167], v[88:91]
	v_mfma_f32_16x16x32_bf16 v[76:79], v[132:135], v[172:175], v[76:79]
	v_mfma_f32_16x16x32_bf16 v[72:75], v[140:143], v[172:175], v[72:75]
	s_setprio 0
	s_barrier
	s_add_i32 s22, s48, s34
	s_mov_b32 m0, s22
	ds_read_b128 v[176:179], v243
	ds_read_b128 v[180:183], v243 offset:1024
	ds_read_b128 v[184:187], v243 offset:2048
	ds_read_b128 v[206:209], v243 offset:3072
	global_load_lds_dwordx4 v190, s[26:27]
	s_add_i32 m0, s22, 0x2000
	s_nop 0
	global_load_lds_dwordx4 v194, s[26:27]
	s_waitcnt vmcnt(10)
	s_barrier
; #define PG8_STAGE(bufoff, gbase, voff) do { _Pragma("unroll") for (int _i = 0; _i < 2; ++_i) \
;         __builtin_amdgcn_global_load_lds((const unsigned*)((const char*)(gbase) + (voff)[_i]), (LAS unsigned*)(lds + (bufoff) + ldsw + _i * 8192), 16, 0, 0); } while (0)
; #define PG8_LDA(dst, b, h) do { _Pragma("unroll") for (int m = 0; m < 4; ++m) _Pragma("unroll") for (int k = 0; k < 2; ++k) dst[m][k] = *(const LAS bf16x8*)(lds + PG8_SA(b, h) + aoff + m * 2048 + k * 1024); } while (0)
; #define PG8_LDB(dst, b, h) do { _Pragma("unroll") for (int n = 0; n < 2; ++n) _Pragma("unroll") for (int k = 0; k < 2; ++k) dst[n][k] = *(const LAS bf16x8*)(lds + PG8_SB(b, h) + boff + n * 2048 + k * 1024); } while (0)
; #define PG8_MMA(ai, bj, At, Bt) do { __builtin_amdgcn_s_setprio(1); _Pragma("unroll") for (int m = 0; m < 4; ++m) _Pragma("unroll") for (int n = 0; n < 2; ++n) _Pragma("unroll") for (int k = 0; k < 2; ++k) \
;         acc[ai][bj][m][n] = __builtin_amdgcn_mfma_f32_16x16x32_bf16(Bt[n][k], At[m][k], acc[ai][bj][m][n], 0, 0, 0); __builtin_amdgcn_s_setprio(0); } while (0)
; #define PG8_WAIT_V(n) asm volatile("s_waitcnt vmcnt(" #n ")" ::: "memory")
; #define PG8_WAIT_L(n) asm volatile("s_waitcnt lgkmcnt(" #n ")" ::: "memory")
; #define PG8_BAR __builtin_amdgcn_s_barrier()
; #define PG8_SCHED __builtin_amdgcn_sched_barrier(0)
; template <class Epi, class Sched>
; __device__ __forceinline__ void gemm_phase(LAS unsigned char* lds, const Gemm g, const Sched& S, const Epi& E) {
;     ...
;             PG8_BAR; PG8_WAIT_L(0); PG8_MMA(0, 1, At, B1); PG8_BAR;
;             PG8_LDA(At, 0, 1); PG8_STAGE(PG8_SA(0, 0), a2, voffA);
;             PG8_BAR; PG8_WAIT_L(0); PG8_MMA(1, 0, At, B0); PG8_BAR; PG8_SCHED;
;             PG8_STAGE(PG8_SB(0, 1), b2 + hstep, voffB);
;             PG8_WAIT_V(6); PG8_BAR; PG8_MMA(1, 1, At, B1); PG8_BAR;
;             PG8_LDB(B0, 1, 0); PG8_SCHED; PG8_LDA(At, 1, 0); PG8_STAGE(PG8_SA(0, 1), a2 + hstep, voffA);
;             PG8_WAIT_L(8); PG8_BAR; PG8_WAIT_L(0); PG8_MMA(0, 0, At, B0); PG8_BAR; PG8_SCHED;
	s_waitcnt lgkmcnt(0)
	s_setprio 1
	s_waitcnt lgkmcnt(0)
	v_mfma_f32_16x16x32_bf16 v[116:119], v[176:179], v[144:147], v[116:119]
	v_mfma_f32_16x16x32_bf16 v[112:115], v[184:187], v[144:147], v[112:115]
	v_mfma_f32_16x16x32_bf16 v[100:103], v[176:179], v[152:155], v[100:103]
	v_mfma_f32_16x16x32_bf16 v[96:99], v[184:187], v[152:155], v[96:99]
	v_mfma_f32_16x16x32_bf16 v[84:87], v[176:179], v[160:163], v[84:87]
	v_mfma_f32_16x16x32_bf16 v[80:83], v[184:187], v[160:163], v[80:83]
	v_mfma_f32_16x16x32_bf16 v[68:71], v[176:179], v[168:171], v[68:71]
	v_mfma_f32_16x16x32_bf16 v[64:67], v[184:187], v[168:171], v[64:67]
	v_mfma_f32_16x16x32_bf16 v[116:119], v[180:183], v[148:151], v[116:119]
	v_mfma_f32_16x16x32_bf16 v[112:115], v[206:209], v[148:151], v[112:115]
	v_mfma_f32_16x16x32_bf16 v[100:103], v[180:183], v[156:159], v[100:103]
	v_mfma_f32_16x16x32_bf16 v[96:99], v[206:209], v[156:159], v[96:99]
	v_mfma_f32_16x16x32_bf16 v[84:87], v[180:183], v[164:167], v[84:87]
	v_mfma_f32_16x16x32_bf16 v[80:83], v[206:209], v[164:167], v[80:83]
	v_mfma_f32_16x16x32_bf16 v[68:71], v[180:183], v[172:175], v[68:71]
	v_mfma_f32_16x16x32_bf16 v[64:67], v[206:209], v[172:175], v[64:67]
	s_setprio 0
	s_mov_b32 m0, s35
	v_lshl_add_u64 v[214:215], s[28:29], 0, v[188:189]
	s_barrier
	ds_read_b128 v[144:147], v242 offset:16384
	ds_read_b128 v[148:151], v242 offset:17408
	ds_read_b128 v[152:155], v242 offset:18432
	ds_read_b128 v[156:159], v242 offset:19456
	ds_read_b128 v[160:163], v242 offset:20480
	ds_read_b128 v[164:167], v242 offset:21504
	ds_read_b128 v[168:171], v242 offset:22528
	ds_read_b128 v[172:175], v242 offset:23552
	global_load_lds_dwordx4 v188, s[28:29]
	v_lshl_add_u64 v[216:217], s[28:29], 0, v[192:193]
	s_mov_b32 m0, s36
	s_nop 0
	global_load_lds_dwordx4 v192, s[28:29]
	s_barrier
	s_waitcnt lgkmcnt(0)
	s_setprio 1
	s_waitcnt lgkmcnt(0)
	v_mfma_f32_16x16x32_bf16 v[60:63], v[128:131], v[144:147], v[60:63]
	v_mfma_f32_16x16x32_bf16 v[56:59], v[136:139], v[144:147], v[56:59]
	v_mfma_f32_16x16x32_bf16 v[44:47], v[128:131], v[152:155], v[44:47]
	v_mfma_f32_16x16x32_bf16 v[40:43], v[136:139], v[152:155], v[40:43]
	v_mfma_f32_16x16x32_bf16 v[28:31], v[128:131], v[160:163], v[28:31]
	v_mfma_f32_16x16x32_bf16 v[24:27], v[136:139], v[160:163], v[24:27]
	v_mfma_f32_16x16x32_bf16 v[12:15], v[128:131], v[168:171], v[12:15]
	v_mfma_f32_16x16x32_bf16 v[8:11], v[136:139], v[168:171], v[8:11]
	v_mfma_f32_16x16x32_bf16 v[60:63], v[132:135], v[148:151], v[60:63]
	v_mfma_f32_16x16x32_bf16 v[56:59], v[140:143], v[148:151], v[56:59]
	v_mfma_f32_16x16x32_bf16 v[44:47], v[132:135], v[156:159], v[44:47]
	v_mfma_f32_16x16x32_bf16 v[40:43], v[140:143], v[156:159], v[40:43]
	v_mfma_f32_16x16x32_bf16 v[28:31], v[132:135], v[164:167], v[28:31]
	v_mfma_f32_16x16x32_bf16 v[24:27], v[140:143], v[164:167], v[24:27]
	v_mfma_f32_16x16x32_bf16 v[12:15], v[132:135], v[172:175], v[12:15]
	v_mfma_f32_16x16x32_bf16 v[8:11], v[140:143], v[172:175], v[8:11]
	s_setprio 0
	s_barrier
	s_add_u32 s22, s26, 0xb0000
	s_addc_u32 s23, s27, 0
	s_add_i32 s57, s49, s34
	s_mov_b32 m0, s57
	s_nop 0
	global_load_lds_dwordx4 v190, s[22:23]
	s_add_i32 m0, s57, 0x2000
	s_nop 0
	global_load_lds_dwordx4 v194, s[22:23]
	s_add_u32 s22, s28, 0xb0000
	s_addc_u32 s23, s29, 0
	s_mov_b32 m0, s37
	s_nop 0
	global_load_lds_dwordx4 v188, s[22:23]
	s_mov_b32 m0, s38
	s_nop 0
	global_load_lds_dwordx4 v192, s[22:23]
	s_waitcnt vmcnt(12)
	s_barrier
	s_setprio 1
	v_mfma_f32_16x16x32_bf16 v[52:55], v[176:179], v[144:147], v[52:55]
	v_mfma_f32_16x16x32_bf16 v[48:51], v[184:187], v[144:147], v[48:51]
	v_mfma_f32_16x16x32_bf16 v[36:39], v[176:179], v[152:155], v[36:39]
	v_mfma_f32_16x16x32_bf16 v[32:35], v[184:187], v[152:155], v[32:35]
	v_mfma_f32_16x16x32_bf16 v[20:23], v[176:179], v[160:163], v[20:23]
	v_mfma_f32_16x16x32_bf16 v[16:19], v[184:187], v[160:163], v[16:19]
	v_mfma_f32_16x16x32_bf16 v[4:7], v[176:179], v[168:171], v[4:7]
	v_mfma_f32_16x16x32_bf16 v[0:3], v[184:187], v[168:171], v[0:3]
	v_mfma_f32_16x16x32_bf16 v[52:55], v[180:183], v[148:151], v[52:55]
	v_mfma_f32_16x16x32_bf16 v[48:51], v[206:209], v[148:151], v[48:51]
	v_mfma_f32_16x16x32_bf16 v[36:39], v[180:183], v[156:159], v[36:39]
	v_mfma_f32_16x16x32_bf16 v[32:35], v[206:209], v[156:159], v[32:35]
	v_mfma_f32_16x16x32_bf16 v[20:23], v[180:183], v[164:167], v[20:23]
	v_mfma_f32_16x16x32_bf16 v[16:19], v[206:209], v[164:167], v[16:19]
	v_mfma_f32_16x16x32_bf16 v[4:7], v[180:183], v[172:175], v[4:7]
	v_mfma_f32_16x16x32_bf16 v[0:3], v[206:209], v[172:175], v[0:3]
	s_setprio 0
	s_add_i32 s57, 0, 0x18000
	v_add_u32_e32 v140, s57, v240
	s_barrier
	ds_read_b128 v[128:131], v140
	ds_read_b128 v[132:135], v140 offset:1024
	ds_read_b128 v[136:139], v140 offset:2048
	ds_read_b128 v[140:143], v140 offset:3072
	ds_read_b128 v[144:147], v242 offset:32768
	ds_read_b128 v[148:151], v242 offset:33792
	ds_read_b128 v[152:155], v242 offset:34816
	ds_read_b128 v[156:159], v242 offset:35840
	ds_read_b128 v[160:163], v242 offset:36864
	ds_read_b128 v[164:167], v242 offset:37888
	ds_read_b128 v[168:171], v242 offset:38912
	ds_read_b128 v[172:175], v242 offset:39936
	s_waitcnt lgkmcnt(8)
	s_waitcnt vmcnt(10)
	s_barrier
; #define PG8_STAGE(bufoff, gbase, voff) do { _Pragma("unroll") for (int _i = 0; _i < 2; ++_i) \
;         __builtin_amdgcn_global_load_lds((const unsigned*)((const char*)(gbase) + (voff)[_i]), (LAS unsigned*)(lds + (bufoff) + ldsw + _i * 8192), 16, 0, 0); } while (0)
; #define PG8_LDA(dst, b, h) do { _Pragma("unroll") for (int m = 0; m < 4; ++m) _Pragma("unroll") for (int k = 0; k < 2; ++k) dst[m][k] = *(const LAS bf16x8*)(lds + PG8_SA(b, h) + aoff + m * 2048 + k * 1024); } while (0)
; #define PG8_LDB(dst, b, h) do { _Pragma("unroll") for (int n = 0; n < 2; ++n) _Pragma("unroll") for (int k = 0; k < 2; ++k) dst[n][k] = *(const LAS bf16x8*)(lds + PG8_SB(b, h) + boff + n * 2048 + k * 1024); } while (0)
; #define PG8_MMA(ai, bj, At, Bt) do { __builtin_amdgcn_s_setprio(1); _Pragma("unroll") for (int m = 0; m < 4; ++m) _Pragma("unroll") for (int n = 0; n < 2; ++n) _Pragma("unroll") for (int k = 0; k < 2; ++k) \
;         acc[ai][bj][m][n] = __builtin_amdgcn_mfma_f32_16x16x32_bf16(Bt[n][k], At[m][k], acc[ai][bj][m][n], 0, 0, 0); __builtin_amdgcn_s_setprio(0); } while (0)
; #define PG8_WAIT_V(n) asm volatile("s_waitcnt vmcnt(" #n ")" ::: "memory")
; #define PG8_WAIT_L(n) asm volatile("s_waitcnt lgkmcnt(" #n ")" ::: "memory")
; #define PG8_BAR __builtin_amdgcn_s_barrier()
; #define PG8_SCHED __builtin_amdgcn_sched_barrier(0)
; template <class Epi, class Sched>
; __device__ __forceinline__ void gemm_phase(LAS unsigned char* lds, const Gemm g, const Sched& S, const Epi& E) {
;     ...
;             PG8_WAIT_L(8); PG8_BAR; PG8_WAIT_L(0); PG8_MMA(0, 0, At, B0); PG8_BAR; PG8_SCHED;
;             PG8_LDB(B1, 1, 1); PG8_STAGE(PG8_SB(1, 0), b3, voffB);
;             PG8_BAR; PG8_WAIT_L(0); PG8_MMA(0, 1, At, B1); PG8_BAR;
;             PG8_LDA(At, 1, 1); PG8_STAGE(PG8_SA(1, 0), a3, voffA);
;             PG8_BAR; PG8_WAIT_L(0); PG8_MMA(1, 0, At, B0); PG8_BAR; PG8_SCHED;
;             PG8_STAGE(PG8_SB(1, 1), b3 + hstep, voffB);
;             PG8_WAIT_V(6); PG8_BAR; PG8_MMA(1, 1, At, B1); PG8_BAR;
	s_waitcnt lgkmcnt(0)
	s_setprio 1
	s_waitcnt lgkmcnt(0)
	v_mfma_f32_16x16x32_bf16 v[124:127], v[128:131], v[144:147], v[124:127]
	v_mfma_f32_16x16x32_bf16 v[120:123], v[136:139], v[144:147], v[120:123]
	v_mfma_f32_16x16x32_bf16 v[108:111], v[128:131], v[152:155], v[108:111]
	v_mfma_f32_16x16x32_bf16 v[104:107], v[136:139], v[152:155], v[104:107]
	v_mfma_f32_16x16x32_bf16 v[92:95], v[128:131], v[160:163], v[92:95]
	v_mfma_f32_16x16x32_bf16 v[88:91], v[136:139], v[160:163], v[88:91]
	v_mfma_f32_16x16x32_bf16 v[76:79], v[128:131], v[168:171], v[76:79]
	v_mfma_f32_16x16x32_bf16 v[72:75], v[136:139], v[168:171], v[72:75]
	v_mfma_f32_16x16x32_bf16 v[124:127], v[132:135], v[148:151], v[124:127]
	v_mfma_f32_16x16x32_bf16 v[120:123], v[140:143], v[148:151], v[120:123]
	v_mfma_f32_16x16x32_bf16 v[108:111], v[132:135], v[156:159], v[108:111]
	v_mfma_f32_16x16x32_bf16 v[104:107], v[140:143], v[156:159], v[104:107]
	v_mfma_f32_16x16x32_bf16 v[92:95], v[132:135], v[164:167], v[92:95]
	v_mfma_f32_16x16x32_bf16 v[88:91], v[140:143], v[164:167], v[88:91]
	v_mfma_f32_16x16x32_bf16 v[76:79], v[132:135], v[172:175], v[76:79]
	v_mfma_f32_16x16x32_bf16 v[72:75], v[140:143], v[172:175], v[72:75]
	s_setprio 0
	s_barrier
	s_add_i32 s28, 0, 0x1c000
	s_add_i32 s22, s57, s34
	v_add_u32_e32 v206, s28, v240
	s_add_u32 s0, s26, 0x80
	s_addc_u32 s1, s27, 0
	s_mov_b32 m0, s22
	ds_read_b128 v[176:179], v206
	ds_read_b128 v[180:183], v206 offset:1024
	ds_read_b128 v[184:187], v206 offset:2048
	ds_read_b128 v[206:209], v206 offset:3072
	global_load_lds_dwordx4 v190, s[0:1]
	s_add_i32 m0, s22, 0x2000
	s_nop 0
	global_load_lds_dwordx4 v194, s[0:1]
	s_waitcnt vmcnt(10)
	s_barrier
	s_waitcnt lgkmcnt(0)
	s_setprio 1
	s_waitcnt lgkmcnt(0)
	v_mfma_f32_16x16x32_bf16 v[116:119], v[176:179], v[144:147], v[116:119]
	v_mfma_f32_16x16x32_bf16 v[112:115], v[184:187], v[144:147], v[112:115]
	v_mfma_f32_16x16x32_bf16 v[100:103], v[176:179], v[152:155], v[100:103]
	v_mfma_f32_16x16x32_bf16 v[96:99], v[184:187], v[152:155], v[96:99]
	v_mfma_f32_16x16x32_bf16 v[84:87], v[176:179], v[160:163], v[84:87]
	v_mfma_f32_16x16x32_bf16 v[80:83], v[184:187], v[160:163], v[80:83]
	v_mfma_f32_16x16x32_bf16 v[68:71], v[176:179], v[168:171], v[68:71]
	v_mfma_f32_16x16x32_bf16 v[64:67], v[184:187], v[168:171], v[64:67]
	v_mfma_f32_16x16x32_bf16 v[116:119], v[180:183], v[148:151], v[116:119]
	v_mfma_f32_16x16x32_bf16 v[112:115], v[206:209], v[148:151], v[112:115]
	v_mfma_f32_16x16x32_bf16 v[100:103], v[180:183], v[156:159], v[100:103]
	v_mfma_f32_16x16x32_bf16 v[96:99], v[206:209], v[156:159], v[96:99]
	v_mfma_f32_16x16x32_bf16 v[84:87], v[180:183], v[164:167], v[84:87]
	v_mfma_f32_16x16x32_bf16 v[80:83], v[206:209], v[164:167], v[80:83]
	v_mfma_f32_16x16x32_bf16 v[68:71], v[180:183], v[172:175], v[68:71]
	v_mfma_f32_16x16x32_bf16 v[64:67], v[206:209], v[172:175], v[64:67]
	s_setprio 0
	s_mov_b32 m0, s44
	s_mov_b64 s[0:1], 0x80
	v_lshl_add_u64 v[210:211], v[214:215], 0, s[0:1]
	s_barrier
	ds_read_b128 v[144:147], v242 offset:49152
	ds_read_b128 v[148:151], v242 offset:50176
	ds_read_b128 v[152:155], v242 offset:51200
	ds_read_b128 v[156:159], v242 offset:52224
	ds_read_b128 v[160:163], v242 offset:53248
	ds_read_b128 v[164:167], v242 offset:54272
	ds_read_b128 v[168:171], v242 offset:55296
	ds_read_b128 v[172:175], v242 offset:56320
	global_load_lds_dwordx4 v[210:211], off
	v_lshl_add_u64 v[210:211], v[216:217], 0, s[0:1]
	s_mov_b32 m0, s45
	s_nop 0
	global_load_lds_dwordx4 v[210:211], off
	s_barrier
	s_waitcnt lgkmcnt(0)
	s_setprio 1
	s_waitcnt lgkmcnt(0)
	v_mfma_f32_16x16x32_bf16 v[60:63], v[128:131], v[144:147], v[60:63]
	v_mfma_f32_16x16x32_bf16 v[56:59], v[136:139], v[144:147], v[56:59]
	v_mfma_f32_16x16x32_bf16 v[44:47], v[128:131], v[152:155], v[44:47]
	v_mfma_f32_16x16x32_bf16 v[40:43], v[136:139], v[152:155], v[40:43]
	v_mfma_f32_16x16x32_bf16 v[28:31], v[128:131], v[160:163], v[28:31]
	v_mfma_f32_16x16x32_bf16 v[24:27], v[136:139], v[160:163], v[24:27]
	v_mfma_f32_16x16x32_bf16 v[12:15], v[128:131], v[168:171], v[12:15]
	v_mfma_f32_16x16x32_bf16 v[8:11], v[136:139], v[168:171], v[8:11]
	v_mfma_f32_16x16x32_bf16 v[60:63], v[132:135], v[148:151], v[60:63]
	v_mfma_f32_16x16x32_bf16 v[56:59], v[140:143], v[148:151], v[56:59]
	v_mfma_f32_16x16x32_bf16 v[44:47], v[132:135], v[156:159], v[44:47]
	v_mfma_f32_16x16x32_bf16 v[40:43], v[140:143], v[156:159], v[40:43]
	v_mfma_f32_16x16x32_bf16 v[28:31], v[132:135], v[164:167], v[28:31]
	v_mfma_f32_16x16x32_bf16 v[24:27], v[140:143], v[164:167], v[24:27]
	v_mfma_f32_16x16x32_bf16 v[12:15], v[132:135], v[172:175], v[12:15]
	v_mfma_f32_16x16x32_bf16 v[8:11], v[140:143], v[172:175], v[8:11]
	s_setprio 0
	s_barrier
	s_add_u32 s22, s26, 0xb0080
	s_addc_u32 s23, s27, 0
	s_add_i32 s26, s28, s34
	s_mov_b32 m0, s26
	s_nop 0
	global_load_lds_dwordx4 v190, s[22:23]
	s_add_i32 m0, s26, 0x2000
	s_nop 0
	global_load_lds_dwordx4 v194, s[22:23]
	s_waitcnt vmcnt(10)
	s_barrier
	s_setprio 1
	v_mfma_f32_16x16x32_bf16 v[52:55], v[176:179], v[144:147], v[52:55]
	v_mfma_f32_16x16x32_bf16 v[48:51], v[184:187], v[144:147], v[48:51]
	v_mfma_f32_16x16x32_bf16 v[36:39], v[176:179], v[152:155], v[36:39]
	v_mfma_f32_16x16x32_bf16 v[32:35], v[184:187], v[152:155], v[32:35]
	v_mfma_f32_16x16x32_bf16 v[20:23], v[176:179], v[160:163], v[20:23]
	v_mfma_f32_16x16x32_bf16 v[16:19], v[184:187], v[160:163], v[16:19]
	v_mfma_f32_16x16x32_bf16 v[4:7], v[176:179], v[168:171], v[4:7]
	v_mfma_f32_16x16x32_bf16 v[0:3], v[184:187], v[168:171], v[0:3]
	v_mfma_f32_16x16x32_bf16 v[52:55], v[180:183], v[148:151], v[52:55]
	v_mfma_f32_16x16x32_bf16 v[48:51], v[206:209], v[148:151], v[48:51]
	v_mfma_f32_16x16x32_bf16 v[36:39], v[180:183], v[156:159], v[36:39]
	v_mfma_f32_16x16x32_bf16 v[32:35], v[206:209], v[156:159], v[32:35]
	v_mfma_f32_16x16x32_bf16 v[20:23], v[180:183], v[164:167], v[20:23]
	v_mfma_f32_16x16x32_bf16 v[16:19], v[206:209], v[164:167], v[16:19]
	v_mfma_f32_16x16x32_bf16 v[4:7], v[180:183], v[172:175], v[4:7]
	v_mfma_f32_16x16x32_bf16 v[0:3], v[206:209], v[172:175], v[0:3]
	s_setprio 0
	s_add_i32 s56, s56, 2
	s_add_u32 s54, s54, 0x100
	s_addc_u32 s55, s55, 0
	s_cmp_gt_u32 s56, 41
	s_mov_b64 s[22:23], s[24:25]
	s_barrier
; __device__ __forceinline__ unsigned cvt_pk_bf16(float lo, float hi) { unsigned r; asm volatile("v_cvt_pk_bf16_f32 %0, %1, %2" : "=v"(r) : "v"(lo), "v"(hi)); return r; }
; __device__ __forceinline__ float bf_lo(unsigned u) { return __uint_as_float(u << 16); }
; __device__ __forceinline__ float bf_hi(unsigned u) { return __uint_as_float(u & 0xffff0000u); }
;     __device__ __forceinline__ void operator()(const AccT& acc, const Unit& u, int wr, int wc, int fr, int fq) const {
;     ...
;         const int rowt = u.pm * 256; const int b = rowt >> 11;
;         const bf16_t* res = res_b + (size_t)rowt * DM; bf16_t* out = hb + (size_t)rowt * DM;
;         const int col0 = u.pn * 256 + wc * 32 + 8 * fq;
;         f32x4 gv[2][2];
; #pragma unroll
;         for (int bj = 0; bj < 2; ++bj)
; #pragma unroll
;             for (int n = 0; n < 2; ++n) gv[bj][n] = *(const f32x4*)(gate + (size_t)b * NMOD + col0 + bj * 128 + n * 4) * gs;
;         u32x4 r[2][4][2];
; #pragma unroll
;         for (int ai = 0; ai < 2; ++ai)
; #pragma unroll
;             for (int m = 0; m < 4; ++m)
; #pragma unroll
;                 for (int bj = 0; bj < 2; ++bj) r[ai][m][bj] = *(const u32x4*)(res + (size_t)(wr * 64 + fr + ai * 128 + m * 16) * DM + col0 + bj * 128);
; #pragma unroll
;         for (int ai = 0; ai < 2; ++ai)
; #pragma unroll
;             for (int m = 0; m < 4; ++m)
; #pragma unroll
;                 for (int bj = 0; bj < 2; ++bj) {
;                     const u32x4 q = r[ai][m][bj];
;                     const f32x4 r0 = {bf_lo(q.x), bf_hi(q.x), bf_lo(q.y), bf_hi(q.y)}, r1 = {bf_lo(q.z), bf_hi(q.z), bf_lo(q.w), bf_hi(q.w)};
;                     const f32x4 h0 = r0 + gv[bj][0] * acc[ai][bj][m][0], h1 = r1 + gv[bj][1] * acc[ai][bj][m][1];
;                     u32x4 w; w.x = cvt_pk_bf16(h0[0], h0[1]); w.y = cvt_pk_bf16(h0[2], h0[3]); w.z = cvt_pk_bf16(h1[0], h1[1]); w.w = cvt_pk_bf16(h1[2], h1[3]);
;                     *(u32x4*)(out + (size_t)(wr * 64 + fr + ai * 128 + m * 16) * DM + col0 + bj * 128) = w;
	s_cbranch_scc0 .LBB0_1097
	s_lshl_b32 s25, s52, 8
	v_mov_b32_e32 v140, v239
	v_mov_b32_e32 v128, v238
	s_lshl_b32 s22, s53, 8
	s_ashr_i32 s24, s53, 3
	s_or_b32 s25, s25, s43
	s_ashr_i32 s23, s22, 31
	v_lshl_add_u32 v136, v128, 3, s25
	s_mul_hi_i32 s25, s24, 0x9000
	s_mul_i32 s24, s24, 0x9000
	s_add_u32 s24, s40, s24
	s_addc_u32 s25, s41, s25
	v_ashrrev_i32_e32 v137, 31, v136
	v_lshl_add_u64 v[138:139], v[136:137], 2, s[24:25]
	global_load_dwordx4 v[128:131], v[138:139], off offset:16
	global_load_dwordx4 v[132:135], v[138:139], off
	s_lshl_b64 s[22:23], s[22:23], 11
	s_add_u32 s24, s80, s22
	s_addc_u32 s25, s81, s23
	v_lshlrev_b64 v[226:227], 1, v[136:137]
	s_add_u32 s22, s96, s22
	s_addc_u32 s23, s97, s23
	s_and_b64 vcc, exec, s[2:3]
	s_mov_b32 s52, s50
	s_mov_b32 s53, s51
	s_waitcnt vmcnt(0)
	v_pk_mul_f32 v[216:217], v[130:131], 0.5 op_sel_hi:[1,0]
	v_pk_mul_f32 v[220:221], v[134:135], 0.5 op_sel_hi:[1,0]
	v_pk_mul_f32 v[218:219], v[132:133], 0.5 op_sel_hi:[1,0]
	v_pk_mul_f32 v[214:215], v[128:129], 0.5 op_sel_hi:[1,0]
	global_load_dwordx4 v[128:131], v[138:139], off offset:528
	global_load_dwordx4 v[132:135], v[138:139], off offset:512
	s_waitcnt vmcnt(0)
	v_pk_mul_f32 v[206:207], v[128:129], 0.5 op_sel_hi:[1,0]
	v_add_u32_e32 v128, s42, v140
	v_ashrrev_i32_e32 v129, 31, v128
	v_pk_mul_f32 v[208:209], v[130:131], 0.5 op_sel_hi:[1,0]
	v_lshl_add_u64 v[130:131], s[24:25], 0, v[226:227]
	v_lshlrev_b64 v[248:249], 11, v[128:129]
	v_lshl_add_u64 v[128:129], v[130:131], 0, v[248:249]
	global_load_dwordx4 v[244:247], v[128:129], off
	global_load_dwordx4 v[184:187], v[128:129], off offset:256
	v_lshl_add_u64 v[236:237], v[248:249], 0, s[8:9]
	v_lshl_add_u64 v[128:129], v[130:131], 0, v[236:237]
	global_load_dwordx4 v[180:183], v[128:129], off
	global_load_dwordx4 v[176:179], v[128:129], off offset:256
	v_lshl_add_u64 v[234:235], v[248:249], 0, s[10:11]
	v_lshl_add_u64 v[128:129], v[130:131], 0, v[234:235]
	global_load_dwordx4 v[172:175], v[128:129], off
	global_load_dwordx4 v[168:171], v[128:129], off offset:256
	v_lshl_add_u64 v[232:233], v[248:249], 0, s[12:13]
	v_lshl_add_u64 v[128:129], v[130:131], 0, v[232:233]
	global_load_dwordx4 v[164:167], v[128:129], off
	global_load_dwordx4 v[160:163], v[128:129], off offset:256
	v_lshl_add_u64 v[230:231], v[248:249], 0, s[14:15]
	v_lshl_add_u64 v[128:129], v[130:131], 0, v[230:231]
	global_load_dwordx4 v[156:159], v[128:129], off
	global_load_dwordx4 v[152:155], v[128:129], off offset:256
	v_lshl_add_u64 v[228:229], v[248:249], 0, s[16:17]
	v_lshl_add_u64 v[128:129], v[130:131], 0, v[228:229]
	global_load_dwordx4 v[148:151], v[128:129], off
	global_load_dwordx4 v[144:147], v[128:129], off offset:256
	v_lshl_add_u64 v[224:225], v[248:249], 0, s[18:19]
	v_lshl_add_u64 v[128:129], v[130:131], 0, v[224:225]
	global_load_dwordx4 v[140:143], v[128:129], off
	global_load_dwordx4 v[136:139], v[128:129], off offset:256
	v_lshl_add_u64 v[222:223], v[248:249], 0, s[20:21]
	v_lshl_add_u64 v[128:129], v[130:131], 0, v[222:223]
	v_pk_mul_f32 v[212:213], v[134:135], 0.5 op_sel_hi:[1,0]
	v_pk_mul_f32 v[210:211], v[132:133], 0.5 op_sel_hi:[1,0]
	global_load_dwordx4 v[132:135], v[128:129], off
	s_nop 0
	global_load_dwordx4 v[128:131], v[128:129], off offset:256
	v_lshl_add_u64 v[226:227], s[22:23], 0, v[226:227]
	v_lshl_add_u64 v[248:249], v[226:227], 0, v[248:249]
	s_mov_b64 s[24:25], s[6:7]
	s_mov_b64 s[22:23], s[4:5]
	s_waitcnt vmcnt(0)
	v_lshlrev_b32_e32 v250, 16, v244
	v_and_b32_e32 v251, 0xffff0000, v244
	v_lshlrev_b32_e32 v244, 16, v245
	v_and_b32_e32 v245, 0xffff0000, v245
	v_lshlrev_b32_e32 v252, 16, v246
	v_and_b32_e32 v253, 0xffff0000, v246
	v_lshlrev_b32_e32 v246, 16, v247
	v_and_b32_e32 v247, 0xffff0000, v247
	v_pk_fma_f32 v[126:127], v[126:127], v[220:221], v[244:245]
	v_pk_fma_f32 v[124:125], v[124:125], v[218:219], v[250:251]
	v_pk_fma_f32 v[244:245], v[122:123], v[216:217], v[246:247]
	v_pk_fma_f32 v[122:123], v[120:121], v[214:215], v[252:253]
	v_cvt_pk_bf16_f32 v120, v124, v125
	v_cvt_pk_bf16_f32 v121, v126, v127
	v_lshlrev_b32_e32 v124, 16, v186
	v_cvt_pk_bf16_f32 v122, v122, v123
	v_cvt_pk_bf16_f32 v123, v244, v245
	global_store_dwordx4 v[248:249], v[120:123], off
	v_and_b32_e32 v125, 0xffff0000, v186
	v_lshlrev_b32_e32 v126, 16, v187
	v_lshlrev_b32_e32 v120, 16, v184
	v_and_b32_e32 v121, 0xffff0000, v184
	v_and_b32_e32 v127, 0xffff0000, v187
	v_lshlrev_b32_e32 v122, 16, v185
	v_and_b32_e32 v123, 0xffff0000, v185
	v_pk_fma_f32 v[116:117], v[116:117], v[210:211], v[120:121]
	v_pk_fma_f32 v[120:121], v[114:115], v[208:209], v[126:127]
	v_pk_fma_f32 v[114:115], v[112:113], v[206:207], v[124:125]
	v_pk_fma_f32 v[118:119], v[118:119], v[212:213], v[122:123]
	v_cvt_pk_bf16_f32 v112, v116, v117
	v_lshlrev_b32_e32 v116, 16, v181
	v_cvt_pk_bf16_f32 v113, v118, v119
	v_cvt_pk_bf16_f32 v114, v114, v115
	v_cvt_pk_bf16_f32 v115, v120, v121
	global_store_dwordx4 v[248:249], v[112:115], off offset:256
	v_and_b32_e32 v117, 0xffff0000, v181
	v_lshlrev_b32_e32 v118, 16, v182
	v_lshlrev_b32_e32 v114, 16, v180
	v_and_b32_e32 v115, 0xffff0000, v180
	v_and_b32_e32 v119, 0xffff0000, v182
	v_lshlrev_b32_e32 v120, 16, v183
	v_and_b32_e32 v121, 0xffff0000, v183
	v_lshl_add_u64 v[112:113], v[226:227], 0, v[236:237]
	v_pk_fma_f32 v[110:111], v[110:111], v[220:221], v[116:117]
	v_pk_fma_f32 v[108:109], v[108:109], v[218:219], v[114:115]
	v_pk_fma_f32 v[114:115], v[106:107], v[216:217], v[120:121]
	v_pk_fma_f32 v[106:107], v[104:105], v[214:215], v[118:119]
	v_cvt_pk_bf16_f32 v104, v108, v109
	v_cvt_pk_bf16_f32 v105, v110, v111
	v_lshlrev_b32_e32 v108, 16, v178
	v_cvt_pk_bf16_f32 v106, v106, v107
	v_cvt_pk_bf16_f32 v107, v114, v115
; __device__ __forceinline__ unsigned cvt_pk_bf16(float lo, float hi) { unsigned r; asm volatile("v_cvt_pk_bf16_f32 %0, %1, %2" : "=v"(r) : "v"(lo), "v"(hi)); return r; }
; __device__ __forceinline__ float bf_lo(unsigned u) { return __uint_as_float(u << 16); }
; __device__ __forceinline__ float bf_hi(unsigned u) { return __uint_as_float(u & 0xffff0000u); }
;     __device__ __forceinline__ void operator()(const AccT& acc, const Unit& u, int wr, int wc, int fr, int fq) const {
;     ...
;         for (int ai = 0; ai < 2; ++ai)
; #pragma unroll
;             for (int m = 0; m < 4; ++m)
; #pragma unroll
;                 for (int bj = 0; bj < 2; ++bj) {
;                     const u32x4 q = r[ai][m][bj];
;                     const f32x4 r0 = {bf_lo(q.x), bf_hi(q.x), bf_lo(q.y), bf_hi(q.y)}, r1 = {bf_lo(q.z), bf_hi(q.z), bf_lo(q.w), bf_hi(q.w)};
;                     const f32x4 h0 = r0 + gv[bj][0] * acc[ai][bj][m][0], h1 = r1 + gv[bj][1] * acc[ai][bj][m][1];
;                     u32x4 w; w.x = cvt_pk_bf16(h0[0], h0[1]); w.y = cvt_pk_bf16(h0[2], h0[3]); w.z = cvt_pk_bf16(h1[0], h1[1]); w.w = cvt_pk_bf16(h1[2], h1[3]);
;                     *(u32x4*)(out + (size_t)(wr * 64 + fr + ai * 128 + m * 16) * DM + col0 + bj * 128) = w;
	global_store_dwordx4 v[112:113], v[104:107], off
	v_and_b32_e32 v109, 0xffff0000, v178
	v_lshlrev_b32_e32 v110, 16, v179
	v_lshlrev_b32_e32 v104, 16, v176
	v_and_b32_e32 v105, 0xffff0000, v176
	v_and_b32_e32 v111, 0xffff0000, v179
	v_lshlrev_b32_e32 v106, 16, v177
	v_and_b32_e32 v107, 0xffff0000, v177
	v_pk_fma_f32 v[100:101], v[100:101], v[210:211], v[104:105]
	v_pk_fma_f32 v[104:105], v[98:99], v[208:209], v[110:111]
	v_pk_fma_f32 v[98:99], v[96:97], v[206:207], v[108:109]
	v_pk_fma_f32 v[102:103], v[102:103], v[212:213], v[106:107]
	v_cvt_pk_bf16_f32 v96, v100, v101
	v_lshlrev_b32_e32 v100, 16, v173
	v_cvt_pk_bf16_f32 v97, v102, v103
	v_cvt_pk_bf16_f32 v98, v98, v99
	v_cvt_pk_bf16_f32 v99, v104, v105
	global_store_dwordx4 v[112:113], v[96:99], off offset:256
	v_and_b32_e32 v101, 0xffff0000, v173
	v_lshlrev_b32_e32 v102, 16, v174
	v_lshlrev_b32_e32 v98, 16, v172
	v_and_b32_e32 v99, 0xffff0000, v172
	v_and_b32_e32 v103, 0xffff0000, v174
	v_lshlrev_b32_e32 v104, 16, v175
	v_and_b32_e32 v105, 0xffff0000, v175
	v_lshl_add_u64 v[96:97], v[226:227], 0, v[234:235]
	v_pk_fma_f32 v[94:95], v[94:95], v[220:221], v[100:101]
	v_pk_fma_f32 v[92:93], v[92:93], v[218:219], v[98:99]
	v_pk_fma_f32 v[98:99], v[90:91], v[216:217], v[104:105]
	v_pk_fma_f32 v[90:91], v[88:89], v[214:215], v[102:103]
	v_cvt_pk_bf16_f32 v88, v92, v93
	v_cvt_pk_bf16_f32 v89, v94, v95
	v_lshlrev_b32_e32 v92, 16, v170
	v_cvt_pk_bf16_f32 v90, v90, v91
	v_cvt_pk_bf16_f32 v91, v98, v99
	global_store_dwordx4 v[96:97], v[88:91], off
	v_and_b32_e32 v93, 0xffff0000, v170
	v_lshlrev_b32_e32 v94, 16, v171
	v_lshlrev_b32_e32 v88, 16, v168
	v_and_b32_e32 v89, 0xffff0000, v168
	v_and_b32_e32 v95, 0xffff0000, v171
	v_lshlrev_b32_e32 v90, 16, v169
	v_and_b32_e32 v91, 0xffff0000, v169
	v_pk_fma_f32 v[84:85], v[84:85], v[210:211], v[88:89]
	v_pk_fma_f32 v[88:89], v[82:83], v[208:209], v[94:95]
	v_pk_fma_f32 v[82:83], v[80:81], v[206:207], v[92:93]
	v_pk_fma_f32 v[86:87], v[86:87], v[212:213], v[90:91]
	v_cvt_pk_bf16_f32 v80, v84, v85
	v_lshlrev_b32_e32 v84, 16, v165
	v_cvt_pk_bf16_f32 v81, v86, v87
	v_cvt_pk_bf16_f32 v82, v82, v83
	v_cvt_pk_bf16_f32 v83, v88, v89
	global_store_dwordx4 v[96:97], v[80:83], off offset:256
	v_and_b32_e32 v85, 0xffff0000, v165
	v_lshlrev_b32_e32 v86, 16, v166
	v_lshlrev_b32_e32 v82, 16, v164
	v_and_b32_e32 v83, 0xffff0000, v164
	v_and_b32_e32 v87, 0xffff0000, v166
	v_lshlrev_b32_e32 v88, 16, v167
	v_and_b32_e32 v89, 0xffff0000, v167
	v_lshl_add_u64 v[80:81], v[226:227], 0, v[232:233]
	v_pk_fma_f32 v[78:79], v[78:79], v[220:221], v[84:85]
	v_pk_fma_f32 v[76:77], v[76:77], v[218:219], v[82:83]
	v_pk_fma_f32 v[82:83], v[74:75], v[216:217], v[88:89]
	v_pk_fma_f32 v[74:75], v[72:73], v[214:215], v[86:87]
	v_cvt_pk_bf16_f32 v72, v76, v77
	v_cvt_pk_bf16_f32 v73, v78, v79
	v_lshlrev_b32_e32 v76, 16, v162
	v_cvt_pk_bf16_f32 v74, v74, v75
	v_cvt_pk_bf16_f32 v75, v82, v83
	global_store_dwordx4 v[80:81], v[72:75], off
	v_and_b32_e32 v77, 0xffff0000, v162
	v_lshlrev_b32_e32 v78, 16, v163
	v_lshlrev_b32_e32 v72, 16, v160
	v_and_b32_e32 v73, 0xffff0000, v160
	v_and_b32_e32 v79, 0xffff0000, v163
	v_lshlrev_b32_e32 v74, 16, v161
	v_and_b32_e32 v75, 0xffff0000, v161
	v_pk_fma_f32 v[68:69], v[68:69], v[210:211], v[72:73]
	v_pk_fma_f32 v[72:73], v[66:67], v[208:209], v[78:79]
	v_pk_fma_f32 v[66:67], v[64:65], v[206:207], v[76:77]
	v_pk_fma_f32 v[70:71], v[70:71], v[212:213], v[74:75]
	v_cvt_pk_bf16_f32 v64, v68, v69
	v_lshlrev_b32_e32 v68, 16, v157
	v_cvt_pk_bf16_f32 v65, v70, v71
	v_cvt_pk_bf16_f32 v66, v66, v67
	v_cvt_pk_bf16_f32 v67, v72, v73
	global_store_dwordx4 v[80:81], v[64:67], off offset:256
	v_and_b32_e32 v69, 0xffff0000, v157
	v_lshlrev_b32_e32 v70, 16, v158
	v_lshlrev_b32_e32 v66, 16, v156
	v_and_b32_e32 v67, 0xffff0000, v156
	v_and_b32_e32 v71, 0xffff0000, v158
	v_lshlrev_b32_e32 v72, 16, v159
	v_and_b32_e32 v73, 0xffff0000, v159
	v_lshl_add_u64 v[64:65], v[226:227], 0, v[230:231]
	v_pk_fma_f32 v[62:63], v[62:63], v[220:221], v[68:69]
	v_pk_fma_f32 v[60:61], v[60:61], v[218:219], v[66:67]
	v_pk_fma_f32 v[66:67], v[58:59], v[216:217], v[72:73]
	v_pk_fma_f32 v[58:59], v[56:57], v[214:215], v[70:71]
	v_cvt_pk_bf16_f32 v56, v60, v61
	v_cvt_pk_bf16_f32 v57, v62, v63
	v_lshlrev_b32_e32 v60, 16, v154
	v_cvt_pk_bf16_f32 v58, v58, v59
	v_cvt_pk_bf16_f32 v59, v66, v67
	global_store_dwordx4 v[64:65], v[56:59], off
	v_and_b32_e32 v61, 0xffff0000, v154
	v_lshlrev_b32_e32 v62, 16, v155
	v_lshlrev_b32_e32 v56, 16, v152
	v_and_b32_e32 v57, 0xffff0000, v152
	v_and_b32_e32 v63, 0xffff0000, v155
	v_lshlrev_b32_e32 v58, 16, v153
	v_and_b32_e32 v59, 0xffff0000, v153
	v_pk_fma_f32 v[52:53], v[52:53], v[210:211], v[56:57]
; __device__ __forceinline__ unsigned cvt_pk_bf16(float lo, float hi) { unsigned r; asm volatile("v_cvt_pk_bf16_f32 %0, %1, %2" : "=v"(r) : "v"(lo), "v"(hi)); return r; }
; __device__ __forceinline__ float bf_lo(unsigned u) { return __uint_as_float(u << 16); }
; __device__ __forceinline__ float bf_hi(unsigned u) { return __uint_as_float(u & 0xffff0000u); }
; #define PG8_WAIT_V(n) asm volatile("s_waitcnt vmcnt(" #n ")" ::: "memory")
; #define PG8_BAR __builtin_amdgcn_s_barrier()
; template <class Epi, class Sched>
; __device__ __forceinline__ void gemm_phase(LAS unsigned char* lds, const Gemm g, const Sched& S, const Epi& E) {
;     ...
;         if (!has_next) break;
; #pragma unroll
;         for (int a = 0; a < 2; ++a)
; #pragma unroll
;             for (int b = 0; b < 2; ++b)
; #pragma unroll
;                 for (int m = 0; m < 4; ++m)
; #pragma unroll
;                     for (int n = 0; n < 2; ++n) acc[a][b][m][n] = (f32x4){0.f, 0.f, 0.f, 0.f};
;         cur = nxt; cA = nA; cB = nB; ++ui;
;     }
;     PG8_WAIT_V(0);
;     if (wr == 0) PG8_BAR;
;     PG8_BAR;
;     __device__ __forceinline__ void operator()(const AccT& acc, const Unit& u, int wr, int wc, int fr, int fq) const {
;     ...
;         for (int ai = 0; ai < 2; ++ai)
; #pragma unroll
;             for (int m = 0; m < 4; ++m)
; #pragma unroll
;                 for (int bj = 0; bj < 2; ++bj) {
;                     const u32x4 q = r[ai][m][bj];
;                     const f32x4 r0 = {bf_lo(q.x), bf_hi(q.x), bf_lo(q.y), bf_hi(q.y)}, r1 = {bf_lo(q.z), bf_hi(q.z), bf_lo(q.w), bf_hi(q.w)};
;                     const f32x4 h0 = r0 + gv[bj][0] * acc[ai][bj][m][0], h1 = r1 + gv[bj][1] * acc[ai][bj][m][1];
;                     u32x4 w; w.x = cvt_pk_bf16(h0[0], h0[1]); w.y = cvt_pk_bf16(h0[2], h0[3]); w.z = cvt_pk_bf16(h1[0], h1[1]); w.w = cvt_pk_bf16(h1[2], h1[3]);
;                     *(u32x4*)(out + (size_t)(wr * 64 + fr + ai * 128 + m * 16) * DM + col0 + bj * 128) = w;
;                 }
	v_pk_fma_f32 v[56:57], v[50:51], v[208:209], v[62:63]
	v_pk_fma_f32 v[50:51], v[48:49], v[206:207], v[60:61]
	v_pk_fma_f32 v[54:55], v[54:55], v[212:213], v[58:59]
	v_cvt_pk_bf16_f32 v48, v52, v53
	v_lshlrev_b32_e32 v52, 16, v149
	v_cvt_pk_bf16_f32 v49, v54, v55
	v_cvt_pk_bf16_f32 v50, v50, v51
	v_cvt_pk_bf16_f32 v51, v56, v57
	global_store_dwordx4 v[64:65], v[48:51], off offset:256
	v_and_b32_e32 v53, 0xffff0000, v149
	v_lshlrev_b32_e32 v54, 16, v150
	v_lshlrev_b32_e32 v50, 16, v148
	v_and_b32_e32 v51, 0xffff0000, v148
	v_and_b32_e32 v55, 0xffff0000, v150
	v_lshlrev_b32_e32 v56, 16, v151
	v_and_b32_e32 v57, 0xffff0000, v151
	v_lshl_add_u64 v[48:49], v[226:227], 0, v[228:229]
	v_pk_fma_f32 v[46:47], v[46:47], v[220:221], v[52:53]
	v_pk_fma_f32 v[44:45], v[44:45], v[218:219], v[50:51]
	v_pk_fma_f32 v[50:51], v[42:43], v[216:217], v[56:57]
	v_pk_fma_f32 v[42:43], v[40:41], v[214:215], v[54:55]
	v_cvt_pk_bf16_f32 v40, v44, v45
	v_cvt_pk_bf16_f32 v41, v46, v47
	v_lshlrev_b32_e32 v44, 16, v146
	v_cvt_pk_bf16_f32 v42, v42, v43
	v_cvt_pk_bf16_f32 v43, v50, v51
	global_store_dwordx4 v[48:49], v[40:43], off
	v_and_b32_e32 v45, 0xffff0000, v146
	v_lshlrev_b32_e32 v46, 16, v147
	v_lshlrev_b32_e32 v40, 16, v144
	v_and_b32_e32 v41, 0xffff0000, v144
	v_and_b32_e32 v47, 0xffff0000, v147
	v_lshlrev_b32_e32 v42, 16, v145
	v_and_b32_e32 v43, 0xffff0000, v145
	v_pk_fma_f32 v[36:37], v[36:37], v[210:211], v[40:41]
	v_pk_fma_f32 v[40:41], v[34:35], v[208:209], v[46:47]
	v_pk_fma_f32 v[34:35], v[32:33], v[206:207], v[44:45]
	v_pk_fma_f32 v[38:39], v[38:39], v[212:213], v[42:43]
	v_cvt_pk_bf16_f32 v32, v36, v37
	v_lshlrev_b32_e32 v36, 16, v141
	v_cvt_pk_bf16_f32 v33, v38, v39
	v_cvt_pk_bf16_f32 v34, v34, v35
	v_cvt_pk_bf16_f32 v35, v40, v41
	global_store_dwordx4 v[48:49], v[32:35], off offset:256
	v_and_b32_e32 v37, 0xffff0000, v141
	v_lshlrev_b32_e32 v38, 16, v142
	v_lshlrev_b32_e32 v34, 16, v140
	v_and_b32_e32 v35, 0xffff0000, v140
	v_and_b32_e32 v39, 0xffff0000, v142
	v_lshlrev_b32_e32 v40, 16, v143
	v_and_b32_e32 v41, 0xffff0000, v143
	v_lshl_add_u64 v[32:33], v[226:227], 0, v[224:225]
	v_pk_fma_f32 v[30:31], v[30:31], v[220:221], v[36:37]
	v_pk_fma_f32 v[28:29], v[28:29], v[218:219], v[34:35]
	v_pk_fma_f32 v[34:35], v[26:27], v[216:217], v[40:41]
	v_pk_fma_f32 v[26:27], v[24:25], v[214:215], v[38:39]
	v_cvt_pk_bf16_f32 v24, v28, v29
	v_cvt_pk_bf16_f32 v25, v30, v31
	v_lshlrev_b32_e32 v28, 16, v138
	v_cvt_pk_bf16_f32 v26, v26, v27
	v_cvt_pk_bf16_f32 v27, v34, v35
	global_store_dwordx4 v[32:33], v[24:27], off
	v_and_b32_e32 v29, 0xffff0000, v138
	v_lshlrev_b32_e32 v30, 16, v139
	v_lshlrev_b32_e32 v24, 16, v136
	v_and_b32_e32 v25, 0xffff0000, v136
	v_and_b32_e32 v31, 0xffff0000, v139
	v_lshlrev_b32_e32 v26, 16, v137
	v_and_b32_e32 v27, 0xffff0000, v137
	v_pk_fma_f32 v[20:21], v[20:21], v[210:211], v[24:25]
	v_pk_fma_f32 v[24:25], v[18:19], v[208:209], v[30:31]
	v_pk_fma_f32 v[18:19], v[16:17], v[206:207], v[28:29]
	v_pk_fma_f32 v[22:23], v[22:23], v[212:213], v[26:27]
	v_cvt_pk_bf16_f32 v16, v20, v21
	v_lshlrev_b32_e32 v20, 16, v133
	v_cvt_pk_bf16_f32 v17, v22, v23
	v_cvt_pk_bf16_f32 v18, v18, v19
	v_cvt_pk_bf16_f32 v19, v24, v25
	global_store_dwordx4 v[32:33], v[16:19], off offset:256
	v_and_b32_e32 v21, 0xffff0000, v133
	v_lshlrev_b32_e32 v22, 16, v134
	v_lshlrev_b32_e32 v18, 16, v132
	v_and_b32_e32 v19, 0xffff0000, v132
	v_and_b32_e32 v23, 0xffff0000, v134
	v_lshlrev_b32_e32 v24, 16, v135
	v_and_b32_e32 v25, 0xffff0000, v135
	v_lshl_add_u64 v[16:17], v[226:227], 0, v[222:223]
	v_pk_fma_f32 v[14:15], v[14:15], v[220:221], v[20:21]
	v_pk_fma_f32 v[12:13], v[12:13], v[218:219], v[18:19]
	v_pk_fma_f32 v[18:19], v[10:11], v[216:217], v[24:25]
	v_pk_fma_f32 v[10:11], v[8:9], v[214:215], v[22:23]
	v_cvt_pk_bf16_f32 v8, v12, v13
	v_cvt_pk_bf16_f32 v9, v14, v15
	v_lshlrev_b32_e32 v12, 16, v130
	v_cvt_pk_bf16_f32 v10, v10, v11
	v_cvt_pk_bf16_f32 v11, v18, v19
	global_store_dwordx4 v[16:17], v[8:11], off
	v_and_b32_e32 v13, 0xffff0000, v130
	v_lshlrev_b32_e32 v14, 16, v131
	v_lshlrev_b32_e32 v8, 16, v128
	v_and_b32_e32 v9, 0xffff0000, v128
	v_and_b32_e32 v15, 0xffff0000, v131
	v_lshlrev_b32_e32 v10, 16, v129
	v_and_b32_e32 v11, 0xffff0000, v129
	v_pk_fma_f32 v[4:5], v[4:5], v[210:211], v[8:9]
	v_pk_fma_f32 v[8:9], v[2:3], v[208:209], v[14:15]
	v_pk_fma_f32 v[2:3], v[0:1], v[206:207], v[12:13]
	v_pk_fma_f32 v[6:7], v[6:7], v[212:213], v[10:11]
	v_cvt_pk_bf16_f32 v0, v4, v5
	s_nop 0
	v_cvt_pk_bf16_f32 v1, v6, v7
	v_cvt_pk_bf16_f32 v2, v2, v3
	v_cvt_pk_bf16_f32 v3, v8, v9
	global_store_dwordx4 v[16:17], v[0:3], off offset:256
	s_cbranch_vccz .LBB0_1086
	s_waitcnt vmcnt(0)
	s_cmpk_gt_u32 s30, 0xff
	s_cbranch_scc1 .LBB0_1101
	s_barrier
